# GEMM K-loop static priority level 2 instead of 1 on the current stack
# speedup vs baseline: 1.0027x; 1.0027x over previous
; DI int BIDX() { int b = blockIdx.x; asm volatile("" : "+s"(b)); return b; }
; DI int tile_groups(int MT, int NT) { return (MT >> 6) * ((NT + 7) >> 3) * 512; }
; DI void load_rstd(float (&rs)[4], const float* ssq, int row0, int lr) {
; #pragma unroll
;   for (int mt = 0; mt < 4; ++mt) {
;     const float4* q = (const float4*)(ssq + (size_t)(row0 + mt * 16 + lr) * 16);
;     const float4 a = q[0], b = q[1], c = q[2], d = q[3];
;     const float s = ((a.x + a.y) + (a.z + a.w)) + ((b.x + b.y) + (b.z + b.w)) + ((c.x + c.y) + (c.z + c.w)) + ((d.x + d.y) + (d.z + d.w));
;     rs[mt] = rsqrtf(s * (1.0f / 1024.0f) + EPS);
;   }
; DI void phase_proj(const Params& P, int l, char* smem) {
;     ...
;   for (int vb = BIDX(); vb < tile_groups(128, 63); vb += gridDim.x) {
;     int tm, tn; if (!tile_of(vb, 128, 63, tm, tn)) continue;
;     const int m0 = tm * 128, n0 = tn * 128;
;     f32x4 acc[4][4]; zero_acc(acc);
;     const int row0 = m0 + wm * 64, col0 = n0 + wn * 64;
;     float rs[4]; load_rstd(rs, ssq, row0, lr);
;     if (n0 >= PW) {
.LBB0_637:
	s_ashr_i32 s1, s28, 9
	s_lshr_b32 s2, s1, 29
	s_add_i32 s2, s1, s2
	s_lshl_b32 s2, s2, 3
	s_and_b32 s4, s2, 0xffffffc0
	s_and_b32 s2, s26, 56
	s_bfe_u32 s5, s28, 0x30003
	s_or_b32 s2, s2, s5
	s_lshl_b32 s1, s1, 3
	s_or_b32 s2, s2, s4
	s_sub_i32 s1, s1, s4
	s_bfe_u32 s4, s28, 0x30006
	s_or_b32 s1, s1, s4
	s_cmpk_lt_i32 s2, 0x80
	s_cselect_b64 s[4:5], -1, 0
	s_cmp_lt_i32 s1, 63
	s_cselect_b64 s[16:17], -1, 0
	s_and_b64 s[4:5], s[4:5], s[16:17]
	s_andn2_b64 vcc, exec, s[4:5]
	s_cbranch_vccnz .LBB0_636
	s_lshl_b32 s18, s2, 7
	v_add_u32_e32 v99, s18, v101
	s_waitcnt vmcnt(0)
	v_or_b32_e32 v70, v99, v97
	v_ashrrev_i32_e32 v71, 31, v70
	v_readlane_b32 s20, v253, 13
	v_lshlrev_b64 v[0:1], 6, v[70:71]
	v_readlane_b32 s21, v253, 14
	v_or_b32_e32 v68, 16, v70
	v_ashrrev_i32_e32 v69, 31, v68
	v_lshl_add_u64 v[12:13], s[20:21], 0, v[0:1]
	global_load_dwordx4 v[0:3], v[12:13], off offset:48
	global_load_dwordx4 v[4:7], v[12:13], off offset:32
	global_load_dwordx4 v[8:11], v[12:13], off offset:16
	s_nop 0
	global_load_dwordx4 v[12:15], v[12:13], off
	s_mov_b32 s2, 0x358637bd
	s_mov_b32 s22, 0x3a800000
	v_or_b32_e32 v66, 32, v70
	v_ashrrev_i32_e32 v67, 31, v66
	v_or_b32_e32 v64, 48, v70
	v_ashrrev_i32_e32 v65, 31, v64
	s_ashr_i32 s19, s18, 31
	s_lshl_b32 s16, s1, 7
	v_or_b32_e32 v94, s16, v85
	s_waitcnt vmcnt(1)
	v_mov_b32_e32 v18, v9
	s_waitcnt vmcnt(0)
	v_mov_b32_e32 v16, v13
	v_mov_b32_e32 v17, v14
	v_mov_b32_e32 v19, v10
	v_mov_b32_e32 v13, v15
	v_mov_b32_e32 v9, v11
	v_pk_add_f32 v[12:13], v[16:17], v[12:13]
	v_pk_add_f32 v[8:9], v[18:19], v[8:9]
	v_pk_add_f32 v[10:11], v[12:13], v[12:13] op_sel:[0,1] op_sel_hi:[1,0]
	v_pk_add_f32 v[8:9], v[8:9], v[8:9] op_sel:[0,1] op_sel_hi:[1,0]
	v_mov_b32_e32 v11, v0
	v_mov_b32_e32 v9, v1
	v_pk_add_f32 v[0:1], v[10:11], v[8:9]
	v_mov_b32_e32 v8, v5
	v_pk_add_f32 v[4:5], v[4:5], v[8:9]
	s_nop 0
	v_mov_b32_e32 v5, v2
	v_mov_b32_e32 v2, v7
	v_pk_add_f32 v[6:7], v[6:7], v[2:3]
	s_nop 0
	v_mov_b32_e32 v7, v3
	v_pk_add_f32 v[2:3], v[4:5], v[6:7]
	s_nop 0
	v_pk_add_f32 v[16:17], v[0:1], v[2:3]
	v_lshlrev_b64 v[0:1], 6, v[68:69]
	v_lshl_add_u64 v[12:13], s[20:21], 0, v[0:1]
	global_load_dwordx4 v[0:3], v[12:13], off offset:48
	global_load_dwordx4 v[4:7], v[12:13], off offset:32
	global_load_dwordx4 v[8:11], v[12:13], off offset:16
	s_nop 0
	global_load_dwordx4 v[12:15], v[12:13], off
	s_waitcnt vmcnt(1)
	v_mov_b32_e32 v20, v9
	s_waitcnt vmcnt(0)
	v_mov_b32_e32 v18, v13
	v_mov_b32_e32 v19, v14
	v_mov_b32_e32 v21, v10
	v_mov_b32_e32 v13, v15
	v_mov_b32_e32 v9, v11
	v_pk_add_f32 v[12:13], v[18:19], v[12:13]
	v_pk_add_f32 v[8:9], v[20:21], v[8:9]
	v_pk_add_f32 v[10:11], v[12:13], v[12:13] op_sel:[0,1] op_sel_hi:[1,0]
	v_pk_add_f32 v[8:9], v[8:9], v[8:9] op_sel:[0,1] op_sel_hi:[1,0]
	v_mov_b32_e32 v11, v0
	v_mov_b32_e32 v9, v1
	v_pk_add_f32 v[0:1], v[10:11], v[8:9]
	v_mov_b32_e32 v8, v5
	v_pk_add_f32 v[4:5], v[4:5], v[8:9]
	s_nop 0
	v_mov_b32_e32 v5, v2
	v_mov_b32_e32 v2, v7
	v_pk_add_f32 v[6:7], v[6:7], v[2:3]
	s_nop 0
	v_mov_b32_e32 v7, v3
	v_pk_add_f32 v[2:3], v[4:5], v[6:7]
	s_nop 0
	v_pk_add_f32 v[0:1], v[0:1], v[2:3]
	v_mov_b32_e32 v3, v16
	v_mov_b32_e32 v2, v0
	v_mov_b32_e32 v16, v1
	v_pk_add_f32 v[0:1], v[2:3], v[16:17]
	v_mov_b64_e32 v[16:17], s[2:3]
	v_pk_fma_f32 v[0:1], v[0:1], s[22:23], v[16:17] op_sel_hi:[1,0,0]
	s_mov_b32 s2, 0x800000
	v_mul_f32_e32 v2, 0x4b800000, v1
	v_cmp_gt_f32_e64 s[4:5], s2, v1
	v_cmp_gt_f32_e32 vcc, s2, v0
	s_nop 0
	v_cndmask_b32_e64 v1, v1, v2, s[4:5]
	v_rsq_f32_e32 v1, v1
	s_nop 0
	v_mul_f32_e32 v2, 0x45800000, v1
	v_cndmask_b32_e64 v98, v1, v2, s[4:5]
	v_mul_f32_e32 v1, 0x4b800000, v0
	v_cndmask_b32_e32 v0, v0, v1, vcc
	v_rsq_f32_e32 v0, v0
	s_nop 0
	v_mul_f32_e32 v1, 0x45800000, v0
	v_cndmask_b32_e32 v96, v0, v1, vcc
	v_lshlrev_b64 v[0:1], 6, v[66:67]
	v_lshl_add_u64 v[12:13], s[20:21], 0, v[0:1]
	global_load_dwordx4 v[0:3], v[12:13], off offset:48
	global_load_dwordx4 v[4:7], v[12:13], off offset:32
	global_load_dwordx4 v[8:11], v[12:13], off offset:16
	s_nop 0
	global_load_dwordx4 v[12:15], v[12:13], off
	s_waitcnt vmcnt(1)
	v_mov_b32_e32 v20, v9
	s_waitcnt vmcnt(0)
	v_mov_b32_e32 v18, v13
	v_mov_b32_e32 v19, v14
	v_mov_b32_e32 v21, v10
	v_mov_b32_e32 v13, v15
	v_mov_b32_e32 v9, v11
	v_pk_add_f32 v[12:13], v[18:19], v[12:13]
	v_pk_add_f32 v[8:9], v[20:21], v[8:9]
	v_pk_add_f32 v[10:11], v[12:13], v[12:13] op_sel:[0,1] op_sel_hi:[1,0]
	v_pk_add_f32 v[8:9], v[8:9], v[8:9] op_sel:[0,1] op_sel_hi:[1,0]
	v_mov_b32_e32 v11, v0
	v_mov_b32_e32 v9, v1
	v_pk_add_f32 v[0:1], v[10:11], v[8:9]
	v_mov_b32_e32 v8, v5
	v_pk_add_f32 v[4:5], v[4:5], v[8:9]
	s_nop 0
	v_mov_b32_e32 v5, v2
	v_mov_b32_e32 v2, v7
	v_pk_add_f32 v[6:7], v[6:7], v[2:3]
	s_nop 0
	v_mov_b32_e32 v7, v3
	v_pk_add_f32 v[2:3], v[4:5], v[6:7]
	s_nop 0
	v_pk_add_f32 v[18:19], v[0:1], v[2:3]
	v_lshlrev_b64 v[0:1], 6, v[64:65]
	v_lshl_add_u64 v[12:13], s[20:21], 0, v[0:1]
	global_load_dwordx4 v[0:3], v[12:13], off offset:48
	global_load_dwordx4 v[4:7], v[12:13], off offset:32
	global_load_dwordx4 v[8:11], v[12:13], off offset:16
	s_nop 0
	global_load_dwordx4 v[12:15], v[12:13], off
	s_waitcnt vmcnt(1)
	v_mov_b32_e32 v22, v9
	s_waitcnt vmcnt(0)
	v_mov_b32_e32 v20, v13
	v_mov_b32_e32 v21, v14
	v_mov_b32_e32 v23, v10
	v_mov_b32_e32 v13, v15
	v_mov_b32_e32 v9, v11
	v_pk_add_f32 v[12:13], v[20:21], v[12:13]
	v_pk_add_f32 v[8:9], v[22:23], v[8:9]
	v_pk_add_f32 v[10:11], v[12:13], v[12:13] op_sel:[0,1] op_sel_hi:[1,0]
	v_pk_add_f32 v[8:9], v[8:9], v[8:9] op_sel:[0,1] op_sel_hi:[1,0]
	v_mov_b32_e32 v11, v0
	v_mov_b32_e32 v9, v1
	v_pk_add_f32 v[0:1], v[10:11], v[8:9]
	v_mov_b32_e32 v8, v5
	v_pk_add_f32 v[4:5], v[4:5], v[8:9]
	s_nop 0
	v_mov_b32_e32 v5, v2
	v_mov_b32_e32 v2, v7
	v_pk_add_f32 v[6:7], v[6:7], v[2:3]
	s_nop 0
	v_mov_b32_e32 v7, v3
	v_pk_add_f32 v[2:3], v[4:5], v[6:7]
	s_nop 0
	v_pk_add_f32 v[0:1], v[0:1], v[2:3]
	v_mov_b32_e32 v3, v18
	v_mov_b32_e32 v2, v0
	v_mov_b32_e32 v18, v1
	v_pk_add_f32 v[0:1], v[2:3], v[18:19]
	s_nop 0
	v_pk_fma_f32 v[0:1], v[0:1], s[22:23], v[16:17] op_sel_hi:[1,0,0]
	s_nop 0
	v_mul_f32_e32 v2, 0x4b800000, v1
	v_cmp_gt_f32_e64 s[4:5], s2, v1
	v_cmp_gt_f32_e32 vcc, s2, v0
	s_nop 0
	v_cndmask_b32_e64 v1, v1, v2, s[4:5]
	v_rsq_f32_e32 v1, v1
	s_nop 0
	v_mul_f32_e32 v2, 0x45800000, v1
	v_cndmask_b32_e64 v102, v1, v2, s[4:5]
	v_mul_f32_e32 v1, 0x4b800000, v0
	v_cndmask_b32_e32 v0, v0, v1, vcc
	v_rsq_f32_e32 v0, v0
	s_lshl_b64 s[4:5], s[18:19], 11
	v_readlane_b32 s18, v253, 11
	v_readlane_b32 s19, v253, 12
	s_add_u32 s18, s18, s4
	v_mul_f32_e32 v1, 0x45800000, v0
	s_addc_u32 s19, s19, s5
	v_cndmask_b32_e32 v100, v0, v1, vcc
	s_cmp_lt_i32 s1, 51
	s_mov_b64 s[4:5], -1
	s_cbranch_scc0 .LBB0_691
; DI int TIDX() { int t = threadIdx.x; asm volatile("" : "+v"(t)); return t; }
; #define GL_LOAD(s_, kt_) if (VAR != 1) { a##s_##0 = GL_A(0, kt_); a##s_##1 = GL_A(1, kt_); a##s_##2 = GL_A(2, kt_); a##s_##3 = GL_A(3, kt_); b##s_##0 = GL_B(0, kt_); b##s_##1 = GL_B(1, kt_); b##s_##2 = GL_B(2, kt_); b##s_##3 = GL_B(3, kt_); }
; #define LDS_STORE(s_, buf_) if (VAR != 2) { LDS_ST1(sA, 0, buf_, a##s_##0) LDS_ST1(sA, 1, buf_, a##s_##1) LDS_ST1(sA, 2, buf_, a##s_##2) LDS_ST1(sA, 3, buf_, a##s_##3) LDS_ST1(sB, 0, buf_, b##s_##0) LDS_ST1(sB, 1, buf_, b##s_##1) LDS_ST1(sB, 2, buf_, b##s_##2) LDS_ST1(sB, 3, buf_, b##s_##3) }
;   const int tid = TIDX(), lane = tid & 63, wid = tid >> 6, wm = wid >> 1, wn = wid & 1, lr = lane & 15, g = lane >> 4;
;   char* sA = smem; char* sB = smem + 2 * LTILE;
;   uint4 a00 = {}, a01 = {}, a02 = {}, a03 = {}, b00 = {}, b01 = {}, b02 = {}, b03 = {}, a10 = {}, a11 = {}, a12 = {}, a13 = {}, b10 = {}, b11 = {}, b12 = {}, b13 = {};
;   constexpr int nk = NK;
;   const int sw0 = (g ^ ((lr >> 1) & 7)) << 4, sw1 = sw0 ^ 64;
;   const int r0 = tid >> 3, kc = tid & 7, kcs = kc ^ ((r0 >> 1) & 7);
;     ...
;   GL_LOAD(0, 0)
;   GL_LOAD(1, 1)
;   LDS_STORE(0, 0)
;   if (VAR != 4) __syncthreads();
; #pragma unroll
;   for (int kt = 0; kt < nk; kt += 2) {
;     if (kt + 2 < nk) { GL_LOAD(0, kt + 2) }
;     MMA_TILE(0)
;     LDS_STORE(1, 1)
;     if (VAR != 4) __syncthreads();
;     if (kt + 3 < nk) { GL_LOAD(1, kt + 3) }
;     MMA_TILE(1)
	v_mov_b32_e32 v56, v148
	s_ashr_i32 s17, s16, 31
	s_lshl_b64 s[4:5], s[16:17], 11
	v_ashrrev_i32_e32 v16, 3, v56
	v_readlane_b32 s1, v252, 19
	v_ashrrev_i32_e32 v17, 31, v16
	s_add_u32 s4, s1, s4
	v_readlane_b32 s1, v252, 20
	v_lshlrev_b64 v[8:9], 11, v[16:17]
	v_lshlrev_b32_e32 v17, 4, v56
	v_add_u32_e32 v18, 32, v16
	s_addc_u32 s5, s1, s5
	v_lshl_add_u64 v[0:1], s[18:19], 0, v[8:9]
	v_and_b32_e32 v150, 0x70, v17
	v_ashrrev_i32_e32 v19, 31, v18
	v_add_u32_e32 v20, 64, v16
	v_lshl_add_u64 v[0:1], v[0:1], 0, v[150:151]
	v_lshlrev_b64 v[10:11], 11, v[18:19]
	v_ashrrev_i32_e32 v21, 31, v20
	v_add_u32_e32 v54, 0x60, v16
	v_lshl_add_u64 v[8:9], s[4:5], 0, v[8:9]
	global_load_dwordx4 v[22:25], v[0:1], off
	v_lshl_add_u64 v[2:3], s[18:19], 0, v[10:11]
	v_lshlrev_b64 v[12:13], 11, v[20:21]
	v_ashrrev_i32_e32 v55, 31, v54
	v_lshl_add_u64 v[8:9], v[8:9], 0, v[150:151]
	v_lshl_add_u64 v[2:3], v[2:3], 0, v[150:151]
	v_lshl_add_u64 v[4:5], s[18:19], 0, v[12:13]
	v_lshlrev_b64 v[14:15], 11, v[54:55]
	global_load_dwordx4 v[38:41], v[8:9], off
	global_load_dwordx4 v[26:29], v[2:3], off
	v_lshl_add_u64 v[4:5], v[4:5], 0, v[150:151]
	v_lshl_add_u64 v[6:7], s[18:19], 0, v[14:15]
	global_load_dwordx4 v[30:33], v[4:5], off
	v_lshl_add_u64 v[6:7], v[6:7], 0, v[150:151]
	v_lshl_add_u64 v[10:11], s[4:5], 0, v[10:11]
	global_load_dwordx4 v[34:37], v[6:7], off
	v_lshl_add_u64 v[10:11], v[10:11], 0, v[150:151]
	v_lshl_add_u64 v[12:13], s[4:5], 0, v[12:13]
	global_load_dwordx4 v[42:45], v[10:11], off
	v_lshl_add_u64 v[12:13], v[12:13], 0, v[150:151]
	v_lshl_add_u64 v[14:15], s[4:5], 0, v[14:15]
	global_load_dwordx4 v[46:49], v[12:13], off
	v_lshl_add_u64 v[14:15], v[14:15], 0, v[150:151]
	global_load_dwordx4 v[50:53], v[14:15], off
	v_lshlrev_b32_e32 v21, 3, v56
	v_and_b32_e32 v62, 48, v56
	s_movk_i32 s1, 0x70
	v_and_b32_e32 v19, 15, v56
	v_lshrrev_b32_e32 v55, 1, v56
	v_lshlrev_b32_e32 v57, 7, v56
	v_and_b32_e32 v63, 0x70, v21
	v_bitop3_b32 v95, v21, v62, s1 bitop3:0x6c
	v_bitop3_b32 v21, v17, s1, v56 bitop3:0x48
	v_and_or_b32 v103, v55, s29, v19
	v_and_b32_e32 v150, 0x2780, v57
	v_lshl_or_b32 v19, v20, 7, v21
	v_lshl_or_b32 v20, v54, 7, v21
	global_load_dwordx4 v[54:57], v[0:1], off offset:128
	global_load_dwordx4 v[58:61], v[8:9], off offset:128
	global_load_dwordx4 v[72:75], v[2:3], off offset:128
	global_load_dwordx4 v[76:79], v[4:5], off offset:128
	global_load_dwordx4 v[80:83], v[6:7], off offset:128
	global_load_dwordx4 v[104:107], v[10:11], off offset:128
	global_load_dwordx4 v[108:111], v[12:13], off offset:128
	global_load_dwordx4 v[112:115], v[14:15], off offset:128
	v_lshl_or_b32 v17, v16, 7, v21
	v_or_b32_e32 v16, v150, v95
	v_lshlrev_b32_e32 v103, 7, v103
	v_lshl_or_b32 v18, v18, 7, v21
	v_bitop3_b32 v21, v103, v63, v62 bitop3:0xf6
	s_movk_i32 s1, 0x1ff
	v_cmp_lt_i32_e32 vcc, s1, v94
	s_mov_b64 s[22:23], -1
	s_mov_b64 s[20:21], 0
	s_waitcnt vmcnt(15)
	ds_write_b128 v17, v[22:25]
	s_waitcnt vmcnt(14)
	ds_write_b128 v17, v[38:41] offset:32768
	s_waitcnt vmcnt(13)
	ds_write_b128 v18, v[26:29]
	s_waitcnt vmcnt(12)
	ds_write_b128 v19, v[30:33]
	s_waitcnt vmcnt(11)
	ds_write_b128 v20, v[34:37]
	s_waitcnt vmcnt(10)
	ds_write_b128 v18, v[42:45] offset:32768
	s_waitcnt vmcnt(9)
	ds_write_b128 v19, v[46:49] offset:32768
	s_waitcnt vmcnt(8)
	ds_write_b128 v20, v[50:53] offset:32768
	s_waitcnt lgkmcnt(0)
	s_barrier
	s_setprio 2
	ds_read_b128 v[22:25], v16 offset:32768
	ds_read_b128 v[30:33], v21
	s_waitcnt lgkmcnt(0)
	v_mfma_f32_16x16x32_f16 v[38:41], v[22:25], v[30:33], 0
	ds_read_b128 v[26:29], v16 offset:34816
	s_waitcnt lgkmcnt(0)
	v_mfma_f32_16x16x32_f16 v[46:49], v[26:29], v[30:33], 0
	ds_read_b128 v[34:37], v21 offset:2048
	ds_read_b128 v[42:45], v16 offset:36864
	s_waitcnt lgkmcnt(0)
	v_mfma_f32_16x16x32_f16 v[116:119], v[42:45], v[30:33], 0
	ds_read_b128 v[50:53], v16 offset:38912
	s_waitcnt lgkmcnt(0)
	v_mfma_f32_16x16x32_f16 v[120:123], v[50:53], v[30:33], 0
	ds_read_b128 v[30:33], v21 offset:4096
	v_mfma_f32_16x16x32_f16 v[124:127], v[22:25], v[34:37], 0
	ds_read_b128 v[136:139], v21 offset:6144
	s_waitcnt lgkmcnt(0)
	v_mfma_f32_16x16x32_f16 v[162:165], v[22:25], v[136:139], 0
	s_waitcnt vmcnt(7)
	ds_write_b128 v17, v[54:57] offset:16384
	v_mfma_f32_16x16x32_f16 v[128:131], v[26:29], v[34:37], 0
	s_waitcnt vmcnt(5)
	ds_write_b128 v18, v[72:75] offset:16384
	v_mfma_f32_16x16x32_f16 v[132:135], v[42:45], v[34:37], 0
	s_waitcnt vmcnt(4)
	ds_write_b128 v19, v[76:79] offset:16384
	v_mfma_f32_16x16x32_f16 v[34:37], v[50:53], v[34:37], 0
	s_waitcnt vmcnt(3)
	ds_write_b128 v20, v[80:83] offset:16384
	v_mfma_f32_16x16x32_f16 v[140:143], v[22:25], v[30:33], 0
	v_xor_b32_e32 v22, 64, v95
	v_or_b32_e32 v22, v150, v22
	v_mfma_f32_16x16x32_f16 v[144:147], v[26:29], v[30:33], 0
	v_mfma_f32_16x16x32_f16 v[154:157], v[42:45], v[30:33], 0
	v_mfma_f32_16x16x32_f16 v[158:161], v[50:53], v[30:33], 0
	v_bitop3_b32 v32, v103, v95, 64 bitop3:0xf6
	ds_read_b128 v[166:169], v32
	ds_read_b128 v[192:195], v22 offset:36864
	s_waitcnt lgkmcnt(0)
	v_mfma_f32_16x16x32_f16 v[116:119], v[192:195], v[166:169], v[116:119]
	ds_read_b128 v[188:191], v32 offset:2048
	ds_read_b128 v[196:199], v22 offset:38912
	s_waitcnt lgkmcnt(0)
	v_mfma_f32_16x16x32_f16 v[120:123], v[196:199], v[166:169], v[120:123]
	ds_write_b128 v17, v[58:61] offset:49152
	v_mfma_f32_16x16x32_f16 v[132:135], v[192:195], v[188:191], v[132:135]
	s_waitcnt vmcnt(2)
	ds_write_b128 v18, v[104:107] offset:49152
	v_mfma_f32_16x16x32_f16 v[34:37], v[196:199], v[188:191], v[34:37]
	s_waitcnt vmcnt(1)
	ds_write_b128 v19, v[108:111] offset:49152
	s_waitcnt vmcnt(0)
; #define GL_LOAD(s_, kt_) if (VAR != 1) { a##s_##0 = GL_A(0, kt_); a##s_##1 = GL_A(1, kt_); a##s_##2 = GL_A(2, kt_); a##s_##3 = GL_A(3, kt_); b##s_##0 = GL_B(0, kt_); b##s_##1 = GL_B(1, kt_); b##s_##2 = GL_B(2, kt_); b##s_##3 = GL_B(3, kt_); }
; #define LDS_STORE(s_, buf_) if (VAR != 2) { LDS_ST1(sA, 0, buf_, a##s_##0) LDS_ST1(sA, 1, buf_, a##s_##1) LDS_ST1(sA, 2, buf_, a##s_##2) LDS_ST1(sA, 3, buf_, a##s_##3) LDS_ST1(sB, 0, buf_, b##s_##0) LDS_ST1(sB, 1, buf_, b##s_##1) LDS_ST1(sB, 2, buf_, b##s_##2) LDS_ST1(sB, 3, buf_, b##s_##3) }
;     ...
;   for (int kt = 0; kt < nk; kt += 2) {
;     if (kt + 2 < nk) { GL_LOAD(0, kt + 2) }
;     MMA_TILE(0)
;     LDS_STORE(1, 1)
;     if (VAR != 4) __syncthreads();
;     if (kt + 3 < nk) { GL_LOAD(1, kt + 3) }
;     MMA_TILE(1)
;     if (kt + 2 < nk) { LDS_STORE(0, 0) }
;     if (VAR != 4) __syncthreads();
	ds_write_b128 v20, v[112:115] offset:49152
	v_mfma_f32_16x16x32_f16 v[24:27], v[26:29], v[136:139], 0
	v_mfma_f32_16x16x32_f16 v[28:31], v[42:45], v[136:139], 0
	ds_read_b128 v[42:45], v22 offset:32768
	v_mfma_f32_16x16x32_f16 v[50:53], v[50:53], v[136:139], 0
	ds_read_b128 v[136:139], v22 offset:34816
	s_waitcnt lgkmcnt(1)
	v_mfma_f32_16x16x32_f16 v[38:41], v[42:45], v[166:169], v[38:41]
	v_mfma_f32_16x16x32_f16 v[124:127], v[42:45], v[188:191], v[124:127]
	s_waitcnt lgkmcnt(0)
	v_mfma_f32_16x16x32_f16 v[46:49], v[136:139], v[166:169], v[46:49]
	ds_read_b128 v[166:169], v32 offset:4096
	v_mfma_f32_16x16x32_f16 v[128:131], v[136:139], v[188:191], v[128:131]
	ds_read_b128 v[188:191], v32 offset:6144
	s_waitcnt lgkmcnt(1)
	v_mfma_f32_16x16x32_f16 v[140:143], v[42:45], v[166:169], v[140:143]
	s_waitcnt lgkmcnt(0)
	v_mfma_f32_16x16x32_f16 v[42:45], v[42:45], v[188:191], v[162:165]
	s_nop 2
	global_load_dwordx4 v[162:165], v[0:1], off offset:256
	v_mfma_f32_16x16x32_f16 v[144:147], v[136:139], v[166:169], v[144:147]
	v_mfma_f32_16x16x32_f16 v[24:27], v[136:139], v[188:191], v[24:27]
	v_mfma_f32_16x16x32_f16 v[154:157], v[192:195], v[166:169], v[154:157]
	v_mfma_f32_16x16x32_f16 v[158:161], v[196:199], v[166:169], v[158:161]
	global_load_dwordx4 v[166:169], v[2:3], off offset:256
	global_load_dwordx4 v[200:203], v[4:5], off offset:256
	global_load_dwordx4 v[204:207], v[6:7], off offset:256
	global_load_dwordx4 v[136:139], v[8:9], off offset:256
	global_load_dwordx4 v[208:211], v[10:11], off offset:256
	global_load_dwordx4 v[212:215], v[12:13], off offset:256
	global_load_dwordx4 v[220:223], v[14:15], off offset:256
	s_waitcnt lgkmcnt(0)
	s_barrier
	v_mfma_f32_16x16x32_f16 v[28:31], v[192:195], v[188:191], v[28:31]
	ds_read_b128 v[54:57], v16 offset:49152
	v_mfma_f32_16x16x32_f16 v[50:53], v[196:199], v[188:191], v[50:53]
	ds_read_b128 v[58:61], v16 offset:51200
	ds_read_b128 v[72:75], v21 offset:16384
	s_waitcnt lgkmcnt(0)
	v_mfma_f32_16x16x32_f16 v[38:41], v[54:57], v[72:75], v[38:41]
	ds_read_b128 v[76:79], v21 offset:18432
	s_waitcnt lgkmcnt(0)
	v_mfma_f32_16x16x32_f16 v[112:115], v[54:57], v[76:79], v[124:127]
	ds_read_b128 v[80:83], v16 offset:53248
	v_mfma_f32_16x16x32_f16 v[46:49], v[58:61], v[72:75], v[46:49]
	ds_read_b128 v[104:107], v16 offset:55296
	s_waitcnt lgkmcnt(1)
	v_mfma_f32_16x16x32_f16 v[108:111], v[80:83], v[72:75], v[116:119]
	v_mfma_f32_16x16x32_f16 v[116:119], v[58:61], v[76:79], v[128:131]
	ds_read_b128 v[124:127], v21 offset:22528
	s_waitcnt vmcnt(7)
	ds_write_b128 v17, v[162:165]
	s_waitcnt lgkmcnt(2)
	v_mfma_f32_16x16x32_f16 v[72:75], v[104:107], v[72:75], v[120:123]
	v_mfma_f32_16x16x32_f16 v[120:123], v[80:83], v[76:79], v[132:135]
	s_waitcnt vmcnt(6)
	ds_write_b128 v18, v[166:169]
	s_waitcnt vmcnt(5)
	ds_write_b128 v19, v[200:203]
	v_mfma_f32_16x16x32_f16 v[34:37], v[104:107], v[76:79], v[34:37]
	ds_read_b128 v[76:79], v21 offset:20480
	s_waitcnt lgkmcnt(0)
	v_mfma_f32_16x16x32_f16 v[128:131], v[54:57], v[76:79], v[140:143]
	s_waitcnt vmcnt(4)
	ds_write_b128 v20, v[204:207]
	v_mfma_f32_16x16x32_f16 v[42:45], v[54:57], v[124:127], v[42:45]
	ds_read_b128 v[54:57], v22 offset:49152
	v_mfma_f32_16x16x32_f16 v[132:135], v[58:61], v[76:79], v[144:147]
	s_nop 2
	ds_read_b128 v[144:147], v22 offset:55296
	v_mfma_f32_16x16x32_f16 v[24:27], v[58:61], v[124:127], v[24:27]
	ds_read_b128 v[58:61], v22 offset:51200
	v_mfma_f32_16x16x32_f16 v[140:143], v[80:83], v[76:79], v[154:157]
	s_waitcnt vmcnt(3)
	ds_write_b128 v17, v[136:139] offset:32768
	v_mfma_f32_16x16x32_f16 v[28:31], v[80:83], v[124:127], v[28:31]
	ds_read_b128 v[80:83], v32 offset:16384
	v_mfma_f32_16x16x32_f16 v[76:79], v[104:107], v[76:79], v[158:161]
	s_waitcnt vmcnt(2)
	ds_write_b128 v18, v[208:211] offset:32768
	v_mfma_f32_16x16x32_f16 v[50:53], v[104:107], v[124:127], v[50:53]
	ds_read_b128 v[104:107], v32 offset:18432
	s_waitcnt lgkmcnt(2)
	v_mfma_f32_16x16x32_f16 v[38:41], v[54:57], v[80:83], v[38:41]
	ds_read_b128 v[124:127], v22 offset:53248
	v_mfma_f32_16x16x32_f16 v[46:49], v[58:61], v[80:83], v[46:49]
	s_waitcnt lgkmcnt(0)
	v_mfma_f32_16x16x32_f16 v[108:111], v[124:127], v[80:83], v[108:111]
	v_mfma_f32_16x16x32_f16 v[72:75], v[144:147], v[80:83], v[72:75]
	v_mfma_f32_16x16x32_f16 v[80:83], v[54:57], v[104:107], v[112:115]
	s_waitcnt vmcnt(1)
	ds_write_b128 v19, v[212:215] offset:32768
	s_waitcnt vmcnt(0)
	ds_write_b128 v20, v[220:223] offset:32768
	v_mfma_f32_16x16x32_f16 v[112:115], v[58:61], v[104:107], v[116:119]
	v_mfma_f32_16x16x32_f16 v[116:119], v[124:127], v[104:107], v[120:123]
	s_nop 2
	ds_read_b128 v[120:123], v32 offset:22528
	v_mfma_f32_16x16x32_f16 v[34:37], v[144:147], v[104:107], v[34:37]
	ds_read_b128 v[104:107], v32 offset:20480
	s_waitcnt lgkmcnt(0)
	v_mfma_f32_16x16x32_f16 v[128:131], v[54:57], v[104:107], v[128:131]
	v_mfma_f32_16x16x32_f16 v[42:45], v[54:57], v[120:123], v[42:45]
	global_load_dwordx4 v[54:57], v[0:1], off offset:384
	v_mfma_f32_16x16x32_f16 v[132:135], v[58:61], v[104:107], v[132:135]
	v_mfma_f32_16x16x32_f16 v[24:27], v[58:61], v[120:123], v[24:27]
	v_mfma_f32_16x16x32_f16 v[140:143], v[124:127], v[104:107], v[140:143]
	v_mfma_f32_16x16x32_f16 v[28:31], v[124:127], v[120:123], v[28:31]
	v_mfma_f32_16x16x32_f16 v[76:79], v[144:147], v[104:107], v[76:79]
	global_load_dwordx4 v[104:107], v[2:3], off offset:384
	global_load_dwordx4 v[154:157], v[4:5], off offset:384
	global_load_dwordx4 v[158:161], v[6:7], off offset:384
	global_load_dwordx4 v[58:61], v[8:9], off offset:384
	global_load_dwordx4 v[188:191], v[10:11], off offset:384
	global_load_dwordx4 v[192:195], v[12:13], off offset:384
	global_load_dwordx4 v[196:199], v[14:15], off offset:384
	s_waitcnt lgkmcnt(0)
	s_barrier
; #define GL_LOAD(s_, kt_) if (VAR != 1) { a##s_##0 = GL_A(0, kt_); a##s_##1 = GL_A(1, kt_); a##s_##2 = GL_A(2, kt_); a##s_##3 = GL_A(3, kt_); b##s_##0 = GL_B(0, kt_); b##s_##1 = GL_B(1, kt_); b##s_##2 = GL_B(2, kt_); b##s_##3 = GL_B(3, kt_); }
; #define LDS_STORE(s_, buf_) if (VAR != 2) { LDS_ST1(sA, 0, buf_, a##s_##0) LDS_ST1(sA, 1, buf_, a##s_##1) LDS_ST1(sA, 2, buf_, a##s_##2) LDS_ST1(sA, 3, buf_, a##s_##3) LDS_ST1(sB, 0, buf_, b##s_##0) LDS_ST1(sB, 1, buf_, b##s_##1) LDS_ST1(sB, 2, buf_, b##s_##2) LDS_ST1(sB, 3, buf_, b##s_##3) }
;     ...
;   for (int kt = 0; kt < nk; kt += 2) {
;     if (kt + 2 < nk) { GL_LOAD(0, kt + 2) }
;     MMA_TILE(0)
;     LDS_STORE(1, 1)
;     if (VAR != 4) __syncthreads();
;     if (kt + 3 < nk) { GL_LOAD(1, kt + 3) }
;     MMA_TILE(1)
;     if (kt + 2 < nk) { LDS_STORE(0, 0) }
;     if (VAR != 4) __syncthreads();
	v_mfma_f32_16x16x32_f16 v[50:53], v[144:147], v[120:123], v[50:53]
	ds_read_b128 v[124:127], v16 offset:32768
	ds_read_b128 v[136:139], v21
	s_waitcnt lgkmcnt(0)
	v_mfma_f32_16x16x32_f16 v[38:41], v[124:127], v[136:139], v[38:41]
	ds_read_b128 v[120:123], v16 offset:34816
	ds_read_b128 v[144:147], v21 offset:2048
	s_waitcnt lgkmcnt(0)
	v_mfma_f32_16x16x32_f16 v[80:83], v[124:127], v[144:147], v[80:83]
	ds_read_b128 v[162:165], v16 offset:36864
	v_mfma_f32_16x16x32_f16 v[46:49], v[120:123], v[136:139], v[46:49]
	ds_read_b128 v[166:169], v16 offset:38912
	v_mfma_f32_16x16x32_f16 v[112:115], v[120:123], v[144:147], v[112:115]
	s_waitcnt vmcnt(7)
	ds_write_b128 v17, v[54:57] offset:16384
	s_waitcnt lgkmcnt(2)
	v_mfma_f32_16x16x32_f16 v[108:111], v[162:165], v[136:139], v[108:111]
	s_waitcnt vmcnt(6)
	ds_write_b128 v18, v[104:107] offset:16384
	v_mfma_f32_16x16x32_f16 v[116:119], v[162:165], v[144:147], v[116:119]
	s_waitcnt vmcnt(5)
	ds_write_b128 v19, v[154:157] offset:16384
	s_waitcnt lgkmcnt(3)
	v_mfma_f32_16x16x32_f16 v[72:75], v[166:169], v[136:139], v[72:75]
	ds_read_b128 v[136:139], v21 offset:4096
	v_mfma_f32_16x16x32_f16 v[34:37], v[166:169], v[144:147], v[34:37]
	ds_read_b128 v[144:147], v21 offset:6144
	s_waitcnt lgkmcnt(1)
	v_mfma_f32_16x16x32_f16 v[128:131], v[124:127], v[136:139], v[128:131]
	s_waitcnt vmcnt(4)
	ds_write_b128 v20, v[158:161] offset:16384
	s_waitcnt lgkmcnt(1)
	v_mfma_f32_16x16x32_f16 v[42:45], v[124:127], v[144:147], v[42:45]
	ds_read_b128 v[124:127], v22 offset:34816
	v_mfma_f32_16x16x32_f16 v[132:135], v[120:123], v[136:139], v[132:135]
	s_waitcnt vmcnt(3)
	ds_write_b128 v17, v[58:61] offset:49152
	v_mfma_f32_16x16x32_f16 v[24:27], v[120:123], v[144:147], v[24:27]
	ds_read_b128 v[120:123], v22 offset:32768
	v_mfma_f32_16x16x32_f16 v[140:143], v[162:165], v[136:139], v[140:143]
	s_waitcnt vmcnt(2)
	ds_write_b128 v18, v[188:191] offset:49152
	v_mfma_f32_16x16x32_f16 v[28:31], v[162:165], v[144:147], v[28:31]
	ds_read_b128 v[162:165], v22 offset:36864
	v_mfma_f32_16x16x32_f16 v[76:79], v[166:169], v[136:139], v[76:79]
	ds_read_b128 v[136:139], v32
	v_mfma_f32_16x16x32_f16 v[50:53], v[166:169], v[144:147], v[50:53]
	ds_read_b128 v[144:147], v32 offset:2048
	s_waitcnt lgkmcnt(1)
	v_mfma_f32_16x16x32_f16 v[38:41], v[120:123], v[136:139], v[38:41]
	ds_read_b128 v[166:169], v22 offset:38912
	s_waitcnt lgkmcnt(1)
	v_mfma_f32_16x16x32_f16 v[80:83], v[120:123], v[144:147], v[80:83]
	s_waitcnt vmcnt(1)
	ds_write_b128 v19, v[192:195] offset:49152
	v_mfma_f32_16x16x32_f16 v[46:49], v[124:127], v[136:139], v[46:49]
	s_waitcnt vmcnt(0)
	ds_write_b128 v20, v[196:199] offset:49152
	v_mfma_f32_16x16x32_f16 v[112:115], v[124:127], v[144:147], v[112:115]
	v_mfma_f32_16x16x32_f16 v[108:111], v[162:165], v[136:139], v[108:111]
	v_mfma_f32_16x16x32_f16 v[116:119], v[162:165], v[144:147], v[116:119]
	s_waitcnt lgkmcnt(2)
	v_mfma_f32_16x16x32_f16 v[72:75], v[166:169], v[136:139], v[72:75]
	ds_read_b128 v[136:139], v32 offset:4096
	v_mfma_f32_16x16x32_f16 v[34:37], v[166:169], v[144:147], v[34:37]
	ds_read_b128 v[144:147], v32 offset:6144
	s_waitcnt lgkmcnt(1)
	v_mfma_f32_16x16x32_f16 v[128:131], v[120:123], v[136:139], v[128:131]
	s_waitcnt lgkmcnt(0)
	v_mfma_f32_16x16x32_f16 v[42:45], v[120:123], v[144:147], v[42:45]
	global_load_dwordx4 v[120:123], v[0:1], off offset:512
	v_mfma_f32_16x16x32_f16 v[132:135], v[124:127], v[136:139], v[132:135]
	v_mfma_f32_16x16x32_f16 v[24:27], v[124:127], v[144:147], v[24:27]
	v_mfma_f32_16x16x32_f16 v[140:143], v[162:165], v[136:139], v[140:143]
	v_mfma_f32_16x16x32_f16 v[28:31], v[162:165], v[144:147], v[28:31]
	v_mfma_f32_16x16x32_f16 v[76:79], v[166:169], v[136:139], v[76:79]
	global_load_dwordx4 v[136:139], v[2:3], off offset:512
	global_load_dwordx4 v[200:203], v[4:5], off offset:512
	global_load_dwordx4 v[204:207], v[6:7], off offset:512
	global_load_dwordx4 v[124:127], v[8:9], off offset:512
	global_load_dwordx4 v[208:211], v[10:11], off offset:512
	global_load_dwordx4 v[212:215], v[12:13], off offset:512
	global_load_dwordx4 v[220:223], v[14:15], off offset:512
	s_waitcnt lgkmcnt(0)
	s_barrier
	v_mfma_f32_16x16x32_f16 v[50:53], v[166:169], v[144:147], v[50:53]
	ds_read_b128 v[54:57], v16 offset:49152
	ds_read_b128 v[104:107], v21 offset:16384
	s_waitcnt lgkmcnt(0)
	v_mfma_f32_16x16x32_f16 v[38:41], v[54:57], v[104:107], v[38:41]
	ds_read_b128 v[58:61], v16 offset:51200
	ds_read_b128 v[144:147], v21 offset:18432
	s_waitcnt lgkmcnt(0)
	v_mfma_f32_16x16x32_f16 v[80:83], v[54:57], v[144:147], v[80:83]
	ds_read_b128 v[154:157], v16 offset:53248
	v_mfma_f32_16x16x32_f16 v[46:49], v[58:61], v[104:107], v[46:49]
	ds_read_b128 v[158:161], v16 offset:55296
	s_waitcnt lgkmcnt(1)
	v_mfma_f32_16x16x32_f16 v[108:111], v[154:157], v[104:107], v[108:111]
	s_waitcnt lgkmcnt(0)
	v_mfma_f32_16x16x32_f16 v[72:75], v[158:161], v[104:107], v[72:75]
	v_mfma_f32_16x16x32_f16 v[104:107], v[58:61], v[144:147], v[112:115]
	s_waitcnt vmcnt(7)
	ds_write_b128 v17, v[120:123]
	s_waitcnt vmcnt(6)
	ds_write_b128 v18, v[136:139]
	v_mfma_f32_16x16x32_f16 v[112:115], v[154:157], v[144:147], v[116:119]
	s_nop 2
	ds_read_b128 v[116:119], v21 offset:20480
	s_waitcnt vmcnt(5)
	ds_write_b128 v19, v[200:203]
	v_mfma_f32_16x16x32_f16 v[34:37], v[158:161], v[144:147], v[34:37]
	ds_read_b128 v[144:147], v21 offset:22528
	s_waitcnt lgkmcnt(2)
	v_mfma_f32_16x16x32_f16 v[128:131], v[54:57], v[116:119], v[128:131]
	s_waitcnt vmcnt(4)
	ds_write_b128 v20, v[204:207]
	s_waitcnt lgkmcnt(1)
	v_mfma_f32_16x16x32_f16 v[42:45], v[54:57], v[144:147], v[42:45]
	ds_read_b128 v[54:57], v22 offset:49152
	v_mfma_f32_16x16x32_f16 v[132:135], v[58:61], v[116:119], v[132:135]
	s_waitcnt vmcnt(3)
; #define GL_LOAD(s_, kt_) if (VAR != 1) { a##s_##0 = GL_A(0, kt_); a##s_##1 = GL_A(1, kt_); a##s_##2 = GL_A(2, kt_); a##s_##3 = GL_A(3, kt_); b##s_##0 = GL_B(0, kt_); b##s_##1 = GL_B(1, kt_); b##s_##2 = GL_B(2, kt_); b##s_##3 = GL_B(3, kt_); }
; #define LDS_STORE(s_, buf_) if (VAR != 2) { LDS_ST1(sA, 0, buf_, a##s_##0) LDS_ST1(sA, 1, buf_, a##s_##1) LDS_ST1(sA, 2, buf_, a##s_##2) LDS_ST1(sA, 3, buf_, a##s_##3) LDS_ST1(sB, 0, buf_, b##s_##0) LDS_ST1(sB, 1, buf_, b##s_##1) LDS_ST1(sB, 2, buf_, b##s_##2) LDS_ST1(sB, 3, buf_, b##s_##3) }
;     ...
;   for (int kt = 0; kt < nk; kt += 2) {
;     if (kt + 2 < nk) { GL_LOAD(0, kt + 2) }
;     MMA_TILE(0)
;     LDS_STORE(1, 1)
;     if (VAR != 4) __syncthreads();
;     if (kt + 3 < nk) { GL_LOAD(1, kt + 3) }
;     MMA_TILE(1)
;     if (kt + 2 < nk) { LDS_STORE(0, 0) }
;     if (VAR != 4) __syncthreads();
	ds_write_b128 v17, v[124:127] offset:32768
	v_mfma_f32_16x16x32_f16 v[24:27], v[58:61], v[144:147], v[24:27]
	ds_read_b128 v[58:61], v22 offset:51200
	v_mfma_f32_16x16x32_f16 v[140:143], v[154:157], v[116:119], v[140:143]
	s_waitcnt vmcnt(2)
	ds_write_b128 v18, v[208:211] offset:32768
	v_mfma_f32_16x16x32_f16 v[28:31], v[154:157], v[144:147], v[28:31]
	ds_read_b128 v[154:157], v22 offset:53248
	v_mfma_f32_16x16x32_f16 v[76:79], v[158:161], v[116:119], v[76:79]
	ds_read_b128 v[116:119], v32 offset:16384
	v_mfma_f32_16x16x32_f16 v[50:53], v[158:161], v[144:147], v[50:53]
	ds_read_b128 v[144:147], v32 offset:18432
	s_waitcnt lgkmcnt(1)
	v_mfma_f32_16x16x32_f16 v[38:41], v[54:57], v[116:119], v[38:41]
	ds_read_b128 v[158:161], v22 offset:55296
	s_waitcnt lgkmcnt(1)
	v_mfma_f32_16x16x32_f16 v[80:83], v[54:57], v[144:147], v[80:83]
	s_waitcnt vmcnt(1)
	ds_write_b128 v19, v[212:215] offset:32768
	v_mfma_f32_16x16x32_f16 v[46:49], v[58:61], v[116:119], v[46:49]
	s_waitcnt vmcnt(0)
	ds_write_b128 v20, v[220:223] offset:32768
	v_mfma_f32_16x16x32_f16 v[104:107], v[58:61], v[144:147], v[104:107]
	v_mfma_f32_16x16x32_f16 v[108:111], v[154:157], v[116:119], v[108:111]
	v_mfma_f32_16x16x32_f16 v[112:115], v[154:157], v[144:147], v[112:115]
	s_waitcnt lgkmcnt(2)
	v_mfma_f32_16x16x32_f16 v[72:75], v[158:161], v[116:119], v[72:75]
	ds_read_b128 v[116:119], v32 offset:20480
	v_mfma_f32_16x16x32_f16 v[34:37], v[158:161], v[144:147], v[34:37]
	ds_read_b128 v[144:147], v32 offset:22528
	s_waitcnt lgkmcnt(1)
	v_mfma_f32_16x16x32_f16 v[128:131], v[54:57], v[116:119], v[128:131]
	s_waitcnt lgkmcnt(0)
	v_mfma_f32_16x16x32_f16 v[42:45], v[54:57], v[144:147], v[42:45]
	global_load_dwordx4 v[54:57], v[0:1], off offset:640
	v_mfma_f32_16x16x32_f16 v[132:135], v[58:61], v[116:119], v[132:135]
	v_mfma_f32_16x16x32_f16 v[24:27], v[58:61], v[144:147], v[24:27]
	v_mfma_f32_16x16x32_f16 v[140:143], v[154:157], v[116:119], v[140:143]
	v_mfma_f32_16x16x32_f16 v[28:31], v[154:157], v[144:147], v[28:31]
	v_mfma_f32_16x16x32_f16 v[76:79], v[158:161], v[116:119], v[76:79]
	global_load_dwordx4 v[116:119], v[2:3], off offset:640
	global_load_dwordx4 v[162:165], v[4:5], off offset:640
	global_load_dwordx4 v[166:169], v[6:7], off offset:640
	global_load_dwordx4 v[58:61], v[8:9], off offset:640
	global_load_dwordx4 v[188:191], v[10:11], off offset:640
	global_load_dwordx4 v[192:195], v[12:13], off offset:640
	global_load_dwordx4 v[196:199], v[14:15], off offset:640
	s_waitcnt lgkmcnt(0)
	s_barrier
	v_mfma_f32_16x16x32_f16 v[50:53], v[158:161], v[144:147], v[50:53]
	ds_read_b128 v[120:123], v16 offset:32768
	ds_read_b128 v[136:139], v21
	s_waitcnt lgkmcnt(0)
	v_mfma_f32_16x16x32_f16 v[38:41], v[120:123], v[136:139], v[38:41]
	ds_read_b128 v[124:127], v16 offset:34816
	ds_read_b128 v[144:147], v21 offset:2048
	s_waitcnt lgkmcnt(0)
	v_mfma_f32_16x16x32_f16 v[80:83], v[120:123], v[144:147], v[80:83]
	ds_read_b128 v[154:157], v16 offset:36864
	v_mfma_f32_16x16x32_f16 v[46:49], v[124:127], v[136:139], v[46:49]
	ds_read_b128 v[158:161], v16 offset:38912
	v_mfma_f32_16x16x32_f16 v[104:107], v[124:127], v[144:147], v[104:107]
	s_waitcnt vmcnt(7)
	ds_write_b128 v17, v[54:57] offset:16384
	s_waitcnt lgkmcnt(2)
	v_mfma_f32_16x16x32_f16 v[108:111], v[154:157], v[136:139], v[108:111]
	s_waitcnt vmcnt(6)
	ds_write_b128 v18, v[116:119] offset:16384
	v_mfma_f32_16x16x32_f16 v[112:115], v[154:157], v[144:147], v[112:115]
	s_waitcnt vmcnt(5)
	ds_write_b128 v19, v[162:165] offset:16384
	s_waitcnt lgkmcnt(3)
	v_mfma_f32_16x16x32_f16 v[72:75], v[158:161], v[136:139], v[72:75]
	ds_read_b128 v[136:139], v21 offset:4096
	v_mfma_f32_16x16x32_f16 v[34:37], v[158:161], v[144:147], v[34:37]
	ds_read_b128 v[144:147], v21 offset:6144
	s_waitcnt lgkmcnt(1)
	v_mfma_f32_16x16x32_f16 v[128:131], v[120:123], v[136:139], v[128:131]
	s_waitcnt vmcnt(4)
	ds_write_b128 v20, v[166:169] offset:16384
	s_waitcnt lgkmcnt(1)
	v_mfma_f32_16x16x32_f16 v[42:45], v[120:123], v[144:147], v[42:45]
	ds_read_b128 v[120:123], v22 offset:32768
	v_mfma_f32_16x16x32_f16 v[132:135], v[124:127], v[136:139], v[132:135]
	s_waitcnt vmcnt(3)
	ds_write_b128 v17, v[58:61] offset:49152
	v_mfma_f32_16x16x32_f16 v[24:27], v[124:127], v[144:147], v[24:27]
	ds_read_b128 v[124:127], v22 offset:34816
	v_mfma_f32_16x16x32_f16 v[140:143], v[154:157], v[136:139], v[140:143]
	s_waitcnt vmcnt(2)
	ds_write_b128 v18, v[188:191] offset:49152
	v_mfma_f32_16x16x32_f16 v[28:31], v[154:157], v[144:147], v[28:31]
	ds_read_b128 v[154:157], v22 offset:36864
	v_mfma_f32_16x16x32_f16 v[76:79], v[158:161], v[136:139], v[76:79]
	ds_read_b128 v[136:139], v32
	v_mfma_f32_16x16x32_f16 v[50:53], v[158:161], v[144:147], v[50:53]
	ds_read_b128 v[144:147], v32 offset:2048
	s_waitcnt lgkmcnt(1)
	v_mfma_f32_16x16x32_f16 v[38:41], v[120:123], v[136:139], v[38:41]
	ds_read_b128 v[158:161], v22 offset:38912
	s_waitcnt lgkmcnt(1)
	v_mfma_f32_16x16x32_f16 v[80:83], v[120:123], v[144:147], v[80:83]
	s_waitcnt vmcnt(1)
	ds_write_b128 v19, v[192:195] offset:49152
	v_mfma_f32_16x16x32_f16 v[46:49], v[124:127], v[136:139], v[46:49]
	s_waitcnt vmcnt(0)
	ds_write_b128 v20, v[196:199] offset:49152
	v_mfma_f32_16x16x32_f16 v[104:107], v[124:127], v[144:147], v[104:107]
	v_mfma_f32_16x16x32_f16 v[108:111], v[154:157], v[136:139], v[108:111]
	v_mfma_f32_16x16x32_f16 v[112:115], v[154:157], v[144:147], v[112:115]
	s_waitcnt lgkmcnt(2)
	v_mfma_f32_16x16x32_f16 v[72:75], v[158:161], v[136:139], v[72:75]
	ds_read_b128 v[136:139], v32 offset:4096
	v_mfma_f32_16x16x32_f16 v[34:37], v[158:161], v[144:147], v[34:37]
	ds_read_b128 v[144:147], v32 offset:6144
	s_waitcnt lgkmcnt(1)
	v_mfma_f32_16x16x32_f16 v[128:131], v[120:123], v[136:139], v[128:131]
	s_waitcnt lgkmcnt(0)
	v_mfma_f32_16x16x32_f16 v[42:45], v[120:123], v[144:147], v[42:45]
	global_load_dwordx4 v[120:123], v[0:1], off offset:768
	v_mfma_f32_16x16x32_f16 v[132:135], v[124:127], v[136:139], v[132:135]
	v_mfma_f32_16x16x32_f16 v[24:27], v[124:127], v[144:147], v[24:27]
	v_mfma_f32_16x16x32_f16 v[140:143], v[154:157], v[136:139], v[140:143]
	v_mfma_f32_16x16x32_f16 v[28:31], v[154:157], v[144:147], v[28:31]
	v_mfma_f32_16x16x32_f16 v[76:79], v[158:161], v[136:139], v[76:79]
	global_load_dwordx4 v[136:139], v[2:3], off offset:768
	global_load_dwordx4 v[200:203], v[4:5], off offset:768
	global_load_dwordx4 v[204:207], v[6:7], off offset:768
	global_load_dwordx4 v[124:127], v[8:9], off offset:768
	global_load_dwordx4 v[208:211], v[10:11], off offset:768
	global_load_dwordx4 v[212:215], v[12:13], off offset:768
	global_load_dwordx4 v[220:223], v[14:15], off offset:768
	s_waitcnt lgkmcnt(0)
	s_barrier
; #define GL_LOAD(s_, kt_) if (VAR != 1) { a##s_##0 = GL_A(0, kt_); a##s_##1 = GL_A(1, kt_); a##s_##2 = GL_A(2, kt_); a##s_##3 = GL_A(3, kt_); b##s_##0 = GL_B(0, kt_); b##s_##1 = GL_B(1, kt_); b##s_##2 = GL_B(2, kt_); b##s_##3 = GL_B(3, kt_); }
; #define LDS_STORE(s_, buf_) if (VAR != 2) { LDS_ST1(sA, 0, buf_, a##s_##0) LDS_ST1(sA, 1, buf_, a##s_##1) LDS_ST1(sA, 2, buf_, a##s_##2) LDS_ST1(sA, 3, buf_, a##s_##3) LDS_ST1(sB, 0, buf_, b##s_##0) LDS_ST1(sB, 1, buf_, b##s_##1) LDS_ST1(sB, 2, buf_, b##s_##2) LDS_ST1(sB, 3, buf_, b##s_##3) }
;     ...
;   for (int kt = 0; kt < nk; kt += 2) {
;     if (kt + 2 < nk) { GL_LOAD(0, kt + 2) }
;     MMA_TILE(0)
;     LDS_STORE(1, 1)
;     if (VAR != 4) __syncthreads();
;     if (kt + 3 < nk) { GL_LOAD(1, kt + 3) }
;     MMA_TILE(1)
;     if (kt + 2 < nk) { LDS_STORE(0, 0) }
;     if (VAR != 4) __syncthreads();
	v_mfma_f32_16x16x32_f16 v[50:53], v[158:161], v[144:147], v[50:53]
	ds_read_b128 v[54:57], v16 offset:49152
	ds_read_b128 v[116:119], v21 offset:16384
	s_waitcnt lgkmcnt(0)
	v_mfma_f32_16x16x32_f16 v[38:41], v[54:57], v[116:119], v[38:41]
	ds_read_b128 v[58:61], v16 offset:51200
	ds_read_b128 v[144:147], v21 offset:18432
	s_waitcnt lgkmcnt(0)
	v_mfma_f32_16x16x32_f16 v[80:83], v[54:57], v[144:147], v[80:83]
	ds_read_b128 v[154:157], v16 offset:53248
	v_mfma_f32_16x16x32_f16 v[46:49], v[58:61], v[116:119], v[46:49]
	ds_read_b128 v[158:161], v16 offset:55296
	v_mfma_f32_16x16x32_f16 v[104:107], v[58:61], v[144:147], v[104:107]
	s_waitcnt vmcnt(7)
	ds_write_b128 v17, v[120:123]
	s_waitcnt lgkmcnt(2)
	v_mfma_f32_16x16x32_f16 v[108:111], v[154:157], v[116:119], v[108:111]
	s_waitcnt vmcnt(6)
	ds_write_b128 v18, v[136:139]
	v_mfma_f32_16x16x32_f16 v[112:115], v[154:157], v[144:147], v[112:115]
	s_waitcnt vmcnt(5)
	ds_write_b128 v19, v[200:203]
	s_waitcnt lgkmcnt(3)
	v_mfma_f32_16x16x32_f16 v[72:75], v[158:161], v[116:119], v[72:75]
	ds_read_b128 v[116:119], v21 offset:20480
	v_mfma_f32_16x16x32_f16 v[34:37], v[158:161], v[144:147], v[34:37]
	ds_read_b128 v[144:147], v21 offset:22528
	s_waitcnt lgkmcnt(1)
	v_mfma_f32_16x16x32_f16 v[128:131], v[54:57], v[116:119], v[128:131]
	s_waitcnt vmcnt(4)
	ds_write_b128 v20, v[204:207]
	s_waitcnt lgkmcnt(1)
	v_mfma_f32_16x16x32_f16 v[42:45], v[54:57], v[144:147], v[42:45]
	ds_read_b128 v[54:57], v22 offset:49152
	v_mfma_f32_16x16x32_f16 v[132:135], v[58:61], v[116:119], v[132:135]
	s_waitcnt vmcnt(3)
	ds_write_b128 v17, v[124:127] offset:32768
	v_mfma_f32_16x16x32_f16 v[24:27], v[58:61], v[144:147], v[24:27]
	ds_read_b128 v[58:61], v22 offset:51200
	v_mfma_f32_16x16x32_f16 v[140:143], v[154:157], v[116:119], v[140:143]
	s_waitcnt vmcnt(2)
	ds_write_b128 v18, v[208:211] offset:32768
	v_mfma_f32_16x16x32_f16 v[28:31], v[154:157], v[144:147], v[28:31]
	ds_read_b128 v[154:157], v22 offset:53248
	v_mfma_f32_16x16x32_f16 v[76:79], v[158:161], v[116:119], v[76:79]
	ds_read_b128 v[116:119], v32 offset:16384
	v_mfma_f32_16x16x32_f16 v[50:53], v[158:161], v[144:147], v[50:53]
	ds_read_b128 v[144:147], v32 offset:18432
	s_waitcnt lgkmcnt(1)
	v_mfma_f32_16x16x32_f16 v[38:41], v[54:57], v[116:119], v[38:41]
	ds_read_b128 v[158:161], v22 offset:55296
	s_waitcnt lgkmcnt(1)
	v_mfma_f32_16x16x32_f16 v[80:83], v[54:57], v[144:147], v[80:83]
	s_waitcnt vmcnt(1)
	ds_write_b128 v19, v[212:215] offset:32768
	v_mfma_f32_16x16x32_f16 v[46:49], v[58:61], v[116:119], v[46:49]
	s_waitcnt vmcnt(0)
	ds_write_b128 v20, v[220:223] offset:32768
	v_mfma_f32_16x16x32_f16 v[104:107], v[58:61], v[144:147], v[104:107]
	v_mfma_f32_16x16x32_f16 v[108:111], v[154:157], v[116:119], v[108:111]
	v_mfma_f32_16x16x32_f16 v[112:115], v[154:157], v[144:147], v[112:115]
	s_waitcnt lgkmcnt(2)
	v_mfma_f32_16x16x32_f16 v[72:75], v[158:161], v[116:119], v[72:75]
	ds_read_b128 v[116:119], v32 offset:20480
	v_mfma_f32_16x16x32_f16 v[34:37], v[158:161], v[144:147], v[34:37]
	ds_read_b128 v[144:147], v32 offset:22528
	s_waitcnt lgkmcnt(1)
	v_mfma_f32_16x16x32_f16 v[128:131], v[54:57], v[116:119], v[128:131]
	s_waitcnt lgkmcnt(0)
	v_mfma_f32_16x16x32_f16 v[42:45], v[54:57], v[144:147], v[42:45]
	global_load_dwordx4 v[54:57], v[0:1], off offset:896
	v_mfma_f32_16x16x32_f16 v[132:135], v[58:61], v[116:119], v[132:135]
	v_mfma_f32_16x16x32_f16 v[24:27], v[58:61], v[144:147], v[24:27]
	v_mfma_f32_16x16x32_f16 v[140:143], v[154:157], v[116:119], v[140:143]
	v_mfma_f32_16x16x32_f16 v[28:31], v[154:157], v[144:147], v[28:31]
	v_mfma_f32_16x16x32_f16 v[76:79], v[158:161], v[116:119], v[76:79]
	global_load_dwordx4 v[116:119], v[2:3], off offset:896
	global_load_dwordx4 v[162:165], v[4:5], off offset:896
	global_load_dwordx4 v[166:169], v[6:7], off offset:896
	global_load_dwordx4 v[58:61], v[8:9], off offset:896
	global_load_dwordx4 v[188:191], v[10:11], off offset:896
	global_load_dwordx4 v[192:195], v[12:13], off offset:896
	global_load_dwordx4 v[196:199], v[14:15], off offset:896
	s_waitcnt lgkmcnt(0)
	s_barrier
	v_mfma_f32_16x16x32_f16 v[50:53], v[158:161], v[144:147], v[50:53]
	ds_read_b128 v[120:123], v16 offset:32768
	ds_read_b128 v[136:139], v21
	s_waitcnt lgkmcnt(0)
	v_mfma_f32_16x16x32_f16 v[38:41], v[120:123], v[136:139], v[38:41]
	ds_read_b128 v[124:127], v16 offset:34816
	ds_read_b128 v[144:147], v21 offset:2048
	s_waitcnt lgkmcnt(0)
	v_mfma_f32_16x16x32_f16 v[80:83], v[120:123], v[144:147], v[80:83]
	ds_read_b128 v[154:157], v16 offset:36864
	v_mfma_f32_16x16x32_f16 v[46:49], v[124:127], v[136:139], v[46:49]
	ds_read_b128 v[158:161], v16 offset:38912
	v_mfma_f32_16x16x32_f16 v[104:107], v[124:127], v[144:147], v[104:107]
	s_waitcnt vmcnt(7)
	ds_write_b128 v17, v[54:57] offset:16384
	s_waitcnt lgkmcnt(2)
	v_mfma_f32_16x16x32_f16 v[108:111], v[154:157], v[136:139], v[108:111]
	s_waitcnt vmcnt(6)
	ds_write_b128 v18, v[116:119] offset:16384
	v_mfma_f32_16x16x32_f16 v[112:115], v[154:157], v[144:147], v[112:115]
	s_waitcnt vmcnt(5)
	ds_write_b128 v19, v[162:165] offset:16384
	s_waitcnt lgkmcnt(3)
	v_mfma_f32_16x16x32_f16 v[72:75], v[158:161], v[136:139], v[72:75]
	ds_read_b128 v[136:139], v21 offset:4096
	v_mfma_f32_16x16x32_f16 v[34:37], v[158:161], v[144:147], v[34:37]
	ds_read_b128 v[144:147], v21 offset:6144
	s_waitcnt lgkmcnt(1)
	v_mfma_f32_16x16x32_f16 v[128:131], v[120:123], v[136:139], v[128:131]
	s_waitcnt vmcnt(4)
	ds_write_b128 v20, v[166:169] offset:16384
	s_waitcnt lgkmcnt(1)
	v_mfma_f32_16x16x32_f16 v[42:45], v[120:123], v[144:147], v[42:45]
	ds_read_b128 v[120:123], v22 offset:32768
	v_mfma_f32_16x16x32_f16 v[132:135], v[124:127], v[136:139], v[132:135]
	s_waitcnt vmcnt(3)
; #define GL_LOAD(s_, kt_) if (VAR != 1) { a##s_##0 = GL_A(0, kt_); a##s_##1 = GL_A(1, kt_); a##s_##2 = GL_A(2, kt_); a##s_##3 = GL_A(3, kt_); b##s_##0 = GL_B(0, kt_); b##s_##1 = GL_B(1, kt_); b##s_##2 = GL_B(2, kt_); b##s_##3 = GL_B(3, kt_); }
; #define LDS_STORE(s_, buf_) if (VAR != 2) { LDS_ST1(sA, 0, buf_, a##s_##0) LDS_ST1(sA, 1, buf_, a##s_##1) LDS_ST1(sA, 2, buf_, a##s_##2) LDS_ST1(sA, 3, buf_, a##s_##3) LDS_ST1(sB, 0, buf_, b##s_##0) LDS_ST1(sB, 1, buf_, b##s_##1) LDS_ST1(sB, 2, buf_, b##s_##2) LDS_ST1(sB, 3, buf_, b##s_##3) }
;     ...
;   for (int kt = 0; kt < nk; kt += 2) {
;     if (kt + 2 < nk) { GL_LOAD(0, kt + 2) }
;     MMA_TILE(0)
;     LDS_STORE(1, 1)
;     if (VAR != 4) __syncthreads();
;     if (kt + 3 < nk) { GL_LOAD(1, kt + 3) }
;     MMA_TILE(1)
;     if (kt + 2 < nk) { LDS_STORE(0, 0) }
;     if (VAR != 4) __syncthreads();
	ds_write_b128 v17, v[58:61] offset:49152
	v_mfma_f32_16x16x32_f16 v[24:27], v[124:127], v[144:147], v[24:27]
	ds_read_b128 v[124:127], v22 offset:34816
	v_mfma_f32_16x16x32_f16 v[140:143], v[154:157], v[136:139], v[140:143]
	s_waitcnt vmcnt(2)
	ds_write_b128 v18, v[188:191] offset:49152
	v_mfma_f32_16x16x32_f16 v[28:31], v[154:157], v[144:147], v[28:31]
	ds_read_b128 v[154:157], v22 offset:36864
	v_mfma_f32_16x16x32_f16 v[76:79], v[158:161], v[136:139], v[76:79]
	ds_read_b128 v[136:139], v32
	v_mfma_f32_16x16x32_f16 v[50:53], v[158:161], v[144:147], v[50:53]
	ds_read_b128 v[144:147], v32 offset:2048
	s_waitcnt lgkmcnt(1)
	v_mfma_f32_16x16x32_f16 v[38:41], v[120:123], v[136:139], v[38:41]
	ds_read_b128 v[158:161], v22 offset:38912
	s_waitcnt lgkmcnt(1)
	v_mfma_f32_16x16x32_f16 v[80:83], v[120:123], v[144:147], v[80:83]
	s_waitcnt vmcnt(1)
	ds_write_b128 v19, v[192:195] offset:49152
	v_mfma_f32_16x16x32_f16 v[46:49], v[124:127], v[136:139], v[46:49]
	s_waitcnt vmcnt(0)
	ds_write_b128 v20, v[196:199] offset:49152
	v_mfma_f32_16x16x32_f16 v[104:107], v[124:127], v[144:147], v[104:107]
	v_mfma_f32_16x16x32_f16 v[108:111], v[154:157], v[136:139], v[108:111]
	v_mfma_f32_16x16x32_f16 v[112:115], v[154:157], v[144:147], v[112:115]
	s_waitcnt lgkmcnt(2)
	v_mfma_f32_16x16x32_f16 v[72:75], v[158:161], v[136:139], v[72:75]
	ds_read_b128 v[136:139], v32 offset:4096
	v_mfma_f32_16x16x32_f16 v[34:37], v[158:161], v[144:147], v[34:37]
	ds_read_b128 v[144:147], v32 offset:6144
	s_waitcnt lgkmcnt(1)
	v_mfma_f32_16x16x32_f16 v[128:131], v[120:123], v[136:139], v[128:131]
	s_waitcnt lgkmcnt(0)
	v_mfma_f32_16x16x32_f16 v[42:45], v[120:123], v[144:147], v[42:45]
	global_load_dwordx4 v[120:123], v[0:1], off offset:1024
	v_mfma_f32_16x16x32_f16 v[132:135], v[124:127], v[136:139], v[132:135]
	v_mfma_f32_16x16x32_f16 v[24:27], v[124:127], v[144:147], v[24:27]
	v_mfma_f32_16x16x32_f16 v[140:143], v[154:157], v[136:139], v[140:143]
	v_mfma_f32_16x16x32_f16 v[28:31], v[154:157], v[144:147], v[28:31]
	v_mfma_f32_16x16x32_f16 v[76:79], v[158:161], v[136:139], v[76:79]
	global_load_dwordx4 v[136:139], v[2:3], off offset:1024
	global_load_dwordx4 v[200:203], v[4:5], off offset:1024
	global_load_dwordx4 v[204:207], v[6:7], off offset:1024
	global_load_dwordx4 v[124:127], v[8:9], off offset:1024
	global_load_dwordx4 v[208:211], v[10:11], off offset:1024
	global_load_dwordx4 v[212:215], v[12:13], off offset:1024
	global_load_dwordx4 v[220:223], v[14:15], off offset:1024
	s_waitcnt lgkmcnt(0)
	s_barrier
	v_mfma_f32_16x16x32_f16 v[50:53], v[158:161], v[144:147], v[50:53]
	ds_read_b128 v[54:57], v16 offset:49152
	ds_read_b128 v[116:119], v21 offset:16384
	s_waitcnt lgkmcnt(0)
	v_mfma_f32_16x16x32_f16 v[38:41], v[54:57], v[116:119], v[38:41]
	ds_read_b128 v[58:61], v16 offset:51200
	ds_read_b128 v[144:147], v21 offset:18432
	s_waitcnt lgkmcnt(0)
	v_mfma_f32_16x16x32_f16 v[80:83], v[54:57], v[144:147], v[80:83]
	ds_read_b128 v[154:157], v16 offset:53248
	v_mfma_f32_16x16x32_f16 v[46:49], v[58:61], v[116:119], v[46:49]
	ds_read_b128 v[158:161], v16 offset:55296
	v_mfma_f32_16x16x32_f16 v[104:107], v[58:61], v[144:147], v[104:107]
	s_waitcnt vmcnt(7)
	ds_write_b128 v17, v[120:123]
	s_waitcnt lgkmcnt(2)
	v_mfma_f32_16x16x32_f16 v[108:111], v[154:157], v[116:119], v[108:111]
	s_waitcnt vmcnt(6)
	ds_write_b128 v18, v[136:139]
	v_mfma_f32_16x16x32_f16 v[112:115], v[154:157], v[144:147], v[112:115]
	s_waitcnt vmcnt(5)
	ds_write_b128 v19, v[200:203]
	s_waitcnt lgkmcnt(3)
	v_mfma_f32_16x16x32_f16 v[72:75], v[158:161], v[116:119], v[72:75]
	ds_read_b128 v[116:119], v21 offset:20480
	v_mfma_f32_16x16x32_f16 v[34:37], v[158:161], v[144:147], v[34:37]
	ds_read_b128 v[144:147], v21 offset:22528
	s_waitcnt lgkmcnt(1)
	v_mfma_f32_16x16x32_f16 v[128:131], v[54:57], v[116:119], v[128:131]
	s_waitcnt vmcnt(4)
	ds_write_b128 v20, v[204:207]
	s_waitcnt lgkmcnt(1)
	v_mfma_f32_16x16x32_f16 v[42:45], v[54:57], v[144:147], v[42:45]
	ds_read_b128 v[54:57], v22 offset:49152
	v_mfma_f32_16x16x32_f16 v[132:135], v[58:61], v[116:119], v[132:135]
	s_waitcnt vmcnt(3)
	ds_write_b128 v17, v[124:127] offset:32768
	v_mfma_f32_16x16x32_f16 v[24:27], v[58:61], v[144:147], v[24:27]
	ds_read_b128 v[58:61], v22 offset:51200
	v_mfma_f32_16x16x32_f16 v[140:143], v[154:157], v[116:119], v[140:143]
	s_waitcnt vmcnt(2)
	ds_write_b128 v18, v[208:211] offset:32768
	v_mfma_f32_16x16x32_f16 v[28:31], v[154:157], v[144:147], v[28:31]
	ds_read_b128 v[154:157], v22 offset:53248
	v_mfma_f32_16x16x32_f16 v[76:79], v[158:161], v[116:119], v[76:79]
	ds_read_b128 v[116:119], v32 offset:16384
	v_mfma_f32_16x16x32_f16 v[50:53], v[158:161], v[144:147], v[50:53]
	ds_read_b128 v[144:147], v32 offset:18432
	s_waitcnt lgkmcnt(1)
	v_mfma_f32_16x16x32_f16 v[38:41], v[54:57], v[116:119], v[38:41]
	ds_read_b128 v[158:161], v22 offset:55296
	s_waitcnt lgkmcnt(1)
	v_mfma_f32_16x16x32_f16 v[80:83], v[54:57], v[144:147], v[80:83]
	s_waitcnt vmcnt(1)
	ds_write_b128 v19, v[212:215] offset:32768
	v_mfma_f32_16x16x32_f16 v[46:49], v[58:61], v[116:119], v[46:49]
	s_waitcnt vmcnt(0)
	ds_write_b128 v20, v[220:223] offset:32768
	v_mfma_f32_16x16x32_f16 v[104:107], v[58:61], v[144:147], v[104:107]
	v_mfma_f32_16x16x32_f16 v[108:111], v[154:157], v[116:119], v[108:111]
	v_mfma_f32_16x16x32_f16 v[112:115], v[154:157], v[144:147], v[112:115]
	s_waitcnt lgkmcnt(2)
	v_mfma_f32_16x16x32_f16 v[72:75], v[158:161], v[116:119], v[72:75]
	ds_read_b128 v[116:119], v32 offset:20480
	v_mfma_f32_16x16x32_f16 v[34:37], v[158:161], v[144:147], v[34:37]
	ds_read_b128 v[144:147], v32 offset:22528
	s_waitcnt lgkmcnt(1)
	v_mfma_f32_16x16x32_f16 v[128:131], v[54:57], v[116:119], v[128:131]
	s_waitcnt lgkmcnt(0)
	v_mfma_f32_16x16x32_f16 v[42:45], v[54:57], v[144:147], v[42:45]
	global_load_dwordx4 v[54:57], v[0:1], off offset:1152
	v_mfma_f32_16x16x32_f16 v[132:135], v[58:61], v[116:119], v[132:135]
	v_mfma_f32_16x16x32_f16 v[24:27], v[58:61], v[144:147], v[24:27]
	v_mfma_f32_16x16x32_f16 v[140:143], v[154:157], v[116:119], v[140:143]
	v_mfma_f32_16x16x32_f16 v[28:31], v[154:157], v[144:147], v[28:31]
	v_mfma_f32_16x16x32_f16 v[76:79], v[158:161], v[116:119], v[76:79]
	global_load_dwordx4 v[116:119], v[2:3], off offset:1152
	global_load_dwordx4 v[162:165], v[4:5], off offset:1152
	global_load_dwordx4 v[166:169], v[6:7], off offset:1152
	global_load_dwordx4 v[58:61], v[8:9], off offset:1152
	global_load_dwordx4 v[188:191], v[10:11], off offset:1152
	global_load_dwordx4 v[192:195], v[12:13], off offset:1152
	global_load_dwordx4 v[196:199], v[14:15], off offset:1152
	s_waitcnt lgkmcnt(0)
	s_barrier
; #define GL_LOAD(s_, kt_) if (VAR != 1) { a##s_##0 = GL_A(0, kt_); a##s_##1 = GL_A(1, kt_); a##s_##2 = GL_A(2, kt_); a##s_##3 = GL_A(3, kt_); b##s_##0 = GL_B(0, kt_); b##s_##1 = GL_B(1, kt_); b##s_##2 = GL_B(2, kt_); b##s_##3 = GL_B(3, kt_); }
; #define LDS_STORE(s_, buf_) if (VAR != 2) { LDS_ST1(sA, 0, buf_, a##s_##0) LDS_ST1(sA, 1, buf_, a##s_##1) LDS_ST1(sA, 2, buf_, a##s_##2) LDS_ST1(sA, 3, buf_, a##s_##3) LDS_ST1(sB, 0, buf_, b##s_##0) LDS_ST1(sB, 1, buf_, b##s_##1) LDS_ST1(sB, 2, buf_, b##s_##2) LDS_ST1(sB, 3, buf_, b##s_##3) }
;     ...
;   for (int kt = 0; kt < nk; kt += 2) {
;     if (kt + 2 < nk) { GL_LOAD(0, kt + 2) }
;     MMA_TILE(0)
;     LDS_STORE(1, 1)
;     if (VAR != 4) __syncthreads();
;     if (kt + 3 < nk) { GL_LOAD(1, kt + 3) }
;     MMA_TILE(1)
;     if (kt + 2 < nk) { LDS_STORE(0, 0) }
;     if (VAR != 4) __syncthreads();
	v_mfma_f32_16x16x32_f16 v[50:53], v[158:161], v[144:147], v[50:53]
	ds_read_b128 v[120:123], v16 offset:32768
	ds_read_b128 v[136:139], v21
	s_waitcnt lgkmcnt(0)
	v_mfma_f32_16x16x32_f16 v[38:41], v[120:123], v[136:139], v[38:41]
	ds_read_b128 v[124:127], v16 offset:34816
	ds_read_b128 v[144:147], v21 offset:2048
	s_waitcnt lgkmcnt(0)
	v_mfma_f32_16x16x32_f16 v[80:83], v[120:123], v[144:147], v[80:83]
	ds_read_b128 v[154:157], v16 offset:36864
	v_mfma_f32_16x16x32_f16 v[46:49], v[124:127], v[136:139], v[46:49]
	ds_read_b128 v[158:161], v16 offset:38912
	v_mfma_f32_16x16x32_f16 v[104:107], v[124:127], v[144:147], v[104:107]
	s_waitcnt vmcnt(7)
	ds_write_b128 v17, v[54:57] offset:16384
	s_waitcnt lgkmcnt(2)
	v_mfma_f32_16x16x32_f16 v[108:111], v[154:157], v[136:139], v[108:111]
	s_waitcnt vmcnt(6)
	ds_write_b128 v18, v[116:119] offset:16384
	v_mfma_f32_16x16x32_f16 v[112:115], v[154:157], v[144:147], v[112:115]
	s_waitcnt vmcnt(5)
	ds_write_b128 v19, v[162:165] offset:16384
	s_waitcnt lgkmcnt(3)
	v_mfma_f32_16x16x32_f16 v[72:75], v[158:161], v[136:139], v[72:75]
	ds_read_b128 v[136:139], v21 offset:4096
	v_mfma_f32_16x16x32_f16 v[34:37], v[158:161], v[144:147], v[34:37]
	ds_read_b128 v[144:147], v21 offset:6144
	s_waitcnt lgkmcnt(1)
	v_mfma_f32_16x16x32_f16 v[128:131], v[120:123], v[136:139], v[128:131]
	s_waitcnt vmcnt(4)
	ds_write_b128 v20, v[166:169] offset:16384
	s_waitcnt lgkmcnt(1)
	v_mfma_f32_16x16x32_f16 v[42:45], v[120:123], v[144:147], v[42:45]
	ds_read_b128 v[120:123], v22 offset:32768
	v_mfma_f32_16x16x32_f16 v[132:135], v[124:127], v[136:139], v[132:135]
	s_waitcnt vmcnt(3)
	ds_write_b128 v17, v[58:61] offset:49152
	v_mfma_f32_16x16x32_f16 v[24:27], v[124:127], v[144:147], v[24:27]
	ds_read_b128 v[124:127], v22 offset:34816
	v_mfma_f32_16x16x32_f16 v[140:143], v[154:157], v[136:139], v[140:143]
	s_waitcnt vmcnt(2)
	ds_write_b128 v18, v[188:191] offset:49152
	v_mfma_f32_16x16x32_f16 v[28:31], v[154:157], v[144:147], v[28:31]
	ds_read_b128 v[154:157], v22 offset:36864
	v_mfma_f32_16x16x32_f16 v[76:79], v[158:161], v[136:139], v[76:79]
	ds_read_b128 v[136:139], v32
	v_mfma_f32_16x16x32_f16 v[50:53], v[158:161], v[144:147], v[50:53]
	ds_read_b128 v[144:147], v32 offset:2048
	s_waitcnt lgkmcnt(1)
	v_mfma_f32_16x16x32_f16 v[38:41], v[120:123], v[136:139], v[38:41]
	ds_read_b128 v[158:161], v22 offset:38912
	s_waitcnt lgkmcnt(1)
	v_mfma_f32_16x16x32_f16 v[80:83], v[120:123], v[144:147], v[80:83]
	s_waitcnt vmcnt(1)
	ds_write_b128 v19, v[192:195] offset:49152
	v_mfma_f32_16x16x32_f16 v[46:49], v[124:127], v[136:139], v[46:49]
	s_waitcnt vmcnt(0)
	ds_write_b128 v20, v[196:199] offset:49152
	v_mfma_f32_16x16x32_f16 v[104:107], v[124:127], v[144:147], v[104:107]
	v_mfma_f32_16x16x32_f16 v[108:111], v[154:157], v[136:139], v[108:111]
	v_mfma_f32_16x16x32_f16 v[112:115], v[154:157], v[144:147], v[112:115]
	s_waitcnt lgkmcnt(2)
	v_mfma_f32_16x16x32_f16 v[72:75], v[158:161], v[136:139], v[72:75]
	ds_read_b128 v[136:139], v32 offset:4096
	v_mfma_f32_16x16x32_f16 v[34:37], v[158:161], v[144:147], v[34:37]
	ds_read_b128 v[144:147], v32 offset:6144
	s_waitcnt lgkmcnt(1)
	v_mfma_f32_16x16x32_f16 v[128:131], v[120:123], v[136:139], v[128:131]
	s_waitcnt lgkmcnt(0)
	v_mfma_f32_16x16x32_f16 v[42:45], v[120:123], v[144:147], v[42:45]
	global_load_dwordx4 v[120:123], v[0:1], off offset:1280
	v_mfma_f32_16x16x32_f16 v[132:135], v[124:127], v[136:139], v[132:135]
	v_mfma_f32_16x16x32_f16 v[24:27], v[124:127], v[144:147], v[24:27]
	v_mfma_f32_16x16x32_f16 v[140:143], v[154:157], v[136:139], v[140:143]
	v_mfma_f32_16x16x32_f16 v[28:31], v[154:157], v[144:147], v[28:31]
	v_mfma_f32_16x16x32_f16 v[76:79], v[158:161], v[136:139], v[76:79]
	global_load_dwordx4 v[136:139], v[2:3], off offset:1280
	global_load_dwordx4 v[200:203], v[4:5], off offset:1280
	global_load_dwordx4 v[204:207], v[6:7], off offset:1280
	global_load_dwordx4 v[124:127], v[8:9], off offset:1280
	global_load_dwordx4 v[208:211], v[10:11], off offset:1280
	global_load_dwordx4 v[212:215], v[12:13], off offset:1280
	global_load_dwordx4 v[220:223], v[14:15], off offset:1280
	s_waitcnt lgkmcnt(0)
	s_barrier
	v_mfma_f32_16x16x32_f16 v[50:53], v[158:161], v[144:147], v[50:53]
	ds_read_b128 v[54:57], v16 offset:49152
	ds_read_b128 v[116:119], v21 offset:16384
	s_waitcnt lgkmcnt(0)
	v_mfma_f32_16x16x32_f16 v[38:41], v[54:57], v[116:119], v[38:41]
	ds_read_b128 v[58:61], v16 offset:51200
	ds_read_b128 v[144:147], v21 offset:18432
	s_waitcnt lgkmcnt(0)
	v_mfma_f32_16x16x32_f16 v[80:83], v[54:57], v[144:147], v[80:83]
	ds_read_b128 v[154:157], v16 offset:53248
	v_mfma_f32_16x16x32_f16 v[46:49], v[58:61], v[116:119], v[46:49]
	ds_read_b128 v[158:161], v16 offset:55296
	v_mfma_f32_16x16x32_f16 v[104:107], v[58:61], v[144:147], v[104:107]
	s_waitcnt vmcnt(7)
	ds_write_b128 v17, v[120:123]
	s_waitcnt lgkmcnt(2)
	v_mfma_f32_16x16x32_f16 v[108:111], v[154:157], v[116:119], v[108:111]
	s_waitcnt vmcnt(6)
	ds_write_b128 v18, v[136:139]
	v_mfma_f32_16x16x32_f16 v[112:115], v[154:157], v[144:147], v[112:115]
	s_waitcnt vmcnt(5)
	ds_write_b128 v19, v[200:203]
	s_waitcnt lgkmcnt(3)
	v_mfma_f32_16x16x32_f16 v[72:75], v[158:161], v[116:119], v[72:75]
	ds_read_b128 v[116:119], v21 offset:20480
	v_mfma_f32_16x16x32_f16 v[34:37], v[158:161], v[144:147], v[34:37]
	ds_read_b128 v[144:147], v21 offset:22528
	s_waitcnt lgkmcnt(1)
	v_mfma_f32_16x16x32_f16 v[128:131], v[54:57], v[116:119], v[128:131]
	s_waitcnt vmcnt(4)
	ds_write_b128 v20, v[204:207]
	s_waitcnt lgkmcnt(1)
	v_mfma_f32_16x16x32_f16 v[42:45], v[54:57], v[144:147], v[42:45]
	ds_read_b128 v[54:57], v22 offset:49152
	v_mfma_f32_16x16x32_f16 v[132:135], v[58:61], v[116:119], v[132:135]
	s_waitcnt vmcnt(3)
; #define GL_LOAD(s_, kt_) if (VAR != 1) { a##s_##0 = GL_A(0, kt_); a##s_##1 = GL_A(1, kt_); a##s_##2 = GL_A(2, kt_); a##s_##3 = GL_A(3, kt_); b##s_##0 = GL_B(0, kt_); b##s_##1 = GL_B(1, kt_); b##s_##2 = GL_B(2, kt_); b##s_##3 = GL_B(3, kt_); }
; #define LDS_STORE(s_, buf_) if (VAR != 2) { LDS_ST1(sA, 0, buf_, a##s_##0) LDS_ST1(sA, 1, buf_, a##s_##1) LDS_ST1(sA, 2, buf_, a##s_##2) LDS_ST1(sA, 3, buf_, a##s_##3) LDS_ST1(sB, 0, buf_, b##s_##0) LDS_ST1(sB, 1, buf_, b##s_##1) LDS_ST1(sB, 2, buf_, b##s_##2) LDS_ST1(sB, 3, buf_, b##s_##3) }
;     ...
;   for (int kt = 0; kt < nk; kt += 2) {
;     if (kt + 2 < nk) { GL_LOAD(0, kt + 2) }
;     MMA_TILE(0)
;     LDS_STORE(1, 1)
;     if (VAR != 4) __syncthreads();
;     if (kt + 3 < nk) { GL_LOAD(1, kt + 3) }
;     MMA_TILE(1)
;     if (kt + 2 < nk) { LDS_STORE(0, 0) }
;     if (VAR != 4) __syncthreads();
	ds_write_b128 v17, v[124:127] offset:32768
	v_mfma_f32_16x16x32_f16 v[24:27], v[58:61], v[144:147], v[24:27]
	ds_read_b128 v[58:61], v22 offset:51200
	v_mfma_f32_16x16x32_f16 v[140:143], v[154:157], v[116:119], v[140:143]
	s_waitcnt vmcnt(2)
	ds_write_b128 v18, v[208:211] offset:32768
	v_mfma_f32_16x16x32_f16 v[28:31], v[154:157], v[144:147], v[28:31]
	ds_read_b128 v[154:157], v22 offset:53248
	v_mfma_f32_16x16x32_f16 v[76:79], v[158:161], v[116:119], v[76:79]
	ds_read_b128 v[116:119], v32 offset:16384
	v_mfma_f32_16x16x32_f16 v[50:53], v[158:161], v[144:147], v[50:53]
	ds_read_b128 v[144:147], v32 offset:18432
	s_waitcnt lgkmcnt(1)
	v_mfma_f32_16x16x32_f16 v[38:41], v[54:57], v[116:119], v[38:41]
	ds_read_b128 v[158:161], v22 offset:55296
	s_waitcnt lgkmcnt(1)
	v_mfma_f32_16x16x32_f16 v[80:83], v[54:57], v[144:147], v[80:83]
	s_waitcnt vmcnt(1)
	ds_write_b128 v19, v[212:215] offset:32768
	v_mfma_f32_16x16x32_f16 v[46:49], v[58:61], v[116:119], v[46:49]
	s_waitcnt vmcnt(0)
	ds_write_b128 v20, v[220:223] offset:32768
	v_mfma_f32_16x16x32_f16 v[104:107], v[58:61], v[144:147], v[104:107]
	v_mfma_f32_16x16x32_f16 v[108:111], v[154:157], v[116:119], v[108:111]
	v_mfma_f32_16x16x32_f16 v[112:115], v[154:157], v[144:147], v[112:115]
	s_waitcnt lgkmcnt(2)
	v_mfma_f32_16x16x32_f16 v[72:75], v[158:161], v[116:119], v[72:75]
	ds_read_b128 v[116:119], v32 offset:20480
	v_mfma_f32_16x16x32_f16 v[34:37], v[158:161], v[144:147], v[34:37]
	ds_read_b128 v[144:147], v32 offset:22528
	s_waitcnt lgkmcnt(1)
	v_mfma_f32_16x16x32_f16 v[128:131], v[54:57], v[116:119], v[128:131]
	s_waitcnt lgkmcnt(0)
	v_mfma_f32_16x16x32_f16 v[42:45], v[54:57], v[144:147], v[42:45]
	global_load_dwordx4 v[54:57], v[0:1], off offset:1408
	v_mfma_f32_16x16x32_f16 v[132:135], v[58:61], v[116:119], v[132:135]
	v_mfma_f32_16x16x32_f16 v[24:27], v[58:61], v[144:147], v[24:27]
	v_mfma_f32_16x16x32_f16 v[140:143], v[154:157], v[116:119], v[140:143]
	v_mfma_f32_16x16x32_f16 v[28:31], v[154:157], v[144:147], v[28:31]
	v_mfma_f32_16x16x32_f16 v[76:79], v[158:161], v[116:119], v[76:79]
	global_load_dwordx4 v[116:119], v[2:3], off offset:1408
	global_load_dwordx4 v[162:165], v[4:5], off offset:1408
	global_load_dwordx4 v[166:169], v[6:7], off offset:1408
	global_load_dwordx4 v[58:61], v[8:9], off offset:1408
	global_load_dwordx4 v[188:191], v[10:11], off offset:1408
	global_load_dwordx4 v[192:195], v[12:13], off offset:1408
	global_load_dwordx4 v[196:199], v[14:15], off offset:1408
	s_waitcnt lgkmcnt(0)
	s_barrier
	v_mfma_f32_16x16x32_f16 v[50:53], v[158:161], v[144:147], v[50:53]
	ds_read_b128 v[120:123], v16 offset:32768
	ds_read_b128 v[136:139], v21
	s_waitcnt lgkmcnt(0)
	v_mfma_f32_16x16x32_f16 v[38:41], v[120:123], v[136:139], v[38:41]
	ds_read_b128 v[124:127], v16 offset:34816
	ds_read_b128 v[144:147], v21 offset:2048
	s_waitcnt lgkmcnt(0)
	v_mfma_f32_16x16x32_f16 v[80:83], v[120:123], v[144:147], v[80:83]
	ds_read_b128 v[154:157], v16 offset:36864
	v_mfma_f32_16x16x32_f16 v[46:49], v[124:127], v[136:139], v[46:49]
	ds_read_b128 v[158:161], v16 offset:38912
	v_mfma_f32_16x16x32_f16 v[104:107], v[124:127], v[144:147], v[104:107]
	s_waitcnt vmcnt(7)
	ds_write_b128 v17, v[54:57] offset:16384
	s_waitcnt lgkmcnt(2)
	v_mfma_f32_16x16x32_f16 v[108:111], v[154:157], v[136:139], v[108:111]
	s_waitcnt vmcnt(6)
	ds_write_b128 v18, v[116:119] offset:16384
	v_mfma_f32_16x16x32_f16 v[112:115], v[154:157], v[144:147], v[112:115]
	s_waitcnt vmcnt(5)
	ds_write_b128 v19, v[162:165] offset:16384
	s_waitcnt lgkmcnt(3)
	v_mfma_f32_16x16x32_f16 v[72:75], v[158:161], v[136:139], v[72:75]
	ds_read_b128 v[136:139], v21 offset:4096
	v_mfma_f32_16x16x32_f16 v[34:37], v[158:161], v[144:147], v[34:37]
	ds_read_b128 v[144:147], v21 offset:6144
	s_waitcnt lgkmcnt(1)
	v_mfma_f32_16x16x32_f16 v[128:131], v[120:123], v[136:139], v[128:131]
	s_waitcnt vmcnt(4)
	ds_write_b128 v20, v[166:169] offset:16384
	s_waitcnt lgkmcnt(1)
	v_mfma_f32_16x16x32_f16 v[42:45], v[120:123], v[144:147], v[42:45]
	ds_read_b128 v[120:123], v22 offset:32768
	v_mfma_f32_16x16x32_f16 v[132:135], v[124:127], v[136:139], v[132:135]
	s_waitcnt vmcnt(3)
	ds_write_b128 v17, v[58:61] offset:49152
	v_mfma_f32_16x16x32_f16 v[24:27], v[124:127], v[144:147], v[24:27]
	ds_read_b128 v[124:127], v22 offset:34816
	v_mfma_f32_16x16x32_f16 v[140:143], v[154:157], v[136:139], v[140:143]
	s_waitcnt vmcnt(2)
	ds_write_b128 v18, v[188:191] offset:49152
	v_mfma_f32_16x16x32_f16 v[28:31], v[154:157], v[144:147], v[28:31]
	ds_read_b128 v[154:157], v22 offset:36864
	v_mfma_f32_16x16x32_f16 v[76:79], v[158:161], v[136:139], v[76:79]
	ds_read_b128 v[136:139], v32
	v_mfma_f32_16x16x32_f16 v[50:53], v[158:161], v[144:147], v[50:53]
	ds_read_b128 v[144:147], v32 offset:2048
	s_waitcnt lgkmcnt(1)
	v_mfma_f32_16x16x32_f16 v[38:41], v[120:123], v[136:139], v[38:41]
	ds_read_b128 v[158:161], v22 offset:38912
	s_waitcnt lgkmcnt(1)
	v_mfma_f32_16x16x32_f16 v[80:83], v[120:123], v[144:147], v[80:83]
	s_waitcnt vmcnt(1)
	ds_write_b128 v19, v[192:195] offset:49152
	v_mfma_f32_16x16x32_f16 v[46:49], v[124:127], v[136:139], v[46:49]
	s_waitcnt vmcnt(0)
	ds_write_b128 v20, v[196:199] offset:49152
	v_mfma_f32_16x16x32_f16 v[104:107], v[124:127], v[144:147], v[104:107]
	v_mfma_f32_16x16x32_f16 v[108:111], v[154:157], v[136:139], v[108:111]
	v_mfma_f32_16x16x32_f16 v[112:115], v[154:157], v[144:147], v[112:115]
	s_waitcnt lgkmcnt(2)
	v_mfma_f32_16x16x32_f16 v[72:75], v[158:161], v[136:139], v[72:75]
	ds_read_b128 v[136:139], v32 offset:4096
	v_mfma_f32_16x16x32_f16 v[34:37], v[158:161], v[144:147], v[34:37]
	ds_read_b128 v[144:147], v32 offset:6144
	s_waitcnt lgkmcnt(1)
	v_mfma_f32_16x16x32_f16 v[128:131], v[120:123], v[136:139], v[128:131]
	s_waitcnt lgkmcnt(0)
	v_mfma_f32_16x16x32_f16 v[42:45], v[120:123], v[144:147], v[42:45]
	global_load_dwordx4 v[120:123], v[0:1], off offset:1536
	v_mfma_f32_16x16x32_f16 v[132:135], v[124:127], v[136:139], v[132:135]
	v_mfma_f32_16x16x32_f16 v[24:27], v[124:127], v[144:147], v[24:27]
	v_mfma_f32_16x16x32_f16 v[140:143], v[154:157], v[136:139], v[140:143]
	v_mfma_f32_16x16x32_f16 v[28:31], v[154:157], v[144:147], v[28:31]
	v_mfma_f32_16x16x32_f16 v[76:79], v[158:161], v[136:139], v[76:79]
	global_load_dwordx4 v[136:139], v[2:3], off offset:1536
	global_load_dwordx4 v[200:203], v[4:5], off offset:1536
	global_load_dwordx4 v[204:207], v[6:7], off offset:1536
	global_load_dwordx4 v[124:127], v[8:9], off offset:1536
	global_load_dwordx4 v[208:211], v[10:11], off offset:1536
	global_load_dwordx4 v[212:215], v[12:13], off offset:1536
	global_load_dwordx4 v[220:223], v[14:15], off offset:1536
	s_waitcnt lgkmcnt(0)
	s_barrier
; #define GL_LOAD(s_, kt_) if (VAR != 1) { a##s_##0 = GL_A(0, kt_); a##s_##1 = GL_A(1, kt_); a##s_##2 = GL_A(2, kt_); a##s_##3 = GL_A(3, kt_); b##s_##0 = GL_B(0, kt_); b##s_##1 = GL_B(1, kt_); b##s_##2 = GL_B(2, kt_); b##s_##3 = GL_B(3, kt_); }
; #define LDS_STORE(s_, buf_) if (VAR != 2) { LDS_ST1(sA, 0, buf_, a##s_##0) LDS_ST1(sA, 1, buf_, a##s_##1) LDS_ST1(sA, 2, buf_, a##s_##2) LDS_ST1(sA, 3, buf_, a##s_##3) LDS_ST1(sB, 0, buf_, b##s_##0) LDS_ST1(sB, 1, buf_, b##s_##1) LDS_ST1(sB, 2, buf_, b##s_##2) LDS_ST1(sB, 3, buf_, b##s_##3) }
;     ...
;   for (int kt = 0; kt < nk; kt += 2) {
;     if (kt + 2 < nk) { GL_LOAD(0, kt + 2) }
;     MMA_TILE(0)
;     LDS_STORE(1, 1)
;     if (VAR != 4) __syncthreads();
;     if (kt + 3 < nk) { GL_LOAD(1, kt + 3) }
;     MMA_TILE(1)
;     if (kt + 2 < nk) { LDS_STORE(0, 0) }
;     if (VAR != 4) __syncthreads();
	v_mfma_f32_16x16x32_f16 v[50:53], v[158:161], v[144:147], v[50:53]
	ds_read_b128 v[54:57], v16 offset:49152
	ds_read_b128 v[116:119], v21 offset:16384
	s_waitcnt lgkmcnt(0)
	v_mfma_f32_16x16x32_f16 v[38:41], v[54:57], v[116:119], v[38:41]
	ds_read_b128 v[58:61], v16 offset:51200
	ds_read_b128 v[144:147], v21 offset:18432
	s_waitcnt lgkmcnt(0)
	v_mfma_f32_16x16x32_f16 v[80:83], v[54:57], v[144:147], v[80:83]
	ds_read_b128 v[154:157], v16 offset:53248
	v_mfma_f32_16x16x32_f16 v[46:49], v[58:61], v[116:119], v[46:49]
	ds_read_b128 v[158:161], v16 offset:55296
	v_mfma_f32_16x16x32_f16 v[104:107], v[58:61], v[144:147], v[104:107]
	s_waitcnt vmcnt(7)
	ds_write_b128 v17, v[120:123]
	s_waitcnt lgkmcnt(2)
	v_mfma_f32_16x16x32_f16 v[108:111], v[154:157], v[116:119], v[108:111]
	s_waitcnt vmcnt(6)
	ds_write_b128 v18, v[136:139]
	v_mfma_f32_16x16x32_f16 v[112:115], v[154:157], v[144:147], v[112:115]
	s_waitcnt vmcnt(5)
	ds_write_b128 v19, v[200:203]
	s_waitcnt lgkmcnt(3)
	v_mfma_f32_16x16x32_f16 v[72:75], v[158:161], v[116:119], v[72:75]
	ds_read_b128 v[116:119], v21 offset:20480
	v_mfma_f32_16x16x32_f16 v[34:37], v[158:161], v[144:147], v[34:37]
	ds_read_b128 v[144:147], v21 offset:22528
	s_waitcnt lgkmcnt(1)
	v_mfma_f32_16x16x32_f16 v[128:131], v[54:57], v[116:119], v[128:131]
	s_waitcnt vmcnt(4)
	ds_write_b128 v20, v[204:207]
	s_waitcnt lgkmcnt(1)
	v_mfma_f32_16x16x32_f16 v[42:45], v[54:57], v[144:147], v[42:45]
	ds_read_b128 v[54:57], v22 offset:49152
	v_mfma_f32_16x16x32_f16 v[132:135], v[58:61], v[116:119], v[132:135]
	s_waitcnt vmcnt(3)
	ds_write_b128 v17, v[124:127] offset:32768
	v_mfma_f32_16x16x32_f16 v[24:27], v[58:61], v[144:147], v[24:27]
	ds_read_b128 v[58:61], v22 offset:51200
	v_mfma_f32_16x16x32_f16 v[140:143], v[154:157], v[116:119], v[140:143]
	s_waitcnt vmcnt(2)
	ds_write_b128 v18, v[208:211] offset:32768
	v_mfma_f32_16x16x32_f16 v[28:31], v[154:157], v[144:147], v[28:31]
	ds_read_b128 v[154:157], v22 offset:53248
	v_mfma_f32_16x16x32_f16 v[76:79], v[158:161], v[116:119], v[76:79]
	ds_read_b128 v[116:119], v32 offset:16384
	v_mfma_f32_16x16x32_f16 v[50:53], v[158:161], v[144:147], v[50:53]
	ds_read_b128 v[144:147], v32 offset:18432
	s_waitcnt lgkmcnt(1)
	v_mfma_f32_16x16x32_f16 v[38:41], v[54:57], v[116:119], v[38:41]
	ds_read_b128 v[158:161], v22 offset:55296
	s_waitcnt lgkmcnt(1)
	v_mfma_f32_16x16x32_f16 v[80:83], v[54:57], v[144:147], v[80:83]
	s_waitcnt vmcnt(1)
	ds_write_b128 v19, v[212:215] offset:32768
	v_mfma_f32_16x16x32_f16 v[46:49], v[58:61], v[116:119], v[46:49]
	s_waitcnt vmcnt(0)
	ds_write_b128 v20, v[220:223] offset:32768
	v_mfma_f32_16x16x32_f16 v[104:107], v[58:61], v[144:147], v[104:107]
	v_mfma_f32_16x16x32_f16 v[108:111], v[154:157], v[116:119], v[108:111]
	v_mfma_f32_16x16x32_f16 v[112:115], v[154:157], v[144:147], v[112:115]
	s_waitcnt lgkmcnt(2)
	v_mfma_f32_16x16x32_f16 v[72:75], v[158:161], v[116:119], v[72:75]
	ds_read_b128 v[116:119], v32 offset:20480
	v_mfma_f32_16x16x32_f16 v[34:37], v[158:161], v[144:147], v[34:37]
	ds_read_b128 v[144:147], v32 offset:22528
	s_waitcnt lgkmcnt(1)
	v_mfma_f32_16x16x32_f16 v[128:131], v[54:57], v[116:119], v[128:131]
	s_waitcnt lgkmcnt(0)
	v_mfma_f32_16x16x32_f16 v[42:45], v[54:57], v[144:147], v[42:45]
	global_load_dwordx4 v[54:57], v[0:1], off offset:1664
	v_mfma_f32_16x16x32_f16 v[132:135], v[58:61], v[116:119], v[132:135]
	v_mfma_f32_16x16x32_f16 v[24:27], v[58:61], v[144:147], v[24:27]
	v_mfma_f32_16x16x32_f16 v[140:143], v[154:157], v[116:119], v[140:143]
	v_mfma_f32_16x16x32_f16 v[28:31], v[154:157], v[144:147], v[28:31]
	v_mfma_f32_16x16x32_f16 v[76:79], v[158:161], v[116:119], v[76:79]
	global_load_dwordx4 v[116:119], v[2:3], off offset:1664
	global_load_dwordx4 v[162:165], v[4:5], off offset:1664
	global_load_dwordx4 v[166:169], v[6:7], off offset:1664
	global_load_dwordx4 v[58:61], v[8:9], off offset:1664
	global_load_dwordx4 v[188:191], v[10:11], off offset:1664
	global_load_dwordx4 v[192:195], v[12:13], off offset:1664
	global_load_dwordx4 v[196:199], v[14:15], off offset:1664
	s_waitcnt lgkmcnt(0)
	s_barrier
	v_mfma_f32_16x16x32_f16 v[50:53], v[158:161], v[144:147], v[50:53]
	ds_read_b128 v[120:123], v16 offset:32768
	ds_read_b128 v[136:139], v21
	s_waitcnt lgkmcnt(0)
	v_mfma_f32_16x16x32_f16 v[38:41], v[120:123], v[136:139], v[38:41]
	ds_read_b128 v[124:127], v16 offset:34816
	ds_read_b128 v[144:147], v21 offset:2048
	s_waitcnt lgkmcnt(0)
	v_mfma_f32_16x16x32_f16 v[80:83], v[120:123], v[144:147], v[80:83]
	ds_read_b128 v[154:157], v16 offset:36864
	v_mfma_f32_16x16x32_f16 v[46:49], v[124:127], v[136:139], v[46:49]
	ds_read_b128 v[158:161], v16 offset:38912
	v_mfma_f32_16x16x32_f16 v[104:107], v[124:127], v[144:147], v[104:107]
	s_waitcnt vmcnt(7)
	ds_write_b128 v17, v[54:57] offset:16384
	s_waitcnt lgkmcnt(2)
	v_mfma_f32_16x16x32_f16 v[108:111], v[154:157], v[136:139], v[108:111]
	s_waitcnt vmcnt(6)
	ds_write_b128 v18, v[116:119] offset:16384
	v_mfma_f32_16x16x32_f16 v[112:115], v[154:157], v[144:147], v[112:115]
	s_waitcnt vmcnt(5)
	ds_write_b128 v19, v[162:165] offset:16384
	s_waitcnt lgkmcnt(3)
	v_mfma_f32_16x16x32_f16 v[72:75], v[158:161], v[136:139], v[72:75]
	ds_read_b128 v[136:139], v21 offset:4096
	v_mfma_f32_16x16x32_f16 v[34:37], v[158:161], v[144:147], v[34:37]
	ds_read_b128 v[144:147], v21 offset:6144
	s_waitcnt lgkmcnt(1)
	v_mfma_f32_16x16x32_f16 v[128:131], v[120:123], v[136:139], v[128:131]
	s_waitcnt vmcnt(4)
	ds_write_b128 v20, v[166:169] offset:16384
	s_waitcnt lgkmcnt(1)
	v_mfma_f32_16x16x32_f16 v[42:45], v[120:123], v[144:147], v[42:45]
	ds_read_b128 v[120:123], v22 offset:32768
	v_mfma_f32_16x16x32_f16 v[132:135], v[124:127], v[136:139], v[132:135]
	s_waitcnt vmcnt(3)
; #define GL_LOAD(s_, kt_) if (VAR != 1) { a##s_##0 = GL_A(0, kt_); a##s_##1 = GL_A(1, kt_); a##s_##2 = GL_A(2, kt_); a##s_##3 = GL_A(3, kt_); b##s_##0 = GL_B(0, kt_); b##s_##1 = GL_B(1, kt_); b##s_##2 = GL_B(2, kt_); b##s_##3 = GL_B(3, kt_); }
; #define LDS_STORE(s_, buf_) if (VAR != 2) { LDS_ST1(sA, 0, buf_, a##s_##0) LDS_ST1(sA, 1, buf_, a##s_##1) LDS_ST1(sA, 2, buf_, a##s_##2) LDS_ST1(sA, 3, buf_, a##s_##3) LDS_ST1(sB, 0, buf_, b##s_##0) LDS_ST1(sB, 1, buf_, b##s_##1) LDS_ST1(sB, 2, buf_, b##s_##2) LDS_ST1(sB, 3, buf_, b##s_##3) }
;     ...
;   for (int kt = 0; kt < nk; kt += 2) {
;     if (kt + 2 < nk) { GL_LOAD(0, kt + 2) }
;     MMA_TILE(0)
;     LDS_STORE(1, 1)
;     if (VAR != 4) __syncthreads();
;     if (kt + 3 < nk) { GL_LOAD(1, kt + 3) }
;     MMA_TILE(1)
;     if (kt + 2 < nk) { LDS_STORE(0, 0) }
;     if (VAR != 4) __syncthreads();
	ds_write_b128 v17, v[58:61] offset:49152
	v_mfma_f32_16x16x32_f16 v[24:27], v[124:127], v[144:147], v[24:27]
	ds_read_b128 v[124:127], v22 offset:34816
	v_mfma_f32_16x16x32_f16 v[140:143], v[154:157], v[136:139], v[140:143]
	s_waitcnt vmcnt(2)
	ds_write_b128 v18, v[188:191] offset:49152
	v_mfma_f32_16x16x32_f16 v[28:31], v[154:157], v[144:147], v[28:31]
	ds_read_b128 v[154:157], v22 offset:36864
	v_mfma_f32_16x16x32_f16 v[76:79], v[158:161], v[136:139], v[76:79]
	ds_read_b128 v[136:139], v32
	v_mfma_f32_16x16x32_f16 v[50:53], v[158:161], v[144:147], v[50:53]
	ds_read_b128 v[144:147], v32 offset:2048
	s_waitcnt lgkmcnt(1)
	v_mfma_f32_16x16x32_f16 v[38:41], v[120:123], v[136:139], v[38:41]
	ds_read_b128 v[158:161], v22 offset:38912
	s_waitcnt lgkmcnt(1)
	v_mfma_f32_16x16x32_f16 v[80:83], v[120:123], v[144:147], v[80:83]
	s_waitcnt vmcnt(1)
	ds_write_b128 v19, v[192:195] offset:49152
	v_mfma_f32_16x16x32_f16 v[46:49], v[124:127], v[136:139], v[46:49]
	s_waitcnt vmcnt(0)
	ds_write_b128 v20, v[196:199] offset:49152
	v_mfma_f32_16x16x32_f16 v[104:107], v[124:127], v[144:147], v[104:107]
	v_mfma_f32_16x16x32_f16 v[108:111], v[154:157], v[136:139], v[108:111]
	v_mfma_f32_16x16x32_f16 v[112:115], v[154:157], v[144:147], v[112:115]
	s_waitcnt lgkmcnt(2)
	v_mfma_f32_16x16x32_f16 v[72:75], v[158:161], v[136:139], v[72:75]
	ds_read_b128 v[136:139], v32 offset:4096
	v_mfma_f32_16x16x32_f16 v[34:37], v[158:161], v[144:147], v[34:37]
	ds_read_b128 v[144:147], v32 offset:6144
	s_waitcnt lgkmcnt(1)
	v_mfma_f32_16x16x32_f16 v[128:131], v[120:123], v[136:139], v[128:131]
	s_waitcnt lgkmcnt(0)
	v_mfma_f32_16x16x32_f16 v[42:45], v[120:123], v[144:147], v[42:45]
	global_load_dwordx4 v[120:123], v[0:1], off offset:1792
	v_mfma_f32_16x16x32_f16 v[132:135], v[124:127], v[136:139], v[132:135]
	v_mfma_f32_16x16x32_f16 v[24:27], v[124:127], v[144:147], v[24:27]
	v_mfma_f32_16x16x32_f16 v[140:143], v[154:157], v[136:139], v[140:143]
	v_mfma_f32_16x16x32_f16 v[28:31], v[154:157], v[144:147], v[28:31]
	v_mfma_f32_16x16x32_f16 v[76:79], v[158:161], v[136:139], v[76:79]
	global_load_dwordx4 v[136:139], v[2:3], off offset:1792
	global_load_dwordx4 v[200:203], v[4:5], off offset:1792
	global_load_dwordx4 v[204:207], v[6:7], off offset:1792
	global_load_dwordx4 v[124:127], v[8:9], off offset:1792
	global_load_dwordx4 v[208:211], v[10:11], off offset:1792
	global_load_dwordx4 v[212:215], v[12:13], off offset:1792
	global_load_dwordx4 v[220:223], v[14:15], off offset:1792
	s_waitcnt lgkmcnt(0)
	s_barrier
	v_mfma_f32_16x16x32_f16 v[50:53], v[158:161], v[144:147], v[50:53]
	ds_read_b128 v[54:57], v16 offset:49152
	ds_read_b128 v[116:119], v21 offset:16384
	s_waitcnt lgkmcnt(0)
	v_mfma_f32_16x16x32_f16 v[38:41], v[54:57], v[116:119], v[38:41]
	ds_read_b128 v[58:61], v16 offset:51200
	ds_read_b128 v[144:147], v21 offset:18432
	s_waitcnt lgkmcnt(0)
	v_mfma_f32_16x16x32_f16 v[80:83], v[54:57], v[144:147], v[80:83]
	ds_read_b128 v[154:157], v16 offset:53248
	v_mfma_f32_16x16x32_f16 v[46:49], v[58:61], v[116:119], v[46:49]
	ds_read_b128 v[158:161], v16 offset:55296
	v_mfma_f32_16x16x32_f16 v[104:107], v[58:61], v[144:147], v[104:107]
	s_waitcnt vmcnt(7)
	ds_write_b128 v17, v[120:123]
	s_waitcnt lgkmcnt(2)
	v_mfma_f32_16x16x32_f16 v[108:111], v[154:157], v[116:119], v[108:111]
	s_waitcnt vmcnt(6)
	ds_write_b128 v18, v[136:139]
	v_mfma_f32_16x16x32_f16 v[112:115], v[154:157], v[144:147], v[112:115]
	s_waitcnt vmcnt(5)
	ds_write_b128 v19, v[200:203]
	s_waitcnt lgkmcnt(3)
	v_mfma_f32_16x16x32_f16 v[72:75], v[158:161], v[116:119], v[72:75]
	ds_read_b128 v[116:119], v21 offset:20480
	v_mfma_f32_16x16x32_f16 v[34:37], v[158:161], v[144:147], v[34:37]
	ds_read_b128 v[144:147], v21 offset:22528
	s_waitcnt lgkmcnt(1)
	v_mfma_f32_16x16x32_f16 v[128:131], v[54:57], v[116:119], v[128:131]
	s_waitcnt vmcnt(4)
	ds_write_b128 v20, v[204:207]
	s_waitcnt lgkmcnt(1)
	v_mfma_f32_16x16x32_f16 v[42:45], v[54:57], v[144:147], v[42:45]
	ds_read_b128 v[54:57], v22 offset:49152
	v_mfma_f32_16x16x32_f16 v[132:135], v[58:61], v[116:119], v[132:135]
	s_waitcnt vmcnt(3)
	ds_write_b128 v17, v[124:127] offset:32768
	v_mfma_f32_16x16x32_f16 v[24:27], v[58:61], v[144:147], v[24:27]
	ds_read_b128 v[58:61], v22 offset:51200
	v_mfma_f32_16x16x32_f16 v[140:143], v[154:157], v[116:119], v[140:143]
	s_waitcnt vmcnt(2)
	ds_write_b128 v18, v[208:211] offset:32768
	v_mfma_f32_16x16x32_f16 v[28:31], v[154:157], v[144:147], v[28:31]
	ds_read_b128 v[154:157], v22 offset:53248
	v_mfma_f32_16x16x32_f16 v[76:79], v[158:161], v[116:119], v[76:79]
	ds_read_b128 v[116:119], v32 offset:16384
	v_mfma_f32_16x16x32_f16 v[50:53], v[158:161], v[144:147], v[50:53]
	ds_read_b128 v[144:147], v32 offset:18432
	s_waitcnt lgkmcnt(1)
	v_mfma_f32_16x16x32_f16 v[38:41], v[54:57], v[116:119], v[38:41]
	ds_read_b128 v[158:161], v22 offset:55296
	s_waitcnt lgkmcnt(1)
	v_mfma_f32_16x16x32_f16 v[80:83], v[54:57], v[144:147], v[80:83]
	s_waitcnt vmcnt(1)
	ds_write_b128 v19, v[212:215] offset:32768
	v_mfma_f32_16x16x32_f16 v[46:49], v[58:61], v[116:119], v[46:49]
	s_waitcnt vmcnt(0)
	ds_write_b128 v20, v[220:223] offset:32768
	v_mfma_f32_16x16x32_f16 v[104:107], v[58:61], v[144:147], v[104:107]
	v_mfma_f32_16x16x32_f16 v[108:111], v[154:157], v[116:119], v[108:111]
	v_mfma_f32_16x16x32_f16 v[112:115], v[154:157], v[144:147], v[112:115]
	s_waitcnt lgkmcnt(2)
	v_mfma_f32_16x16x32_f16 v[72:75], v[158:161], v[116:119], v[72:75]
	ds_read_b128 v[116:119], v32 offset:20480
	v_mfma_f32_16x16x32_f16 v[34:37], v[158:161], v[144:147], v[34:37]
	ds_read_b128 v[144:147], v32 offset:22528
	s_waitcnt lgkmcnt(1)
	v_mfma_f32_16x16x32_f16 v[128:131], v[54:57], v[116:119], v[128:131]
	s_waitcnt lgkmcnt(0)
	v_mfma_f32_16x16x32_f16 v[42:45], v[54:57], v[144:147], v[42:45]
	global_load_dwordx4 v[54:57], v[0:1], off offset:1920
	global_load_dwordx4 v[0:3], v[2:3], off offset:1920
	v_mfma_f32_16x16x32_f16 v[132:135], v[58:61], v[116:119], v[132:135]
	v_mfma_f32_16x16x32_f16 v[24:27], v[58:61], v[144:147], v[24:27]
	v_mfma_f32_16x16x32_f16 v[140:143], v[154:157], v[116:119], v[140:143]
	v_mfma_f32_16x16x32_f16 v[28:31], v[154:157], v[144:147], v[28:31]
	v_mfma_f32_16x16x32_f16 v[76:79], v[158:161], v[116:119], v[76:79]
	global_load_dwordx4 v[116:119], v[4:5], off offset:1920
	global_load_dwordx4 v[4:7], v[6:7], off offset:1920
	global_load_dwordx4 v[58:61], v[8:9], off offset:1920
	global_load_dwordx4 v[8:11], v[10:11], off offset:1920
	global_load_dwordx4 v[162:165], v[12:13], off offset:1920
	global_load_dwordx4 v[12:15], v[14:15], off offset:1920
	s_waitcnt lgkmcnt(0)
	s_barrier
; #define GL_LOAD(s_, kt_) if (VAR != 1) { a##s_##0 = GL_A(0, kt_); a##s_##1 = GL_A(1, kt_); a##s_##2 = GL_A(2, kt_); a##s_##3 = GL_A(3, kt_); b##s_##0 = GL_B(0, kt_); b##s_##1 = GL_B(1, kt_); b##s_##2 = GL_B(2, kt_); b##s_##3 = GL_B(3, kt_); }
; #define LDS_STORE(s_, buf_) if (VAR != 2) { LDS_ST1(sA, 0, buf_, a##s_##0) LDS_ST1(sA, 1, buf_, a##s_##1) LDS_ST1(sA, 2, buf_, a##s_##2) LDS_ST1(sA, 3, buf_, a##s_##3) LDS_ST1(sB, 0, buf_, b##s_##0) LDS_ST1(sB, 1, buf_, b##s_##1) LDS_ST1(sB, 2, buf_, b##s_##2) LDS_ST1(sB, 3, buf_, b##s_##3) }
;     ...
;   for (int kt = 0; kt < nk; kt += 2) {
;     if (kt + 2 < nk) { GL_LOAD(0, kt + 2) }
;     MMA_TILE(0)
;     LDS_STORE(1, 1)
;     if (VAR != 4) __syncthreads();
;     if (kt + 3 < nk) { GL_LOAD(1, kt + 3) }
;     MMA_TILE(1)
;     if (kt + 2 < nk) { LDS_STORE(0, 0) }
;     if (VAR != 4) __syncthreads();
	ds_read_b128 v[120:123], v16 offset:32768
	v_mfma_f32_16x16x32_f16 v[50:53], v[158:161], v[144:147], v[50:53]
	ds_read_b128 v[124:127], v16 offset:34816
	ds_read_b128 v[136:139], v21
	ds_read_b128 v[144:147], v21 offset:2048
	ds_read_b128 v[154:157], v16 offset:36864
	ds_read_b128 v[158:161], v16 offset:38912
	s_waitcnt lgkmcnt(3)
	v_mfma_f32_16x16x32_f16 v[38:41], v[120:123], v[136:139], v[38:41]
	v_mfma_f32_16x16x32_f16 v[46:49], v[124:127], v[136:139], v[46:49]
	s_waitcnt lgkmcnt(1)
	v_mfma_f32_16x16x32_f16 v[108:111], v[154:157], v[136:139], v[108:111]
	s_waitcnt lgkmcnt(0)
	v_mfma_f32_16x16x32_f16 v[72:75], v[158:161], v[136:139], v[72:75]
	v_mfma_f32_16x16x32_f16 v[80:83], v[120:123], v[144:147], v[80:83]
	v_mfma_f32_16x16x32_f16 v[104:107], v[124:127], v[144:147], v[104:107]
	v_mfma_f32_16x16x32_f16 v[112:115], v[154:157], v[144:147], v[112:115]
	v_mfma_f32_16x16x32_f16 v[34:37], v[158:161], v[144:147], v[34:37]
	ds_read_b128 v[136:139], v21 offset:4096
	ds_read_b128 v[144:147], v21 offset:6144
	s_waitcnt lgkmcnt(1)
	v_mfma_f32_16x16x32_f16 v[128:131], v[120:123], v[136:139], v[128:131]
	v_mfma_f32_16x16x32_f16 v[132:135], v[124:127], v[136:139], v[132:135]
	v_mfma_f32_16x16x32_f16 v[140:143], v[154:157], v[136:139], v[140:143]
	v_mfma_f32_16x16x32_f16 v[76:79], v[158:161], v[136:139], v[76:79]
	s_waitcnt lgkmcnt(0)
	v_mfma_f32_16x16x32_f16 v[42:45], v[120:123], v[144:147], v[42:45]
	ds_read_b128 v[120:123], v22 offset:32768
	v_mfma_f32_16x16x32_f16 v[24:27], v[124:127], v[144:147], v[24:27]
	v_mfma_f32_16x16x32_f16 v[28:31], v[154:157], v[144:147], v[28:31]
	v_mfma_f32_16x16x32_f16 v[50:53], v[158:161], v[144:147], v[50:53]
	ds_read_b128 v[124:127], v22 offset:34816
	ds_read_b128 v[136:139], v32
	ds_read_b128 v[144:147], v32 offset:2048
	ds_read_b128 v[154:157], v22 offset:36864
	ds_read_b128 v[158:161], v22 offset:38912
	s_waitcnt lgkmcnt(3)
	v_mfma_f32_16x16x32_f16 v[38:41], v[120:123], v[136:139], v[38:41]
	v_mfma_f32_16x16x32_f16 v[46:49], v[124:127], v[136:139], v[46:49]
	s_waitcnt lgkmcnt(1)
	v_mfma_f32_16x16x32_f16 v[108:111], v[154:157], v[136:139], v[108:111]
	s_waitcnt lgkmcnt(0)
	v_mfma_f32_16x16x32_f16 v[72:75], v[158:161], v[136:139], v[72:75]
	v_mfma_f32_16x16x32_f16 v[80:83], v[120:123], v[144:147], v[80:83]
	v_mfma_f32_16x16x32_f16 v[104:107], v[124:127], v[144:147], v[104:107]
	v_mfma_f32_16x16x32_f16 v[112:115], v[154:157], v[144:147], v[112:115]
	v_mfma_f32_16x16x32_f16 v[34:37], v[158:161], v[144:147], v[34:37]
	ds_read_b128 v[136:139], v32 offset:4096
	ds_read_b128 v[144:147], v32 offset:6144
	s_waitcnt vmcnt(7)
	ds_write_b128 v17, v[54:57] offset:16384
	s_waitcnt vmcnt(6)
	ds_write_b128 v18, v[0:3] offset:16384
	s_waitcnt vmcnt(5)
	ds_write_b128 v19, v[116:119] offset:16384
	s_waitcnt vmcnt(4)
	ds_write_b128 v20, v[4:7] offset:16384
	s_waitcnt vmcnt(3)
	ds_write_b128 v17, v[58:61] offset:49152
	s_waitcnt vmcnt(2)
	ds_write_b128 v18, v[8:11] offset:49152
	s_waitcnt vmcnt(1)
	ds_write_b128 v19, v[162:165] offset:49152
	s_waitcnt vmcnt(0)
	ds_write_b128 v20, v[12:15] offset:49152
	s_waitcnt lgkmcnt(0)
	s_barrier
; #define LDS_STORE(s_, buf_) if (VAR != 2) { LDS_ST1(sA, 0, buf_, a##s_##0) LDS_ST1(sA, 1, buf_, a##s_##1) LDS_ST1(sA, 2, buf_, a##s_##2) LDS_ST1(sA, 3, buf_, a##s_##3) LDS_ST1(sB, 0, buf_, b##s_##0) LDS_ST1(sB, 1, buf_, b##s_##1) LDS_ST1(sB, 2, buf_, b##s_##2) LDS_ST1(sB, 3, buf_, b##s_##3) }
;     ...
;     MMA_TILE(1)
;     if (kt + 2 < nk) { LDS_STORE(0, 0) }
;     if (VAR != 4) __syncthreads();
; DI void phase_proj(const Params& P, int l, char* smem) {
;     ...
;       gemm_kloop<false, true, 16>(acc, xb + (size_t)m0 * DM, DM, Wt + (size_t)n0 * DM, DM, smem);
; #pragma unroll
;       for (int mt = 0; mt < 4; ++mt)
; #pragma unroll
;         for (int nt = 0; nt < 4; ++nt) acc[mt][nt] *= rs[mt];
;       const float* gain = nullptr; bool rope = false; float sc = 1.f; bool sig = false;
;       constexpr float QS = 0.125f * 1.4426950408889634f;
;       if (col0 < C_AK) { gain = P.a_q_norm + l * 64; rope = true; sc = QS; }
;       else if (col0 < C_BQ) { gain = P.a_k_norm + l * 64; rope = true; }
;       else if (col0 < C_BK) { sc = QS; }
;       else if (col0 < C_CQ) { }
;       else if (col0 < C_CK) { gain = P.c_q_norm + l * 64; rope = true; sc = QS; }
;       else if (col0 < C_IQ) { gain = P.c_k_norm + l * 64; rope = true; }
;       else if (col0 < C_IK) { rope = true; sc = 0.125f; }
;       else if (col0 < C_IW) { gain = P.idx_k_norm + l * 64; rope = true; }
;       else if (col0 < C_GL) { sc = 0.5f; }
;       else { sig = true; }
;       if (gain) {
	ds_read_b128 v[0:3], v16 offset:49152
	v_mfma_f32_16x16x32_f16 v[4:7], v[158:161], v[144:147], v[50:53]
	ds_read_b128 v[8:11], v16 offset:51200
	ds_read_b128 v[12:15], v21 offset:16384
	s_nop 0
	ds_read_b128 v[50:53], v21 offset:18432
	ds_read_b128 v[54:57], v16 offset:53248
	ds_read_b128 v[16:19], v16 offset:55296
	s_waitcnt lgkmcnt(3)
	v_mfma_f32_16x16x32_f16 v[38:41], v[0:3], v[12:15], v[38:41]
	v_mfma_f32_16x16x32_f16 v[46:49], v[8:11], v[12:15], v[46:49]
	s_waitcnt lgkmcnt(1)
	v_mfma_f32_16x16x32_f16 v[58:61], v[54:57], v[12:15], v[108:111]
	s_waitcnt lgkmcnt(0)
	v_mfma_f32_16x16x32_f16 v[12:15], v[16:19], v[12:15], v[72:75]
	v_mfma_f32_16x16x32_f16 v[72:75], v[0:3], v[50:53], v[80:83]
	v_mfma_f32_16x16x32_f16 v[80:83], v[8:11], v[50:53], v[104:107]
	v_mfma_f32_16x16x32_f16 v[104:107], v[54:57], v[50:53], v[112:115]
	v_mfma_f32_16x16x32_f16 v[34:37], v[16:19], v[50:53], v[34:37]
	ds_read_b128 v[50:53], v21 offset:20480
	ds_read_b128 v[108:111], v21 offset:22528
	v_mfma_f32_16x16x32_f16 v[128:131], v[120:123], v[136:139], v[128:131]
	v_mfma_f32_16x16x32_f16 v[132:135], v[124:127], v[136:139], v[132:135]
	v_mfma_f32_16x16x32_f16 v[140:143], v[154:157], v[136:139], v[140:143]
	v_mfma_f32_16x16x32_f16 v[42:45], v[120:123], v[144:147], v[42:45]
	v_mfma_f32_16x16x32_f16 v[24:27], v[124:127], v[144:147], v[24:27]
	v_mfma_f32_16x16x32_f16 v[28:31], v[154:157], v[144:147], v[28:31]
	v_mfma_f32_16x16x32_f16 v[76:79], v[158:161], v[136:139], v[76:79]
	s_waitcnt lgkmcnt(1)
	v_mfma_f32_16x16x32_f16 v[112:115], v[0:3], v[50:53], v[128:131]
	v_mfma_f32_16x16x32_f16 v[116:119], v[8:11], v[50:53], v[132:135]
	v_mfma_f32_16x16x32_f16 v[120:123], v[54:57], v[50:53], v[140:143]
	s_nop 1
	ds_read_b128 v[132:135], v22 offset:49152
	s_waitcnt lgkmcnt(1)
	v_mfma_f32_16x16x32_f16 v[0:3], v[0:3], v[108:111], v[42:45]
	v_mfma_f32_16x16x32_f16 v[124:127], v[8:11], v[108:111], v[24:27]
	v_mfma_f32_16x16x32_f16 v[128:131], v[54:57], v[108:111], v[28:31]
	v_mfma_f32_16x16x32_f16 v[108:111], v[16:19], v[108:111], v[4:7]
	ds_read_b128 v[136:139], v22 offset:51200
	s_nop 1
	ds_read_b128 v[4:7], v32 offset:16384
	ds_read_b128 v[8:11], v32 offset:18432
	ds_read_b128 v[140:143], v22 offset:53248
	ds_read_b128 v[144:147], v22 offset:55296
	v_mfma_f32_16x16x32_f16 v[76:79], v[16:19], v[50:53], v[76:79]
	s_waitcnt lgkmcnt(3)
	v_mfma_f32_16x16x32_f16 v[28:31], v[132:135], v[4:7], v[38:41]
	v_mfma_f32_16x16x32_f16 v[24:27], v[136:139], v[4:7], v[46:49]
	s_waitcnt lgkmcnt(1)
	v_mfma_f32_16x16x32_f16 v[60:63], v[140:143], v[4:7], v[58:61]
	s_waitcnt lgkmcnt(0)
	v_mfma_f32_16x16x32_f16 v[56:59], v[144:147], v[4:7], v[12:15]
	v_mfma_f32_16x16x32_f16 v[48:51], v[144:147], v[8:11], v[34:37]
	ds_read_b128 v[4:7], v32 offset:20480
	s_nop 1
	ds_read_b128 v[32:35], v32 offset:22528
	s_waitcnt lgkmcnt(0)
	s_barrier
	s_setprio 0
	v_mfma_f32_16x16x32_f16 v[20:23], v[132:135], v[8:11], v[72:75]
	v_mfma_f32_16x16x32_f16 v[16:19], v[136:139], v[8:11], v[80:83]
	s_nop 1
	v_mov_b32_e32 v72, 0x3e38aa3b
	v_mfma_f32_16x16x32_f16 v[52:55], v[140:143], v[8:11], v[104:107]
	v_mfma_f32_16x16x32_f16 v[12:15], v[132:135], v[4:7], v[112:115]
	v_mfma_f32_16x16x32_f16 v[8:11], v[136:139], v[4:7], v[116:119]
	v_mfma_f32_16x16x32_f16 v[44:47], v[140:143], v[4:7], v[120:123]
	v_mfma_f32_16x16x32_f16 v[40:43], v[144:147], v[4:7], v[76:79]
	s_nop 1
	v_mov_b64_e32 v[122:123], s[14:15]
	v_mfma_f32_16x16x32_f16 v[4:7], v[132:135], v[32:35], v[0:3]
	v_mfma_f32_16x16x32_f16 v[0:3], v[136:139], v[32:35], v[124:127]
	v_mfma_f32_16x16x32_f16 v[36:39], v[140:143], v[32:35], v[128:131]
	v_mfma_f32_16x16x32_f16 v[32:35], v[144:147], v[32:35], v[108:111]
	s_and_saveexec_b64 s[4:5], vcc
	s_cbranch_execz .LBB0_654
	s_cmpk_lt_u32 s16, 0x400
	s_cbranch_scc1 .LBB0_649
	s_cmpk_lt_u32 s16, 0x600
	s_cbranch_scc1 .LBB0_650
	s_cmpk_lt_u32 s16, 0x800
	s_cbranch_scc1 .LBB0_651
	s_cmpk_lt_u32 s16, 0xa00
	s_cbranch_scc1 .LBB0_693
	s_cmpk_lt_u32 s16, 0xc00
	s_cbranch_scc1 .LBB0_694
	s_cmpk_lt_u32 s16, 0xd00
	s_cbranch_scc1 .LBB0_695
	s_movk_i32 s1, 0xd3f
	v_cmp_lt_u32_e32 vcc, s1, v94
	v_mov_b32_e32 v72, 1.0
	v_mov_b64_e32 v[122:123], s[6:7]
	s_and_saveexec_b64 s[24:25], vcc
	s_cmpk_gt_u32 s16, 0xd7f
	s_cselect_b64 s[20:21], -1, 0
	v_cndmask_b32_e64 v72, 0.5, 1.0, s[20:21]
	v_mov_b64_e32 v[122:123], 0
	s_xor_b64 s[22:23], exec, -1
	s_and_b64 s[20:21], s[20:21], exec
	s_or_b64 exec, exec, s[24:25]
	v_readlane_b32 s30, v252, 17
	v_readlane_b32 s31, v252, 18
	s_branch .LBB0_653

; #define GL_LOAD(s_, kt_) if (VAR != 1) { a##s_##0 = GL_A(0, kt_); a##s_##1 = GL_A(1, kt_); a##s_##2 = GL_A(2, kt_); a##s_##3 = GL_A(3, kt_); b##s_##0 = GL_B(0, kt_); b##s_##1 = GL_B(1, kt_); b##s_##2 = GL_B(2, kt_); b##s_##3 = GL_B(3, kt_); }
; #define LDS_STORE(s_, buf_) if (VAR != 2) { LDS_ST1(sA, 0, buf_, a##s_##0) LDS_ST1(sA, 1, buf_, a##s_##1) LDS_ST1(sA, 2, buf_, a##s_##2) LDS_ST1(sA, 3, buf_, a##s_##3) LDS_ST1(sB, 0, buf_, b##s_##0) LDS_ST1(sB, 1, buf_, b##s_##1) LDS_ST1(sB, 2, buf_, b##s_##2) LDS_ST1(sB, 3, buf_, b##s_##3) }
;     ...
;   GL_LOAD(0, 0)
;   GL_LOAD(1, 1)
;   LDS_STORE(0, 0)
;   if (VAR != 4) __syncthreads();
; #pragma unroll
;   for (int kt = 0; kt < nk; kt += 2) {
;     if (kt + 2 < nk) { GL_LOAD(0, kt + 2) }
;     MMA_TILE(0)
;     LDS_STORE(1, 1)
;     if (VAR != 4) __syncthreads();
;     if (kt + 3 < nk) { GL_LOAD(1, kt + 3) }
;     MMA_TILE(1)
; DI void phase_proj(const Params& P, int l, char* smem) {
;     ...
;     if (n0 >= PW) {
;       gemm_kloop<false, false, 16>(acc, xb + (size_t)m0 * DM, DM, Wt + (size_t)n0 * DM, DM, smem);
.LBB0_691:
	s_and_b64 vcc, exec, s[4:5]
	s_cbranch_vccz .LBB0_636
	v_mov_b32_e32 v18, v148
	s_mov_b32 s17, s27
	s_lshl_b64 s[4:5], s[16:17], 11
	v_ashrrev_i32_e32 v16, 3, v18
	v_readlane_b32 s1, v252, 19
	v_ashrrev_i32_e32 v17, 31, v16
	v_add_u32_e32 v54, 64, v16
	s_add_u32 s4, s1, s4
	v_readlane_b32 s1, v252, 20
	v_lshlrev_b64 v[6:7], 11, v[16:17]
	v_lshlrev_b32_e32 v17, 4, v18
	v_add_u32_e32 v20, 32, v16
	v_ashrrev_i32_e32 v55, 31, v54
	s_addc_u32 s5, s1, s5
	v_lshl_add_u64 v[0:1], s[18:19], 0, v[6:7]
	v_and_b32_e32 v150, 0x70, v17
	v_ashrrev_i32_e32 v21, 31, v20
	v_lshlrev_b64 v[12:13], 11, v[54:55]
	v_lshl_add_u64 v[0:1], v[0:1], 0, v[150:151]
	v_lshlrev_b64 v[10:11], 11, v[20:21]
	v_lshl_add_u64 v[4:5], s[18:19], 0, v[12:13]
	v_add_u32_e32 v56, 0x60, v16
	v_lshl_add_u64 v[6:7], s[4:5], 0, v[6:7]
	global_load_dwordx4 v[22:25], v[0:1], off
	v_lshl_add_u64 v[2:3], s[18:19], 0, v[10:11]
	v_lshl_add_u64 v[4:5], v[4:5], 0, v[150:151]
	v_ashrrev_i32_e32 v57, 31, v56
	v_lshl_add_u64 v[6:7], v[6:7], 0, v[150:151]
	v_lshl_add_u64 v[2:3], v[2:3], 0, v[150:151]
	global_load_dwordx4 v[30:33], v[4:5], off
	global_load_dwordx4 v[38:41], v[6:7], off
	v_lshlrev_b64 v[14:15], 11, v[56:57]
	global_load_dwordx4 v[26:29], v[2:3], off
	v_lshl_add_u64 v[8:9], s[18:19], 0, v[14:15]
	v_lshl_add_u64 v[8:9], v[8:9], 0, v[150:151]
	v_lshl_add_u64 v[10:11], s[4:5], 0, v[10:11]
	global_load_dwordx4 v[34:37], v[8:9], off
	v_lshl_add_u64 v[10:11], v[10:11], 0, v[150:151]
	v_lshl_add_u64 v[12:13], s[4:5], 0, v[12:13]
	global_load_dwordx4 v[42:45], v[10:11], off
	v_lshl_add_u64 v[12:13], v[12:13], 0, v[150:151]
	v_lshl_add_u64 v[14:15], s[4:5], 0, v[14:15]
	global_load_dwordx4 v[46:49], v[12:13], off
	v_lshl_add_u64 v[14:15], v[14:15], 0, v[150:151]
	global_load_dwordx4 v[50:53], v[14:15], off
	v_and_b32_e32 v19, 15, v18
	v_lshrrev_b32_e32 v55, 1, v18
	v_lshlrev_b32_e32 v21, 3, v18
	s_movk_i32 s1, 0x70
	v_and_or_b32 v55, v55, s29, v19
	v_and_b32_e32 v82, 48, v18
	v_and_b32_e32 v57, 0x70, v21
	v_bitop3_b32 v17, v17, s1, v18 bitop3:0x48
	v_lshlrev_b32_e32 v95, 7, v55
	v_lshlrev_b32_e32 v83, 7, v18
	v_lshl_or_b32 v18, v16, 7, v17
	v_lshl_or_b32 v19, v20, 7, v17
	v_lshl_or_b32 v20, v54, 7, v17
	v_lshl_or_b32 v17, v56, 7, v17
	v_bitop3_b32 v16, v95, v57, v82 bitop3:0xf6
	global_load_dwordx4 v[54:57], v[0:1], off offset:128
	global_load_dwordx4 v[58:61], v[6:7], off offset:128
	global_load_dwordx4 v[62:65], v[2:3], off offset:128
	global_load_dwordx4 v[66:69], v[4:5], off offset:128
	global_load_dwordx4 v[70:73], v[8:9], off offset:128
	global_load_dwordx4 v[74:77], v[10:11], off offset:128
	global_load_dwordx4 v[78:81], v[12:13], off offset:128
	global_load_dwordx4 v[104:107], v[14:15], off offset:128
	v_bitop3_b32 v21, v21, v82, s1 bitop3:0x6c
	v_add_u32_e32 v94, 0xffffe680, v94
	s_movk_i32 s1, 0x1c0
	v_and_or_b32 v103, v175, 64, v84
	s_mov_b64 s[4:5], 0x60
	s_waitcnt vmcnt(15)
	ds_write_b128 v18, v[22:25]
	s_waitcnt vmcnt(13)
	ds_write_b128 v18, v[38:41] offset:32768
	s_waitcnt vmcnt(12)
	ds_write_b128 v19, v[26:29]
	ds_write_b128 v20, v[30:33]
	s_waitcnt vmcnt(11)
	ds_write_b128 v17, v[34:37]
	s_waitcnt vmcnt(10)
	ds_write_b128 v19, v[42:45] offset:32768
	s_waitcnt vmcnt(9)
	ds_write_b128 v20, v[46:49] offset:32768
	s_waitcnt vmcnt(8)
	ds_write_b128 v17, v[50:53] offset:32768
	s_waitcnt lgkmcnt(0)
	s_barrier
	s_setprio 2
	ds_read_b128 v[22:25], v16
	v_and_b32_e32 v26, 0x2780, v83
	v_or_b32_e32 v28, v26, v21
	ds_read_b128 v[30:33], v28 offset:32768
	s_waitcnt lgkmcnt(0)
	v_mfma_f32_16x16x32_f16 v[42:45], v[22:25], v[30:33], 0
	ds_read_b128 v[34:37], v16 offset:2048
	s_waitcnt lgkmcnt(0)
	v_mfma_f32_16x16x32_f16 v[116:119], v[34:37], v[30:33], 0
	ds_read_b128 v[38:41], v28 offset:34816
	ds_read_b128 v[128:131], v16 offset:4096
	s_waitcnt lgkmcnt(0)
	v_mfma_f32_16x16x32_f16 v[136:139], v[128:131], v[30:33], 0
	ds_read_b128 v[50:53], v28 offset:36864
	ds_read_b128 v[132:135], v16 offset:6144
	s_waitcnt lgkmcnt(0)
	v_mfma_f32_16x16x32_f16 v[154:157], v[132:135], v[30:33], 0
	ds_read_b128 v[108:111], v28 offset:38912
	v_mfma_f32_16x16x32_f16 v[46:49], v[22:25], v[38:41], 0
	v_bitop3_b32 v29, v95, v21, 64 bitop3:0xf6
	v_mfma_f32_16x16x32_f16 v[112:115], v[22:25], v[50:53], 0
	ds_read_b128 v[158:161], v29
	s_waitcnt lgkmcnt(1)
	v_mfma_f32_16x16x32_f16 v[22:25], v[22:25], v[108:111], 0
	ds_read_b128 v[162:165], v29 offset:2048
	v_mfma_f32_16x16x32_f16 v[120:123], v[34:37], v[38:41], 0
	v_xor_b32_e32 v21, 64, v21
	v_mfma_f32_16x16x32_f16 v[124:127], v[34:37], v[50:53], 0
	v_ashrrev_i32_e32 v95, 12, v99
	v_mfma_f32_16x16x32_f16 v[34:37], v[34:37], v[108:111], 0
	v_and_b32_e32 v99, 0xfc0, v99
	v_mfma_f32_16x16x32_f16 v[140:143], v[128:131], v[38:41], 0
	v_lshlrev_b32_e32 v150, 1, v99
	v_or_b32_e32 v32, v26, v21
	v_mfma_f32_16x16x32_f16 v[144:147], v[128:131], v[50:53], 0
	ds_read_b128 v[166:169], v32 offset:34816
	ds_read_b128 v[188:191], v32 offset:36864
	v_mfma_f32_16x16x32_f16 v[128:131], v[128:131], v[108:111], 0
	ds_read_b128 v[192:195], v32 offset:38912
	s_waitcnt vmcnt(7)
	ds_write_b128 v18, v[54:57] offset:16384
	v_mfma_f32_16x16x32_f16 v[38:41], v[132:135], v[38:41], 0
	s_waitcnt vmcnt(5)
	ds_write_b128 v19, v[62:65] offset:16384
	v_mfma_f32_16x16x32_f16 v[50:53], v[132:135], v[50:53], 0
	s_waitcnt vmcnt(4)
	ds_write_b128 v20, v[66:69] offset:16384
	v_mfma_f32_16x16x32_f16 v[108:111], v[132:135], v[108:111], 0
	ds_read_b128 v[132:135], v32 offset:32768
	s_waitcnt lgkmcnt(6)
	v_mfma_f32_16x16x32_f16 v[46:49], v[158:161], v[166:169], v[46:49]
	s_waitcnt vmcnt(3)
	ds_write_b128 v17, v[70:73] offset:16384
	s_waitcnt lgkmcnt(6)
; #define GL_LOAD(s_, kt_) if (VAR != 1) { a##s_##0 = GL_A(0, kt_); a##s_##1 = GL_A(1, kt_); a##s_##2 = GL_A(2, kt_); a##s_##3 = GL_A(3, kt_); b##s_##0 = GL_B(0, kt_); b##s_##1 = GL_B(1, kt_); b##s_##2 = GL_B(2, kt_); b##s_##3 = GL_B(3, kt_); }
; #define LDS_STORE(s_, buf_) if (VAR != 2) { LDS_ST1(sA, 0, buf_, a##s_##0) LDS_ST1(sA, 1, buf_, a##s_##1) LDS_ST1(sA, 2, buf_, a##s_##2) LDS_ST1(sA, 3, buf_, a##s_##3) LDS_ST1(sB, 0, buf_, b##s_##0) LDS_ST1(sB, 1, buf_, b##s_##1) LDS_ST1(sB, 2, buf_, b##s_##2) LDS_ST1(sB, 3, buf_, b##s_##3) }
;     ...
;   for (int kt = 0; kt < nk; kt += 2) {
;     if (kt + 2 < nk) { GL_LOAD(0, kt + 2) }
;     MMA_TILE(0)
;     LDS_STORE(1, 1)
;     if (VAR != 4) __syncthreads();
;     if (kt + 3 < nk) { GL_LOAD(1, kt + 3) }
;     MMA_TILE(1)
;     if (kt + 2 < nk) { LDS_STORE(0, 0) }
;     if (VAR != 4) __syncthreads();
	v_mfma_f32_16x16x32_f16 v[112:115], v[158:161], v[188:191], v[112:115]
	ds_write_b128 v18, v[58:61] offset:49152
	s_waitcnt lgkmcnt(6)
	v_mfma_f32_16x16x32_f16 v[22:25], v[158:161], v[192:195], v[22:25]
	s_waitcnt vmcnt(2)
	ds_write_b128 v19, v[74:77] offset:49152
	v_mfma_f32_16x16x32_f16 v[120:123], v[162:165], v[166:169], v[120:123]
	s_waitcnt vmcnt(1)
	ds_write_b128 v20, v[78:81] offset:49152
	v_mfma_f32_16x16x32_f16 v[124:127], v[162:165], v[188:191], v[124:127]
	s_waitcnt vmcnt(0)
	ds_write_b128 v17, v[104:107] offset:49152
	v_mfma_f32_16x16x32_f16 v[34:37], v[162:165], v[192:195], v[34:37]
	s_waitcnt lgkmcnt(5)
	v_mfma_f32_16x16x32_f16 v[42:45], v[158:161], v[132:135], v[42:45]
	ds_read_b128 v[158:161], v29 offset:4096
	v_mfma_f32_16x16x32_f16 v[116:119], v[162:165], v[132:135], v[116:119]
	ds_read_b128 v[162:165], v29 offset:6144
	s_waitcnt lgkmcnt(1)
	v_mfma_f32_16x16x32_f16 v[136:139], v[158:161], v[132:135], v[136:139]
	v_mfma_f32_16x16x32_f16 v[140:143], v[158:161], v[166:169], v[140:143]
	s_waitcnt lgkmcnt(0)
	v_mfma_f32_16x16x32_f16 v[132:135], v[162:165], v[132:135], v[154:157]
	s_nop 2
	global_load_dwordx4 v[154:157], v[0:1], off offset:256
	v_mfma_f32_16x16x32_f16 v[38:41], v[162:165], v[166:169], v[38:41]
	v_mfma_f32_16x16x32_f16 v[144:147], v[158:161], v[188:191], v[144:147]
	v_mfma_f32_16x16x32_f16 v[128:131], v[158:161], v[192:195], v[128:131]
	global_load_dwordx4 v[158:161], v[2:3], off offset:256
	global_load_dwordx4 v[196:199], v[4:5], off offset:256
	global_load_dwordx4 v[200:203], v[8:9], off offset:256
	global_load_dwordx4 v[166:169], v[6:7], off offset:256
	global_load_dwordx4 v[204:207], v[10:11], off offset:256
	global_load_dwordx4 v[208:211], v[12:13], off offset:256
	global_load_dwordx4 v[212:215], v[14:15], off offset:256
	s_waitcnt lgkmcnt(0)
	s_barrier
	v_mfma_f32_16x16x32_f16 v[58:61], v[162:165], v[192:195], v[108:111]
	ds_read_b128 v[54:57], v16 offset:16384
	v_mfma_f32_16x16x32_f16 v[50:53], v[162:165], v[188:191], v[50:53]
	ds_read_b128 v[62:65], v28 offset:49152
	s_waitcnt lgkmcnt(0)
	v_mfma_f32_16x16x32_f16 v[42:45], v[54:57], v[62:65], v[42:45]
	ds_read_b128 v[66:69], v16 offset:18432
	ds_read_b128 v[70:73], v28 offset:51200
	s_waitcnt lgkmcnt(0)
	v_mfma_f32_16x16x32_f16 v[46:49], v[54:57], v[70:73], v[46:49]
	ds_read_b128 v[74:77], v28 offset:53248
	s_waitcnt lgkmcnt(0)
	v_mfma_f32_16x16x32_f16 v[104:107], v[54:57], v[74:77], v[112:115]
	ds_read_b128 v[78:81], v28 offset:55296
	s_waitcnt lgkmcnt(0)
	v_mfma_f32_16x16x32_f16 v[22:25], v[54:57], v[78:81], v[22:25]
	v_mfma_f32_16x16x32_f16 v[54:57], v[66:69], v[62:65], v[116:119]
	s_nop 2
	ds_read_b128 v[116:119], v16 offset:22528
	v_mfma_f32_16x16x32_f16 v[108:111], v[66:69], v[70:73], v[120:123]
	s_waitcnt vmcnt(7)
	ds_write_b128 v18, v[154:157]
	s_waitcnt vmcnt(6)
	ds_write_b128 v19, v[158:161]
	s_waitcnt vmcnt(5)
	ds_write_b128 v20, v[196:199]
	v_mfma_f32_16x16x32_f16 v[112:115], v[66:69], v[74:77], v[124:127]
	s_waitcnt vmcnt(4)
	ds_write_b128 v17, v[200:203]
	v_mfma_f32_16x16x32_f16 v[34:37], v[66:69], v[78:81], v[34:37]
	ds_read_b128 v[66:69], v16 offset:20480
	s_waitcnt lgkmcnt(0)
	v_mfma_f32_16x16x32_f16 v[124:127], v[66:69], v[70:73], v[140:143]
	s_waitcnt vmcnt(3)
	ds_write_b128 v18, v[166:169] offset:32768
	v_mfma_f32_16x16x32_f16 v[120:123], v[66:69], v[62:65], v[136:139]
	s_waitcnt vmcnt(2)
	ds_write_b128 v19, v[204:207] offset:32768
	v_mfma_f32_16x16x32_f16 v[38:41], v[116:119], v[70:73], v[38:41]
	ds_read_b128 v[70:73], v29 offset:16384
	v_mfma_f32_16x16x32_f16 v[62:65], v[116:119], v[62:65], v[132:135]
	s_nop 2
	ds_read_b128 v[132:135], v32 offset:55296
	v_mfma_f32_16x16x32_f16 v[136:139], v[66:69], v[74:77], v[144:147]
	s_waitcnt vmcnt(1)
	ds_write_b128 v20, v[208:211] offset:32768
	v_mfma_f32_16x16x32_f16 v[66:69], v[66:69], v[78:81], v[128:131]
	s_nop 2
	ds_read_b128 v[128:131], v32 offset:53248
	v_mfma_f32_16x16x32_f16 v[50:53], v[116:119], v[74:77], v[50:53]
	ds_read_b128 v[74:77], v32 offset:49152
	v_mfma_f32_16x16x32_f16 v[58:61], v[116:119], v[78:81], v[58:61]
	ds_read_b128 v[78:81], v29 offset:18432
	s_waitcnt lgkmcnt(1)
	v_mfma_f32_16x16x32_f16 v[42:45], v[70:73], v[74:77], v[42:45]
	ds_read_b128 v[116:119], v32 offset:51200
	s_waitcnt lgkmcnt(0)
	v_mfma_f32_16x16x32_f16 v[46:49], v[70:73], v[116:119], v[46:49]
	s_waitcnt vmcnt(0)
	ds_write_b128 v17, v[212:215] offset:32768
	v_mfma_f32_16x16x32_f16 v[54:57], v[78:81], v[74:77], v[54:57]
	v_mfma_f32_16x16x32_f16 v[104:107], v[70:73], v[128:131], v[104:107]
	v_mfma_f32_16x16x32_f16 v[22:25], v[70:73], v[132:135], v[22:25]
	v_mfma_f32_16x16x32_f16 v[70:73], v[78:81], v[116:119], v[108:111]
	v_mfma_f32_16x16x32_f16 v[108:111], v[78:81], v[128:131], v[112:115]
	s_nop 2
	ds_read_b128 v[112:115], v29 offset:22528
	v_mfma_f32_16x16x32_f16 v[34:37], v[78:81], v[132:135], v[34:37]
	ds_read_b128 v[78:81], v29 offset:20480
	s_waitcnt lgkmcnt(0)
	v_mfma_f32_16x16x32_f16 v[120:123], v[78:81], v[74:77], v[120:123]
	v_mfma_f32_16x16x32_f16 v[124:127], v[78:81], v[116:119], v[124:127]
	v_mfma_f32_16x16x32_f16 v[62:65], v[112:115], v[74:77], v[62:65]
	global_load_dwordx4 v[74:77], v[0:1], off offset:384
	v_mfma_f32_16x16x32_f16 v[38:41], v[112:115], v[116:119], v[38:41]
	v_mfma_f32_16x16x32_f16 v[136:139], v[78:81], v[128:131], v[136:139]
	v_mfma_f32_16x16x32_f16 v[66:69], v[78:81], v[132:135], v[66:69]
	global_load_dwordx4 v[78:81], v[2:3], off offset:384
	global_load_dwordx4 v[140:143], v[4:5], off offset:384
	v_mfma_f32_16x16x32_f16 v[50:53], v[112:115], v[128:131], v[50:53]
	global_load_dwordx4 v[144:147], v[8:9], off offset:384
	global_load_dwordx4 v[116:119], v[6:7], off offset:384
	global_load_dwordx4 v[162:165], v[10:11], off offset:384
	global_load_dwordx4 v[188:191], v[12:13], off offset:384
	global_load_dwordx4 v[192:195], v[14:15], off offset:384
	s_waitcnt lgkmcnt(0)
	s_barrier
; #define GL_LOAD(s_, kt_) if (VAR != 1) { a##s_##0 = GL_A(0, kt_); a##s_##1 = GL_A(1, kt_); a##s_##2 = GL_A(2, kt_); a##s_##3 = GL_A(3, kt_); b##s_##0 = GL_B(0, kt_); b##s_##1 = GL_B(1, kt_); b##s_##2 = GL_B(2, kt_); b##s_##3 = GL_B(3, kt_); }
; #define LDS_STORE(s_, buf_) if (VAR != 2) { LDS_ST1(sA, 0, buf_, a##s_##0) LDS_ST1(sA, 1, buf_, a##s_##1) LDS_ST1(sA, 2, buf_, a##s_##2) LDS_ST1(sA, 3, buf_, a##s_##3) LDS_ST1(sB, 0, buf_, b##s_##0) LDS_ST1(sB, 1, buf_, b##s_##1) LDS_ST1(sB, 2, buf_, b##s_##2) LDS_ST1(sB, 3, buf_, b##s_##3) }
;     ...
;   for (int kt = 0; kt < nk; kt += 2) {
;     if (kt + 2 < nk) { GL_LOAD(0, kt + 2) }
;     MMA_TILE(0)
;     LDS_STORE(1, 1)
;     if (VAR != 4) __syncthreads();
;     if (kt + 3 < nk) { GL_LOAD(1, kt + 3) }
;     MMA_TILE(1)
;     if (kt + 2 < nk) { LDS_STORE(0, 0) }
;     if (VAR != 4) __syncthreads();
	v_mfma_f32_16x16x32_f16 v[58:61], v[112:115], v[132:135], v[58:61]
	ds_read_b128 v[128:131], v16
	ds_read_b128 v[112:115], v28 offset:32768
	s_waitcnt lgkmcnt(0)
	v_mfma_f32_16x16x32_f16 v[42:45], v[128:131], v[112:115], v[42:45]
	ds_read_b128 v[132:135], v16 offset:2048
	ds_read_b128 v[154:157], v28 offset:34816
	s_waitcnt lgkmcnt(0)
	v_mfma_f32_16x16x32_f16 v[46:49], v[128:131], v[154:157], v[46:49]
	ds_read_b128 v[158:161], v28 offset:36864
	v_mfma_f32_16x16x32_f16 v[54:57], v[132:135], v[112:115], v[54:57]
	ds_read_b128 v[166:169], v28 offset:38912
	v_mfma_f32_16x16x32_f16 v[70:73], v[132:135], v[154:157], v[70:73]
	s_waitcnt vmcnt(7)
	ds_write_b128 v18, v[74:77] offset:16384
	s_waitcnt lgkmcnt(2)
	v_mfma_f32_16x16x32_f16 v[104:107], v[128:131], v[158:161], v[104:107]
	s_waitcnt vmcnt(6)
	ds_write_b128 v19, v[78:81] offset:16384
	s_waitcnt lgkmcnt(2)
	v_mfma_f32_16x16x32_f16 v[22:25], v[128:131], v[166:169], v[22:25]
	ds_read_b128 v[128:131], v16 offset:4096
	v_mfma_f32_16x16x32_f16 v[108:111], v[132:135], v[158:161], v[108:111]
	s_waitcnt vmcnt(5)
	ds_write_b128 v20, v[140:143] offset:16384
	v_mfma_f32_16x16x32_f16 v[34:37], v[132:135], v[166:169], v[34:37]
	ds_read_b128 v[132:135], v16 offset:6144
	s_waitcnt lgkmcnt(2)
	v_mfma_f32_16x16x32_f16 v[120:123], v[128:131], v[112:115], v[120:123]
	s_waitcnt vmcnt(4)
	ds_write_b128 v17, v[144:147] offset:16384
	v_mfma_f32_16x16x32_f16 v[124:127], v[128:131], v[154:157], v[124:127]
	s_waitcnt vmcnt(3)
	ds_write_b128 v18, v[116:119] offset:49152
	s_waitcnt lgkmcnt(2)
	v_mfma_f32_16x16x32_f16 v[62:65], v[132:135], v[112:115], v[62:65]
	ds_read_b128 v[112:115], v29
	v_mfma_f32_16x16x32_f16 v[38:41], v[132:135], v[154:157], v[38:41]
	ds_read_b128 v[154:157], v32 offset:34816
	v_mfma_f32_16x16x32_f16 v[136:139], v[128:131], v[158:161], v[136:139]
	s_waitcnt vmcnt(2)
	ds_write_b128 v19, v[162:165] offset:49152
	v_mfma_f32_16x16x32_f16 v[66:69], v[128:131], v[166:169], v[66:69]
	ds_read_b128 v[128:131], v32 offset:32768
	v_mfma_f32_16x16x32_f16 v[50:53], v[132:135], v[158:161], v[50:53]
	ds_read_b128 v[158:161], v32 offset:36864
	v_mfma_f32_16x16x32_f16 v[58:61], v[132:135], v[166:169], v[58:61]
	ds_read_b128 v[132:135], v29 offset:2048
	s_waitcnt lgkmcnt(2)
	v_mfma_f32_16x16x32_f16 v[42:45], v[112:115], v[128:131], v[42:45]
	ds_read_b128 v[166:169], v32 offset:38912
	v_mfma_f32_16x16x32_f16 v[46:49], v[112:115], v[154:157], v[46:49]
	s_waitcnt vmcnt(1)
	ds_write_b128 v20, v[188:191] offset:49152
	s_waitcnt lgkmcnt(2)
	v_mfma_f32_16x16x32_f16 v[54:57], v[132:135], v[128:131], v[54:57]
	s_waitcnt vmcnt(0)
	ds_write_b128 v17, v[192:195] offset:49152
	v_mfma_f32_16x16x32_f16 v[70:73], v[132:135], v[154:157], v[70:73]
	v_mfma_f32_16x16x32_f16 v[104:107], v[112:115], v[158:161], v[104:107]
	s_waitcnt lgkmcnt(2)
	v_mfma_f32_16x16x32_f16 v[22:25], v[112:115], v[166:169], v[22:25]
	ds_read_b128 v[112:115], v29 offset:4096
	v_mfma_f32_16x16x32_f16 v[108:111], v[132:135], v[158:161], v[108:111]
	v_mfma_f32_16x16x32_f16 v[34:37], v[132:135], v[166:169], v[34:37]
	ds_read_b128 v[132:135], v29 offset:6144
	s_waitcnt lgkmcnt(1)
	v_mfma_f32_16x16x32_f16 v[120:123], v[112:115], v[128:131], v[120:123]
	v_mfma_f32_16x16x32_f16 v[124:127], v[112:115], v[154:157], v[124:127]
	s_waitcnt lgkmcnt(0)
	v_mfma_f32_16x16x32_f16 v[62:65], v[132:135], v[128:131], v[62:65]
	v_mfma_f32_16x16x32_f16 v[38:41], v[132:135], v[154:157], v[38:41]
	v_mfma_f32_16x16x32_f16 v[136:139], v[112:115], v[158:161], v[136:139]
	v_mfma_f32_16x16x32_f16 v[66:69], v[112:115], v[166:169], v[66:69]
	global_load_dwordx4 v[112:115], v[0:1], off offset:512
	global_load_dwordx4 v[128:131], v[2:3], off offset:512
	global_load_dwordx4 v[196:199], v[4:5], off offset:512
	global_load_dwordx4 v[200:203], v[8:9], off offset:512
	global_load_dwordx4 v[154:157], v[6:7], off offset:512
	global_load_dwordx4 v[204:207], v[10:11], off offset:512
	global_load_dwordx4 v[208:211], v[12:13], off offset:512
	global_load_dwordx4 v[212:215], v[14:15], off offset:512
	s_waitcnt lgkmcnt(0)
	s_barrier
	v_mfma_f32_16x16x32_f16 v[50:53], v[132:135], v[158:161], v[50:53]
	ds_read_b128 v[74:77], v16 offset:16384
	v_mfma_f32_16x16x32_f16 v[58:61], v[132:135], v[166:169], v[58:61]
	ds_read_b128 v[78:81], v28 offset:49152
	s_waitcnt lgkmcnt(0)
	v_mfma_f32_16x16x32_f16 v[42:45], v[74:77], v[78:81], v[42:45]
	ds_read_b128 v[116:119], v16 offset:18432
	ds_read_b128 v[132:135], v28 offset:51200
	s_waitcnt lgkmcnt(0)
	v_mfma_f32_16x16x32_f16 v[46:49], v[74:77], v[132:135], v[46:49]
	ds_read_b128 v[140:143], v28 offset:53248
	v_mfma_f32_16x16x32_f16 v[54:57], v[116:119], v[78:81], v[54:57]
	ds_read_b128 v[144:147], v28 offset:55296
	v_mfma_f32_16x16x32_f16 v[70:73], v[116:119], v[132:135], v[70:73]
	s_waitcnt vmcnt(7)
	ds_write_b128 v18, v[112:115]
	s_waitcnt lgkmcnt(2)
	v_mfma_f32_16x16x32_f16 v[104:107], v[74:77], v[140:143], v[104:107]
	s_waitcnt vmcnt(6)
	ds_write_b128 v19, v[128:131]
	s_waitcnt lgkmcnt(2)
	v_mfma_f32_16x16x32_f16 v[22:25], v[74:77], v[144:147], v[22:25]
	s_waitcnt vmcnt(5)
	ds_write_b128 v20, v[196:199]
	v_mfma_f32_16x16x32_f16 v[74:77], v[116:119], v[140:143], v[108:111]
	s_nop 2
	ds_read_b128 v[108:111], v16 offset:20480
	v_mfma_f32_16x16x32_f16 v[34:37], v[116:119], v[144:147], v[34:37]
	ds_read_b128 v[116:119], v16 offset:22528
	s_waitcnt lgkmcnt(1)
	v_mfma_f32_16x16x32_f16 v[120:123], v[108:111], v[78:81], v[120:123]
	s_waitcnt vmcnt(4)
	ds_write_b128 v17, v[200:203]
	v_mfma_f32_16x16x32_f16 v[124:127], v[108:111], v[132:135], v[124:127]
	s_waitcnt vmcnt(3)
	ds_write_b128 v18, v[154:157] offset:32768
	s_waitcnt lgkmcnt(2)
; #define GL_LOAD(s_, kt_) if (VAR != 1) { a##s_##0 = GL_A(0, kt_); a##s_##1 = GL_A(1, kt_); a##s_##2 = GL_A(2, kt_); a##s_##3 = GL_A(3, kt_); b##s_##0 = GL_B(0, kt_); b##s_##1 = GL_B(1, kt_); b##s_##2 = GL_B(2, kt_); b##s_##3 = GL_B(3, kt_); }
; #define LDS_STORE(s_, buf_) if (VAR != 2) { LDS_ST1(sA, 0, buf_, a##s_##0) LDS_ST1(sA, 1, buf_, a##s_##1) LDS_ST1(sA, 2, buf_, a##s_##2) LDS_ST1(sA, 3, buf_, a##s_##3) LDS_ST1(sB, 0, buf_, b##s_##0) LDS_ST1(sB, 1, buf_, b##s_##1) LDS_ST1(sB, 2, buf_, b##s_##2) LDS_ST1(sB, 3, buf_, b##s_##3) }
;     ...
;   for (int kt = 0; kt < nk; kt += 2) {
;     if (kt + 2 < nk) { GL_LOAD(0, kt + 2) }
;     MMA_TILE(0)
;     LDS_STORE(1, 1)
;     if (VAR != 4) __syncthreads();
;     if (kt + 3 < nk) { GL_LOAD(1, kt + 3) }
;     MMA_TILE(1)
;     if (kt + 2 < nk) { LDS_STORE(0, 0) }
;     if (VAR != 4) __syncthreads();
	v_mfma_f32_16x16x32_f16 v[62:65], v[116:119], v[78:81], v[62:65]
	ds_read_b128 v[78:81], v29 offset:16384
	v_mfma_f32_16x16x32_f16 v[38:41], v[116:119], v[132:135], v[38:41]
	ds_read_b128 v[132:135], v32 offset:51200
	v_mfma_f32_16x16x32_f16 v[136:139], v[108:111], v[140:143], v[136:139]
	s_waitcnt vmcnt(2)
	ds_write_b128 v19, v[204:207] offset:32768
	v_mfma_f32_16x16x32_f16 v[66:69], v[108:111], v[144:147], v[66:69]
	ds_read_b128 v[108:111], v32 offset:49152
	v_mfma_f32_16x16x32_f16 v[50:53], v[116:119], v[140:143], v[50:53]
	ds_read_b128 v[140:143], v32 offset:53248
	v_mfma_f32_16x16x32_f16 v[58:61], v[116:119], v[144:147], v[58:61]
	ds_read_b128 v[116:119], v29 offset:18432
	s_waitcnt lgkmcnt(2)
	v_mfma_f32_16x16x32_f16 v[42:45], v[78:81], v[108:111], v[42:45]
	ds_read_b128 v[144:147], v32 offset:55296
	v_mfma_f32_16x16x32_f16 v[46:49], v[78:81], v[132:135], v[46:49]
	s_waitcnt vmcnt(1)
	ds_write_b128 v20, v[208:211] offset:32768
	s_waitcnt lgkmcnt(2)
	v_mfma_f32_16x16x32_f16 v[54:57], v[116:119], v[108:111], v[54:57]
	s_waitcnt vmcnt(0)
	ds_write_b128 v17, v[212:215] offset:32768
	v_mfma_f32_16x16x32_f16 v[70:73], v[116:119], v[132:135], v[70:73]
	v_mfma_f32_16x16x32_f16 v[104:107], v[78:81], v[140:143], v[104:107]
	s_waitcnt lgkmcnt(2)
	v_mfma_f32_16x16x32_f16 v[22:25], v[78:81], v[144:147], v[22:25]
	ds_read_b128 v[78:81], v29 offset:20480
	v_mfma_f32_16x16x32_f16 v[74:77], v[116:119], v[140:143], v[74:77]
	v_mfma_f32_16x16x32_f16 v[34:37], v[116:119], v[144:147], v[34:37]
	ds_read_b128 v[116:119], v29 offset:22528
	s_waitcnt lgkmcnt(1)
	v_mfma_f32_16x16x32_f16 v[120:123], v[78:81], v[108:111], v[120:123]
	v_mfma_f32_16x16x32_f16 v[124:127], v[78:81], v[132:135], v[124:127]
	s_waitcnt lgkmcnt(0)
	v_mfma_f32_16x16x32_f16 v[62:65], v[116:119], v[108:111], v[62:65]
	v_mfma_f32_16x16x32_f16 v[38:41], v[116:119], v[132:135], v[38:41]
	v_mfma_f32_16x16x32_f16 v[136:139], v[78:81], v[140:143], v[136:139]
	v_mfma_f32_16x16x32_f16 v[66:69], v[78:81], v[144:147], v[66:69]
	global_load_dwordx4 v[78:81], v[0:1], off offset:640
	global_load_dwordx4 v[108:111], v[2:3], off offset:640
	global_load_dwordx4 v[158:161], v[4:5], off offset:640
	global_load_dwordx4 v[162:165], v[8:9], off offset:640
	global_load_dwordx4 v[132:135], v[6:7], off offset:640
	global_load_dwordx4 v[166:169], v[10:11], off offset:640
	global_load_dwordx4 v[188:191], v[12:13], off offset:640
	global_load_dwordx4 v[192:195], v[14:15], off offset:640
	s_waitcnt lgkmcnt(0)
	s_barrier
	v_mfma_f32_16x16x32_f16 v[50:53], v[116:119], v[140:143], v[50:53]
	ds_read_b128 v[112:115], v16
	v_mfma_f32_16x16x32_f16 v[58:61], v[116:119], v[144:147], v[58:61]
	ds_read_b128 v[116:119], v28 offset:32768
	s_waitcnt lgkmcnt(0)
	v_mfma_f32_16x16x32_f16 v[42:45], v[112:115], v[116:119], v[42:45]
	ds_read_b128 v[128:131], v16 offset:2048
	ds_read_b128 v[140:143], v28 offset:34816
	s_waitcnt lgkmcnt(0)
	v_mfma_f32_16x16x32_f16 v[46:49], v[112:115], v[140:143], v[46:49]
	ds_read_b128 v[144:147], v28 offset:36864
	v_mfma_f32_16x16x32_f16 v[54:57], v[128:131], v[116:119], v[54:57]
	ds_read_b128 v[154:157], v28 offset:38912
	v_mfma_f32_16x16x32_f16 v[70:73], v[128:131], v[140:143], v[70:73]
	s_waitcnt vmcnt(7)
	ds_write_b128 v18, v[78:81] offset:16384
	s_waitcnt lgkmcnt(2)
	v_mfma_f32_16x16x32_f16 v[104:107], v[112:115], v[144:147], v[104:107]
	s_waitcnt vmcnt(6)
	ds_write_b128 v19, v[108:111] offset:16384
	s_waitcnt lgkmcnt(2)
	v_mfma_f32_16x16x32_f16 v[22:25], v[112:115], v[154:157], v[22:25]
	ds_read_b128 v[112:115], v16 offset:4096
	v_mfma_f32_16x16x32_f16 v[74:77], v[128:131], v[144:147], v[74:77]
	s_waitcnt vmcnt(5)
	ds_write_b128 v20, v[158:161] offset:16384
	v_mfma_f32_16x16x32_f16 v[34:37], v[128:131], v[154:157], v[34:37]
	ds_read_b128 v[128:131], v16 offset:6144
	s_waitcnt lgkmcnt(2)
	v_mfma_f32_16x16x32_f16 v[120:123], v[112:115], v[116:119], v[120:123]
	s_waitcnt vmcnt(4)
	ds_write_b128 v17, v[162:165] offset:16384
	v_mfma_f32_16x16x32_f16 v[124:127], v[112:115], v[140:143], v[124:127]
	s_waitcnt vmcnt(3)
	ds_write_b128 v18, v[132:135] offset:49152
	s_waitcnt lgkmcnt(2)
	v_mfma_f32_16x16x32_f16 v[62:65], v[128:131], v[116:119], v[62:65]
	ds_read_b128 v[116:119], v32 offset:32768
	v_mfma_f32_16x16x32_f16 v[38:41], v[128:131], v[140:143], v[38:41]
	ds_read_b128 v[140:143], v32 offset:34816
	v_mfma_f32_16x16x32_f16 v[136:139], v[112:115], v[144:147], v[136:139]
	s_waitcnt vmcnt(2)
	ds_write_b128 v19, v[166:169] offset:49152
	v_mfma_f32_16x16x32_f16 v[66:69], v[112:115], v[154:157], v[66:69]
	ds_read_b128 v[112:115], v29
	v_mfma_f32_16x16x32_f16 v[50:53], v[128:131], v[144:147], v[50:53]
	ds_read_b128 v[144:147], v32 offset:36864
	v_mfma_f32_16x16x32_f16 v[58:61], v[128:131], v[154:157], v[58:61]
	ds_read_b128 v[128:131], v29 offset:2048
	s_waitcnt lgkmcnt(2)
	v_mfma_f32_16x16x32_f16 v[42:45], v[112:115], v[116:119], v[42:45]
	ds_read_b128 v[154:157], v32 offset:38912
	v_mfma_f32_16x16x32_f16 v[46:49], v[112:115], v[140:143], v[46:49]
	s_waitcnt vmcnt(1)
	ds_write_b128 v20, v[188:191] offset:49152
	s_waitcnt lgkmcnt(2)
	v_mfma_f32_16x16x32_f16 v[54:57], v[128:131], v[116:119], v[54:57]
	s_waitcnt vmcnt(0)
	ds_write_b128 v17, v[192:195] offset:49152
	v_mfma_f32_16x16x32_f16 v[70:73], v[128:131], v[140:143], v[70:73]
	v_mfma_f32_16x16x32_f16 v[104:107], v[112:115], v[144:147], v[104:107]
	s_waitcnt lgkmcnt(2)
	v_mfma_f32_16x16x32_f16 v[22:25], v[112:115], v[154:157], v[22:25]
	ds_read_b128 v[112:115], v29 offset:4096
	v_mfma_f32_16x16x32_f16 v[74:77], v[128:131], v[144:147], v[74:77]
	v_mfma_f32_16x16x32_f16 v[34:37], v[128:131], v[154:157], v[34:37]
	ds_read_b128 v[128:131], v29 offset:6144
	s_waitcnt lgkmcnt(1)
	v_mfma_f32_16x16x32_f16 v[120:123], v[112:115], v[116:119], v[120:123]
	v_mfma_f32_16x16x32_f16 v[124:127], v[112:115], v[140:143], v[124:127]
	s_waitcnt lgkmcnt(0)
	v_mfma_f32_16x16x32_f16 v[62:65], v[128:131], v[116:119], v[62:65]
	v_mfma_f32_16x16x32_f16 v[38:41], v[128:131], v[140:143], v[38:41]
	v_mfma_f32_16x16x32_f16 v[136:139], v[112:115], v[144:147], v[136:139]
	v_mfma_f32_16x16x32_f16 v[66:69], v[112:115], v[154:157], v[66:69]
	global_load_dwordx4 v[112:115], v[0:1], off offset:768
	global_load_dwordx4 v[116:119], v[2:3], off offset:768
	global_load_dwordx4 v[196:199], v[4:5], off offset:768
	global_load_dwordx4 v[200:203], v[8:9], off offset:768
	global_load_dwordx4 v[140:143], v[6:7], off offset:768
	global_load_dwordx4 v[204:207], v[10:11], off offset:768
	global_load_dwordx4 v[208:211], v[12:13], off offset:768
	global_load_dwordx4 v[212:215], v[14:15], off offset:768
	s_waitcnt lgkmcnt(0)
	s_barrier
; #define GL_LOAD(s_, kt_) if (VAR != 1) { a##s_##0 = GL_A(0, kt_); a##s_##1 = GL_A(1, kt_); a##s_##2 = GL_A(2, kt_); a##s_##3 = GL_A(3, kt_); b##s_##0 = GL_B(0, kt_); b##s_##1 = GL_B(1, kt_); b##s_##2 = GL_B(2, kt_); b##s_##3 = GL_B(3, kt_); }
; #define LDS_STORE(s_, buf_) if (VAR != 2) { LDS_ST1(sA, 0, buf_, a##s_##0) LDS_ST1(sA, 1, buf_, a##s_##1) LDS_ST1(sA, 2, buf_, a##s_##2) LDS_ST1(sA, 3, buf_, a##s_##3) LDS_ST1(sB, 0, buf_, b##s_##0) LDS_ST1(sB, 1, buf_, b##s_##1) LDS_ST1(sB, 2, buf_, b##s_##2) LDS_ST1(sB, 3, buf_, b##s_##3) }
;     ...
;   GL_LOAD(0, 0)
;   GL_LOAD(1, 1)
;   LDS_STORE(0, 0)
;   if (VAR != 4) __syncthreads();
; #pragma unroll
;   for (int kt = 0; kt < nk; kt += 2) {
;     if (kt + 2 < nk) { GL_LOAD(0, kt + 2) }
;     MMA_TILE(0)
;     LDS_STORE(1, 1)
;     if (VAR != 4) __syncthreads();
;     if (kt + 3 < nk) { GL_LOAD(1, kt + 3) }
;     MMA_TILE(1)
;     if (kt + 2 < nk) { LDS_STORE(0, 0) }
;     if (VAR != 4) __syncthreads();
;   }
	v_mfma_f32_16x16x32_f16 v[50:53], v[128:131], v[144:147], v[50:53]
	ds_read_b128 v[78:81], v16 offset:16384
	v_mfma_f32_16x16x32_f16 v[58:61], v[128:131], v[154:157], v[58:61]
	ds_read_b128 v[108:111], v28 offset:49152
	s_waitcnt lgkmcnt(0)
	v_mfma_f32_16x16x32_f16 v[42:45], v[78:81], v[108:111], v[42:45]
	ds_read_b128 v[128:131], v16 offset:18432
	ds_read_b128 v[132:135], v28 offset:51200
	s_waitcnt lgkmcnt(0)
	v_mfma_f32_16x16x32_f16 v[46:49], v[78:81], v[132:135], v[46:49]
	ds_read_b128 v[144:147], v28 offset:53248
	v_mfma_f32_16x16x32_f16 v[54:57], v[128:131], v[108:111], v[54:57]
	ds_read_b128 v[154:157], v28 offset:55296
	v_mfma_f32_16x16x32_f16 v[70:73], v[128:131], v[132:135], v[70:73]
	s_waitcnt vmcnt(7)
	ds_write_b128 v18, v[112:115]
	s_waitcnt lgkmcnt(2)
	v_mfma_f32_16x16x32_f16 v[104:107], v[78:81], v[144:147], v[104:107]
	s_waitcnt vmcnt(6)
	ds_write_b128 v19, v[116:119]
	s_waitcnt lgkmcnt(2)
	v_mfma_f32_16x16x32_f16 v[22:25], v[78:81], v[154:157], v[22:25]
	ds_read_b128 v[78:81], v16 offset:20480
	v_mfma_f32_16x16x32_f16 v[74:77], v[128:131], v[144:147], v[74:77]
	s_waitcnt vmcnt(5)
	ds_write_b128 v20, v[196:199]
	v_mfma_f32_16x16x32_f16 v[34:37], v[128:131], v[154:157], v[34:37]
	ds_read_b128 v[128:131], v16 offset:22528
	s_waitcnt lgkmcnt(2)
	v_mfma_f32_16x16x32_f16 v[120:123], v[78:81], v[108:111], v[120:123]
	s_waitcnt vmcnt(4)
	ds_write_b128 v17, v[200:203]
	v_mfma_f32_16x16x32_f16 v[124:127], v[78:81], v[132:135], v[124:127]
	s_waitcnt vmcnt(3)
	ds_write_b128 v18, v[140:143] offset:32768
	s_waitcnt lgkmcnt(2)
	v_mfma_f32_16x16x32_f16 v[62:65], v[128:131], v[108:111], v[62:65]
	ds_read_b128 v[108:111], v32 offset:49152
	v_mfma_f32_16x16x32_f16 v[38:41], v[128:131], v[132:135], v[38:41]
	ds_read_b128 v[132:135], v32 offset:51200
	v_mfma_f32_16x16x32_f16 v[136:139], v[78:81], v[144:147], v[136:139]
	s_waitcnt vmcnt(2)
	ds_write_b128 v19, v[204:207] offset:32768
	v_mfma_f32_16x16x32_f16 v[66:69], v[78:81], v[154:157], v[66:69]
	ds_read_b128 v[78:81], v29 offset:16384
	v_mfma_f32_16x16x32_f16 v[50:53], v[128:131], v[144:147], v[50:53]
	ds_read_b128 v[144:147], v32 offset:53248
	v_mfma_f32_16x16x32_f16 v[58:61], v[128:131], v[154:157], v[58:61]
	ds_read_b128 v[128:131], v29 offset:18432
	s_waitcnt lgkmcnt(2)
	v_mfma_f32_16x16x32_f16 v[42:45], v[78:81], v[108:111], v[42:45]
	ds_read_b128 v[154:157], v32 offset:55296
	v_mfma_f32_16x16x32_f16 v[46:49], v[78:81], v[132:135], v[46:49]
	s_waitcnt vmcnt(1)
	ds_write_b128 v20, v[208:211] offset:32768
	s_waitcnt lgkmcnt(2)
	v_mfma_f32_16x16x32_f16 v[54:57], v[128:131], v[108:111], v[54:57]
	s_waitcnt vmcnt(0)
	ds_write_b128 v17, v[212:215] offset:32768
	v_mfma_f32_16x16x32_f16 v[70:73], v[128:131], v[132:135], v[70:73]
	v_mfma_f32_16x16x32_f16 v[104:107], v[78:81], v[144:147], v[104:107]
	s_waitcnt lgkmcnt(2)
	v_mfma_f32_16x16x32_f16 v[22:25], v[78:81], v[154:157], v[22:25]
	ds_read_b128 v[78:81], v29 offset:20480
	v_mfma_f32_16x16x32_f16 v[74:77], v[128:131], v[144:147], v[74:77]
	v_mfma_f32_16x16x32_f16 v[34:37], v[128:131], v[154:157], v[34:37]
	ds_read_b128 v[128:131], v29 offset:22528
	s_waitcnt lgkmcnt(1)
	v_mfma_f32_16x16x32_f16 v[120:123], v[78:81], v[108:111], v[120:123]
	v_mfma_f32_16x16x32_f16 v[124:127], v[78:81], v[132:135], v[124:127]
	s_waitcnt lgkmcnt(0)
	v_mfma_f32_16x16x32_f16 v[62:65], v[128:131], v[108:111], v[62:65]
	v_mfma_f32_16x16x32_f16 v[38:41], v[128:131], v[132:135], v[38:41]
	v_mfma_f32_16x16x32_f16 v[136:139], v[78:81], v[144:147], v[136:139]
	v_mfma_f32_16x16x32_f16 v[66:69], v[78:81], v[154:157], v[66:69]
	global_load_dwordx4 v[78:81], v[0:1], off offset:896
	global_load_dwordx4 v[108:111], v[2:3], off offset:896
	global_load_dwordx4 v[158:161], v[4:5], off offset:896
	global_load_dwordx4 v[162:165], v[8:9], off offset:896
	global_load_dwordx4 v[132:135], v[6:7], off offset:896
	global_load_dwordx4 v[166:169], v[10:11], off offset:896
	global_load_dwordx4 v[188:191], v[12:13], off offset:896
	global_load_dwordx4 v[192:195], v[14:15], off offset:896
	s_waitcnt lgkmcnt(0)
	s_barrier
	v_mfma_f32_16x16x32_f16 v[50:53], v[128:131], v[144:147], v[50:53]
	ds_read_b128 v[112:115], v16
	v_mfma_f32_16x16x32_f16 v[58:61], v[128:131], v[154:157], v[58:61]
	ds_read_b128 v[116:119], v28 offset:32768
	s_waitcnt lgkmcnt(0)
	v_mfma_f32_16x16x32_f16 v[42:45], v[112:115], v[116:119], v[42:45]
	ds_read_b128 v[128:131], v16 offset:2048
	ds_read_b128 v[140:143], v28 offset:34816
	s_waitcnt lgkmcnt(0)
	v_mfma_f32_16x16x32_f16 v[46:49], v[112:115], v[140:143], v[46:49]
	ds_read_b128 v[144:147], v28 offset:36864
	v_mfma_f32_16x16x32_f16 v[54:57], v[128:131], v[116:119], v[54:57]
	ds_read_b128 v[154:157], v28 offset:38912
	v_mfma_f32_16x16x32_f16 v[70:73], v[128:131], v[140:143], v[70:73]
	s_waitcnt vmcnt(7)
	ds_write_b128 v18, v[78:81] offset:16384
	s_waitcnt lgkmcnt(2)
	v_mfma_f32_16x16x32_f16 v[104:107], v[112:115], v[144:147], v[104:107]
	s_waitcnt vmcnt(6)
	ds_write_b128 v19, v[108:111] offset:16384
	s_waitcnt lgkmcnt(2)
	v_mfma_f32_16x16x32_f16 v[22:25], v[112:115], v[154:157], v[22:25]
	ds_read_b128 v[112:115], v16 offset:4096
	v_mfma_f32_16x16x32_f16 v[74:77], v[128:131], v[144:147], v[74:77]
	s_waitcnt vmcnt(5)
	ds_write_b128 v20, v[158:161] offset:16384
	v_mfma_f32_16x16x32_f16 v[34:37], v[128:131], v[154:157], v[34:37]
	ds_read_b128 v[128:131], v16 offset:6144
	s_waitcnt lgkmcnt(2)
	v_mfma_f32_16x16x32_f16 v[120:123], v[112:115], v[116:119], v[120:123]
	s_waitcnt vmcnt(4)
	ds_write_b128 v17, v[162:165] offset:16384
	v_mfma_f32_16x16x32_f16 v[124:127], v[112:115], v[140:143], v[124:127]
	s_waitcnt vmcnt(3)
	ds_write_b128 v18, v[132:135] offset:49152
	s_waitcnt lgkmcnt(2)
; #define GL_LOAD(s_, kt_) if (VAR != 1) { a##s_##0 = GL_A(0, kt_); a##s_##1 = GL_A(1, kt_); a##s_##2 = GL_A(2, kt_); a##s_##3 = GL_A(3, kt_); b##s_##0 = GL_B(0, kt_); b##s_##1 = GL_B(1, kt_); b##s_##2 = GL_B(2, kt_); b##s_##3 = GL_B(3, kt_); }
; #define LDS_STORE(s_, buf_) if (VAR != 2) { LDS_ST1(sA, 0, buf_, a##s_##0) LDS_ST1(sA, 1, buf_, a##s_##1) LDS_ST1(sA, 2, buf_, a##s_##2) LDS_ST1(sA, 3, buf_, a##s_##3) LDS_ST1(sB, 0, buf_, b##s_##0) LDS_ST1(sB, 1, buf_, b##s_##1) LDS_ST1(sB, 2, buf_, b##s_##2) LDS_ST1(sB, 3, buf_, b##s_##3) }
;     ...
;   GL_LOAD(0, 0)
;   GL_LOAD(1, 1)
;   LDS_STORE(0, 0)
;   if (VAR != 4) __syncthreads();
; #pragma unroll
;   for (int kt = 0; kt < nk; kt += 2) {
;     if (kt + 2 < nk) { GL_LOAD(0, kt + 2) }
;     MMA_TILE(0)
;     LDS_STORE(1, 1)
;     if (VAR != 4) __syncthreads();
;     if (kt + 3 < nk) { GL_LOAD(1, kt + 3) }
;     MMA_TILE(1)
;     if (kt + 2 < nk) { LDS_STORE(0, 0) }
;     if (VAR != 4) __syncthreads();
;   }
	v_mfma_f32_16x16x32_f16 v[62:65], v[128:131], v[116:119], v[62:65]
	ds_read_b128 v[116:119], v32 offset:32768
	v_mfma_f32_16x16x32_f16 v[38:41], v[128:131], v[140:143], v[38:41]
	ds_read_b128 v[140:143], v32 offset:34816
	v_mfma_f32_16x16x32_f16 v[136:139], v[112:115], v[144:147], v[136:139]
	s_waitcnt vmcnt(2)
	ds_write_b128 v19, v[166:169] offset:49152
	v_mfma_f32_16x16x32_f16 v[66:69], v[112:115], v[154:157], v[66:69]
	ds_read_b128 v[112:115], v29
	v_mfma_f32_16x16x32_f16 v[50:53], v[128:131], v[144:147], v[50:53]
	ds_read_b128 v[144:147], v32 offset:36864
	v_mfma_f32_16x16x32_f16 v[58:61], v[128:131], v[154:157], v[58:61]
	ds_read_b128 v[128:131], v29 offset:2048
	s_waitcnt lgkmcnt(2)
	v_mfma_f32_16x16x32_f16 v[42:45], v[112:115], v[116:119], v[42:45]
	ds_read_b128 v[154:157], v32 offset:38912
	v_mfma_f32_16x16x32_f16 v[46:49], v[112:115], v[140:143], v[46:49]
	s_waitcnt vmcnt(1)
	ds_write_b128 v20, v[188:191] offset:49152
	s_waitcnt lgkmcnt(2)
	v_mfma_f32_16x16x32_f16 v[54:57], v[128:131], v[116:119], v[54:57]
	s_waitcnt vmcnt(0)
	ds_write_b128 v17, v[192:195] offset:49152
	v_mfma_f32_16x16x32_f16 v[70:73], v[128:131], v[140:143], v[70:73]
	v_mfma_f32_16x16x32_f16 v[104:107], v[112:115], v[144:147], v[104:107]
	s_waitcnt lgkmcnt(2)
	v_mfma_f32_16x16x32_f16 v[22:25], v[112:115], v[154:157], v[22:25]
	ds_read_b128 v[112:115], v29 offset:4096
	v_mfma_f32_16x16x32_f16 v[74:77], v[128:131], v[144:147], v[74:77]
	v_mfma_f32_16x16x32_f16 v[34:37], v[128:131], v[154:157], v[34:37]
	ds_read_b128 v[128:131], v29 offset:6144
	s_waitcnt lgkmcnt(1)
	v_mfma_f32_16x16x32_f16 v[120:123], v[112:115], v[116:119], v[120:123]
	v_mfma_f32_16x16x32_f16 v[124:127], v[112:115], v[140:143], v[124:127]
	s_waitcnt lgkmcnt(0)
	v_mfma_f32_16x16x32_f16 v[62:65], v[128:131], v[116:119], v[62:65]
	v_mfma_f32_16x16x32_f16 v[38:41], v[128:131], v[140:143], v[38:41]
	v_mfma_f32_16x16x32_f16 v[136:139], v[112:115], v[144:147], v[136:139]
	v_mfma_f32_16x16x32_f16 v[66:69], v[112:115], v[154:157], v[66:69]
	global_load_dwordx4 v[112:115], v[0:1], off offset:1024
	global_load_dwordx4 v[116:119], v[2:3], off offset:1024
	global_load_dwordx4 v[196:199], v[4:5], off offset:1024
	global_load_dwordx4 v[200:203], v[8:9], off offset:1024
	global_load_dwordx4 v[140:143], v[6:7], off offset:1024
	global_load_dwordx4 v[204:207], v[10:11], off offset:1024
	global_load_dwordx4 v[208:211], v[12:13], off offset:1024
	global_load_dwordx4 v[212:215], v[14:15], off offset:1024
	s_waitcnt lgkmcnt(0)
	s_barrier
	v_mfma_f32_16x16x32_f16 v[50:53], v[128:131], v[144:147], v[50:53]
	ds_read_b128 v[78:81], v16 offset:16384
	v_mfma_f32_16x16x32_f16 v[58:61], v[128:131], v[154:157], v[58:61]
	ds_read_b128 v[108:111], v28 offset:49152
	s_waitcnt lgkmcnt(0)
	v_mfma_f32_16x16x32_f16 v[42:45], v[78:81], v[108:111], v[42:45]
	ds_read_b128 v[128:131], v16 offset:18432
	ds_read_b128 v[132:135], v28 offset:51200
	s_waitcnt lgkmcnt(0)
	v_mfma_f32_16x16x32_f16 v[46:49], v[78:81], v[132:135], v[46:49]
	ds_read_b128 v[144:147], v28 offset:53248
	v_mfma_f32_16x16x32_f16 v[54:57], v[128:131], v[108:111], v[54:57]
	ds_read_b128 v[154:157], v28 offset:55296
	v_mfma_f32_16x16x32_f16 v[70:73], v[128:131], v[132:135], v[70:73]
	s_waitcnt vmcnt(7)
	ds_write_b128 v18, v[112:115]
	s_waitcnt lgkmcnt(2)
	v_mfma_f32_16x16x32_f16 v[104:107], v[78:81], v[144:147], v[104:107]
	s_waitcnt vmcnt(6)
	ds_write_b128 v19, v[116:119]
	s_waitcnt lgkmcnt(2)
	v_mfma_f32_16x16x32_f16 v[22:25], v[78:81], v[154:157], v[22:25]
	ds_read_b128 v[78:81], v16 offset:20480
	v_mfma_f32_16x16x32_f16 v[74:77], v[128:131], v[144:147], v[74:77]
	s_waitcnt vmcnt(5)
	ds_write_b128 v20, v[196:199]
	v_mfma_f32_16x16x32_f16 v[34:37], v[128:131], v[154:157], v[34:37]
	ds_read_b128 v[128:131], v16 offset:22528
	s_waitcnt lgkmcnt(2)
	v_mfma_f32_16x16x32_f16 v[120:123], v[78:81], v[108:111], v[120:123]
	s_waitcnt vmcnt(4)
	ds_write_b128 v17, v[200:203]
	v_mfma_f32_16x16x32_f16 v[124:127], v[78:81], v[132:135], v[124:127]
	s_waitcnt vmcnt(3)
	ds_write_b128 v18, v[140:143] offset:32768
	s_waitcnt lgkmcnt(2)
	v_mfma_f32_16x16x32_f16 v[62:65], v[128:131], v[108:111], v[62:65]
	ds_read_b128 v[108:111], v32 offset:49152
	v_mfma_f32_16x16x32_f16 v[38:41], v[128:131], v[132:135], v[38:41]
	ds_read_b128 v[132:135], v32 offset:51200
	v_mfma_f32_16x16x32_f16 v[136:139], v[78:81], v[144:147], v[136:139]
	s_waitcnt vmcnt(2)
	ds_write_b128 v19, v[204:207] offset:32768
	v_mfma_f32_16x16x32_f16 v[66:69], v[78:81], v[154:157], v[66:69]
	ds_read_b128 v[78:81], v29 offset:16384
	v_mfma_f32_16x16x32_f16 v[50:53], v[128:131], v[144:147], v[50:53]
	ds_read_b128 v[144:147], v32 offset:53248
	v_mfma_f32_16x16x32_f16 v[58:61], v[128:131], v[154:157], v[58:61]
	ds_read_b128 v[128:131], v29 offset:18432
	s_waitcnt lgkmcnt(2)
	v_mfma_f32_16x16x32_f16 v[42:45], v[78:81], v[108:111], v[42:45]
	ds_read_b128 v[154:157], v32 offset:55296
	v_mfma_f32_16x16x32_f16 v[46:49], v[78:81], v[132:135], v[46:49]
	s_waitcnt vmcnt(1)
	ds_write_b128 v20, v[208:211] offset:32768
	s_waitcnt lgkmcnt(2)
	v_mfma_f32_16x16x32_f16 v[54:57], v[128:131], v[108:111], v[54:57]
	s_waitcnt vmcnt(0)
	ds_write_b128 v17, v[212:215] offset:32768
	v_mfma_f32_16x16x32_f16 v[70:73], v[128:131], v[132:135], v[70:73]
	v_mfma_f32_16x16x32_f16 v[104:107], v[78:81], v[144:147], v[104:107]
	s_waitcnt lgkmcnt(2)
	v_mfma_f32_16x16x32_f16 v[22:25], v[78:81], v[154:157], v[22:25]
	ds_read_b128 v[78:81], v29 offset:20480
	v_mfma_f32_16x16x32_f16 v[74:77], v[128:131], v[144:147], v[74:77]
	v_mfma_f32_16x16x32_f16 v[34:37], v[128:131], v[154:157], v[34:37]
	ds_read_b128 v[128:131], v29 offset:22528
	s_waitcnt lgkmcnt(1)
	v_mfma_f32_16x16x32_f16 v[120:123], v[78:81], v[108:111], v[120:123]
	v_mfma_f32_16x16x32_f16 v[124:127], v[78:81], v[132:135], v[124:127]
	s_waitcnt lgkmcnt(0)
	v_mfma_f32_16x16x32_f16 v[62:65], v[128:131], v[108:111], v[62:65]
	v_mfma_f32_16x16x32_f16 v[38:41], v[128:131], v[132:135], v[38:41]
	v_mfma_f32_16x16x32_f16 v[136:139], v[78:81], v[144:147], v[136:139]
	v_mfma_f32_16x16x32_f16 v[66:69], v[78:81], v[154:157], v[66:69]
	global_load_dwordx4 v[78:81], v[0:1], off offset:1152
	global_load_dwordx4 v[108:111], v[2:3], off offset:1152
	global_load_dwordx4 v[158:161], v[4:5], off offset:1152
	global_load_dwordx4 v[162:165], v[8:9], off offset:1152
	global_load_dwordx4 v[132:135], v[6:7], off offset:1152
	global_load_dwordx4 v[166:169], v[10:11], off offset:1152
	global_load_dwordx4 v[188:191], v[12:13], off offset:1152
	global_load_dwordx4 v[192:195], v[14:15], off offset:1152
	s_waitcnt lgkmcnt(0)
	s_barrier
; #define GL_LOAD(s_, kt_) if (VAR != 1) { a##s_##0 = GL_A(0, kt_); a##s_##1 = GL_A(1, kt_); a##s_##2 = GL_A(2, kt_); a##s_##3 = GL_A(3, kt_); b##s_##0 = GL_B(0, kt_); b##s_##1 = GL_B(1, kt_); b##s_##2 = GL_B(2, kt_); b##s_##3 = GL_B(3, kt_); }
; #define LDS_STORE(s_, buf_) if (VAR != 2) { LDS_ST1(sA, 0, buf_, a##s_##0) LDS_ST1(sA, 1, buf_, a##s_##1) LDS_ST1(sA, 2, buf_, a##s_##2) LDS_ST1(sA, 3, buf_, a##s_##3) LDS_ST1(sB, 0, buf_, b##s_##0) LDS_ST1(sB, 1, buf_, b##s_##1) LDS_ST1(sB, 2, buf_, b##s_##2) LDS_ST1(sB, 3, buf_, b##s_##3) }
;     ...
;   GL_LOAD(0, 0)
;   GL_LOAD(1, 1)
;   LDS_STORE(0, 0)
;   if (VAR != 4) __syncthreads();
; #pragma unroll
;   for (int kt = 0; kt < nk; kt += 2) {
;     if (kt + 2 < nk) { GL_LOAD(0, kt + 2) }
;     MMA_TILE(0)
;     LDS_STORE(1, 1)
;     if (VAR != 4) __syncthreads();
;     if (kt + 3 < nk) { GL_LOAD(1, kt + 3) }
;     MMA_TILE(1)
;     if (kt + 2 < nk) { LDS_STORE(0, 0) }
;     if (VAR != 4) __syncthreads();
;   }
	v_mfma_f32_16x16x32_f16 v[50:53], v[128:131], v[144:147], v[50:53]
	ds_read_b128 v[112:115], v16
	v_mfma_f32_16x16x32_f16 v[58:61], v[128:131], v[154:157], v[58:61]
	ds_read_b128 v[116:119], v28 offset:32768
	s_waitcnt lgkmcnt(0)
	v_mfma_f32_16x16x32_f16 v[42:45], v[112:115], v[116:119], v[42:45]
	ds_read_b128 v[128:131], v16 offset:2048
	ds_read_b128 v[140:143], v28 offset:34816
	s_waitcnt lgkmcnt(0)
	v_mfma_f32_16x16x32_f16 v[46:49], v[112:115], v[140:143], v[46:49]
	ds_read_b128 v[144:147], v28 offset:36864
	v_mfma_f32_16x16x32_f16 v[54:57], v[128:131], v[116:119], v[54:57]
	ds_read_b128 v[154:157], v28 offset:38912
	v_mfma_f32_16x16x32_f16 v[70:73], v[128:131], v[140:143], v[70:73]
	s_waitcnt vmcnt(7)
	ds_write_b128 v18, v[78:81] offset:16384
	s_waitcnt lgkmcnt(2)
	v_mfma_f32_16x16x32_f16 v[104:107], v[112:115], v[144:147], v[104:107]
	s_waitcnt vmcnt(6)
	ds_write_b128 v19, v[108:111] offset:16384
	s_waitcnt lgkmcnt(2)
	v_mfma_f32_16x16x32_f16 v[22:25], v[112:115], v[154:157], v[22:25]
	ds_read_b128 v[112:115], v16 offset:4096
	v_mfma_f32_16x16x32_f16 v[74:77], v[128:131], v[144:147], v[74:77]
	s_waitcnt vmcnt(5)
	ds_write_b128 v20, v[158:161] offset:16384
	v_mfma_f32_16x16x32_f16 v[34:37], v[128:131], v[154:157], v[34:37]
	ds_read_b128 v[128:131], v16 offset:6144
	s_waitcnt lgkmcnt(2)
	v_mfma_f32_16x16x32_f16 v[120:123], v[112:115], v[116:119], v[120:123]
	s_waitcnt vmcnt(4)
	ds_write_b128 v17, v[162:165] offset:16384
	v_mfma_f32_16x16x32_f16 v[124:127], v[112:115], v[140:143], v[124:127]
	s_waitcnt vmcnt(3)
	ds_write_b128 v18, v[132:135] offset:49152
	s_waitcnt lgkmcnt(2)
	v_mfma_f32_16x16x32_f16 v[62:65], v[128:131], v[116:119], v[62:65]
	ds_read_b128 v[116:119], v32 offset:32768
	v_mfma_f32_16x16x32_f16 v[38:41], v[128:131], v[140:143], v[38:41]
	ds_read_b128 v[140:143], v32 offset:34816
	v_mfma_f32_16x16x32_f16 v[136:139], v[112:115], v[144:147], v[136:139]
	s_waitcnt vmcnt(2)
	ds_write_b128 v19, v[166:169] offset:49152
	v_mfma_f32_16x16x32_f16 v[66:69], v[112:115], v[154:157], v[66:69]
	ds_read_b128 v[112:115], v29
	v_mfma_f32_16x16x32_f16 v[50:53], v[128:131], v[144:147], v[50:53]
	ds_read_b128 v[144:147], v32 offset:36864
	v_mfma_f32_16x16x32_f16 v[58:61], v[128:131], v[154:157], v[58:61]
	ds_read_b128 v[128:131], v29 offset:2048
	s_waitcnt lgkmcnt(2)
	v_mfma_f32_16x16x32_f16 v[42:45], v[112:115], v[116:119], v[42:45]
	ds_read_b128 v[154:157], v32 offset:38912
	v_mfma_f32_16x16x32_f16 v[46:49], v[112:115], v[140:143], v[46:49]
	s_waitcnt vmcnt(1)
	ds_write_b128 v20, v[188:191] offset:49152
	s_waitcnt lgkmcnt(2)
	v_mfma_f32_16x16x32_f16 v[54:57], v[128:131], v[116:119], v[54:57]
	s_waitcnt vmcnt(0)
	ds_write_b128 v17, v[192:195] offset:49152
	v_mfma_f32_16x16x32_f16 v[70:73], v[128:131], v[140:143], v[70:73]
	v_mfma_f32_16x16x32_f16 v[104:107], v[112:115], v[144:147], v[104:107]
	s_waitcnt lgkmcnt(2)
	v_mfma_f32_16x16x32_f16 v[22:25], v[112:115], v[154:157], v[22:25]
	ds_read_b128 v[112:115], v29 offset:4096
	v_mfma_f32_16x16x32_f16 v[74:77], v[128:131], v[144:147], v[74:77]
	v_mfma_f32_16x16x32_f16 v[34:37], v[128:131], v[154:157], v[34:37]
	ds_read_b128 v[128:131], v29 offset:6144
	s_waitcnt lgkmcnt(1)
	v_mfma_f32_16x16x32_f16 v[120:123], v[112:115], v[116:119], v[120:123]
	v_mfma_f32_16x16x32_f16 v[124:127], v[112:115], v[140:143], v[124:127]
	s_waitcnt lgkmcnt(0)
	v_mfma_f32_16x16x32_f16 v[62:65], v[128:131], v[116:119], v[62:65]
	v_mfma_f32_16x16x32_f16 v[38:41], v[128:131], v[140:143], v[38:41]
	v_mfma_f32_16x16x32_f16 v[136:139], v[112:115], v[144:147], v[136:139]
	v_mfma_f32_16x16x32_f16 v[66:69], v[112:115], v[154:157], v[66:69]
	global_load_dwordx4 v[112:115], v[0:1], off offset:1280
	global_load_dwordx4 v[116:119], v[2:3], off offset:1280
	global_load_dwordx4 v[196:199], v[4:5], off offset:1280
	global_load_dwordx4 v[200:203], v[8:9], off offset:1280
	global_load_dwordx4 v[140:143], v[6:7], off offset:1280
	global_load_dwordx4 v[204:207], v[10:11], off offset:1280
	global_load_dwordx4 v[208:211], v[12:13], off offset:1280
	global_load_dwordx4 v[212:215], v[14:15], off offset:1280
	s_waitcnt lgkmcnt(0)
	s_barrier
	v_mfma_f32_16x16x32_f16 v[50:53], v[128:131], v[144:147], v[50:53]
	ds_read_b128 v[78:81], v16 offset:16384
	v_mfma_f32_16x16x32_f16 v[58:61], v[128:131], v[154:157], v[58:61]
	ds_read_b128 v[108:111], v28 offset:49152
	s_waitcnt lgkmcnt(0)
	v_mfma_f32_16x16x32_f16 v[42:45], v[78:81], v[108:111], v[42:45]
	ds_read_b128 v[128:131], v16 offset:18432
	ds_read_b128 v[132:135], v28 offset:51200
	s_waitcnt lgkmcnt(0)
	v_mfma_f32_16x16x32_f16 v[46:49], v[78:81], v[132:135], v[46:49]
	ds_read_b128 v[144:147], v28 offset:53248
	v_mfma_f32_16x16x32_f16 v[54:57], v[128:131], v[108:111], v[54:57]
	ds_read_b128 v[154:157], v28 offset:55296
	v_mfma_f32_16x16x32_f16 v[70:73], v[128:131], v[132:135], v[70:73]
	s_waitcnt vmcnt(7)
	ds_write_b128 v18, v[112:115]
	s_waitcnt lgkmcnt(2)
	v_mfma_f32_16x16x32_f16 v[104:107], v[78:81], v[144:147], v[104:107]
	s_waitcnt vmcnt(6)
	ds_write_b128 v19, v[116:119]
	s_waitcnt lgkmcnt(2)
	v_mfma_f32_16x16x32_f16 v[22:25], v[78:81], v[154:157], v[22:25]
	ds_read_b128 v[78:81], v16 offset:20480
	v_mfma_f32_16x16x32_f16 v[74:77], v[128:131], v[144:147], v[74:77]
	s_waitcnt vmcnt(5)
	ds_write_b128 v20, v[196:199]
	v_mfma_f32_16x16x32_f16 v[34:37], v[128:131], v[154:157], v[34:37]
	ds_read_b128 v[128:131], v16 offset:22528
	s_waitcnt lgkmcnt(2)
	v_mfma_f32_16x16x32_f16 v[120:123], v[78:81], v[108:111], v[120:123]
	s_waitcnt vmcnt(4)
	ds_write_b128 v17, v[200:203]
	v_mfma_f32_16x16x32_f16 v[124:127], v[78:81], v[132:135], v[124:127]
	s_waitcnt vmcnt(3)
	ds_write_b128 v18, v[140:143] offset:32768
	s_waitcnt lgkmcnt(2)
; #define GL_LOAD(s_, kt_) if (VAR != 1) { a##s_##0 = GL_A(0, kt_); a##s_##1 = GL_A(1, kt_); a##s_##2 = GL_A(2, kt_); a##s_##3 = GL_A(3, kt_); b##s_##0 = GL_B(0, kt_); b##s_##1 = GL_B(1, kt_); b##s_##2 = GL_B(2, kt_); b##s_##3 = GL_B(3, kt_); }
; #define LDS_STORE(s_, buf_) if (VAR != 2) { LDS_ST1(sA, 0, buf_, a##s_##0) LDS_ST1(sA, 1, buf_, a##s_##1) LDS_ST1(sA, 2, buf_, a##s_##2) LDS_ST1(sA, 3, buf_, a##s_##3) LDS_ST1(sB, 0, buf_, b##s_##0) LDS_ST1(sB, 1, buf_, b##s_##1) LDS_ST1(sB, 2, buf_, b##s_##2) LDS_ST1(sB, 3, buf_, b##s_##3) }
;     ...
;   GL_LOAD(0, 0)
;   GL_LOAD(1, 1)
;   LDS_STORE(0, 0)
;   if (VAR != 4) __syncthreads();
; #pragma unroll
;   for (int kt = 0; kt < nk; kt += 2) {
;     if (kt + 2 < nk) { GL_LOAD(0, kt + 2) }
;     MMA_TILE(0)
;     LDS_STORE(1, 1)
;     if (VAR != 4) __syncthreads();
;     if (kt + 3 < nk) { GL_LOAD(1, kt + 3) }
;     MMA_TILE(1)
;     if (kt + 2 < nk) { LDS_STORE(0, 0) }
;     if (VAR != 4) __syncthreads();
;   }
	v_mfma_f32_16x16x32_f16 v[62:65], v[128:131], v[108:111], v[62:65]
	ds_read_b128 v[108:111], v32 offset:49152
	v_mfma_f32_16x16x32_f16 v[38:41], v[128:131], v[132:135], v[38:41]
	ds_read_b128 v[132:135], v32 offset:51200
	v_mfma_f32_16x16x32_f16 v[136:139], v[78:81], v[144:147], v[136:139]
	s_waitcnt vmcnt(2)
	ds_write_b128 v19, v[204:207] offset:32768
	v_mfma_f32_16x16x32_f16 v[66:69], v[78:81], v[154:157], v[66:69]
	ds_read_b128 v[78:81], v29 offset:16384
	v_mfma_f32_16x16x32_f16 v[50:53], v[128:131], v[144:147], v[50:53]
	ds_read_b128 v[144:147], v32 offset:53248
	v_mfma_f32_16x16x32_f16 v[58:61], v[128:131], v[154:157], v[58:61]
	ds_read_b128 v[128:131], v29 offset:18432
	s_waitcnt lgkmcnt(2)
	v_mfma_f32_16x16x32_f16 v[42:45], v[78:81], v[108:111], v[42:45]
	ds_read_b128 v[154:157], v32 offset:55296
	v_mfma_f32_16x16x32_f16 v[46:49], v[78:81], v[132:135], v[46:49]
	s_waitcnt vmcnt(1)
	ds_write_b128 v20, v[208:211] offset:32768
	s_waitcnt lgkmcnt(2)
	v_mfma_f32_16x16x32_f16 v[54:57], v[128:131], v[108:111], v[54:57]
	s_waitcnt vmcnt(0)
	ds_write_b128 v17, v[212:215] offset:32768
	v_mfma_f32_16x16x32_f16 v[70:73], v[128:131], v[132:135], v[70:73]
	v_mfma_f32_16x16x32_f16 v[104:107], v[78:81], v[144:147], v[104:107]
	s_waitcnt lgkmcnt(2)
	v_mfma_f32_16x16x32_f16 v[22:25], v[78:81], v[154:157], v[22:25]
	ds_read_b128 v[78:81], v29 offset:20480
	v_mfma_f32_16x16x32_f16 v[74:77], v[128:131], v[144:147], v[74:77]
	v_mfma_f32_16x16x32_f16 v[34:37], v[128:131], v[154:157], v[34:37]
	ds_read_b128 v[128:131], v29 offset:22528
	s_waitcnt lgkmcnt(1)
	v_mfma_f32_16x16x32_f16 v[120:123], v[78:81], v[108:111], v[120:123]
	v_mfma_f32_16x16x32_f16 v[124:127], v[78:81], v[132:135], v[124:127]
	s_waitcnt lgkmcnt(0)
	v_mfma_f32_16x16x32_f16 v[62:65], v[128:131], v[108:111], v[62:65]
	v_mfma_f32_16x16x32_f16 v[38:41], v[128:131], v[132:135], v[38:41]
	v_mfma_f32_16x16x32_f16 v[136:139], v[78:81], v[144:147], v[136:139]
	v_mfma_f32_16x16x32_f16 v[66:69], v[78:81], v[154:157], v[66:69]
	global_load_dwordx4 v[78:81], v[0:1], off offset:1408
	global_load_dwordx4 v[108:111], v[2:3], off offset:1408
	global_load_dwordx4 v[158:161], v[4:5], off offset:1408
	global_load_dwordx4 v[162:165], v[8:9], off offset:1408
	global_load_dwordx4 v[132:135], v[6:7], off offset:1408
	global_load_dwordx4 v[166:169], v[10:11], off offset:1408
	global_load_dwordx4 v[188:191], v[12:13], off offset:1408
	global_load_dwordx4 v[192:195], v[14:15], off offset:1408
	s_waitcnt lgkmcnt(0)
	s_barrier
	v_mfma_f32_16x16x32_f16 v[50:53], v[128:131], v[144:147], v[50:53]
	ds_read_b128 v[112:115], v16
	v_mfma_f32_16x16x32_f16 v[58:61], v[128:131], v[154:157], v[58:61]
	ds_read_b128 v[116:119], v28 offset:32768
	s_waitcnt lgkmcnt(0)
	v_mfma_f32_16x16x32_f16 v[42:45], v[112:115], v[116:119], v[42:45]
	ds_read_b128 v[128:131], v16 offset:2048
	ds_read_b128 v[140:143], v28 offset:34816
	s_waitcnt lgkmcnt(0)
	v_mfma_f32_16x16x32_f16 v[46:49], v[112:115], v[140:143], v[46:49]
	ds_read_b128 v[144:147], v28 offset:36864
	v_mfma_f32_16x16x32_f16 v[54:57], v[128:131], v[116:119], v[54:57]
	ds_read_b128 v[154:157], v28 offset:38912
	v_mfma_f32_16x16x32_f16 v[70:73], v[128:131], v[140:143], v[70:73]
	s_waitcnt vmcnt(7)
	ds_write_b128 v18, v[78:81] offset:16384
	s_waitcnt lgkmcnt(2)
	v_mfma_f32_16x16x32_f16 v[104:107], v[112:115], v[144:147], v[104:107]
	s_waitcnt vmcnt(6)
	ds_write_b128 v19, v[108:111] offset:16384
	s_waitcnt lgkmcnt(2)
	v_mfma_f32_16x16x32_f16 v[22:25], v[112:115], v[154:157], v[22:25]
	ds_read_b128 v[112:115], v16 offset:4096
	v_mfma_f32_16x16x32_f16 v[74:77], v[128:131], v[144:147], v[74:77]
	s_waitcnt vmcnt(5)
	ds_write_b128 v20, v[158:161] offset:16384
	v_mfma_f32_16x16x32_f16 v[34:37], v[128:131], v[154:157], v[34:37]
	ds_read_b128 v[128:131], v16 offset:6144
	s_waitcnt lgkmcnt(2)
	v_mfma_f32_16x16x32_f16 v[120:123], v[112:115], v[116:119], v[120:123]
	s_waitcnt vmcnt(4)
	ds_write_b128 v17, v[162:165] offset:16384
	v_mfma_f32_16x16x32_f16 v[124:127], v[112:115], v[140:143], v[124:127]
	s_waitcnt vmcnt(3)
	ds_write_b128 v18, v[132:135] offset:49152
	s_waitcnt lgkmcnt(2)
	v_mfma_f32_16x16x32_f16 v[62:65], v[128:131], v[116:119], v[62:65]
	ds_read_b128 v[116:119], v32 offset:32768
	v_mfma_f32_16x16x32_f16 v[38:41], v[128:131], v[140:143], v[38:41]
	ds_read_b128 v[140:143], v32 offset:34816
	v_mfma_f32_16x16x32_f16 v[136:139], v[112:115], v[144:147], v[136:139]
	s_waitcnt vmcnt(2)
	ds_write_b128 v19, v[166:169] offset:49152
	v_mfma_f32_16x16x32_f16 v[66:69], v[112:115], v[154:157], v[66:69]
	ds_read_b128 v[112:115], v29
	v_mfma_f32_16x16x32_f16 v[50:53], v[128:131], v[144:147], v[50:53]
	ds_read_b128 v[144:147], v32 offset:36864
	v_mfma_f32_16x16x32_f16 v[58:61], v[128:131], v[154:157], v[58:61]
	ds_read_b128 v[128:131], v29 offset:2048
	s_waitcnt lgkmcnt(2)
	v_mfma_f32_16x16x32_f16 v[42:45], v[112:115], v[116:119], v[42:45]
	ds_read_b128 v[154:157], v32 offset:38912
	v_mfma_f32_16x16x32_f16 v[46:49], v[112:115], v[140:143], v[46:49]
	s_waitcnt vmcnt(1)
	ds_write_b128 v20, v[188:191] offset:49152
	s_waitcnt lgkmcnt(2)
	v_mfma_f32_16x16x32_f16 v[54:57], v[128:131], v[116:119], v[54:57]
	s_waitcnt vmcnt(0)
	ds_write_b128 v17, v[192:195] offset:49152
	v_mfma_f32_16x16x32_f16 v[70:73], v[128:131], v[140:143], v[70:73]
	v_mfma_f32_16x16x32_f16 v[104:107], v[112:115], v[144:147], v[104:107]
	s_waitcnt lgkmcnt(2)
	v_mfma_f32_16x16x32_f16 v[22:25], v[112:115], v[154:157], v[22:25]
	ds_read_b128 v[112:115], v29 offset:4096
	v_mfma_f32_16x16x32_f16 v[74:77], v[128:131], v[144:147], v[74:77]
	v_mfma_f32_16x16x32_f16 v[34:37], v[128:131], v[154:157], v[34:37]
	ds_read_b128 v[128:131], v29 offset:6144
	s_waitcnt lgkmcnt(1)
	v_mfma_f32_16x16x32_f16 v[120:123], v[112:115], v[116:119], v[120:123]
	v_mfma_f32_16x16x32_f16 v[124:127], v[112:115], v[140:143], v[124:127]
	s_waitcnt lgkmcnt(0)
	v_mfma_f32_16x16x32_f16 v[62:65], v[128:131], v[116:119], v[62:65]
	v_mfma_f32_16x16x32_f16 v[38:41], v[128:131], v[140:143], v[38:41]
	v_mfma_f32_16x16x32_f16 v[136:139], v[112:115], v[144:147], v[136:139]
	v_mfma_f32_16x16x32_f16 v[66:69], v[112:115], v[154:157], v[66:69]
	global_load_dwordx4 v[112:115], v[0:1], off offset:1536
	global_load_dwordx4 v[116:119], v[2:3], off offset:1536
	global_load_dwordx4 v[196:199], v[4:5], off offset:1536
	global_load_dwordx4 v[200:203], v[8:9], off offset:1536
	global_load_dwordx4 v[140:143], v[6:7], off offset:1536
	global_load_dwordx4 v[204:207], v[10:11], off offset:1536
	global_load_dwordx4 v[208:211], v[12:13], off offset:1536
	global_load_dwordx4 v[212:215], v[14:15], off offset:1536
	s_waitcnt lgkmcnt(0)
	s_barrier
; #define GL_LOAD(s_, kt_) if (VAR != 1) { a##s_##0 = GL_A(0, kt_); a##s_##1 = GL_A(1, kt_); a##s_##2 = GL_A(2, kt_); a##s_##3 = GL_A(3, kt_); b##s_##0 = GL_B(0, kt_); b##s_##1 = GL_B(1, kt_); b##s_##2 = GL_B(2, kt_); b##s_##3 = GL_B(3, kt_); }
; #define LDS_STORE(s_, buf_) if (VAR != 2) { LDS_ST1(sA, 0, buf_, a##s_##0) LDS_ST1(sA, 1, buf_, a##s_##1) LDS_ST1(sA, 2, buf_, a##s_##2) LDS_ST1(sA, 3, buf_, a##s_##3) LDS_ST1(sB, 0, buf_, b##s_##0) LDS_ST1(sB, 1, buf_, b##s_##1) LDS_ST1(sB, 2, buf_, b##s_##2) LDS_ST1(sB, 3, buf_, b##s_##3) }
;     ...
;   GL_LOAD(0, 0)
;   GL_LOAD(1, 1)
;   LDS_STORE(0, 0)
;   if (VAR != 4) __syncthreads();
; #pragma unroll
;   for (int kt = 0; kt < nk; kt += 2) {
;     if (kt + 2 < nk) { GL_LOAD(0, kt + 2) }
;     MMA_TILE(0)
;     LDS_STORE(1, 1)
;     if (VAR != 4) __syncthreads();
;     if (kt + 3 < nk) { GL_LOAD(1, kt + 3) }
;     MMA_TILE(1)
;     if (kt + 2 < nk) { LDS_STORE(0, 0) }
;     if (VAR != 4) __syncthreads();
;   }
	v_mfma_f32_16x16x32_f16 v[50:53], v[128:131], v[144:147], v[50:53]
	ds_read_b128 v[78:81], v16 offset:16384
	v_mfma_f32_16x16x32_f16 v[58:61], v[128:131], v[154:157], v[58:61]
	ds_read_b128 v[108:111], v28 offset:49152
	s_waitcnt lgkmcnt(0)
	v_mfma_f32_16x16x32_f16 v[42:45], v[78:81], v[108:111], v[42:45]
	ds_read_b128 v[128:131], v16 offset:18432
	ds_read_b128 v[132:135], v28 offset:51200
	s_waitcnt lgkmcnt(0)
	v_mfma_f32_16x16x32_f16 v[46:49], v[78:81], v[132:135], v[46:49]
	ds_read_b128 v[144:147], v28 offset:53248
	v_mfma_f32_16x16x32_f16 v[54:57], v[128:131], v[108:111], v[54:57]
	ds_read_b128 v[154:157], v28 offset:55296
	v_mfma_f32_16x16x32_f16 v[70:73], v[128:131], v[132:135], v[70:73]
	s_waitcnt vmcnt(7)
	ds_write_b128 v18, v[112:115]
	s_waitcnt lgkmcnt(2)
	v_mfma_f32_16x16x32_f16 v[104:107], v[78:81], v[144:147], v[104:107]
	s_waitcnt vmcnt(6)
	ds_write_b128 v19, v[116:119]
	s_waitcnt lgkmcnt(2)
	v_mfma_f32_16x16x32_f16 v[22:25], v[78:81], v[154:157], v[22:25]
	ds_read_b128 v[78:81], v16 offset:20480
	v_mfma_f32_16x16x32_f16 v[74:77], v[128:131], v[144:147], v[74:77]
	s_waitcnt vmcnt(5)
	ds_write_b128 v20, v[196:199]
	v_mfma_f32_16x16x32_f16 v[34:37], v[128:131], v[154:157], v[34:37]
	ds_read_b128 v[128:131], v16 offset:22528
	s_waitcnt lgkmcnt(2)
	v_mfma_f32_16x16x32_f16 v[120:123], v[78:81], v[108:111], v[120:123]
	s_waitcnt vmcnt(4)
	ds_write_b128 v17, v[200:203]
	v_mfma_f32_16x16x32_f16 v[124:127], v[78:81], v[132:135], v[124:127]
	s_waitcnt vmcnt(3)
	ds_write_b128 v18, v[140:143] offset:32768
	s_waitcnt lgkmcnt(2)
	v_mfma_f32_16x16x32_f16 v[62:65], v[128:131], v[108:111], v[62:65]
	ds_read_b128 v[108:111], v32 offset:49152
	v_mfma_f32_16x16x32_f16 v[38:41], v[128:131], v[132:135], v[38:41]
	ds_read_b128 v[132:135], v32 offset:51200
	v_mfma_f32_16x16x32_f16 v[136:139], v[78:81], v[144:147], v[136:139]
	s_waitcnt vmcnt(2)
	ds_write_b128 v19, v[204:207] offset:32768
	v_mfma_f32_16x16x32_f16 v[66:69], v[78:81], v[154:157], v[66:69]
	ds_read_b128 v[78:81], v29 offset:16384
	v_mfma_f32_16x16x32_f16 v[50:53], v[128:131], v[144:147], v[50:53]
	ds_read_b128 v[144:147], v32 offset:53248
	v_mfma_f32_16x16x32_f16 v[58:61], v[128:131], v[154:157], v[58:61]
	ds_read_b128 v[128:131], v29 offset:18432
	s_waitcnt lgkmcnt(2)
	v_mfma_f32_16x16x32_f16 v[42:45], v[78:81], v[108:111], v[42:45]
	ds_read_b128 v[154:157], v32 offset:55296
	v_mfma_f32_16x16x32_f16 v[46:49], v[78:81], v[132:135], v[46:49]
	s_waitcnt vmcnt(1)
	ds_write_b128 v20, v[208:211] offset:32768
	s_waitcnt lgkmcnt(2)
	v_mfma_f32_16x16x32_f16 v[54:57], v[128:131], v[108:111], v[54:57]
	s_waitcnt vmcnt(0)
	ds_write_b128 v17, v[212:215] offset:32768
	v_mfma_f32_16x16x32_f16 v[70:73], v[128:131], v[132:135], v[70:73]
	v_mfma_f32_16x16x32_f16 v[104:107], v[78:81], v[144:147], v[104:107]
	s_waitcnt lgkmcnt(2)
	v_mfma_f32_16x16x32_f16 v[22:25], v[78:81], v[154:157], v[22:25]
	ds_read_b128 v[78:81], v29 offset:20480
	v_mfma_f32_16x16x32_f16 v[74:77], v[128:131], v[144:147], v[74:77]
	v_mfma_f32_16x16x32_f16 v[34:37], v[128:131], v[154:157], v[34:37]
	ds_read_b128 v[128:131], v29 offset:22528
	s_waitcnt lgkmcnt(1)
	v_mfma_f32_16x16x32_f16 v[120:123], v[78:81], v[108:111], v[120:123]
	v_mfma_f32_16x16x32_f16 v[124:127], v[78:81], v[132:135], v[124:127]
	s_waitcnt lgkmcnt(0)
	v_mfma_f32_16x16x32_f16 v[62:65], v[128:131], v[108:111], v[62:65]
	v_mfma_f32_16x16x32_f16 v[38:41], v[128:131], v[132:135], v[38:41]
	v_mfma_f32_16x16x32_f16 v[136:139], v[78:81], v[144:147], v[136:139]
	v_mfma_f32_16x16x32_f16 v[66:69], v[78:81], v[154:157], v[66:69]
	global_load_dwordx4 v[78:81], v[0:1], off offset:1664
	global_load_dwordx4 v[108:111], v[2:3], off offset:1664
	global_load_dwordx4 v[158:161], v[4:5], off offset:1664
	global_load_dwordx4 v[162:165], v[8:9], off offset:1664
	global_load_dwordx4 v[132:135], v[6:7], off offset:1664
	global_load_dwordx4 v[166:169], v[10:11], off offset:1664
	global_load_dwordx4 v[188:191], v[12:13], off offset:1664
	global_load_dwordx4 v[192:195], v[14:15], off offset:1664
	s_waitcnt lgkmcnt(0)
	s_barrier
	v_mfma_f32_16x16x32_f16 v[50:53], v[128:131], v[144:147], v[50:53]
	ds_read_b128 v[112:115], v16
	v_mfma_f32_16x16x32_f16 v[58:61], v[128:131], v[154:157], v[58:61]
	ds_read_b128 v[116:119], v28 offset:32768
	s_waitcnt lgkmcnt(0)
	v_mfma_f32_16x16x32_f16 v[42:45], v[112:115], v[116:119], v[42:45]
	ds_read_b128 v[128:131], v16 offset:2048
	ds_read_b128 v[140:143], v28 offset:34816
	s_waitcnt lgkmcnt(0)
	v_mfma_f32_16x16x32_f16 v[46:49], v[112:115], v[140:143], v[46:49]
	ds_read_b128 v[144:147], v28 offset:36864
	v_mfma_f32_16x16x32_f16 v[54:57], v[128:131], v[116:119], v[54:57]
	ds_read_b128 v[154:157], v28 offset:38912
	v_mfma_f32_16x16x32_f16 v[70:73], v[128:131], v[140:143], v[70:73]
	s_waitcnt vmcnt(7)
	ds_write_b128 v18, v[78:81] offset:16384
	s_waitcnt lgkmcnt(2)
	v_mfma_f32_16x16x32_f16 v[104:107], v[112:115], v[144:147], v[104:107]
	s_waitcnt vmcnt(6)
	ds_write_b128 v19, v[108:111] offset:16384
	s_waitcnt lgkmcnt(2)
	v_mfma_f32_16x16x32_f16 v[22:25], v[112:115], v[154:157], v[22:25]
	ds_read_b128 v[112:115], v16 offset:4096
	v_mfma_f32_16x16x32_f16 v[74:77], v[128:131], v[144:147], v[74:77]
	s_waitcnt vmcnt(5)
	ds_write_b128 v20, v[158:161] offset:16384
	v_mfma_f32_16x16x32_f16 v[34:37], v[128:131], v[154:157], v[34:37]
	ds_read_b128 v[128:131], v16 offset:6144
	s_waitcnt lgkmcnt(2)
	v_mfma_f32_16x16x32_f16 v[120:123], v[112:115], v[116:119], v[120:123]
	s_waitcnt vmcnt(4)
	ds_write_b128 v17, v[162:165] offset:16384
	v_mfma_f32_16x16x32_f16 v[124:127], v[112:115], v[140:143], v[124:127]
	s_waitcnt vmcnt(3)
	ds_write_b128 v18, v[132:135] offset:49152
	s_waitcnt lgkmcnt(2)
; #define GL_LOAD(s_, kt_) if (VAR != 1) { a##s_##0 = GL_A(0, kt_); a##s_##1 = GL_A(1, kt_); a##s_##2 = GL_A(2, kt_); a##s_##3 = GL_A(3, kt_); b##s_##0 = GL_B(0, kt_); b##s_##1 = GL_B(1, kt_); b##s_##2 = GL_B(2, kt_); b##s_##3 = GL_B(3, kt_); }
; #define LDS_STORE(s_, buf_) if (VAR != 2) { LDS_ST1(sA, 0, buf_, a##s_##0) LDS_ST1(sA, 1, buf_, a##s_##1) LDS_ST1(sA, 2, buf_, a##s_##2) LDS_ST1(sA, 3, buf_, a##s_##3) LDS_ST1(sB, 0, buf_, b##s_##0) LDS_ST1(sB, 1, buf_, b##s_##1) LDS_ST1(sB, 2, buf_, b##s_##2) LDS_ST1(sB, 3, buf_, b##s_##3) }
;     ...
;   GL_LOAD(0, 0)
;   GL_LOAD(1, 1)
;   LDS_STORE(0, 0)
;   if (VAR != 4) __syncthreads();
; #pragma unroll
;   for (int kt = 0; kt < nk; kt += 2) {
;     if (kt + 2 < nk) { GL_LOAD(0, kt + 2) }
;     MMA_TILE(0)
;     LDS_STORE(1, 1)
;     if (VAR != 4) __syncthreads();
;     if (kt + 3 < nk) { GL_LOAD(1, kt + 3) }
;     MMA_TILE(1)
;     if (kt + 2 < nk) { LDS_STORE(0, 0) }
;     if (VAR != 4) __syncthreads();
;   }
	v_mfma_f32_16x16x32_f16 v[62:65], v[128:131], v[116:119], v[62:65]
	ds_read_b128 v[116:119], v32 offset:32768
	v_mfma_f32_16x16x32_f16 v[38:41], v[128:131], v[140:143], v[38:41]
	ds_read_b128 v[140:143], v32 offset:34816
	v_mfma_f32_16x16x32_f16 v[136:139], v[112:115], v[144:147], v[136:139]
	s_waitcnt vmcnt(2)
	ds_write_b128 v19, v[166:169] offset:49152
	v_mfma_f32_16x16x32_f16 v[66:69], v[112:115], v[154:157], v[66:69]
	ds_read_b128 v[112:115], v29
	v_mfma_f32_16x16x32_f16 v[50:53], v[128:131], v[144:147], v[50:53]
	ds_read_b128 v[144:147], v32 offset:36864
	v_mfma_f32_16x16x32_f16 v[58:61], v[128:131], v[154:157], v[58:61]
	ds_read_b128 v[128:131], v29 offset:2048
	s_waitcnt lgkmcnt(2)
	v_mfma_f32_16x16x32_f16 v[42:45], v[112:115], v[116:119], v[42:45]
	ds_read_b128 v[154:157], v32 offset:38912
	v_mfma_f32_16x16x32_f16 v[46:49], v[112:115], v[140:143], v[46:49]
	s_waitcnt vmcnt(1)
	ds_write_b128 v20, v[188:191] offset:49152
	s_waitcnt lgkmcnt(2)
	v_mfma_f32_16x16x32_f16 v[54:57], v[128:131], v[116:119], v[54:57]
	s_waitcnt vmcnt(0)
	ds_write_b128 v17, v[192:195] offset:49152
	v_mfma_f32_16x16x32_f16 v[70:73], v[128:131], v[140:143], v[70:73]
	v_mfma_f32_16x16x32_f16 v[104:107], v[112:115], v[144:147], v[104:107]
	s_waitcnt lgkmcnt(2)
	v_mfma_f32_16x16x32_f16 v[22:25], v[112:115], v[154:157], v[22:25]
	ds_read_b128 v[112:115], v29 offset:4096
	v_mfma_f32_16x16x32_f16 v[74:77], v[128:131], v[144:147], v[74:77]
	v_mfma_f32_16x16x32_f16 v[34:37], v[128:131], v[154:157], v[34:37]
	ds_read_b128 v[128:131], v29 offset:6144
	s_waitcnt lgkmcnt(1)
	v_mfma_f32_16x16x32_f16 v[120:123], v[112:115], v[116:119], v[120:123]
	v_mfma_f32_16x16x32_f16 v[124:127], v[112:115], v[140:143], v[124:127]
	s_waitcnt lgkmcnt(0)
	v_mfma_f32_16x16x32_f16 v[62:65], v[128:131], v[116:119], v[62:65]
	v_mfma_f32_16x16x32_f16 v[38:41], v[128:131], v[140:143], v[38:41]
	v_mfma_f32_16x16x32_f16 v[136:139], v[112:115], v[144:147], v[136:139]
	v_mfma_f32_16x16x32_f16 v[66:69], v[112:115], v[154:157], v[66:69]
	global_load_dwordx4 v[112:115], v[0:1], off offset:1792
	global_load_dwordx4 v[116:119], v[2:3], off offset:1792
	global_load_dwordx4 v[196:199], v[4:5], off offset:1792
	global_load_dwordx4 v[200:203], v[8:9], off offset:1792
	global_load_dwordx4 v[140:143], v[6:7], off offset:1792
	global_load_dwordx4 v[204:207], v[10:11], off offset:1792
	global_load_dwordx4 v[208:211], v[12:13], off offset:1792
	global_load_dwordx4 v[212:215], v[14:15], off offset:1792
	s_waitcnt lgkmcnt(0)
	s_barrier
	v_mfma_f32_16x16x32_f16 v[50:53], v[128:131], v[144:147], v[50:53]
	ds_read_b128 v[78:81], v16 offset:16384
	v_mfma_f32_16x16x32_f16 v[58:61], v[128:131], v[154:157], v[58:61]
	ds_read_b128 v[108:111], v28 offset:49152
	s_waitcnt lgkmcnt(0)
	v_mfma_f32_16x16x32_f16 v[42:45], v[78:81], v[108:111], v[42:45]
	ds_read_b128 v[128:131], v16 offset:18432
	ds_read_b128 v[132:135], v28 offset:51200
	s_waitcnt lgkmcnt(0)
	v_mfma_f32_16x16x32_f16 v[46:49], v[78:81], v[132:135], v[46:49]
	ds_read_b128 v[144:147], v28 offset:53248
	v_mfma_f32_16x16x32_f16 v[54:57], v[128:131], v[108:111], v[54:57]
	ds_read_b128 v[154:157], v28 offset:55296
	v_mfma_f32_16x16x32_f16 v[70:73], v[128:131], v[132:135], v[70:73]
	s_waitcnt vmcnt(7)
	ds_write_b128 v18, v[112:115]
	s_waitcnt lgkmcnt(2)
	v_mfma_f32_16x16x32_f16 v[104:107], v[78:81], v[144:147], v[104:107]
	s_waitcnt vmcnt(6)
	ds_write_b128 v19, v[116:119]
	s_waitcnt lgkmcnt(2)
	v_mfma_f32_16x16x32_f16 v[22:25], v[78:81], v[154:157], v[22:25]
	ds_read_b128 v[78:81], v16 offset:20480
	v_mfma_f32_16x16x32_f16 v[74:77], v[128:131], v[144:147], v[74:77]
	s_waitcnt vmcnt(5)
	ds_write_b128 v20, v[196:199]
	v_mfma_f32_16x16x32_f16 v[34:37], v[128:131], v[154:157], v[34:37]
	ds_read_b128 v[128:131], v16 offset:22528
	s_waitcnt lgkmcnt(2)
	v_mfma_f32_16x16x32_f16 v[120:123], v[78:81], v[108:111], v[120:123]
	s_waitcnt vmcnt(4)
	ds_write_b128 v17, v[200:203]
	v_mfma_f32_16x16x32_f16 v[124:127], v[78:81], v[132:135], v[124:127]
	s_waitcnt vmcnt(3)
	ds_write_b128 v18, v[140:143] offset:32768
	s_waitcnt lgkmcnt(2)
	v_mfma_f32_16x16x32_f16 v[62:65], v[128:131], v[108:111], v[62:65]
	ds_read_b128 v[108:111], v32 offset:49152
	v_mfma_f32_16x16x32_f16 v[38:41], v[128:131], v[132:135], v[38:41]
	ds_read_b128 v[132:135], v32 offset:51200
	v_mfma_f32_16x16x32_f16 v[136:139], v[78:81], v[144:147], v[136:139]
	s_waitcnt vmcnt(2)
	ds_write_b128 v19, v[204:207] offset:32768
	v_mfma_f32_16x16x32_f16 v[66:69], v[78:81], v[154:157], v[66:69]
	ds_read_b128 v[78:81], v29 offset:16384
	v_mfma_f32_16x16x32_f16 v[50:53], v[128:131], v[144:147], v[50:53]
	ds_read_b128 v[144:147], v32 offset:53248
	v_mfma_f32_16x16x32_f16 v[58:61], v[128:131], v[154:157], v[58:61]
	ds_read_b128 v[128:131], v29 offset:18432
	s_waitcnt lgkmcnt(2)
	v_mfma_f32_16x16x32_f16 v[42:45], v[78:81], v[108:111], v[42:45]
	ds_read_b128 v[154:157], v32 offset:55296
	v_mfma_f32_16x16x32_f16 v[46:49], v[78:81], v[132:135], v[46:49]
	s_waitcnt vmcnt(1)
	ds_write_b128 v20, v[208:211] offset:32768
	s_waitcnt lgkmcnt(2)
	v_mfma_f32_16x16x32_f16 v[54:57], v[128:131], v[108:111], v[54:57]
	s_waitcnt vmcnt(0)
	ds_write_b128 v17, v[212:215] offset:32768
	v_mfma_f32_16x16x32_f16 v[70:73], v[128:131], v[132:135], v[70:73]
	v_mfma_f32_16x16x32_f16 v[104:107], v[78:81], v[144:147], v[104:107]
	s_waitcnt lgkmcnt(2)
	v_mfma_f32_16x16x32_f16 v[22:25], v[78:81], v[154:157], v[22:25]
	ds_read_b128 v[78:81], v29 offset:20480
	v_mfma_f32_16x16x32_f16 v[74:77], v[128:131], v[144:147], v[74:77]
	v_mfma_f32_16x16x32_f16 v[34:37], v[128:131], v[154:157], v[34:37]
	ds_read_b128 v[128:131], v29 offset:22528
	s_waitcnt lgkmcnt(1)
	v_mfma_f32_16x16x32_f16 v[120:123], v[78:81], v[108:111], v[120:123]
	v_mfma_f32_16x16x32_f16 v[124:127], v[78:81], v[132:135], v[124:127]
	s_waitcnt lgkmcnt(0)
	v_mfma_f32_16x16x32_f16 v[62:65], v[128:131], v[108:111], v[62:65]
	v_mfma_f32_16x16x32_f16 v[38:41], v[128:131], v[132:135], v[38:41]
	v_mfma_f32_16x16x32_f16 v[136:139], v[78:81], v[144:147], v[136:139]
	v_mfma_f32_16x16x32_f16 v[66:69], v[78:81], v[154:157], v[66:69]
	global_load_dwordx4 v[80:83], v[0:1], off offset:1920
	global_load_dwordx4 v[108:111], v[2:3], off offset:1920
	global_load_dwordx4 v[158:161], v[4:5], off offset:1920
	global_load_dwordx4 v[162:165], v[8:9], off offset:1920
	global_load_dwordx4 v[132:135], v[6:7], off offset:1920
	global_load_dwordx4 v[166:169], v[10:11], off offset:1920
	global_load_dwordx4 v[188:191], v[12:13], off offset:1920
	global_load_dwordx4 v[12:15], v[14:15], off offset:1920
	s_waitcnt lgkmcnt(0)
	s_barrier
; DI unsigned pack2(float lo, float hi) { f2_t v = {lo, hi}; h2_t b = __builtin_convertvector(v, h2_t); return __builtin_bit_cast(unsigned, b); }
; #define GL_LOAD(s_, kt_) if (VAR != 1) { a##s_##0 = GL_A(0, kt_); a##s_##1 = GL_A(1, kt_); a##s_##2 = GL_A(2, kt_); a##s_##3 = GL_A(3, kt_); b##s_##0 = GL_B(0, kt_); b##s_##1 = GL_B(1, kt_); b##s_##2 = GL_B(2, kt_); b##s_##3 = GL_B(3, kt_); }
; #define LDS_STORE(s_, buf_) if (VAR != 2) { LDS_ST1(sA, 0, buf_, a##s_##0) LDS_ST1(sA, 1, buf_, a##s_##1) LDS_ST1(sA, 2, buf_, a##s_##2) LDS_ST1(sA, 3, buf_, a##s_##3) LDS_ST1(sB, 0, buf_, b##s_##0) LDS_ST1(sB, 1, buf_, b##s_##1) LDS_ST1(sB, 2, buf_, b##s_##2) LDS_ST1(sB, 3, buf_, b##s_##3) }
;     ...
;   for (int kt = 0; kt < nk; kt += 2) {
;     if (kt + 2 < nk) { GL_LOAD(0, kt + 2) }
;     MMA_TILE(0)
;     LDS_STORE(1, 1)
;     if (VAR != 4) __syncthreads();
;     if (kt + 3 < nk) { GL_LOAD(1, kt + 3) }
;     MMA_TILE(1)
;     if (kt + 2 < nk) { LDS_STORE(0, 0) }
;     if (VAR != 4) __syncthreads();
;   }
; DI void phase_proj(const Params& P, int l, char* smem) {
;     ...
; #pragma unroll
;       for (int mt = 0; mt < 4; ++mt) {
;         float r4[4];
; #pragma unroll
;         for (int j = 0; j < 4; ++j) r4[j] = __shfl(rs[mt], 4 * g + j);
; #pragma unroll
;         for (int nt = 0; nt < 4; ++nt) {
;           const int c = c0 + nt * 16 + lr;
;           bf16_t* dst = VT + ((size_t)(br * NB + b) * 512 + c) * SEQ + s0 + mt * 16 + 4 * g;
;           *(uint2*)dst = make_uint2(pack2(acc[mt][nt][0] * r4[0], acc[mt][nt][1] * r4[1]), pack2(acc[mt][nt][2] * r4[2], acc[mt][nt][3] * r4[3]));
;         }
;       }
	ds_read_b128 v[0:3], v16
	v_mfma_f32_16x16x32_f16 v[50:53], v[128:131], v[144:147], v[50:53]
	v_mfma_f32_16x16x32_f16 v[112:115], v[128:131], v[154:157], v[58:61]
	ds_read_b128 v[116:119], v28 offset:32768
	ds_read_b128 v[4:7], v16 offset:2048
	ds_read_b128 v[128:131], v28 offset:34816
	s_waitcnt lgkmcnt(2)
	v_mfma_f32_16x16x32_f16 v[140:143], v[0:3], v[116:119], v[42:45]
	s_waitcnt lgkmcnt(0)
	v_mfma_f32_16x16x32_f16 v[144:147], v[0:3], v[128:131], v[46:49]
	s_nop 0
	ds_read_b128 v[42:45], v28 offset:36864
	s_nop 0
	ds_read_b128 v[46:49], v28 offset:38912
	s_waitcnt lgkmcnt(0)
	v_mfma_f32_16x16x32_f16 v[154:157], v[0:3], v[46:49], v[22:25]
	v_mfma_f32_16x16x32_f16 v[204:207], v[4:7], v[46:49], v[34:37]
	s_nop 1
	ds_read_b128 v[22:25], v16 offset:4096
	ds_read_b128 v[34:37], v16 offset:6144
	ds_read_b128 v[208:211], v29
	ds_read_b128 v[212:215], v29 offset:2048
	v_mfma_f32_16x16x32_f16 v[104:107], v[0:3], v[42:45], v[104:107]
	v_mfma_f32_16x16x32_f16 v[192:195], v[4:7], v[116:119], v[54:57]
	v_mfma_f32_16x16x32_f16 v[200:203], v[4:7], v[42:45], v[74:77]
	s_nop 2
	ds_read_b128 v[76:79], v32 offset:32768
	ds_read_b128 v[56:59], v32 offset:34816
	ds_read_b128 v[220:223], v29 offset:4096
	ds_read_b128 v[0:3], v29 offset:6144
	v_mfma_f32_16x16x32_f16 v[196:199], v[4:7], v[128:131], v[70:73]
	ds_read_b128 v[8:11], v32 offset:36864
	ds_read_b128 v[4:7], v32 offset:38912
	s_waitcnt vmcnt(7)
	ds_write_b128 v18, v[80:83] offset:16384
	s_waitcnt lgkmcnt(10)
	v_mfma_f32_16x16x32_f16 v[120:123], v[22:25], v[116:119], v[120:123]
	s_waitcnt vmcnt(6)
	ds_write_b128 v19, v[108:111] offset:16384
	s_waitcnt vmcnt(5)
	ds_write_b128 v20, v[158:161] offset:16384
	s_waitcnt vmcnt(4)
	ds_write_b128 v17, v[162:165] offset:16384
	s_waitcnt vmcnt(3)
	ds_write_b128 v18, v[132:135] offset:49152
	s_waitcnt vmcnt(2)
	ds_write_b128 v19, v[166:169] offset:49152
	s_waitcnt vmcnt(1)
	ds_write_b128 v20, v[188:191] offset:49152
	v_mfma_f32_16x16x32_f16 v[136:139], v[22:25], v[42:45], v[136:139]
	s_waitcnt vmcnt(0)
	ds_write_b128 v17, v[12:15] offset:49152
	s_waitcnt lgkmcnt(0)
	s_barrier
	v_mfma_f32_16x16x32_f16 v[224:227], v[22:25], v[46:49], v[66:69]
	v_and_or_b32 v188, v94, s1, v97
	v_ashrrev_i32_e32 v94, 7, v94
	v_mfma_f32_16x16x32_f16 v[108:111], v[34:37], v[116:119], v[62:65]
	ds_read_b128 v[116:119], v16 offset:16384
	ds_read_b128 v[80:83], v16 offset:18432
	v_and_b32_e32 v94, -4, v94
	v_add_u32_e32 v94, v94, v95
	v_mfma_f32_16x16x32_f16 v[72:75], v[34:37], v[128:131], v[38:41]
	v_ashrrev_i32_e32 v95, 31, v94
	v_lshlrev_b64 v[170:171], 21, v[94:95]
	v_lshl_add_u64 v[94:95], v[92:93], 0, v[150:151]
	v_mfma_f32_16x16x32_f16 v[40:43], v[34:37], v[42:45], v[50:53]
	v_lshlrev_b32_e32 v150, 2, v103
	v_lshl_or_b32 v170, v188, 12, v170
	ds_bpermute_b32 v188, v150, v98
	v_mfma_f32_16x16x32_f16 v[44:47], v[34:37], v[46:49], v[112:115]
	ds_bpermute_b32 v189, v150, v98 offset:4
	ds_bpermute_b32 v190, v150, v98 offset:8
	v_mfma_f32_16x16x32_f16 v[112:115], v[208:211], v[76:79], v[140:143]
	v_mfma_f32_16x16x32_f16 v[124:127], v[22:25], v[128:131], v[124:127]
	ds_read_b128 v[36:39], v28 offset:49152
	ds_read_b128 v[24:27], v28 offset:51200
	ds_read_b128 v[64:67], v16 offset:20480
	ds_read_b128 v[12:15], v16 offset:22528
	ds_read_b128 v[20:23], v28 offset:53248
	ds_read_b128 v[16:19], v28 offset:55296
	ds_read_b128 v[128:131], v29 offset:16384
	ds_read_b128 v[132:135], v29 offset:18432
	ds_read_b128 v[60:63], v32 offset:49152
	ds_read_b128 v[52:55], v32 offset:51200
	ds_read_b128 v[68:71], v29 offset:20480
	ds_read_b128 v[28:31], v29 offset:22528
	s_waitcnt lgkmcnt(11)
	v_mfma_f32_16x16x32_f16 v[112:115], v[116:119], v[36:39], v[112:115]
	ds_read_b128 v[48:51], v32 offset:53248
	ds_read_b128 v[32:35], v32 offset:55296
	s_waitcnt lgkmcnt(0)
	s_barrier
	s_setprio 0
	v_mfma_f32_16x16x32_f16 v[140:143], v[208:211], v[56:59], v[144:147]
	v_mfma_f32_16x16x32_f16 v[144:147], v[208:211], v[4:7], v[154:157]
	v_mfma_f32_16x16x32_f16 v[154:157], v[212:215], v[76:79], v[192:195]
	s_nop 2
	v_or_b32_e32 v194, 12, v150
	ds_bpermute_b32 v191, v194, v98
	v_mfma_f32_16x16x32_f16 v[112:115], v[128:131], v[60:63], v[112:115]
	v_lshl_add_u64 v[98:99], v[170:171], 1, v[94:95]
	v_mfma_f32_16x16x32_f16 v[104:107], v[208:211], v[8:11], v[104:107]
	v_mfma_f32_16x16x32_f16 v[104:107], v[116:119], v[20:23], v[104:107]
	s_nop 4
	v_mul_f32_e64 v112, v112, v188
	v_mul_f32_e64 v113, v113, v189
	s_waitcnt lgkmcnt(0)
	v_pk_mul_f32 v[114:115], v[114:115], v[190:191]
	v_cvt_pk_f16_f32 v112, v112, v113
	v_cvt_pk_f16_f32 v113, v114, v115
	v_mov_b32_e32 v228, v112
	v_mov_b32_e32 v229, v113
	v_mfma_f32_16x16x32_f16 v[112:115], v[116:119], v[24:27], v[140:143]
	v_mfma_f32_16x16x32_f16 v[112:115], v[128:131], v[52:55], v[112:115]
	s_nop 1
	v_or_b32_e32 v140, 0x10000, v170
	v_mov_b32_e32 v141, v171
	v_lshlrev_b64 v[140:141], 1, v[140:141]
	v_mfma_f32_16x16x32_f16 v[104:107], v[128:131], v[48:51], v[104:107]
	v_lshl_add_u64 v[142:143], v[94:95], 0, v[140:141]
	s_nop 0
	v_pk_mul_f32 v[112:113], v[112:113], v[188:189]
	v_pk_mul_f32 v[114:115], v[114:115], v[190:191]
	v_cvt_pk_f16_f32 v112, v112, v113
	v_cvt_pk_f16_f32 v113, v114, v115
	v_mov_b32_e32 v232, v112
	v_mov_b32_e32 v233, v113
	v_or_b32_e32 v112, 0x20000, v170
	v_mov_b32_e32 v113, v171
	v_lshlrev_b64 v[142:143], 1, v[112:113]
	v_pk_mul_f32 v[104:105], v[104:105], v[188:189]
	v_pk_mul_f32 v[106:107], v[106:107], v[190:191]
	v_lshl_add_u64 v[192:193], v[94:95], 0, v[142:143]
	v_cvt_pk_f16_f32 v104, v104, v105
	v_cvt_pk_f16_f32 v105, v106, v107
	v_mov_b32_e32 v236, v104
	v_mov_b32_e32 v237, v105
	v_mfma_f32_16x16x32_f16 v[104:107], v[116:119], v[16:19], v[144:147]
	v_or_b32_e32 v170, 0x30000, v170
	v_lshlrev_b64 v[116:117], 1, v[170:171]
	v_lshl_add_u64 v[118:119], v[94:95], 0, v[116:117]
	v_mfma_f32_16x16x32_f16 v[104:107], v[128:131], v[32:35], v[104:107]
	ds_bpermute_b32 v128, v150, v96 offset:8
	ds_bpermute_b32 v129, v194, v96
	v_lshl_add_u64 v[130:131], v[94:95], 0, 32
	v_mfma_f32_16x16x32_f16 v[158:161], v[212:215], v[56:59], v[196:199]
	v_lshl_add_u64 v[144:145], v[130:131], 0, v[140:141]
	s_nop 2
	v_pk_mul_f32 v[104:105], v[104:105], v[188:189]
	v_pk_mul_f32 v[106:107], v[106:107], v[190:191]
	v_cvt_pk_f16_f32 v104, v104, v105
	v_cvt_pk_f16_f32 v105, v106, v107
	v_mov_b32_e32 v240, v104
	v_mov_b32_e32 v241, v105
	v_mfma_f32_16x16x32_f16 v[104:107], v[80:83], v[36:39], v[154:157]
	ds_bpermute_b32 v118, v150, v96
	ds_bpermute_b32 v119, v150, v96 offset:4
	v_mfma_f32_16x16x32_f16 v[104:107], v[132:135], v[60:63], v[104:107]
	v_mfma_f32_16x16x32_f16 v[120:123], v[220:223], v[76:79], v[120:123]
	v_mfma_f32_16x16x32_f16 v[76:79], v[0:3], v[76:79], v[108:111]
	s_waitcnt lgkmcnt(0)
; DI unsigned pack2(float lo, float hi) { f2_t v = {lo, hi}; h2_t b = __builtin_convertvector(v, h2_t); return __builtin_bit_cast(unsigned, b); }
; DI void phase_proj(const Params& P, int l, char* smem) {
;     ...
; #pragma unroll
;       for (int mt = 0; mt < 4; ++mt) {
;         float r4[4];
; #pragma unroll
;         for (int j = 0; j < 4; ++j) r4[j] = __shfl(rs[mt], 4 * g + j);
; #pragma unroll
;         for (int nt = 0; nt < 4; ++nt) {
;           const int c = c0 + nt * 16 + lr;
;           bf16_t* dst = VT + ((size_t)(br * NB + b) * 512 + c) * SEQ + s0 + mt * 16 + 4 * g;
;           *(uint2*)dst = make_uint2(pack2(acc[mt][nt][0] * r4[0], acc[mt][nt][1] * r4[1]), pack2(acc[mt][nt][2] * r4[2], acc[mt][nt][3] * r4[3]));
;         }
;       }
	s_nop 4
	v_pk_mul_f32 v[104:105], v[104:105], v[118:119]
	v_pk_mul_f32 v[106:107], v[106:107], v[128:129]
	v_cvt_pk_f16_f32 v104, v104, v105
	v_mfma_f32_16x16x32_f16 v[108:111], v[80:83], v[24:27], v[158:161]
	v_cvt_pk_f16_f32 v105, v106, v107
	v_mov_b32_e32 v230, v104
	v_mov_b32_e32 v231, v105
	v_and_b32_e32 v244, 16, v148
	v_lshrrev_b32_e32 v245, 1, v244
	v_add_u32_e32 v244, v244, v245
	v_mov_b32_e32 v245, 0
	v_lshl_add_u64 v[244:245], v[244:245], 0, v[98:99]
	v_permlane16_swap_b32_e32 v228, v230
	v_permlane16_swap_b32_e32 v229, v231
	global_store_dwordx4 v[244:245], v[228:231], off
	v_mfma_f32_16x16x32_f16 v[162:165], v[212:215], v[8:11], v[200:203]
	v_mfma_f32_16x16x32_f16 v[166:169], v[212:215], v[4:7], v[204:207]
	v_mfma_f32_16x16x32_f16 v[104:107], v[132:135], v[52:55], v[108:111]
	v_mfma_f32_16x16x32_f16 v[108:111], v[80:83], v[20:23], v[162:165]
	v_mfma_f32_16x16x32_f16 v[80:83], v[80:83], v[16:19], v[166:169]
	s_nop 5
	v_mul_f32_e64 v104, v104, v118
	v_mul_f32_e64 v105, v105, v119
	v_pk_mul_f32 v[106:107], v[106:107], v[128:129]
	v_cvt_pk_f16_f32 v104, v104, v105
	v_cvt_pk_f16_f32 v105, v106, v107
	v_mfma_f32_16x16x32_f16 v[80:83], v[132:135], v[32:35], v[80:83]
	v_mov_b32_e32 v234, v104
	v_mov_b32_e32 v235, v105
	v_and_b32_e32 v244, 16, v148
	v_lshrrev_b32_e32 v245, 1, v244
	v_add_u32_e32 v244, v244, v245
	v_mov_b32_e32 v245, 0
	v_lshl_add_u64 v[244:245], v[244:245], 0, v[144:145]
	v_permlane16_swap_b32_e32 v232, v234
	v_permlane16_swap_b32_e32 v233, v235
	global_store_dwordx4 v[244:245], v[232:235], off offset:-32
	v_mfma_f32_16x16x32_f16 v[104:107], v[132:135], v[48:51], v[108:111]
	v_mfma_f32_16x16x32_f16 v[124:127], v[220:223], v[56:59], v[124:127]
	s_nop 4
	v_mul_f32_e64 v80, v80, v118
	v_mul_f32_e64 v81, v81, v119
	v_pk_mul_f32 v[104:105], v[104:105], v[118:119]
	v_pk_mul_f32 v[106:107], v[106:107], v[128:129]
	v_mfma_f32_16x16x32_f16 v[56:59], v[0:3], v[56:59], v[72:75]
	v_cvt_pk_f16_f32 v80, v80, v81
	v_lshl_add_u64 v[108:109], v[130:131], 0, v[142:143]
	v_cvt_pk_f16_f32 v104, v104, v105
	v_pk_mul_f32 v[72:73], v[82:83], v[128:129]
	v_cvt_pk_f16_f32 v105, v106, v107
	v_cvt_pk_f16_f32 v81, v72, v73
	v_mfma_f32_16x16x32_f16 v[72:75], v[64:67], v[36:39], v[120:123]
	v_mov_b32_e32 v238, v104
	v_mov_b32_e32 v239, v105
	v_and_b32_e32 v244, 16, v148
	v_lshrrev_b32_e32 v245, 1, v244
	v_add_u32_e32 v244, v244, v245
	v_mov_b32_e32 v245, 0
	v_lshl_add_u64 v[244:245], v[244:245], 0, v[108:109]
	v_permlane16_swap_b32_e32 v236, v238
	v_permlane16_swap_b32_e32 v237, v239
	global_store_dwordx4 v[244:245], v[236:239], off offset:-32
	v_lshl_add_u64 v[104:105], v[130:131], 0, v[116:117]
	v_mov_b32_e32 v242, v80
	v_mov_b32_e32 v243, v81
	v_and_b32_e32 v244, 16, v148
	v_lshrrev_b32_e32 v245, 1, v244
	v_add_u32_e32 v244, v244, v245
	v_mov_b32_e32 v245, 0
	v_lshl_add_u64 v[244:245], v[244:245], 0, v[104:105]
	v_permlane16_swap_b32_e32 v240, v242
	v_permlane16_swap_b32_e32 v241, v243
	global_store_dwordx4 v[244:245], v[240:243], off offset:-32
	ds_bpermute_b32 v104, v150, v102
	ds_bpermute_b32 v105, v150, v102 offset:4
	ds_bpermute_b32 v106, v150, v102 offset:8
	v_mfma_f32_16x16x32_f16 v[72:75], v[68:71], v[60:63], v[72:75]
	ds_bpermute_b32 v107, v194, v102
	v_lshl_add_u64 v[102:103], v[94:95], 0, 64
	v_mfma_f32_16x16x32_f16 v[80:83], v[64:67], v[24:27], v[124:127]
	v_mfma_f32_16x16x32_f16 v[136:139], v[220:223], v[8:11], v[136:139]
	s_waitcnt lgkmcnt(2)
	s_nop 2
	v_pk_mul_f32 v[72:73], v[72:73], v[104:105]
	s_nop 0
	v_cvt_pk_f16_f32 v108, v72, v73
	v_mfma_f32_16x16x32_f16 v[112:115], v[220:223], v[4:7], v[224:227]
	s_waitcnt lgkmcnt(0)
; DI unsigned pack2(float lo, float hi) { f2_t v = {lo, hi}; h2_t b = __builtin_convertvector(v, h2_t); return __builtin_bit_cast(unsigned, b); }
; DI void phase_proj(const Params& P, int l, char* smem) {
;     ...
; #pragma unroll
;       for (int mt = 0; mt < 4; ++mt) {
;         float r4[4];
; #pragma unroll
;         for (int j = 0; j < 4; ++j) r4[j] = __shfl(rs[mt], 4 * g + j);
; #pragma unroll
;         for (int nt = 0; nt < 4; ++nt) {
;           const int c = c0 + nt * 16 + lr;
;           bf16_t* dst = VT + ((size_t)(br * NB + b) * 512 + c) * SEQ + s0 + mt * 16 + 4 * g;
;           *(uint2*)dst = make_uint2(pack2(acc[mt][nt][0] * r4[0], acc[mt][nt][1] * r4[1]), pack2(acc[mt][nt][2] * r4[2], acc[mt][nt][3] * r4[3]));
;         }
;       }
	v_pk_mul_f32 v[72:73], v[74:75], v[106:107]
	s_nop 0
	v_cvt_pk_f16_f32 v109, v72, v73
	v_mfma_f32_16x16x32_f16 v[72:75], v[68:71], v[52:55], v[80:83]
	v_mov_b32_e32 v228, v108
	v_mov_b32_e32 v229, v109
	v_lshl_add_u64 v[108:109], v[102:103], 0, v[140:141]
	v_mfma_f32_16x16x32_f16 v[80:83], v[64:67], v[20:23], v[136:139]
	v_mfma_f32_16x16x32_f16 v[64:67], v[64:67], v[16:19], v[112:115]
	s_nop 3
	v_mul_f32_e64 v72, v72, v104
	v_mul_f32_e64 v73, v73, v105
	v_cvt_pk_f16_f32 v110, v72, v73
	v_pk_mul_f32 v[72:73], v[74:75], v[106:107]
	v_mfma_f32_16x16x32_f16 v[64:67], v[68:71], v[32:35], v[64:67]
	v_cvt_pk_f16_f32 v111, v72, v73
	v_mov_b32_e32 v232, v110
	v_mov_b32_e32 v233, v111
	v_mfma_f32_16x16x32_f16 v[72:75], v[68:71], v[48:51], v[80:83]
	v_lshl_add_u64 v[68:69], v[102:103], 0, v[116:117]
	s_nop 3
	v_pk_mul_f32 v[64:65], v[64:65], v[104:105]
	v_mfma_f32_16x16x32_f16 v[8:11], v[0:3], v[8:11], v[40:43]
	v_lshl_add_u64 v[80:81], v[102:103], 0, v[142:143]
	v_pk_mul_f32 v[72:73], v[72:73], v[104:105]
	v_pk_mul_f32 v[74:75], v[74:75], v[106:107]
	v_mfma_f32_16x16x32_f16 v[0:3], v[0:3], v[4:7], v[44:47]
	v_mul_f32_e64 v42, v66, v106
	v_mul_f32_e64 v43, v67, v107
	v_cvt_pk_f16_f32 v72, v72, v73
	v_cvt_pk_f16_f32 v73, v74, v75
	v_mfma_f32_16x16x32_f16 v[4:7], v[12:15], v[36:39], v[76:79]
	v_cvt_pk_f16_f32 v40, v64, v65
	v_cvt_pk_f16_f32 v41, v42, v43
	v_mov_b32_e32 v236, v72
	v_mov_b32_e32 v237, v73
	v_mov_b32_e32 v240, v40
	v_mov_b32_e32 v241, v41
	ds_bpermute_b32 v40, v150, v100
	ds_bpermute_b32 v41, v150, v100 offset:4
	ds_bpermute_b32 v36, v150, v100 offset:8
	ds_bpermute_b32 v37, v194, v100
	v_mfma_f32_16x16x32_f16 v[4:7], v[28:31], v[60:63], v[4:7]
	v_lshl_add_u64 v[38:39], v[94:95], 0, s[4:5]
	v_mfma_f32_16x16x32_f16 v[0:3], v[12:15], v[16:19], v[0:3]
	v_mfma_f32_16x16x32_f16 v[0:3], v[28:31], v[32:35], v[0:3]
	s_waitcnt lgkmcnt(2)
	s_nop 3
	v_pk_mul_f32 v[4:5], v[4:5], v[40:41]
	s_waitcnt lgkmcnt(0)
	v_pk_mul_f32 v[44:45], v[6:7], v[36:37]
	v_cvt_pk_f16_f32 v42, v4, v5
	v_mfma_f32_16x16x32_f16 v[4:7], v[12:15], v[24:27], v[56:59]
	v_cvt_pk_f16_f32 v43, v44, v45
	v_mov_b32_e32 v230, v42
	v_mov_b32_e32 v231, v43
	v_and_b32_e32 v244, 16, v148
	v_lshrrev_b32_e32 v245, 1, v244
	v_add_u32_e32 v244, v244, v245
	v_mov_b32_e32 v245, 0
	v_lshl_add_u64 v[244:245], v[244:245], 0, v[98:99]
	v_permlane16_swap_b32_e32 v228, v230
	v_permlane16_swap_b32_e32 v229, v231
	global_store_dwordx4 v[244:245], v[228:231], off offset:64
	v_lshl_add_u64 v[24:25], v[38:39], 0, v[140:141]
	v_mfma_f32_16x16x32_f16 v[4:7], v[28:31], v[52:55], v[4:7]
	v_mul_f32_e64 v0, v0, v40
	v_mul_f32_e64 v1, v1, v41
	v_pk_mul_f32 v[2:3], v[2:3], v[36:37]
	v_cvt_pk_f16_f32 v0, v0, v1
	v_cvt_pk_f16_f32 v1, v2, v3
	s_nop 2
	v_pk_mul_f32 v[4:5], v[4:5], v[40:41]
	v_pk_mul_f32 v[42:43], v[6:7], v[36:37]
	v_cvt_pk_f16_f32 v26, v4, v5
	v_mfma_f32_16x16x32_f16 v[4:7], v[12:15], v[20:23], v[8:11]
	v_cvt_pk_f16_f32 v27, v42, v43
	v_mov_b32_e32 v234, v26
	v_mov_b32_e32 v235, v27
	v_and_b32_e32 v244, 16, v148
	v_lshrrev_b32_e32 v245, 1, v244
	v_add_u32_e32 v244, v244, v245
	v_mov_b32_e32 v245, 0
	v_lshl_add_u64 v[244:245], v[244:245], 0, v[24:25]
	v_permlane16_swap_b32_e32 v232, v234
	v_permlane16_swap_b32_e32 v233, v235
	global_store_dwordx4 v[244:245], v[232:235], off offset:-32
	v_mfma_f32_16x16x32_f16 v[4:7], v[28:31], v[48:51], v[4:7]
	v_lshl_add_u64 v[8:9], v[38:39], 0, v[142:143]
	s_nop 6
	v_pk_mul_f32 v[4:5], v[4:5], v[40:41]
	v_pk_mul_f32 v[6:7], v[6:7], v[36:37]
	v_cvt_pk_f16_f32 v4, v4, v5
	v_cvt_pk_f16_f32 v5, v6, v7
	v_mov_b32_e32 v238, v4
	v_mov_b32_e32 v239, v5
	v_and_b32_e32 v244, 16, v148
	v_lshrrev_b32_e32 v245, 1, v244
	v_add_u32_e32 v244, v244, v245
	v_mov_b32_e32 v245, 0
	v_lshl_add_u64 v[244:245], v[244:245], 0, v[8:9]
	v_permlane16_swap_b32_e32 v236, v238
	v_permlane16_swap_b32_e32 v237, v239
	global_store_dwordx4 v[244:245], v[236:239], off offset:-32
	v_lshl_add_u64 v[4:5], v[38:39], 0, v[116:117]
	v_mov_b32_e32 v242, v0
	v_mov_b32_e32 v243, v1
	v_and_b32_e32 v244, 16, v148
	v_lshrrev_b32_e32 v245, 1, v244
	v_add_u32_e32 v244, v244, v245
	v_mov_b32_e32 v245, 0
	v_lshl_add_u64 v[244:245], v[244:245], 0, v[4:5]
	v_permlane16_swap_b32_e32 v240, v242
	v_permlane16_swap_b32_e32 v241, v243
	global_store_dwordx4 v[244:245], v[240:243], off offset:-32
	s_branch .LBB0_636

; DI int TIDX() { int t = threadIdx.x; asm volatile("" : "+v"(t)); return t; }
; #define GL_LOAD(s_, kt_) if (VAR != 1) { a##s_##0 = GL_A(0, kt_); a##s_##1 = GL_A(1, kt_); a##s_##2 = GL_A(2, kt_); a##s_##3 = GL_A(3, kt_); b##s_##0 = GL_B(0, kt_); b##s_##1 = GL_B(1, kt_); b##s_##2 = GL_B(2, kt_); b##s_##3 = GL_B(3, kt_); }
; #define LDS_STORE(s_, buf_) if (VAR != 2) { LDS_ST1(sA, 0, buf_, a##s_##0) LDS_ST1(sA, 1, buf_, a##s_##1) LDS_ST1(sA, 2, buf_, a##s_##2) LDS_ST1(sA, 3, buf_, a##s_##3) LDS_ST1(sB, 0, buf_, b##s_##0) LDS_ST1(sB, 1, buf_, b##s_##1) LDS_ST1(sB, 2, buf_, b##s_##2) LDS_ST1(sB, 3, buf_, b##s_##3) }
;   const int tid = TIDX(), lane = tid & 63, wid = tid >> 6, wm = wid >> 1, wn = wid & 1, lr = lane & 15, g = lane >> 4;
;   char* sA = smem; char* sB = smem + 2 * LTILE;
;   uint4 a00 = {}, a01 = {}, a02 = {}, a03 = {}, b00 = {}, b01 = {}, b02 = {}, b03 = {}, a10 = {}, a11 = {}, a12 = {}, a13 = {}, b10 = {}, b11 = {}, b12 = {}, b13 = {};
;   constexpr int nk = NK;
;   const int sw0 = (g ^ ((lr >> 1) & 7)) << 4, sw1 = sw0 ^ 64;
;   const int r0 = tid >> 3, kc = tid & 7, kcs = kc ^ ((r0 >> 1) & 7);
;     ...
;   GL_LOAD(0, 0)
;   GL_LOAD(1, 1)
;   LDS_STORE(0, 0)
;   if (VAR != 4) __syncthreads();
; DI void phase_merge(const Params& P, int l, char* smem) {
;     ...
;     for (int br = 0; br < 3; ++br) {
;       f32x4 acc[4][4]; zero_acc(acc);
;       const int ycol = br == 0 ? C_AQ : (br == 1 ? C_BQ : C_CQ);
;       const bf16_t* Wb = W + (br == 0 ? WO_BRA : (br == 1 ? WO_BRB : WO_BRC));
;       gemm_kloop<false, true, 8>(acc, Pb + (size_t)m0 * PW + ycol, PW, Wb + (size_t)n0 * 512, 512, smem);
.LBB0_1161:
	s_cmp_lg_u32 s4, 0
	s_cselect_b64 s[6:7], -1, 0
	s_cmpk_eq_i32 s4, 0x800
	s_mov_b32 s8, 0x860000
	s_cselect_b32 s17, 0x400, s36
	s_cselect_b32 s20, s8, 0x8e0000
	s_cmp_eq_u32 s4, 0
	s_cselect_b64 s[8:9], -1, 0
	s_and_b64 s[18:19], s[8:9], exec
	s_cselect_b32 s17, 0, s17
	s_cselect_b32 s20, 0x7e0000, s20
	s_lshl_b32 s17, s17, 1
	s_add_u32 s18, s13, s17
	s_addc_u32 s19, s14, 0
	v_mov_b32_e32 v56, v148
	v_mov_b64_e32 v[6:7], s[18:19]
	v_ashrrev_i32_e32 v16, 3, v56
	v_lshlrev_b32_e32 v57, 4, v56
	v_mad_i64_i32 v[0:1], s[18:19], v16, s0, v[6:7]
	v_and_b32_e32 v150, 0x70, v57
	v_add_u32_e32 v18, 32, v16
	s_lshl_b32 s17, s20, 1
	v_lshl_add_u64 v[0:1], v[0:1], 0, v[150:151]
	v_mad_i64_i32 v[2:3], s[18:19], v18, s0, v[6:7]
	v_add_u32_e32 v52, 64, v16
	s_add_u32 s20, s15, s17
	v_ashrrev_i32_e32 v17, 31, v16
	global_load_dwordx4 v[20:23], v[0:1], off
	v_lshl_add_u64 v[2:3], v[2:3], 0, v[150:151]
	v_mad_i64_i32 v[4:5], s[18:19], v52, s0, v[6:7]
	v_add_u32_e32 v54, 0x60, v16
	s_addc_u32 s21, s16, 0
	v_ashrrev_i32_e32 v19, 31, v18
	global_load_dwordx4 v[24:27], v[2:3], off
	v_lshl_add_u64 v[4:5], v[4:5], 0, v[150:151]
	v_mad_i64_i32 v[6:7], s[18:19], v54, s0, v[6:7]
	v_lshlrev_b64 v[8:9], 10, v[16:17]
	v_ashrrev_i32_e32 v53, 31, v52
	global_load_dwordx4 v[28:31], v[4:5], off
	v_lshl_add_u64 v[6:7], v[6:7], 0, v[150:151]
	v_lshl_add_u64 v[8:9], s[20:21], 0, v[8:9]
	v_lshlrev_b64 v[10:11], 10, v[18:19]
	v_ashrrev_i32_e32 v55, 31, v54
	global_load_dwordx4 v[32:35], v[6:7], off
	v_lshl_add_u64 v[8:9], v[8:9], 0, v[150:151]
	v_lshl_add_u64 v[10:11], s[20:21], 0, v[10:11]
	v_lshlrev_b64 v[12:13], 10, v[52:53]
	global_load_dwordx4 v[36:39], v[8:9], off
	v_lshl_add_u64 v[10:11], v[10:11], 0, v[150:151]
	v_lshl_add_u64 v[12:13], s[20:21], 0, v[12:13]
	v_lshlrev_b64 v[14:15], 10, v[54:55]
	global_load_dwordx4 v[40:43], v[10:11], off
	v_lshl_add_u64 v[12:13], v[12:13], 0, v[150:151]
	v_lshl_add_u64 v[14:15], s[20:21], 0, v[14:15]
	global_load_dwordx4 v[44:47], v[12:13], off
	v_lshl_add_u64 v[14:15], v[14:15], 0, v[150:151]
	global_load_dwordx4 v[48:51], v[14:15], off
	v_lshlrev_b32_e32 v19, 3, v56
	v_and_b32_e32 v108, 48, v56
	v_and_b32_e32 v17, 15, v56
	v_lshrrev_b32_e32 v53, 1, v56
	v_lshlrev_b32_e32 v55, 7, v56
	v_and_b32_e32 v109, 0x70, v19
	v_bitop3_b32 v115, v19, v108, s23 bitop3:0x6c
	v_bitop3_b32 v19, v57, s23, v56 bitop3:0x48
	v_and_or_b32 v136, v53, s24, v17
	v_and_b32_e32 v150, 0x2780, v55
	v_lshl_or_b32 v16, v16, 7, v19
	v_lshl_or_b32 v17, v18, 7, v19
	v_lshl_or_b32 v18, v52, 7, v19
	v_lshl_or_b32 v19, v54, 7, v19
	global_load_dwordx4 v[52:55], v[0:1], off offset:128
	global_load_dwordx4 v[56:59], v[2:3], off offset:128
	global_load_dwordx4 v[104:107], v[4:5], off offset:128
	global_load_dwordx4 v[116:119], v[6:7], off offset:128
	global_load_dwordx4 v[120:123], v[8:9], off offset:128
	global_load_dwordx4 v[124:127], v[10:11], off offset:128
	global_load_dwordx4 v[128:131], v[12:13], off offset:128
	global_load_dwordx4 v[132:135], v[14:15], off offset:128
	s_and_b64 vcc, s[8:9], exec
	s_waitcnt vmcnt(15)
	ds_write_b128 v16, v[20:23]
	s_waitcnt vmcnt(14)
	ds_write_b128 v17, v[24:27]
	s_waitcnt vmcnt(13)
	ds_write_b128 v18, v[28:31]
	s_waitcnt vmcnt(12)
	ds_write_b128 v19, v[32:35]
	s_waitcnt vmcnt(11)
	ds_write_b128 v16, v[36:39] offset:32768
	s_waitcnt vmcnt(10)
	ds_write_b128 v17, v[40:43] offset:32768
	s_waitcnt vmcnt(9)
	ds_write_b128 v18, v[44:47] offset:32768
	s_waitcnt vmcnt(8)
	ds_write_b128 v19, v[48:51] offset:32768
	v_or_b32_e32 v20, v150, v115
	s_waitcnt lgkmcnt(0)
	s_barrier
	s_setprio 2
	ds_read_b128 v[22:25], v20 offset:32768
	v_lshlrev_b32_e32 v50, 7, v136
	v_bitop3_b32 v21, v50, v109, v108 bitop3:0xf6
	ds_read_b128 v[30:33], v21
	s_waitcnt lgkmcnt(0)
	v_mfma_f32_16x16x32_f16 v[38:41], v[22:25], v[30:33], 0
	ds_read_b128 v[26:29], v20 offset:34816
	ds_read_b128 v[34:37], v21 offset:2048
	s_waitcnt lgkmcnt(0)
	v_mfma_f32_16x16x32_f16 v[144:147], v[22:25], v[34:37], 0
	ds_read_b128 v[42:45], v20 offset:36864
	ds_read_b128 v[162:165], v21 offset:4096
	s_waitcnt lgkmcnt(0)
	v_mfma_f32_16x16x32_f16 v[190:193], v[22:25], v[162:165], 0
	ds_read_b128 v[136:139], v20 offset:38912
	ds_read_b128 v[166:169], v21 offset:6144
	s_waitcnt lgkmcnt(0)
	v_mfma_f32_16x16x32_f16 v[202:205], v[22:25], v[166:169], 0
	v_lshl_add_u64 v[108:109], v[80:81], 0, s[4:5]
	v_mfma_f32_16x16x32_f16 v[46:49], v[26:29], v[30:33], 0
	v_xor_b32_e32 v22, 64, v115
	v_mfma_f32_16x16x32_f16 v[140:143], v[42:45], v[30:33], 0
	v_or_b32_e32 v23, v150, v22
	v_mfma_f32_16x16x32_f16 v[30:33], v[136:139], v[30:33], 0
	ds_read_b128 v[206:209], v23 offset:32768
	v_mfma_f32_16x16x32_f16 v[154:157], v[26:29], v[34:37], 0
	ds_read_b128 v[224:227], v23 offset:36864
	v_mfma_f32_16x16x32_f16 v[158:161], v[42:45], v[34:37], 0
	ds_read_b128 v[228:231], v23 offset:38912
	v_mfma_f32_16x16x32_f16 v[34:37], v[136:139], v[34:37], 0
	v_bitop3_b32 v22, v50, v115, 64 bitop3:0xf6
	v_mfma_f32_16x16x32_f16 v[194:197], v[26:29], v[162:165], 0
	ds_read_b128 v[210:213], v22
	v_mfma_f32_16x16x32_f16 v[198:201], v[42:45], v[162:165], 0
	ds_read_b128 v[220:223], v22 offset:2048
	v_mfma_f32_16x16x32_f16 v[162:165], v[136:139], v[162:165], 0
	s_waitcnt vmcnt(7)
	ds_write_b128 v16, v[52:55] offset:16384
	v_mfma_f32_16x16x32_f16 v[24:27], v[26:29], v[166:169], 0
	s_waitcnt vmcnt(6)
	ds_write_b128 v17, v[56:59] offset:16384
	v_mfma_f32_16x16x32_f16 v[42:45], v[42:45], v[166:169], 0
	s_waitcnt vmcnt(5)
	ds_write_b128 v18, v[104:107] offset:16384
	v_mfma_f32_16x16x32_f16 v[136:139], v[136:139], v[166:169], 0
	ds_read_b128 v[166:169], v23 offset:34816
	s_waitcnt lgkmcnt(5)
; #define GL_LOAD(s_, kt_) if (VAR != 1) { a##s_##0 = GL_A(0, kt_); a##s_##1 = GL_A(1, kt_); a##s_##2 = GL_A(2, kt_); a##s_##3 = GL_A(3, kt_); b##s_##0 = GL_B(0, kt_); b##s_##1 = GL_B(1, kt_); b##s_##2 = GL_B(2, kt_); b##s_##3 = GL_B(3, kt_); }
; #define LDS_STORE(s_, buf_) if (VAR != 2) { LDS_ST1(sA, 0, buf_, a##s_##0) LDS_ST1(sA, 1, buf_, a##s_##1) LDS_ST1(sA, 2, buf_, a##s_##2) LDS_ST1(sA, 3, buf_, a##s_##3) LDS_ST1(sB, 0, buf_, b##s_##0) LDS_ST1(sB, 1, buf_, b##s_##1) LDS_ST1(sB, 2, buf_, b##s_##2) LDS_ST1(sB, 3, buf_, b##s_##3) }
;     ...
;   GL_LOAD(0, 0)
;   GL_LOAD(1, 1)
;   LDS_STORE(0, 0)
;   if (VAR != 4) __syncthreads();
; #pragma unroll
;   for (int kt = 0; kt < nk; kt += 2) {
;     if (kt + 2 < nk) { GL_LOAD(0, kt + 2) }
;     MMA_TILE(0)
;     LDS_STORE(1, 1)
;     if (VAR != 4) __syncthreads();
;     if (kt + 3 < nk) { GL_LOAD(1, kt + 3) }
;     MMA_TILE(1)
;     if (kt + 2 < nk) { LDS_STORE(0, 0) }
;     if (VAR != 4) __syncthreads();
;   }
	v_mfma_f32_16x16x32_f16 v[38:41], v[206:209], v[210:213], v[38:41]
	s_waitcnt vmcnt(4)
	ds_write_b128 v19, v[116:119] offset:16384
	v_mfma_f32_16x16x32_f16 v[140:143], v[224:227], v[210:213], v[140:143]
	s_waitcnt vmcnt(3)
	ds_write_b128 v16, v[120:123] offset:49152
	v_mfma_f32_16x16x32_f16 v[28:31], v[228:231], v[210:213], v[30:33]
	s_waitcnt vmcnt(2)
	ds_write_b128 v17, v[124:127] offset:49152
	s_waitcnt lgkmcnt(7)
	v_mfma_f32_16x16x32_f16 v[144:147], v[206:209], v[220:223], v[144:147]
	s_waitcnt vmcnt(1)
	ds_write_b128 v18, v[128:131] offset:49152
	v_mfma_f32_16x16x32_f16 v[158:161], v[224:227], v[220:223], v[158:161]
	s_waitcnt vmcnt(0)
	ds_write_b128 v19, v[132:135] offset:49152
	v_mfma_f32_16x16x32_f16 v[32:35], v[228:231], v[220:223], v[34:37]
	s_waitcnt lgkmcnt(5)
	v_mfma_f32_16x16x32_f16 v[46:49], v[166:169], v[210:213], v[46:49]
	ds_read_b128 v[210:213], v22 offset:4096
	v_mfma_f32_16x16x32_f16 v[154:157], v[166:169], v[220:223], v[154:157]
	ds_read_b128 v[220:223], v22 offset:6144
	s_waitcnt lgkmcnt(1)
	v_mfma_f32_16x16x32_f16 v[190:193], v[206:209], v[210:213], v[190:193]
	s_waitcnt lgkmcnt(0)
	v_mfma_f32_16x16x32_f16 v[202:205], v[206:209], v[220:223], v[202:205]
	global_load_dwordx4 v[206:209], v[0:1], off offset:256
	v_mfma_f32_16x16x32_f16 v[194:197], v[166:169], v[210:213], v[194:197]
	v_mfma_f32_16x16x32_f16 v[24:27], v[166:169], v[220:223], v[24:27]
	v_mfma_f32_16x16x32_f16 v[198:201], v[224:227], v[210:213], v[198:201]
	v_mfma_f32_16x16x32_f16 v[162:165], v[228:231], v[210:213], v[162:165]
	global_load_dwordx4 v[210:213], v[2:3], off offset:256
	global_load_dwordx4 v[232:235], v[4:5], off offset:256
	global_load_dwordx4 v[236:239], v[6:7], off offset:256
	global_load_dwordx4 v[166:169], v[8:9], off offset:256
	global_load_dwordx4 v[240:243], v[10:11], off offset:256
	global_load_dwordx4 v[244:247], v[12:13], off offset:256
	global_load_dwordx4 v[248:251], v[14:15], off offset:256
	s_waitcnt lgkmcnt(0)
	s_barrier
	v_mfma_f32_16x16x32_f16 v[54:57], v[228:231], v[220:223], v[136:139]
	ds_read_b128 v[50:53], v20 offset:49152
	v_mfma_f32_16x16x32_f16 v[42:45], v[224:227], v[220:223], v[42:45]
	ds_read_b128 v[104:107], v20 offset:51200
	ds_read_b128 v[116:119], v21 offset:16384
	s_waitcnt lgkmcnt(0)
	v_mfma_f32_16x16x32_f16 v[36:39], v[50:53], v[116:119], v[38:41]
	ds_read_b128 v[120:123], v21 offset:18432
	v_mfma_f32_16x16x32_f16 v[46:49], v[104:107], v[116:119], v[46:49]
	ds_read_b128 v[124:127], v20 offset:53248
	s_waitcnt lgkmcnt(0)
	v_mfma_f32_16x16x32_f16 v[132:135], v[124:127], v[116:119], v[140:143]
	ds_read_b128 v[128:131], v20 offset:55296
	s_waitcnt lgkmcnt(0)
	v_mfma_f32_16x16x32_f16 v[28:31], v[128:131], v[116:119], v[28:31]
	v_mfma_f32_16x16x32_f16 v[116:119], v[50:53], v[120:123], v[144:147]
	s_nop 2
	ds_read_b128 v[144:147], v21 offset:22528
	s_waitcnt vmcnt(7)
	ds_write_b128 v16, v[206:209]
	v_mfma_f32_16x16x32_f16 v[136:139], v[104:107], v[120:123], v[154:157]
	s_waitcnt vmcnt(6)
	ds_write_b128 v17, v[210:213]
	s_waitcnt vmcnt(5)
	ds_write_b128 v18, v[232:235]
	v_mfma_f32_16x16x32_f16 v[140:143], v[124:127], v[120:123], v[158:161]
	s_waitcnt vmcnt(4)
	ds_write_b128 v19, v[236:239]
	s_waitcnt vmcnt(3)
	ds_write_b128 v16, v[166:169] offset:32768
	v_mfma_f32_16x16x32_f16 v[32:35], v[128:131], v[120:123], v[32:35]
	ds_read_b128 v[120:123], v21 offset:20480
	s_waitcnt lgkmcnt(0)
	v_mfma_f32_16x16x32_f16 v[154:157], v[50:53], v[120:123], v[190:193]
	s_waitcnt vmcnt(2)
	ds_write_b128 v17, v[240:243] offset:32768
	v_mfma_f32_16x16x32_f16 v[50:53], v[50:53], v[144:147], v[202:205]
	s_waitcnt vmcnt(1)
	ds_write_b128 v18, v[244:247] offset:32768
	v_mfma_f32_16x16x32_f16 v[158:161], v[104:107], v[120:123], v[194:197]
	s_nop 2
	ds_read_b128 v[194:197], v23 offset:55296
	v_mfma_f32_16x16x32_f16 v[24:27], v[104:107], v[144:147], v[24:27]
	ds_read_b128 v[104:107], v23 offset:49152
	v_mfma_f32_16x16x32_f16 v[190:193], v[124:127], v[120:123], v[198:201]
	s_waitcnt vmcnt(0)
	ds_write_b128 v19, v[248:251] offset:32768
	v_mfma_f32_16x16x32_f16 v[40:43], v[124:127], v[144:147], v[42:45]
	ds_read_b128 v[124:127], v23 offset:51200
	v_mfma_f32_16x16x32_f16 v[120:123], v[128:131], v[120:123], v[162:165]
	s_nop 2
	ds_read_b128 v[162:165], v23 offset:53248
	v_mfma_f32_16x16x32_f16 v[54:57], v[128:131], v[144:147], v[54:57]
	ds_read_b128 v[128:131], v22 offset:16384
	s_waitcnt lgkmcnt(0)
	v_mfma_f32_16x16x32_f16 v[36:39], v[104:107], v[128:131], v[36:39]
	ds_read_b128 v[144:147], v22 offset:18432
	s_waitcnt lgkmcnt(0)
	v_mfma_f32_16x16x32_f16 v[116:119], v[104:107], v[144:147], v[116:119]
	v_mfma_f32_16x16x32_f16 v[44:47], v[124:127], v[128:131], v[46:49]
	v_mfma_f32_16x16x32_f16 v[132:135], v[162:165], v[128:131], v[132:135]
	v_mfma_f32_16x16x32_f16 v[28:31], v[194:197], v[128:131], v[28:31]
	v_mfma_f32_16x16x32_f16 v[128:131], v[124:127], v[144:147], v[136:139]
	v_mfma_f32_16x16x32_f16 v[136:139], v[162:165], v[144:147], v[140:143]
	s_nop 2
	ds_read_b128 v[140:143], v22 offset:20480
	v_mfma_f32_16x16x32_f16 v[32:35], v[194:197], v[144:147], v[32:35]
	ds_read_b128 v[144:147], v22 offset:22528
	s_waitcnt lgkmcnt(1)
	v_mfma_f32_16x16x32_f16 v[154:157], v[104:107], v[140:143], v[154:157]
	s_waitcnt lgkmcnt(0)
	v_mfma_f32_16x16x32_f16 v[48:51], v[104:107], v[144:147], v[50:53]
	global_load_dwordx4 v[104:107], v[0:1], off offset:384
	v_mfma_f32_16x16x32_f16 v[158:161], v[124:127], v[140:143], v[158:161]
	v_mfma_f32_16x16x32_f16 v[24:27], v[124:127], v[144:147], v[24:27]
	v_mfma_f32_16x16x32_f16 v[190:193], v[162:165], v[140:143], v[190:193]
	v_mfma_f32_16x16x32_f16 v[40:43], v[162:165], v[144:147], v[40:43]
	v_mfma_f32_16x16x32_f16 v[120:123], v[194:197], v[140:143], v[120:123]
	global_load_dwordx4 v[140:143], v[2:3], off offset:384
	global_load_dwordx4 v[198:201], v[4:5], off offset:384
	global_load_dwordx4 v[202:205], v[6:7], off offset:384
	global_load_dwordx4 v[124:127], v[8:9], off offset:384
	global_load_dwordx4 v[220:223], v[10:11], off offset:384
	global_load_dwordx4 v[224:227], v[12:13], off offset:384
	global_load_dwordx4 v[228:231], v[14:15], off offset:384
	s_waitcnt lgkmcnt(0)
	s_barrier
; #define GL_LOAD(s_, kt_) if (VAR != 1) { a##s_##0 = GL_A(0, kt_); a##s_##1 = GL_A(1, kt_); a##s_##2 = GL_A(2, kt_); a##s_##3 = GL_A(3, kt_); b##s_##0 = GL_B(0, kt_); b##s_##1 = GL_B(1, kt_); b##s_##2 = GL_B(2, kt_); b##s_##3 = GL_B(3, kt_); }
; #define LDS_STORE(s_, buf_) if (VAR != 2) { LDS_ST1(sA, 0, buf_, a##s_##0) LDS_ST1(sA, 1, buf_, a##s_##1) LDS_ST1(sA, 2, buf_, a##s_##2) LDS_ST1(sA, 3, buf_, a##s_##3) LDS_ST1(sB, 0, buf_, b##s_##0) LDS_ST1(sB, 1, buf_, b##s_##1) LDS_ST1(sB, 2, buf_, b##s_##2) LDS_ST1(sB, 3, buf_, b##s_##3) }
;     ...
;   GL_LOAD(0, 0)
;   GL_LOAD(1, 1)
;   LDS_STORE(0, 0)
;   if (VAR != 4) __syncthreads();
; #pragma unroll
;   for (int kt = 0; kt < nk; kt += 2) {
;     if (kt + 2 < nk) { GL_LOAD(0, kt + 2) }
;     MMA_TILE(0)
;     LDS_STORE(1, 1)
;     if (VAR != 4) __syncthreads();
;     if (kt + 3 < nk) { GL_LOAD(1, kt + 3) }
;     MMA_TILE(1)
;     if (kt + 2 < nk) { LDS_STORE(0, 0) }
;     if (VAR != 4) __syncthreads();
;   }
	v_mfma_f32_16x16x32_f16 v[52:55], v[194:197], v[144:147], v[54:57]
	ds_read_b128 v[162:165], v20 offset:32768
	ds_read_b128 v[144:147], v21
	s_waitcnt lgkmcnt(0)
	v_mfma_f32_16x16x32_f16 v[36:39], v[162:165], v[144:147], v[36:39]
	ds_read_b128 v[56:59], v20 offset:34816
	ds_read_b128 v[166:169], v21 offset:2048
	s_waitcnt lgkmcnt(0)
	v_mfma_f32_16x16x32_f16 v[116:119], v[162:165], v[166:169], v[116:119]
	ds_read_b128 v[194:197], v20 offset:36864
	v_mfma_f32_16x16x32_f16 v[44:47], v[56:59], v[144:147], v[44:47]
	ds_read_b128 v[206:209], v20 offset:38912
	v_mfma_f32_16x16x32_f16 v[128:131], v[56:59], v[166:169], v[128:131]
	s_waitcnt vmcnt(7)
	ds_write_b128 v16, v[104:107] offset:16384
	s_waitcnt lgkmcnt(2)
	v_mfma_f32_16x16x32_f16 v[132:135], v[194:197], v[144:147], v[132:135]
	s_waitcnt vmcnt(6)
	ds_write_b128 v17, v[140:143] offset:16384
	v_mfma_f32_16x16x32_f16 v[136:139], v[194:197], v[166:169], v[136:139]
	s_waitcnt vmcnt(5)
	ds_write_b128 v18, v[198:201] offset:16384
	s_waitcnt lgkmcnt(3)
	v_mfma_f32_16x16x32_f16 v[28:31], v[206:209], v[144:147], v[28:31]
	ds_read_b128 v[144:147], v21 offset:4096
	v_mfma_f32_16x16x32_f16 v[32:35], v[206:209], v[166:169], v[32:35]
	ds_read_b128 v[166:169], v21 offset:6144
	s_waitcnt lgkmcnt(1)
	v_mfma_f32_16x16x32_f16 v[154:157], v[162:165], v[144:147], v[154:157]
	s_waitcnt vmcnt(4)
	ds_write_b128 v19, v[202:205] offset:16384
	s_waitcnt lgkmcnt(1)
	v_mfma_f32_16x16x32_f16 v[48:51], v[162:165], v[166:169], v[48:51]
	ds_read_b128 v[162:165], v22
	v_mfma_f32_16x16x32_f16 v[158:161], v[56:59], v[144:147], v[158:161]
	s_waitcnt vmcnt(3)
	ds_write_b128 v16, v[124:127] offset:49152
	v_mfma_f32_16x16x32_f16 v[24:27], v[56:59], v[166:169], v[24:27]
	ds_read_b128 v[56:59], v23 offset:32768
	v_mfma_f32_16x16x32_f16 v[190:193], v[194:197], v[144:147], v[190:193]
	s_waitcnt vmcnt(2)
	ds_write_b128 v17, v[220:223] offset:49152
	v_mfma_f32_16x16x32_f16 v[40:43], v[194:197], v[166:169], v[40:43]
	ds_read_b128 v[194:197], v23 offset:36864
	v_mfma_f32_16x16x32_f16 v[120:123], v[206:209], v[144:147], v[120:123]
	ds_read_b128 v[144:147], v23 offset:34816
	v_mfma_f32_16x16x32_f16 v[52:55], v[206:209], v[166:169], v[52:55]
	ds_read_b128 v[166:169], v22 offset:2048
	s_waitcnt lgkmcnt(4)
	v_mfma_f32_16x16x32_f16 v[36:39], v[56:59], v[162:165], v[36:39]
	ds_read_b128 v[206:209], v23 offset:38912
	s_waitcnt lgkmcnt(1)
	v_mfma_f32_16x16x32_f16 v[116:119], v[56:59], v[166:169], v[116:119]
	s_waitcnt vmcnt(1)
	ds_write_b128 v18, v[224:227] offset:49152
	v_mfma_f32_16x16x32_f16 v[44:47], v[144:147], v[162:165], v[44:47]
	s_waitcnt vmcnt(0)
	ds_write_b128 v19, v[228:231] offset:49152
	v_mfma_f32_16x16x32_f16 v[128:131], v[144:147], v[166:169], v[128:131]
	v_mfma_f32_16x16x32_f16 v[132:135], v[194:197], v[162:165], v[132:135]
	v_mfma_f32_16x16x32_f16 v[136:139], v[194:197], v[166:169], v[136:139]
	s_waitcnt lgkmcnt(2)
	v_mfma_f32_16x16x32_f16 v[28:31], v[206:209], v[162:165], v[28:31]
	ds_read_b128 v[162:165], v22 offset:4096
	v_mfma_f32_16x16x32_f16 v[32:35], v[206:209], v[166:169], v[32:35]
	ds_read_b128 v[166:169], v22 offset:6144
	s_waitcnt lgkmcnt(1)
	v_mfma_f32_16x16x32_f16 v[154:157], v[56:59], v[162:165], v[154:157]
	s_waitcnt lgkmcnt(0)
	v_mfma_f32_16x16x32_f16 v[48:51], v[56:59], v[166:169], v[48:51]
	global_load_dwordx4 v[56:59], v[0:1], off offset:512
	v_mfma_f32_16x16x32_f16 v[158:161], v[144:147], v[162:165], v[158:161]
	v_mfma_f32_16x16x32_f16 v[24:27], v[144:147], v[166:169], v[24:27]
	v_mfma_f32_16x16x32_f16 v[190:193], v[194:197], v[162:165], v[190:193]
	v_mfma_f32_16x16x32_f16 v[40:43], v[194:197], v[166:169], v[40:43]
	v_mfma_f32_16x16x32_f16 v[120:123], v[206:209], v[162:165], v[120:123]
	global_load_dwordx4 v[162:165], v[2:3], off offset:512
	global_load_dwordx4 v[210:213], v[4:5], off offset:512
	global_load_dwordx4 v[232:235], v[6:7], off offset:512
	global_load_dwordx4 v[144:147], v[8:9], off offset:512
	global_load_dwordx4 v[236:239], v[10:11], off offset:512
	global_load_dwordx4 v[240:243], v[12:13], off offset:512
	global_load_dwordx4 v[244:247], v[14:15], off offset:512
	s_waitcnt lgkmcnt(0)
	s_barrier
	v_mfma_f32_16x16x32_f16 v[52:55], v[206:209], v[166:169], v[52:55]
	ds_read_b128 v[104:107], v20 offset:49152
	ds_read_b128 v[140:143], v21 offset:16384
	s_waitcnt lgkmcnt(0)
	v_mfma_f32_16x16x32_f16 v[36:39], v[104:107], v[140:143], v[36:39]
	ds_read_b128 v[124:127], v20 offset:51200
	ds_read_b128 v[166:169], v21 offset:18432
	s_waitcnt lgkmcnt(0)
	v_mfma_f32_16x16x32_f16 v[116:119], v[104:107], v[166:169], v[116:119]
	ds_read_b128 v[194:197], v20 offset:53248
	v_mfma_f32_16x16x32_f16 v[44:47], v[124:127], v[140:143], v[44:47]
	ds_read_b128 v[198:201], v20 offset:55296
	v_mfma_f32_16x16x32_f16 v[128:131], v[124:127], v[166:169], v[128:131]
	s_waitcnt vmcnt(7)
	ds_write_b128 v16, v[56:59]
	s_waitcnt lgkmcnt(2)
	v_mfma_f32_16x16x32_f16 v[132:135], v[194:197], v[140:143], v[132:135]
	s_waitcnt vmcnt(6)
	ds_write_b128 v17, v[162:165]
	v_mfma_f32_16x16x32_f16 v[136:139], v[194:197], v[166:169], v[136:139]
	s_waitcnt vmcnt(5)
	ds_write_b128 v18, v[210:213]
	s_waitcnt lgkmcnt(3)
	v_mfma_f32_16x16x32_f16 v[28:31], v[198:201], v[140:143], v[28:31]
	ds_read_b128 v[140:143], v21 offset:20480
	v_mfma_f32_16x16x32_f16 v[32:35], v[198:201], v[166:169], v[32:35]
	ds_read_b128 v[166:169], v21 offset:22528
	s_waitcnt lgkmcnt(1)
	v_mfma_f32_16x16x32_f16 v[154:157], v[104:107], v[140:143], v[154:157]
	s_waitcnt vmcnt(4)
	ds_write_b128 v19, v[232:235]
	s_waitcnt lgkmcnt(1)
	v_mfma_f32_16x16x32_f16 v[48:51], v[104:107], v[166:169], v[48:51]
	ds_read_b128 v[104:107], v23 offset:49152
	v_mfma_f32_16x16x32_f16 v[158:161], v[124:127], v[140:143], v[158:161]
	s_waitcnt vmcnt(3)
; #define GL_LOAD(s_, kt_) if (VAR != 1) { a##s_##0 = GL_A(0, kt_); a##s_##1 = GL_A(1, kt_); a##s_##2 = GL_A(2, kt_); a##s_##3 = GL_A(3, kt_); b##s_##0 = GL_B(0, kt_); b##s_##1 = GL_B(1, kt_); b##s_##2 = GL_B(2, kt_); b##s_##3 = GL_B(3, kt_); }
; #define LDS_STORE(s_, buf_) if (VAR != 2) { LDS_ST1(sA, 0, buf_, a##s_##0) LDS_ST1(sA, 1, buf_, a##s_##1) LDS_ST1(sA, 2, buf_, a##s_##2) LDS_ST1(sA, 3, buf_, a##s_##3) LDS_ST1(sB, 0, buf_, b##s_##0) LDS_ST1(sB, 1, buf_, b##s_##1) LDS_ST1(sB, 2, buf_, b##s_##2) LDS_ST1(sB, 3, buf_, b##s_##3) }
;     ...
;   GL_LOAD(0, 0)
;   GL_LOAD(1, 1)
;   LDS_STORE(0, 0)
;   if (VAR != 4) __syncthreads();
; #pragma unroll
;   for (int kt = 0; kt < nk; kt += 2) {
;     if (kt + 2 < nk) { GL_LOAD(0, kt + 2) }
;     MMA_TILE(0)
;     LDS_STORE(1, 1)
;     if (VAR != 4) __syncthreads();
;     if (kt + 3 < nk) { GL_LOAD(1, kt + 3) }
;     MMA_TILE(1)
;     if (kt + 2 < nk) { LDS_STORE(0, 0) }
;     if (VAR != 4) __syncthreads();
;   }
	ds_write_b128 v16, v[144:147] offset:32768
	v_mfma_f32_16x16x32_f16 v[24:27], v[124:127], v[166:169], v[24:27]
	ds_read_b128 v[124:127], v23 offset:51200
	v_mfma_f32_16x16x32_f16 v[190:193], v[194:197], v[140:143], v[190:193]
	s_waitcnt vmcnt(2)
	ds_write_b128 v17, v[236:239] offset:32768
	v_mfma_f32_16x16x32_f16 v[40:43], v[194:197], v[166:169], v[40:43]
	ds_read_b128 v[194:197], v23 offset:53248
	v_mfma_f32_16x16x32_f16 v[120:123], v[198:201], v[140:143], v[120:123]
	ds_read_b128 v[140:143], v22 offset:16384
	v_mfma_f32_16x16x32_f16 v[52:55], v[198:201], v[166:169], v[52:55]
	ds_read_b128 v[166:169], v22 offset:18432
	s_waitcnt lgkmcnt(1)
	v_mfma_f32_16x16x32_f16 v[36:39], v[104:107], v[140:143], v[36:39]
	ds_read_b128 v[198:201], v23 offset:55296
	s_waitcnt lgkmcnt(1)
	v_mfma_f32_16x16x32_f16 v[116:119], v[104:107], v[166:169], v[116:119]
	s_waitcnt vmcnt(1)
	ds_write_b128 v18, v[240:243] offset:32768
	v_mfma_f32_16x16x32_f16 v[44:47], v[124:127], v[140:143], v[44:47]
	s_waitcnt vmcnt(0)
	ds_write_b128 v19, v[244:247] offset:32768
	v_mfma_f32_16x16x32_f16 v[128:131], v[124:127], v[166:169], v[128:131]
	v_mfma_f32_16x16x32_f16 v[132:135], v[194:197], v[140:143], v[132:135]
	v_mfma_f32_16x16x32_f16 v[136:139], v[194:197], v[166:169], v[136:139]
	s_waitcnt lgkmcnt(2)
	v_mfma_f32_16x16x32_f16 v[28:31], v[198:201], v[140:143], v[28:31]
	ds_read_b128 v[140:143], v22 offset:20480
	v_mfma_f32_16x16x32_f16 v[32:35], v[198:201], v[166:169], v[32:35]
	ds_read_b128 v[166:169], v22 offset:22528
	s_waitcnt lgkmcnt(1)
	v_mfma_f32_16x16x32_f16 v[154:157], v[104:107], v[140:143], v[154:157]
	s_waitcnt lgkmcnt(0)
	v_mfma_f32_16x16x32_f16 v[48:51], v[104:107], v[166:169], v[48:51]
	global_load_dwordx4 v[104:107], v[0:1], off offset:640
	v_mfma_f32_16x16x32_f16 v[158:161], v[124:127], v[140:143], v[158:161]
	v_mfma_f32_16x16x32_f16 v[24:27], v[124:127], v[166:169], v[24:27]
	v_mfma_f32_16x16x32_f16 v[190:193], v[194:197], v[140:143], v[190:193]
	v_mfma_f32_16x16x32_f16 v[40:43], v[194:197], v[166:169], v[40:43]
	v_mfma_f32_16x16x32_f16 v[120:123], v[198:201], v[140:143], v[120:123]
	global_load_dwordx4 v[140:143], v[2:3], off offset:640
	global_load_dwordx4 v[202:205], v[4:5], off offset:640
	global_load_dwordx4 v[206:209], v[6:7], off offset:640
	global_load_dwordx4 v[124:127], v[8:9], off offset:640
	global_load_dwordx4 v[220:223], v[10:11], off offset:640
	global_load_dwordx4 v[224:227], v[12:13], off offset:640
	global_load_dwordx4 v[228:231], v[14:15], off offset:640
	s_waitcnt lgkmcnt(0)
	s_barrier
	v_mfma_f32_16x16x32_f16 v[52:55], v[198:201], v[166:169], v[52:55]
	ds_read_b128 v[56:59], v20 offset:32768
	ds_read_b128 v[162:165], v21
	s_waitcnt lgkmcnt(0)
	v_mfma_f32_16x16x32_f16 v[36:39], v[56:59], v[162:165], v[36:39]
	ds_read_b128 v[144:147], v20 offset:34816
	ds_read_b128 v[166:169], v21 offset:2048
	s_waitcnt lgkmcnt(0)
	v_mfma_f32_16x16x32_f16 v[116:119], v[56:59], v[166:169], v[116:119]
	ds_read_b128 v[194:197], v20 offset:36864
	v_mfma_f32_16x16x32_f16 v[44:47], v[144:147], v[162:165], v[44:47]
	ds_read_b128 v[198:201], v20 offset:38912
	v_mfma_f32_16x16x32_f16 v[128:131], v[144:147], v[166:169], v[128:131]
	s_waitcnt vmcnt(7)
	ds_write_b128 v16, v[104:107] offset:16384
	s_waitcnt lgkmcnt(2)
	v_mfma_f32_16x16x32_f16 v[132:135], v[194:197], v[162:165], v[132:135]
	s_waitcnt vmcnt(6)
	ds_write_b128 v17, v[140:143] offset:16384
	v_mfma_f32_16x16x32_f16 v[136:139], v[194:197], v[166:169], v[136:139]
	s_waitcnt vmcnt(5)
	ds_write_b128 v18, v[202:205] offset:16384
	s_waitcnt lgkmcnt(3)
	v_mfma_f32_16x16x32_f16 v[28:31], v[198:201], v[162:165], v[28:31]
	ds_read_b128 v[162:165], v21 offset:4096
	v_mfma_f32_16x16x32_f16 v[32:35], v[198:201], v[166:169], v[32:35]
	ds_read_b128 v[166:169], v21 offset:6144
	s_waitcnt lgkmcnt(1)
	v_mfma_f32_16x16x32_f16 v[154:157], v[56:59], v[162:165], v[154:157]
	s_waitcnt vmcnt(4)
	ds_write_b128 v19, v[206:209] offset:16384
	s_waitcnt lgkmcnt(1)
	v_mfma_f32_16x16x32_f16 v[48:51], v[56:59], v[166:169], v[48:51]
	ds_read_b128 v[56:59], v23 offset:32768
	v_mfma_f32_16x16x32_f16 v[158:161], v[144:147], v[162:165], v[158:161]
	s_waitcnt vmcnt(3)
	ds_write_b128 v16, v[124:127] offset:49152
	v_mfma_f32_16x16x32_f16 v[24:27], v[144:147], v[166:169], v[24:27]
	ds_read_b128 v[144:147], v23 offset:34816
	v_mfma_f32_16x16x32_f16 v[190:193], v[194:197], v[162:165], v[190:193]
	s_waitcnt vmcnt(2)
	ds_write_b128 v17, v[220:223] offset:49152
	v_mfma_f32_16x16x32_f16 v[40:43], v[194:197], v[166:169], v[40:43]
	ds_read_b128 v[194:197], v23 offset:36864
	v_mfma_f32_16x16x32_f16 v[120:123], v[198:201], v[162:165], v[120:123]
	ds_read_b128 v[162:165], v22
	v_mfma_f32_16x16x32_f16 v[52:55], v[198:201], v[166:169], v[52:55]
	ds_read_b128 v[166:169], v22 offset:2048
	s_waitcnt lgkmcnt(1)
	v_mfma_f32_16x16x32_f16 v[36:39], v[56:59], v[162:165], v[36:39]
	ds_read_b128 v[198:201], v23 offset:38912
	s_waitcnt lgkmcnt(1)
	v_mfma_f32_16x16x32_f16 v[116:119], v[56:59], v[166:169], v[116:119]
	s_waitcnt vmcnt(1)
	ds_write_b128 v18, v[224:227] offset:49152
	v_mfma_f32_16x16x32_f16 v[44:47], v[144:147], v[162:165], v[44:47]
	s_waitcnt vmcnt(0)
	ds_write_b128 v19, v[228:231] offset:49152
	v_mfma_f32_16x16x32_f16 v[128:131], v[144:147], v[166:169], v[128:131]
	v_mfma_f32_16x16x32_f16 v[132:135], v[194:197], v[162:165], v[132:135]
	v_mfma_f32_16x16x32_f16 v[136:139], v[194:197], v[166:169], v[136:139]
	s_waitcnt lgkmcnt(2)
	v_mfma_f32_16x16x32_f16 v[28:31], v[198:201], v[162:165], v[28:31]
	ds_read_b128 v[162:165], v22 offset:4096
	v_mfma_f32_16x16x32_f16 v[32:35], v[198:201], v[166:169], v[32:35]
	ds_read_b128 v[166:169], v22 offset:6144
	s_waitcnt lgkmcnt(1)
	v_mfma_f32_16x16x32_f16 v[154:157], v[56:59], v[162:165], v[154:157]
	s_waitcnt lgkmcnt(0)
	v_mfma_f32_16x16x32_f16 v[48:51], v[56:59], v[166:169], v[48:51]
	global_load_dwordx4 v[56:59], v[0:1], off offset:768
	v_mfma_f32_16x16x32_f16 v[158:161], v[144:147], v[162:165], v[158:161]
	v_mfma_f32_16x16x32_f16 v[24:27], v[144:147], v[166:169], v[24:27]
	v_mfma_f32_16x16x32_f16 v[190:193], v[194:197], v[162:165], v[190:193]
	v_mfma_f32_16x16x32_f16 v[40:43], v[194:197], v[166:169], v[40:43]
	v_mfma_f32_16x16x32_f16 v[120:123], v[198:201], v[162:165], v[120:123]
	global_load_dwordx4 v[162:165], v[2:3], off offset:768
	global_load_dwordx4 v[210:213], v[4:5], off offset:768
	global_load_dwordx4 v[232:235], v[6:7], off offset:768
	global_load_dwordx4 v[144:147], v[8:9], off offset:768
	global_load_dwordx4 v[236:239], v[10:11], off offset:768
	global_load_dwordx4 v[240:243], v[12:13], off offset:768
	global_load_dwordx4 v[244:247], v[14:15], off offset:768
	s_waitcnt lgkmcnt(0)
	s_barrier
; #define GL_LOAD(s_, kt_) if (VAR != 1) { a##s_##0 = GL_A(0, kt_); a##s_##1 = GL_A(1, kt_); a##s_##2 = GL_A(2, kt_); a##s_##3 = GL_A(3, kt_); b##s_##0 = GL_B(0, kt_); b##s_##1 = GL_B(1, kt_); b##s_##2 = GL_B(2, kt_); b##s_##3 = GL_B(3, kt_); }
; #define LDS_STORE(s_, buf_) if (VAR != 2) { LDS_ST1(sA, 0, buf_, a##s_##0) LDS_ST1(sA, 1, buf_, a##s_##1) LDS_ST1(sA, 2, buf_, a##s_##2) LDS_ST1(sA, 3, buf_, a##s_##3) LDS_ST1(sB, 0, buf_, b##s_##0) LDS_ST1(sB, 1, buf_, b##s_##1) LDS_ST1(sB, 2, buf_, b##s_##2) LDS_ST1(sB, 3, buf_, b##s_##3) }
;     ...
;   GL_LOAD(0, 0)
;   GL_LOAD(1, 1)
;   LDS_STORE(0, 0)
;   if (VAR != 4) __syncthreads();
; #pragma unroll
;   for (int kt = 0; kt < nk; kt += 2) {
;     if (kt + 2 < nk) { GL_LOAD(0, kt + 2) }
;     MMA_TILE(0)
;     LDS_STORE(1, 1)
;     if (VAR != 4) __syncthreads();
;     if (kt + 3 < nk) { GL_LOAD(1, kt + 3) }
;     MMA_TILE(1)
;     if (kt + 2 < nk) { LDS_STORE(0, 0) }
;     if (VAR != 4) __syncthreads();
;   }
	v_mfma_f32_16x16x32_f16 v[52:55], v[198:201], v[166:169], v[52:55]
	ds_read_b128 v[104:107], v20 offset:49152
	ds_read_b128 v[140:143], v21 offset:16384
	s_waitcnt lgkmcnt(0)
	v_mfma_f32_16x16x32_f16 v[36:39], v[104:107], v[140:143], v[36:39]
	ds_read_b128 v[124:127], v20 offset:51200
	ds_read_b128 v[166:169], v21 offset:18432
	s_waitcnt lgkmcnt(0)
	v_mfma_f32_16x16x32_f16 v[116:119], v[104:107], v[166:169], v[116:119]
	ds_read_b128 v[194:197], v20 offset:53248
	v_mfma_f32_16x16x32_f16 v[44:47], v[124:127], v[140:143], v[44:47]
	ds_read_b128 v[198:201], v20 offset:55296
	v_mfma_f32_16x16x32_f16 v[128:131], v[124:127], v[166:169], v[128:131]
	s_waitcnt vmcnt(7)
	ds_write_b128 v16, v[56:59]
	s_waitcnt lgkmcnt(2)
	v_mfma_f32_16x16x32_f16 v[132:135], v[194:197], v[140:143], v[132:135]
	s_waitcnt vmcnt(6)
	ds_write_b128 v17, v[162:165]
	v_mfma_f32_16x16x32_f16 v[136:139], v[194:197], v[166:169], v[136:139]
	s_waitcnt vmcnt(5)
	ds_write_b128 v18, v[210:213]
	s_waitcnt lgkmcnt(3)
	v_mfma_f32_16x16x32_f16 v[28:31], v[198:201], v[140:143], v[28:31]
	ds_read_b128 v[140:143], v21 offset:20480
	v_mfma_f32_16x16x32_f16 v[32:35], v[198:201], v[166:169], v[32:35]
	ds_read_b128 v[166:169], v21 offset:22528
	s_waitcnt lgkmcnt(1)
	v_mfma_f32_16x16x32_f16 v[154:157], v[104:107], v[140:143], v[154:157]
	s_waitcnt vmcnt(4)
	ds_write_b128 v19, v[232:235]
	s_waitcnt lgkmcnt(1)
	v_mfma_f32_16x16x32_f16 v[48:51], v[104:107], v[166:169], v[48:51]
	ds_read_b128 v[104:107], v23 offset:49152
	v_mfma_f32_16x16x32_f16 v[158:161], v[124:127], v[140:143], v[158:161]
	s_waitcnt vmcnt(3)
	ds_write_b128 v16, v[144:147] offset:32768
	v_mfma_f32_16x16x32_f16 v[24:27], v[124:127], v[166:169], v[24:27]
	ds_read_b128 v[124:127], v23 offset:51200
	v_mfma_f32_16x16x32_f16 v[190:193], v[194:197], v[140:143], v[190:193]
	s_waitcnt vmcnt(2)
	ds_write_b128 v17, v[236:239] offset:32768
	v_mfma_f32_16x16x32_f16 v[40:43], v[194:197], v[166:169], v[40:43]
	ds_read_b128 v[194:197], v23 offset:53248
	v_mfma_f32_16x16x32_f16 v[120:123], v[198:201], v[140:143], v[120:123]
	ds_read_b128 v[140:143], v22 offset:16384
	v_mfma_f32_16x16x32_f16 v[52:55], v[198:201], v[166:169], v[52:55]
	ds_read_b128 v[166:169], v22 offset:18432
	s_waitcnt lgkmcnt(1)
	v_mfma_f32_16x16x32_f16 v[36:39], v[104:107], v[140:143], v[36:39]
	ds_read_b128 v[198:201], v23 offset:55296
	s_waitcnt lgkmcnt(1)
	v_mfma_f32_16x16x32_f16 v[116:119], v[104:107], v[166:169], v[116:119]
	s_waitcnt vmcnt(1)
	ds_write_b128 v18, v[240:243] offset:32768
	v_mfma_f32_16x16x32_f16 v[44:47], v[124:127], v[140:143], v[44:47]
	s_waitcnt vmcnt(0)
	ds_write_b128 v19, v[244:247] offset:32768
	v_mfma_f32_16x16x32_f16 v[128:131], v[124:127], v[166:169], v[128:131]
	v_mfma_f32_16x16x32_f16 v[132:135], v[194:197], v[140:143], v[132:135]
	v_mfma_f32_16x16x32_f16 v[136:139], v[194:197], v[166:169], v[136:139]
	s_waitcnt lgkmcnt(2)
	v_mfma_f32_16x16x32_f16 v[28:31], v[198:201], v[140:143], v[28:31]
	ds_read_b128 v[140:143], v22 offset:20480
	v_mfma_f32_16x16x32_f16 v[32:35], v[198:201], v[166:169], v[32:35]
	ds_read_b128 v[166:169], v22 offset:22528
	s_waitcnt lgkmcnt(1)
	v_mfma_f32_16x16x32_f16 v[154:157], v[104:107], v[140:143], v[154:157]
	s_waitcnt lgkmcnt(0)
	v_mfma_f32_16x16x32_f16 v[48:51], v[104:107], v[166:169], v[48:51]
	global_load_dwordx4 v[104:107], v[0:1], off offset:896
	global_load_dwordx4 v[0:3], v[2:3], off offset:896
	v_mfma_f32_16x16x32_f16 v[158:161], v[124:127], v[140:143], v[158:161]
	v_mfma_f32_16x16x32_f16 v[24:27], v[124:127], v[166:169], v[24:27]
	v_mfma_f32_16x16x32_f16 v[190:193], v[194:197], v[140:143], v[190:193]
	v_mfma_f32_16x16x32_f16 v[40:43], v[194:197], v[166:169], v[40:43]
	v_mfma_f32_16x16x32_f16 v[120:123], v[198:201], v[140:143], v[120:123]
	global_load_dwordx4 v[140:143], v[4:5], off offset:896
	global_load_dwordx4 v[4:7], v[6:7], off offset:896
	global_load_dwordx4 v[124:127], v[8:9], off offset:896
	global_load_dwordx4 v[8:11], v[10:11], off offset:896
	global_load_dwordx4 v[202:205], v[12:13], off offset:896
	global_load_dwordx4 v[12:15], v[14:15], off offset:896
	s_waitcnt lgkmcnt(0)
	s_barrier
	ds_read_b128 v[56:59], v20 offset:32768
	v_mfma_f32_16x16x32_f16 v[52:55], v[198:201], v[166:169], v[52:55]
	ds_read_b128 v[144:147], v20 offset:34816
	ds_read_b128 v[162:165], v21
	ds_read_b128 v[166:169], v21 offset:2048
	ds_read_b128 v[194:197], v20 offset:36864
	ds_read_b128 v[198:201], v20 offset:38912
	s_waitcnt lgkmcnt(3)
	v_mfma_f32_16x16x32_f16 v[36:39], v[56:59], v[162:165], v[36:39]
	v_mfma_f32_16x16x32_f16 v[44:47], v[144:147], v[162:165], v[44:47]
	s_waitcnt lgkmcnt(1)
	v_mfma_f32_16x16x32_f16 v[132:135], v[194:197], v[162:165], v[132:135]
	s_waitcnt lgkmcnt(0)
	v_mfma_f32_16x16x32_f16 v[28:31], v[198:201], v[162:165], v[28:31]
	v_mfma_f32_16x16x32_f16 v[116:119], v[56:59], v[166:169], v[116:119]
	v_mfma_f32_16x16x32_f16 v[128:131], v[144:147], v[166:169], v[128:131]
	v_mfma_f32_16x16x32_f16 v[136:139], v[194:197], v[166:169], v[136:139]
	v_mfma_f32_16x16x32_f16 v[32:35], v[198:201], v[166:169], v[32:35]
	ds_read_b128 v[162:165], v21 offset:4096
	ds_read_b128 v[166:169], v21 offset:6144
	s_waitcnt lgkmcnt(1)
	v_mfma_f32_16x16x32_f16 v[154:157], v[56:59], v[162:165], v[154:157]
	v_mfma_f32_16x16x32_f16 v[158:161], v[144:147], v[162:165], v[158:161]
	v_mfma_f32_16x16x32_f16 v[190:193], v[194:197], v[162:165], v[190:193]
	v_mfma_f32_16x16x32_f16 v[120:123], v[198:201], v[162:165], v[120:123]
	s_waitcnt lgkmcnt(0)
; DI unsigned pack2(float lo, float hi) { f2_t v = {lo, hi}; h2_t b = __builtin_convertvector(v, h2_t); return __builtin_bit_cast(unsigned, b); }
; DI float lo_f(unsigned u) { return (float)(__builtin_bit_cast(h2_t, u)[0]); }
; DI float hi_f(unsigned u) { return (float)(__builtin_bit_cast(h2_t, u)[1]); }
; #define GL_LOAD(s_, kt_) if (VAR != 1) { a##s_##0 = GL_A(0, kt_); a##s_##1 = GL_A(1, kt_); a##s_##2 = GL_A(2, kt_); a##s_##3 = GL_A(3, kt_); b##s_##0 = GL_B(0, kt_); b##s_##1 = GL_B(1, kt_); b##s_##2 = GL_B(2, kt_); b##s_##3 = GL_B(3, kt_); }
; #define LDS_STORE(s_, buf_) if (VAR != 2) { LDS_ST1(sA, 0, buf_, a##s_##0) LDS_ST1(sA, 1, buf_, a##s_##1) LDS_ST1(sA, 2, buf_, a##s_##2) LDS_ST1(sA, 3, buf_, a##s_##3) LDS_ST1(sB, 0, buf_, b##s_##0) LDS_ST1(sB, 1, buf_, b##s_##1) LDS_ST1(sB, 2, buf_, b##s_##2) LDS_ST1(sB, 3, buf_, b##s_##3) }
;     ...
;   for (int kt = 0; kt < nk; kt += 2) {
;     if (kt + 2 < nk) { GL_LOAD(0, kt + 2) }
;     MMA_TILE(0)
;     LDS_STORE(1, 1)
;     if (VAR != 4) __syncthreads();
;     if (kt + 3 < nk) { GL_LOAD(1, kt + 3) }
;     MMA_TILE(1)
;     if (kt + 2 < nk) { LDS_STORE(0, 0) }
;     if (VAR != 4) __syncthreads();
;   }
; DI void phase_merge(const Params& P, int l, char* smem) {
;     ...
; #pragma unroll
;       for (int mt = 0; mt < 4; ++mt) {
;         const int row = row0 + mt * 16 + lr;
; #pragma unroll
;         for (int nt = 0; nt < 4; ++nt) {
;           const uint2 gu = *(const uint2*)(Pb + (size_t)row * PW + C_GL + br * 1024 + col0 + nt * 16 + 4 * g);
;           float t0 = lo_f(gu.x) * acc[mt][nt][0], t1 = hi_f(gu.x) * acc[mt][nt][1], t2 = lo_f(gu.y) * acc[mt][nt][2], t3 = hi_f(gu.y) * acc[mt][nt][3];
;           if (br > 0) { t0 += lo_f(tot[mt][nt][0]); t1 += hi_f(tot[mt][nt][0]); t2 += lo_f(tot[mt][nt][1]); t3 += hi_f(tot[mt][nt][1]); }
;           tot[mt][nt][0] = pack2(t0, t1); tot[mt][nt][1] = pack2(t2, t3);
;         }
;       }
;     }
	v_mfma_f32_16x16x32_f16 v[48:51], v[56:59], v[166:169], v[48:51]
	ds_read_b128 v[56:59], v23 offset:32768
	v_mfma_f32_16x16x32_f16 v[24:27], v[144:147], v[166:169], v[24:27]
	v_mfma_f32_16x16x32_f16 v[40:43], v[194:197], v[166:169], v[40:43]
	v_mfma_f32_16x16x32_f16 v[52:55], v[198:201], v[166:169], v[52:55]
	ds_read_b128 v[144:147], v23 offset:34816
	ds_read_b128 v[162:165], v22
	ds_read_b128 v[166:169], v22 offset:2048
	ds_read_b128 v[194:197], v23 offset:36864
	ds_read_b128 v[198:201], v23 offset:38912
	s_waitcnt lgkmcnt(3)
	v_mfma_f32_16x16x32_f16 v[36:39], v[56:59], v[162:165], v[36:39]
	v_mfma_f32_16x16x32_f16 v[44:47], v[144:147], v[162:165], v[44:47]
	s_waitcnt lgkmcnt(1)
	v_mfma_f32_16x16x32_f16 v[132:135], v[194:197], v[162:165], v[132:135]
	s_waitcnt lgkmcnt(0)
	v_mfma_f32_16x16x32_f16 v[28:31], v[198:201], v[162:165], v[28:31]
	v_mfma_f32_16x16x32_f16 v[116:119], v[56:59], v[166:169], v[116:119]
	v_mfma_f32_16x16x32_f16 v[128:131], v[144:147], v[166:169], v[128:131]
	v_mfma_f32_16x16x32_f16 v[136:139], v[194:197], v[166:169], v[136:139]
	v_mfma_f32_16x16x32_f16 v[32:35], v[198:201], v[166:169], v[32:35]
	ds_read_b128 v[162:165], v22 offset:4096
	ds_read_b128 v[166:169], v22 offset:6144
	s_waitcnt vmcnt(7)
	ds_write_b128 v16, v[104:107] offset:16384
	s_waitcnt vmcnt(6)
	ds_write_b128 v17, v[0:3] offset:16384
	s_waitcnt vmcnt(5)
	ds_write_b128 v18, v[140:143] offset:16384
	s_waitcnt vmcnt(4)
	ds_write_b128 v19, v[4:7] offset:16384
	s_waitcnt vmcnt(3)
	ds_write_b128 v16, v[124:127] offset:49152
	s_waitcnt vmcnt(2)
	ds_write_b128 v17, v[8:11] offset:49152
	s_waitcnt vmcnt(1)
	ds_write_b128 v18, v[202:205] offset:49152
	s_waitcnt vmcnt(0)
	ds_write_b128 v19, v[12:15] offset:49152
	s_waitcnt lgkmcnt(0)
	v_mfma_f32_16x16x32_f16 v[154:157], v[56:59], v[162:165], v[154:157]
	s_barrier
	ds_read_b128 v[0:3], v20 offset:49152
	v_mfma_f32_16x16x32_f16 v[48:51], v[56:59], v[166:169], v[48:51]
	ds_read_b128 v[8:11], v20 offset:51200
	ds_read_b128 v[12:15], v21 offset:16384
	ds_read_b128 v[16:19], v21 offset:18432
	ds_read_b128 v[56:59], v20 offset:55296
	v_mfma_f32_16x16x32_f16 v[4:7], v[198:201], v[166:169], v[52:55]
	s_nop 2
	ds_read_b128 v[52:55], v20 offset:53248
	s_waitcnt lgkmcnt(3)
	v_mfma_f32_16x16x32_f16 v[36:39], v[0:3], v[12:15], v[36:39]
	v_mfma_f32_16x16x32_f16 v[44:47], v[8:11], v[12:15], v[44:47]
	s_waitcnt lgkmcnt(0)
	v_mfma_f32_16x16x32_f16 v[104:107], v[52:55], v[12:15], v[132:135]
	v_mfma_f32_16x16x32_f16 v[12:15], v[56:59], v[12:15], v[28:31]
	v_mfma_f32_16x16x32_f16 v[28:31], v[0:3], v[16:19], v[116:119]
	v_mfma_f32_16x16x32_f16 v[116:119], v[8:11], v[16:19], v[128:131]
	v_mfma_f32_16x16x32_f16 v[124:127], v[52:55], v[16:19], v[136:139]
	v_mfma_f32_16x16x32_f16 v[16:19], v[56:59], v[16:19], v[32:35]
	s_nop 2
	ds_read_b128 v[32:35], v21 offset:20480
	ds_read_b128 v[128:131], v21 offset:22528
	v_mfma_f32_16x16x32_f16 v[158:161], v[144:147], v[162:165], v[158:161]
	v_mfma_f32_16x16x32_f16 v[190:193], v[194:197], v[162:165], v[190:193]
	v_mfma_f32_16x16x32_f16 v[120:123], v[198:201], v[162:165], v[120:123]
	v_mfma_f32_16x16x32_f16 v[24:27], v[144:147], v[166:169], v[24:27]
	v_mfma_f32_16x16x32_f16 v[40:43], v[194:197], v[166:169], v[40:43]
	s_waitcnt lgkmcnt(1)
	v_mfma_f32_16x16x32_f16 v[132:135], v[0:3], v[32:35], v[154:157]
	v_mfma_f32_16x16x32_f16 v[136:139], v[8:11], v[32:35], v[158:161]
	s_nop 1
	ds_read_b128 v[154:157], v23 offset:49152
	v_mfma_f32_16x16x32_f16 v[140:143], v[52:55], v[32:35], v[190:193]
	v_mfma_f32_16x16x32_f16 v[120:123], v[56:59], v[32:35], v[120:123]
	s_waitcnt lgkmcnt(1)
	v_mfma_f32_16x16x32_f16 v[0:3], v[0:3], v[128:131], v[48:51]
	v_mfma_f32_16x16x32_f16 v[8:11], v[8:11], v[128:131], v[24:27]
	v_mfma_f32_16x16x32_f16 v[144:147], v[52:55], v[128:131], v[40:43]
	v_mfma_f32_16x16x32_f16 v[128:131], v[56:59], v[128:131], v[4:7]
	s_nop 2
	ds_read_b128 v[4:7], v23 offset:51200
	ds_read_b128 v[24:27], v22 offset:16384
	ds_read_b128 v[32:35], v22 offset:18432
	ds_read_b128 v[162:165], v23 offset:53248
	ds_read_b128 v[166:169], v23 offset:55296
	s_waitcnt lgkmcnt(0)
	v_mfma_f32_16x16x32_f16 v[48:51], v[166:169], v[24:27], v[12:15]
	v_mfma_f32_16x16x32_f16 v[40:43], v[4:7], v[32:35], v[116:119]
	s_nop 1
	ds_read_b128 v[12:15], v22 offset:20480
	ds_read_b128 v[116:119], v22 offset:22528
	s_waitcnt lgkmcnt(0)
	s_barrier
	s_setprio 0
	v_mfma_f32_16x16x32_f16 v[158:161], v[154:157], v[24:27], v[36:39]
	v_mfma_f32_16x16x32_f16 v[56:59], v[4:7], v[24:27], v[44:47]
	v_mfma_f32_16x16x32_f16 v[52:55], v[162:165], v[24:27], v[104:107]
	v_mfma_f32_16x16x32_f16 v[44:47], v[154:157], v[32:35], v[28:31]
	v_mfma_f32_16x16x32_f16 v[36:39], v[162:165], v[32:35], v[124:127]
	v_mfma_f32_16x16x32_f16 v[32:35], v[166:169], v[32:35], v[16:19]
	v_mfma_f32_16x16x32_f16 v[28:31], v[154:157], v[12:15], v[132:135]
	v_mfma_f32_16x16x32_f16 v[24:27], v[4:7], v[12:15], v[136:139]
	v_mfma_f32_16x16x32_f16 v[20:23], v[162:165], v[12:15], v[140:143]
	v_mfma_f32_16x16x32_f16 v[16:19], v[166:169], v[12:15], v[120:123]
	v_mfma_f32_16x16x32_f16 v[12:15], v[154:157], v[116:119], v[0:3]
	s_nop 2
	global_load_dwordx2 v[154:155], v[108:109], off offset:-64
	global_load_dwordx2 v[156:157], v[108:109], off offset:-32
	global_load_dwordx2 v[120:121], v[108:109], off
	global_load_dwordx2 v[122:123], v[108:109], off offset:32
	v_lshl_add_u64 v[124:125], v[82:83], 0, s[4:5]
	global_load_dwordx2 v[124:125], v[124:125], off offset:-64
	v_lshl_add_u64 v[126:127], v[82:83], 0, s[4:5]
	global_load_dwordx2 v[126:127], v[126:127], off offset:-32
	v_mfma_f32_16x16x32_f16 v[8:11], v[4:7], v[116:119], v[8:11]
	s_waitcnt vmcnt(5)
	v_cvt_f32_f16_e32 v2, v154
	v_cvt_f32_f16_sdwa v3, v154 dst_sel:DWORD dst_unused:UNUSED_PAD src0_sel:WORD_1
	v_cvt_f32_f16_e32 v0, v155
	v_cvt_f32_f16_sdwa v1, v155 dst_sel:DWORD dst_unused:UNUSED_PAD src0_sel:WORD_1
	v_lshl_add_u64 v[154:155], v[82:83], 0, s[4:5]
	global_load_dwordx2 v[154:155], v[154:155], off
	v_mfma_f32_16x16x32_f16 v[4:7], v[162:165], v[116:119], v[144:147]
	v_mul_f32_e64 v104, v158, v2
	v_mul_f32_e64 v105, v159, v3
	v_pk_mul_f32 v[106:107], v[160:161], v[0:1]
	v_mfma_f32_16x16x32_f16 v[0:3], v[166:169], v[116:119], v[128:131]
	s_cbranch_vccnz .LBB0_1163
	v_cvt_f32_f16_sdwa v117, v102 dst_sel:DWORD dst_unused:UNUSED_PAD src0_sel:WORD_1
	v_cvt_f32_f16_e32 v116, v102
	v_pk_add_f32 v[104:105], v[104:105], v[116:117]
	v_cvt_f32_f16_sdwa v117, v103 dst_sel:DWORD dst_unused:UNUSED_PAD src0_sel:WORD_1
	v_cvt_f32_f16_e32 v116, v103
	v_pk_add_f32 v[106:107], v[106:107], v[116:117]

; DI int TIDX() { int t = threadIdx.x; asm volatile("" : "+v"(t)); return t; }
; DI int BIDX() { int b = blockIdx.x; asm volatile("" : "+s"(b)); return b; }
; #define GL_LOAD(s_, kt_) if (VAR != 1) { a##s_##0 = GL_A(0, kt_); a##s_##1 = GL_A(1, kt_); a##s_##2 = GL_A(2, kt_); a##s_##3 = GL_A(3, kt_); b##s_##0 = GL_B(0, kt_); b##s_##1 = GL_B(1, kt_); b##s_##2 = GL_B(2, kt_); b##s_##3 = GL_B(3, kt_); }
; #define LDS_STORE(s_, buf_) if (VAR != 2) { LDS_ST1(sA, 0, buf_, a##s_##0) LDS_ST1(sA, 1, buf_, a##s_##1) LDS_ST1(sA, 2, buf_, a##s_##2) LDS_ST1(sA, 3, buf_, a##s_##3) LDS_ST1(sB, 0, buf_, b##s_##0) LDS_ST1(sB, 1, buf_, b##s_##1) LDS_ST1(sB, 2, buf_, b##s_##2) LDS_ST1(sB, 3, buf_, b##s_##3) }
; DI int tile_groups(int MT, int NT) { return (MT >> 6) * ((NT + 7) >> 3) * 512; }
;   const int tid = TIDX(), lane = tid & 63, wid = tid >> 6, wm = wid >> 1, wn = wid & 1, lr = lane & 15, g = lane >> 4;
;   char* sA = smem; char* sB = smem + 2 * LTILE;
;   uint4 a00 = {}, a01 = {}, a02 = {}, a03 = {}, b00 = {}, b01 = {}, b02 = {}, b03 = {}, a10 = {}, a11 = {}, a12 = {}, a13 = {}, b10 = {}, b11 = {}, b12 = {}, b13 = {};
;   constexpr int nk = NK;
;   const int sw0 = (g ^ ((lr >> 1) & 7)) << 4, sw1 = sw0 ^ 64;
;   const int r0 = tid >> 3, kc = tid & 7, kcs = kc ^ ((r0 >> 1) & 7);
;     ...
;   GL_LOAD(0, 0)
;   GL_LOAD(1, 1)
;   LDS_STORE(0, 0)
;   if (VAR != 4) __syncthreads();
; DI void phase_resgemm(const Params& P, const bf16_t* A, int K, const bf16_t* Wt, float* ssq_out, const float* xsrc, char* smem) {
;     ...
;   for (int vb = BIDX(); vb < tile_groups(128, 8); vb += gridDim.x) {
;     int tm, tn; if (!tile_of(vb, 128, 8, tm, tn)) continue;
;     const int m0 = tm * 128, n0 = tn * 128;
;     f32x4 acc[4][4]; zero_acc(acc);
;     if (K == 1024) gemm_kloop<false, true, 16>(acc, A + (size_t)m0 * K, K, Wt + (size_t)n0 * K, K, smem);
.LBB0_1249:
	s_ashr_i32 s6, s1, 3
	s_andn2_b32 s6, s6, 63
	s_and_b32 s7, s10, 56
	s_or_b32 s6, s6, s7
	s_bfe_u32 s7, s1, 0x30003
	s_or_b32 s6, s6, s7
	s_cmpk_gt_i32 s6, 0x7f
	s_cbranch_scc1 .LBB0_1248
	s_lshl_b32 s6, s6, 7
	s_ashr_i32 s7, s6, 31
	v_mov_b32_e32 v20, v148
	s_and_b32 s11, s9, 0x380
	s_lshl_b64 s[12:13], s[6:7], 11
	v_readlane_b32 s14, v253, 19
	v_readlane_b32 s15, v253, 20
	v_ashrrev_i32_e32 v16, 3, v20
	s_add_u32 s12, s14, s12
	v_ashrrev_i32_e32 v17, 31, v16
	v_add_u32_e32 v18, 32, v16
	s_addc_u32 s13, s15, s13
	v_lshlrev_b64 v[8:9], 11, v[16:17]
	v_lshlrev_b32_e32 v17, 4, v20
	v_ashrrev_i32_e32 v19, 31, v18
	v_add_u32_e32 v54, 64, v16
	s_waitcnt lgkmcnt(0)
	v_lshl_add_u64 v[0:1], s[12:13], 0, v[8:9]
	v_and_b32_e32 v150, 0x70, v17
	v_lshlrev_b64 v[10:11], 11, v[18:19]
	v_ashrrev_i32_e32 v55, 31, v54
	v_add_u32_e32 v58, 0x60, v16
	s_lshl_b32 s7, s11, 11
	v_lshl_add_u64 v[0:1], v[0:1], 0, v[150:151]
	v_lshl_add_u64 v[2:3], s[12:13], 0, v[10:11]
	v_lshlrev_b64 v[12:13], 11, v[54:55]
	v_ashrrev_i32_e32 v59, 31, v58
	s_add_u32 s14, s2, s7
	global_load_dwordx4 v[22:25], v[0:1], off
	v_lshl_add_u64 v[2:3], v[2:3], 0, v[150:151]
	v_lshl_add_u64 v[4:5], s[12:13], 0, v[12:13]
	v_lshlrev_b64 v[14:15], 11, v[58:59]
	s_addc_u32 s15, s8, 0
	global_load_dwordx4 v[26:29], v[2:3], off
	v_lshl_add_u64 v[4:5], v[4:5], 0, v[150:151]
	v_lshl_add_u64 v[6:7], s[12:13], 0, v[14:15]
	global_load_dwordx4 v[30:33], v[4:5], off
	v_lshl_add_u64 v[6:7], v[6:7], 0, v[150:151]
	v_lshl_add_u64 v[8:9], s[14:15], 0, v[8:9]
	global_load_dwordx4 v[34:37], v[6:7], off
	v_lshl_add_u64 v[8:9], v[8:9], 0, v[150:151]
	v_lshl_add_u64 v[10:11], s[14:15], 0, v[10:11]
	global_load_dwordx4 v[38:41], v[8:9], off
	v_lshl_add_u64 v[10:11], v[10:11], 0, v[150:151]
	v_lshl_add_u64 v[12:13], s[14:15], 0, v[12:13]
	global_load_dwordx4 v[42:45], v[10:11], off
	v_lshl_add_u64 v[12:13], v[12:13], 0, v[150:151]
	v_lshl_add_u64 v[14:15], s[14:15], 0, v[14:15]
	global_load_dwordx4 v[46:49], v[12:13], off
	v_lshl_add_u64 v[14:15], v[14:15], 0, v[150:151]
	global_load_dwordx4 v[50:53], v[14:15], off
	v_lshlrev_b32_e32 v21, 3, v20
	v_and_b32_e32 v55, 48, v20
	v_and_b32_e32 v19, 15, v20
	v_lshrrev_b32_e32 v59, 1, v20
	s_waitcnt vmcnt(10)
	v_lshlrev_b32_e32 v60, 7, v20
	v_and_b32_e32 v90, 0x70, v21
	v_bitop3_b32 v134, v21, v55, s23 bitop3:0x6c
	v_bitop3_b32 v21, v17, s23, v20 bitop3:0x48
	v_and_or_b32 v91, v59, s24, v19
	v_and_b32_e32 v130, 0x2780, v60
	v_lshl_or_b32 v20, v18, 7, v21
	v_lshl_or_b32 v18, v58, 7, v21
	global_load_dwordx4 v[58:61], v[0:1], off offset:128
	global_load_dwordx4 v[62:65], v[2:3], off offset:128
	global_load_dwordx4 v[66:69], v[4:5], off offset:128
	global_load_dwordx4 v[70:73], v[6:7], off offset:128
	global_load_dwordx4 v[74:77], v[8:9], off offset:128
	global_load_dwordx4 v[78:81], v[10:11], off offset:128
	global_load_dwordx4 v[82:85], v[12:13], off offset:128
	global_load_dwordx4 v[86:89], v[14:15], off offset:128
	v_lshl_or_b32 v19, v16, 7, v21
	v_or_b32_e32 v16, v130, v134
	v_lshl_or_b32 v17, v54, 7, v21
	v_lshlrev_b32_e32 v54, 7, v91
	v_bitop3_b32 v21, v54, v90, v55 bitop3:0xf6
	v_readlane_b32 s12, v254, 55
	v_readlane_b32 s13, v254, 56
	v_readlane_b32 s14, v254, 57
	v_readlane_b32 s15, v254, 58
	s_waitcnt vmcnt(15)
	ds_write_b128 v19, v[22:25]
	s_waitcnt vmcnt(14)
	ds_write_b128 v20, v[26:29]
	s_waitcnt vmcnt(13)
	ds_write_b128 v17, v[30:33]
	s_waitcnt vmcnt(12)
	ds_write_b128 v18, v[34:37]
	s_waitcnt vmcnt(11)
	ds_write_b128 v19, v[38:41] offset:32768
	s_waitcnt vmcnt(10)
	ds_write_b128 v20, v[42:45] offset:32768
	s_waitcnt vmcnt(9)
	ds_write_b128 v17, v[46:49] offset:32768
	s_waitcnt vmcnt(8)
	ds_write_b128 v18, v[50:53] offset:32768
	s_waitcnt lgkmcnt(0)
	s_barrier
	s_setprio 2
	ds_read_b128 v[22:25], v16 offset:32768
	ds_read_b128 v[30:33], v21
	s_waitcnt lgkmcnt(0)
	v_mfma_f32_16x16x32_f16 v[38:41], v[22:25], v[30:33], 0
	ds_read_b128 v[26:29], v16 offset:34816
	ds_read_b128 v[34:37], v21 offset:2048
	s_waitcnt lgkmcnt(0)
	v_mfma_f32_16x16x32_f16 v[94:97], v[22:25], v[34:37], 0
	ds_read_b128 v[42:45], v16 offset:36864
	ds_read_b128 v[106:109], v21 offset:4096
	s_waitcnt lgkmcnt(0)
	v_mfma_f32_16x16x32_f16 v[114:117], v[22:25], v[106:109], 0
	ds_read_b128 v[50:53], v16 offset:38912
	ds_read_b128 v[110:113], v21 offset:6144
	s_waitcnt lgkmcnt(0)
	v_mfma_f32_16x16x32_f16 v[126:129], v[22:25], v[110:113], 0
	v_xor_b32_e32 v22, 64, v134
	v_mfma_f32_16x16x32_f16 v[46:49], v[26:29], v[30:33], 0
	v_or_b32_e32 v22, v130, v22
	v_mfma_f32_16x16x32_f16 v[90:93], v[42:45], v[30:33], 0
	ds_read_b128 v[130:133], v22 offset:32768
	v_mfma_f32_16x16x32_f16 v[30:33], v[50:53], v[30:33], 0
	ds_read_b128 v[142:145], v22 offset:36864
	v_mfma_f32_16x16x32_f16 v[98:101], v[26:29], v[34:37], 0
	ds_read_b128 v[154:157], v22 offset:38912
	v_mfma_f32_16x16x32_f16 v[102:105], v[42:45], v[34:37], 0
	v_bitop3_b32 v23, v54, v134, 64 bitop3:0xf6
	v_mfma_f32_16x16x32_f16 v[34:37], v[50:53], v[34:37], 0
	ds_read_b128 v[134:137], v23
	v_mfma_f32_16x16x32_f16 v[118:121], v[26:29], v[106:109], 0
	ds_read_b128 v[138:141], v23 offset:2048
	v_mfma_f32_16x16x32_f16 v[122:125], v[42:45], v[106:109], 0
	s_waitcnt vmcnt(7)
	ds_write_b128 v19, v[58:61] offset:16384
	v_mfma_f32_16x16x32_f16 v[106:109], v[50:53], v[106:109], 0
	s_waitcnt vmcnt(6)
	ds_write_b128 v20, v[62:65] offset:16384
	v_mfma_f32_16x16x32_f16 v[24:27], v[26:29], v[110:113], 0
	s_waitcnt vmcnt(5)
	ds_write_b128 v17, v[66:69] offset:16384
	v_mfma_f32_16x16x32_f16 v[42:45], v[42:45], v[110:113], 0
	s_waitcnt vmcnt(4)
	ds_write_b128 v18, v[70:73] offset:16384
	v_mfma_f32_16x16x32_f16 v[50:53], v[50:53], v[110:113], 0
	ds_read_b128 v[110:113], v22 offset:34816
	s_waitcnt lgkmcnt(6)
; #define GL_LOAD(s_, kt_) if (VAR != 1) { a##s_##0 = GL_A(0, kt_); a##s_##1 = GL_A(1, kt_); a##s_##2 = GL_A(2, kt_); a##s_##3 = GL_A(3, kt_); b##s_##0 = GL_B(0, kt_); b##s_##1 = GL_B(1, kt_); b##s_##2 = GL_B(2, kt_); b##s_##3 = GL_B(3, kt_); }
; #define LDS_STORE(s_, buf_) if (VAR != 2) { LDS_ST1(sA, 0, buf_, a##s_##0) LDS_ST1(sA, 1, buf_, a##s_##1) LDS_ST1(sA, 2, buf_, a##s_##2) LDS_ST1(sA, 3, buf_, a##s_##3) LDS_ST1(sB, 0, buf_, b##s_##0) LDS_ST1(sB, 1, buf_, b##s_##1) LDS_ST1(sB, 2, buf_, b##s_##2) LDS_ST1(sB, 3, buf_, b##s_##3) }
;     ...
;   GL_LOAD(0, 0)
;   GL_LOAD(1, 1)
;   LDS_STORE(0, 0)
;   if (VAR != 4) __syncthreads();
; #pragma unroll
;   for (int kt = 0; kt < nk; kt += 2) {
;     if (kt + 2 < nk) { GL_LOAD(0, kt + 2) }
;     MMA_TILE(0)
;     LDS_STORE(1, 1)
;     if (VAR != 4) __syncthreads();
;     if (kt + 3 < nk) { GL_LOAD(1, kt + 3) }
;     MMA_TILE(1)
;     if (kt + 2 < nk) { LDS_STORE(0, 0) }
;     if (VAR != 4) __syncthreads();
;   }
	v_mfma_f32_16x16x32_f16 v[38:41], v[130:133], v[134:137], v[38:41]
	s_waitcnt vmcnt(3)
	ds_write_b128 v19, v[74:77] offset:49152
	v_mfma_f32_16x16x32_f16 v[90:93], v[142:145], v[134:137], v[90:93]
	s_waitcnt vmcnt(2)
	ds_write_b128 v20, v[78:81] offset:49152
	v_mfma_f32_16x16x32_f16 v[28:31], v[154:157], v[134:137], v[30:33]
	s_waitcnt vmcnt(1)
	ds_write_b128 v17, v[82:85] offset:49152
	s_waitcnt lgkmcnt(8)
	v_mfma_f32_16x16x32_f16 v[94:97], v[130:133], v[138:141], v[94:97]
	s_waitcnt vmcnt(0)
	ds_write_b128 v18, v[86:89] offset:49152
	v_mfma_f32_16x16x32_f16 v[102:105], v[142:145], v[138:141], v[102:105]
	v_mfma_f32_16x16x32_f16 v[32:35], v[154:157], v[138:141], v[34:37]
	s_waitcnt lgkmcnt(4)
	v_mfma_f32_16x16x32_f16 v[46:49], v[110:113], v[134:137], v[46:49]
	ds_read_b128 v[134:137], v23 offset:4096
	v_mfma_f32_16x16x32_f16 v[98:101], v[110:113], v[138:141], v[98:101]
	ds_read_b128 v[138:141], v23 offset:6144
	s_waitcnt lgkmcnt(1)
	v_mfma_f32_16x16x32_f16 v[114:117], v[130:133], v[134:137], v[114:117]
	s_waitcnt lgkmcnt(0)
	v_mfma_f32_16x16x32_f16 v[126:129], v[130:133], v[138:141], v[126:129]
	global_load_dwordx4 v[130:133], v[0:1], off offset:256
	v_mfma_f32_16x16x32_f16 v[118:121], v[110:113], v[134:137], v[118:121]
	v_mfma_f32_16x16x32_f16 v[24:27], v[110:113], v[138:141], v[24:27]
	v_mfma_f32_16x16x32_f16 v[122:125], v[142:145], v[134:137], v[122:125]
	v_mfma_f32_16x16x32_f16 v[106:109], v[154:157], v[134:137], v[106:109]
	global_load_dwordx4 v[134:137], v[2:3], off offset:256
	global_load_dwordx4 v[158:161], v[4:5], off offset:256
	global_load_dwordx4 v[162:165], v[6:7], off offset:256
	global_load_dwordx4 v[110:113], v[8:9], off offset:256
	global_load_dwordx4 v[166:169], v[10:11], off offset:256
	global_load_dwordx4 v[190:193], v[12:13], off offset:256
	global_load_dwordx4 v[194:197], v[14:15], off offset:256
	s_waitcnt lgkmcnt(0)
	s_barrier
	v_mfma_f32_16x16x32_f16 v[42:45], v[142:145], v[138:141], v[42:45]
	ds_read_b128 v[58:61], v16 offset:49152
	v_mfma_f32_16x16x32_f16 v[50:53], v[154:157], v[138:141], v[50:53]
	ds_read_b128 v[62:65], v16 offset:51200
	ds_read_b128 v[66:69], v21 offset:16384
	s_waitcnt lgkmcnt(0)
	v_mfma_f32_16x16x32_f16 v[36:39], v[58:61], v[66:69], v[38:41]
	ds_read_b128 v[70:73], v21 offset:18432
	v_mfma_f32_16x16x32_f16 v[46:49], v[62:65], v[66:69], v[46:49]
	ds_read_b128 v[74:77], v16 offset:53248
	s_waitcnt lgkmcnt(0)
	v_mfma_f32_16x16x32_f16 v[82:85], v[74:77], v[66:69], v[90:93]
	ds_read_b128 v[78:81], v16 offset:55296
	s_waitcnt lgkmcnt(0)
	v_mfma_f32_16x16x32_f16 v[28:31], v[78:81], v[66:69], v[28:31]
	v_mfma_f32_16x16x32_f16 v[66:69], v[58:61], v[70:73], v[94:97]
	s_nop 2
	ds_read_b128 v[94:97], v21 offset:22528
	s_waitcnt vmcnt(7)
	ds_write_b128 v19, v[130:133]
	v_mfma_f32_16x16x32_f16 v[86:89], v[62:65], v[70:73], v[98:101]
	s_waitcnt vmcnt(6)
	ds_write_b128 v20, v[134:137]
	s_waitcnt vmcnt(5)
	ds_write_b128 v17, v[158:161]
	v_mfma_f32_16x16x32_f16 v[90:93], v[74:77], v[70:73], v[102:105]
	s_waitcnt vmcnt(4)
	ds_write_b128 v18, v[162:165]
	s_waitcnt vmcnt(3)
	ds_write_b128 v19, v[110:113] offset:32768
	v_mfma_f32_16x16x32_f16 v[32:35], v[78:81], v[70:73], v[32:35]
	ds_read_b128 v[70:73], v21 offset:20480
	s_waitcnt lgkmcnt(0)
	v_mfma_f32_16x16x32_f16 v[98:101], v[58:61], v[70:73], v[114:117]
	s_waitcnt vmcnt(2)
	ds_write_b128 v20, v[166:169] offset:32768
	v_mfma_f32_16x16x32_f16 v[58:61], v[58:61], v[94:97], v[126:129]
	s_waitcnt vmcnt(1)
	ds_write_b128 v17, v[190:193] offset:32768
	v_mfma_f32_16x16x32_f16 v[102:105], v[62:65], v[70:73], v[118:121]
	s_nop 2
	ds_read_b128 v[118:121], v22 offset:55296
	v_mfma_f32_16x16x32_f16 v[24:27], v[62:65], v[94:97], v[24:27]
	ds_read_b128 v[62:65], v22 offset:49152
	v_mfma_f32_16x16x32_f16 v[114:117], v[74:77], v[70:73], v[122:125]
	s_waitcnt vmcnt(0)
	ds_write_b128 v18, v[194:197] offset:32768
	v_mfma_f32_16x16x32_f16 v[40:43], v[74:77], v[94:97], v[42:45]
	ds_read_b128 v[74:77], v22 offset:51200
	v_mfma_f32_16x16x32_f16 v[70:73], v[78:81], v[70:73], v[106:109]
	s_nop 2
	ds_read_b128 v[106:109], v22 offset:53248
	v_mfma_f32_16x16x32_f16 v[50:53], v[78:81], v[94:97], v[50:53]
	ds_read_b128 v[78:81], v23 offset:16384
	s_waitcnt lgkmcnt(0)
	v_mfma_f32_16x16x32_f16 v[36:39], v[62:65], v[78:81], v[36:39]
	ds_read_b128 v[94:97], v23 offset:18432
	s_waitcnt lgkmcnt(0)
	v_mfma_f32_16x16x32_f16 v[66:69], v[62:65], v[94:97], v[66:69]
	v_mfma_f32_16x16x32_f16 v[44:47], v[74:77], v[78:81], v[46:49]
	v_mfma_f32_16x16x32_f16 v[82:85], v[106:109], v[78:81], v[82:85]
	v_mfma_f32_16x16x32_f16 v[28:31], v[118:121], v[78:81], v[28:31]
	v_mfma_f32_16x16x32_f16 v[78:81], v[74:77], v[94:97], v[86:89]
	v_mfma_f32_16x16x32_f16 v[86:89], v[106:109], v[94:97], v[90:93]
	s_nop 2
	ds_read_b128 v[90:93], v23 offset:20480
	v_mfma_f32_16x16x32_f16 v[32:35], v[118:121], v[94:97], v[32:35]
	ds_read_b128 v[94:97], v23 offset:22528
	s_waitcnt lgkmcnt(1)
	v_mfma_f32_16x16x32_f16 v[98:101], v[62:65], v[90:93], v[98:101]
	s_waitcnt lgkmcnt(0)
	v_mfma_f32_16x16x32_f16 v[58:61], v[62:65], v[94:97], v[58:61]
	global_load_dwordx4 v[62:65], v[0:1], off offset:384
	v_mfma_f32_16x16x32_f16 v[102:105], v[74:77], v[90:93], v[102:105]
	v_mfma_f32_16x16x32_f16 v[24:27], v[74:77], v[94:97], v[24:27]
	v_mfma_f32_16x16x32_f16 v[114:117], v[106:109], v[90:93], v[114:117]
	v_mfma_f32_16x16x32_f16 v[40:43], v[106:109], v[94:97], v[40:43]
	v_mfma_f32_16x16x32_f16 v[70:73], v[118:121], v[90:93], v[70:73]
	global_load_dwordx4 v[90:93], v[2:3], off offset:384
	global_load_dwordx4 v[122:125], v[4:5], off offset:384
	global_load_dwordx4 v[126:129], v[6:7], off offset:384
	global_load_dwordx4 v[74:77], v[8:9], off offset:384
	global_load_dwordx4 v[138:141], v[10:11], off offset:384
	global_load_dwordx4 v[142:145], v[12:13], off offset:384
	global_load_dwordx4 v[154:157], v[14:15], off offset:384
	s_waitcnt lgkmcnt(0)
	s_barrier
; #define GL_LOAD(s_, kt_) if (VAR != 1) { a##s_##0 = GL_A(0, kt_); a##s_##1 = GL_A(1, kt_); a##s_##2 = GL_A(2, kt_); a##s_##3 = GL_A(3, kt_); b##s_##0 = GL_B(0, kt_); b##s_##1 = GL_B(1, kt_); b##s_##2 = GL_B(2, kt_); b##s_##3 = GL_B(3, kt_); }
; #define LDS_STORE(s_, buf_) if (VAR != 2) { LDS_ST1(sA, 0, buf_, a##s_##0) LDS_ST1(sA, 1, buf_, a##s_##1) LDS_ST1(sA, 2, buf_, a##s_##2) LDS_ST1(sA, 3, buf_, a##s_##3) LDS_ST1(sB, 0, buf_, b##s_##0) LDS_ST1(sB, 1, buf_, b##s_##1) LDS_ST1(sB, 2, buf_, b##s_##2) LDS_ST1(sB, 3, buf_, b##s_##3) }
;     ...
;   GL_LOAD(0, 0)
;   GL_LOAD(1, 1)
;   LDS_STORE(0, 0)
;   if (VAR != 4) __syncthreads();
; #pragma unroll
;   for (int kt = 0; kt < nk; kt += 2) {
;     if (kt + 2 < nk) { GL_LOAD(0, kt + 2) }
;     MMA_TILE(0)
;     LDS_STORE(1, 1)
;     if (VAR != 4) __syncthreads();
;     if (kt + 3 < nk) { GL_LOAD(1, kt + 3) }
;     MMA_TILE(1)
;     if (kt + 2 < nk) { LDS_STORE(0, 0) }
;     if (VAR != 4) __syncthreads();
;   }
	v_mfma_f32_16x16x32_f16 v[48:51], v[118:121], v[94:97], v[50:53]
	ds_read_b128 v[106:109], v16 offset:32768
	ds_read_b128 v[94:97], v21
	s_waitcnt lgkmcnt(0)
	v_mfma_f32_16x16x32_f16 v[36:39], v[106:109], v[94:97], v[36:39]
	ds_read_b128 v[52:55], v16 offset:34816
	ds_read_b128 v[110:113], v21 offset:2048
	s_waitcnt lgkmcnt(0)
	v_mfma_f32_16x16x32_f16 v[66:69], v[106:109], v[110:113], v[66:69]
	ds_read_b128 v[118:121], v16 offset:36864
	v_mfma_f32_16x16x32_f16 v[44:47], v[52:55], v[94:97], v[44:47]
	ds_read_b128 v[130:133], v16 offset:38912
	v_mfma_f32_16x16x32_f16 v[78:81], v[52:55], v[110:113], v[78:81]
	s_waitcnt vmcnt(7)
	ds_write_b128 v19, v[62:65] offset:16384
	s_waitcnt lgkmcnt(2)
	v_mfma_f32_16x16x32_f16 v[82:85], v[118:121], v[94:97], v[82:85]
	s_waitcnt vmcnt(6)
	ds_write_b128 v20, v[90:93] offset:16384
	v_mfma_f32_16x16x32_f16 v[86:89], v[118:121], v[110:113], v[86:89]
	s_waitcnt vmcnt(5)
	ds_write_b128 v17, v[122:125] offset:16384
	s_waitcnt lgkmcnt(3)
	v_mfma_f32_16x16x32_f16 v[28:31], v[130:133], v[94:97], v[28:31]
	ds_read_b128 v[94:97], v21 offset:4096
	v_mfma_f32_16x16x32_f16 v[32:35], v[130:133], v[110:113], v[32:35]
	ds_read_b128 v[110:113], v21 offset:6144
	s_waitcnt lgkmcnt(1)
	v_mfma_f32_16x16x32_f16 v[98:101], v[106:109], v[94:97], v[98:101]
	s_waitcnt vmcnt(4)
	ds_write_b128 v18, v[126:129] offset:16384
	s_waitcnt lgkmcnt(1)
	v_mfma_f32_16x16x32_f16 v[58:61], v[106:109], v[110:113], v[58:61]
	ds_read_b128 v[106:109], v23
	v_mfma_f32_16x16x32_f16 v[102:105], v[52:55], v[94:97], v[102:105]
	s_waitcnt vmcnt(3)
	ds_write_b128 v19, v[74:77] offset:49152
	v_mfma_f32_16x16x32_f16 v[24:27], v[52:55], v[110:113], v[24:27]
	ds_read_b128 v[52:55], v22 offset:32768
	v_mfma_f32_16x16x32_f16 v[114:117], v[118:121], v[94:97], v[114:117]
	s_waitcnt vmcnt(2)
	ds_write_b128 v20, v[138:141] offset:49152
	v_mfma_f32_16x16x32_f16 v[40:43], v[118:121], v[110:113], v[40:43]
	ds_read_b128 v[118:121], v22 offset:36864
	v_mfma_f32_16x16x32_f16 v[70:73], v[130:133], v[94:97], v[70:73]
	ds_read_b128 v[94:97], v22 offset:34816
	v_mfma_f32_16x16x32_f16 v[48:51], v[130:133], v[110:113], v[48:51]
	ds_read_b128 v[110:113], v23 offset:2048
	s_waitcnt lgkmcnt(4)
	v_mfma_f32_16x16x32_f16 v[36:39], v[52:55], v[106:109], v[36:39]
	ds_read_b128 v[130:133], v22 offset:38912
	s_waitcnt lgkmcnt(1)
	v_mfma_f32_16x16x32_f16 v[66:69], v[52:55], v[110:113], v[66:69]
	s_waitcnt vmcnt(1)
	ds_write_b128 v17, v[142:145] offset:49152
	v_mfma_f32_16x16x32_f16 v[44:47], v[94:97], v[106:109], v[44:47]
	s_waitcnt vmcnt(0)
	ds_write_b128 v18, v[154:157] offset:49152
	v_mfma_f32_16x16x32_f16 v[78:81], v[94:97], v[110:113], v[78:81]
	v_mfma_f32_16x16x32_f16 v[82:85], v[118:121], v[106:109], v[82:85]
	v_mfma_f32_16x16x32_f16 v[86:89], v[118:121], v[110:113], v[86:89]
	s_waitcnt lgkmcnt(2)
	v_mfma_f32_16x16x32_f16 v[28:31], v[130:133], v[106:109], v[28:31]
	ds_read_b128 v[106:109], v23 offset:4096
	v_mfma_f32_16x16x32_f16 v[32:35], v[130:133], v[110:113], v[32:35]
	ds_read_b128 v[110:113], v23 offset:6144
	s_waitcnt lgkmcnt(1)
	v_mfma_f32_16x16x32_f16 v[98:101], v[52:55], v[106:109], v[98:101]
	s_waitcnt lgkmcnt(0)
	v_mfma_f32_16x16x32_f16 v[52:55], v[52:55], v[110:113], v[58:61]
	s_nop 2
	global_load_dwordx4 v[58:61], v[0:1], off offset:512
	v_mfma_f32_16x16x32_f16 v[102:105], v[94:97], v[106:109], v[102:105]
	v_mfma_f32_16x16x32_f16 v[24:27], v[94:97], v[110:113], v[24:27]
	v_mfma_f32_16x16x32_f16 v[114:117], v[118:121], v[106:109], v[114:117]
	v_mfma_f32_16x16x32_f16 v[40:43], v[118:121], v[110:113], v[40:43]
	v_mfma_f32_16x16x32_f16 v[70:73], v[130:133], v[106:109], v[70:73]
	global_load_dwordx4 v[106:109], v[2:3], off offset:512
	global_load_dwordx4 v[134:137], v[4:5], off offset:512
	global_load_dwordx4 v[158:161], v[6:7], off offset:512
	global_load_dwordx4 v[94:97], v[8:9], off offset:512
	global_load_dwordx4 v[162:165], v[10:11], off offset:512
	global_load_dwordx4 v[166:169], v[12:13], off offset:512
	global_load_dwordx4 v[190:193], v[14:15], off offset:512
	s_waitcnt lgkmcnt(0)
	s_barrier
	v_mfma_f32_16x16x32_f16 v[48:51], v[130:133], v[110:113], v[48:51]
	ds_read_b128 v[62:65], v16 offset:49152
	ds_read_b128 v[90:93], v21 offset:16384
	s_waitcnt lgkmcnt(0)
	v_mfma_f32_16x16x32_f16 v[36:39], v[62:65], v[90:93], v[36:39]
	ds_read_b128 v[74:77], v16 offset:51200
	ds_read_b128 v[110:113], v21 offset:18432
	s_waitcnt lgkmcnt(0)
	v_mfma_f32_16x16x32_f16 v[66:69], v[62:65], v[110:113], v[66:69]
	ds_read_b128 v[118:121], v16 offset:53248
	v_mfma_f32_16x16x32_f16 v[44:47], v[74:77], v[90:93], v[44:47]
	ds_read_b128 v[122:125], v16 offset:55296
	v_mfma_f32_16x16x32_f16 v[78:81], v[74:77], v[110:113], v[78:81]
	s_waitcnt vmcnt(7)
	ds_write_b128 v19, v[58:61]
	s_waitcnt lgkmcnt(2)
	v_mfma_f32_16x16x32_f16 v[82:85], v[118:121], v[90:93], v[82:85]
	s_waitcnt vmcnt(6)
	ds_write_b128 v20, v[106:109]
	v_mfma_f32_16x16x32_f16 v[86:89], v[118:121], v[110:113], v[86:89]
	s_waitcnt vmcnt(5)
	ds_write_b128 v17, v[134:137]
	s_waitcnt lgkmcnt(3)
	v_mfma_f32_16x16x32_f16 v[28:31], v[122:125], v[90:93], v[28:31]
	ds_read_b128 v[90:93], v21 offset:20480
	v_mfma_f32_16x16x32_f16 v[32:35], v[122:125], v[110:113], v[32:35]
	ds_read_b128 v[110:113], v21 offset:22528
	s_waitcnt lgkmcnt(1)
	v_mfma_f32_16x16x32_f16 v[98:101], v[62:65], v[90:93], v[98:101]
	s_waitcnt vmcnt(4)
	ds_write_b128 v18, v[158:161]
	s_waitcnt lgkmcnt(1)
	v_mfma_f32_16x16x32_f16 v[52:55], v[62:65], v[110:113], v[52:55]
	ds_read_b128 v[62:65], v22 offset:49152
	v_mfma_f32_16x16x32_f16 v[102:105], v[74:77], v[90:93], v[102:105]
	s_waitcnt vmcnt(3)
; #define GL_LOAD(s_, kt_) if (VAR != 1) { a##s_##0 = GL_A(0, kt_); a##s_##1 = GL_A(1, kt_); a##s_##2 = GL_A(2, kt_); a##s_##3 = GL_A(3, kt_); b##s_##0 = GL_B(0, kt_); b##s_##1 = GL_B(1, kt_); b##s_##2 = GL_B(2, kt_); b##s_##3 = GL_B(3, kt_); }
; #define LDS_STORE(s_, buf_) if (VAR != 2) { LDS_ST1(sA, 0, buf_, a##s_##0) LDS_ST1(sA, 1, buf_, a##s_##1) LDS_ST1(sA, 2, buf_, a##s_##2) LDS_ST1(sA, 3, buf_, a##s_##3) LDS_ST1(sB, 0, buf_, b##s_##0) LDS_ST1(sB, 1, buf_, b##s_##1) LDS_ST1(sB, 2, buf_, b##s_##2) LDS_ST1(sB, 3, buf_, b##s_##3) }
;     ...
;   GL_LOAD(0, 0)
;   GL_LOAD(1, 1)
;   LDS_STORE(0, 0)
;   if (VAR != 4) __syncthreads();
; #pragma unroll
;   for (int kt = 0; kt < nk; kt += 2) {
;     if (kt + 2 < nk) { GL_LOAD(0, kt + 2) }
;     MMA_TILE(0)
;     LDS_STORE(1, 1)
;     if (VAR != 4) __syncthreads();
;     if (kt + 3 < nk) { GL_LOAD(1, kt + 3) }
;     MMA_TILE(1)
;     if (kt + 2 < nk) { LDS_STORE(0, 0) }
;     if (VAR != 4) __syncthreads();
;   }
	ds_write_b128 v19, v[94:97] offset:32768
	v_mfma_f32_16x16x32_f16 v[24:27], v[74:77], v[110:113], v[24:27]
	ds_read_b128 v[74:77], v22 offset:51200
	v_mfma_f32_16x16x32_f16 v[114:117], v[118:121], v[90:93], v[114:117]
	s_waitcnt vmcnt(2)
	ds_write_b128 v20, v[162:165] offset:32768
	v_mfma_f32_16x16x32_f16 v[40:43], v[118:121], v[110:113], v[40:43]
	ds_read_b128 v[118:121], v22 offset:53248
	v_mfma_f32_16x16x32_f16 v[70:73], v[122:125], v[90:93], v[70:73]
	ds_read_b128 v[90:93], v23 offset:16384
	v_mfma_f32_16x16x32_f16 v[48:51], v[122:125], v[110:113], v[48:51]
	ds_read_b128 v[110:113], v23 offset:18432
	s_waitcnt lgkmcnt(1)
	v_mfma_f32_16x16x32_f16 v[36:39], v[62:65], v[90:93], v[36:39]
	ds_read_b128 v[122:125], v22 offset:55296
	s_waitcnt lgkmcnt(1)
	v_mfma_f32_16x16x32_f16 v[66:69], v[62:65], v[110:113], v[66:69]
	s_waitcnt vmcnt(1)
	ds_write_b128 v17, v[166:169] offset:32768
	v_mfma_f32_16x16x32_f16 v[44:47], v[74:77], v[90:93], v[44:47]
	s_waitcnt vmcnt(0)
	ds_write_b128 v18, v[190:193] offset:32768
	v_mfma_f32_16x16x32_f16 v[78:81], v[74:77], v[110:113], v[78:81]
	v_mfma_f32_16x16x32_f16 v[82:85], v[118:121], v[90:93], v[82:85]
	v_mfma_f32_16x16x32_f16 v[86:89], v[118:121], v[110:113], v[86:89]
	s_waitcnt lgkmcnt(2)
	v_mfma_f32_16x16x32_f16 v[28:31], v[122:125], v[90:93], v[28:31]
	ds_read_b128 v[90:93], v23 offset:20480
	v_mfma_f32_16x16x32_f16 v[32:35], v[122:125], v[110:113], v[32:35]
	ds_read_b128 v[110:113], v23 offset:22528
	s_waitcnt lgkmcnt(1)
	v_mfma_f32_16x16x32_f16 v[98:101], v[62:65], v[90:93], v[98:101]
	s_waitcnt lgkmcnt(0)
	v_mfma_f32_16x16x32_f16 v[52:55], v[62:65], v[110:113], v[52:55]
	global_load_dwordx4 v[62:65], v[0:1], off offset:640
	v_mfma_f32_16x16x32_f16 v[102:105], v[74:77], v[90:93], v[102:105]
	v_mfma_f32_16x16x32_f16 v[24:27], v[74:77], v[110:113], v[24:27]
	v_mfma_f32_16x16x32_f16 v[114:117], v[118:121], v[90:93], v[114:117]
	v_mfma_f32_16x16x32_f16 v[40:43], v[118:121], v[110:113], v[40:43]
	v_mfma_f32_16x16x32_f16 v[70:73], v[122:125], v[90:93], v[70:73]
	global_load_dwordx4 v[90:93], v[2:3], off offset:640
	global_load_dwordx4 v[126:129], v[4:5], off offset:640
	global_load_dwordx4 v[130:133], v[6:7], off offset:640
	global_load_dwordx4 v[74:77], v[8:9], off offset:640
	global_load_dwordx4 v[138:141], v[10:11], off offset:640
	global_load_dwordx4 v[142:145], v[12:13], off offset:640
	global_load_dwordx4 v[154:157], v[14:15], off offset:640
	s_waitcnt lgkmcnt(0)
	s_barrier
	v_mfma_f32_16x16x32_f16 v[48:51], v[122:125], v[110:113], v[48:51]
	ds_read_b128 v[58:61], v16 offset:32768
	ds_read_b128 v[106:109], v21
	s_waitcnt lgkmcnt(0)
	v_mfma_f32_16x16x32_f16 v[36:39], v[58:61], v[106:109], v[36:39]
	ds_read_b128 v[94:97], v16 offset:34816
	ds_read_b128 v[110:113], v21 offset:2048
	s_waitcnt lgkmcnt(0)
	v_mfma_f32_16x16x32_f16 v[66:69], v[58:61], v[110:113], v[66:69]
	ds_read_b128 v[118:121], v16 offset:36864
	v_mfma_f32_16x16x32_f16 v[44:47], v[94:97], v[106:109], v[44:47]
	ds_read_b128 v[122:125], v16 offset:38912
	v_mfma_f32_16x16x32_f16 v[78:81], v[94:97], v[110:113], v[78:81]
	s_waitcnt vmcnt(7)
	ds_write_b128 v19, v[62:65] offset:16384
	s_waitcnt lgkmcnt(2)
	v_mfma_f32_16x16x32_f16 v[82:85], v[118:121], v[106:109], v[82:85]
	s_waitcnt vmcnt(6)
	ds_write_b128 v20, v[90:93] offset:16384
	v_mfma_f32_16x16x32_f16 v[86:89], v[118:121], v[110:113], v[86:89]
	s_waitcnt vmcnt(5)
	ds_write_b128 v17, v[126:129] offset:16384
	s_waitcnt lgkmcnt(3)
	v_mfma_f32_16x16x32_f16 v[28:31], v[122:125], v[106:109], v[28:31]
	ds_read_b128 v[106:109], v21 offset:4096
	v_mfma_f32_16x16x32_f16 v[32:35], v[122:125], v[110:113], v[32:35]
	ds_read_b128 v[110:113], v21 offset:6144
	s_waitcnt lgkmcnt(1)
	v_mfma_f32_16x16x32_f16 v[98:101], v[58:61], v[106:109], v[98:101]
	s_waitcnt vmcnt(4)
	ds_write_b128 v18, v[130:133] offset:16384
	s_waitcnt lgkmcnt(1)
	v_mfma_f32_16x16x32_f16 v[52:55], v[58:61], v[110:113], v[52:55]
	ds_read_b128 v[58:61], v22 offset:32768
	v_mfma_f32_16x16x32_f16 v[102:105], v[94:97], v[106:109], v[102:105]
	s_waitcnt vmcnt(3)
	ds_write_b128 v19, v[74:77] offset:49152
	v_mfma_f32_16x16x32_f16 v[24:27], v[94:97], v[110:113], v[24:27]
	ds_read_b128 v[94:97], v22 offset:34816
	v_mfma_f32_16x16x32_f16 v[114:117], v[118:121], v[106:109], v[114:117]
	s_waitcnt vmcnt(2)
	ds_write_b128 v20, v[138:141] offset:49152
	v_mfma_f32_16x16x32_f16 v[40:43], v[118:121], v[110:113], v[40:43]
	ds_read_b128 v[118:121], v22 offset:36864
	v_mfma_f32_16x16x32_f16 v[70:73], v[122:125], v[106:109], v[70:73]
	ds_read_b128 v[106:109], v23
	v_mfma_f32_16x16x32_f16 v[48:51], v[122:125], v[110:113], v[48:51]
	ds_read_b128 v[110:113], v23 offset:2048
	s_waitcnt lgkmcnt(1)
	v_mfma_f32_16x16x32_f16 v[36:39], v[58:61], v[106:109], v[36:39]
	ds_read_b128 v[122:125], v22 offset:38912
	s_waitcnt lgkmcnt(1)
	v_mfma_f32_16x16x32_f16 v[66:69], v[58:61], v[110:113], v[66:69]
	s_waitcnt vmcnt(1)
	ds_write_b128 v17, v[142:145] offset:49152
	v_mfma_f32_16x16x32_f16 v[44:47], v[94:97], v[106:109], v[44:47]
	s_waitcnt vmcnt(0)
	ds_write_b128 v18, v[154:157] offset:49152
	v_mfma_f32_16x16x32_f16 v[78:81], v[94:97], v[110:113], v[78:81]
	v_mfma_f32_16x16x32_f16 v[82:85], v[118:121], v[106:109], v[82:85]
	v_mfma_f32_16x16x32_f16 v[86:89], v[118:121], v[110:113], v[86:89]
	s_waitcnt lgkmcnt(2)
	v_mfma_f32_16x16x32_f16 v[28:31], v[122:125], v[106:109], v[28:31]
	ds_read_b128 v[106:109], v23 offset:4096
	v_mfma_f32_16x16x32_f16 v[32:35], v[122:125], v[110:113], v[32:35]
	ds_read_b128 v[110:113], v23 offset:6144
	s_waitcnt lgkmcnt(1)
	v_mfma_f32_16x16x32_f16 v[98:101], v[58:61], v[106:109], v[98:101]
	s_waitcnt lgkmcnt(0)
	v_mfma_f32_16x16x32_f16 v[52:55], v[58:61], v[110:113], v[52:55]
	global_load_dwordx4 v[58:61], v[0:1], off offset:768
	v_mfma_f32_16x16x32_f16 v[102:105], v[94:97], v[106:109], v[102:105]
	v_mfma_f32_16x16x32_f16 v[24:27], v[94:97], v[110:113], v[24:27]
	v_mfma_f32_16x16x32_f16 v[114:117], v[118:121], v[106:109], v[114:117]
	v_mfma_f32_16x16x32_f16 v[40:43], v[118:121], v[110:113], v[40:43]
	v_mfma_f32_16x16x32_f16 v[70:73], v[122:125], v[106:109], v[70:73]
	global_load_dwordx4 v[106:109], v[2:3], off offset:768
	global_load_dwordx4 v[134:137], v[4:5], off offset:768
	global_load_dwordx4 v[158:161], v[6:7], off offset:768
	global_load_dwordx4 v[94:97], v[8:9], off offset:768
	global_load_dwordx4 v[162:165], v[10:11], off offset:768
	global_load_dwordx4 v[166:169], v[12:13], off offset:768
	global_load_dwordx4 v[190:193], v[14:15], off offset:768
	s_waitcnt lgkmcnt(0)
	s_barrier
; #define GL_LOAD(s_, kt_) if (VAR != 1) { a##s_##0 = GL_A(0, kt_); a##s_##1 = GL_A(1, kt_); a##s_##2 = GL_A(2, kt_); a##s_##3 = GL_A(3, kt_); b##s_##0 = GL_B(0, kt_); b##s_##1 = GL_B(1, kt_); b##s_##2 = GL_B(2, kt_); b##s_##3 = GL_B(3, kt_); }
; #define LDS_STORE(s_, buf_) if (VAR != 2) { LDS_ST1(sA, 0, buf_, a##s_##0) LDS_ST1(sA, 1, buf_, a##s_##1) LDS_ST1(sA, 2, buf_, a##s_##2) LDS_ST1(sA, 3, buf_, a##s_##3) LDS_ST1(sB, 0, buf_, b##s_##0) LDS_ST1(sB, 1, buf_, b##s_##1) LDS_ST1(sB, 2, buf_, b##s_##2) LDS_ST1(sB, 3, buf_, b##s_##3) }
;     ...
;   GL_LOAD(0, 0)
;   GL_LOAD(1, 1)
;   LDS_STORE(0, 0)
;   if (VAR != 4) __syncthreads();
; #pragma unroll
;   for (int kt = 0; kt < nk; kt += 2) {
;     if (kt + 2 < nk) { GL_LOAD(0, kt + 2) }
;     MMA_TILE(0)
;     LDS_STORE(1, 1)
;     if (VAR != 4) __syncthreads();
;     if (kt + 3 < nk) { GL_LOAD(1, kt + 3) }
;     MMA_TILE(1)
;     if (kt + 2 < nk) { LDS_STORE(0, 0) }
;     if (VAR != 4) __syncthreads();
;   }
	v_mfma_f32_16x16x32_f16 v[48:51], v[122:125], v[110:113], v[48:51]
	ds_read_b128 v[62:65], v16 offset:49152
	ds_read_b128 v[90:93], v21 offset:16384
	s_waitcnt lgkmcnt(0)
	v_mfma_f32_16x16x32_f16 v[36:39], v[62:65], v[90:93], v[36:39]
	ds_read_b128 v[74:77], v16 offset:51200
	ds_read_b128 v[110:113], v21 offset:18432
	s_waitcnt lgkmcnt(0)
	v_mfma_f32_16x16x32_f16 v[66:69], v[62:65], v[110:113], v[66:69]
	ds_read_b128 v[118:121], v16 offset:53248
	v_mfma_f32_16x16x32_f16 v[44:47], v[74:77], v[90:93], v[44:47]
	ds_read_b128 v[122:125], v16 offset:55296
	v_mfma_f32_16x16x32_f16 v[78:81], v[74:77], v[110:113], v[78:81]
	s_waitcnt vmcnt(7)
	ds_write_b128 v19, v[58:61]
	s_waitcnt lgkmcnt(2)
	v_mfma_f32_16x16x32_f16 v[82:85], v[118:121], v[90:93], v[82:85]
	s_waitcnt vmcnt(6)
	ds_write_b128 v20, v[106:109]
	v_mfma_f32_16x16x32_f16 v[86:89], v[118:121], v[110:113], v[86:89]
	s_waitcnt vmcnt(5)
	ds_write_b128 v17, v[134:137]
	s_waitcnt lgkmcnt(3)
	v_mfma_f32_16x16x32_f16 v[28:31], v[122:125], v[90:93], v[28:31]
	ds_read_b128 v[90:93], v21 offset:20480
	v_mfma_f32_16x16x32_f16 v[32:35], v[122:125], v[110:113], v[32:35]
	ds_read_b128 v[110:113], v21 offset:22528
	s_waitcnt lgkmcnt(1)
	v_mfma_f32_16x16x32_f16 v[98:101], v[62:65], v[90:93], v[98:101]
	s_waitcnt vmcnt(4)
	ds_write_b128 v18, v[158:161]
	s_waitcnt lgkmcnt(1)
	v_mfma_f32_16x16x32_f16 v[52:55], v[62:65], v[110:113], v[52:55]
	ds_read_b128 v[62:65], v22 offset:49152
	v_mfma_f32_16x16x32_f16 v[102:105], v[74:77], v[90:93], v[102:105]
	s_waitcnt vmcnt(3)
	ds_write_b128 v19, v[94:97] offset:32768
	v_mfma_f32_16x16x32_f16 v[24:27], v[74:77], v[110:113], v[24:27]
	ds_read_b128 v[74:77], v22 offset:51200
	v_mfma_f32_16x16x32_f16 v[114:117], v[118:121], v[90:93], v[114:117]
	s_waitcnt vmcnt(2)
	ds_write_b128 v20, v[162:165] offset:32768
	v_mfma_f32_16x16x32_f16 v[40:43], v[118:121], v[110:113], v[40:43]
	ds_read_b128 v[118:121], v22 offset:53248
	v_mfma_f32_16x16x32_f16 v[70:73], v[122:125], v[90:93], v[70:73]
	ds_read_b128 v[90:93], v23 offset:16384
	v_mfma_f32_16x16x32_f16 v[48:51], v[122:125], v[110:113], v[48:51]
	ds_read_b128 v[110:113], v23 offset:18432
	s_waitcnt lgkmcnt(1)
	v_mfma_f32_16x16x32_f16 v[36:39], v[62:65], v[90:93], v[36:39]
	ds_read_b128 v[122:125], v22 offset:55296
	s_waitcnt lgkmcnt(1)
	v_mfma_f32_16x16x32_f16 v[66:69], v[62:65], v[110:113], v[66:69]
	s_waitcnt vmcnt(1)
	ds_write_b128 v17, v[166:169] offset:32768
	v_mfma_f32_16x16x32_f16 v[44:47], v[74:77], v[90:93], v[44:47]
	s_waitcnt vmcnt(0)
	ds_write_b128 v18, v[190:193] offset:32768
	v_mfma_f32_16x16x32_f16 v[78:81], v[74:77], v[110:113], v[78:81]
	v_mfma_f32_16x16x32_f16 v[82:85], v[118:121], v[90:93], v[82:85]
	v_mfma_f32_16x16x32_f16 v[86:89], v[118:121], v[110:113], v[86:89]
	s_waitcnt lgkmcnt(2)
	v_mfma_f32_16x16x32_f16 v[28:31], v[122:125], v[90:93], v[28:31]
	ds_read_b128 v[90:93], v23 offset:20480
	v_mfma_f32_16x16x32_f16 v[32:35], v[122:125], v[110:113], v[32:35]
	ds_read_b128 v[110:113], v23 offset:22528
	s_waitcnt lgkmcnt(1)
	v_mfma_f32_16x16x32_f16 v[98:101], v[62:65], v[90:93], v[98:101]
	s_waitcnt lgkmcnt(0)
	v_mfma_f32_16x16x32_f16 v[52:55], v[62:65], v[110:113], v[52:55]
	global_load_dwordx4 v[62:65], v[0:1], off offset:896
	v_mfma_f32_16x16x32_f16 v[102:105], v[74:77], v[90:93], v[102:105]
	v_mfma_f32_16x16x32_f16 v[24:27], v[74:77], v[110:113], v[24:27]
	v_mfma_f32_16x16x32_f16 v[114:117], v[118:121], v[90:93], v[114:117]
	v_mfma_f32_16x16x32_f16 v[40:43], v[118:121], v[110:113], v[40:43]
	v_mfma_f32_16x16x32_f16 v[70:73], v[122:125], v[90:93], v[70:73]
	global_load_dwordx4 v[90:93], v[2:3], off offset:896
	global_load_dwordx4 v[126:129], v[4:5], off offset:896
	global_load_dwordx4 v[130:133], v[6:7], off offset:896
	global_load_dwordx4 v[74:77], v[8:9], off offset:896
	global_load_dwordx4 v[138:141], v[10:11], off offset:896
	global_load_dwordx4 v[142:145], v[12:13], off offset:896
	global_load_dwordx4 v[154:157], v[14:15], off offset:896
	s_waitcnt lgkmcnt(0)
	s_barrier
	v_mfma_f32_16x16x32_f16 v[48:51], v[122:125], v[110:113], v[48:51]
	ds_read_b128 v[58:61], v16 offset:32768
	ds_read_b128 v[106:109], v21
	s_waitcnt lgkmcnt(0)
	v_mfma_f32_16x16x32_f16 v[36:39], v[58:61], v[106:109], v[36:39]
	ds_read_b128 v[94:97], v16 offset:34816
	ds_read_b128 v[110:113], v21 offset:2048
	s_waitcnt lgkmcnt(0)
	v_mfma_f32_16x16x32_f16 v[66:69], v[58:61], v[110:113], v[66:69]
	ds_read_b128 v[118:121], v16 offset:36864
	v_mfma_f32_16x16x32_f16 v[44:47], v[94:97], v[106:109], v[44:47]
	ds_read_b128 v[122:125], v16 offset:38912
	v_mfma_f32_16x16x32_f16 v[78:81], v[94:97], v[110:113], v[78:81]
	s_waitcnt vmcnt(7)
	ds_write_b128 v19, v[62:65] offset:16384
	s_waitcnt lgkmcnt(2)
	v_mfma_f32_16x16x32_f16 v[82:85], v[118:121], v[106:109], v[82:85]
	s_waitcnt vmcnt(6)
	ds_write_b128 v20, v[90:93] offset:16384
	v_mfma_f32_16x16x32_f16 v[86:89], v[118:121], v[110:113], v[86:89]
	s_waitcnt vmcnt(5)
	ds_write_b128 v17, v[126:129] offset:16384
	s_waitcnt lgkmcnt(3)
	v_mfma_f32_16x16x32_f16 v[28:31], v[122:125], v[106:109], v[28:31]
	ds_read_b128 v[106:109], v21 offset:4096
	v_mfma_f32_16x16x32_f16 v[32:35], v[122:125], v[110:113], v[32:35]
	ds_read_b128 v[110:113], v21 offset:6144
	s_waitcnt lgkmcnt(1)
	v_mfma_f32_16x16x32_f16 v[98:101], v[58:61], v[106:109], v[98:101]
	s_waitcnt vmcnt(4)
	ds_write_b128 v18, v[130:133] offset:16384
	s_waitcnt lgkmcnt(1)
	v_mfma_f32_16x16x32_f16 v[52:55], v[58:61], v[110:113], v[52:55]
	ds_read_b128 v[58:61], v22 offset:32768
	v_mfma_f32_16x16x32_f16 v[102:105], v[94:97], v[106:109], v[102:105]
	s_waitcnt vmcnt(3)
; #define GL_LOAD(s_, kt_) if (VAR != 1) { a##s_##0 = GL_A(0, kt_); a##s_##1 = GL_A(1, kt_); a##s_##2 = GL_A(2, kt_); a##s_##3 = GL_A(3, kt_); b##s_##0 = GL_B(0, kt_); b##s_##1 = GL_B(1, kt_); b##s_##2 = GL_B(2, kt_); b##s_##3 = GL_B(3, kt_); }
; #define LDS_STORE(s_, buf_) if (VAR != 2) { LDS_ST1(sA, 0, buf_, a##s_##0) LDS_ST1(sA, 1, buf_, a##s_##1) LDS_ST1(sA, 2, buf_, a##s_##2) LDS_ST1(sA, 3, buf_, a##s_##3) LDS_ST1(sB, 0, buf_, b##s_##0) LDS_ST1(sB, 1, buf_, b##s_##1) LDS_ST1(sB, 2, buf_, b##s_##2) LDS_ST1(sB, 3, buf_, b##s_##3) }
;     ...
;   GL_LOAD(0, 0)
;   GL_LOAD(1, 1)
;   LDS_STORE(0, 0)
;   if (VAR != 4) __syncthreads();
; #pragma unroll
;   for (int kt = 0; kt < nk; kt += 2) {
;     if (kt + 2 < nk) { GL_LOAD(0, kt + 2) }
;     MMA_TILE(0)
;     LDS_STORE(1, 1)
;     if (VAR != 4) __syncthreads();
;     if (kt + 3 < nk) { GL_LOAD(1, kt + 3) }
;     MMA_TILE(1)
;     if (kt + 2 < nk) { LDS_STORE(0, 0) }
;     if (VAR != 4) __syncthreads();
;   }
	ds_write_b128 v19, v[74:77] offset:49152
	v_mfma_f32_16x16x32_f16 v[24:27], v[94:97], v[110:113], v[24:27]
	ds_read_b128 v[94:97], v22 offset:34816
	v_mfma_f32_16x16x32_f16 v[114:117], v[118:121], v[106:109], v[114:117]
	s_waitcnt vmcnt(2)
	ds_write_b128 v20, v[138:141] offset:49152
	v_mfma_f32_16x16x32_f16 v[40:43], v[118:121], v[110:113], v[40:43]
	ds_read_b128 v[118:121], v22 offset:36864
	v_mfma_f32_16x16x32_f16 v[70:73], v[122:125], v[106:109], v[70:73]
	ds_read_b128 v[106:109], v23
	v_mfma_f32_16x16x32_f16 v[48:51], v[122:125], v[110:113], v[48:51]
	ds_read_b128 v[110:113], v23 offset:2048
	s_waitcnt lgkmcnt(1)
	v_mfma_f32_16x16x32_f16 v[36:39], v[58:61], v[106:109], v[36:39]
	ds_read_b128 v[122:125], v22 offset:38912
	s_waitcnt lgkmcnt(1)
	v_mfma_f32_16x16x32_f16 v[66:69], v[58:61], v[110:113], v[66:69]
	s_waitcnt vmcnt(1)
	ds_write_b128 v17, v[142:145] offset:49152
	v_mfma_f32_16x16x32_f16 v[44:47], v[94:97], v[106:109], v[44:47]
	s_waitcnt vmcnt(0)
	ds_write_b128 v18, v[154:157] offset:49152
	v_mfma_f32_16x16x32_f16 v[78:81], v[94:97], v[110:113], v[78:81]
	v_mfma_f32_16x16x32_f16 v[82:85], v[118:121], v[106:109], v[82:85]
	v_mfma_f32_16x16x32_f16 v[86:89], v[118:121], v[110:113], v[86:89]
	s_waitcnt lgkmcnt(2)
	v_mfma_f32_16x16x32_f16 v[28:31], v[122:125], v[106:109], v[28:31]
	ds_read_b128 v[106:109], v23 offset:4096
	v_mfma_f32_16x16x32_f16 v[32:35], v[122:125], v[110:113], v[32:35]
	ds_read_b128 v[110:113], v23 offset:6144
	s_waitcnt lgkmcnt(1)
	v_mfma_f32_16x16x32_f16 v[98:101], v[58:61], v[106:109], v[98:101]
	s_waitcnt lgkmcnt(0)
	v_mfma_f32_16x16x32_f16 v[52:55], v[58:61], v[110:113], v[52:55]
	global_load_dwordx4 v[58:61], v[0:1], off offset:1024
	v_mfma_f32_16x16x32_f16 v[102:105], v[94:97], v[106:109], v[102:105]
	v_mfma_f32_16x16x32_f16 v[24:27], v[94:97], v[110:113], v[24:27]
	v_mfma_f32_16x16x32_f16 v[114:117], v[118:121], v[106:109], v[114:117]
	v_mfma_f32_16x16x32_f16 v[40:43], v[118:121], v[110:113], v[40:43]
	v_mfma_f32_16x16x32_f16 v[70:73], v[122:125], v[106:109], v[70:73]
	global_load_dwordx4 v[106:109], v[2:3], off offset:1024
	global_load_dwordx4 v[134:137], v[4:5], off offset:1024
	global_load_dwordx4 v[158:161], v[6:7], off offset:1024
	global_load_dwordx4 v[94:97], v[8:9], off offset:1024
	global_load_dwordx4 v[162:165], v[10:11], off offset:1024
	global_load_dwordx4 v[166:169], v[12:13], off offset:1024
	global_load_dwordx4 v[190:193], v[14:15], off offset:1024
	s_waitcnt lgkmcnt(0)
	s_barrier
	v_mfma_f32_16x16x32_f16 v[48:51], v[122:125], v[110:113], v[48:51]
	ds_read_b128 v[62:65], v16 offset:49152
	ds_read_b128 v[90:93], v21 offset:16384
	s_waitcnt lgkmcnt(0)
	v_mfma_f32_16x16x32_f16 v[36:39], v[62:65], v[90:93], v[36:39]
	ds_read_b128 v[74:77], v16 offset:51200
	ds_read_b128 v[110:113], v21 offset:18432
	s_waitcnt lgkmcnt(0)
	v_mfma_f32_16x16x32_f16 v[66:69], v[62:65], v[110:113], v[66:69]
	ds_read_b128 v[118:121], v16 offset:53248
	v_mfma_f32_16x16x32_f16 v[44:47], v[74:77], v[90:93], v[44:47]
	ds_read_b128 v[122:125], v16 offset:55296
	v_mfma_f32_16x16x32_f16 v[78:81], v[74:77], v[110:113], v[78:81]
	s_waitcnt vmcnt(7)
	ds_write_b128 v19, v[58:61]
	s_waitcnt lgkmcnt(2)
	v_mfma_f32_16x16x32_f16 v[82:85], v[118:121], v[90:93], v[82:85]
	s_waitcnt vmcnt(6)
	ds_write_b128 v20, v[106:109]
	v_mfma_f32_16x16x32_f16 v[86:89], v[118:121], v[110:113], v[86:89]
	s_waitcnt vmcnt(5)
	ds_write_b128 v17, v[134:137]
	s_waitcnt lgkmcnt(3)
	v_mfma_f32_16x16x32_f16 v[28:31], v[122:125], v[90:93], v[28:31]
	ds_read_b128 v[90:93], v21 offset:20480
	v_mfma_f32_16x16x32_f16 v[32:35], v[122:125], v[110:113], v[32:35]
	ds_read_b128 v[110:113], v21 offset:22528
	s_waitcnt lgkmcnt(1)
	v_mfma_f32_16x16x32_f16 v[98:101], v[62:65], v[90:93], v[98:101]
	s_waitcnt vmcnt(4)
	ds_write_b128 v18, v[158:161]
	s_waitcnt lgkmcnt(1)
	v_mfma_f32_16x16x32_f16 v[52:55], v[62:65], v[110:113], v[52:55]
	ds_read_b128 v[62:65], v22 offset:49152
	v_mfma_f32_16x16x32_f16 v[102:105], v[74:77], v[90:93], v[102:105]
	s_waitcnt vmcnt(3)
	ds_write_b128 v19, v[94:97] offset:32768
	v_mfma_f32_16x16x32_f16 v[24:27], v[74:77], v[110:113], v[24:27]
	ds_read_b128 v[74:77], v22 offset:51200
	v_mfma_f32_16x16x32_f16 v[114:117], v[118:121], v[90:93], v[114:117]
	s_waitcnt vmcnt(2)
	ds_write_b128 v20, v[162:165] offset:32768
	v_mfma_f32_16x16x32_f16 v[40:43], v[118:121], v[110:113], v[40:43]
	ds_read_b128 v[118:121], v22 offset:53248
	v_mfma_f32_16x16x32_f16 v[70:73], v[122:125], v[90:93], v[70:73]
	ds_read_b128 v[90:93], v23 offset:16384
	v_mfma_f32_16x16x32_f16 v[48:51], v[122:125], v[110:113], v[48:51]
	ds_read_b128 v[110:113], v23 offset:18432
	s_waitcnt lgkmcnt(1)
	v_mfma_f32_16x16x32_f16 v[36:39], v[62:65], v[90:93], v[36:39]
	ds_read_b128 v[122:125], v22 offset:55296
	s_waitcnt lgkmcnt(1)
	v_mfma_f32_16x16x32_f16 v[66:69], v[62:65], v[110:113], v[66:69]
	s_waitcnt vmcnt(1)
	ds_write_b128 v17, v[166:169] offset:32768
	v_mfma_f32_16x16x32_f16 v[44:47], v[74:77], v[90:93], v[44:47]
	s_waitcnt vmcnt(0)
	ds_write_b128 v18, v[190:193] offset:32768
	v_mfma_f32_16x16x32_f16 v[78:81], v[74:77], v[110:113], v[78:81]
	v_mfma_f32_16x16x32_f16 v[82:85], v[118:121], v[90:93], v[82:85]
	v_mfma_f32_16x16x32_f16 v[86:89], v[118:121], v[110:113], v[86:89]
	s_waitcnt lgkmcnt(2)
	v_mfma_f32_16x16x32_f16 v[28:31], v[122:125], v[90:93], v[28:31]
	ds_read_b128 v[90:93], v23 offset:20480
	v_mfma_f32_16x16x32_f16 v[32:35], v[122:125], v[110:113], v[32:35]
	ds_read_b128 v[110:113], v23 offset:22528
	s_waitcnt lgkmcnt(1)
	v_mfma_f32_16x16x32_f16 v[98:101], v[62:65], v[90:93], v[98:101]
	s_waitcnt lgkmcnt(0)
	v_mfma_f32_16x16x32_f16 v[52:55], v[62:65], v[110:113], v[52:55]
	global_load_dwordx4 v[62:65], v[0:1], off offset:1152
	v_mfma_f32_16x16x32_f16 v[102:105], v[74:77], v[90:93], v[102:105]
	v_mfma_f32_16x16x32_f16 v[24:27], v[74:77], v[110:113], v[24:27]
	v_mfma_f32_16x16x32_f16 v[114:117], v[118:121], v[90:93], v[114:117]
	v_mfma_f32_16x16x32_f16 v[40:43], v[118:121], v[110:113], v[40:43]
	v_mfma_f32_16x16x32_f16 v[70:73], v[122:125], v[90:93], v[70:73]
	global_load_dwordx4 v[90:93], v[2:3], off offset:1152
	global_load_dwordx4 v[126:129], v[4:5], off offset:1152
	global_load_dwordx4 v[130:133], v[6:7], off offset:1152
	global_load_dwordx4 v[74:77], v[8:9], off offset:1152
	global_load_dwordx4 v[138:141], v[10:11], off offset:1152
	global_load_dwordx4 v[142:145], v[12:13], off offset:1152
	global_load_dwordx4 v[154:157], v[14:15], off offset:1152
	s_waitcnt lgkmcnt(0)
	s_barrier
; #define GL_LOAD(s_, kt_) if (VAR != 1) { a##s_##0 = GL_A(0, kt_); a##s_##1 = GL_A(1, kt_); a##s_##2 = GL_A(2, kt_); a##s_##3 = GL_A(3, kt_); b##s_##0 = GL_B(0, kt_); b##s_##1 = GL_B(1, kt_); b##s_##2 = GL_B(2, kt_); b##s_##3 = GL_B(3, kt_); }
; #define LDS_STORE(s_, buf_) if (VAR != 2) { LDS_ST1(sA, 0, buf_, a##s_##0) LDS_ST1(sA, 1, buf_, a##s_##1) LDS_ST1(sA, 2, buf_, a##s_##2) LDS_ST1(sA, 3, buf_, a##s_##3) LDS_ST1(sB, 0, buf_, b##s_##0) LDS_ST1(sB, 1, buf_, b##s_##1) LDS_ST1(sB, 2, buf_, b##s_##2) LDS_ST1(sB, 3, buf_, b##s_##3) }
;     ...
;   GL_LOAD(0, 0)
;   GL_LOAD(1, 1)
;   LDS_STORE(0, 0)
;   if (VAR != 4) __syncthreads();
; #pragma unroll
;   for (int kt = 0; kt < nk; kt += 2) {
;     if (kt + 2 < nk) { GL_LOAD(0, kt + 2) }
;     MMA_TILE(0)
;     LDS_STORE(1, 1)
;     if (VAR != 4) __syncthreads();
;     if (kt + 3 < nk) { GL_LOAD(1, kt + 3) }
;     MMA_TILE(1)
;     if (kt + 2 < nk) { LDS_STORE(0, 0) }
;     if (VAR != 4) __syncthreads();
	v_mfma_f32_16x16x32_f16 v[48:51], v[122:125], v[110:113], v[48:51]
	ds_read_b128 v[58:61], v16 offset:32768
	ds_read_b128 v[106:109], v21
	s_waitcnt lgkmcnt(0)
	v_mfma_f32_16x16x32_f16 v[36:39], v[58:61], v[106:109], v[36:39]
	ds_read_b128 v[94:97], v16 offset:34816
	ds_read_b128 v[110:113], v21 offset:2048
	s_waitcnt lgkmcnt(0)
	v_mfma_f32_16x16x32_f16 v[66:69], v[58:61], v[110:113], v[66:69]
	ds_read_b128 v[118:121], v16 offset:36864
	v_mfma_f32_16x16x32_f16 v[44:47], v[94:97], v[106:109], v[44:47]
	ds_read_b128 v[122:125], v16 offset:38912
	v_mfma_f32_16x16x32_f16 v[78:81], v[94:97], v[110:113], v[78:81]
	s_waitcnt vmcnt(7)
	ds_write_b128 v19, v[62:65] offset:16384
	s_waitcnt lgkmcnt(2)
	v_mfma_f32_16x16x32_f16 v[82:85], v[118:121], v[106:109], v[82:85]
	s_waitcnt vmcnt(6)
	ds_write_b128 v20, v[90:93] offset:16384
	v_mfma_f32_16x16x32_f16 v[86:89], v[118:121], v[110:113], v[86:89]
	s_waitcnt vmcnt(5)
	ds_write_b128 v17, v[126:129] offset:16384
	s_waitcnt lgkmcnt(3)
	v_mfma_f32_16x16x32_f16 v[28:31], v[122:125], v[106:109], v[28:31]
	ds_read_b128 v[106:109], v21 offset:4096
	v_mfma_f32_16x16x32_f16 v[32:35], v[122:125], v[110:113], v[32:35]
	ds_read_b128 v[110:113], v21 offset:6144
	s_waitcnt lgkmcnt(1)
	v_mfma_f32_16x16x32_f16 v[98:101], v[58:61], v[106:109], v[98:101]
	s_waitcnt vmcnt(4)
	ds_write_b128 v18, v[130:133] offset:16384
	s_waitcnt lgkmcnt(1)
	v_mfma_f32_16x16x32_f16 v[52:55], v[58:61], v[110:113], v[52:55]
	ds_read_b128 v[58:61], v22 offset:32768
	v_mfma_f32_16x16x32_f16 v[102:105], v[94:97], v[106:109], v[102:105]
	s_waitcnt vmcnt(3)
	ds_write_b128 v19, v[74:77] offset:49152
	v_mfma_f32_16x16x32_f16 v[24:27], v[94:97], v[110:113], v[24:27]
	ds_read_b128 v[94:97], v22 offset:34816
	v_mfma_f32_16x16x32_f16 v[114:117], v[118:121], v[106:109], v[114:117]
	s_waitcnt vmcnt(2)
	ds_write_b128 v20, v[138:141] offset:49152
	v_mfma_f32_16x16x32_f16 v[40:43], v[118:121], v[110:113], v[40:43]
	ds_read_b128 v[118:121], v22 offset:36864
	v_mfma_f32_16x16x32_f16 v[70:73], v[122:125], v[106:109], v[70:73]
	ds_read_b128 v[106:109], v23
	v_mfma_f32_16x16x32_f16 v[48:51], v[122:125], v[110:113], v[48:51]
	ds_read_b128 v[110:113], v23 offset:2048
	s_waitcnt lgkmcnt(1)
	v_mfma_f32_16x16x32_f16 v[36:39], v[58:61], v[106:109], v[36:39]
	ds_read_b128 v[122:125], v22 offset:38912
	s_waitcnt lgkmcnt(1)
	v_mfma_f32_16x16x32_f16 v[66:69], v[58:61], v[110:113], v[66:69]
	s_waitcnt vmcnt(1)
	ds_write_b128 v17, v[142:145] offset:49152
	v_mfma_f32_16x16x32_f16 v[44:47], v[94:97], v[106:109], v[44:47]
	s_waitcnt vmcnt(0)
	ds_write_b128 v18, v[154:157] offset:49152
	v_mfma_f32_16x16x32_f16 v[78:81], v[94:97], v[110:113], v[78:81]
	v_mfma_f32_16x16x32_f16 v[82:85], v[118:121], v[106:109], v[82:85]
	v_mfma_f32_16x16x32_f16 v[86:89], v[118:121], v[110:113], v[86:89]
	s_waitcnt lgkmcnt(2)
	v_mfma_f32_16x16x32_f16 v[28:31], v[122:125], v[106:109], v[28:31]
	ds_read_b128 v[106:109], v23 offset:4096
	v_mfma_f32_16x16x32_f16 v[32:35], v[122:125], v[110:113], v[32:35]
	ds_read_b128 v[110:113], v23 offset:6144
	s_waitcnt lgkmcnt(1)
	v_mfma_f32_16x16x32_f16 v[98:101], v[58:61], v[106:109], v[98:101]
	s_waitcnt lgkmcnt(0)
	v_mfma_f32_16x16x32_f16 v[52:55], v[58:61], v[110:113], v[52:55]
	global_load_dwordx4 v[58:61], v[0:1], off offset:1280
	v_mfma_f32_16x16x32_f16 v[102:105], v[94:97], v[106:109], v[102:105]
	v_mfma_f32_16x16x32_f16 v[24:27], v[94:97], v[110:113], v[24:27]
	v_mfma_f32_16x16x32_f16 v[114:117], v[118:121], v[106:109], v[114:117]
	v_mfma_f32_16x16x32_f16 v[40:43], v[118:121], v[110:113], v[40:43]
	v_mfma_f32_16x16x32_f16 v[70:73], v[122:125], v[106:109], v[70:73]
	global_load_dwordx4 v[106:109], v[2:3], off offset:1280
	global_load_dwordx4 v[134:137], v[4:5], off offset:1280
	global_load_dwordx4 v[158:161], v[6:7], off offset:1280
	global_load_dwordx4 v[94:97], v[8:9], off offset:1280
	global_load_dwordx4 v[162:165], v[10:11], off offset:1280
	global_load_dwordx4 v[166:169], v[12:13], off offset:1280
	global_load_dwordx4 v[190:193], v[14:15], off offset:1280
	s_waitcnt lgkmcnt(0)
	s_barrier
	v_mfma_f32_16x16x32_f16 v[48:51], v[122:125], v[110:113], v[48:51]
	ds_read_b128 v[62:65], v16 offset:49152
	ds_read_b128 v[90:93], v21 offset:16384
	s_waitcnt lgkmcnt(0)
	v_mfma_f32_16x16x32_f16 v[36:39], v[62:65], v[90:93], v[36:39]
	ds_read_b128 v[74:77], v16 offset:51200
	ds_read_b128 v[110:113], v21 offset:18432
	s_waitcnt lgkmcnt(0)
	v_mfma_f32_16x16x32_f16 v[66:69], v[62:65], v[110:113], v[66:69]
	ds_read_b128 v[118:121], v16 offset:53248
	v_mfma_f32_16x16x32_f16 v[44:47], v[74:77], v[90:93], v[44:47]
	ds_read_b128 v[122:125], v16 offset:55296
	v_mfma_f32_16x16x32_f16 v[78:81], v[74:77], v[110:113], v[78:81]
	s_waitcnt vmcnt(7)
	ds_write_b128 v19, v[58:61]
	s_waitcnt lgkmcnt(2)
	v_mfma_f32_16x16x32_f16 v[82:85], v[118:121], v[90:93], v[82:85]
	s_waitcnt vmcnt(6)
	ds_write_b128 v20, v[106:109]
	v_mfma_f32_16x16x32_f16 v[86:89], v[118:121], v[110:113], v[86:89]
	s_waitcnt vmcnt(5)
	ds_write_b128 v17, v[134:137]
	s_waitcnt lgkmcnt(3)
	v_mfma_f32_16x16x32_f16 v[28:31], v[122:125], v[90:93], v[28:31]
	ds_read_b128 v[90:93], v21 offset:20480
	v_mfma_f32_16x16x32_f16 v[32:35], v[122:125], v[110:113], v[32:35]
	ds_read_b128 v[110:113], v21 offset:22528
	s_waitcnt lgkmcnt(1)
	v_mfma_f32_16x16x32_f16 v[98:101], v[62:65], v[90:93], v[98:101]
	s_waitcnt vmcnt(4)
	ds_write_b128 v18, v[158:161]
	s_waitcnt lgkmcnt(1)
	v_mfma_f32_16x16x32_f16 v[52:55], v[62:65], v[110:113], v[52:55]
	ds_read_b128 v[62:65], v22 offset:49152
	v_mfma_f32_16x16x32_f16 v[102:105], v[74:77], v[90:93], v[102:105]
	s_waitcnt vmcnt(3)
; #define GL_LOAD(s_, kt_) if (VAR != 1) { a##s_##0 = GL_A(0, kt_); a##s_##1 = GL_A(1, kt_); a##s_##2 = GL_A(2, kt_); a##s_##3 = GL_A(3, kt_); b##s_##0 = GL_B(0, kt_); b##s_##1 = GL_B(1, kt_); b##s_##2 = GL_B(2, kt_); b##s_##3 = GL_B(3, kt_); }
; #define LDS_STORE(s_, buf_) if (VAR != 2) { LDS_ST1(sA, 0, buf_, a##s_##0) LDS_ST1(sA, 1, buf_, a##s_##1) LDS_ST1(sA, 2, buf_, a##s_##2) LDS_ST1(sA, 3, buf_, a##s_##3) LDS_ST1(sB, 0, buf_, b##s_##0) LDS_ST1(sB, 1, buf_, b##s_##1) LDS_ST1(sB, 2, buf_, b##s_##2) LDS_ST1(sB, 3, buf_, b##s_##3) }
;     ...
;   GL_LOAD(0, 0)
;   GL_LOAD(1, 1)
;   LDS_STORE(0, 0)
;   if (VAR != 4) __syncthreads();
; #pragma unroll
;   for (int kt = 0; kt < nk; kt += 2) {
;     if (kt + 2 < nk) { GL_LOAD(0, kt + 2) }
;     MMA_TILE(0)
;     LDS_STORE(1, 1)
;     if (VAR != 4) __syncthreads();
;     if (kt + 3 < nk) { GL_LOAD(1, kt + 3) }
;     MMA_TILE(1)
;     if (kt + 2 < nk) { LDS_STORE(0, 0) }
;     if (VAR != 4) __syncthreads();
	ds_write_b128 v19, v[94:97] offset:32768
	v_mfma_f32_16x16x32_f16 v[24:27], v[74:77], v[110:113], v[24:27]
	ds_read_b128 v[74:77], v22 offset:51200
	v_mfma_f32_16x16x32_f16 v[114:117], v[118:121], v[90:93], v[114:117]
	s_waitcnt vmcnt(2)
	ds_write_b128 v20, v[162:165] offset:32768
	v_mfma_f32_16x16x32_f16 v[40:43], v[118:121], v[110:113], v[40:43]
	ds_read_b128 v[118:121], v22 offset:53248
	v_mfma_f32_16x16x32_f16 v[70:73], v[122:125], v[90:93], v[70:73]
	ds_read_b128 v[90:93], v23 offset:16384
	v_mfma_f32_16x16x32_f16 v[48:51], v[122:125], v[110:113], v[48:51]
	ds_read_b128 v[110:113], v23 offset:18432
	s_waitcnt lgkmcnt(1)
	v_mfma_f32_16x16x32_f16 v[36:39], v[62:65], v[90:93], v[36:39]
	ds_read_b128 v[122:125], v22 offset:55296
	s_waitcnt lgkmcnt(1)
	v_mfma_f32_16x16x32_f16 v[66:69], v[62:65], v[110:113], v[66:69]
	s_waitcnt vmcnt(1)
	ds_write_b128 v17, v[166:169] offset:32768
	v_mfma_f32_16x16x32_f16 v[44:47], v[74:77], v[90:93], v[44:47]
	s_waitcnt vmcnt(0)
	ds_write_b128 v18, v[190:193] offset:32768
	v_mfma_f32_16x16x32_f16 v[78:81], v[74:77], v[110:113], v[78:81]
	v_mfma_f32_16x16x32_f16 v[82:85], v[118:121], v[90:93], v[82:85]
	v_mfma_f32_16x16x32_f16 v[86:89], v[118:121], v[110:113], v[86:89]
	s_waitcnt lgkmcnt(2)
	v_mfma_f32_16x16x32_f16 v[28:31], v[122:125], v[90:93], v[28:31]
	ds_read_b128 v[90:93], v23 offset:20480
	v_mfma_f32_16x16x32_f16 v[32:35], v[122:125], v[110:113], v[32:35]
	ds_read_b128 v[110:113], v23 offset:22528
	s_waitcnt lgkmcnt(1)
	v_mfma_f32_16x16x32_f16 v[98:101], v[62:65], v[90:93], v[98:101]
	s_waitcnt lgkmcnt(0)
	v_mfma_f32_16x16x32_f16 v[52:55], v[62:65], v[110:113], v[52:55]
	global_load_dwordx4 v[62:65], v[0:1], off offset:1408
	v_mfma_f32_16x16x32_f16 v[102:105], v[74:77], v[90:93], v[102:105]
	v_mfma_f32_16x16x32_f16 v[24:27], v[74:77], v[110:113], v[24:27]
	v_mfma_f32_16x16x32_f16 v[114:117], v[118:121], v[90:93], v[114:117]
	v_mfma_f32_16x16x32_f16 v[40:43], v[118:121], v[110:113], v[40:43]
	v_mfma_f32_16x16x32_f16 v[70:73], v[122:125], v[90:93], v[70:73]
	global_load_dwordx4 v[90:93], v[2:3], off offset:1408
	global_load_dwordx4 v[126:129], v[4:5], off offset:1408
	global_load_dwordx4 v[130:133], v[6:7], off offset:1408
	global_load_dwordx4 v[74:77], v[8:9], off offset:1408
	global_load_dwordx4 v[138:141], v[10:11], off offset:1408
	global_load_dwordx4 v[142:145], v[12:13], off offset:1408
	global_load_dwordx4 v[154:157], v[14:15], off offset:1408
	s_waitcnt lgkmcnt(0)
	s_barrier
	v_mfma_f32_16x16x32_f16 v[48:51], v[122:125], v[110:113], v[48:51]
	ds_read_b128 v[58:61], v16 offset:32768
	ds_read_b128 v[106:109], v21
	s_waitcnt lgkmcnt(0)
	v_mfma_f32_16x16x32_f16 v[36:39], v[58:61], v[106:109], v[36:39]
	ds_read_b128 v[94:97], v16 offset:34816
	ds_read_b128 v[110:113], v21 offset:2048
	s_waitcnt lgkmcnt(0)
	v_mfma_f32_16x16x32_f16 v[66:69], v[58:61], v[110:113], v[66:69]
	ds_read_b128 v[118:121], v16 offset:36864
	v_mfma_f32_16x16x32_f16 v[44:47], v[94:97], v[106:109], v[44:47]
	ds_read_b128 v[122:125], v16 offset:38912
	v_mfma_f32_16x16x32_f16 v[78:81], v[94:97], v[110:113], v[78:81]
	s_waitcnt vmcnt(7)
	ds_write_b128 v19, v[62:65] offset:16384
	s_waitcnt lgkmcnt(2)
	v_mfma_f32_16x16x32_f16 v[82:85], v[118:121], v[106:109], v[82:85]
	s_waitcnt vmcnt(6)
	ds_write_b128 v20, v[90:93] offset:16384
	v_mfma_f32_16x16x32_f16 v[86:89], v[118:121], v[110:113], v[86:89]
	s_waitcnt vmcnt(5)
	ds_write_b128 v17, v[126:129] offset:16384
	s_waitcnt lgkmcnt(3)
	v_mfma_f32_16x16x32_f16 v[28:31], v[122:125], v[106:109], v[28:31]
	ds_read_b128 v[106:109], v21 offset:4096
	v_mfma_f32_16x16x32_f16 v[32:35], v[122:125], v[110:113], v[32:35]
	ds_read_b128 v[110:113], v21 offset:6144
	s_waitcnt lgkmcnt(1)
	v_mfma_f32_16x16x32_f16 v[98:101], v[58:61], v[106:109], v[98:101]
	s_waitcnt vmcnt(4)
	ds_write_b128 v18, v[130:133] offset:16384
	s_waitcnt lgkmcnt(1)
	v_mfma_f32_16x16x32_f16 v[52:55], v[58:61], v[110:113], v[52:55]
	ds_read_b128 v[58:61], v22 offset:32768
	v_mfma_f32_16x16x32_f16 v[102:105], v[94:97], v[106:109], v[102:105]
	s_waitcnt vmcnt(3)
	ds_write_b128 v19, v[74:77] offset:49152
	v_mfma_f32_16x16x32_f16 v[24:27], v[94:97], v[110:113], v[24:27]
	ds_read_b128 v[94:97], v22 offset:34816
	v_mfma_f32_16x16x32_f16 v[114:117], v[118:121], v[106:109], v[114:117]
	s_waitcnt vmcnt(2)
	ds_write_b128 v20, v[138:141] offset:49152
	v_mfma_f32_16x16x32_f16 v[40:43], v[118:121], v[110:113], v[40:43]
	ds_read_b128 v[118:121], v22 offset:36864
	v_mfma_f32_16x16x32_f16 v[70:73], v[122:125], v[106:109], v[70:73]
	ds_read_b128 v[106:109], v23
	v_mfma_f32_16x16x32_f16 v[48:51], v[122:125], v[110:113], v[48:51]
	ds_read_b128 v[110:113], v23 offset:2048
	s_waitcnt lgkmcnt(1)
	v_mfma_f32_16x16x32_f16 v[36:39], v[58:61], v[106:109], v[36:39]
	ds_read_b128 v[122:125], v22 offset:38912
	s_waitcnt lgkmcnt(1)
	v_mfma_f32_16x16x32_f16 v[66:69], v[58:61], v[110:113], v[66:69]
	s_waitcnt vmcnt(1)
	ds_write_b128 v17, v[142:145] offset:49152
	v_mfma_f32_16x16x32_f16 v[44:47], v[94:97], v[106:109], v[44:47]
	s_waitcnt vmcnt(0)
	ds_write_b128 v18, v[154:157] offset:49152
	v_mfma_f32_16x16x32_f16 v[78:81], v[94:97], v[110:113], v[78:81]
	v_mfma_f32_16x16x32_f16 v[82:85], v[118:121], v[106:109], v[82:85]
	v_mfma_f32_16x16x32_f16 v[86:89], v[118:121], v[110:113], v[86:89]
	s_waitcnt lgkmcnt(2)
	v_mfma_f32_16x16x32_f16 v[28:31], v[122:125], v[106:109], v[28:31]
	ds_read_b128 v[106:109], v23 offset:4096
	v_mfma_f32_16x16x32_f16 v[32:35], v[122:125], v[110:113], v[32:35]
	ds_read_b128 v[110:113], v23 offset:6144
	s_waitcnt lgkmcnt(1)
	v_mfma_f32_16x16x32_f16 v[98:101], v[58:61], v[106:109], v[98:101]
	s_waitcnt lgkmcnt(0)
	v_mfma_f32_16x16x32_f16 v[52:55], v[58:61], v[110:113], v[52:55]
	global_load_dwordx4 v[58:61], v[0:1], off offset:1536
	v_mfma_f32_16x16x32_f16 v[102:105], v[94:97], v[106:109], v[102:105]
	v_mfma_f32_16x16x32_f16 v[24:27], v[94:97], v[110:113], v[24:27]
	v_mfma_f32_16x16x32_f16 v[114:117], v[118:121], v[106:109], v[114:117]
	v_mfma_f32_16x16x32_f16 v[40:43], v[118:121], v[110:113], v[40:43]
	v_mfma_f32_16x16x32_f16 v[70:73], v[122:125], v[106:109], v[70:73]
	global_load_dwordx4 v[106:109], v[2:3], off offset:1536
	global_load_dwordx4 v[134:137], v[4:5], off offset:1536
	global_load_dwordx4 v[158:161], v[6:7], off offset:1536
	global_load_dwordx4 v[94:97], v[8:9], off offset:1536
	global_load_dwordx4 v[162:165], v[10:11], off offset:1536
	global_load_dwordx4 v[166:169], v[12:13], off offset:1536
	global_load_dwordx4 v[190:193], v[14:15], off offset:1536
	s_waitcnt lgkmcnt(0)
	s_barrier
; #define GL_LOAD(s_, kt_) if (VAR != 1) { a##s_##0 = GL_A(0, kt_); a##s_##1 = GL_A(1, kt_); a##s_##2 = GL_A(2, kt_); a##s_##3 = GL_A(3, kt_); b##s_##0 = GL_B(0, kt_); b##s_##1 = GL_B(1, kt_); b##s_##2 = GL_B(2, kt_); b##s_##3 = GL_B(3, kt_); }
; #define LDS_STORE(s_, buf_) if (VAR != 2) { LDS_ST1(sA, 0, buf_, a##s_##0) LDS_ST1(sA, 1, buf_, a##s_##1) LDS_ST1(sA, 2, buf_, a##s_##2) LDS_ST1(sA, 3, buf_, a##s_##3) LDS_ST1(sB, 0, buf_, b##s_##0) LDS_ST1(sB, 1, buf_, b##s_##1) LDS_ST1(sB, 2, buf_, b##s_##2) LDS_ST1(sB, 3, buf_, b##s_##3) }
;     ...
;   GL_LOAD(0, 0)
;   GL_LOAD(1, 1)
;   LDS_STORE(0, 0)
;   if (VAR != 4) __syncthreads();
; #pragma unroll
;   for (int kt = 0; kt < nk; kt += 2) {
;     if (kt + 2 < nk) { GL_LOAD(0, kt + 2) }
;     MMA_TILE(0)
;     LDS_STORE(1, 1)
;     if (VAR != 4) __syncthreads();
;     if (kt + 3 < nk) { GL_LOAD(1, kt + 3) }
;     MMA_TILE(1)
;     if (kt + 2 < nk) { LDS_STORE(0, 0) }
;     if (VAR != 4) __syncthreads();
	v_mfma_f32_16x16x32_f16 v[48:51], v[122:125], v[110:113], v[48:51]
	ds_read_b128 v[62:65], v16 offset:49152
	ds_read_b128 v[90:93], v21 offset:16384
	s_waitcnt lgkmcnt(0)
	v_mfma_f32_16x16x32_f16 v[36:39], v[62:65], v[90:93], v[36:39]
	ds_read_b128 v[74:77], v16 offset:51200
	ds_read_b128 v[110:113], v21 offset:18432
	s_waitcnt lgkmcnt(0)
	v_mfma_f32_16x16x32_f16 v[66:69], v[62:65], v[110:113], v[66:69]
	ds_read_b128 v[118:121], v16 offset:53248
	v_mfma_f32_16x16x32_f16 v[44:47], v[74:77], v[90:93], v[44:47]
	ds_read_b128 v[122:125], v16 offset:55296
	v_mfma_f32_16x16x32_f16 v[78:81], v[74:77], v[110:113], v[78:81]
	s_waitcnt vmcnt(7)
	ds_write_b128 v19, v[58:61]
	s_waitcnt lgkmcnt(2)
	v_mfma_f32_16x16x32_f16 v[82:85], v[118:121], v[90:93], v[82:85]
	s_waitcnt vmcnt(6)
	ds_write_b128 v20, v[106:109]
	v_mfma_f32_16x16x32_f16 v[86:89], v[118:121], v[110:113], v[86:89]
	s_waitcnt vmcnt(5)
	ds_write_b128 v17, v[134:137]
	s_waitcnt lgkmcnt(3)
	v_mfma_f32_16x16x32_f16 v[28:31], v[122:125], v[90:93], v[28:31]
	ds_read_b128 v[90:93], v21 offset:20480
	v_mfma_f32_16x16x32_f16 v[32:35], v[122:125], v[110:113], v[32:35]
	ds_read_b128 v[110:113], v21 offset:22528
	s_waitcnt lgkmcnt(1)
	v_mfma_f32_16x16x32_f16 v[98:101], v[62:65], v[90:93], v[98:101]
	s_waitcnt vmcnt(4)
	ds_write_b128 v18, v[158:161]
	s_waitcnt lgkmcnt(1)
	v_mfma_f32_16x16x32_f16 v[52:55], v[62:65], v[110:113], v[52:55]
	ds_read_b128 v[62:65], v22 offset:49152
	v_mfma_f32_16x16x32_f16 v[102:105], v[74:77], v[90:93], v[102:105]
	s_waitcnt vmcnt(3)
	ds_write_b128 v19, v[94:97] offset:32768
	v_mfma_f32_16x16x32_f16 v[24:27], v[74:77], v[110:113], v[24:27]
	ds_read_b128 v[74:77], v22 offset:51200
	v_mfma_f32_16x16x32_f16 v[114:117], v[118:121], v[90:93], v[114:117]
	s_waitcnt vmcnt(2)
	ds_write_b128 v20, v[162:165] offset:32768
	v_mfma_f32_16x16x32_f16 v[40:43], v[118:121], v[110:113], v[40:43]
	ds_read_b128 v[118:121], v22 offset:53248
	v_mfma_f32_16x16x32_f16 v[70:73], v[122:125], v[90:93], v[70:73]
	ds_read_b128 v[90:93], v23 offset:16384
	v_mfma_f32_16x16x32_f16 v[48:51], v[122:125], v[110:113], v[48:51]
	ds_read_b128 v[110:113], v23 offset:18432
	s_waitcnt lgkmcnt(1)
	v_mfma_f32_16x16x32_f16 v[36:39], v[62:65], v[90:93], v[36:39]
	ds_read_b128 v[122:125], v22 offset:55296
	s_waitcnt lgkmcnt(1)
	v_mfma_f32_16x16x32_f16 v[66:69], v[62:65], v[110:113], v[66:69]
	s_waitcnt vmcnt(1)
	ds_write_b128 v17, v[166:169] offset:32768
	v_mfma_f32_16x16x32_f16 v[44:47], v[74:77], v[90:93], v[44:47]
	s_waitcnt vmcnt(0)
	ds_write_b128 v18, v[190:193] offset:32768
	v_mfma_f32_16x16x32_f16 v[78:81], v[74:77], v[110:113], v[78:81]
	v_mfma_f32_16x16x32_f16 v[82:85], v[118:121], v[90:93], v[82:85]
	v_mfma_f32_16x16x32_f16 v[86:89], v[118:121], v[110:113], v[86:89]
	s_waitcnt lgkmcnt(2)
	v_mfma_f32_16x16x32_f16 v[28:31], v[122:125], v[90:93], v[28:31]
	ds_read_b128 v[90:93], v23 offset:20480
	v_mfma_f32_16x16x32_f16 v[32:35], v[122:125], v[110:113], v[32:35]
	ds_read_b128 v[110:113], v23 offset:22528
	s_waitcnt lgkmcnt(1)
	v_mfma_f32_16x16x32_f16 v[98:101], v[62:65], v[90:93], v[98:101]
	s_waitcnt lgkmcnt(0)
	v_mfma_f32_16x16x32_f16 v[52:55], v[62:65], v[110:113], v[52:55]
	global_load_dwordx4 v[62:65], v[0:1], off offset:1664
	v_mfma_f32_16x16x32_f16 v[102:105], v[74:77], v[90:93], v[102:105]
	v_mfma_f32_16x16x32_f16 v[24:27], v[74:77], v[110:113], v[24:27]
	v_mfma_f32_16x16x32_f16 v[114:117], v[118:121], v[90:93], v[114:117]
	v_mfma_f32_16x16x32_f16 v[40:43], v[118:121], v[110:113], v[40:43]
	v_mfma_f32_16x16x32_f16 v[70:73], v[122:125], v[90:93], v[70:73]
	global_load_dwordx4 v[90:93], v[2:3], off offset:1664
	global_load_dwordx4 v[126:129], v[4:5], off offset:1664
	global_load_dwordx4 v[130:133], v[6:7], off offset:1664
	global_load_dwordx4 v[74:77], v[8:9], off offset:1664
	global_load_dwordx4 v[138:141], v[10:11], off offset:1664
	global_load_dwordx4 v[142:145], v[12:13], off offset:1664
	global_load_dwordx4 v[154:157], v[14:15], off offset:1664
	s_waitcnt lgkmcnt(0)
	s_barrier
	v_mfma_f32_16x16x32_f16 v[48:51], v[122:125], v[110:113], v[48:51]
	ds_read_b128 v[58:61], v16 offset:32768
	ds_read_b128 v[106:109], v21
	s_waitcnt lgkmcnt(0)
	v_mfma_f32_16x16x32_f16 v[36:39], v[58:61], v[106:109], v[36:39]
	ds_read_b128 v[94:97], v16 offset:34816
	ds_read_b128 v[110:113], v21 offset:2048
	s_waitcnt lgkmcnt(0)
	v_mfma_f32_16x16x32_f16 v[66:69], v[58:61], v[110:113], v[66:69]
	ds_read_b128 v[118:121], v16 offset:36864
	v_mfma_f32_16x16x32_f16 v[44:47], v[94:97], v[106:109], v[44:47]
	ds_read_b128 v[122:125], v16 offset:38912
	v_mfma_f32_16x16x32_f16 v[78:81], v[94:97], v[110:113], v[78:81]
	s_waitcnt vmcnt(7)
	ds_write_b128 v19, v[62:65] offset:16384
	s_waitcnt lgkmcnt(2)
	v_mfma_f32_16x16x32_f16 v[82:85], v[118:121], v[106:109], v[82:85]
	s_waitcnt vmcnt(6)
	ds_write_b128 v20, v[90:93] offset:16384
	v_mfma_f32_16x16x32_f16 v[86:89], v[118:121], v[110:113], v[86:89]
	s_waitcnt vmcnt(5)
	ds_write_b128 v17, v[126:129] offset:16384
	s_waitcnt lgkmcnt(3)
	v_mfma_f32_16x16x32_f16 v[28:31], v[122:125], v[106:109], v[28:31]
	ds_read_b128 v[106:109], v21 offset:4096
	v_mfma_f32_16x16x32_f16 v[32:35], v[122:125], v[110:113], v[32:35]
	ds_read_b128 v[110:113], v21 offset:6144
	s_waitcnt lgkmcnt(1)
	v_mfma_f32_16x16x32_f16 v[98:101], v[58:61], v[106:109], v[98:101]
	s_waitcnt vmcnt(4)
	ds_write_b128 v18, v[130:133] offset:16384
	s_waitcnt lgkmcnt(1)
	v_mfma_f32_16x16x32_f16 v[52:55], v[58:61], v[110:113], v[52:55]
	ds_read_b128 v[58:61], v22 offset:32768
	v_mfma_f32_16x16x32_f16 v[102:105], v[94:97], v[106:109], v[102:105]
	s_waitcnt vmcnt(3)
; #define GL_LOAD(s_, kt_) if (VAR != 1) { a##s_##0 = GL_A(0, kt_); a##s_##1 = GL_A(1, kt_); a##s_##2 = GL_A(2, kt_); a##s_##3 = GL_A(3, kt_); b##s_##0 = GL_B(0, kt_); b##s_##1 = GL_B(1, kt_); b##s_##2 = GL_B(2, kt_); b##s_##3 = GL_B(3, kt_); }
; #define LDS_STORE(s_, buf_) if (VAR != 2) { LDS_ST1(sA, 0, buf_, a##s_##0) LDS_ST1(sA, 1, buf_, a##s_##1) LDS_ST1(sA, 2, buf_, a##s_##2) LDS_ST1(sA, 3, buf_, a##s_##3) LDS_ST1(sB, 0, buf_, b##s_##0) LDS_ST1(sB, 1, buf_, b##s_##1) LDS_ST1(sB, 2, buf_, b##s_##2) LDS_ST1(sB, 3, buf_, b##s_##3) }
;     ...
;   GL_LOAD(0, 0)
;   GL_LOAD(1, 1)
;   LDS_STORE(0, 0)
;   if (VAR != 4) __syncthreads();
; #pragma unroll
;   for (int kt = 0; kt < nk; kt += 2) {
;     if (kt + 2 < nk) { GL_LOAD(0, kt + 2) }
;     MMA_TILE(0)
;     LDS_STORE(1, 1)
;     if (VAR != 4) __syncthreads();
;     if (kt + 3 < nk) { GL_LOAD(1, kt + 3) }
;     MMA_TILE(1)
;     if (kt + 2 < nk) { LDS_STORE(0, 0) }
;     if (VAR != 4) __syncthreads();
	ds_write_b128 v19, v[74:77] offset:49152
	v_mfma_f32_16x16x32_f16 v[24:27], v[94:97], v[110:113], v[24:27]
	ds_read_b128 v[94:97], v22 offset:34816
	v_mfma_f32_16x16x32_f16 v[114:117], v[118:121], v[106:109], v[114:117]
	s_waitcnt vmcnt(2)
	ds_write_b128 v20, v[138:141] offset:49152
	v_mfma_f32_16x16x32_f16 v[40:43], v[118:121], v[110:113], v[40:43]
	ds_read_b128 v[118:121], v22 offset:36864
	v_mfma_f32_16x16x32_f16 v[70:73], v[122:125], v[106:109], v[70:73]
	ds_read_b128 v[106:109], v23
	v_mfma_f32_16x16x32_f16 v[48:51], v[122:125], v[110:113], v[48:51]
	ds_read_b128 v[110:113], v23 offset:2048
	s_waitcnt lgkmcnt(1)
	v_mfma_f32_16x16x32_f16 v[36:39], v[58:61], v[106:109], v[36:39]
	ds_read_b128 v[122:125], v22 offset:38912
	s_waitcnt lgkmcnt(1)
	v_mfma_f32_16x16x32_f16 v[66:69], v[58:61], v[110:113], v[66:69]
	s_waitcnt vmcnt(1)
	ds_write_b128 v17, v[142:145] offset:49152
	v_mfma_f32_16x16x32_f16 v[44:47], v[94:97], v[106:109], v[44:47]
	s_waitcnt vmcnt(0)
	ds_write_b128 v18, v[154:157] offset:49152
	v_mfma_f32_16x16x32_f16 v[78:81], v[94:97], v[110:113], v[78:81]
	v_mfma_f32_16x16x32_f16 v[82:85], v[118:121], v[106:109], v[82:85]
	v_mfma_f32_16x16x32_f16 v[86:89], v[118:121], v[110:113], v[86:89]
	s_waitcnt lgkmcnt(2)
	v_mfma_f32_16x16x32_f16 v[28:31], v[122:125], v[106:109], v[28:31]
	ds_read_b128 v[106:109], v23 offset:4096
	v_mfma_f32_16x16x32_f16 v[32:35], v[122:125], v[110:113], v[32:35]
	ds_read_b128 v[110:113], v23 offset:6144
	s_waitcnt lgkmcnt(1)
	v_mfma_f32_16x16x32_f16 v[98:101], v[58:61], v[106:109], v[98:101]
	s_waitcnt lgkmcnt(0)
	v_mfma_f32_16x16x32_f16 v[52:55], v[58:61], v[110:113], v[52:55]
	global_load_dwordx4 v[58:61], v[0:1], off offset:1792
	v_mfma_f32_16x16x32_f16 v[102:105], v[94:97], v[106:109], v[102:105]
	v_mfma_f32_16x16x32_f16 v[24:27], v[94:97], v[110:113], v[24:27]
	v_mfma_f32_16x16x32_f16 v[114:117], v[118:121], v[106:109], v[114:117]
	v_mfma_f32_16x16x32_f16 v[40:43], v[118:121], v[110:113], v[40:43]
	v_mfma_f32_16x16x32_f16 v[70:73], v[122:125], v[106:109], v[70:73]
	global_load_dwordx4 v[106:109], v[2:3], off offset:1792
	global_load_dwordx4 v[134:137], v[4:5], off offset:1792
	global_load_dwordx4 v[158:161], v[6:7], off offset:1792
	global_load_dwordx4 v[94:97], v[8:9], off offset:1792
	global_load_dwordx4 v[162:165], v[10:11], off offset:1792
	global_load_dwordx4 v[166:169], v[12:13], off offset:1792
	global_load_dwordx4 v[190:193], v[14:15], off offset:1792
	s_waitcnt lgkmcnt(0)
	s_barrier
	v_mfma_f32_16x16x32_f16 v[48:51], v[122:125], v[110:113], v[48:51]
	ds_read_b128 v[62:65], v16 offset:49152
	ds_read_b128 v[90:93], v21 offset:16384
	s_waitcnt lgkmcnt(0)
	v_mfma_f32_16x16x32_f16 v[36:39], v[62:65], v[90:93], v[36:39]
	ds_read_b128 v[74:77], v16 offset:51200
	ds_read_b128 v[110:113], v21 offset:18432
	s_waitcnt lgkmcnt(0)
	v_mfma_f32_16x16x32_f16 v[66:69], v[62:65], v[110:113], v[66:69]
	ds_read_b128 v[118:121], v16 offset:53248
	v_mfma_f32_16x16x32_f16 v[44:47], v[74:77], v[90:93], v[44:47]
	ds_read_b128 v[122:125], v16 offset:55296
	v_mfma_f32_16x16x32_f16 v[78:81], v[74:77], v[110:113], v[78:81]
	v_or_b32_e32 v130, s11, v56
	s_waitcnt lgkmcnt(1)
	v_mfma_f32_16x16x32_f16 v[82:85], v[118:121], v[90:93], v[82:85]
	v_lshrrev_b32_e32 v150, 4, v130
	v_mfma_f32_16x16x32_f16 v[86:89], v[118:121], v[110:113], v[86:89]
	s_waitcnt vmcnt(7)
	ds_write_b128 v19, v[58:61]
	s_waitcnt lgkmcnt(1)
	v_mfma_f32_16x16x32_f16 v[28:31], v[122:125], v[90:93], v[28:31]
	ds_read_b128 v[90:93], v21 offset:20480
	v_mfma_f32_16x16x32_f16 v[32:35], v[122:125], v[110:113], v[32:35]
	ds_read_b128 v[110:113], v21 offset:22528
	s_waitcnt lgkmcnt(1)
	v_mfma_f32_16x16x32_f16 v[98:101], v[62:65], v[90:93], v[98:101]
	s_waitcnt vmcnt(6)
	ds_write_b128 v20, v[106:109]
	s_waitcnt lgkmcnt(1)
	v_mfma_f32_16x16x32_f16 v[52:55], v[62:65], v[110:113], v[52:55]
	ds_read_b128 v[62:65], v22 offset:49152
	v_mfma_f32_16x16x32_f16 v[102:105], v[74:77], v[90:93], v[102:105]
	s_waitcnt vmcnt(5)
	ds_write_b128 v17, v[134:137]
	v_mfma_f32_16x16x32_f16 v[24:27], v[74:77], v[110:113], v[24:27]
	ds_read_b128 v[74:77], v22 offset:51200
	v_mfma_f32_16x16x32_f16 v[114:117], v[118:121], v[90:93], v[114:117]
	s_waitcnt vmcnt(4)
	ds_write_b128 v18, v[158:161]
	v_mfma_f32_16x16x32_f16 v[40:43], v[118:121], v[110:113], v[40:43]
	ds_read_b128 v[118:121], v22 offset:53248
	v_mfma_f32_16x16x32_f16 v[70:73], v[122:125], v[90:93], v[70:73]
	ds_read_b128 v[90:93], v23 offset:16384
	v_mfma_f32_16x16x32_f16 v[48:51], v[122:125], v[110:113], v[48:51]
	ds_read_b128 v[110:113], v23 offset:18432
	s_waitcnt lgkmcnt(1)
	v_mfma_f32_16x16x32_f16 v[36:39], v[62:65], v[90:93], v[36:39]
	ds_read_b128 v[122:125], v22 offset:55296
	s_waitcnt lgkmcnt(1)
	v_mfma_f32_16x16x32_f16 v[66:69], v[62:65], v[110:113], v[66:69]
	s_waitcnt vmcnt(3)
	ds_write_b128 v19, v[94:97] offset:32768
	v_mfma_f32_16x16x32_f16 v[44:47], v[74:77], v[90:93], v[44:47]
	s_waitcnt vmcnt(2)
	ds_write_b128 v20, v[162:165] offset:32768
	v_mfma_f32_16x16x32_f16 v[78:81], v[74:77], v[110:113], v[78:81]
	s_waitcnt vmcnt(1)
	ds_write_b128 v17, v[166:169] offset:32768
	v_mfma_f32_16x16x32_f16 v[82:85], v[118:121], v[90:93], v[82:85]
	s_waitcnt vmcnt(0)
	ds_write_b128 v18, v[190:193] offset:32768
	v_mfma_f32_16x16x32_f16 v[86:89], v[118:121], v[110:113], v[86:89]
	s_waitcnt lgkmcnt(4)
	v_mfma_f32_16x16x32_f16 v[28:31], v[122:125], v[90:93], v[28:31]
	ds_read_b128 v[90:93], v23 offset:20480
	v_mfma_f32_16x16x32_f16 v[32:35], v[122:125], v[110:113], v[32:35]
	ds_read_b128 v[110:113], v23 offset:22528
	s_waitcnt lgkmcnt(1)
	v_mfma_f32_16x16x32_f16 v[98:101], v[62:65], v[90:93], v[98:101]
	s_waitcnt lgkmcnt(0)
	v_mfma_f32_16x16x32_f16 v[52:55], v[62:65], v[110:113], v[52:55]
	global_load_dwordx4 v[62:65], v[0:1], off offset:1920
	global_load_dwordx4 v[0:3], v[2:3], off offset:1920
	v_mfma_f32_16x16x32_f16 v[102:105], v[74:77], v[90:93], v[102:105]
	v_mfma_f32_16x16x32_f16 v[24:27], v[74:77], v[110:113], v[24:27]
	v_mfma_f32_16x16x32_f16 v[114:117], v[118:121], v[90:93], v[114:117]
	v_mfma_f32_16x16x32_f16 v[40:43], v[118:121], v[110:113], v[40:43]
	v_mfma_f32_16x16x32_f16 v[70:73], v[122:125], v[90:93], v[70:73]
	global_load_dwordx4 v[90:93], v[4:5], off offset:1920
	global_load_dwordx4 v[4:7], v[6:7], off offset:1920
	global_load_dwordx4 v[74:77], v[8:9], off offset:1920
	global_load_dwordx4 v[8:11], v[10:11], off offset:1920
	global_load_dwordx4 v[126:129], v[12:13], off offset:1920
	global_load_dwordx4 v[12:15], v[14:15], off offset:1920
	s_waitcnt lgkmcnt(0)
	s_barrier
; #define GL_LOAD(s_, kt_) if (VAR != 1) { a##s_##0 = GL_A(0, kt_); a##s_##1 = GL_A(1, kt_); a##s_##2 = GL_A(2, kt_); a##s_##3 = GL_A(3, kt_); b##s_##0 = GL_B(0, kt_); b##s_##1 = GL_B(1, kt_); b##s_##2 = GL_B(2, kt_); b##s_##3 = GL_B(3, kt_); }
; #define LDS_STORE(s_, buf_) if (VAR != 2) { LDS_ST1(sA, 0, buf_, a##s_##0) LDS_ST1(sA, 1, buf_, a##s_##1) LDS_ST1(sA, 2, buf_, a##s_##2) LDS_ST1(sA, 3, buf_, a##s_##3) LDS_ST1(sB, 0, buf_, b##s_##0) LDS_ST1(sB, 1, buf_, b##s_##1) LDS_ST1(sB, 2, buf_, b##s_##2) LDS_ST1(sB, 3, buf_, b##s_##3) }
;     ...
;   GL_LOAD(0, 0)
;   GL_LOAD(1, 1)
;   LDS_STORE(0, 0)
;   if (VAR != 4) __syncthreads();
; #pragma unroll
;   for (int kt = 0; kt < nk; kt += 2) {
;     if (kt + 2 < nk) { GL_LOAD(0, kt + 2) }
;     MMA_TILE(0)
;     LDS_STORE(1, 1)
;     if (VAR != 4) __syncthreads();
;     if (kt + 3 < nk) { GL_LOAD(1, kt + 3) }
;     MMA_TILE(1)
;     if (kt + 2 < nk) { LDS_STORE(0, 0) }
;     if (VAR != 4) __syncthreads();
	ds_read_b128 v[58:61], v16 offset:32768
	v_mfma_f32_16x16x32_f16 v[48:51], v[122:125], v[110:113], v[48:51]
	ds_read_b128 v[94:97], v16 offset:34816
	ds_read_b128 v[106:109], v21
	ds_read_b128 v[110:113], v21 offset:2048
	ds_read_b128 v[118:121], v16 offset:36864
	ds_read_b128 v[122:125], v16 offset:38912
	s_waitcnt lgkmcnt(3)
	v_mfma_f32_16x16x32_f16 v[36:39], v[58:61], v[106:109], v[36:39]
	v_mfma_f32_16x16x32_f16 v[44:47], v[94:97], v[106:109], v[44:47]
	s_waitcnt lgkmcnt(1)
	v_mfma_f32_16x16x32_f16 v[82:85], v[118:121], v[106:109], v[82:85]
	s_waitcnt lgkmcnt(0)
	v_mfma_f32_16x16x32_f16 v[28:31], v[122:125], v[106:109], v[28:31]
	v_mfma_f32_16x16x32_f16 v[66:69], v[58:61], v[110:113], v[66:69]
	v_mfma_f32_16x16x32_f16 v[78:81], v[94:97], v[110:113], v[78:81]
	v_mfma_f32_16x16x32_f16 v[86:89], v[118:121], v[110:113], v[86:89]
	v_mfma_f32_16x16x32_f16 v[32:35], v[122:125], v[110:113], v[32:35]
	ds_read_b128 v[106:109], v21 offset:4096
	ds_read_b128 v[110:113], v21 offset:6144
	s_waitcnt lgkmcnt(1)
	v_mfma_f32_16x16x32_f16 v[98:101], v[58:61], v[106:109], v[98:101]
	v_mfma_f32_16x16x32_f16 v[102:105], v[94:97], v[106:109], v[102:105]
	v_mfma_f32_16x16x32_f16 v[114:117], v[118:121], v[106:109], v[114:117]
	v_mfma_f32_16x16x32_f16 v[70:73], v[122:125], v[106:109], v[70:73]
	s_waitcnt lgkmcnt(0)
	v_mfma_f32_16x16x32_f16 v[52:55], v[58:61], v[110:113], v[52:55]
	ds_read_b128 v[58:61], v22 offset:32768
	v_mfma_f32_16x16x32_f16 v[24:27], v[94:97], v[110:113], v[24:27]
	v_mfma_f32_16x16x32_f16 v[40:43], v[118:121], v[110:113], v[40:43]
	v_mfma_f32_16x16x32_f16 v[48:51], v[122:125], v[110:113], v[48:51]
	ds_read_b128 v[94:97], v22 offset:34816
	ds_read_b128 v[106:109], v23
	ds_read_b128 v[110:113], v23 offset:2048
	ds_read_b128 v[118:121], v22 offset:36864
	ds_read_b128 v[122:125], v22 offset:38912
	s_waitcnt lgkmcnt(3)
	v_mfma_f32_16x16x32_f16 v[36:39], v[58:61], v[106:109], v[36:39]
	v_mfma_f32_16x16x32_f16 v[44:47], v[94:97], v[106:109], v[44:47]
	s_waitcnt lgkmcnt(1)
	v_mfma_f32_16x16x32_f16 v[82:85], v[118:121], v[106:109], v[82:85]
	s_waitcnt lgkmcnt(0)
	v_mfma_f32_16x16x32_f16 v[28:31], v[122:125], v[106:109], v[28:31]
	v_mfma_f32_16x16x32_f16 v[66:69], v[58:61], v[110:113], v[66:69]
	v_mfma_f32_16x16x32_f16 v[78:81], v[94:97], v[110:113], v[78:81]
	v_mfma_f32_16x16x32_f16 v[86:89], v[118:121], v[110:113], v[86:89]
	v_mfma_f32_16x16x32_f16 v[32:35], v[122:125], v[110:113], v[32:35]
	ds_read_b128 v[106:109], v23 offset:4096
	ds_read_b128 v[110:113], v23 offset:6144
	s_waitcnt vmcnt(7)
	ds_write_b128 v19, v[62:65] offset:16384
	s_waitcnt vmcnt(6)
	ds_write_b128 v20, v[0:3] offset:16384
	s_waitcnt vmcnt(5)
	ds_write_b128 v17, v[90:93] offset:16384
	s_waitcnt vmcnt(4)
	ds_write_b128 v18, v[4:7] offset:16384
	s_waitcnt vmcnt(3)
	ds_write_b128 v19, v[74:77] offset:49152
	s_waitcnt vmcnt(2)
	ds_write_b128 v20, v[8:11] offset:49152
	s_waitcnt lgkmcnt(7)
	v_mfma_f32_16x16x32_f16 v[98:101], v[58:61], v[106:109], v[98:101]
	s_waitcnt vmcnt(1)
	ds_write_b128 v17, v[126:129] offset:49152
	s_waitcnt vmcnt(0)
	ds_write_b128 v18, v[12:15] offset:49152
	s_waitcnt lgkmcnt(0)
	s_barrier
	v_mfma_f32_16x16x32_f16 v[52:55], v[58:61], v[110:113], v[52:55]
	ds_read_b128 v[8:11], v16 offset:49152
	v_mfma_f32_16x16x32_f16 v[0:3], v[94:97], v[110:113], v[24:27]
	v_mfma_f32_16x16x32_f16 v[4:7], v[118:121], v[110:113], v[40:43]
	v_mfma_f32_16x16x32_f16 v[12:15], v[122:125], v[110:113], v[48:51]
	s_nop 0
	ds_read_b128 v[24:27], v16 offset:51200
	ds_read_b128 v[40:43], v21 offset:16384
	ds_read_b128 v[48:51], v21 offset:18432
	ds_read_b128 v[58:61], v16 offset:53248
	ds_read_b128 v[16:19], v16 offset:55296
	v_mfma_f32_16x16x32_f16 v[102:105], v[94:97], v[106:109], v[102:105]
	v_mfma_f32_16x16x32_f16 v[114:117], v[118:121], v[106:109], v[114:117]
	v_mfma_f32_16x16x32_f16 v[70:73], v[122:125], v[106:109], v[70:73]
	s_waitcnt lgkmcnt(3)
	v_mfma_f32_16x16x32_f16 v[36:39], v[8:11], v[40:43], v[36:39]
	v_mfma_f32_16x16x32_f16 v[44:47], v[24:27], v[40:43], v[44:47]
	s_waitcnt lgkmcnt(1)
	v_mfma_f32_16x16x32_f16 v[62:65], v[58:61], v[40:43], v[82:85]
	ds_read_b128 v[74:77], v21 offset:20480
	s_nop 1
	ds_read_b128 v[82:85], v21 offset:22528
	s_waitcnt lgkmcnt(2)
	v_mfma_f32_16x16x32_f16 v[28:31], v[16:19], v[40:43], v[28:31]
	ds_read_b128 v[40:43], v23 offset:16384
	ds_read_b128 v[90:93], v23 offset:18432
	ds_read_b128 v[94:97], v22 offset:49152
	ds_read_b128 v[106:109], v22 offset:51200
	ds_read_b128 v[110:113], v23 offset:20480
	ds_read_b128 v[118:121], v23 offset:22528
	ds_read_b128 v[122:125], v22 offset:53248
	ds_read_b128 v[126:129], v22 offset:55296
	s_waitcnt lgkmcnt(0)
	v_mfma_f32_16x16x32_f16 v[20:23], v[24:27], v[48:51], v[78:81]
	s_barrier
; DI int TIDX() { int t = threadIdx.x; asm volatile("" : "+v"(t)); return t; }
; DI unsigned pack2(float lo, float hi) { f2_t v = {lo, hi}; h2_t b = __builtin_convertvector(v, h2_t); return __builtin_bit_cast(unsigned, b); }
; DI void epi_residual(const f32x4 (&v)[4][4], int row0, int col0, const float* xsrc, float* x, bf16_t* xb, float* ssq_out, bool write_xb, bool write_ssq) {
;   const int lane = TIDX() & 63, lr = lane & 15, g = lane >> 4;
; #pragma unroll
;   for (int mt = 0; mt < 4; ++mt) {
;     const int row = row0 + mt * 16 + lr;
;     float ss = 0.f;
; #pragma unroll
;     for (int nt = 0; nt < 4; ++nt) {
;       const int col = col0 + nt * 16 + 4 * g;
;       float4* px = (float4*)(x + (size_t)row * DM + col);
;       float4 o = *(const float4*)(xsrc + (size_t)row * DM + col);
;       o.x += v[mt][nt][0]; o.y += v[mt][nt][1]; o.z += v[mt][nt][2]; o.w += v[mt][nt][3];
;       *px = o;
;       ss += (o.x * o.x + o.y * o.y) + (o.z * o.z + o.w * o.w);
;       if (write_xb) *(uint2*)(xb + (size_t)row * DM + col) = make_uint2(pack2(o.x, o.y), pack2(o.z, o.w));
;     }
;     if (write_ssq) {
;       ss += __shfl_xor(ss, 16); ss += __shfl_xor(ss, 32);
;       if (g == 0) ssq_out[(size_t)row * 16 + (col0 >> 6)] = ss;
;     }
;   }
; }
	s_setprio 0
	v_mfma_f32_16x16x32_f16 v[78:81], v[58:61], v[48:51], v[86:89]
	s_nop 2
	v_add_u32_e32 v86, s6, v57
	v_mov_b32_e32 v87, v148
	v_mfma_f32_16x16x32_f16 v[66:69], v[8:11], v[48:51], v[66:69]
	v_readlane_b32 s6, v254, 41
	v_bfe_u32 v134, v87, 4, 2
	v_mfma_f32_16x16x32_f16 v[32:35], v[16:19], v[48:51], v[32:35]
	v_and_or_b32 v50, v87, 15, v86
	v_ashrrev_i32_e32 v51, 31, v50
	v_lshl_or_b32 v135, v134, 2, v130
	v_readlane_b32 s7, v254, 42
	v_lshlrev_b64 v[130:131], 12, v[50:51]
	v_lshl_add_u64 v[132:133], s[4:5], 0, v[130:131]
	v_lshl_add_u64 v[48:49], s[6:7], 0, v[150:151]
	v_lshlrev_b32_e32 v150, 2, v135
	v_lshl_add_u64 v[132:133], v[132:133], 0, v[150:151]
	v_mfma_f32_16x16x32_f16 v[86:89], v[8:11], v[74:77], v[98:101]
	v_readlane_b32 s6, v254, 43
	v_readlane_b32 s7, v254, 44
	v_cmp_eq_u32_e32 vcc, 0, v134
	v_mfma_f32_16x16x32_f16 v[98:101], v[24:27], v[74:77], v[102:105]
	v_mfma_f32_16x16x32_f16 v[102:105], v[58:61], v[74:77], v[114:117]
	s_nop 2
	global_load_dwordx4 v[114:117], v[132:133], off
	v_mfma_f32_16x16x32_f16 v[36:39], v[94:97], v[40:43], v[36:39]
	v_mfma_f32_16x16x32_f16 v[70:73], v[16:19], v[74:77], v[70:73]
	v_lshlrev_b64 v[76:77], 11, v[50:51]
	v_lshl_add_u64 v[74:75], s[12:13], 0, v[130:131]
	v_lshl_add_u64 v[76:77], s[6:7], 0, v[76:77]
	v_mfma_f32_16x16x32_f16 v[8:11], v[8:11], v[82:85], v[52:55]
	v_lshl_add_u64 v[74:75], v[74:75], 0, v[150:151]
	s_waitcnt vmcnt(0)
	s_nop 0
	v_pk_add_f32 v[36:37], v[36:37], v[114:115]
	v_pk_add_f32 v[38:39], v[38:39], v[116:117]
	v_lshlrev_b32_e32 v52, 1, v135
	v_mov_b32_e32 v53, v151
	v_cvt_pk_f16_f32 v54, v36, v37
	v_cvt_pk_f16_f32 v55, v38, v39
	v_lshl_add_u64 v[76:77], v[76:77], 0, v[52:53]
	global_store_dwordx4 v[74:75], v[36:39], off
	v_mov_b32_e32 v136, v54
	v_mov_b32_e32 v137, v55
	v_mfma_f32_16x16x32_f16 v[0:3], v[24:27], v[82:85], v[0:3]
	v_mul_f32_e64 v54, v36, v36
	v_mul_f32_e64 v55, v37, v37
	v_mfma_f32_16x16x32_f16 v[24:27], v[106:109], v[40:43], v[44:47]
	s_nop 2
	global_load_dwordx4 v[44:47], v[132:133], off offset:64
	v_mfma_f32_16x16x32_f16 v[4:7], v[58:61], v[82:85], v[4:7]
	s_waitcnt vmcnt(0)
	s_nop 1
	v_pk_add_f32 v[24:25], v[24:25], v[44:45]
	v_pk_add_f32 v[26:27], v[26:27], v[46:47]
	v_cvt_pk_f16_f32 v44, v24, v25
	v_cvt_pk_f16_f32 v45, v26, v27
	global_store_dwordx4 v[74:75], v[24:27], off offset:64
	v_mov_b32_e32 v138, v44
	v_mov_b32_e32 v139, v45
	v_and_b32_e32 v144, 16, v148
	v_lshrrev_b32_e32 v145, 1, v144
	v_add_u32_e32 v144, v144, v145
	v_mov_b32_e32 v145, 0
	v_lshl_add_u64 v[144:145], v[144:145], 0, v[76:77]
	v_permlane16_swap_b32_e32 v136, v138
	v_permlane16_swap_b32_e32 v137, v139
	global_store_dwordx4 v[144:145], v[136:139], off
	v_mfma_f32_16x16x32_f16 v[58:61], v[16:19], v[82:85], v[12:15]
	s_nop 2
	global_load_dwordx4 v[12:15], v[132:133], off offset:128
	v_mfma_f32_16x16x32_f16 v[16:19], v[122:125], v[40:43], v[62:65]
	v_mfma_f32_16x16x32_f16 v[44:47], v[94:97], v[90:93], v[66:69]
	s_nop 2
	v_mul_f32_e64 v66, v26, v26
	v_mul_f32_e64 v67, v27, v27
	v_mfma_f32_16x16x32_f16 v[32:35], v[126:129], v[90:93], v[32:35]
	s_waitcnt vmcnt(0)
	v_pk_add_f32 v[12:13], v[16:17], v[12:13]
	v_pk_add_f32 v[14:15], v[18:19], v[14:15]
	v_mfma_f32_16x16x32_f16 v[16:19], v[126:129], v[40:43], v[28:31]
	global_store_dwordx4 v[74:75], v[12:15], off offset:128
	s_nop 1
	v_cvt_pk_f16_f32 v28, v12, v13
	v_cvt_pk_f16_f32 v29, v14, v15
	v_mov_b32_e32 v140, v28
	v_mov_b32_e32 v141, v29
	global_load_dwordx4 v[28:31], v[132:133], off offset:192
	v_mfma_f32_16x16x32_f16 v[40:43], v[106:109], v[90:93], v[20:23]
	v_mul_f32_e64 v12, v12, v12
	v_mul_f32_e64 v13, v13, v13
	v_pk_mul_f32 v[14:15], v[14:15], v[14:15]
	v_add_f32_e32 v12, v12, v13
	v_pk_mul_f32 v[20:21], v[38:39], v[38:39]
	v_pk_mul_f32 v[22:23], v[24:25], v[24:25]
	v_add_f32_e32 v14, v14, v15
	v_add_f32_e32 v12, v12, v14
	v_mfma_f32_16x16x32_f16 v[36:39], v[122:125], v[90:93], v[78:81]
	s_waitcnt vmcnt(0)
	v_pk_add_f32 v[62:63], v[16:17], v[28:29]
	v_add_f32_e32 v16, v20, v21
	v_add_f32_e32 v17, v54, v55
	v_pk_add_f32 v[64:65], v[18:19], v[30:31]
	v_add_f32_e32 v16, v17, v16
	v_add_f32_e32 v17, v66, v67
	v_add_f32_e32 v18, v22, v23
	v_add_f32_e32 v17, v18, v17
	global_store_dwordx4 v[74:75], v[62:65], off offset:192
	v_pk_mul_f32 v[68:69], v[62:63], v[62:63]
	v_pk_mul_f32 v[74:75], v[64:65], v[64:65]
	v_add_f32_e32 v54, v16, v17
	v_add_f32_e32 v54, v54, v12
	v_mfma_f32_16x16x32_f16 v[12:15], v[94:97], v[118:121], v[8:11]
	s_nop 2
	v_add_f32_e32 v8, v74, v75
	v_add_f32_e32 v9, v68, v69
	v_add_f32_e32 v55, v9, v8
	v_mfma_f32_16x16x32_f16 v[8:11], v[106:109], v[118:121], v[0:3]
	s_nop 2
	v_add_f32_e32 v2, v54, v55
	ds_bpermute_b32 v3, v189, v2
	v_cvt_pk_f16_f32 v0, v62, v63
	v_cvt_pk_f16_f32 v1, v64, v65
	v_mfma_f32_16x16x32_f16 v[28:31], v[94:97], v[110:113], v[86:89]
	v_mov_b32_e32 v142, v0
	v_mov_b32_e32 v143, v1
	v_and_b32_e32 v144, 16, v148
	v_lshrrev_b32_e32 v145, 1, v144
	v_add_u32_e32 v144, v144, v145
	v_mov_b32_e32 v145, 0
	v_lshl_add_u64 v[144:145], v[144:145], 0, v[76:77]
	v_permlane16_swap_b32_e32 v140, v142
	v_permlane16_swap_b32_e32 v141, v143
	global_store_dwordx4 v[144:145], v[140:143], off offset:64
	s_waitcnt lgkmcnt(0)
	v_add_f32_e32 v54, v2, v3
	ds_bpermute_b32 v55, v188, v54
	v_mfma_f32_16x16x32_f16 v[24:27], v[106:109], v[110:113], v[98:101]
	v_mfma_f32_16x16x32_f16 v[20:23], v[122:125], v[110:113], v[102:105]
	v_mfma_f32_16x16x32_f16 v[16:19], v[126:129], v[110:113], v[70:73]
	v_mfma_f32_16x16x32_f16 v[4:7], v[122:125], v[118:121], v[4:7]
	v_mfma_f32_16x16x32_f16 v[0:3], v[126:129], v[118:121], v[58:61]
	s_and_saveexec_b64 s[6:7], vcc
	s_cbranch_execz .LBB0_1252
	s_waitcnt lgkmcnt(0)
	v_add_f32_e32 v58, v54, v55
	v_lshlrev_b64 v[54:55], 6, v[50:51]
	v_lshl_add_u64 v[54:55], v[48:49], 0, v[54:55]
	global_store_dword v[54:55], v58, off

; #define GL_LOAD(s_, kt_) if (VAR != 1) { a##s_##0 = GL_A(0, kt_); a##s_##1 = GL_A(1, kt_); a##s_##2 = GL_A(2, kt_); a##s_##3 = GL_A(3, kt_); b##s_##0 = GL_B(0, kt_); b##s_##1 = GL_B(1, kt_); b##s_##2 = GL_B(2, kt_); b##s_##3 = GL_B(3, kt_); }
; #define LDS_STORE(s_, buf_) if (VAR != 2) { LDS_ST1(sA, 0, buf_, a##s_##0) LDS_ST1(sA, 1, buf_, a##s_##1) LDS_ST1(sA, 2, buf_, a##s_##2) LDS_ST1(sA, 3, buf_, a##s_##3) LDS_ST1(sB, 0, buf_, b##s_##0) LDS_ST1(sB, 1, buf_, b##s_##1) LDS_ST1(sB, 2, buf_, b##s_##2) LDS_ST1(sB, 3, buf_, b##s_##3) }
;     ...
;   GL_LOAD(0, 0)
;   GL_LOAD(1, 1)
;   LDS_STORE(0, 0)
;   if (VAR != 4) __syncthreads();
; #pragma unroll
;   for (int kt = 0; kt < nk; kt += 2) {
;     if (kt + 2 < nk) { GL_LOAD(0, kt + 2) }
;     MMA_TILE(0)
;     LDS_STORE(1, 1)
;     if (VAR != 4) __syncthreads();
;     if (kt + 3 < nk) { GL_LOAD(1, kt + 3) }
;     MMA_TILE(1)
;     if (kt + 2 < nk) { LDS_STORE(0, 0) }
;     if (VAR != 4) __syncthreads();
.Lp6d_join:
	s_barrier
	s_setprio 2
	ds_read_b128 v[64:67], v133
	ds_read_b128 v[68:71], v136 offset:32768
	s_waitcnt lgkmcnt(0)
	v_mfma_f32_16x16x32_f16 v[138:141], v[68:71], v[64:67], 0
	ds_read_b128 v[72:75], v133 offset:2048
	ds_read_b128 v[76:79], v136 offset:34816
	s_waitcnt lgkmcnt(1)
	v_mfma_f32_16x16x32_f16 v[158:161], v[68:71], v[72:75], 0
	ds_read_b128 v[80:83], v133 offset:4096
	ds_read_b128 v[84:87], v136 offset:36864
	s_waitcnt lgkmcnt(2)
	v_mfma_f32_16x16x32_f16 v[142:145], v[76:79], v[64:67], 0
	ds_read_b128 v[88:91], v133 offset:6144
	ds_read_b128 v[92:95], v136 offset:38912
	v_mfma_f32_16x16x32_f16 v[162:165], v[76:79], v[72:75], 0
	ds_read_b128 v[202:205], v135 offset:32768
	ds_read_b128 v[206:209], v134 offset:2048
	s_waitcnt lgkmcnt(5)
	v_mfma_f32_16x16x32_f16 v[190:193], v[68:71], v[80:83], 0
	ds_read_b128 v[210:213], v135 offset:34816
	ds_read_b128 v[220:223], v134 offset:4096
	s_waitcnt lgkmcnt(5)
	v_mfma_f32_16x16x32_f16 v[68:71], v[68:71], v[88:91], 0
	ds_read_b128 v[224:227], v135 offset:36864
	v_mfma_f32_16x16x32_f16 v[194:197], v[76:79], v[80:83], 0
	ds_read_b128 v[228:231], v134 offset:6144
	v_mfma_f32_16x16x32_f16 v[76:79], v[76:79], v[88:91], 0
	ds_read_b128 v[232:235], v135 offset:38912
	v_mfma_f32_16x16x32_f16 v[154:157], v[84:87], v[64:67], 0
	v_mfma_f32_16x16x32_f16 v[166:169], v[84:87], v[72:75], 0
	s_waitcnt lgkmcnt(7)
	v_mfma_f32_16x16x32_f16 v[64:67], v[92:95], v[64:67], 0
	v_mfma_f32_16x16x32_f16 v[72:75], v[92:95], v[72:75], 0
	v_mfma_f32_16x16x32_f16 v[198:201], v[84:87], v[80:83], 0
	v_and_b32_e32 v62, 7, v148
	v_bfe_u32 v63, v148, 4, 3
	v_xor_b32_e32 v63, v63, v62
	v_sub_u32_e32 v63, v63, v62
	v_lshlrev_b32_e32 v62, 4, v63
	v_add_u32_e32 v62, 0x80, v62
	v_ashrrev_i32_e32 v63, 31, v62
	v_mfma_f32_16x16x32_f16 v[84:87], v[84:87], v[88:91], 0
	v_lshl_add_u64 v[32:33], v[108:109], 0, v[62:63]
	s_mov_b32 m0, s61
	s_nop 0
	global_load_lds_dwordx4 v[32:33], off
	v_lshl_add_u64 v[36:37], v[110:111], 0, v[62:63]
	s_mov_b32 m0, s69
	s_nop 0
	global_load_lds_dwordx4 v[36:37], off
	v_mfma_f32_16x16x32_f16 v[80:83], v[92:95], v[80:83], 0
	v_lshl_add_u64 v[40:41], v[112:113], 0, v[62:63]
	s_mov_b32 m0, s73
	s_nop 0
	global_load_lds_dwordx4 v[40:41], off
	v_lshl_add_u64 v[44:45], v[114:115], 0, v[62:63]
	s_mov_b32 m0, s65
	s_nop 0
	global_load_lds_dwordx4 v[44:45], off
	v_mfma_f32_16x16x32_f16 v[88:91], v[92:95], v[88:91], 0
	ds_read_b128 v[92:95], v134
	v_lshl_add_u64 v[48:49], v[116:117], 0, v[62:63]
	s_mov_b32 m0, s63
	s_nop 0
	global_load_lds_dwordx4 v[48:49], off
	v_lshl_add_u64 v[52:53], v[118:119], 0, v[62:63]
	s_mov_b32 m0, s71
	s_nop 0
	global_load_lds_dwordx4 v[52:53], off
	v_lshl_add_u64 v[56:57], v[120:121], 0, v[62:63]
	s_mov_b32 m0, s75
	s_nop 0
	global_load_lds_dwordx4 v[56:57], off
	v_lshl_add_u64 v[60:61], v[122:123], 0, v[62:63]
	s_mov_b32 m0, s67
	s_nop 0
	global_load_lds_dwordx4 v[60:61], off
	s_waitcnt vmcnt(0) lgkmcnt(0)
	s_barrier
	v_mfma_f32_16x16x32_f16 v[138:141], v[202:205], v[92:95], v[138:141]
	v_mfma_f32_16x16x32_f16 v[142:145], v[210:213], v[92:95], v[142:145]
	v_mfma_f32_16x16x32_f16 v[154:157], v[224:227], v[92:95], v[154:157]
	v_mfma_f32_16x16x32_f16 v[64:67], v[232:235], v[92:95], v[64:67]
	v_mfma_f32_16x16x32_f16 v[92:95], v[202:205], v[206:209], v[158:161]
	v_mfma_f32_16x16x32_f16 v[158:161], v[210:213], v[206:209], v[162:165]
	v_mfma_f32_16x16x32_f16 v[162:165], v[224:227], v[206:209], v[166:169]
	v_mfma_f32_16x16x32_f16 v[166:169], v[202:205], v[220:223], v[190:193]
	v_mfma_f32_16x16x32_f16 v[68:71], v[202:205], v[228:231], v[68:71]
	ds_read_b128 v[202:205], v136 offset:49152
	v_mfma_f32_16x16x32_f16 v[190:193], v[210:213], v[220:223], v[194:197]
	v_mfma_f32_16x16x32_f16 v[76:79], v[210:213], v[228:231], v[76:79]
	ds_read_b128 v[210:213], v136 offset:51200
	v_and_b32_e32 v30, 7, v148
	v_bfe_u32 v31, v148, 4, 3
	v_xor_b32_e32 v31, v31, v30
	v_sub_u32_e32 v31, v31, v30
	v_lshlrev_b32_e32 v30, 4, v31
	v_add_u32_e32 v30, 0x100, v30
	v_ashrrev_i32_e32 v31, 31, v30
	v_mfma_f32_16x16x32_f16 v[72:75], v[232:235], v[206:209], v[72:75]
	ds_read_b128 v[206:209], v133 offset:18432
	v_mfma_f32_16x16x32_f16 v[194:197], v[224:227], v[220:223], v[198:201]
	s_nop 2
	ds_read_b128 v[198:201], v133 offset:16384
	v_mfma_f32_16x16x32_f16 v[84:87], v[224:227], v[228:231], v[84:87]
	ds_read_b128 v[224:227], v136 offset:53248
	v_mfma_f32_16x16x32_f16 v[80:83], v[232:235], v[220:223], v[80:83]
	ds_read_b128 v[220:223], v133 offset:20480
	v_mfma_f32_16x16x32_f16 v[88:91], v[232:235], v[228:231], v[88:91]
	ds_read_b128 v[228:231], v133 offset:22528
	s_waitcnt lgkmcnt(3)
	v_mfma_f32_16x16x32_f16 v[138:141], v[202:205], v[198:201], v[138:141]
	ds_read_b128 v[232:235], v136 offset:55296
	v_mfma_f32_16x16x32_f16 v[92:95], v[202:205], v[206:209], v[92:95]
	v_lshl_add_u64 v[0:1], v[108:109], 0, v[30:31]
	s_mov_b32 m0, s60
	s_nop 0
	global_load_lds_dwordx4 v[0:1], off
	v_mfma_f32_16x16x32_f16 v[142:145], v[210:213], v[198:201], v[142:145]
	v_lshl_add_u64 v[4:5], v[110:111], 0, v[30:31]
	s_mov_b32 m0, s68
	s_nop 0
	global_load_lds_dwordx4 v[4:5], off
	v_mfma_f32_16x16x32_f16 v[158:161], v[210:213], v[206:209], v[158:161]
	v_lshl_add_u64 v[8:9], v[112:113], 0, v[30:31]
	s_mov_b32 m0, s72
	s_nop 0
	global_load_lds_dwordx4 v[8:9], off
	s_waitcnt lgkmcnt(2)
	v_mfma_f32_16x16x32_f16 v[166:169], v[202:205], v[220:223], v[166:169]
	v_lshl_add_u64 v[12:13], v[114:115], 0, v[30:31]
	s_mov_b32 m0, s64
	s_nop 0
	global_load_lds_dwordx4 v[12:13], off
	s_waitcnt lgkmcnt(1)
; #define GL_LOAD(s_, kt_) if (VAR != 1) { a##s_##0 = GL_A(0, kt_); a##s_##1 = GL_A(1, kt_); a##s_##2 = GL_A(2, kt_); a##s_##3 = GL_A(3, kt_); b##s_##0 = GL_B(0, kt_); b##s_##1 = GL_B(1, kt_); b##s_##2 = GL_B(2, kt_); b##s_##3 = GL_B(3, kt_); }
; #define LDS_STORE(s_, buf_) if (VAR != 2) { LDS_ST1(sA, 0, buf_, a##s_##0) LDS_ST1(sA, 1, buf_, a##s_##1) LDS_ST1(sA, 2, buf_, a##s_##2) LDS_ST1(sA, 3, buf_, a##s_##3) LDS_ST1(sB, 0, buf_, b##s_##0) LDS_ST1(sB, 1, buf_, b##s_##1) LDS_ST1(sB, 2, buf_, b##s_##2) LDS_ST1(sB, 3, buf_, b##s_##3) }
;     ...
;   GL_LOAD(0, 0)
;   GL_LOAD(1, 1)
;   LDS_STORE(0, 0)
;   if (VAR != 4) __syncthreads();
; #pragma unroll
;   for (int kt = 0; kt < nk; kt += 2) {
;     if (kt + 2 < nk) { GL_LOAD(0, kt + 2) }
;     MMA_TILE(0)
;     LDS_STORE(1, 1)
;     if (VAR != 4) __syncthreads();
;     if (kt + 3 < nk) { GL_LOAD(1, kt + 3) }
;     MMA_TILE(1)
;     if (kt + 2 < nk) { LDS_STORE(0, 0) }
;     if (VAR != 4) __syncthreads();
	v_mfma_f32_16x16x32_f16 v[68:71], v[202:205], v[228:231], v[68:71]
	ds_read_b128 v[202:205], v135 offset:49152
	v_mfma_f32_16x16x32_f16 v[190:193], v[210:213], v[220:223], v[190:193]
	v_lshl_add_u64 v[16:17], v[116:117], 0, v[30:31]
	s_mov_b32 m0, s62
	s_nop 0
	global_load_lds_dwordx4 v[16:17], off
	v_mfma_f32_16x16x32_f16 v[76:79], v[210:213], v[228:231], v[76:79]
	ds_read_b128 v[210:213], v135 offset:51200
	v_mfma_f32_16x16x32_f16 v[154:157], v[224:227], v[198:201], v[154:157]
	v_lshl_add_u64 v[20:21], v[118:119], 0, v[30:31]
	s_mov_b32 m0, s70
	s_nop 0
	global_load_lds_dwordx4 v[20:21], off
	v_mfma_f32_16x16x32_f16 v[162:165], v[224:227], v[206:209], v[162:165]
	v_lshl_add_u64 v[24:25], v[120:121], 0, v[30:31]
	s_mov_b32 m0, s74
	s_nop 0
	global_load_lds_dwordx4 v[24:25], off
	s_waitcnt lgkmcnt(2)
	v_mfma_f32_16x16x32_f16 v[64:67], v[232:235], v[198:201], v[64:67]
	ds_read_b128 v[198:201], v134 offset:16384
	v_mfma_f32_16x16x32_f16 v[72:75], v[232:235], v[206:209], v[72:75]
	ds_read_b128 v[206:209], v134 offset:18432
	v_mfma_f32_16x16x32_f16 v[194:197], v[224:227], v[220:223], v[194:197]
	v_lshl_add_u64 v[28:29], v[122:123], 0, v[30:31]
	s_mov_b32 m0, s66
	s_nop 0
	global_load_lds_dwordx4 v[28:29], off
	v_mfma_f32_16x16x32_f16 v[84:87], v[224:227], v[228:231], v[84:87]
	ds_read_b128 v[224:227], v135 offset:53248
	v_mfma_f32_16x16x32_f16 v[80:83], v[232:235], v[220:223], v[80:83]
	ds_read_b128 v[220:223], v134 offset:20480
	v_mfma_f32_16x16x32_f16 v[88:91], v[232:235], v[228:231], v[88:91]
	ds_read_b128 v[228:231], v134 offset:22528
	ds_read_b128 v[232:235], v135 offset:55296
	s_waitcnt vmcnt(0) lgkmcnt(0)
	s_barrier
	v_mfma_f32_16x16x32_f16 v[138:141], v[202:205], v[198:201], v[138:141]
	v_mfma_f32_16x16x32_f16 v[92:95], v[202:205], v[206:209], v[92:95]
	v_mfma_f32_16x16x32_f16 v[142:145], v[210:213], v[198:201], v[142:145]
	v_mfma_f32_16x16x32_f16 v[158:161], v[210:213], v[206:209], v[158:161]
	v_mfma_f32_16x16x32_f16 v[166:169], v[202:205], v[220:223], v[166:169]
	v_mfma_f32_16x16x32_f16 v[68:71], v[202:205], v[228:231], v[68:71]
	ds_read_b128 v[202:205], v136 offset:32768
	v_mfma_f32_16x16x32_f16 v[190:193], v[210:213], v[220:223], v[190:193]
	v_mfma_f32_16x16x32_f16 v[76:79], v[210:213], v[228:231], v[76:79]
	ds_read_b128 v[210:213], v136 offset:34816
	v_mfma_f32_16x16x32_f16 v[154:157], v[224:227], v[198:201], v[154:157]
	v_mfma_f32_16x16x32_f16 v[162:165], v[224:227], v[206:209], v[162:165]
	v_mfma_f32_16x16x32_f16 v[64:67], v[232:235], v[198:201], v[64:67]
	ds_read_b128 v[198:201], v133
	v_mfma_f32_16x16x32_f16 v[72:75], v[232:235], v[206:209], v[72:75]
	ds_read_b128 v[206:209], v133 offset:2048
	v_mfma_f32_16x16x32_f16 v[194:197], v[224:227], v[220:223], v[194:197]
	v_and_b32_e32 v62, 7, v148
	v_bfe_u32 v63, v148, 4, 3
	v_xor_b32_e32 v63, v63, v62
	v_sub_u32_e32 v63, v63, v62
	v_lshlrev_b32_e32 v62, 4, v63
	v_add_u32_e32 v62, 0x180, v62
	v_ashrrev_i32_e32 v63, 31, v62
	v_mfma_f32_16x16x32_f16 v[84:87], v[224:227], v[228:231], v[84:87]
	ds_read_b128 v[224:227], v136 offset:36864
	v_mfma_f32_16x16x32_f16 v[80:83], v[232:235], v[220:223], v[80:83]
	ds_read_b128 v[220:223], v133 offset:4096
	v_mfma_f32_16x16x32_f16 v[88:91], v[232:235], v[228:231], v[88:91]
	ds_read_b128 v[228:231], v133 offset:6144
	s_waitcnt lgkmcnt(4)
	v_mfma_f32_16x16x32_f16 v[138:141], v[202:205], v[198:201], v[138:141]
	ds_read_b128 v[232:235], v136 offset:38912
	s_waitcnt lgkmcnt(4)
	v_mfma_f32_16x16x32_f16 v[92:95], v[202:205], v[206:209], v[92:95]
	v_lshl_add_u64 v[32:33], v[108:109], 0, v[62:63]
	s_mov_b32 m0, s61
	s_nop 0
	global_load_lds_dwordx4 v[32:33], off
	v_mfma_f32_16x16x32_f16 v[142:145], v[210:213], v[198:201], v[142:145]
	v_lshl_add_u64 v[36:37], v[110:111], 0, v[62:63]
	s_mov_b32 m0, s69
	s_nop 0
	global_load_lds_dwordx4 v[36:37], off
	v_mfma_f32_16x16x32_f16 v[158:161], v[210:213], v[206:209], v[158:161]
	v_lshl_add_u64 v[40:41], v[112:113], 0, v[62:63]
	s_mov_b32 m0, s73
	s_nop 0
	global_load_lds_dwordx4 v[40:41], off
	s_waitcnt lgkmcnt(2)
	v_mfma_f32_16x16x32_f16 v[166:169], v[202:205], v[220:223], v[166:169]
	v_lshl_add_u64 v[44:45], v[114:115], 0, v[62:63]
	s_mov_b32 m0, s65
	s_nop 0
	global_load_lds_dwordx4 v[44:45], off
	s_waitcnt lgkmcnt(1)
	v_mfma_f32_16x16x32_f16 v[68:71], v[202:205], v[228:231], v[68:71]
	ds_read_b128 v[202:205], v135 offset:32768
	v_mfma_f32_16x16x32_f16 v[190:193], v[210:213], v[220:223], v[190:193]
	v_lshl_add_u64 v[48:49], v[116:117], 0, v[62:63]
	s_mov_b32 m0, s63
	s_nop 0
	global_load_lds_dwordx4 v[48:49], off
	v_mfma_f32_16x16x32_f16 v[76:79], v[210:213], v[228:231], v[76:79]
	ds_read_b128 v[210:213], v135 offset:34816
	v_mfma_f32_16x16x32_f16 v[154:157], v[224:227], v[198:201], v[154:157]
	v_lshl_add_u64 v[52:53], v[118:119], 0, v[62:63]
	s_mov_b32 m0, s71
	s_nop 0
	global_load_lds_dwordx4 v[52:53], off
	v_mfma_f32_16x16x32_f16 v[162:165], v[224:227], v[206:209], v[162:165]
	v_lshl_add_u64 v[56:57], v[120:121], 0, v[62:63]
	s_mov_b32 m0, s75
	s_nop 0
	global_load_lds_dwordx4 v[56:57], off
	s_waitcnt lgkmcnt(2)
	v_mfma_f32_16x16x32_f16 v[64:67], v[232:235], v[198:201], v[64:67]
	ds_read_b128 v[198:201], v134
	v_mfma_f32_16x16x32_f16 v[72:75], v[232:235], v[206:209], v[72:75]
	ds_read_b128 v[206:209], v134 offset:2048
	v_mfma_f32_16x16x32_f16 v[194:197], v[224:227], v[220:223], v[194:197]
	v_lshl_add_u64 v[60:61], v[122:123], 0, v[62:63]
	s_mov_b32 m0, s67
	s_nop 0
	global_load_lds_dwordx4 v[60:61], off
	v_mfma_f32_16x16x32_f16 v[84:87], v[224:227], v[228:231], v[84:87]
	ds_read_b128 v[224:227], v135 offset:36864
	v_mfma_f32_16x16x32_f16 v[80:83], v[232:235], v[220:223], v[80:83]
	ds_read_b128 v[220:223], v134 offset:4096
	v_mfma_f32_16x16x32_f16 v[88:91], v[232:235], v[228:231], v[88:91]
	ds_read_b128 v[228:231], v134 offset:6144
	ds_read_b128 v[232:235], v135 offset:38912
	s_waitcnt vmcnt(0) lgkmcnt(0)
	s_barrier
; #define GL_LOAD(s_, kt_) if (VAR != 1) { a##s_##0 = GL_A(0, kt_); a##s_##1 = GL_A(1, kt_); a##s_##2 = GL_A(2, kt_); a##s_##3 = GL_A(3, kt_); b##s_##0 = GL_B(0, kt_); b##s_##1 = GL_B(1, kt_); b##s_##2 = GL_B(2, kt_); b##s_##3 = GL_B(3, kt_); }
; #define LDS_STORE(s_, buf_) if (VAR != 2) { LDS_ST1(sA, 0, buf_, a##s_##0) LDS_ST1(sA, 1, buf_, a##s_##1) LDS_ST1(sA, 2, buf_, a##s_##2) LDS_ST1(sA, 3, buf_, a##s_##3) LDS_ST1(sB, 0, buf_, b##s_##0) LDS_ST1(sB, 1, buf_, b##s_##1) LDS_ST1(sB, 2, buf_, b##s_##2) LDS_ST1(sB, 3, buf_, b##s_##3) }
;     ...
;   GL_LOAD(0, 0)
;   GL_LOAD(1, 1)
;   LDS_STORE(0, 0)
;   if (VAR != 4) __syncthreads();
; #pragma unroll
;   for (int kt = 0; kt < nk; kt += 2) {
;     if (kt + 2 < nk) { GL_LOAD(0, kt + 2) }
;     MMA_TILE(0)
;     LDS_STORE(1, 1)
;     if (VAR != 4) __syncthreads();
;     if (kt + 3 < nk) { GL_LOAD(1, kt + 3) }
;     MMA_TILE(1)
;     if (kt + 2 < nk) { LDS_STORE(0, 0) }
;     if (VAR != 4) __syncthreads();
	v_mfma_f32_16x16x32_f16 v[138:141], v[202:205], v[198:201], v[138:141]
	v_mfma_f32_16x16x32_f16 v[92:95], v[202:205], v[206:209], v[92:95]
	v_mfma_f32_16x16x32_f16 v[142:145], v[210:213], v[198:201], v[142:145]
	v_mfma_f32_16x16x32_f16 v[158:161], v[210:213], v[206:209], v[158:161]
	v_mfma_f32_16x16x32_f16 v[166:169], v[202:205], v[220:223], v[166:169]
	v_mfma_f32_16x16x32_f16 v[68:71], v[202:205], v[228:231], v[68:71]
	ds_read_b128 v[202:205], v136 offset:49152
	v_mfma_f32_16x16x32_f16 v[190:193], v[210:213], v[220:223], v[190:193]
	v_mfma_f32_16x16x32_f16 v[76:79], v[210:213], v[228:231], v[76:79]
	ds_read_b128 v[210:213], v136 offset:51200
	v_mfma_f32_16x16x32_f16 v[154:157], v[224:227], v[198:201], v[154:157]
	v_mfma_f32_16x16x32_f16 v[162:165], v[224:227], v[206:209], v[162:165]
	v_mfma_f32_16x16x32_f16 v[64:67], v[232:235], v[198:201], v[64:67]
	ds_read_b128 v[198:201], v133 offset:16384
	v_mfma_f32_16x16x32_f16 v[72:75], v[232:235], v[206:209], v[72:75]
	ds_read_b128 v[206:209], v133 offset:18432
	v_mfma_f32_16x16x32_f16 v[194:197], v[224:227], v[220:223], v[194:197]
	v_and_b32_e32 v30, 7, v148
	v_bfe_u32 v31, v148, 4, 3
	v_xor_b32_e32 v31, v31, v30
	v_sub_u32_e32 v31, v31, v30
	v_lshlrev_b32_e32 v30, 4, v31
	v_add_u32_e32 v30, 0x200, v30
	v_ashrrev_i32_e32 v31, 31, v30
	v_mfma_f32_16x16x32_f16 v[84:87], v[224:227], v[228:231], v[84:87]
	ds_read_b128 v[224:227], v136 offset:53248
	v_mfma_f32_16x16x32_f16 v[80:83], v[232:235], v[220:223], v[80:83]
	ds_read_b128 v[220:223], v133 offset:20480
	v_mfma_f32_16x16x32_f16 v[88:91], v[232:235], v[228:231], v[88:91]
	ds_read_b128 v[228:231], v133 offset:22528
	s_waitcnt lgkmcnt(4)
	v_mfma_f32_16x16x32_f16 v[138:141], v[202:205], v[198:201], v[138:141]
	ds_read_b128 v[232:235], v136 offset:55296
	s_waitcnt lgkmcnt(4)
	v_mfma_f32_16x16x32_f16 v[92:95], v[202:205], v[206:209], v[92:95]
	v_lshl_add_u64 v[0:1], v[108:109], 0, v[30:31]
	s_mov_b32 m0, s60
	s_nop 0
	global_load_lds_dwordx4 v[0:1], off
	v_mfma_f32_16x16x32_f16 v[142:145], v[210:213], v[198:201], v[142:145]
	v_lshl_add_u64 v[4:5], v[110:111], 0, v[30:31]
	s_mov_b32 m0, s68
	s_nop 0
	global_load_lds_dwordx4 v[4:5], off
	v_mfma_f32_16x16x32_f16 v[158:161], v[210:213], v[206:209], v[158:161]
	v_lshl_add_u64 v[8:9], v[112:113], 0, v[30:31]
	s_mov_b32 m0, s72
	s_nop 0
	global_load_lds_dwordx4 v[8:9], off
	s_waitcnt lgkmcnt(2)
	v_mfma_f32_16x16x32_f16 v[166:169], v[202:205], v[220:223], v[166:169]
	v_lshl_add_u64 v[12:13], v[114:115], 0, v[30:31]
	s_mov_b32 m0, s64
	s_nop 0
	global_load_lds_dwordx4 v[12:13], off
	s_waitcnt lgkmcnt(1)
	v_mfma_f32_16x16x32_f16 v[68:71], v[202:205], v[228:231], v[68:71]
	ds_read_b128 v[202:205], v135 offset:49152
	v_mfma_f32_16x16x32_f16 v[190:193], v[210:213], v[220:223], v[190:193]
	v_lshl_add_u64 v[16:17], v[116:117], 0, v[30:31]
	s_mov_b32 m0, s62
	s_nop 0
	global_load_lds_dwordx4 v[16:17], off
	v_mfma_f32_16x16x32_f16 v[76:79], v[210:213], v[228:231], v[76:79]
	ds_read_b128 v[210:213], v135 offset:51200
	v_mfma_f32_16x16x32_f16 v[154:157], v[224:227], v[198:201], v[154:157]
	v_lshl_add_u64 v[20:21], v[118:119], 0, v[30:31]
	s_mov_b32 m0, s70
	s_nop 0
	global_load_lds_dwordx4 v[20:21], off
	v_mfma_f32_16x16x32_f16 v[162:165], v[224:227], v[206:209], v[162:165]
	v_lshl_add_u64 v[24:25], v[120:121], 0, v[30:31]
	s_mov_b32 m0, s74
	s_nop 0
	global_load_lds_dwordx4 v[24:25], off
	s_waitcnt lgkmcnt(2)
	v_mfma_f32_16x16x32_f16 v[64:67], v[232:235], v[198:201], v[64:67]
	ds_read_b128 v[198:201], v134 offset:16384
	v_mfma_f32_16x16x32_f16 v[72:75], v[232:235], v[206:209], v[72:75]
	ds_read_b128 v[206:209], v134 offset:18432
	v_mfma_f32_16x16x32_f16 v[194:197], v[224:227], v[220:223], v[194:197]
	v_lshl_add_u64 v[28:29], v[122:123], 0, v[30:31]
	s_mov_b32 m0, s66
	s_nop 0
	global_load_lds_dwordx4 v[28:29], off
	v_mfma_f32_16x16x32_f16 v[84:87], v[224:227], v[228:231], v[84:87]
	ds_read_b128 v[224:227], v135 offset:53248
	v_mfma_f32_16x16x32_f16 v[80:83], v[232:235], v[220:223], v[80:83]
	ds_read_b128 v[220:223], v134 offset:20480
	v_mfma_f32_16x16x32_f16 v[88:91], v[232:235], v[228:231], v[88:91]
	ds_read_b128 v[228:231], v134 offset:22528
	ds_read_b128 v[232:235], v135 offset:55296
	s_waitcnt vmcnt(0) lgkmcnt(0)
	s_barrier
	v_mfma_f32_16x16x32_f16 v[138:141], v[202:205], v[198:201], v[138:141]
	v_mfma_f32_16x16x32_f16 v[92:95], v[202:205], v[206:209], v[92:95]
	v_mfma_f32_16x16x32_f16 v[142:145], v[210:213], v[198:201], v[142:145]
	v_mfma_f32_16x16x32_f16 v[158:161], v[210:213], v[206:209], v[158:161]
	v_mfma_f32_16x16x32_f16 v[166:169], v[202:205], v[220:223], v[166:169]
	v_mfma_f32_16x16x32_f16 v[68:71], v[202:205], v[228:231], v[68:71]
	ds_read_b128 v[202:205], v136 offset:32768
	v_mfma_f32_16x16x32_f16 v[190:193], v[210:213], v[220:223], v[190:193]
	v_mfma_f32_16x16x32_f16 v[76:79], v[210:213], v[228:231], v[76:79]
	ds_read_b128 v[210:213], v136 offset:34816
	v_mfma_f32_16x16x32_f16 v[154:157], v[224:227], v[198:201], v[154:157]
	v_mfma_f32_16x16x32_f16 v[162:165], v[224:227], v[206:209], v[162:165]
	v_mfma_f32_16x16x32_f16 v[64:67], v[232:235], v[198:201], v[64:67]
	ds_read_b128 v[198:201], v133
	v_mfma_f32_16x16x32_f16 v[72:75], v[232:235], v[206:209], v[72:75]
	ds_read_b128 v[206:209], v133 offset:2048
	v_mfma_f32_16x16x32_f16 v[194:197], v[224:227], v[220:223], v[194:197]
	v_and_b32_e32 v62, 7, v148
	v_bfe_u32 v63, v148, 4, 3
	v_xor_b32_e32 v63, v63, v62
	v_sub_u32_e32 v63, v63, v62
	v_lshlrev_b32_e32 v62, 4, v63
	v_add_u32_e32 v62, 0x280, v62
	v_ashrrev_i32_e32 v63, 31, v62
	v_mfma_f32_16x16x32_f16 v[84:87], v[224:227], v[228:231], v[84:87]
	ds_read_b128 v[224:227], v136 offset:36864
	v_mfma_f32_16x16x32_f16 v[80:83], v[232:235], v[220:223], v[80:83]
	ds_read_b128 v[220:223], v133 offset:4096
	v_mfma_f32_16x16x32_f16 v[88:91], v[232:235], v[228:231], v[88:91]
	ds_read_b128 v[228:231], v133 offset:6144
	s_waitcnt lgkmcnt(4)
; #define GL_LOAD(s_, kt_) if (VAR != 1) { a##s_##0 = GL_A(0, kt_); a##s_##1 = GL_A(1, kt_); a##s_##2 = GL_A(2, kt_); a##s_##3 = GL_A(3, kt_); b##s_##0 = GL_B(0, kt_); b##s_##1 = GL_B(1, kt_); b##s_##2 = GL_B(2, kt_); b##s_##3 = GL_B(3, kt_); }
; #define LDS_STORE(s_, buf_) if (VAR != 2) { LDS_ST1(sA, 0, buf_, a##s_##0) LDS_ST1(sA, 1, buf_, a##s_##1) LDS_ST1(sA, 2, buf_, a##s_##2) LDS_ST1(sA, 3, buf_, a##s_##3) LDS_ST1(sB, 0, buf_, b##s_##0) LDS_ST1(sB, 1, buf_, b##s_##1) LDS_ST1(sB, 2, buf_, b##s_##2) LDS_ST1(sB, 3, buf_, b##s_##3) }
;     ...
;   GL_LOAD(0, 0)
;   GL_LOAD(1, 1)
;   LDS_STORE(0, 0)
;   if (VAR != 4) __syncthreads();
; #pragma unroll
;   for (int kt = 0; kt < nk; kt += 2) {
;     if (kt + 2 < nk) { GL_LOAD(0, kt + 2) }
;     MMA_TILE(0)
;     LDS_STORE(1, 1)
;     if (VAR != 4) __syncthreads();
;     if (kt + 3 < nk) { GL_LOAD(1, kt + 3) }
;     MMA_TILE(1)
;     if (kt + 2 < nk) { LDS_STORE(0, 0) }
;     if (VAR != 4) __syncthreads();
	v_mfma_f32_16x16x32_f16 v[138:141], v[202:205], v[198:201], v[138:141]
	ds_read_b128 v[232:235], v136 offset:38912
	s_waitcnt lgkmcnt(4)
	v_mfma_f32_16x16x32_f16 v[92:95], v[202:205], v[206:209], v[92:95]
	v_lshl_add_u64 v[32:33], v[108:109], 0, v[62:63]
	s_mov_b32 m0, s61
	s_nop 0
	global_load_lds_dwordx4 v[32:33], off
	v_mfma_f32_16x16x32_f16 v[142:145], v[210:213], v[198:201], v[142:145]
	v_lshl_add_u64 v[36:37], v[110:111], 0, v[62:63]
	s_mov_b32 m0, s69
	s_nop 0
	global_load_lds_dwordx4 v[36:37], off
	v_mfma_f32_16x16x32_f16 v[158:161], v[210:213], v[206:209], v[158:161]
	v_lshl_add_u64 v[40:41], v[112:113], 0, v[62:63]
	s_mov_b32 m0, s73
	s_nop 0
	global_load_lds_dwordx4 v[40:41], off
	s_waitcnt lgkmcnt(2)
	v_mfma_f32_16x16x32_f16 v[166:169], v[202:205], v[220:223], v[166:169]
	v_lshl_add_u64 v[44:45], v[114:115], 0, v[62:63]
	s_mov_b32 m0, s65
	s_nop 0
	global_load_lds_dwordx4 v[44:45], off
	s_waitcnt lgkmcnt(1)
	v_mfma_f32_16x16x32_f16 v[68:71], v[202:205], v[228:231], v[68:71]
	ds_read_b128 v[202:205], v135 offset:32768
	v_mfma_f32_16x16x32_f16 v[190:193], v[210:213], v[220:223], v[190:193]
	v_lshl_add_u64 v[48:49], v[116:117], 0, v[62:63]
	s_mov_b32 m0, s63
	s_nop 0
	global_load_lds_dwordx4 v[48:49], off
	v_mfma_f32_16x16x32_f16 v[76:79], v[210:213], v[228:231], v[76:79]
	ds_read_b128 v[210:213], v135 offset:34816
	v_mfma_f32_16x16x32_f16 v[154:157], v[224:227], v[198:201], v[154:157]
	v_lshl_add_u64 v[52:53], v[118:119], 0, v[62:63]
	s_mov_b32 m0, s71
	s_nop 0
	global_load_lds_dwordx4 v[52:53], off
	v_mfma_f32_16x16x32_f16 v[162:165], v[224:227], v[206:209], v[162:165]
	v_lshl_add_u64 v[56:57], v[120:121], 0, v[62:63]
	s_mov_b32 m0, s75
	s_nop 0
	global_load_lds_dwordx4 v[56:57], off
	s_waitcnt lgkmcnt(2)
	v_mfma_f32_16x16x32_f16 v[64:67], v[232:235], v[198:201], v[64:67]
	ds_read_b128 v[198:201], v134
	v_mfma_f32_16x16x32_f16 v[72:75], v[232:235], v[206:209], v[72:75]
	ds_read_b128 v[206:209], v134 offset:2048
	v_mfma_f32_16x16x32_f16 v[194:197], v[224:227], v[220:223], v[194:197]
	v_lshl_add_u64 v[60:61], v[122:123], 0, v[62:63]
	s_mov_b32 m0, s67
	s_nop 0
	global_load_lds_dwordx4 v[60:61], off
	v_mfma_f32_16x16x32_f16 v[84:87], v[224:227], v[228:231], v[84:87]
	ds_read_b128 v[224:227], v135 offset:36864
	v_mfma_f32_16x16x32_f16 v[80:83], v[232:235], v[220:223], v[80:83]
	ds_read_b128 v[220:223], v134 offset:4096
	v_mfma_f32_16x16x32_f16 v[88:91], v[232:235], v[228:231], v[88:91]
	ds_read_b128 v[228:231], v134 offset:6144
	ds_read_b128 v[232:235], v135 offset:38912
	s_waitcnt vmcnt(0) lgkmcnt(0)
	s_barrier
	v_mfma_f32_16x16x32_f16 v[138:141], v[202:205], v[198:201], v[138:141]
	v_mfma_f32_16x16x32_f16 v[92:95], v[202:205], v[206:209], v[92:95]
	v_mfma_f32_16x16x32_f16 v[142:145], v[210:213], v[198:201], v[142:145]
	v_mfma_f32_16x16x32_f16 v[158:161], v[210:213], v[206:209], v[158:161]
	v_mfma_f32_16x16x32_f16 v[166:169], v[202:205], v[220:223], v[166:169]
	v_mfma_f32_16x16x32_f16 v[68:71], v[202:205], v[228:231], v[68:71]
	ds_read_b128 v[202:205], v136 offset:49152
	v_mfma_f32_16x16x32_f16 v[190:193], v[210:213], v[220:223], v[190:193]
	v_mfma_f32_16x16x32_f16 v[76:79], v[210:213], v[228:231], v[76:79]
	ds_read_b128 v[210:213], v136 offset:51200
	v_mfma_f32_16x16x32_f16 v[154:157], v[224:227], v[198:201], v[154:157]
	v_mfma_f32_16x16x32_f16 v[162:165], v[224:227], v[206:209], v[162:165]
	v_mfma_f32_16x16x32_f16 v[64:67], v[232:235], v[198:201], v[64:67]
	ds_read_b128 v[198:201], v133 offset:16384
	v_mfma_f32_16x16x32_f16 v[72:75], v[232:235], v[206:209], v[72:75]
	ds_read_b128 v[206:209], v133 offset:18432
	v_mfma_f32_16x16x32_f16 v[194:197], v[224:227], v[220:223], v[194:197]
	v_and_b32_e32 v30, 7, v148
	v_bfe_u32 v31, v148, 4, 3
	v_xor_b32_e32 v31, v31, v30
	v_sub_u32_e32 v31, v31, v30
	v_lshlrev_b32_e32 v30, 4, v31
	v_add_u32_e32 v30, 0x300, v30
	v_ashrrev_i32_e32 v31, 31, v30
	v_mfma_f32_16x16x32_f16 v[84:87], v[224:227], v[228:231], v[84:87]
	ds_read_b128 v[224:227], v136 offset:53248
	v_mfma_f32_16x16x32_f16 v[80:83], v[232:235], v[220:223], v[80:83]
	ds_read_b128 v[220:223], v133 offset:20480
	v_mfma_f32_16x16x32_f16 v[88:91], v[232:235], v[228:231], v[88:91]
	ds_read_b128 v[228:231], v133 offset:22528
	s_waitcnt lgkmcnt(4)
	v_mfma_f32_16x16x32_f16 v[138:141], v[202:205], v[198:201], v[138:141]
	ds_read_b128 v[232:235], v136 offset:55296
	s_waitcnt lgkmcnt(4)
	v_mfma_f32_16x16x32_f16 v[92:95], v[202:205], v[206:209], v[92:95]
	v_lshl_add_u64 v[0:1], v[108:109], 0, v[30:31]
	s_mov_b32 m0, s60
	s_nop 0
	global_load_lds_dwordx4 v[0:1], off
	v_mfma_f32_16x16x32_f16 v[142:145], v[210:213], v[198:201], v[142:145]
	v_lshl_add_u64 v[4:5], v[110:111], 0, v[30:31]
	s_mov_b32 m0, s68
	s_nop 0
	global_load_lds_dwordx4 v[4:5], off
	v_mfma_f32_16x16x32_f16 v[158:161], v[210:213], v[206:209], v[158:161]
	v_lshl_add_u64 v[8:9], v[112:113], 0, v[30:31]
	s_mov_b32 m0, s72
	s_nop 0
	global_load_lds_dwordx4 v[8:9], off
	s_waitcnt lgkmcnt(2)
	v_mfma_f32_16x16x32_f16 v[166:169], v[202:205], v[220:223], v[166:169]
	v_lshl_add_u64 v[12:13], v[114:115], 0, v[30:31]
	s_mov_b32 m0, s64
	s_nop 0
	global_load_lds_dwordx4 v[12:13], off
	s_waitcnt lgkmcnt(1)
	v_mfma_f32_16x16x32_f16 v[68:71], v[202:205], v[228:231], v[68:71]
	ds_read_b128 v[202:205], v135 offset:49152
	v_mfma_f32_16x16x32_f16 v[190:193], v[210:213], v[220:223], v[190:193]
	v_lshl_add_u64 v[16:17], v[116:117], 0, v[30:31]
	s_mov_b32 m0, s62
	s_nop 0
	global_load_lds_dwordx4 v[16:17], off
	v_mfma_f32_16x16x32_f16 v[76:79], v[210:213], v[228:231], v[76:79]
	ds_read_b128 v[210:213], v135 offset:51200
	v_mfma_f32_16x16x32_f16 v[154:157], v[224:227], v[198:201], v[154:157]
	v_lshl_add_u64 v[20:21], v[118:119], 0, v[30:31]
	s_mov_b32 m0, s70
	s_nop 0
	global_load_lds_dwordx4 v[20:21], off
	v_mfma_f32_16x16x32_f16 v[162:165], v[224:227], v[206:209], v[162:165]
	v_lshl_add_u64 v[24:25], v[120:121], 0, v[30:31]
	s_mov_b32 m0, s74
	s_nop 0
	global_load_lds_dwordx4 v[24:25], off
	s_waitcnt lgkmcnt(2)
	v_mfma_f32_16x16x32_f16 v[64:67], v[232:235], v[198:201], v[64:67]
	ds_read_b128 v[198:201], v134 offset:16384
	v_mfma_f32_16x16x32_f16 v[72:75], v[232:235], v[206:209], v[72:75]
	ds_read_b128 v[206:209], v134 offset:18432
	v_mfma_f32_16x16x32_f16 v[194:197], v[224:227], v[220:223], v[194:197]
	v_lshl_add_u64 v[28:29], v[122:123], 0, v[30:31]
	s_mov_b32 m0, s66
	s_nop 0
	global_load_lds_dwordx4 v[28:29], off
	v_mfma_f32_16x16x32_f16 v[84:87], v[224:227], v[228:231], v[84:87]
	ds_read_b128 v[224:227], v135 offset:53248
	v_mfma_f32_16x16x32_f16 v[80:83], v[232:235], v[220:223], v[80:83]
	ds_read_b128 v[220:223], v134 offset:20480
	v_mfma_f32_16x16x32_f16 v[88:91], v[232:235], v[228:231], v[88:91]
	ds_read_b128 v[228:231], v134 offset:22528
	ds_read_b128 v[232:235], v135 offset:55296
	s_waitcnt vmcnt(0) lgkmcnt(0)
	s_barrier
; #define GL_LOAD(s_, kt_) if (VAR != 1) { a##s_##0 = GL_A(0, kt_); a##s_##1 = GL_A(1, kt_); a##s_##2 = GL_A(2, kt_); a##s_##3 = GL_A(3, kt_); b##s_##0 = GL_B(0, kt_); b##s_##1 = GL_B(1, kt_); b##s_##2 = GL_B(2, kt_); b##s_##3 = GL_B(3, kt_); }
; #define LDS_STORE(s_, buf_) if (VAR != 2) { LDS_ST1(sA, 0, buf_, a##s_##0) LDS_ST1(sA, 1, buf_, a##s_##1) LDS_ST1(sA, 2, buf_, a##s_##2) LDS_ST1(sA, 3, buf_, a##s_##3) LDS_ST1(sB, 0, buf_, b##s_##0) LDS_ST1(sB, 1, buf_, b##s_##1) LDS_ST1(sB, 2, buf_, b##s_##2) LDS_ST1(sB, 3, buf_, b##s_##3) }
;     ...
;   GL_LOAD(0, 0)
;   GL_LOAD(1, 1)
;   LDS_STORE(0, 0)
;   if (VAR != 4) __syncthreads();
; #pragma unroll
;   for (int kt = 0; kt < nk; kt += 2) {
;     if (kt + 2 < nk) { GL_LOAD(0, kt + 2) }
;     MMA_TILE(0)
;     LDS_STORE(1, 1)
;     if (VAR != 4) __syncthreads();
;     if (kt + 3 < nk) { GL_LOAD(1, kt + 3) }
;     MMA_TILE(1)
;     if (kt + 2 < nk) { LDS_STORE(0, 0) }
;     if (VAR != 4) __syncthreads();
	v_mfma_f32_16x16x32_f16 v[138:141], v[202:205], v[198:201], v[138:141]
	v_mfma_f32_16x16x32_f16 v[92:95], v[202:205], v[206:209], v[92:95]
	v_mfma_f32_16x16x32_f16 v[142:145], v[210:213], v[198:201], v[142:145]
	v_mfma_f32_16x16x32_f16 v[158:161], v[210:213], v[206:209], v[158:161]
	v_mfma_f32_16x16x32_f16 v[166:169], v[202:205], v[220:223], v[166:169]
	v_mfma_f32_16x16x32_f16 v[68:71], v[202:205], v[228:231], v[68:71]
	ds_read_b128 v[202:205], v136 offset:32768
	v_mfma_f32_16x16x32_f16 v[190:193], v[210:213], v[220:223], v[190:193]
	v_mfma_f32_16x16x32_f16 v[76:79], v[210:213], v[228:231], v[76:79]
	ds_read_b128 v[210:213], v136 offset:34816
	v_mfma_f32_16x16x32_f16 v[154:157], v[224:227], v[198:201], v[154:157]
	v_mfma_f32_16x16x32_f16 v[162:165], v[224:227], v[206:209], v[162:165]
	v_mfma_f32_16x16x32_f16 v[64:67], v[232:235], v[198:201], v[64:67]
	ds_read_b128 v[198:201], v133
	v_mfma_f32_16x16x32_f16 v[72:75], v[232:235], v[206:209], v[72:75]
	ds_read_b128 v[206:209], v133 offset:2048
	v_mfma_f32_16x16x32_f16 v[194:197], v[224:227], v[220:223], v[194:197]
	v_and_b32_e32 v62, 7, v148
	v_bfe_u32 v63, v148, 4, 3
	v_xor_b32_e32 v63, v63, v62
	v_sub_u32_e32 v63, v63, v62
	v_lshlrev_b32_e32 v62, 4, v63
	v_add_u32_e32 v62, 0x380, v62
	v_ashrrev_i32_e32 v63, 31, v62
	v_mfma_f32_16x16x32_f16 v[84:87], v[224:227], v[228:231], v[84:87]
	ds_read_b128 v[224:227], v136 offset:36864
	v_mfma_f32_16x16x32_f16 v[80:83], v[232:235], v[220:223], v[80:83]
	ds_read_b128 v[220:223], v133 offset:4096
	v_mfma_f32_16x16x32_f16 v[88:91], v[232:235], v[228:231], v[88:91]
	ds_read_b128 v[228:231], v133 offset:6144
	s_waitcnt lgkmcnt(4)
	v_mfma_f32_16x16x32_f16 v[138:141], v[202:205], v[198:201], v[138:141]
	ds_read_b128 v[232:235], v136 offset:38912
	s_waitcnt lgkmcnt(4)
	v_mfma_f32_16x16x32_f16 v[92:95], v[202:205], v[206:209], v[92:95]
	v_lshl_add_u64 v[32:33], v[108:109], 0, v[62:63]
	s_mov_b32 m0, s61
	s_nop 0
	global_load_lds_dwordx4 v[32:33], off
	v_mfma_f32_16x16x32_f16 v[142:145], v[210:213], v[198:201], v[142:145]
	v_lshl_add_u64 v[36:37], v[110:111], 0, v[62:63]
	s_mov_b32 m0, s69
	s_nop 0
	global_load_lds_dwordx4 v[36:37], off
	v_mfma_f32_16x16x32_f16 v[158:161], v[210:213], v[206:209], v[158:161]
	v_lshl_add_u64 v[40:41], v[112:113], 0, v[62:63]
	s_mov_b32 m0, s73
	s_nop 0
	global_load_lds_dwordx4 v[40:41], off
	s_waitcnt lgkmcnt(2)
	v_mfma_f32_16x16x32_f16 v[166:169], v[202:205], v[220:223], v[166:169]
	v_lshl_add_u64 v[44:45], v[114:115], 0, v[62:63]
	s_mov_b32 m0, s65
	s_nop 0
	global_load_lds_dwordx4 v[44:45], off
	s_waitcnt lgkmcnt(1)
	v_mfma_f32_16x16x32_f16 v[68:71], v[202:205], v[228:231], v[68:71]
	ds_read_b128 v[202:205], v135 offset:32768
	v_mfma_f32_16x16x32_f16 v[190:193], v[210:213], v[220:223], v[190:193]
	v_lshl_add_u64 v[48:49], v[116:117], 0, v[62:63]
	s_mov_b32 m0, s63
	s_nop 0
	global_load_lds_dwordx4 v[48:49], off
	v_mfma_f32_16x16x32_f16 v[76:79], v[210:213], v[228:231], v[76:79]
	ds_read_b128 v[210:213], v135 offset:34816
	v_mfma_f32_16x16x32_f16 v[154:157], v[224:227], v[198:201], v[154:157]
	v_lshl_add_u64 v[52:53], v[118:119], 0, v[62:63]
	s_mov_b32 m0, s71
	s_nop 0
	global_load_lds_dwordx4 v[52:53], off
	v_mfma_f32_16x16x32_f16 v[162:165], v[224:227], v[206:209], v[162:165]
	v_lshl_add_u64 v[56:57], v[120:121], 0, v[62:63]
	s_mov_b32 m0, s75
	s_nop 0
	global_load_lds_dwordx4 v[56:57], off
	s_waitcnt lgkmcnt(2)
	v_mfma_f32_16x16x32_f16 v[64:67], v[232:235], v[198:201], v[64:67]
	ds_read_b128 v[198:201], v134
	v_mfma_f32_16x16x32_f16 v[72:75], v[232:235], v[206:209], v[72:75]
	ds_read_b128 v[206:209], v134 offset:2048
	v_mfma_f32_16x16x32_f16 v[194:197], v[224:227], v[220:223], v[194:197]
	v_lshl_add_u64 v[60:61], v[122:123], 0, v[62:63]
	s_mov_b32 m0, s67
	s_nop 0
	global_load_lds_dwordx4 v[60:61], off
	v_mfma_f32_16x16x32_f16 v[84:87], v[224:227], v[228:231], v[84:87]
	ds_read_b128 v[224:227], v135 offset:36864
	v_mfma_f32_16x16x32_f16 v[80:83], v[232:235], v[220:223], v[80:83]
	ds_read_b128 v[220:223], v134 offset:4096
	v_mfma_f32_16x16x32_f16 v[88:91], v[232:235], v[228:231], v[88:91]
	ds_read_b128 v[228:231], v134 offset:6144
	ds_read_b128 v[232:235], v135 offset:38912
	s_waitcnt vmcnt(0) lgkmcnt(0)
	s_barrier
	v_mfma_f32_16x16x32_f16 v[138:141], v[202:205], v[198:201], v[138:141]
	v_mfma_f32_16x16x32_f16 v[92:95], v[202:205], v[206:209], v[92:95]
	v_mfma_f32_16x16x32_f16 v[142:145], v[210:213], v[198:201], v[142:145]
	v_mfma_f32_16x16x32_f16 v[158:161], v[210:213], v[206:209], v[158:161]
	v_mfma_f32_16x16x32_f16 v[166:169], v[202:205], v[220:223], v[166:169]
	v_mfma_f32_16x16x32_f16 v[68:71], v[202:205], v[228:231], v[68:71]
	ds_read_b128 v[202:205], v136 offset:49152
	v_mfma_f32_16x16x32_f16 v[190:193], v[210:213], v[220:223], v[190:193]
	v_mfma_f32_16x16x32_f16 v[76:79], v[210:213], v[228:231], v[76:79]
	ds_read_b128 v[210:213], v136 offset:51200
	v_mfma_f32_16x16x32_f16 v[154:157], v[224:227], v[198:201], v[154:157]
	v_mfma_f32_16x16x32_f16 v[162:165], v[224:227], v[206:209], v[162:165]
	v_mfma_f32_16x16x32_f16 v[64:67], v[232:235], v[198:201], v[64:67]
	ds_read_b128 v[198:201], v133 offset:16384
	v_mfma_f32_16x16x32_f16 v[72:75], v[232:235], v[206:209], v[72:75]
	ds_read_b128 v[206:209], v133 offset:18432
	v_mfma_f32_16x16x32_f16 v[194:197], v[224:227], v[220:223], v[194:197]
	v_and_b32_e32 v30, 7, v148
	v_bfe_u32 v31, v148, 4, 3
	v_xor_b32_e32 v31, v31, v30
	v_sub_u32_e32 v31, v31, v30
	v_lshlrev_b32_e32 v30, 4, v31
	v_add_u32_e32 v30, 0x400, v30
	v_ashrrev_i32_e32 v31, 31, v30
	v_mfma_f32_16x16x32_f16 v[84:87], v[224:227], v[228:231], v[84:87]
	ds_read_b128 v[224:227], v136 offset:53248
	v_mfma_f32_16x16x32_f16 v[80:83], v[232:235], v[220:223], v[80:83]
	ds_read_b128 v[220:223], v133 offset:20480
	v_mfma_f32_16x16x32_f16 v[88:91], v[232:235], v[228:231], v[88:91]
	ds_read_b128 v[228:231], v133 offset:22528
	s_waitcnt lgkmcnt(4)
; #define GL_LOAD(s_, kt_) if (VAR != 1) { a##s_##0 = GL_A(0, kt_); a##s_##1 = GL_A(1, kt_); a##s_##2 = GL_A(2, kt_); a##s_##3 = GL_A(3, kt_); b##s_##0 = GL_B(0, kt_); b##s_##1 = GL_B(1, kt_); b##s_##2 = GL_B(2, kt_); b##s_##3 = GL_B(3, kt_); }
; #define LDS_STORE(s_, buf_) if (VAR != 2) { LDS_ST1(sA, 0, buf_, a##s_##0) LDS_ST1(sA, 1, buf_, a##s_##1) LDS_ST1(sA, 2, buf_, a##s_##2) LDS_ST1(sA, 3, buf_, a##s_##3) LDS_ST1(sB, 0, buf_, b##s_##0) LDS_ST1(sB, 1, buf_, b##s_##1) LDS_ST1(sB, 2, buf_, b##s_##2) LDS_ST1(sB, 3, buf_, b##s_##3) }
;     ...
;   GL_LOAD(0, 0)
;   GL_LOAD(1, 1)
;   LDS_STORE(0, 0)
;   if (VAR != 4) __syncthreads();
; #pragma unroll
;   for (int kt = 0; kt < nk; kt += 2) {
;     if (kt + 2 < nk) { GL_LOAD(0, kt + 2) }
;     MMA_TILE(0)
;     LDS_STORE(1, 1)
;     if (VAR != 4) __syncthreads();
;     if (kt + 3 < nk) { GL_LOAD(1, kt + 3) }
;     MMA_TILE(1)
;     if (kt + 2 < nk) { LDS_STORE(0, 0) }
;     if (VAR != 4) __syncthreads();
	v_mfma_f32_16x16x32_f16 v[138:141], v[202:205], v[198:201], v[138:141]
	ds_read_b128 v[232:235], v136 offset:55296
	s_waitcnt lgkmcnt(4)
	v_mfma_f32_16x16x32_f16 v[92:95], v[202:205], v[206:209], v[92:95]
	v_lshl_add_u64 v[0:1], v[108:109], 0, v[30:31]
	s_mov_b32 m0, s60
	s_nop 0
	global_load_lds_dwordx4 v[0:1], off
	v_mfma_f32_16x16x32_f16 v[142:145], v[210:213], v[198:201], v[142:145]
	v_lshl_add_u64 v[4:5], v[110:111], 0, v[30:31]
	s_mov_b32 m0, s68
	s_nop 0
	global_load_lds_dwordx4 v[4:5], off
	v_mfma_f32_16x16x32_f16 v[158:161], v[210:213], v[206:209], v[158:161]
	v_lshl_add_u64 v[8:9], v[112:113], 0, v[30:31]
	s_mov_b32 m0, s72
	s_nop 0
	global_load_lds_dwordx4 v[8:9], off
	s_waitcnt lgkmcnt(2)
	v_mfma_f32_16x16x32_f16 v[166:169], v[202:205], v[220:223], v[166:169]
	v_lshl_add_u64 v[12:13], v[114:115], 0, v[30:31]
	s_mov_b32 m0, s64
	s_nop 0
	global_load_lds_dwordx4 v[12:13], off
	s_waitcnt lgkmcnt(1)
	v_mfma_f32_16x16x32_f16 v[68:71], v[202:205], v[228:231], v[68:71]
	ds_read_b128 v[202:205], v135 offset:49152
	v_mfma_f32_16x16x32_f16 v[190:193], v[210:213], v[220:223], v[190:193]
	v_lshl_add_u64 v[16:17], v[116:117], 0, v[30:31]
	s_mov_b32 m0, s62
	s_nop 0
	global_load_lds_dwordx4 v[16:17], off
	v_mfma_f32_16x16x32_f16 v[76:79], v[210:213], v[228:231], v[76:79]
	ds_read_b128 v[210:213], v135 offset:51200
	v_mfma_f32_16x16x32_f16 v[154:157], v[224:227], v[198:201], v[154:157]
	v_lshl_add_u64 v[20:21], v[118:119], 0, v[30:31]
	s_mov_b32 m0, s70
	s_nop 0
	global_load_lds_dwordx4 v[20:21], off
	v_mfma_f32_16x16x32_f16 v[162:165], v[224:227], v[206:209], v[162:165]
	v_lshl_add_u64 v[24:25], v[120:121], 0, v[30:31]
	s_mov_b32 m0, s74
	s_nop 0
	global_load_lds_dwordx4 v[24:25], off
	s_waitcnt lgkmcnt(2)
	v_mfma_f32_16x16x32_f16 v[64:67], v[232:235], v[198:201], v[64:67]
	ds_read_b128 v[198:201], v134 offset:16384
	v_mfma_f32_16x16x32_f16 v[72:75], v[232:235], v[206:209], v[72:75]
	ds_read_b128 v[206:209], v134 offset:18432
	v_mfma_f32_16x16x32_f16 v[194:197], v[224:227], v[220:223], v[194:197]
	v_lshl_add_u64 v[28:29], v[122:123], 0, v[30:31]
	s_mov_b32 m0, s66
	s_nop 0
	global_load_lds_dwordx4 v[28:29], off
	v_mfma_f32_16x16x32_f16 v[84:87], v[224:227], v[228:231], v[84:87]
	ds_read_b128 v[224:227], v135 offset:53248
	v_mfma_f32_16x16x32_f16 v[80:83], v[232:235], v[220:223], v[80:83]
	ds_read_b128 v[220:223], v134 offset:20480
	v_mfma_f32_16x16x32_f16 v[88:91], v[232:235], v[228:231], v[88:91]
	ds_read_b128 v[228:231], v134 offset:22528
	s_waitcnt lgkmcnt(4)
	v_mfma_f32_16x16x32_f16 v[138:141], v[202:205], v[198:201], v[138:141]
	ds_read_b128 v[232:235], v135 offset:55296
	s_waitcnt vmcnt(0) lgkmcnt(0)
	s_barrier
	v_mfma_f32_16x16x32_f16 v[142:145], v[210:213], v[198:201], v[142:145]
	ds_read_b128 v[0:3], v133
	v_mfma_f32_16x16x32_f16 v[158:161], v[210:213], v[206:209], v[158:161]
	ds_read_b128 v[4:7], v136 offset:32768
	v_mfma_f32_16x16x32_f16 v[154:157], v[224:227], v[198:201], v[154:157]
	ds_read_b128 v[8:11], v133 offset:2048
	v_mfma_f32_16x16x32_f16 v[162:165], v[224:227], v[206:209], v[162:165]
	ds_read_b128 v[12:15], v136 offset:34816
	v_mfma_f32_16x16x32_f16 v[190:193], v[210:213], v[220:223], v[190:193]
	ds_read_b128 v[16:19], v133 offset:4096
	v_mfma_f32_16x16x32_f16 v[210:213], v[210:213], v[228:231], v[76:79]
	ds_read_b128 v[20:23], v136 offset:36864
	v_mfma_f32_16x16x32_f16 v[194:197], v[224:227], v[220:223], v[194:197]
	ds_read_b128 v[24:27], v133 offset:6144
	v_mfma_f32_16x16x32_f16 v[224:227], v[224:227], v[228:231], v[84:87]
	ds_read_b128 v[28:31], v136 offset:38912
	v_mfma_f32_16x16x32_f16 v[198:201], v[232:235], v[198:201], v[64:67]
	s_nop 2
	v_mfma_f32_16x16x32_f16 v[236:239], v[202:205], v[206:209], v[92:95]
	v_mfma_f32_16x16x32_f16 v[206:209], v[232:235], v[206:209], v[72:75]
	v_mfma_f32_16x16x32_f16 v[166:169], v[202:205], v[220:223], v[166:169]
	v_mfma_f32_16x16x32_f16 v[220:223], v[232:235], v[220:223], v[80:83]
	v_mfma_f32_16x16x32_f16 v[202:205], v[202:205], v[228:231], v[68:71]
	v_mfma_f32_16x16x32_f16 v[228:231], v[232:235], v[228:231], v[88:91]
	ds_read_b128 v[232:235], v135 offset:38912
	s_nop 0
	s_waitcnt lgkmcnt(7)
	v_mfma_f32_16x16x32_f16 v[138:141], v[4:7], v[0:3], v[138:141]
	s_waitcnt lgkmcnt(5)
	v_mfma_f32_16x16x32_f16 v[142:145], v[12:15], v[0:3], v[142:145]
	s_waitcnt lgkmcnt(3)
	v_mfma_f32_16x16x32_f16 v[154:157], v[20:23], v[0:3], v[154:157]
	s_waitcnt lgkmcnt(1)
	v_mfma_f32_16x16x32_f16 v[0:3], v[28:31], v[0:3], v[198:201]
	v_mfma_f32_16x16x32_f16 v[198:201], v[4:7], v[8:11], v[236:239]
	v_mfma_f32_16x16x32_f16 v[158:161], v[12:15], v[8:11], v[158:161]
	v_and_b32_e32 v62, 7, v148
	v_bfe_u32 v63, v148, 4, 3
	v_xor_b32_e32 v63, v63, v62
	v_sub_u32_e32 v63, v63, v62
	v_lshlrev_b32_e32 v62, 4, v63
	v_add_u32_e32 v62, 0x480, v62
	v_ashrrev_i32_e32 v63, 31, v62
	v_lshl_add_u64 v[32:33], v[108:109], 0, v[62:63]
	s_mov_b32 m0, s61
	s_nop 0
	global_load_lds_dwordx4 v[32:33], off
	v_mfma_f32_16x16x32_f16 v[166:169], v[4:7], v[16:19], v[166:169]
	v_lshl_add_u64 v[36:37], v[110:111], 0, v[62:63]
	s_mov_b32 m0, s69
	s_nop 0
	global_load_lds_dwordx4 v[36:37], off
	v_lshl_add_u64 v[40:41], v[112:113], 0, v[62:63]
	s_mov_b32 m0, s73
	s_nop 0
	global_load_lds_dwordx4 v[40:41], off
	v_mfma_f32_16x16x32_f16 v[4:7], v[4:7], v[24:27], v[202:205]
	s_nop 2
	ds_read_b128 v[202:205], v135 offset:32768
	v_lshl_add_u64 v[44:45], v[114:115], 0, v[62:63]
	s_mov_b32 m0, s65
	s_nop 0
	global_load_lds_dwordx4 v[44:45], off
	v_mfma_f32_16x16x32_f16 v[190:193], v[12:15], v[16:19], v[190:193]
	v_lshl_add_u64 v[48:49], v[116:117], 0, v[62:63]
	s_mov_b32 m0, s63
	s_nop 0
	global_load_lds_dwordx4 v[48:49], off
	v_mfma_f32_16x16x32_f16 v[12:15], v[12:15], v[24:27], v[210:213]
	s_nop 2
	ds_read_b128 v[210:213], v135 offset:34816
	v_lshl_add_u64 v[52:53], v[118:119], 0, v[62:63]
	s_mov_b32 m0, s71
	s_nop 0
	global_load_lds_dwordx4 v[52:53], off
	v_mfma_f32_16x16x32_f16 v[162:165], v[20:23], v[8:11], v[162:165]
	v_lshl_add_u64 v[56:57], v[120:121], 0, v[62:63]
	s_mov_b32 m0, s75
	s_nop 0
	global_load_lds_dwordx4 v[56:57], off
	v_lshl_add_u64 v[60:61], v[122:123], 0, v[62:63]
	s_mov_b32 m0, s67
	s_nop 0
	global_load_lds_dwordx4 v[60:61], off
	v_mfma_f32_16x16x32_f16 v[8:11], v[28:31], v[8:11], v[206:209]
	s_nop 2
	ds_read_b128 v[206:209], v134 offset:2048
	v_mfma_f32_16x16x32_f16 v[194:197], v[20:23], v[16:19], v[194:197]
	v_mfma_f32_16x16x32_f16 v[20:23], v[20:23], v[24:27], v[224:227]
	s_nop 2
	ds_read_b128 v[224:227], v135 offset:36864
	v_mfma_f32_16x16x32_f16 v[16:19], v[28:31], v[16:19], v[220:223]
	s_nop 2
	ds_read_b128 v[220:223], v134 offset:4096
	v_mfma_f32_16x16x32_f16 v[24:27], v[28:31], v[24:27], v[228:231]
	ds_read_b128 v[28:31], v134
	s_waitcnt lgkmcnt(0)
	v_mfma_f32_16x16x32_f16 v[138:141], v[202:205], v[28:31], v[138:141]
	ds_read_b128 v[228:231], v134 offset:6144
	s_waitcnt vmcnt(0) lgkmcnt(0)
	s_barrier
; #define GL_LOAD(s_, kt_) if (VAR != 1) { a##s_##0 = GL_A(0, kt_); a##s_##1 = GL_A(1, kt_); a##s_##2 = GL_A(2, kt_); a##s_##3 = GL_A(3, kt_); b##s_##0 = GL_B(0, kt_); b##s_##1 = GL_B(1, kt_); b##s_##2 = GL_B(2, kt_); b##s_##3 = GL_B(3, kt_); }
; #define LDS_STORE(s_, buf_) if (VAR != 2) { LDS_ST1(sA, 0, buf_, a##s_##0) LDS_ST1(sA, 1, buf_, a##s_##1) LDS_ST1(sA, 2, buf_, a##s_##2) LDS_ST1(sA, 3, buf_, a##s_##3) LDS_ST1(sB, 0, buf_, b##s_##0) LDS_ST1(sB, 1, buf_, b##s_##1) LDS_ST1(sB, 2, buf_, b##s_##2) LDS_ST1(sB, 3, buf_, b##s_##3) }
;     ...
;   GL_LOAD(0, 0)
;   GL_LOAD(1, 1)
;   LDS_STORE(0, 0)
;   if (VAR != 4) __syncthreads();
; #pragma unroll
;   for (int kt = 0; kt < nk; kt += 2) {
;     if (kt + 2 < nk) { GL_LOAD(0, kt + 2) }
;     MMA_TILE(0)
;     LDS_STORE(1, 1)
;     if (VAR != 4) __syncthreads();
;     if (kt + 3 < nk) { GL_LOAD(1, kt + 3) }
;     MMA_TILE(1)
;     if (kt + 2 < nk) { LDS_STORE(0, 0) }
;     if (VAR != 4) __syncthreads();
	v_mfma_f32_16x16x32_f16 v[142:145], v[210:213], v[28:31], v[142:145]
	ds_read_b128 v[32:35], v133 offset:16384
	v_mfma_f32_16x16x32_f16 v[158:161], v[210:213], v[206:209], v[158:161]
	ds_read_b128 v[36:39], v136 offset:49152
	v_mfma_f32_16x16x32_f16 v[154:157], v[224:227], v[28:31], v[154:157]
	ds_read_b128 v[40:43], v133 offset:18432
	v_mfma_f32_16x16x32_f16 v[162:165], v[224:227], v[206:209], v[162:165]
	ds_read_b128 v[44:47], v136 offset:51200
	v_mfma_f32_16x16x32_f16 v[190:193], v[210:213], v[220:223], v[190:193]
	ds_read_b128 v[48:51], v133 offset:20480
	v_mfma_f32_16x16x32_f16 v[210:213], v[210:213], v[228:231], v[12:15]
	ds_read_b128 v[52:55], v136 offset:53248
	v_mfma_f32_16x16x32_f16 v[194:197], v[224:227], v[220:223], v[194:197]
	ds_read_b128 v[56:59], v133 offset:22528
	v_mfma_f32_16x16x32_f16 v[224:227], v[224:227], v[228:231], v[20:23]
	ds_read_b128 v[60:63], v136 offset:55296
	v_mfma_f32_16x16x32_f16 v[236:239], v[232:235], v[28:31], v[0:3]
	v_mfma_f32_16x16x32_f16 v[198:201], v[202:205], v[206:209], v[198:201]
	v_mfma_f32_16x16x32_f16 v[206:209], v[232:235], v[206:209], v[8:11]
	v_mfma_f32_16x16x32_f16 v[166:169], v[202:205], v[220:223], v[166:169]
	v_mfma_f32_16x16x32_f16 v[220:223], v[232:235], v[220:223], v[16:19]
	v_mfma_f32_16x16x32_f16 v[202:205], v[202:205], v[228:231], v[4:7]
	v_mfma_f32_16x16x32_f16 v[228:231], v[232:235], v[228:231], v[24:27]
	ds_read_b128 v[232:235], v135 offset:55296
	s_nop 1
	s_waitcnt lgkmcnt(7)
	v_mfma_f32_16x16x32_f16 v[138:141], v[36:39], v[32:35], v[138:141]
	s_waitcnt lgkmcnt(6)
	v_mfma_f32_16x16x32_f16 v[198:201], v[36:39], v[40:43], v[198:201]
	s_waitcnt lgkmcnt(5)
	v_mfma_f32_16x16x32_f16 v[142:145], v[44:47], v[32:35], v[142:145]
	v_mfma_f32_16x16x32_f16 v[158:161], v[44:47], v[40:43], v[158:161]
	s_waitcnt lgkmcnt(4)
	v_mfma_f32_16x16x32_f16 v[166:169], v[36:39], v[48:51], v[166:169]
	v_and_b32_e32 v94, 7, v148
	v_bfe_u32 v95, v148, 4, 3
	v_xor_b32_e32 v95, v95, v94
	v_sub_u32_e32 v95, v95, v94
	v_lshlrev_b32_e32 v94, 4, v95
	v_add_u32_e32 v94, 0x500, v94
	v_ashrrev_i32_e32 v95, 31, v94
	s_waitcnt lgkmcnt(2)
	v_mfma_f32_16x16x32_f16 v[36:39], v[36:39], v[56:59], v[202:205]
	s_nop 2
	ds_read_b128 v[202:205], v135 offset:49152
	v_lshl_add_u64 v[64:65], v[108:109], 0, v[94:95]
	s_mov_b32 m0, s60
	s_nop 0
	global_load_lds_dwordx4 v[64:65], off
	v_mfma_f32_16x16x32_f16 v[190:193], v[44:47], v[48:51], v[190:193]
	v_lshl_add_u64 v[68:69], v[110:111], 0, v[94:95]
	s_mov_b32 m0, s68
	s_nop 0
	global_load_lds_dwordx4 v[68:69], off
	v_lshl_add_u64 v[72:73], v[112:113], 0, v[94:95]
	s_mov_b32 m0, s72
	s_nop 0
	global_load_lds_dwordx4 v[72:73], off
	v_mfma_f32_16x16x32_f16 v[44:47], v[44:47], v[56:59], v[210:213]
	s_nop 2
	ds_read_b128 v[210:213], v135 offset:51200
	v_mfma_f32_16x16x32_f16 v[154:157], v[52:55], v[32:35], v[154:157]
	v_lshl_add_u64 v[76:77], v[114:115], 0, v[94:95]
	s_mov_b32 m0, s64
	s_nop 0
	global_load_lds_dwordx4 v[76:77], off
	v_mfma_f32_16x16x32_f16 v[162:165], v[52:55], v[40:43], v[162:165]
	v_lshl_add_u64 v[80:81], v[116:117], 0, v[94:95]
	s_mov_b32 m0, s62
	s_nop 0
	global_load_lds_dwordx4 v[80:81], off
	s_waitcnt lgkmcnt(3)
	v_mfma_f32_16x16x32_f16 v[32:35], v[60:63], v[32:35], v[236:239]
	v_lshl_add_u64 v[84:85], v[118:119], 0, v[94:95]
	s_mov_b32 m0, s70
	s_nop 0
	global_load_lds_dwordx4 v[84:85], off
	v_mfma_f32_16x16x32_f16 v[40:43], v[60:63], v[40:43], v[206:209]
	s_nop 2
	ds_read_b128 v[206:209], v134 offset:18432
	v_mfma_f32_16x16x32_f16 v[194:197], v[52:55], v[48:51], v[194:197]
	v_lshl_add_u64 v[88:89], v[120:121], 0, v[94:95]
	s_mov_b32 m0, s74
	s_nop 0
	global_load_lds_dwordx4 v[88:89], off
	v_mfma_f32_16x16x32_f16 v[52:55], v[52:55], v[56:59], v[224:227]
	s_nop 2
	ds_read_b128 v[224:227], v135 offset:53248
	v_mfma_f32_16x16x32_f16 v[48:51], v[60:63], v[48:51], v[220:223]
	s_nop 2
	ds_read_b128 v[220:223], v134 offset:20480
	v_mfma_f32_16x16x32_f16 v[56:59], v[60:63], v[56:59], v[228:231]
	ds_read_b128 v[60:63], v134 offset:16384
	s_waitcnt lgkmcnt(0)
	v_mfma_f32_16x16x32_f16 v[138:141], v[202:205], v[60:63], v[138:141]
	ds_read_b128 v[228:231], v134 offset:22528
	v_lshl_add_u64 v[92:93], v[122:123], 0, v[94:95]
	s_mov_b32 m0, s66
	s_nop 0
	global_load_lds_dwordx4 v[92:93], off
	s_waitcnt vmcnt(0) lgkmcnt(0)
	s_barrier
; #define GL_LOAD(s_, kt_) if (VAR != 1) { a##s_##0 = GL_A(0, kt_); a##s_##1 = GL_A(1, kt_); a##s_##2 = GL_A(2, kt_); a##s_##3 = GL_A(3, kt_); b##s_##0 = GL_B(0, kt_); b##s_##1 = GL_B(1, kt_); b##s_##2 = GL_B(2, kt_); b##s_##3 = GL_B(3, kt_); }
; #define LDS_STORE(s_, buf_) if (VAR != 2) { LDS_ST1(sA, 0, buf_, a##s_##0) LDS_ST1(sA, 1, buf_, a##s_##1) LDS_ST1(sA, 2, buf_, a##s_##2) LDS_ST1(sA, 3, buf_, a##s_##3) LDS_ST1(sB, 0, buf_, b##s_##0) LDS_ST1(sB, 1, buf_, b##s_##1) LDS_ST1(sB, 2, buf_, b##s_##2) LDS_ST1(sB, 3, buf_, b##s_##3) }
;     ...
;   GL_LOAD(0, 0)
;   GL_LOAD(1, 1)
;   LDS_STORE(0, 0)
;   if (VAR != 4) __syncthreads();
; #pragma unroll
;   for (int kt = 0; kt < nk; kt += 2) {
;     if (kt + 2 < nk) { GL_LOAD(0, kt + 2) }
;     MMA_TILE(0)
;     LDS_STORE(1, 1)
;     if (VAR != 4) __syncthreads();
;     if (kt + 3 < nk) { GL_LOAD(1, kt + 3) }
;     MMA_TILE(1)
;     if (kt + 2 < nk) { LDS_STORE(0, 0) }
;     if (VAR != 4) __syncthreads();
	v_mfma_f32_16x16x32_f16 v[142:145], v[210:213], v[60:63], v[142:145]
	ds_read_b128 v[64:67], v133
	v_mfma_f32_16x16x32_f16 v[158:161], v[210:213], v[206:209], v[158:161]
	ds_read_b128 v[68:71], v136 offset:32768
	v_mfma_f32_16x16x32_f16 v[154:157], v[224:227], v[60:63], v[154:157]
	ds_read_b128 v[72:75], v133 offset:2048
	v_mfma_f32_16x16x32_f16 v[162:165], v[224:227], v[206:209], v[162:165]
	ds_read_b128 v[76:79], v136 offset:34816
	v_mfma_f32_16x16x32_f16 v[190:193], v[210:213], v[220:223], v[190:193]
	ds_read_b128 v[80:83], v133 offset:4096
	v_mfma_f32_16x16x32_f16 v[210:213], v[210:213], v[228:231], v[44:47]
	ds_read_b128 v[84:87], v136 offset:36864
	v_mfma_f32_16x16x32_f16 v[194:197], v[224:227], v[220:223], v[194:197]
	ds_read_b128 v[88:91], v133 offset:6144
	v_mfma_f32_16x16x32_f16 v[224:227], v[224:227], v[228:231], v[52:55]
	ds_read_b128 v[92:95], v136 offset:38912
	v_mfma_f32_16x16x32_f16 v[236:239], v[232:235], v[60:63], v[32:35]
	s_nop 0
	v_mfma_f32_16x16x32_f16 v[198:201], v[202:205], v[206:209], v[198:201]
	v_mfma_f32_16x16x32_f16 v[206:209], v[232:235], v[206:209], v[40:43]
	v_mfma_f32_16x16x32_f16 v[166:169], v[202:205], v[220:223], v[166:169]
	v_mfma_f32_16x16x32_f16 v[220:223], v[232:235], v[220:223], v[48:51]
	v_mfma_f32_16x16x32_f16 v[202:205], v[202:205], v[228:231], v[36:39]
	v_mfma_f32_16x16x32_f16 v[228:231], v[232:235], v[228:231], v[56:59]
	ds_read_b128 v[232:235], v135 offset:38912
	s_nop 1
	s_waitcnt lgkmcnt(7)
	v_mfma_f32_16x16x32_f16 v[138:141], v[68:71], v[64:67], v[138:141]
	s_waitcnt lgkmcnt(6)
	v_mfma_f32_16x16x32_f16 v[198:201], v[68:71], v[72:75], v[198:201]
	s_waitcnt lgkmcnt(5)
	v_mfma_f32_16x16x32_f16 v[142:145], v[76:79], v[64:67], v[142:145]
	v_mfma_f32_16x16x32_f16 v[158:161], v[76:79], v[72:75], v[158:161]
	s_waitcnt lgkmcnt(4)
	v_mfma_f32_16x16x32_f16 v[166:169], v[68:71], v[80:83], v[166:169]
	v_and_b32_e32 v10, 7, v148
	v_bfe_u32 v11, v148, 4, 3
	v_xor_b32_e32 v11, v11, v10
	v_sub_u32_e32 v11, v11, v10
	v_lshlrev_b32_e32 v10, 4, v11
	v_add_u32_e32 v10, 0x580, v10
	v_ashrrev_i32_e32 v11, 31, v10
	v_lshl_add_u64 v[28:29], v[108:109], 0, v[10:11]
	s_mov_b32 m0, s61
	s_nop 0
	global_load_lds_dwordx4 v[28:29], off
	s_waitcnt lgkmcnt(2)
	v_mfma_f32_16x16x32_f16 v[68:71], v[68:71], v[88:91], v[202:205]
	s_nop 2
	ds_read_b128 v[202:205], v135 offset:32768
	v_lshl_add_u64 v[24:25], v[110:111], 0, v[10:11]
	s_mov_b32 m0, s69
	s_nop 0
	global_load_lds_dwordx4 v[24:25], off
	v_mfma_f32_16x16x32_f16 v[190:193], v[76:79], v[80:83], v[190:193]
	v_lshl_add_u64 v[12:13], v[112:113], 0, v[10:11]
	s_mov_b32 m0, s73
	s_nop 0
	global_load_lds_dwordx4 v[12:13], off
	v_lshl_add_u64 v[16:17], v[114:115], 0, v[10:11]
	s_mov_b32 m0, s65
	s_nop 0
	global_load_lds_dwordx4 v[16:17], off
	v_mfma_f32_16x16x32_f16 v[76:79], v[76:79], v[88:91], v[210:213]
	s_nop 2
	ds_read_b128 v[210:213], v135 offset:34816
	v_mfma_f32_16x16x32_f16 v[154:157], v[84:87], v[64:67], v[154:157]
	v_lshl_add_u64 v[20:21], v[116:117], 0, v[10:11]
	s_mov_b32 m0, s63
	s_nop 0
	global_load_lds_dwordx4 v[20:21], off
	v_mfma_f32_16x16x32_f16 v[162:165], v[84:87], v[72:75], v[162:165]
	v_lshl_add_u64 v[0:1], v[118:119], 0, v[10:11]
	s_mov_b32 m0, s71
	s_nop 0
	global_load_lds_dwordx4 v[0:1], off
	s_waitcnt lgkmcnt(3)
	v_mfma_f32_16x16x32_f16 v[64:67], v[92:95], v[64:67], v[236:239]
	v_lshl_add_u64 v[4:5], v[120:121], 0, v[10:11]
	s_mov_b32 m0, s75
	s_nop 0
	global_load_lds_dwordx4 v[4:5], off
	v_mfma_f32_16x16x32_f16 v[72:75], v[92:95], v[72:75], v[206:209]
	s_nop 2
	ds_read_b128 v[206:209], v134 offset:2048
	v_mfma_f32_16x16x32_f16 v[194:197], v[84:87], v[80:83], v[194:197]
	v_lshl_add_u64 v[8:9], v[122:123], 0, v[10:11]
	s_mov_b32 m0, s67
	s_nop 0
	global_load_lds_dwordx4 v[8:9], off
	v_mfma_f32_16x16x32_f16 v[84:87], v[84:87], v[88:91], v[224:227]
	s_nop 2
	ds_read_b128 v[224:227], v135 offset:36864
	v_mfma_f32_16x16x32_f16 v[80:83], v[92:95], v[80:83], v[220:223]
	s_nop 2
	ds_read_b128 v[220:223], v134 offset:4096
	v_mfma_f32_16x16x32_f16 v[88:91], v[92:95], v[88:91], v[228:231]
	ds_read_b128 v[92:95], v134
	s_nop 1
	ds_read_b128 v[228:231], v134 offset:6144
	s_waitcnt vmcnt(0) lgkmcnt(0)
	s_barrier
	v_mfma_f32_16x16x32_f16 v[138:141], v[202:205], v[92:95], v[138:141]
	v_mfma_f32_16x16x32_f16 v[142:145], v[210:213], v[92:95], v[142:145]
	v_mfma_f32_16x16x32_f16 v[154:157], v[224:227], v[92:95], v[154:157]
	v_mfma_f32_16x16x32_f16 v[64:67], v[232:235], v[92:95], v[64:67]
	v_mfma_f32_16x16x32_f16 v[92:95], v[202:205], v[206:209], v[198:201]
	s_nop 2
	ds_read_b128 v[198:201], v133 offset:16384
	v_mfma_f32_16x16x32_f16 v[158:161], v[210:213], v[206:209], v[158:161]
	v_mfma_f32_16x16x32_f16 v[166:169], v[202:205], v[220:223], v[166:169]
	v_mfma_f32_16x16x32_f16 v[68:71], v[202:205], v[228:231], v[68:71]
	ds_read_b128 v[202:205], v136 offset:49152
	v_mfma_f32_16x16x32_f16 v[190:193], v[210:213], v[220:223], v[190:193]
	v_mfma_f32_16x16x32_f16 v[76:79], v[210:213], v[228:231], v[76:79]
	ds_read_b128 v[210:213], v136 offset:51200
	v_mfma_f32_16x16x32_f16 v[162:165], v[224:227], v[206:209], v[162:165]
	v_mfma_f32_16x16x32_f16 v[72:75], v[232:235], v[206:209], v[72:75]
	ds_read_b128 v[206:209], v133 offset:18432
	v_mfma_f32_16x16x32_f16 v[194:197], v[224:227], v[220:223], v[194:197]
	v_and_b32_e32 v38, 7, v148
	v_bfe_u32 v39, v148, 4, 3
	v_xor_b32_e32 v39, v39, v38
	v_sub_u32_e32 v39, v39, v38
	v_lshlrev_b32_e32 v38, 4, v39
	v_add_u32_e32 v38, 0x600, v38
	v_ashrrev_i32_e32 v39, 31, v38
	v_mfma_f32_16x16x32_f16 v[84:87], v[224:227], v[228:231], v[84:87]
	ds_read_b128 v[224:227], v136 offset:53248
	v_mfma_f32_16x16x32_f16 v[80:83], v[232:235], v[220:223], v[80:83]
	ds_read_b128 v[220:223], v133 offset:20480
	v_mfma_f32_16x16x32_f16 v[88:91], v[232:235], v[228:231], v[88:91]
	ds_read_b128 v[228:231], v133 offset:22528
	s_waitcnt lgkmcnt(5)
; #define GL_LOAD(s_, kt_) if (VAR != 1) { a##s_##0 = GL_A(0, kt_); a##s_##1 = GL_A(1, kt_); a##s_##2 = GL_A(2, kt_); a##s_##3 = GL_A(3, kt_); b##s_##0 = GL_B(0, kt_); b##s_##1 = GL_B(1, kt_); b##s_##2 = GL_B(2, kt_); b##s_##3 = GL_B(3, kt_); }
; #define LDS_STORE(s_, buf_) if (VAR != 2) { LDS_ST1(sA, 0, buf_, a##s_##0) LDS_ST1(sA, 1, buf_, a##s_##1) LDS_ST1(sA, 2, buf_, a##s_##2) LDS_ST1(sA, 3, buf_, a##s_##3) LDS_ST1(sB, 0, buf_, b##s_##0) LDS_ST1(sB, 1, buf_, b##s_##1) LDS_ST1(sB, 2, buf_, b##s_##2) LDS_ST1(sB, 3, buf_, b##s_##3) }
;     ...
;   GL_LOAD(0, 0)
;   GL_LOAD(1, 1)
;   LDS_STORE(0, 0)
;   if (VAR != 4) __syncthreads();
; #pragma unroll
;   for (int kt = 0; kt < nk; kt += 2) {
;     if (kt + 2 < nk) { GL_LOAD(0, kt + 2) }
;     MMA_TILE(0)
;     LDS_STORE(1, 1)
;     if (VAR != 4) __syncthreads();
;     if (kt + 3 < nk) { GL_LOAD(1, kt + 3) }
;     MMA_TILE(1)
;     if (kt + 2 < nk) { LDS_STORE(0, 0) }
;     if (VAR != 4) __syncthreads();
	v_mfma_f32_16x16x32_f16 v[138:141], v[202:205], v[198:201], v[138:141]
	ds_read_b128 v[232:235], v136 offset:55296
	s_waitcnt lgkmcnt(4)
	v_mfma_f32_16x16x32_f16 v[92:95], v[202:205], v[206:209], v[92:95]
	v_lshl_add_u64 v[52:53], v[108:109], 0, v[38:39]
	s_mov_b32 m0, s60
	s_nop 0
	global_load_lds_dwordx4 v[52:53], off
	v_mfma_f32_16x16x32_f16 v[142:145], v[210:213], v[198:201], v[142:145]
	v_lshl_add_u64 v[56:57], v[110:111], 0, v[38:39]
	s_mov_b32 m0, s68
	s_nop 0
	global_load_lds_dwordx4 v[56:57], off
	v_mfma_f32_16x16x32_f16 v[158:161], v[210:213], v[206:209], v[158:161]
	v_lshl_add_u64 v[60:61], v[112:113], 0, v[38:39]
	s_mov_b32 m0, s72
	s_nop 0
	global_load_lds_dwordx4 v[60:61], off
	s_waitcnt lgkmcnt(2)
	v_mfma_f32_16x16x32_f16 v[166:169], v[202:205], v[220:223], v[166:169]
	v_lshl_add_u64 v[40:41], v[114:115], 0, v[38:39]
	s_mov_b32 m0, s64
	s_nop 0
	global_load_lds_dwordx4 v[40:41], off
	s_waitcnt lgkmcnt(1)
	v_mfma_f32_16x16x32_f16 v[68:71], v[202:205], v[228:231], v[68:71]
	ds_read_b128 v[202:205], v135 offset:49152
	v_mfma_f32_16x16x32_f16 v[190:193], v[210:213], v[220:223], v[190:193]
	v_lshl_add_u64 v[44:45], v[116:117], 0, v[38:39]
	s_mov_b32 m0, s62
	s_nop 0
	global_load_lds_dwordx4 v[44:45], off
	v_mfma_f32_16x16x32_f16 v[76:79], v[210:213], v[228:231], v[76:79]
	ds_read_b128 v[210:213], v135 offset:51200
	v_mfma_f32_16x16x32_f16 v[154:157], v[224:227], v[198:201], v[154:157]
	v_lshl_add_u64 v[48:49], v[118:119], 0, v[38:39]
	s_mov_b32 m0, s70
	s_nop 0
	global_load_lds_dwordx4 v[48:49], off
	v_mfma_f32_16x16x32_f16 v[162:165], v[224:227], v[206:209], v[162:165]
	v_lshl_add_u64 v[32:33], v[120:121], 0, v[38:39]
	s_mov_b32 m0, s74
	s_nop 0
	global_load_lds_dwordx4 v[32:33], off
	s_waitcnt lgkmcnt(2)
	v_mfma_f32_16x16x32_f16 v[64:67], v[232:235], v[198:201], v[64:67]
	ds_read_b128 v[198:201], v134 offset:16384
	v_mfma_f32_16x16x32_f16 v[72:75], v[232:235], v[206:209], v[72:75]
	ds_read_b128 v[206:209], v134 offset:18432
	v_mfma_f32_16x16x32_f16 v[194:197], v[224:227], v[220:223], v[194:197]
	v_lshl_add_u64 v[36:37], v[122:123], 0, v[38:39]
	s_mov_b32 m0, s66
	s_nop 0
	global_load_lds_dwordx4 v[36:37], off
	v_mfma_f32_16x16x32_f16 v[84:87], v[224:227], v[228:231], v[84:87]
	ds_read_b128 v[224:227], v135 offset:53248
	v_mfma_f32_16x16x32_f16 v[80:83], v[232:235], v[220:223], v[80:83]
	ds_read_b128 v[220:223], v134 offset:20480
	v_mfma_f32_16x16x32_f16 v[88:91], v[232:235], v[228:231], v[88:91]
	ds_read_b128 v[228:231], v134 offset:22528
	ds_read_b128 v[232:235], v135 offset:55296
	s_waitcnt vmcnt(0) lgkmcnt(0)
	s_barrier
	v_mfma_f32_16x16x32_f16 v[138:141], v[202:205], v[198:201], v[138:141]
	v_and_b32_e32 v6, 7, v148
	v_bfe_u32 v7, v148, 4, 3
	v_xor_b32_e32 v7, v7, v6
	v_sub_u32_e32 v7, v7, v6
	v_lshlrev_b32_e32 v6, 4, v7
	v_add_u32_e32 v6, 0x680, v6
	v_ashrrev_i32_e32 v7, 31, v6
	v_mfma_f32_16x16x32_f16 v[92:95], v[202:205], v[206:209], v[92:95]
	global_load_dwordx4 v[60:63], v[108:109], off offset:1792
	v_mfma_f32_16x16x32_f16 v[142:145], v[210:213], v[198:201], v[142:145]
	global_load_dwordx4 v[48:51], v[110:111], off offset:1792
	v_mfma_f32_16x16x32_f16 v[158:161], v[210:213], v[206:209], v[158:161]
	global_load_dwordx4 v[52:55], v[112:113], off offset:1792
	v_mfma_f32_16x16x32_f16 v[166:169], v[202:205], v[220:223], v[166:169]
	global_load_dwordx4 v[56:59], v[114:115], off offset:1792
	v_mfma_f32_16x16x32_f16 v[68:71], v[202:205], v[228:231], v[68:71]
	ds_read_b128 v[202:205], v136 offset:32768
	v_mfma_f32_16x16x32_f16 v[190:193], v[210:213], v[220:223], v[190:193]
	global_load_dwordx4 v[36:39], v[116:117], off offset:1792
	v_mfma_f32_16x16x32_f16 v[76:79], v[210:213], v[228:231], v[76:79]
	ds_read_b128 v[210:213], v136 offset:34816
	v_mfma_f32_16x16x32_f16 v[154:157], v[224:227], v[198:201], v[154:157]
	global_load_dwordx4 v[40:43], v[118:119], off offset:1792
	v_mfma_f32_16x16x32_f16 v[162:165], v[224:227], v[206:209], v[162:165]
	global_load_dwordx4 v[44:47], v[120:121], off offset:1792
	v_mfma_f32_16x16x32_f16 v[64:67], v[232:235], v[198:201], v[64:67]
	ds_read_b128 v[198:201], v133
	v_mfma_f32_16x16x32_f16 v[72:75], v[232:235], v[206:209], v[72:75]
	ds_read_b128 v[206:209], v133 offset:2048
	v_mfma_f32_16x16x32_f16 v[194:197], v[224:227], v[220:223], v[194:197]
	global_load_dwordx4 v[32:35], v[122:123], off offset:1792
	v_mfma_f32_16x16x32_f16 v[84:87], v[224:227], v[228:231], v[84:87]
	ds_read_b128 v[224:227], v136 offset:36864
	v_mfma_f32_16x16x32_f16 v[80:83], v[232:235], v[220:223], v[80:83]
	ds_read_b128 v[220:223], v133 offset:4096
	v_mfma_f32_16x16x32_f16 v[88:91], v[232:235], v[228:231], v[88:91]
	ds_read_b128 v[228:231], v133 offset:6144
	s_waitcnt lgkmcnt(4)
	v_mfma_f32_16x16x32_f16 v[138:141], v[202:205], v[198:201], v[138:141]
	ds_read_b128 v[232:235], v136 offset:38912
	s_waitcnt lgkmcnt(4)
	v_mfma_f32_16x16x32_f16 v[92:95], v[202:205], v[206:209], v[92:95]
	v_lshl_add_u64 v[20:21], v[108:109], 0, v[6:7]
	s_mov_b32 m0, s61
	s_nop 0
	global_load_lds_dwordx4 v[20:21], off
	v_mfma_f32_16x16x32_f16 v[142:145], v[210:213], v[198:201], v[142:145]
	v_lshl_add_u64 v[24:25], v[110:111], 0, v[6:7]
	s_mov_b32 m0, s69
	s_nop 0
	global_load_lds_dwordx4 v[24:25], off
	v_mfma_f32_16x16x32_f16 v[158:161], v[210:213], v[206:209], v[158:161]
	v_lshl_add_u64 v[28:29], v[112:113], 0, v[6:7]
	s_mov_b32 m0, s73
	s_nop 0
	global_load_lds_dwordx4 v[28:29], off
	s_waitcnt lgkmcnt(2)
	v_mfma_f32_16x16x32_f16 v[166:169], v[202:205], v[220:223], v[166:169]
	v_lshl_add_u64 v[8:9], v[114:115], 0, v[6:7]
	s_mov_b32 m0, s65
	s_nop 0
	global_load_lds_dwordx4 v[8:9], off
	s_waitcnt lgkmcnt(1)
; #define GL_LOAD(s_, kt_) if (VAR != 1) { a##s_##0 = GL_A(0, kt_); a##s_##1 = GL_A(1, kt_); a##s_##2 = GL_A(2, kt_); a##s_##3 = GL_A(3, kt_); b##s_##0 = GL_B(0, kt_); b##s_##1 = GL_B(1, kt_); b##s_##2 = GL_B(2, kt_); b##s_##3 = GL_B(3, kt_); }
; #define LDS_STORE(s_, buf_) if (VAR != 2) { LDS_ST1(sA, 0, buf_, a##s_##0) LDS_ST1(sA, 1, buf_, a##s_##1) LDS_ST1(sA, 2, buf_, a##s_##2) LDS_ST1(sA, 3, buf_, a##s_##3) LDS_ST1(sB, 0, buf_, b##s_##0) LDS_ST1(sB, 1, buf_, b##s_##1) LDS_ST1(sB, 2, buf_, b##s_##2) LDS_ST1(sB, 3, buf_, b##s_##3) }
;     ...
;   GL_LOAD(0, 0)
;   GL_LOAD(1, 1)
;   LDS_STORE(0, 0)
;   if (VAR != 4) __syncthreads();
; #pragma unroll
;   for (int kt = 0; kt < nk; kt += 2) {
;     if (kt + 2 < nk) { GL_LOAD(0, kt + 2) }
;     MMA_TILE(0)
;     LDS_STORE(1, 1)
;     if (VAR != 4) __syncthreads();
;     if (kt + 3 < nk) { GL_LOAD(1, kt + 3) }
;     MMA_TILE(1)
;     if (kt + 2 < nk) { LDS_STORE(0, 0) }
;     if (VAR != 4) __syncthreads();
	v_mfma_f32_16x16x32_f16 v[68:71], v[202:205], v[228:231], v[68:71]
	ds_read_b128 v[202:205], v135 offset:32768
	v_mfma_f32_16x16x32_f16 v[190:193], v[210:213], v[220:223], v[190:193]
	v_lshl_add_u64 v[12:13], v[116:117], 0, v[6:7]
	s_mov_b32 m0, s63
	s_nop 0
	global_load_lds_dwordx4 v[12:13], off
	v_mfma_f32_16x16x32_f16 v[76:79], v[210:213], v[228:231], v[76:79]
	ds_read_b128 v[210:213], v135 offset:34816
	v_mfma_f32_16x16x32_f16 v[154:157], v[224:227], v[198:201], v[154:157]
	v_lshl_add_u64 v[16:17], v[118:119], 0, v[6:7]
	s_mov_b32 m0, s71
	s_nop 0
	global_load_lds_dwordx4 v[16:17], off
	v_mfma_f32_16x16x32_f16 v[162:165], v[224:227], v[206:209], v[162:165]
	v_lshl_add_u64 v[0:1], v[120:121], 0, v[6:7]
	s_mov_b32 m0, s75
	s_nop 0
	global_load_lds_dwordx4 v[0:1], off
	s_waitcnt lgkmcnt(2)
	v_mfma_f32_16x16x32_f16 v[64:67], v[232:235], v[198:201], v[64:67]
	ds_read_b128 v[198:201], v134
	v_mfma_f32_16x16x32_f16 v[72:75], v[232:235], v[206:209], v[72:75]
	ds_read_b128 v[206:209], v134 offset:2048
	v_mfma_f32_16x16x32_f16 v[194:197], v[224:227], v[220:223], v[194:197]
	v_lshl_add_u64 v[4:5], v[122:123], 0, v[6:7]
	s_mov_b32 m0, s67
	s_nop 0
	global_load_lds_dwordx4 v[4:5], off
	v_mfma_f32_16x16x32_f16 v[84:87], v[224:227], v[228:231], v[84:87]
	ds_read_b128 v[224:227], v135 offset:36864
	v_mfma_f32_16x16x32_f16 v[80:83], v[232:235], v[220:223], v[80:83]
	ds_read_b128 v[220:223], v134 offset:4096
	v_mfma_f32_16x16x32_f16 v[88:91], v[232:235], v[228:231], v[88:91]
	ds_read_b128 v[228:231], v134 offset:6144
	ds_read_b128 v[232:235], v135 offset:38912
	s_waitcnt vmcnt(0) lgkmcnt(0)
	s_barrier
	v_mfma_f32_16x16x32_f16 v[138:141], v[202:205], v[198:201], v[138:141]
	global_load_dwordx4 v[28:31], v[108:109], off offset:1920
	v_mfma_f32_16x16x32_f16 v[92:95], v[202:205], v[206:209], v[92:95]
	global_load_dwordx4 v[16:19], v[110:111], off offset:1920
	v_mfma_f32_16x16x32_f16 v[142:145], v[210:213], v[198:201], v[142:145]
	ds_read_b128 v[108:111], v133 offset:16384
	v_mfma_f32_16x16x32_f16 v[158:161], v[210:213], v[206:209], v[158:161]
	global_load_dwordx4 v[20:23], v[112:113], off offset:1920
	v_mfma_f32_16x16x32_f16 v[166:169], v[202:205], v[220:223], v[166:169]
	global_load_dwordx4 v[24:27], v[114:115], off offset:1920
	v_mfma_f32_16x16x32_f16 v[68:71], v[202:205], v[228:231], v[68:71]
	ds_read_b128 v[112:115], v136 offset:49152
	v_mfma_f32_16x16x32_f16 v[190:193], v[210:213], v[220:223], v[190:193]
	ds_read_b128 v[202:205], v136 offset:53248
	v_mfma_f32_16x16x32_f16 v[76:79], v[210:213], v[228:231], v[76:79]
	ds_read_b128 v[210:213], v136 offset:55296
	v_mfma_f32_16x16x32_f16 v[154:157], v[224:227], v[198:201], v[154:157]
	global_load_dwordx4 v[4:7], v[116:117], off offset:1920
	v_mfma_f32_16x16x32_f16 v[162:165], v[224:227], v[206:209], v[162:165]
	global_load_dwordx4 v[8:11], v[118:119], off offset:1920
	v_mfma_f32_16x16x32_f16 v[64:67], v[232:235], v[198:201], v[64:67]
	ds_read_b128 v[116:119], v133 offset:18432
	v_mfma_f32_16x16x32_f16 v[72:75], v[232:235], v[206:209], v[72:75]
	ds_read_b128 v[198:201], v133 offset:20480
	v_mfma_f32_16x16x32_f16 v[194:197], v[224:227], v[220:223], v[194:197]
	ds_read_b128 v[206:209], v133 offset:22528
	v_mfma_f32_16x16x32_f16 v[84:87], v[224:227], v[228:231], v[84:87]
	global_load_dwordx4 v[12:15], v[120:121], off offset:1920
	v_mfma_f32_16x16x32_f16 v[80:83], v[232:235], v[220:223], v[80:83]
	global_load_dwordx4 v[0:3], v[122:123], off offset:1920
	v_mfma_f32_16x16x32_f16 v[88:91], v[232:235], v[228:231], v[88:91]
	ds_read_b128 v[120:123], v136 offset:51200
	s_waitcnt lgkmcnt(6)
	v_mfma_f32_16x16x32_f16 v[138:141], v[112:115], v[108:111], v[138:141]
	ds_write_b128 v101, v[60:63]
	s_waitcnt lgkmcnt(4)
	v_mfma_f32_16x16x32_f16 v[92:95], v[112:115], v[116:119], v[92:95]
	ds_write_b128 v131, v[48:51]
	s_waitcnt lgkmcnt(2)
	v_mfma_f32_16x16x32_f16 v[142:145], v[120:123], v[108:111], v[142:145]
	ds_write_b128 v132, v[52:55]
	v_mfma_f32_16x16x32_f16 v[154:157], v[202:205], v[108:111], v[154:157]
	v_mfma_f32_16x16x32_f16 v[64:67], v[210:213], v[108:111], v[64:67]
	v_mfma_f32_16x16x32_f16 v[108:111], v[120:123], v[116:119], v[158:161]
	ds_write_b128 v130, v[56:59]
	v_mfma_f32_16x16x32_f16 v[158:161], v[202:205], v[116:119], v[162:165]
	v_mfma_f32_16x16x32_f16 v[72:75], v[210:213], v[116:119], v[72:75]
	v_mfma_f32_16x16x32_f16 v[116:119], v[112:115], v[198:201], v[166:169]
	ds_write_b128 v101, v[36:39] offset:32768
	ds_write_b128 v131, v[40:43] offset:32768
	v_mfma_f32_16x16x32_f16 v[68:71], v[112:115], v[206:209], v[68:71]
	ds_read_b128 v[112:115], v134 offset:16384
	ds_write_b128 v132, v[44:47] offset:32768
	v_mfma_f32_16x16x32_f16 v[162:165], v[120:123], v[198:201], v[190:193]
	s_nop 2
	ds_read_b128 v[190:193], v134 offset:18432
	v_mfma_f32_16x16x32_f16 v[76:79], v[120:123], v[206:209], v[76:79]
	ds_read_b128 v[120:123], v135 offset:49152
	ds_write_b128 v130, v[32:35] offset:32768
	v_mfma_f32_16x16x32_f16 v[166:169], v[202:205], v[198:201], v[194:197]
	s_nop 2
	ds_read_b128 v[194:197], v135 offset:51200
	v_mfma_f32_16x16x32_f16 v[84:87], v[202:205], v[206:209], v[84:87]
	ds_read_b128 v[202:205], v135 offset:53248
	v_mfma_f32_16x16x32_f16 v[80:83], v[210:213], v[198:201], v[80:83]
	ds_read_b128 v[198:201], v134 offset:20480
	v_mfma_f32_16x16x32_f16 v[88:91], v[210:213], v[206:209], v[88:91]
	ds_read_b128 v[206:209], v134 offset:22528
	s_waitcnt lgkmcnt(5)
	v_mfma_f32_16x16x32_f16 v[138:141], v[120:123], v[112:115], v[138:141]
	ds_read_b128 v[210:213], v135 offset:55296
	s_waitcnt lgkmcnt(0)
	s_barrier
; #define GL_LOAD(s_, kt_) if (VAR != 1) { a##s_##0 = GL_A(0, kt_); a##s_##1 = GL_A(1, kt_); a##s_##2 = GL_A(2, kt_); a##s_##3 = GL_A(3, kt_); b##s_##0 = GL_B(0, kt_); b##s_##1 = GL_B(1, kt_); b##s_##2 = GL_B(2, kt_); b##s_##3 = GL_B(3, kt_); }
; #define LDS_STORE(s_, buf_) if (VAR != 2) { LDS_ST1(sA, 0, buf_, a##s_##0) LDS_ST1(sA, 1, buf_, a##s_##1) LDS_ST1(sA, 2, buf_, a##s_##2) LDS_ST1(sA, 3, buf_, a##s_##3) LDS_ST1(sB, 0, buf_, b##s_##0) LDS_ST1(sB, 1, buf_, b##s_##1) LDS_ST1(sB, 2, buf_, b##s_##2) LDS_ST1(sB, 3, buf_, b##s_##3) }
;     ...
;   GL_LOAD(0, 0)
;   GL_LOAD(1, 1)
;   LDS_STORE(0, 0)
;   if (VAR != 4) __syncthreads();
; #pragma unroll
;   for (int kt = 0; kt < nk; kt += 2) {
;     if (kt + 2 < nk) { GL_LOAD(0, kt + 2) }
;     MMA_TILE(0)
;     LDS_STORE(1, 1)
;     if (VAR != 4) __syncthreads();
;     if (kt + 3 < nk) { GL_LOAD(1, kt + 3) }
;     MMA_TILE(1)
;     if (kt + 2 < nk) { LDS_STORE(0, 0) }
;     if (VAR != 4) __syncthreads();
	v_mfma_f32_16x16x32_f16 v[142:145], v[194:197], v[112:115], v[142:145]
	ds_read_b128 v[32:35], v133
	v_mfma_f32_16x16x32_f16 v[108:111], v[194:197], v[190:193], v[108:111]
	ds_read_b128 v[36:39], v136 offset:32768
	v_mfma_f32_16x16x32_f16 v[154:157], v[202:205], v[112:115], v[154:157]
	ds_read_b128 v[40:43], v133 offset:2048
	v_mfma_f32_16x16x32_f16 v[64:67], v[210:213], v[112:115], v[64:67]
	v_mfma_f32_16x16x32_f16 v[112:115], v[202:205], v[190:193], v[158:161]
	ds_read_b128 v[44:47], v136 offset:34816
	v_mfma_f32_16x16x32_f16 v[158:161], v[194:197], v[198:201], v[162:165]
	ds_read_b128 v[48:51], v133 offset:4096
	v_mfma_f32_16x16x32_f16 v[76:79], v[194:197], v[206:209], v[76:79]
	ds_read_b128 v[52:55], v136 offset:36864
	v_mfma_f32_16x16x32_f16 v[162:165], v[202:205], v[198:201], v[166:169]
	ds_read_b128 v[56:59], v133 offset:6144
	v_mfma_f32_16x16x32_f16 v[84:87], v[202:205], v[206:209], v[84:87]
	ds_read_b128 v[60:63], v136 offset:38912
	s_waitcnt vmcnt(7)
	ds_write_b128 v101, v[28:31] offset:16384
	v_mfma_f32_16x16x32_f16 v[72:75], v[210:213], v[190:193], v[72:75]
	s_waitcnt vmcnt(6)
	ds_write_b128 v131, v[16:19] offset:16384
	v_mfma_f32_16x16x32_f16 v[92:95], v[120:123], v[190:193], v[92:95]
	s_waitcnt vmcnt(5)
	ds_write_b128 v132, v[20:23] offset:16384
	v_mfma_f32_16x16x32_f16 v[80:83], v[210:213], v[198:201], v[80:83]
	s_waitcnt vmcnt(4)
	ds_write_b128 v130, v[24:27] offset:16384
	v_mfma_f32_16x16x32_f16 v[88:91], v[210:213], v[206:209], v[88:91]
	s_waitcnt vmcnt(3)
	ds_write_b128 v101, v[4:7] offset:49152
	v_mfma_f32_16x16x32_f16 v[116:119], v[120:123], v[198:201], v[116:119]
	s_waitcnt vmcnt(2)
	ds_write_b128 v131, v[8:11] offset:49152
	v_mfma_f32_16x16x32_f16 v[68:71], v[120:123], v[206:209], v[68:71]
	s_waitcnt vmcnt(1)
	ds_write_b128 v132, v[12:15] offset:49152
	s_waitcnt lgkmcnt(13)
	v_mfma_f32_16x16x32_f16 v[120:123], v[36:39], v[32:35], v[138:141]
	s_waitcnt vmcnt(0)
	ds_write_b128 v130, v[0:3] offset:49152
	s_waitcnt lgkmcnt(12)
	v_mfma_f32_16x16x32_f16 v[138:141], v[44:47], v[32:35], v[142:145]
	s_waitcnt lgkmcnt(10)
	v_mfma_f32_16x16x32_f16 v[142:145], v[52:55], v[32:35], v[154:157]
	s_waitcnt lgkmcnt(8)
	v_mfma_f32_16x16x32_f16 v[32:35], v[60:63], v[32:35], v[64:67]
	v_mfma_f32_16x16x32_f16 v[64:67], v[36:39], v[40:43], v[92:95]
	ds_read_b128 v[154:157], v134 offset:6144
	v_mfma_f32_16x16x32_f16 v[92:95], v[44:47], v[40:43], v[108:111]
	v_mfma_f32_16x16x32_f16 v[108:111], v[52:55], v[40:43], v[112:115]
	v_mfma_f32_16x16x32_f16 v[40:43], v[60:63], v[40:43], v[72:75]
	v_mfma_f32_16x16x32_f16 v[72:75], v[36:39], v[48:51], v[116:119]
	v_mfma_f32_16x16x32_f16 v[36:39], v[36:39], v[56:59], v[68:71]
	s_nop 2
	ds_read_b128 v[68:71], v135 offset:32768
	v_mfma_f32_16x16x32_f16 v[112:115], v[44:47], v[48:51], v[158:161]
	s_nop 2
	ds_read_b128 v[158:161], v135 offset:38912
	v_mfma_f32_16x16x32_f16 v[44:47], v[44:47], v[56:59], v[76:79]
	s_nop 2
	ds_read_b128 v[76:79], v134 offset:2048
	v_mfma_f32_16x16x32_f16 v[116:119], v[52:55], v[48:51], v[162:165]
	v_mfma_f32_16x16x32_f16 v[52:55], v[52:55], v[56:59], v[84:87]
	s_nop 2
	ds_read_b128 v[84:87], v134 offset:4096
	v_mfma_f32_16x16x32_f16 v[48:51], v[60:63], v[48:51], v[80:83]
	s_nop 2
	ds_read_b128 v[80:83], v135 offset:34816
	v_mfma_f32_16x16x32_f16 v[56:59], v[60:63], v[56:59], v[88:91]
	ds_read_b128 v[60:63], v134
	s_waitcnt lgkmcnt(0)
	v_mfma_f32_16x16x32_f16 v[120:123], v[68:71], v[60:63], v[120:123]
	ds_read_b128 v[88:91], v135 offset:36864
	s_waitcnt lgkmcnt(0)
	s_barrier
	v_mfma_f32_16x16x32_f16 v[138:141], v[80:83], v[60:63], v[138:141]
	ds_read_b128 v[0:3], v133 offset:16384
	v_mfma_f32_16x16x32_f16 v[142:145], v[88:91], v[60:63], v[142:145]
	v_mfma_f32_16x16x32_f16 v[32:35], v[158:161], v[60:63], v[32:35]
	v_mfma_f32_16x16x32_f16 v[60:63], v[68:71], v[76:79], v[64:67]
	v_mfma_f32_16x16x32_f16 v[64:67], v[80:83], v[76:79], v[92:95]
	ds_read_b128 v[4:7], v136 offset:49152
	ds_read_b128 v[8:11], v133 offset:18432
	v_mfma_f32_16x16x32_f16 v[92:95], v[88:91], v[76:79], v[108:111]
	ds_read_b128 v[12:15], v136 offset:51200
	v_mfma_f32_16x16x32_f16 v[40:43], v[158:161], v[76:79], v[40:43]
	v_mfma_f32_16x16x32_f16 v[76:79], v[80:83], v[84:87], v[112:115]
	ds_read_b128 v[16:19], v133 offset:20480
	v_mfma_f32_16x16x32_f16 v[44:47], v[80:83], v[154:157], v[44:47]
	ds_read_b128 v[20:23], v136 offset:53248
	v_mfma_f32_16x16x32_f16 v[108:111], v[88:91], v[84:87], v[116:119]
	ds_read_b128 v[24:27], v133 offset:22528
	v_mfma_f32_16x16x32_f16 v[52:55], v[88:91], v[154:157], v[52:55]
	ds_read_b128 v[28:31], v136 offset:55296
	ds_read_b128 v[112:115], v135 offset:53248
	ds_read_b128 v[116:119], v134 offset:22528
	v_ashrrev_i32_e32 v101, 31, v100
	v_mfma_f32_16x16x32_f16 v[48:51], v[158:161], v[84:87], v[48:51]
	v_mfma_f32_16x16x32_f16 v[56:59], v[158:161], v[154:157], v[56:59]
	v_mfma_f32_16x16x32_f16 v[72:75], v[68:71], v[84:87], v[72:75]
	v_mfma_f32_16x16x32_f16 v[36:39], v[68:71], v[154:157], v[36:39]
	s_waitcnt lgkmcnt(8)
	v_mfma_f32_16x16x32_f16 v[68:71], v[4:7], v[0:3], v[120:123]
	s_nop 2
	ds_read_b128 v[120:123], v135 offset:55296
	s_waitcnt lgkmcnt(7)
	v_mfma_f32_16x16x32_f16 v[80:83], v[12:15], v[0:3], v[138:141]
	s_waitcnt lgkmcnt(5)
	v_mfma_f32_16x16x32_f16 v[84:87], v[20:23], v[0:3], v[142:145]
	s_waitcnt lgkmcnt(3)
	v_mfma_f32_16x16x32_f16 v[0:3], v[28:31], v[0:3], v[32:35]
	v_mfma_f32_16x16x32_f16 v[32:35], v[4:7], v[8:11], v[60:63]
	v_mfma_f32_16x16x32_f16 v[60:63], v[12:15], v[8:11], v[64:67]
	v_mfma_f32_16x16x32_f16 v[72:75], v[4:7], v[16:19], v[72:75]
	v_mfma_f32_16x16x32_f16 v[76:79], v[12:15], v[16:19], v[76:79]
	v_mfma_f32_16x16x32_f16 v[44:47], v[12:15], v[24:27], v[44:47]
	ds_read_b128 v[12:15], v134 offset:16384
	v_mfma_f32_16x16x32_f16 v[64:67], v[20:23], v[8:11], v[92:95]
	s_nop 2
	ds_read_b128 v[92:95], v135 offset:51200
	v_mfma_f32_16x16x32_f16 v[88:91], v[20:23], v[16:19], v[108:111]
	s_nop 2
	ds_read_b128 v[108:111], v134 offset:20480
	v_mfma_f32_16x16x32_f16 v[16:19], v[28:31], v[16:19], v[48:51]
	v_mfma_f32_16x16x32_f16 v[48:51], v[20:23], v[24:27], v[52:55]
	ds_read_b128 v[20:23], v134 offset:18432
	v_mfma_f32_16x16x32_f16 v[52:55], v[28:31], v[24:27], v[56:59]
	s_nop 2
	ds_read_b128 v[56:59], v135 offset:49152
	s_waitcnt lgkmcnt(0)
	s_barrier
; DI unsigned pack2(float lo, float hi) { f2_t v = {lo, hi}; h2_t b = __builtin_convertvector(v, h2_t); return __builtin_bit_cast(unsigned, b); }
; template <int VAR> DI void phase_up(const Params& P, int l, char* smem) {
;     ...
; #pragma unroll
;     for (int mt = 0; mt < 4; ++mt) {
;       const int row = row0 + mt * 16 + lr;
; #pragma unroll
;       for (int nt = 0; nt < 4; ++nt) {
;         float v[4];
; #pragma unroll
;         for (int j = 0; j < 4; ++j) { const float a = fmaxf(acc[mt][nt][j] * rs[mt], 0.f); v[j] = a * a; }
;         *(uint2*)(U + (size_t)row * DFF + col0 + nt * 16 + 4 * g) = make_uint2(pack2(v[0], v[1]), pack2(v[2], v[3]));
;       }
	s_setprio 0
	v_readlane_b32 s60, v255, 0
	v_readlane_b32 s61, v255, 1
	v_readlane_b32 s62, v255, 2
	v_readlane_b32 s63, v255, 3
	v_readlane_b32 s64, v255, 4
	v_readlane_b32 s65, v255, 5
	v_readlane_b32 s66, v255, 6
	v_readlane_b32 s67, v255, 7
	v_readlane_b32 s68, v255, 8
	v_readlane_b32 s69, v255, 9
	v_readlane_b32 s70, v255, 10
	v_readlane_b32 s71, v255, 11
	v_readlane_b32 s72, v255, 12
	v_readlane_b32 s73, v255, 13
	v_readlane_b32 s74, v255, 14
	v_readlane_b32 s75, v255, 15
	s_nop 4
	v_mfma_f32_16x16x32_f16 v[4:7], v[4:7], v[24:27], v[36:39]
	v_mfma_f32_16x16x32_f16 v[68:71], v[56:59], v[12:15], v[68:71]
	v_mfma_f32_16x16x32_f16 v[8:11], v[28:31], v[8:11], v[40:43]
	v_mfma_f32_16x16x32_f16 v[80:83], v[92:95], v[12:15], v[80:83]
	v_mfma_f32_16x16x32_f16 v[84:87], v[112:115], v[12:15], v[84:87]
	v_mfma_f32_16x16x32_f16 v[130:133], v[120:123], v[12:15], v[0:3]
	v_mfma_f32_16x16x32_f16 v[12:15], v[56:59], v[116:119], v[4:7]
	v_mfma_f32_16x16x32_f16 v[4:7], v[112:115], v[116:119], v[48:51]
	v_mfma_f32_16x16x32_f16 v[134:137], v[56:59], v[20:23], v[32:35]
	v_mfma_f32_16x16x32_f16 v[32:35], v[120:123], v[20:23], v[8:11]
	v_mfma_f32_16x16x32_f16 v[8:11], v[92:95], v[116:119], v[44:47]
	v_mfma_f32_16x16x32_f16 v[16:19], v[120:123], v[108:111], v[16:19]
	v_mfma_f32_16x16x32_f16 v[40:43], v[92:95], v[20:23], v[60:63]
	v_mfma_f32_16x16x32_f16 v[36:39], v[112:115], v[20:23], v[64:67]
	v_mfma_f32_16x16x32_f16 v[28:31], v[56:59], v[108:111], v[72:75]
	v_mfma_f32_16x16x32_f16 v[24:27], v[92:95], v[108:111], v[76:79]
	v_mfma_f32_16x16x32_f16 v[20:23], v[112:115], v[108:111], v[88:91]
	v_mfma_f32_16x16x32_f16 v[0:3], v[120:123], v[116:119], v[52:55]
	v_lshl_add_u64 v[92:93], v[100:101], 1, v[96:97]
	v_and_b32_e32 v76, 16, v148
	v_lshrrev_b32_e32 v77, 1, v76
	v_add_u32_e32 v76, v76, v77
	v_and_b32_e32 v77, 8, v148
	v_lshl_add_u32 v76, v77, 3, v76
	v_lshlrev_b32_e32 v77, 13, v77
	v_sub_u32_e32 v76, v76, v77
	v_ashrrev_i32_e32 v77, 31, v76
	v_lshl_add_u64 v[92:93], v[76:77], 0, v[92:93]
	v_mov_b32_e32 v94, 0x10000
	v_mov_b32_e32 v95, 0
	v_lshlrev_b64 v[154:155], 13, v[98:99]
	v_lshl_add_u64 v[154:155], v[92:93], 0, v[154:155]
	v_lshl_add_u64 v[156:157], v[94:95], 0, v[154:155]
	v_mul_f32_e32 v134, v126, v134
	v_mul_f32_e32 v135, v126, v135
	v_mul_f32_e32 v136, v126, v136
	v_mul_f32_e32 v137, v126, v137
	v_mul_f32_e32 v40, v126, v40
	v_mul_f32_e32 v41, v126, v41
	v_mul_f32_e32 v42, v126, v42
	v_mul_f32_e32 v43, v126, v43
	v_max_f32_e32 v134, 0, v134
	v_max_f32_e32 v135, 0, v135
	v_max_f32_e32 v136, 0, v136
	v_max_f32_e32 v137, 0, v137
	v_max_f32_e32 v40, 0, v40
	v_max_f32_e32 v41, 0, v41
	v_max_f32_e32 v42, 0, v42
	v_max_f32_e32 v43, 0, v43
	v_mul_f32_e32 v134, v134, v134
	v_mul_f32_e32 v135, v135, v135
	v_mul_f32_e32 v136, v136, v136
	v_mul_f32_e32 v137, v137, v137
	v_mul_f32_e32 v40, v40, v40
	v_mul_f32_e32 v41, v41, v41
	v_mul_f32_e32 v42, v42, v42
	v_mul_f32_e32 v43, v43, v43
	v_cvt_pk_f16_f32 v44, v134, v135
	v_cvt_pk_f16_f32 v45, v136, v137
	v_cvt_pk_f16_f32 v46, v40, v41
	v_cvt_pk_f16_f32 v47, v42, v43
	s_nop 1
	v_permlane16_swap_b32_e32 v44, v46
	v_permlane16_swap_b32_e32 v45, v47
	v_mul_f32_e32 v36, v126, v36
	v_mul_f32_e32 v37, v126, v37
	v_mul_f32_e32 v38, v126, v38
	v_mul_f32_e32 v39, v126, v39
	v_mul_f32_e32 v32, v126, v32
	v_mul_f32_e32 v33, v126, v33
	v_mul_f32_e32 v34, v126, v34
	v_mul_f32_e32 v35, v126, v35
	v_max_f32_e32 v36, 0, v36
	v_max_f32_e32 v37, 0, v37
	v_max_f32_e32 v38, 0, v38
	v_max_f32_e32 v39, 0, v39
	v_max_f32_e32 v32, 0, v32
	v_max_f32_e32 v33, 0, v33
	v_max_f32_e32 v34, 0, v34
	v_max_f32_e32 v35, 0, v35
	v_mul_f32_e32 v36, v36, v36
	v_mul_f32_e32 v37, v37, v37
	v_mul_f32_e32 v38, v38, v38
	v_mul_f32_e32 v39, v39, v39
	v_mul_f32_e32 v32, v32, v32
	v_mul_f32_e32 v33, v33, v33
	v_mul_f32_e32 v34, v34, v34
	v_mul_f32_e32 v35, v35, v35
	v_cvt_pk_f16_f32 v48, v36, v37
	v_cvt_pk_f16_f32 v49, v38, v39
	v_cvt_pk_f16_f32 v50, v32, v33
	v_cvt_pk_f16_f32 v51, v34, v35
	s_nop 1
	v_permlane16_swap_b32_e32 v48, v50
	v_permlane16_swap_b32_e32 v49, v51
	s_nop 1
	v_mov_b32_dpp v240, v44 row_ror:8 row_mask:0xf bank_mask:0x3
	v_mov_b32_dpp v241, v45 row_ror:8 row_mask:0xf bank_mask:0x3
	v_mov_b32_dpp v242, v46 row_ror:8 row_mask:0xf bank_mask:0x3
	v_mov_b32_dpp v243, v47 row_ror:8 row_mask:0xf bank_mask:0x3
	v_mov_b32_dpp v44, v48 row_ror:8 row_mask:0xf bank_mask:0xc
	v_mov_b32_dpp v45, v49 row_ror:8 row_mask:0xf bank_mask:0xc
	v_mov_b32_dpp v46, v50 row_ror:8 row_mask:0xf bank_mask:0xc
	v_mov_b32_dpp v47, v51 row_ror:8 row_mask:0xf bank_mask:0xc
	v_mov_b32_dpp v48, v240 quad_perm:[0,1,2,3] row_mask:0xf bank_mask:0x3
	v_mov_b32_dpp v49, v241 quad_perm:[0,1,2,3] row_mask:0xf bank_mask:0x3
	v_mov_b32_dpp v50, v242 quad_perm:[0,1,2,3] row_mask:0xf bank_mask:0x3
	v_mov_b32_dpp v51, v243 quad_perm:[0,1,2,3] row_mask:0xf bank_mask:0x3
	v_lshlrev_b64 v[158:159], 13, v[102:103]
	v_lshl_add_u64 v[158:159], v[92:93], 0, v[158:159]
	v_lshl_add_u64 v[160:161], v[94:95], 0, v[158:159]
	v_mul_f32_e32 v68, v128, v68
	v_mul_f32_e32 v69, v128, v69
	v_mul_f32_e32 v70, v128, v70
	v_mul_f32_e32 v71, v128, v71
	v_mul_f32_e32 v80, v128, v80
	v_mul_f32_e32 v81, v128, v81
	v_mul_f32_e32 v82, v128, v82
	v_mul_f32_e32 v83, v128, v83
	v_max_f32_e32 v68, 0, v68
	v_max_f32_e32 v69, 0, v69
	v_max_f32_e32 v70, 0, v70
	v_max_f32_e32 v71, 0, v71
	v_max_f32_e32 v80, 0, v80
	v_max_f32_e32 v81, 0, v81
	v_max_f32_e32 v82, 0, v82
	v_max_f32_e32 v83, 0, v83
	v_mul_f32_e32 v68, v68, v68
	v_mul_f32_e32 v69, v69, v69
	v_mul_f32_e32 v70, v70, v70
	v_mul_f32_e32 v71, v71, v71
	v_mul_f32_e32 v80, v80, v80
	v_mul_f32_e32 v81, v81, v81
	v_mul_f32_e32 v82, v82, v82
	v_mul_f32_e32 v83, v83, v83
; DI unsigned pack2(float lo, float hi) { f2_t v = {lo, hi}; h2_t b = __builtin_convertvector(v, h2_t); return __builtin_bit_cast(unsigned, b); }
; template <int VAR> DI void phase_up(const Params& P, int l, char* smem) {
;     ...
; #pragma unroll
;     for (int mt = 0; mt < 4; ++mt) {
;       const int row = row0 + mt * 16 + lr;
; #pragma unroll
;       for (int nt = 0; nt < 4; ++nt) {
;         float v[4];
; #pragma unroll
;         for (int j = 0; j < 4; ++j) { const float a = fmaxf(acc[mt][nt][j] * rs[mt], 0.f); v[j] = a * a; }
;         *(uint2*)(U + (size_t)row * DFF + col0 + nt * 16 + 4 * g) = make_uint2(pack2(v[0], v[1]), pack2(v[2], v[3]));
;       }
	v_cvt_pk_f16_f32 v52, v68, v69
	v_cvt_pk_f16_f32 v53, v70, v71
	v_cvt_pk_f16_f32 v54, v80, v81
	v_cvt_pk_f16_f32 v55, v82, v83
	s_nop 1
	v_permlane16_swap_b32_e32 v52, v54
	v_permlane16_swap_b32_e32 v53, v55
	v_mul_f32_e32 v84, v128, v84
	v_mul_f32_e32 v85, v128, v85
	v_mul_f32_e32 v86, v128, v86
	v_mul_f32_e32 v87, v128, v87
	v_mul_f32_e32 v130, v128, v130
	v_mul_f32_e32 v131, v128, v131
	v_mul_f32_e32 v132, v128, v132
	v_mul_f32_e32 v133, v128, v133
	v_max_f32_e32 v84, 0, v84
	v_max_f32_e32 v85, 0, v85
	v_max_f32_e32 v86, 0, v86
	v_max_f32_e32 v87, 0, v87
	v_max_f32_e32 v130, 0, v130
	v_max_f32_e32 v131, 0, v131
	v_max_f32_e32 v132, 0, v132
	v_max_f32_e32 v133, 0, v133
	v_mul_f32_e32 v84, v84, v84
	v_mul_f32_e32 v85, v85, v85
	v_mul_f32_e32 v86, v86, v86
	v_mul_f32_e32 v87, v87, v87
	v_mul_f32_e32 v130, v130, v130
	v_mul_f32_e32 v131, v131, v131
	v_mul_f32_e32 v132, v132, v132
	v_mul_f32_e32 v133, v133, v133
	v_cvt_pk_f16_f32 v56, v84, v85
	v_cvt_pk_f16_f32 v57, v86, v87
	v_cvt_pk_f16_f32 v58, v130, v131
	v_cvt_pk_f16_f32 v59, v132, v133
	s_nop 1
	v_permlane16_swap_b32_e32 v56, v58
	v_permlane16_swap_b32_e32 v57, v59
	s_nop 1
	v_mov_b32_dpp v240, v52 row_ror:8 row_mask:0xf bank_mask:0x3
	v_mov_b32_dpp v241, v53 row_ror:8 row_mask:0xf bank_mask:0x3
	v_mov_b32_dpp v242, v54 row_ror:8 row_mask:0xf bank_mask:0x3
	v_mov_b32_dpp v243, v55 row_ror:8 row_mask:0xf bank_mask:0x3
	v_mov_b32_dpp v52, v56 row_ror:8 row_mask:0xf bank_mask:0xc
	v_mov_b32_dpp v53, v57 row_ror:8 row_mask:0xf bank_mask:0xc
	v_mov_b32_dpp v54, v58 row_ror:8 row_mask:0xf bank_mask:0xc
	v_mov_b32_dpp v55, v59 row_ror:8 row_mask:0xf bank_mask:0xc
	v_mov_b32_dpp v56, v240 quad_perm:[0,1,2,3] row_mask:0xf bank_mask:0x3
	v_mov_b32_dpp v57, v241 quad_perm:[0,1,2,3] row_mask:0xf bank_mask:0x3
	v_mov_b32_dpp v58, v242 quad_perm:[0,1,2,3] row_mask:0xf bank_mask:0x3
	v_mov_b32_dpp v59, v243 quad_perm:[0,1,2,3] row_mask:0xf bank_mask:0x3
	v_lshlrev_b64 v[162:163], 13, v[106:107]
	v_lshl_add_u64 v[162:163], v[92:93], 0, v[162:163]
	v_lshl_add_u64 v[164:165], v[94:95], 0, v[162:163]
	v_mul_f32_e32 v28, v129, v28
	v_mul_f32_e32 v29, v129, v29
	v_mul_f32_e32 v30, v129, v30
	v_mul_f32_e32 v31, v129, v31
	v_mul_f32_e32 v24, v129, v24
	v_mul_f32_e32 v25, v129, v25
	v_mul_f32_e32 v26, v129, v26
	v_mul_f32_e32 v27, v129, v27
	v_max_f32_e32 v28, 0, v28
	v_max_f32_e32 v29, 0, v29
	v_max_f32_e32 v30, 0, v30
	v_max_f32_e32 v31, 0, v31
	v_max_f32_e32 v24, 0, v24
	v_max_f32_e32 v25, 0, v25
	v_max_f32_e32 v26, 0, v26
	v_max_f32_e32 v27, 0, v27
	v_mul_f32_e32 v28, v28, v28
	v_mul_f32_e32 v29, v29, v29
	v_mul_f32_e32 v30, v30, v30
	v_mul_f32_e32 v31, v31, v31
	v_mul_f32_e32 v24, v24, v24
	v_mul_f32_e32 v25, v25, v25
	v_mul_f32_e32 v26, v26, v26
	v_mul_f32_e32 v27, v27, v27
	v_cvt_pk_f16_f32 v60, v28, v29
	v_cvt_pk_f16_f32 v61, v30, v31
	v_cvt_pk_f16_f32 v62, v24, v25
	v_cvt_pk_f16_f32 v63, v26, v27
	s_nop 1
	v_permlane16_swap_b32_e32 v60, v62
	v_permlane16_swap_b32_e32 v61, v63
	v_mul_f32_e32 v20, v129, v20
	v_mul_f32_e32 v21, v129, v21
	v_mul_f32_e32 v22, v129, v22
	v_mul_f32_e32 v23, v129, v23
	v_mul_f32_e32 v16, v129, v16
	v_mul_f32_e32 v17, v129, v17
	v_mul_f32_e32 v18, v129, v18
	v_mul_f32_e32 v19, v129, v19
	v_max_f32_e32 v20, 0, v20
	v_max_f32_e32 v21, 0, v21
	v_max_f32_e32 v22, 0, v22
	v_max_f32_e32 v23, 0, v23
	v_max_f32_e32 v16, 0, v16
	v_max_f32_e32 v17, 0, v17
	v_max_f32_e32 v18, 0, v18
	v_max_f32_e32 v19, 0, v19
	v_mul_f32_e32 v20, v20, v20
	v_mul_f32_e32 v21, v21, v21
	v_mul_f32_e32 v22, v22, v22
	v_mul_f32_e32 v23, v23, v23
	v_mul_f32_e32 v16, v16, v16
	v_mul_f32_e32 v17, v17, v17
	v_mul_f32_e32 v18, v18, v18
	v_mul_f32_e32 v19, v19, v19
; DI unsigned pack2(float lo, float hi) { f2_t v = {lo, hi}; h2_t b = __builtin_convertvector(v, h2_t); return __builtin_bit_cast(unsigned, b); }
; template <int VAR> DI void phase_up(const Params& P, int l, char* smem) {
;     ...
; #pragma unroll
;     for (int mt = 0; mt < 4; ++mt) {
;       const int row = row0 + mt * 16 + lr;
; #pragma unroll
;       for (int nt = 0; nt < 4; ++nt) {
;         float v[4];
; #pragma unroll
;         for (int j = 0; j < 4; ++j) { const float a = fmaxf(acc[mt][nt][j] * rs[mt], 0.f); v[j] = a * a; }
;         *(uint2*)(U + (size_t)row * DFF + col0 + nt * 16 + 4 * g) = make_uint2(pack2(v[0], v[1]), pack2(v[2], v[3]));
;       }
	v_cvt_pk_f16_f32 v32, v20, v21
	v_cvt_pk_f16_f32 v33, v22, v23
	v_cvt_pk_f16_f32 v34, v16, v17
	v_cvt_pk_f16_f32 v35, v18, v19
	s_nop 1
	v_permlane16_swap_b32_e32 v32, v34
	v_permlane16_swap_b32_e32 v33, v35
	s_nop 1
	v_mov_b32_dpp v240, v60 row_ror:8 row_mask:0xf bank_mask:0x3
	v_mov_b32_dpp v241, v61 row_ror:8 row_mask:0xf bank_mask:0x3
	v_mov_b32_dpp v242, v62 row_ror:8 row_mask:0xf bank_mask:0x3
	v_mov_b32_dpp v243, v63 row_ror:8 row_mask:0xf bank_mask:0x3
	v_mov_b32_dpp v60, v32 row_ror:8 row_mask:0xf bank_mask:0xc
	v_mov_b32_dpp v61, v33 row_ror:8 row_mask:0xf bank_mask:0xc
	v_mov_b32_dpp v62, v34 row_ror:8 row_mask:0xf bank_mask:0xc
	v_mov_b32_dpp v63, v35 row_ror:8 row_mask:0xf bank_mask:0xc
	v_mov_b32_dpp v32, v240 quad_perm:[0,1,2,3] row_mask:0xf bank_mask:0x3
	v_mov_b32_dpp v33, v241 quad_perm:[0,1,2,3] row_mask:0xf bank_mask:0x3
	v_mov_b32_dpp v34, v242 quad_perm:[0,1,2,3] row_mask:0xf bank_mask:0x3
	v_mov_b32_dpp v35, v243 quad_perm:[0,1,2,3] row_mask:0xf bank_mask:0x3
	v_lshlrev_b64 v[166:167], 13, v[104:105]
	v_lshl_add_u64 v[166:167], v[92:93], 0, v[166:167]
	v_lshl_add_u64 v[168:169], v[94:95], 0, v[166:167]
	v_mul_f32_e32 v12, v127, v12
	v_mul_f32_e32 v13, v127, v13
	v_mul_f32_e32 v14, v127, v14
	v_mul_f32_e32 v15, v127, v15
	v_mul_f32_e32 v8, v127, v8
	v_mul_f32_e32 v9, v127, v9
	v_mul_f32_e32 v10, v127, v10
	v_mul_f32_e32 v11, v127, v11
	v_max_f32_e32 v12, 0, v12
	v_max_f32_e32 v13, 0, v13
	v_max_f32_e32 v14, 0, v14
	v_max_f32_e32 v15, 0, v15
	v_max_f32_e32 v8, 0, v8
	v_max_f32_e32 v9, 0, v9
	v_max_f32_e32 v10, 0, v10
	v_max_f32_e32 v11, 0, v11
	v_mul_f32_e32 v12, v12, v12
	v_mul_f32_e32 v13, v13, v13
	v_mul_f32_e32 v14, v14, v14
	v_mul_f32_e32 v15, v15, v15
	v_mul_f32_e32 v8, v8, v8
	v_mul_f32_e32 v9, v9, v9
	v_mul_f32_e32 v10, v10, v10
	v_mul_f32_e32 v11, v11, v11
	v_cvt_pk_f16_f32 v36, v12, v13
	v_cvt_pk_f16_f32 v37, v14, v15
	v_cvt_pk_f16_f32 v38, v8, v9
	v_cvt_pk_f16_f32 v39, v10, v11
	s_nop 1
	v_permlane16_swap_b32_e32 v36, v38
	v_permlane16_swap_b32_e32 v37, v39
	v_mul_f32_e32 v4, v127, v4
	v_mul_f32_e32 v5, v127, v5
	v_mul_f32_e32 v6, v127, v6
	v_mul_f32_e32 v7, v127, v7
	v_mul_f32_e32 v0, v127, v0
	v_mul_f32_e32 v1, v127, v1
	v_mul_f32_e32 v2, v127, v2
	v_mul_f32_e32 v3, v127, v3
	v_max_f32_e32 v4, 0, v4
	v_max_f32_e32 v5, 0, v5
	v_max_f32_e32 v6, 0, v6
	v_max_f32_e32 v7, 0, v7
	v_max_f32_e32 v0, 0, v0
	v_max_f32_e32 v1, 0, v1
	v_max_f32_e32 v2, 0, v2
	v_max_f32_e32 v3, 0, v3
	v_mul_f32_e32 v4, v4, v4
	v_mul_f32_e32 v5, v5, v5
	v_mul_f32_e32 v6, v6, v6
	v_mul_f32_e32 v7, v7, v7
	v_mul_f32_e32 v0, v0, v0
	v_mul_f32_e32 v1, v1, v1
	v_mul_f32_e32 v2, v2, v2
	v_mul_f32_e32 v3, v3, v3
	v_cvt_pk_f16_f32 v40, v4, v5
	v_cvt_pk_f16_f32 v41, v6, v7
	v_cvt_pk_f16_f32 v42, v0, v1
	v_cvt_pk_f16_f32 v43, v2, v3
	s_nop 1
	v_permlane16_swap_b32_e32 v40, v42
	v_permlane16_swap_b32_e32 v41, v43
	s_nop 1
	v_mov_b32_dpp v240, v36 row_ror:8 row_mask:0xf bank_mask:0x3
	v_mov_b32_dpp v241, v37 row_ror:8 row_mask:0xf bank_mask:0x3
	v_mov_b32_dpp v242, v38 row_ror:8 row_mask:0xf bank_mask:0x3
	v_mov_b32_dpp v243, v39 row_ror:8 row_mask:0xf bank_mask:0x3
	v_mov_b32_dpp v36, v40 row_ror:8 row_mask:0xf bank_mask:0xc
	v_mov_b32_dpp v37, v41 row_ror:8 row_mask:0xf bank_mask:0xc
	v_mov_b32_dpp v38, v42 row_ror:8 row_mask:0xf bank_mask:0xc
	v_mov_b32_dpp v39, v43 row_ror:8 row_mask:0xf bank_mask:0xc
	v_mov_b32_dpp v40, v240 quad_perm:[0,1,2,3] row_mask:0xf bank_mask:0x3
	v_mov_b32_dpp v41, v241 quad_perm:[0,1,2,3] row_mask:0xf bank_mask:0x3
	v_mov_b32_dpp v42, v242 quad_perm:[0,1,2,3] row_mask:0xf bank_mask:0x3
	v_mov_b32_dpp v43, v243 quad_perm:[0,1,2,3] row_mask:0xf bank_mask:0x3
	s_mov_b32 s100, 1
	s_branch .LBB0_1312

; #define GL_LOAD(s_, kt_) if (VAR != 1) { a##s_##0 = GL_A(0, kt_); a##s_##1 = GL_A(1, kt_); a##s_##2 = GL_A(2, kt_); a##s_##3 = GL_A(3, kt_); b##s_##0 = GL_B(0, kt_); b##s_##1 = GL_B(1, kt_); b##s_##2 = GL_B(2, kt_); b##s_##3 = GL_B(3, kt_); }
; #define LDS_STORE(s_, buf_) if (VAR != 2) { LDS_ST1(sA, 0, buf_, a##s_##0) LDS_ST1(sA, 1, buf_, a##s_##1) LDS_ST1(sA, 2, buf_, a##s_##2) LDS_ST1(sA, 3, buf_, a##s_##3) LDS_ST1(sB, 0, buf_, b##s_##0) LDS_ST1(sB, 1, buf_, b##s_##1) LDS_ST1(sB, 2, buf_, b##s_##2) LDS_ST1(sB, 3, buf_, b##s_##3) }
;     ...
;   GL_LOAD(0, 0)
;   GL_LOAD(1, 1)
;   LDS_STORE(0, 0)
;   if (VAR != 4) __syncthreads();
; #pragma unroll
;   for (int kt = 0; kt < nk; kt += 2) {
;     if (kt + 2 < nk) { GL_LOAD(0, kt + 2) }
;     MMA_TILE(0)
;     LDS_STORE(1, 1)
;     if (VAR != 4) __syncthreads();
;     if (kt + 3 < nk) { GL_LOAD(1, kt + 3) }
;     MMA_TILE(1)
.LBB0_1371:
	s_ashr_i32 s1, s2, 3
	s_andn2_b32 s1, s1, 63
	s_and_b32 s4, s9, 56
	s_or_b32 s1, s1, s4
	s_bfe_u32 s4, s2, 0x30003
	s_or_b32 s1, s1, s4
	s_cmpk_gt_i32 s1, 0x7f
	s_cbranch_scc1 .LBB0_1370
	s_lshl_b32 s4, s1, 7
	s_ashr_i32 s5, s4, 31
	v_mov_b32_e32 v58, v148
	s_and_b32 s10, s8, 0x380
	s_lshl_b64 s[12:13], s[4:5], 13
	s_add_u32 s12, s34, s12
	v_ashrrev_i32_e32 v16, 3, v58
	v_ashrrev_i32_e32 v17, 31, v16
	v_add_u32_e32 v18, 32, v16
	s_addc_u32 s13, s35, s13
	v_lshlrev_b64 v[6:7], 13, v[16:17]
	v_lshlrev_b32_e32 v17, 4, v58
	v_ashrrev_i32_e32 v19, 31, v18
	v_add_u32_e32 v20, 64, v16
	s_waitcnt lgkmcnt(0)
	v_lshl_add_u64 v[0:1], s[12:13], 0, v[6:7]
	v_and_b32_e32 v150, 0x70, v17
	v_lshlrev_b64 v[8:9], 13, v[18:19]
	v_ashrrev_i32_e32 v21, 31, v20
	v_add_u32_e32 v54, 0x60, v16
	s_lshl_b32 s1, s10, 13
	v_lshl_add_u64 v[0:1], v[0:1], 0, v[150:151]
	v_lshl_add_u64 v[2:3], s[12:13], 0, v[8:9]
	v_lshlrev_b64 v[46:47], 13, v[20:21]
	v_ashrrev_i32_e32 v55, 31, v54
	s_add_u32 s14, s6, s1
	global_load_dwordx4 v[22:25], v[0:1], off
	v_lshl_add_u64 v[2:3], v[2:3], 0, v[150:151]
	v_lshl_add_u64 v[4:5], s[12:13], 0, v[46:47]
	v_lshlrev_b64 v[50:51], 13, v[54:55]
	s_addc_u32 s15, s7, 0
	global_load_dwordx4 v[26:29], v[2:3], off
	v_lshl_add_u64 v[4:5], v[4:5], 0, v[150:151]
	v_lshl_add_u64 v[10:11], s[12:13], 0, v[50:51]
	global_load_dwordx4 v[30:33], v[4:5], off
	v_lshl_add_u64 v[14:15], v[10:11], 0, v[150:151]
	v_lshl_add_u64 v[6:7], s[14:15], 0, v[6:7]
	global_load_dwordx4 v[34:37], v[14:15], off
	v_lshl_add_u64 v[10:11], v[6:7], 0, v[150:151]
	v_lshl_add_u64 v[6:7], s[14:15], 0, v[8:9]
	global_load_dwordx4 v[38:41], v[10:11], off
	v_lshl_add_u64 v[12:13], v[6:7], 0, v[150:151]
	v_lshl_add_u64 v[6:7], s[14:15], 0, v[46:47]
	global_load_dwordx4 v[42:45], v[12:13], off
	v_lshl_add_u64 v[8:9], v[6:7], 0, v[150:151]
	v_lshl_add_u64 v[6:7], s[14:15], 0, v[50:51]
	global_load_dwordx4 v[46:49], v[8:9], off
	v_lshl_add_u64 v[6:7], v[6:7], 0, v[150:151]
	global_load_dwordx4 v[50:53], v[6:7], off
	v_and_b32_e32 v19, 15, v58
	v_lshlrev_b32_e32 v21, 3, v58
	v_and_b32_e32 v55, 48, v58
	v_lshrrev_b32_e32 v59, 1, v58
	s_waitcnt vmcnt(10)
	v_lshlrev_b32_e32 v60, 7, v58
	v_and_b32_e32 v90, 0x70, v21
	v_bitop3_b32 v134, v21, v55, s23 bitop3:0x6c
	v_bitop3_b32 v21, v17, s23, v58 bitop3:0x48
	v_and_or_b32 v91, v59, s24, v19
	v_and_b32_e32 v130, 0x2780, v60
	global_load_dwordx4 v[58:61], v[0:1], off offset:128
	global_load_dwordx4 v[62:65], v[2:3], off offset:128
	global_load_dwordx4 v[66:69], v[4:5], off offset:128
	global_load_dwordx4 v[70:73], v[14:15], off offset:128
	global_load_dwordx4 v[74:77], v[10:11], off offset:128
	global_load_dwordx4 v[78:81], v[12:13], off offset:128
	global_load_dwordx4 v[82:85], v[8:9], off offset:128
	global_load_dwordx4 v[86:89], v[6:7], off offset:128
	v_lshl_or_b32 v17, v16, 7, v21
	v_or_b32_e32 v16, v130, v134
	v_lshl_or_b32 v18, v18, 7, v21
	v_lshl_or_b32 v19, v20, 7, v21
	v_lshl_or_b32 v20, v54, 7, v21
	v_lshlrev_b32_e32 v54, 7, v91
	v_bitop3_b32 v21, v54, v90, v55 bitop3:0xf6
	s_movk_i32 s1, 0x1000
	v_readlane_b32 s12, v254, 55
	v_readlane_b32 s13, v254, 56
	v_readlane_b32 s14, v254, 57
	v_readlane_b32 s15, v254, 58
	s_waitcnt vmcnt(15)
	ds_write_b128 v17, v[22:25]
	s_waitcnt vmcnt(14)
	ds_write_b128 v18, v[26:29]
	s_waitcnt vmcnt(13)
	ds_write_b128 v19, v[30:33]
	s_waitcnt vmcnt(12)
	ds_write_b128 v20, v[34:37]
	s_waitcnt vmcnt(11)
	ds_write_b128 v17, v[38:41] offset:32768
	s_waitcnt vmcnt(10)
	ds_write_b128 v18, v[42:45] offset:32768
	s_waitcnt vmcnt(9)
	ds_write_b128 v19, v[46:49] offset:32768
	s_waitcnt vmcnt(8)
	ds_write_b128 v20, v[50:53] offset:32768
	s_waitcnt lgkmcnt(0)
	s_barrier
	s_setprio 2
	ds_read_b128 v[22:25], v16 offset:32768
	ds_read_b128 v[30:33], v21
	s_waitcnt lgkmcnt(0)
	v_mfma_f32_16x16x32_f16 v[38:41], v[22:25], v[30:33], 0
	ds_read_b128 v[26:29], v16 offset:34816
	ds_read_b128 v[34:37], v21 offset:2048
	s_waitcnt lgkmcnt(0)
	v_mfma_f32_16x16x32_f16 v[94:97], v[22:25], v[34:37], 0
	ds_read_b128 v[42:45], v16 offset:36864
	ds_read_b128 v[106:109], v21 offset:4096
	s_waitcnt lgkmcnt(0)
	v_mfma_f32_16x16x32_f16 v[114:117], v[22:25], v[106:109], 0
	ds_read_b128 v[50:53], v16 offset:38912
	ds_read_b128 v[110:113], v21 offset:6144
	s_waitcnt lgkmcnt(0)
	v_mfma_f32_16x16x32_f16 v[126:129], v[22:25], v[110:113], 0
	v_xor_b32_e32 v22, 64, v134
	v_mfma_f32_16x16x32_f16 v[46:49], v[26:29], v[30:33], 0
	v_or_b32_e32 v22, v130, v22
	v_mfma_f32_16x16x32_f16 v[90:93], v[42:45], v[30:33], 0
	ds_read_b128 v[130:133], v22 offset:32768
	v_mfma_f32_16x16x32_f16 v[30:33], v[50:53], v[30:33], 0
	ds_read_b128 v[142:145], v22 offset:36864
	v_mfma_f32_16x16x32_f16 v[98:101], v[26:29], v[34:37], 0
	ds_read_b128 v[154:157], v22 offset:38912
	v_mfma_f32_16x16x32_f16 v[102:105], v[42:45], v[34:37], 0
	v_bitop3_b32 v23, v54, v134, 64 bitop3:0xf6
	v_mfma_f32_16x16x32_f16 v[34:37], v[50:53], v[34:37], 0
	ds_read_b128 v[134:137], v23
	v_mfma_f32_16x16x32_f16 v[118:121], v[26:29], v[106:109], 0
	ds_read_b128 v[138:141], v23 offset:2048
	v_mfma_f32_16x16x32_f16 v[122:125], v[42:45], v[106:109], 0
	s_waitcnt vmcnt(7)
	ds_write_b128 v17, v[58:61] offset:16384
	v_mfma_f32_16x16x32_f16 v[106:109], v[50:53], v[106:109], 0
	s_waitcnt vmcnt(6)
	ds_write_b128 v18, v[62:65] offset:16384
	v_mfma_f32_16x16x32_f16 v[24:27], v[26:29], v[110:113], 0
	s_waitcnt vmcnt(5)
	ds_write_b128 v19, v[66:69] offset:16384
	v_mfma_f32_16x16x32_f16 v[42:45], v[42:45], v[110:113], 0
	s_waitcnt vmcnt(4)
	ds_write_b128 v20, v[70:73] offset:16384
	v_mfma_f32_16x16x32_f16 v[50:53], v[50:53], v[110:113], 0
	ds_read_b128 v[110:113], v22 offset:34816
	s_waitcnt lgkmcnt(6)
; #define GL_LOAD(s_, kt_) if (VAR != 1) { a##s_##0 = GL_A(0, kt_); a##s_##1 = GL_A(1, kt_); a##s_##2 = GL_A(2, kt_); a##s_##3 = GL_A(3, kt_); b##s_##0 = GL_B(0, kt_); b##s_##1 = GL_B(1, kt_); b##s_##2 = GL_B(2, kt_); b##s_##3 = GL_B(3, kt_); }
; #define LDS_STORE(s_, buf_) if (VAR != 2) { LDS_ST1(sA, 0, buf_, a##s_##0) LDS_ST1(sA, 1, buf_, a##s_##1) LDS_ST1(sA, 2, buf_, a##s_##2) LDS_ST1(sA, 3, buf_, a##s_##3) LDS_ST1(sB, 0, buf_, b##s_##0) LDS_ST1(sB, 1, buf_, b##s_##1) LDS_ST1(sB, 2, buf_, b##s_##2) LDS_ST1(sB, 3, buf_, b##s_##3) }
;     ...
;   for (int kt = 0; kt < nk; kt += 2) {
;     if (kt + 2 < nk) { GL_LOAD(0, kt + 2) }
;     MMA_TILE(0)
;     LDS_STORE(1, 1)
;     if (VAR != 4) __syncthreads();
;     if (kt + 3 < nk) { GL_LOAD(1, kt + 3) }
;     MMA_TILE(1)
;     if (kt + 2 < nk) { LDS_STORE(0, 0) }
;     if (VAR != 4) __syncthreads();
	v_mfma_f32_16x16x32_f16 v[38:41], v[130:133], v[134:137], v[38:41]
	s_waitcnt vmcnt(3)
	ds_write_b128 v17, v[74:77] offset:49152
	v_mfma_f32_16x16x32_f16 v[90:93], v[142:145], v[134:137], v[90:93]
	s_waitcnt vmcnt(2)
	ds_write_b128 v18, v[78:81] offset:49152
	v_mfma_f32_16x16x32_f16 v[28:31], v[154:157], v[134:137], v[30:33]
	s_waitcnt vmcnt(1)
	ds_write_b128 v19, v[82:85] offset:49152
	s_waitcnt lgkmcnt(8)
	v_mfma_f32_16x16x32_f16 v[94:97], v[130:133], v[138:141], v[94:97]
	s_waitcnt vmcnt(0)
	ds_write_b128 v20, v[86:89] offset:49152
	v_mfma_f32_16x16x32_f16 v[102:105], v[142:145], v[138:141], v[102:105]
	v_mfma_f32_16x16x32_f16 v[32:35], v[154:157], v[138:141], v[34:37]
	s_waitcnt lgkmcnt(4)
	v_mfma_f32_16x16x32_f16 v[46:49], v[110:113], v[134:137], v[46:49]
	ds_read_b128 v[134:137], v23 offset:4096
	v_mfma_f32_16x16x32_f16 v[98:101], v[110:113], v[138:141], v[98:101]
	ds_read_b128 v[138:141], v23 offset:6144
	s_waitcnt lgkmcnt(1)
	v_mfma_f32_16x16x32_f16 v[114:117], v[130:133], v[134:137], v[114:117]
	s_waitcnt lgkmcnt(0)
	v_mfma_f32_16x16x32_f16 v[126:129], v[130:133], v[138:141], v[126:129]
	global_load_dwordx4 v[130:133], v[0:1], off offset:256
	v_mfma_f32_16x16x32_f16 v[118:121], v[110:113], v[134:137], v[118:121]
	v_mfma_f32_16x16x32_f16 v[24:27], v[110:113], v[138:141], v[24:27]
	v_mfma_f32_16x16x32_f16 v[122:125], v[142:145], v[134:137], v[122:125]
	v_mfma_f32_16x16x32_f16 v[106:109], v[154:157], v[134:137], v[106:109]
	global_load_dwordx4 v[134:137], v[2:3], off offset:256
	global_load_dwordx4 v[158:161], v[4:5], off offset:256
	global_load_dwordx4 v[162:165], v[14:15], off offset:256
	global_load_dwordx4 v[110:113], v[10:11], off offset:256
	global_load_dwordx4 v[166:169], v[12:13], off offset:256
	global_load_dwordx4 v[190:193], v[8:9], off offset:256
	global_load_dwordx4 v[194:197], v[6:7], off offset:256
	s_waitcnt lgkmcnt(0)
	s_barrier
	v_mfma_f32_16x16x32_f16 v[42:45], v[142:145], v[138:141], v[42:45]
	ds_read_b128 v[58:61], v16 offset:49152
	v_mfma_f32_16x16x32_f16 v[50:53], v[154:157], v[138:141], v[50:53]
	ds_read_b128 v[62:65], v16 offset:51200
	ds_read_b128 v[66:69], v21 offset:16384
	s_waitcnt lgkmcnt(0)
	v_mfma_f32_16x16x32_f16 v[36:39], v[58:61], v[66:69], v[38:41]
	ds_read_b128 v[70:73], v21 offset:18432
	v_mfma_f32_16x16x32_f16 v[46:49], v[62:65], v[66:69], v[46:49]
	ds_read_b128 v[74:77], v16 offset:53248
	s_waitcnt lgkmcnt(0)
	v_mfma_f32_16x16x32_f16 v[82:85], v[74:77], v[66:69], v[90:93]
	ds_read_b128 v[78:81], v16 offset:55296
	s_waitcnt lgkmcnt(0)
	v_mfma_f32_16x16x32_f16 v[28:31], v[78:81], v[66:69], v[28:31]
	v_mfma_f32_16x16x32_f16 v[66:69], v[58:61], v[70:73], v[94:97]
	s_nop 2
	ds_read_b128 v[94:97], v21 offset:22528
	s_waitcnt vmcnt(7)
	ds_write_b128 v17, v[130:133]
	v_mfma_f32_16x16x32_f16 v[86:89], v[62:65], v[70:73], v[98:101]
	s_waitcnt vmcnt(6)
	ds_write_b128 v18, v[134:137]
	s_waitcnt vmcnt(5)
	ds_write_b128 v19, v[158:161]
	v_mfma_f32_16x16x32_f16 v[90:93], v[74:77], v[70:73], v[102:105]
	s_waitcnt vmcnt(4)
	ds_write_b128 v20, v[162:165]
	s_waitcnt vmcnt(3)
	ds_write_b128 v17, v[110:113] offset:32768
	v_mfma_f32_16x16x32_f16 v[32:35], v[78:81], v[70:73], v[32:35]
	ds_read_b128 v[70:73], v21 offset:20480
	s_waitcnt lgkmcnt(0)
	v_mfma_f32_16x16x32_f16 v[98:101], v[58:61], v[70:73], v[114:117]
	s_waitcnt vmcnt(2)
	ds_write_b128 v18, v[166:169] offset:32768
	v_mfma_f32_16x16x32_f16 v[58:61], v[58:61], v[94:97], v[126:129]
	s_waitcnt vmcnt(1)
	ds_write_b128 v19, v[190:193] offset:32768
	v_mfma_f32_16x16x32_f16 v[102:105], v[62:65], v[70:73], v[118:121]
	s_nop 2
	ds_read_b128 v[118:121], v22 offset:55296
	v_mfma_f32_16x16x32_f16 v[24:27], v[62:65], v[94:97], v[24:27]
	ds_read_b128 v[62:65], v22 offset:49152
	v_mfma_f32_16x16x32_f16 v[114:117], v[74:77], v[70:73], v[122:125]
	s_waitcnt vmcnt(0)
	ds_write_b128 v20, v[194:197] offset:32768
	v_mfma_f32_16x16x32_f16 v[40:43], v[74:77], v[94:97], v[42:45]
	ds_read_b128 v[74:77], v22 offset:51200
	v_mfma_f32_16x16x32_f16 v[70:73], v[78:81], v[70:73], v[106:109]
	s_nop 2
	ds_read_b128 v[106:109], v22 offset:53248
	v_mfma_f32_16x16x32_f16 v[50:53], v[78:81], v[94:97], v[50:53]
	ds_read_b128 v[78:81], v23 offset:16384
	s_waitcnt lgkmcnt(0)
	v_mfma_f32_16x16x32_f16 v[36:39], v[62:65], v[78:81], v[36:39]
	ds_read_b128 v[94:97], v23 offset:18432
	s_waitcnt lgkmcnt(0)
	v_mfma_f32_16x16x32_f16 v[66:69], v[62:65], v[94:97], v[66:69]
	v_mfma_f32_16x16x32_f16 v[44:47], v[74:77], v[78:81], v[46:49]
	v_mfma_f32_16x16x32_f16 v[82:85], v[106:109], v[78:81], v[82:85]
	v_mfma_f32_16x16x32_f16 v[28:31], v[118:121], v[78:81], v[28:31]
	v_mfma_f32_16x16x32_f16 v[78:81], v[74:77], v[94:97], v[86:89]
	v_mfma_f32_16x16x32_f16 v[86:89], v[106:109], v[94:97], v[90:93]
	s_nop 2
	ds_read_b128 v[90:93], v23 offset:20480
	v_mfma_f32_16x16x32_f16 v[32:35], v[118:121], v[94:97], v[32:35]
	ds_read_b128 v[94:97], v23 offset:22528
	s_waitcnt lgkmcnt(1)
	v_mfma_f32_16x16x32_f16 v[98:101], v[62:65], v[90:93], v[98:101]
	s_waitcnt lgkmcnt(0)
	v_mfma_f32_16x16x32_f16 v[58:61], v[62:65], v[94:97], v[58:61]
	global_load_dwordx4 v[62:65], v[0:1], off offset:384
	v_mfma_f32_16x16x32_f16 v[102:105], v[74:77], v[90:93], v[102:105]
	v_mfma_f32_16x16x32_f16 v[24:27], v[74:77], v[94:97], v[24:27]
	v_mfma_f32_16x16x32_f16 v[114:117], v[106:109], v[90:93], v[114:117]
	v_mfma_f32_16x16x32_f16 v[40:43], v[106:109], v[94:97], v[40:43]
	v_mfma_f32_16x16x32_f16 v[70:73], v[118:121], v[90:93], v[70:73]
	global_load_dwordx4 v[90:93], v[2:3], off offset:384
	global_load_dwordx4 v[122:125], v[4:5], off offset:384
	global_load_dwordx4 v[126:129], v[14:15], off offset:384
	global_load_dwordx4 v[74:77], v[10:11], off offset:384
	global_load_dwordx4 v[138:141], v[12:13], off offset:384
	global_load_dwordx4 v[142:145], v[8:9], off offset:384
	global_load_dwordx4 v[154:157], v[6:7], off offset:384
	s_waitcnt lgkmcnt(0)
	s_barrier
; #define GL_LOAD(s_, kt_) if (VAR != 1) { a##s_##0 = GL_A(0, kt_); a##s_##1 = GL_A(1, kt_); a##s_##2 = GL_A(2, kt_); a##s_##3 = GL_A(3, kt_); b##s_##0 = GL_B(0, kt_); b##s_##1 = GL_B(1, kt_); b##s_##2 = GL_B(2, kt_); b##s_##3 = GL_B(3, kt_); }
; #define LDS_STORE(s_, buf_) if (VAR != 2) { LDS_ST1(sA, 0, buf_, a##s_##0) LDS_ST1(sA, 1, buf_, a##s_##1) LDS_ST1(sA, 2, buf_, a##s_##2) LDS_ST1(sA, 3, buf_, a##s_##3) LDS_ST1(sB, 0, buf_, b##s_##0) LDS_ST1(sB, 1, buf_, b##s_##1) LDS_ST1(sB, 2, buf_, b##s_##2) LDS_ST1(sB, 3, buf_, b##s_##3) }
;     ...
;   GL_LOAD(0, 0)
;   GL_LOAD(1, 1)
;   LDS_STORE(0, 0)
;   if (VAR != 4) __syncthreads();
; #pragma unroll
;   for (int kt = 0; kt < nk; kt += 2) {
;     if (kt + 2 < nk) { GL_LOAD(0, kt + 2) }
;     MMA_TILE(0)
;     LDS_STORE(1, 1)
;     if (VAR != 4) __syncthreads();
;     if (kt + 3 < nk) { GL_LOAD(1, kt + 3) }
;     MMA_TILE(1)
;     if (kt + 2 < nk) { LDS_STORE(0, 0) }
;     if (VAR != 4) __syncthreads();
	v_mfma_f32_16x16x32_f16 v[48:51], v[118:121], v[94:97], v[50:53]
	ds_read_b128 v[106:109], v16 offset:32768
	ds_read_b128 v[94:97], v21
	s_waitcnt lgkmcnt(0)
	v_mfma_f32_16x16x32_f16 v[36:39], v[106:109], v[94:97], v[36:39]
	ds_read_b128 v[52:55], v16 offset:34816
	ds_read_b128 v[110:113], v21 offset:2048
	s_waitcnt lgkmcnt(0)
	v_mfma_f32_16x16x32_f16 v[66:69], v[106:109], v[110:113], v[66:69]
	ds_read_b128 v[118:121], v16 offset:36864
	v_mfma_f32_16x16x32_f16 v[44:47], v[52:55], v[94:97], v[44:47]
	ds_read_b128 v[130:133], v16 offset:38912
	v_mfma_f32_16x16x32_f16 v[78:81], v[52:55], v[110:113], v[78:81]
	s_waitcnt vmcnt(7)
	ds_write_b128 v17, v[62:65] offset:16384
	s_waitcnt lgkmcnt(2)
	v_mfma_f32_16x16x32_f16 v[82:85], v[118:121], v[94:97], v[82:85]
	s_waitcnt vmcnt(6)
	ds_write_b128 v18, v[90:93] offset:16384
	v_mfma_f32_16x16x32_f16 v[86:89], v[118:121], v[110:113], v[86:89]
	s_waitcnt vmcnt(5)
	ds_write_b128 v19, v[122:125] offset:16384
	s_waitcnt lgkmcnt(3)
	v_mfma_f32_16x16x32_f16 v[28:31], v[130:133], v[94:97], v[28:31]
	ds_read_b128 v[94:97], v21 offset:4096
	v_mfma_f32_16x16x32_f16 v[32:35], v[130:133], v[110:113], v[32:35]
	ds_read_b128 v[110:113], v21 offset:6144
	s_waitcnt lgkmcnt(1)
	v_mfma_f32_16x16x32_f16 v[98:101], v[106:109], v[94:97], v[98:101]
	s_waitcnt vmcnt(4)
	ds_write_b128 v20, v[126:129] offset:16384
	s_waitcnt lgkmcnt(1)
	v_mfma_f32_16x16x32_f16 v[58:61], v[106:109], v[110:113], v[58:61]
	ds_read_b128 v[106:109], v23
	v_mfma_f32_16x16x32_f16 v[102:105], v[52:55], v[94:97], v[102:105]
	s_waitcnt vmcnt(3)
	ds_write_b128 v17, v[74:77] offset:49152
	v_mfma_f32_16x16x32_f16 v[24:27], v[52:55], v[110:113], v[24:27]
	ds_read_b128 v[52:55], v22 offset:32768
	v_mfma_f32_16x16x32_f16 v[114:117], v[118:121], v[94:97], v[114:117]
	s_waitcnt vmcnt(2)
	ds_write_b128 v18, v[138:141] offset:49152
	v_mfma_f32_16x16x32_f16 v[40:43], v[118:121], v[110:113], v[40:43]
	ds_read_b128 v[118:121], v22 offset:36864
	v_mfma_f32_16x16x32_f16 v[70:73], v[130:133], v[94:97], v[70:73]
	ds_read_b128 v[94:97], v22 offset:34816
	v_mfma_f32_16x16x32_f16 v[48:51], v[130:133], v[110:113], v[48:51]
	ds_read_b128 v[110:113], v23 offset:2048
	s_waitcnt lgkmcnt(4)
	v_mfma_f32_16x16x32_f16 v[36:39], v[52:55], v[106:109], v[36:39]
	ds_read_b128 v[130:133], v22 offset:38912
	s_waitcnt lgkmcnt(1)
	v_mfma_f32_16x16x32_f16 v[66:69], v[52:55], v[110:113], v[66:69]
	s_waitcnt vmcnt(1)
	ds_write_b128 v19, v[142:145] offset:49152
	v_mfma_f32_16x16x32_f16 v[44:47], v[94:97], v[106:109], v[44:47]
	s_waitcnt vmcnt(0)
	ds_write_b128 v20, v[154:157] offset:49152
	v_mfma_f32_16x16x32_f16 v[78:81], v[94:97], v[110:113], v[78:81]
	v_mfma_f32_16x16x32_f16 v[82:85], v[118:121], v[106:109], v[82:85]
	v_mfma_f32_16x16x32_f16 v[86:89], v[118:121], v[110:113], v[86:89]
	s_waitcnt lgkmcnt(2)
	v_mfma_f32_16x16x32_f16 v[28:31], v[130:133], v[106:109], v[28:31]
	ds_read_b128 v[106:109], v23 offset:4096
	v_mfma_f32_16x16x32_f16 v[32:35], v[130:133], v[110:113], v[32:35]
	ds_read_b128 v[110:113], v23 offset:6144
	s_waitcnt lgkmcnt(1)
	v_mfma_f32_16x16x32_f16 v[98:101], v[52:55], v[106:109], v[98:101]
	s_waitcnt lgkmcnt(0)
	v_mfma_f32_16x16x32_f16 v[52:55], v[52:55], v[110:113], v[58:61]
	s_nop 2
	global_load_dwordx4 v[58:61], v[0:1], off offset:512
	v_mfma_f32_16x16x32_f16 v[102:105], v[94:97], v[106:109], v[102:105]
	v_mfma_f32_16x16x32_f16 v[24:27], v[94:97], v[110:113], v[24:27]
	v_mfma_f32_16x16x32_f16 v[114:117], v[118:121], v[106:109], v[114:117]
	v_mfma_f32_16x16x32_f16 v[40:43], v[118:121], v[110:113], v[40:43]
	v_mfma_f32_16x16x32_f16 v[70:73], v[130:133], v[106:109], v[70:73]
	global_load_dwordx4 v[106:109], v[2:3], off offset:512
	global_load_dwordx4 v[134:137], v[4:5], off offset:512
	global_load_dwordx4 v[158:161], v[14:15], off offset:512
	global_load_dwordx4 v[94:97], v[10:11], off offset:512
	global_load_dwordx4 v[162:165], v[12:13], off offset:512
	global_load_dwordx4 v[166:169], v[8:9], off offset:512
	global_load_dwordx4 v[190:193], v[6:7], off offset:512
	s_waitcnt lgkmcnt(0)
	s_barrier
	v_mfma_f32_16x16x32_f16 v[48:51], v[130:133], v[110:113], v[48:51]
	ds_read_b128 v[62:65], v16 offset:49152
	ds_read_b128 v[90:93], v21 offset:16384
	s_waitcnt lgkmcnt(0)
	v_mfma_f32_16x16x32_f16 v[36:39], v[62:65], v[90:93], v[36:39]
	ds_read_b128 v[74:77], v16 offset:51200
	ds_read_b128 v[110:113], v21 offset:18432
	s_waitcnt lgkmcnt(0)
	v_mfma_f32_16x16x32_f16 v[66:69], v[62:65], v[110:113], v[66:69]
	ds_read_b128 v[118:121], v16 offset:53248
	v_mfma_f32_16x16x32_f16 v[44:47], v[74:77], v[90:93], v[44:47]
	ds_read_b128 v[122:125], v16 offset:55296
	v_mfma_f32_16x16x32_f16 v[78:81], v[74:77], v[110:113], v[78:81]
	s_waitcnt vmcnt(7)
	ds_write_b128 v17, v[58:61]
	s_waitcnt lgkmcnt(2)
	v_mfma_f32_16x16x32_f16 v[82:85], v[118:121], v[90:93], v[82:85]
	s_waitcnt vmcnt(6)
	ds_write_b128 v18, v[106:109]
	v_mfma_f32_16x16x32_f16 v[86:89], v[118:121], v[110:113], v[86:89]
	s_waitcnt vmcnt(5)
	ds_write_b128 v19, v[134:137]
	s_waitcnt lgkmcnt(3)
	v_mfma_f32_16x16x32_f16 v[28:31], v[122:125], v[90:93], v[28:31]
	ds_read_b128 v[90:93], v21 offset:20480
	v_mfma_f32_16x16x32_f16 v[32:35], v[122:125], v[110:113], v[32:35]
	ds_read_b128 v[110:113], v21 offset:22528
	s_waitcnt lgkmcnt(1)
	v_mfma_f32_16x16x32_f16 v[98:101], v[62:65], v[90:93], v[98:101]
	s_waitcnt vmcnt(4)
	ds_write_b128 v20, v[158:161]
	s_waitcnt lgkmcnt(1)
	v_mfma_f32_16x16x32_f16 v[52:55], v[62:65], v[110:113], v[52:55]
	ds_read_b128 v[62:65], v22 offset:49152
	v_mfma_f32_16x16x32_f16 v[102:105], v[74:77], v[90:93], v[102:105]
	s_waitcnt vmcnt(3)
; #define GL_LOAD(s_, kt_) if (VAR != 1) { a##s_##0 = GL_A(0, kt_); a##s_##1 = GL_A(1, kt_); a##s_##2 = GL_A(2, kt_); a##s_##3 = GL_A(3, kt_); b##s_##0 = GL_B(0, kt_); b##s_##1 = GL_B(1, kt_); b##s_##2 = GL_B(2, kt_); b##s_##3 = GL_B(3, kt_); }
; #define LDS_STORE(s_, buf_) if (VAR != 2) { LDS_ST1(sA, 0, buf_, a##s_##0) LDS_ST1(sA, 1, buf_, a##s_##1) LDS_ST1(sA, 2, buf_, a##s_##2) LDS_ST1(sA, 3, buf_, a##s_##3) LDS_ST1(sB, 0, buf_, b##s_##0) LDS_ST1(sB, 1, buf_, b##s_##1) LDS_ST1(sB, 2, buf_, b##s_##2) LDS_ST1(sB, 3, buf_, b##s_##3) }
;     ...
;   GL_LOAD(0, 0)
;   GL_LOAD(1, 1)
;   LDS_STORE(0, 0)
;   if (VAR != 4) __syncthreads();
; #pragma unroll
;   for (int kt = 0; kt < nk; kt += 2) {
;     if (kt + 2 < nk) { GL_LOAD(0, kt + 2) }
;     MMA_TILE(0)
;     LDS_STORE(1, 1)
;     if (VAR != 4) __syncthreads();
;     if (kt + 3 < nk) { GL_LOAD(1, kt + 3) }
;     MMA_TILE(1)
;     if (kt + 2 < nk) { LDS_STORE(0, 0) }
;     if (VAR != 4) __syncthreads();
	ds_write_b128 v17, v[94:97] offset:32768
	v_mfma_f32_16x16x32_f16 v[24:27], v[74:77], v[110:113], v[24:27]
	ds_read_b128 v[74:77], v22 offset:51200
	v_mfma_f32_16x16x32_f16 v[114:117], v[118:121], v[90:93], v[114:117]
	s_waitcnt vmcnt(2)
	ds_write_b128 v18, v[162:165] offset:32768
	v_mfma_f32_16x16x32_f16 v[40:43], v[118:121], v[110:113], v[40:43]
	ds_read_b128 v[118:121], v22 offset:53248
	v_mfma_f32_16x16x32_f16 v[70:73], v[122:125], v[90:93], v[70:73]
	ds_read_b128 v[90:93], v23 offset:16384
	v_mfma_f32_16x16x32_f16 v[48:51], v[122:125], v[110:113], v[48:51]
	ds_read_b128 v[110:113], v23 offset:18432
	s_waitcnt lgkmcnt(1)
	v_mfma_f32_16x16x32_f16 v[36:39], v[62:65], v[90:93], v[36:39]
	ds_read_b128 v[122:125], v22 offset:55296
	s_waitcnt lgkmcnt(1)
	v_mfma_f32_16x16x32_f16 v[66:69], v[62:65], v[110:113], v[66:69]
	s_waitcnt vmcnt(1)
	ds_write_b128 v19, v[166:169] offset:32768
	v_mfma_f32_16x16x32_f16 v[44:47], v[74:77], v[90:93], v[44:47]
	s_waitcnt vmcnt(0)
	ds_write_b128 v20, v[190:193] offset:32768
	v_mfma_f32_16x16x32_f16 v[78:81], v[74:77], v[110:113], v[78:81]
	v_mfma_f32_16x16x32_f16 v[82:85], v[118:121], v[90:93], v[82:85]
	v_mfma_f32_16x16x32_f16 v[86:89], v[118:121], v[110:113], v[86:89]
	s_waitcnt lgkmcnt(2)
	v_mfma_f32_16x16x32_f16 v[28:31], v[122:125], v[90:93], v[28:31]
	ds_read_b128 v[90:93], v23 offset:20480
	v_mfma_f32_16x16x32_f16 v[32:35], v[122:125], v[110:113], v[32:35]
	ds_read_b128 v[110:113], v23 offset:22528
	s_waitcnt lgkmcnt(1)
	v_mfma_f32_16x16x32_f16 v[98:101], v[62:65], v[90:93], v[98:101]
	s_waitcnt lgkmcnt(0)
	v_mfma_f32_16x16x32_f16 v[52:55], v[62:65], v[110:113], v[52:55]
	global_load_dwordx4 v[62:65], v[0:1], off offset:640
	v_mfma_f32_16x16x32_f16 v[102:105], v[74:77], v[90:93], v[102:105]
	v_mfma_f32_16x16x32_f16 v[24:27], v[74:77], v[110:113], v[24:27]
	v_mfma_f32_16x16x32_f16 v[114:117], v[118:121], v[90:93], v[114:117]
	v_mfma_f32_16x16x32_f16 v[40:43], v[118:121], v[110:113], v[40:43]
	v_mfma_f32_16x16x32_f16 v[70:73], v[122:125], v[90:93], v[70:73]
	global_load_dwordx4 v[90:93], v[2:3], off offset:640
	global_load_dwordx4 v[126:129], v[4:5], off offset:640
	global_load_dwordx4 v[130:133], v[14:15], off offset:640
	global_load_dwordx4 v[74:77], v[10:11], off offset:640
	global_load_dwordx4 v[138:141], v[12:13], off offset:640
	global_load_dwordx4 v[142:145], v[8:9], off offset:640
	global_load_dwordx4 v[154:157], v[6:7], off offset:640
	s_waitcnt lgkmcnt(0)
	s_barrier
	v_mfma_f32_16x16x32_f16 v[48:51], v[122:125], v[110:113], v[48:51]
	ds_read_b128 v[58:61], v16 offset:32768
	ds_read_b128 v[106:109], v21
	s_waitcnt lgkmcnt(0)
	v_mfma_f32_16x16x32_f16 v[36:39], v[58:61], v[106:109], v[36:39]
	ds_read_b128 v[94:97], v16 offset:34816
	ds_read_b128 v[110:113], v21 offset:2048
	s_waitcnt lgkmcnt(0)
	v_mfma_f32_16x16x32_f16 v[66:69], v[58:61], v[110:113], v[66:69]
	ds_read_b128 v[118:121], v16 offset:36864
	v_mfma_f32_16x16x32_f16 v[44:47], v[94:97], v[106:109], v[44:47]
	ds_read_b128 v[122:125], v16 offset:38912
	v_mfma_f32_16x16x32_f16 v[78:81], v[94:97], v[110:113], v[78:81]
	s_waitcnt vmcnt(7)
	ds_write_b128 v17, v[62:65] offset:16384
	s_waitcnt lgkmcnt(2)
	v_mfma_f32_16x16x32_f16 v[82:85], v[118:121], v[106:109], v[82:85]
	s_waitcnt vmcnt(6)
	ds_write_b128 v18, v[90:93] offset:16384
	v_mfma_f32_16x16x32_f16 v[86:89], v[118:121], v[110:113], v[86:89]
	s_waitcnt vmcnt(5)
	ds_write_b128 v19, v[126:129] offset:16384
	s_waitcnt lgkmcnt(3)
	v_mfma_f32_16x16x32_f16 v[28:31], v[122:125], v[106:109], v[28:31]
	ds_read_b128 v[106:109], v21 offset:4096
	v_mfma_f32_16x16x32_f16 v[32:35], v[122:125], v[110:113], v[32:35]
	ds_read_b128 v[110:113], v21 offset:6144
	s_waitcnt lgkmcnt(1)
	v_mfma_f32_16x16x32_f16 v[98:101], v[58:61], v[106:109], v[98:101]
	s_waitcnt vmcnt(4)
	ds_write_b128 v20, v[130:133] offset:16384
	s_waitcnt lgkmcnt(1)
	v_mfma_f32_16x16x32_f16 v[52:55], v[58:61], v[110:113], v[52:55]
	ds_read_b128 v[58:61], v22 offset:32768
	v_mfma_f32_16x16x32_f16 v[102:105], v[94:97], v[106:109], v[102:105]
	s_waitcnt vmcnt(3)
	ds_write_b128 v17, v[74:77] offset:49152
	v_mfma_f32_16x16x32_f16 v[24:27], v[94:97], v[110:113], v[24:27]
	ds_read_b128 v[94:97], v22 offset:34816
	v_mfma_f32_16x16x32_f16 v[114:117], v[118:121], v[106:109], v[114:117]
	s_waitcnt vmcnt(2)
	ds_write_b128 v18, v[138:141] offset:49152
	v_mfma_f32_16x16x32_f16 v[40:43], v[118:121], v[110:113], v[40:43]
	ds_read_b128 v[118:121], v22 offset:36864
	v_mfma_f32_16x16x32_f16 v[70:73], v[122:125], v[106:109], v[70:73]
	ds_read_b128 v[106:109], v23
	v_mfma_f32_16x16x32_f16 v[48:51], v[122:125], v[110:113], v[48:51]
	ds_read_b128 v[110:113], v23 offset:2048
	s_waitcnt lgkmcnt(1)
	v_mfma_f32_16x16x32_f16 v[36:39], v[58:61], v[106:109], v[36:39]
	ds_read_b128 v[122:125], v22 offset:38912
	s_waitcnt lgkmcnt(1)
	v_mfma_f32_16x16x32_f16 v[66:69], v[58:61], v[110:113], v[66:69]
	s_waitcnt vmcnt(1)
	ds_write_b128 v19, v[142:145] offset:49152
	v_mfma_f32_16x16x32_f16 v[44:47], v[94:97], v[106:109], v[44:47]
	s_waitcnt vmcnt(0)
	ds_write_b128 v20, v[154:157] offset:49152
	v_mfma_f32_16x16x32_f16 v[78:81], v[94:97], v[110:113], v[78:81]
	v_mfma_f32_16x16x32_f16 v[82:85], v[118:121], v[106:109], v[82:85]
	v_mfma_f32_16x16x32_f16 v[86:89], v[118:121], v[110:113], v[86:89]
	s_waitcnt lgkmcnt(2)
	v_mfma_f32_16x16x32_f16 v[28:31], v[122:125], v[106:109], v[28:31]
	ds_read_b128 v[106:109], v23 offset:4096
	v_mfma_f32_16x16x32_f16 v[32:35], v[122:125], v[110:113], v[32:35]
	ds_read_b128 v[110:113], v23 offset:6144
	s_waitcnt lgkmcnt(1)
	v_mfma_f32_16x16x32_f16 v[98:101], v[58:61], v[106:109], v[98:101]
	s_waitcnt lgkmcnt(0)
	v_mfma_f32_16x16x32_f16 v[52:55], v[58:61], v[110:113], v[52:55]
	global_load_dwordx4 v[58:61], v[0:1], off offset:768
	v_mfma_f32_16x16x32_f16 v[102:105], v[94:97], v[106:109], v[102:105]
	v_mfma_f32_16x16x32_f16 v[24:27], v[94:97], v[110:113], v[24:27]
	v_mfma_f32_16x16x32_f16 v[114:117], v[118:121], v[106:109], v[114:117]
	v_mfma_f32_16x16x32_f16 v[40:43], v[118:121], v[110:113], v[40:43]
	v_mfma_f32_16x16x32_f16 v[70:73], v[122:125], v[106:109], v[70:73]
	global_load_dwordx4 v[106:109], v[2:3], off offset:768
	global_load_dwordx4 v[134:137], v[4:5], off offset:768
	global_load_dwordx4 v[158:161], v[14:15], off offset:768
	global_load_dwordx4 v[94:97], v[10:11], off offset:768
	global_load_dwordx4 v[162:165], v[12:13], off offset:768
	global_load_dwordx4 v[166:169], v[8:9], off offset:768
	global_load_dwordx4 v[190:193], v[6:7], off offset:768
	s_waitcnt lgkmcnt(0)
	s_barrier
; #define GL_LOAD(s_, kt_) if (VAR != 1) { a##s_##0 = GL_A(0, kt_); a##s_##1 = GL_A(1, kt_); a##s_##2 = GL_A(2, kt_); a##s_##3 = GL_A(3, kt_); b##s_##0 = GL_B(0, kt_); b##s_##1 = GL_B(1, kt_); b##s_##2 = GL_B(2, kt_); b##s_##3 = GL_B(3, kt_); }
; #define LDS_STORE(s_, buf_) if (VAR != 2) { LDS_ST1(sA, 0, buf_, a##s_##0) LDS_ST1(sA, 1, buf_, a##s_##1) LDS_ST1(sA, 2, buf_, a##s_##2) LDS_ST1(sA, 3, buf_, a##s_##3) LDS_ST1(sB, 0, buf_, b##s_##0) LDS_ST1(sB, 1, buf_, b##s_##1) LDS_ST1(sB, 2, buf_, b##s_##2) LDS_ST1(sB, 3, buf_, b##s_##3) }
;     ...
;   GL_LOAD(0, 0)
;   GL_LOAD(1, 1)
;   LDS_STORE(0, 0)
;   if (VAR != 4) __syncthreads();
; #pragma unroll
;   for (int kt = 0; kt < nk; kt += 2) {
;     if (kt + 2 < nk) { GL_LOAD(0, kt + 2) }
;     MMA_TILE(0)
;     LDS_STORE(1, 1)
;     if (VAR != 4) __syncthreads();
;     if (kt + 3 < nk) { GL_LOAD(1, kt + 3) }
;     MMA_TILE(1)
;     if (kt + 2 < nk) { LDS_STORE(0, 0) }
;     if (VAR != 4) __syncthreads();
	v_mfma_f32_16x16x32_f16 v[48:51], v[122:125], v[110:113], v[48:51]
	ds_read_b128 v[62:65], v16 offset:49152
	ds_read_b128 v[90:93], v21 offset:16384
	s_waitcnt lgkmcnt(0)
	v_mfma_f32_16x16x32_f16 v[36:39], v[62:65], v[90:93], v[36:39]
	ds_read_b128 v[74:77], v16 offset:51200
	ds_read_b128 v[110:113], v21 offset:18432
	s_waitcnt lgkmcnt(0)
	v_mfma_f32_16x16x32_f16 v[66:69], v[62:65], v[110:113], v[66:69]
	ds_read_b128 v[118:121], v16 offset:53248
	v_mfma_f32_16x16x32_f16 v[44:47], v[74:77], v[90:93], v[44:47]
	ds_read_b128 v[122:125], v16 offset:55296
	v_mfma_f32_16x16x32_f16 v[78:81], v[74:77], v[110:113], v[78:81]
	s_waitcnt vmcnt(7)
	ds_write_b128 v17, v[58:61]
	s_waitcnt lgkmcnt(2)
	v_mfma_f32_16x16x32_f16 v[82:85], v[118:121], v[90:93], v[82:85]
	s_waitcnt vmcnt(6)
	ds_write_b128 v18, v[106:109]
	v_mfma_f32_16x16x32_f16 v[86:89], v[118:121], v[110:113], v[86:89]
	s_waitcnt vmcnt(5)
	ds_write_b128 v19, v[134:137]
	s_waitcnt lgkmcnt(3)
	v_mfma_f32_16x16x32_f16 v[28:31], v[122:125], v[90:93], v[28:31]
	ds_read_b128 v[90:93], v21 offset:20480
	v_mfma_f32_16x16x32_f16 v[32:35], v[122:125], v[110:113], v[32:35]
	ds_read_b128 v[110:113], v21 offset:22528
	s_waitcnt lgkmcnt(1)
	v_mfma_f32_16x16x32_f16 v[98:101], v[62:65], v[90:93], v[98:101]
	s_waitcnt vmcnt(4)
	ds_write_b128 v20, v[158:161]
	s_waitcnt lgkmcnt(1)
	v_mfma_f32_16x16x32_f16 v[52:55], v[62:65], v[110:113], v[52:55]
	ds_read_b128 v[62:65], v22 offset:49152
	v_mfma_f32_16x16x32_f16 v[102:105], v[74:77], v[90:93], v[102:105]
	s_waitcnt vmcnt(3)
	ds_write_b128 v17, v[94:97] offset:32768
	v_mfma_f32_16x16x32_f16 v[24:27], v[74:77], v[110:113], v[24:27]
	ds_read_b128 v[74:77], v22 offset:51200
	v_mfma_f32_16x16x32_f16 v[114:117], v[118:121], v[90:93], v[114:117]
	s_waitcnt vmcnt(2)
	ds_write_b128 v18, v[162:165] offset:32768
	v_mfma_f32_16x16x32_f16 v[40:43], v[118:121], v[110:113], v[40:43]
	ds_read_b128 v[118:121], v22 offset:53248
	v_mfma_f32_16x16x32_f16 v[70:73], v[122:125], v[90:93], v[70:73]
	ds_read_b128 v[90:93], v23 offset:16384
	v_mfma_f32_16x16x32_f16 v[48:51], v[122:125], v[110:113], v[48:51]
	ds_read_b128 v[110:113], v23 offset:18432
	s_waitcnt lgkmcnt(1)
	v_mfma_f32_16x16x32_f16 v[36:39], v[62:65], v[90:93], v[36:39]
	ds_read_b128 v[122:125], v22 offset:55296
	s_waitcnt lgkmcnt(1)
	v_mfma_f32_16x16x32_f16 v[66:69], v[62:65], v[110:113], v[66:69]
	s_waitcnt vmcnt(1)
	ds_write_b128 v19, v[166:169] offset:32768
	v_mfma_f32_16x16x32_f16 v[44:47], v[74:77], v[90:93], v[44:47]
	s_waitcnt vmcnt(0)
	ds_write_b128 v20, v[190:193] offset:32768
	v_mfma_f32_16x16x32_f16 v[78:81], v[74:77], v[110:113], v[78:81]
	v_mfma_f32_16x16x32_f16 v[82:85], v[118:121], v[90:93], v[82:85]
	v_mfma_f32_16x16x32_f16 v[86:89], v[118:121], v[110:113], v[86:89]
	s_waitcnt lgkmcnt(2)
	v_mfma_f32_16x16x32_f16 v[28:31], v[122:125], v[90:93], v[28:31]
	ds_read_b128 v[90:93], v23 offset:20480
	v_mfma_f32_16x16x32_f16 v[32:35], v[122:125], v[110:113], v[32:35]
	ds_read_b128 v[110:113], v23 offset:22528
	s_waitcnt lgkmcnt(1)
	v_mfma_f32_16x16x32_f16 v[98:101], v[62:65], v[90:93], v[98:101]
	s_waitcnt lgkmcnt(0)
	v_mfma_f32_16x16x32_f16 v[52:55], v[62:65], v[110:113], v[52:55]
	global_load_dwordx4 v[62:65], v[0:1], off offset:896
	v_mfma_f32_16x16x32_f16 v[102:105], v[74:77], v[90:93], v[102:105]
	v_mfma_f32_16x16x32_f16 v[24:27], v[74:77], v[110:113], v[24:27]
	v_mfma_f32_16x16x32_f16 v[114:117], v[118:121], v[90:93], v[114:117]
	v_mfma_f32_16x16x32_f16 v[40:43], v[118:121], v[110:113], v[40:43]
	v_mfma_f32_16x16x32_f16 v[70:73], v[122:125], v[90:93], v[70:73]
	global_load_dwordx4 v[90:93], v[2:3], off offset:896
	global_load_dwordx4 v[126:129], v[4:5], off offset:896
	global_load_dwordx4 v[130:133], v[14:15], off offset:896
	global_load_dwordx4 v[74:77], v[10:11], off offset:896
	global_load_dwordx4 v[138:141], v[12:13], off offset:896
	global_load_dwordx4 v[142:145], v[8:9], off offset:896
	global_load_dwordx4 v[154:157], v[6:7], off offset:896
	s_waitcnt lgkmcnt(0)
	s_barrier
	v_mfma_f32_16x16x32_f16 v[48:51], v[122:125], v[110:113], v[48:51]
	ds_read_b128 v[58:61], v16 offset:32768
	ds_read_b128 v[106:109], v21
	s_waitcnt lgkmcnt(0)
	v_mfma_f32_16x16x32_f16 v[36:39], v[58:61], v[106:109], v[36:39]
	ds_read_b128 v[94:97], v16 offset:34816
	ds_read_b128 v[110:113], v21 offset:2048
	s_waitcnt lgkmcnt(0)
	v_mfma_f32_16x16x32_f16 v[66:69], v[58:61], v[110:113], v[66:69]
	ds_read_b128 v[118:121], v16 offset:36864
	v_mfma_f32_16x16x32_f16 v[44:47], v[94:97], v[106:109], v[44:47]
	ds_read_b128 v[122:125], v16 offset:38912
	v_mfma_f32_16x16x32_f16 v[78:81], v[94:97], v[110:113], v[78:81]
	s_waitcnt vmcnt(7)
	ds_write_b128 v17, v[62:65] offset:16384
	s_waitcnt lgkmcnt(2)
	v_mfma_f32_16x16x32_f16 v[82:85], v[118:121], v[106:109], v[82:85]
	s_waitcnt vmcnt(6)
	ds_write_b128 v18, v[90:93] offset:16384
	v_mfma_f32_16x16x32_f16 v[86:89], v[118:121], v[110:113], v[86:89]
	s_waitcnt vmcnt(5)
	ds_write_b128 v19, v[126:129] offset:16384
	s_waitcnt lgkmcnt(3)
	v_mfma_f32_16x16x32_f16 v[28:31], v[122:125], v[106:109], v[28:31]
	ds_read_b128 v[106:109], v21 offset:4096
	v_mfma_f32_16x16x32_f16 v[32:35], v[122:125], v[110:113], v[32:35]
	ds_read_b128 v[110:113], v21 offset:6144
	s_waitcnt lgkmcnt(1)
	v_mfma_f32_16x16x32_f16 v[98:101], v[58:61], v[106:109], v[98:101]
	s_waitcnt vmcnt(4)
	ds_write_b128 v20, v[130:133] offset:16384
	s_waitcnt lgkmcnt(1)
	v_mfma_f32_16x16x32_f16 v[52:55], v[58:61], v[110:113], v[52:55]
	ds_read_b128 v[58:61], v22 offset:32768
	v_mfma_f32_16x16x32_f16 v[102:105], v[94:97], v[106:109], v[102:105]
	s_waitcnt vmcnt(3)
; #define GL_LOAD(s_, kt_) if (VAR != 1) { a##s_##0 = GL_A(0, kt_); a##s_##1 = GL_A(1, kt_); a##s_##2 = GL_A(2, kt_); a##s_##3 = GL_A(3, kt_); b##s_##0 = GL_B(0, kt_); b##s_##1 = GL_B(1, kt_); b##s_##2 = GL_B(2, kt_); b##s_##3 = GL_B(3, kt_); }
; #define LDS_STORE(s_, buf_) if (VAR != 2) { LDS_ST1(sA, 0, buf_, a##s_##0) LDS_ST1(sA, 1, buf_, a##s_##1) LDS_ST1(sA, 2, buf_, a##s_##2) LDS_ST1(sA, 3, buf_, a##s_##3) LDS_ST1(sB, 0, buf_, b##s_##0) LDS_ST1(sB, 1, buf_, b##s_##1) LDS_ST1(sB, 2, buf_, b##s_##2) LDS_ST1(sB, 3, buf_, b##s_##3) }
;     ...
;   GL_LOAD(0, 0)
;   GL_LOAD(1, 1)
;   LDS_STORE(0, 0)
;   if (VAR != 4) __syncthreads();
; #pragma unroll
;   for (int kt = 0; kt < nk; kt += 2) {
;     if (kt + 2 < nk) { GL_LOAD(0, kt + 2) }
;     MMA_TILE(0)
;     LDS_STORE(1, 1)
;     if (VAR != 4) __syncthreads();
;     if (kt + 3 < nk) { GL_LOAD(1, kt + 3) }
;     MMA_TILE(1)
;     if (kt + 2 < nk) { LDS_STORE(0, 0) }
;     if (VAR != 4) __syncthreads();
	ds_write_b128 v17, v[74:77] offset:49152
	v_mfma_f32_16x16x32_f16 v[24:27], v[94:97], v[110:113], v[24:27]
	ds_read_b128 v[94:97], v22 offset:34816
	v_mfma_f32_16x16x32_f16 v[114:117], v[118:121], v[106:109], v[114:117]
	s_waitcnt vmcnt(2)
	ds_write_b128 v18, v[138:141] offset:49152
	v_mfma_f32_16x16x32_f16 v[40:43], v[118:121], v[110:113], v[40:43]
	ds_read_b128 v[118:121], v22 offset:36864
	v_mfma_f32_16x16x32_f16 v[70:73], v[122:125], v[106:109], v[70:73]
	ds_read_b128 v[106:109], v23
	v_mfma_f32_16x16x32_f16 v[48:51], v[122:125], v[110:113], v[48:51]
	ds_read_b128 v[110:113], v23 offset:2048
	s_waitcnt lgkmcnt(1)
	v_mfma_f32_16x16x32_f16 v[36:39], v[58:61], v[106:109], v[36:39]
	ds_read_b128 v[122:125], v22 offset:38912
	s_waitcnt lgkmcnt(1)
	v_mfma_f32_16x16x32_f16 v[66:69], v[58:61], v[110:113], v[66:69]
	s_waitcnt vmcnt(1)
	ds_write_b128 v19, v[142:145] offset:49152
	v_mfma_f32_16x16x32_f16 v[44:47], v[94:97], v[106:109], v[44:47]
	s_waitcnt vmcnt(0)
	ds_write_b128 v20, v[154:157] offset:49152
	v_mfma_f32_16x16x32_f16 v[78:81], v[94:97], v[110:113], v[78:81]
	v_mfma_f32_16x16x32_f16 v[82:85], v[118:121], v[106:109], v[82:85]
	v_mfma_f32_16x16x32_f16 v[86:89], v[118:121], v[110:113], v[86:89]
	s_waitcnt lgkmcnt(2)
	v_mfma_f32_16x16x32_f16 v[28:31], v[122:125], v[106:109], v[28:31]
	ds_read_b128 v[106:109], v23 offset:4096
	v_mfma_f32_16x16x32_f16 v[32:35], v[122:125], v[110:113], v[32:35]
	ds_read_b128 v[110:113], v23 offset:6144
	s_waitcnt lgkmcnt(1)
	v_mfma_f32_16x16x32_f16 v[98:101], v[58:61], v[106:109], v[98:101]
	s_waitcnt lgkmcnt(0)
	v_mfma_f32_16x16x32_f16 v[52:55], v[58:61], v[110:113], v[52:55]
	global_load_dwordx4 v[58:61], v[0:1], off offset:1024
	v_mfma_f32_16x16x32_f16 v[102:105], v[94:97], v[106:109], v[102:105]
	v_mfma_f32_16x16x32_f16 v[24:27], v[94:97], v[110:113], v[24:27]
	v_mfma_f32_16x16x32_f16 v[114:117], v[118:121], v[106:109], v[114:117]
	v_mfma_f32_16x16x32_f16 v[40:43], v[118:121], v[110:113], v[40:43]
	v_mfma_f32_16x16x32_f16 v[70:73], v[122:125], v[106:109], v[70:73]
	global_load_dwordx4 v[106:109], v[2:3], off offset:1024
	global_load_dwordx4 v[134:137], v[4:5], off offset:1024
	global_load_dwordx4 v[158:161], v[14:15], off offset:1024
	global_load_dwordx4 v[94:97], v[10:11], off offset:1024
	global_load_dwordx4 v[162:165], v[12:13], off offset:1024
	global_load_dwordx4 v[166:169], v[8:9], off offset:1024
	global_load_dwordx4 v[190:193], v[6:7], off offset:1024
	s_waitcnt lgkmcnt(0)
	s_barrier
	v_mfma_f32_16x16x32_f16 v[48:51], v[122:125], v[110:113], v[48:51]
	ds_read_b128 v[62:65], v16 offset:49152
	ds_read_b128 v[90:93], v21 offset:16384
	s_waitcnt lgkmcnt(0)
	v_mfma_f32_16x16x32_f16 v[36:39], v[62:65], v[90:93], v[36:39]
	ds_read_b128 v[74:77], v16 offset:51200
	ds_read_b128 v[110:113], v21 offset:18432
	s_waitcnt lgkmcnt(0)
	v_mfma_f32_16x16x32_f16 v[66:69], v[62:65], v[110:113], v[66:69]
	ds_read_b128 v[118:121], v16 offset:53248
	v_mfma_f32_16x16x32_f16 v[44:47], v[74:77], v[90:93], v[44:47]
	ds_read_b128 v[122:125], v16 offset:55296
	v_mfma_f32_16x16x32_f16 v[78:81], v[74:77], v[110:113], v[78:81]
	s_waitcnt vmcnt(7)
	ds_write_b128 v17, v[58:61]
	s_waitcnt lgkmcnt(2)
	v_mfma_f32_16x16x32_f16 v[82:85], v[118:121], v[90:93], v[82:85]
	s_waitcnt vmcnt(6)
	ds_write_b128 v18, v[106:109]
	v_mfma_f32_16x16x32_f16 v[86:89], v[118:121], v[110:113], v[86:89]
	s_waitcnt vmcnt(5)
	ds_write_b128 v19, v[134:137]
	s_waitcnt lgkmcnt(3)
	v_mfma_f32_16x16x32_f16 v[28:31], v[122:125], v[90:93], v[28:31]
	ds_read_b128 v[90:93], v21 offset:20480
	v_mfma_f32_16x16x32_f16 v[32:35], v[122:125], v[110:113], v[32:35]
	ds_read_b128 v[110:113], v21 offset:22528
	s_waitcnt lgkmcnt(1)
	v_mfma_f32_16x16x32_f16 v[98:101], v[62:65], v[90:93], v[98:101]
	s_waitcnt vmcnt(4)
	ds_write_b128 v20, v[158:161]
	s_waitcnt lgkmcnt(1)
	v_mfma_f32_16x16x32_f16 v[52:55], v[62:65], v[110:113], v[52:55]
	ds_read_b128 v[62:65], v22 offset:49152
	v_mfma_f32_16x16x32_f16 v[102:105], v[74:77], v[90:93], v[102:105]
	s_waitcnt vmcnt(3)
	ds_write_b128 v17, v[94:97] offset:32768
	v_mfma_f32_16x16x32_f16 v[24:27], v[74:77], v[110:113], v[24:27]
	ds_read_b128 v[74:77], v22 offset:51200
	v_mfma_f32_16x16x32_f16 v[114:117], v[118:121], v[90:93], v[114:117]
	s_waitcnt vmcnt(2)
	ds_write_b128 v18, v[162:165] offset:32768
	v_mfma_f32_16x16x32_f16 v[40:43], v[118:121], v[110:113], v[40:43]
	ds_read_b128 v[118:121], v22 offset:53248
	v_mfma_f32_16x16x32_f16 v[70:73], v[122:125], v[90:93], v[70:73]
	ds_read_b128 v[90:93], v23 offset:16384
	v_mfma_f32_16x16x32_f16 v[48:51], v[122:125], v[110:113], v[48:51]
	ds_read_b128 v[110:113], v23 offset:18432
	s_waitcnt lgkmcnt(1)
	v_mfma_f32_16x16x32_f16 v[36:39], v[62:65], v[90:93], v[36:39]
	ds_read_b128 v[122:125], v22 offset:55296
	s_waitcnt lgkmcnt(1)
	v_mfma_f32_16x16x32_f16 v[66:69], v[62:65], v[110:113], v[66:69]
	s_waitcnt vmcnt(1)
	ds_write_b128 v19, v[166:169] offset:32768
	v_mfma_f32_16x16x32_f16 v[44:47], v[74:77], v[90:93], v[44:47]
	s_waitcnt vmcnt(0)
	ds_write_b128 v20, v[190:193] offset:32768
	v_mfma_f32_16x16x32_f16 v[78:81], v[74:77], v[110:113], v[78:81]
	v_mfma_f32_16x16x32_f16 v[82:85], v[118:121], v[90:93], v[82:85]
	v_mfma_f32_16x16x32_f16 v[86:89], v[118:121], v[110:113], v[86:89]
	s_waitcnt lgkmcnt(2)
	v_mfma_f32_16x16x32_f16 v[28:31], v[122:125], v[90:93], v[28:31]
	ds_read_b128 v[90:93], v23 offset:20480
	v_mfma_f32_16x16x32_f16 v[32:35], v[122:125], v[110:113], v[32:35]
	ds_read_b128 v[110:113], v23 offset:22528
	s_waitcnt lgkmcnt(1)
	v_mfma_f32_16x16x32_f16 v[98:101], v[62:65], v[90:93], v[98:101]
	s_waitcnt lgkmcnt(0)
	v_mfma_f32_16x16x32_f16 v[52:55], v[62:65], v[110:113], v[52:55]
	global_load_dwordx4 v[62:65], v[0:1], off offset:1152
	v_mfma_f32_16x16x32_f16 v[102:105], v[74:77], v[90:93], v[102:105]
	v_mfma_f32_16x16x32_f16 v[24:27], v[74:77], v[110:113], v[24:27]
	v_mfma_f32_16x16x32_f16 v[114:117], v[118:121], v[90:93], v[114:117]
	v_mfma_f32_16x16x32_f16 v[40:43], v[118:121], v[110:113], v[40:43]
	v_mfma_f32_16x16x32_f16 v[70:73], v[122:125], v[90:93], v[70:73]
	global_load_dwordx4 v[90:93], v[2:3], off offset:1152
	global_load_dwordx4 v[126:129], v[4:5], off offset:1152
	global_load_dwordx4 v[130:133], v[14:15], off offset:1152
	global_load_dwordx4 v[74:77], v[10:11], off offset:1152
	global_load_dwordx4 v[138:141], v[12:13], off offset:1152
	global_load_dwordx4 v[142:145], v[8:9], off offset:1152
	global_load_dwordx4 v[154:157], v[6:7], off offset:1152
	s_waitcnt lgkmcnt(0)
	s_barrier
; #define GL_LOAD(s_, kt_) if (VAR != 1) { a##s_##0 = GL_A(0, kt_); a##s_##1 = GL_A(1, kt_); a##s_##2 = GL_A(2, kt_); a##s_##3 = GL_A(3, kt_); b##s_##0 = GL_B(0, kt_); b##s_##1 = GL_B(1, kt_); b##s_##2 = GL_B(2, kt_); b##s_##3 = GL_B(3, kt_); }
; #define LDS_STORE(s_, buf_) if (VAR != 2) { LDS_ST1(sA, 0, buf_, a##s_##0) LDS_ST1(sA, 1, buf_, a##s_##1) LDS_ST1(sA, 2, buf_, a##s_##2) LDS_ST1(sA, 3, buf_, a##s_##3) LDS_ST1(sB, 0, buf_, b##s_##0) LDS_ST1(sB, 1, buf_, b##s_##1) LDS_ST1(sB, 2, buf_, b##s_##2) LDS_ST1(sB, 3, buf_, b##s_##3) }
;     ...
;   GL_LOAD(0, 0)
;   GL_LOAD(1, 1)
;   LDS_STORE(0, 0)
;   if (VAR != 4) __syncthreads();
; #pragma unroll
;   for (int kt = 0; kt < nk; kt += 2) {
;     if (kt + 2 < nk) { GL_LOAD(0, kt + 2) }
;     MMA_TILE(0)
;     LDS_STORE(1, 1)
;     if (VAR != 4) __syncthreads();
;     if (kt + 3 < nk) { GL_LOAD(1, kt + 3) }
;     MMA_TILE(1)
;     if (kt + 2 < nk) { LDS_STORE(0, 0) }
;     if (VAR != 4) __syncthreads();
	v_mfma_f32_16x16x32_f16 v[48:51], v[122:125], v[110:113], v[48:51]
	ds_read_b128 v[58:61], v16 offset:32768
	ds_read_b128 v[106:109], v21
	s_waitcnt lgkmcnt(0)
	v_mfma_f32_16x16x32_f16 v[36:39], v[58:61], v[106:109], v[36:39]
	ds_read_b128 v[94:97], v16 offset:34816
	ds_read_b128 v[110:113], v21 offset:2048
	s_waitcnt lgkmcnt(0)
	v_mfma_f32_16x16x32_f16 v[66:69], v[58:61], v[110:113], v[66:69]
	ds_read_b128 v[118:121], v16 offset:36864
	v_mfma_f32_16x16x32_f16 v[44:47], v[94:97], v[106:109], v[44:47]
	ds_read_b128 v[122:125], v16 offset:38912
	v_mfma_f32_16x16x32_f16 v[78:81], v[94:97], v[110:113], v[78:81]
	s_waitcnt vmcnt(7)
	ds_write_b128 v17, v[62:65] offset:16384
	s_waitcnt lgkmcnt(2)
	v_mfma_f32_16x16x32_f16 v[82:85], v[118:121], v[106:109], v[82:85]
	s_waitcnt vmcnt(6)
	ds_write_b128 v18, v[90:93] offset:16384
	v_mfma_f32_16x16x32_f16 v[86:89], v[118:121], v[110:113], v[86:89]
	s_waitcnt vmcnt(5)
	ds_write_b128 v19, v[126:129] offset:16384
	s_waitcnt lgkmcnt(3)
	v_mfma_f32_16x16x32_f16 v[28:31], v[122:125], v[106:109], v[28:31]
	ds_read_b128 v[106:109], v21 offset:4096
	v_mfma_f32_16x16x32_f16 v[32:35], v[122:125], v[110:113], v[32:35]
	ds_read_b128 v[110:113], v21 offset:6144
	s_waitcnt lgkmcnt(1)
	v_mfma_f32_16x16x32_f16 v[98:101], v[58:61], v[106:109], v[98:101]
	s_waitcnt vmcnt(4)
	ds_write_b128 v20, v[130:133] offset:16384
	s_waitcnt lgkmcnt(1)
	v_mfma_f32_16x16x32_f16 v[52:55], v[58:61], v[110:113], v[52:55]
	ds_read_b128 v[58:61], v22 offset:32768
	v_mfma_f32_16x16x32_f16 v[102:105], v[94:97], v[106:109], v[102:105]
	s_waitcnt vmcnt(3)
	ds_write_b128 v17, v[74:77] offset:49152
	v_mfma_f32_16x16x32_f16 v[24:27], v[94:97], v[110:113], v[24:27]
	ds_read_b128 v[94:97], v22 offset:34816
	v_mfma_f32_16x16x32_f16 v[114:117], v[118:121], v[106:109], v[114:117]
	s_waitcnt vmcnt(2)
	ds_write_b128 v18, v[138:141] offset:49152
	v_mfma_f32_16x16x32_f16 v[40:43], v[118:121], v[110:113], v[40:43]
	ds_read_b128 v[118:121], v22 offset:36864
	v_mfma_f32_16x16x32_f16 v[70:73], v[122:125], v[106:109], v[70:73]
	ds_read_b128 v[106:109], v23
	v_mfma_f32_16x16x32_f16 v[48:51], v[122:125], v[110:113], v[48:51]
	ds_read_b128 v[110:113], v23 offset:2048
	s_waitcnt lgkmcnt(1)
	v_mfma_f32_16x16x32_f16 v[36:39], v[58:61], v[106:109], v[36:39]
	ds_read_b128 v[122:125], v22 offset:38912
	s_waitcnt lgkmcnt(1)
	v_mfma_f32_16x16x32_f16 v[66:69], v[58:61], v[110:113], v[66:69]
	s_waitcnt vmcnt(1)
	ds_write_b128 v19, v[142:145] offset:49152
	v_mfma_f32_16x16x32_f16 v[44:47], v[94:97], v[106:109], v[44:47]
	s_waitcnt vmcnt(0)
	ds_write_b128 v20, v[154:157] offset:49152
	v_mfma_f32_16x16x32_f16 v[78:81], v[94:97], v[110:113], v[78:81]
	v_mfma_f32_16x16x32_f16 v[82:85], v[118:121], v[106:109], v[82:85]
	v_mfma_f32_16x16x32_f16 v[86:89], v[118:121], v[110:113], v[86:89]
	s_waitcnt lgkmcnt(2)
	v_mfma_f32_16x16x32_f16 v[28:31], v[122:125], v[106:109], v[28:31]
	ds_read_b128 v[106:109], v23 offset:4096
	v_mfma_f32_16x16x32_f16 v[32:35], v[122:125], v[110:113], v[32:35]
	ds_read_b128 v[110:113], v23 offset:6144
	s_waitcnt lgkmcnt(1)
	v_mfma_f32_16x16x32_f16 v[98:101], v[58:61], v[106:109], v[98:101]
	s_waitcnt lgkmcnt(0)
	v_mfma_f32_16x16x32_f16 v[52:55], v[58:61], v[110:113], v[52:55]
	global_load_dwordx4 v[58:61], v[0:1], off offset:1280
	v_mfma_f32_16x16x32_f16 v[102:105], v[94:97], v[106:109], v[102:105]
	v_mfma_f32_16x16x32_f16 v[24:27], v[94:97], v[110:113], v[24:27]
	v_mfma_f32_16x16x32_f16 v[114:117], v[118:121], v[106:109], v[114:117]
	v_mfma_f32_16x16x32_f16 v[40:43], v[118:121], v[110:113], v[40:43]
	v_mfma_f32_16x16x32_f16 v[70:73], v[122:125], v[106:109], v[70:73]
	global_load_dwordx4 v[106:109], v[2:3], off offset:1280
	global_load_dwordx4 v[134:137], v[4:5], off offset:1280
	global_load_dwordx4 v[158:161], v[14:15], off offset:1280
	global_load_dwordx4 v[94:97], v[10:11], off offset:1280
	global_load_dwordx4 v[162:165], v[12:13], off offset:1280
	global_load_dwordx4 v[166:169], v[8:9], off offset:1280
	global_load_dwordx4 v[190:193], v[6:7], off offset:1280
	s_waitcnt lgkmcnt(0)
	s_barrier
	v_mfma_f32_16x16x32_f16 v[48:51], v[122:125], v[110:113], v[48:51]
	ds_read_b128 v[62:65], v16 offset:49152
	ds_read_b128 v[90:93], v21 offset:16384
	s_waitcnt lgkmcnt(0)
	v_mfma_f32_16x16x32_f16 v[36:39], v[62:65], v[90:93], v[36:39]
	ds_read_b128 v[74:77], v16 offset:51200
	ds_read_b128 v[110:113], v21 offset:18432
	s_waitcnt lgkmcnt(0)
	v_mfma_f32_16x16x32_f16 v[66:69], v[62:65], v[110:113], v[66:69]
	ds_read_b128 v[118:121], v16 offset:53248
	v_mfma_f32_16x16x32_f16 v[44:47], v[74:77], v[90:93], v[44:47]
	ds_read_b128 v[122:125], v16 offset:55296
	v_mfma_f32_16x16x32_f16 v[78:81], v[74:77], v[110:113], v[78:81]
	s_waitcnt vmcnt(7)
	ds_write_b128 v17, v[58:61]
	s_waitcnt lgkmcnt(2)
	v_mfma_f32_16x16x32_f16 v[82:85], v[118:121], v[90:93], v[82:85]
	s_waitcnt vmcnt(6)
	ds_write_b128 v18, v[106:109]
	v_mfma_f32_16x16x32_f16 v[86:89], v[118:121], v[110:113], v[86:89]
	s_waitcnt vmcnt(5)
	ds_write_b128 v19, v[134:137]
	s_waitcnt lgkmcnt(3)
	v_mfma_f32_16x16x32_f16 v[28:31], v[122:125], v[90:93], v[28:31]
	ds_read_b128 v[90:93], v21 offset:20480
	v_mfma_f32_16x16x32_f16 v[32:35], v[122:125], v[110:113], v[32:35]
	ds_read_b128 v[110:113], v21 offset:22528
	s_waitcnt lgkmcnt(1)
	v_mfma_f32_16x16x32_f16 v[98:101], v[62:65], v[90:93], v[98:101]
	s_waitcnt vmcnt(4)
	ds_write_b128 v20, v[158:161]
	s_waitcnt lgkmcnt(1)
	v_mfma_f32_16x16x32_f16 v[52:55], v[62:65], v[110:113], v[52:55]
	ds_read_b128 v[62:65], v22 offset:49152
	v_mfma_f32_16x16x32_f16 v[102:105], v[74:77], v[90:93], v[102:105]
	s_waitcnt vmcnt(3)
; #define GL_LOAD(s_, kt_) if (VAR != 1) { a##s_##0 = GL_A(0, kt_); a##s_##1 = GL_A(1, kt_); a##s_##2 = GL_A(2, kt_); a##s_##3 = GL_A(3, kt_); b##s_##0 = GL_B(0, kt_); b##s_##1 = GL_B(1, kt_); b##s_##2 = GL_B(2, kt_); b##s_##3 = GL_B(3, kt_); }
; #define LDS_STORE(s_, buf_) if (VAR != 2) { LDS_ST1(sA, 0, buf_, a##s_##0) LDS_ST1(sA, 1, buf_, a##s_##1) LDS_ST1(sA, 2, buf_, a##s_##2) LDS_ST1(sA, 3, buf_, a##s_##3) LDS_ST1(sB, 0, buf_, b##s_##0) LDS_ST1(sB, 1, buf_, b##s_##1) LDS_ST1(sB, 2, buf_, b##s_##2) LDS_ST1(sB, 3, buf_, b##s_##3) }
;     ...
;   GL_LOAD(0, 0)
;   GL_LOAD(1, 1)
;   LDS_STORE(0, 0)
;   if (VAR != 4) __syncthreads();
; #pragma unroll
;   for (int kt = 0; kt < nk; kt += 2) {
;     if (kt + 2 < nk) { GL_LOAD(0, kt + 2) }
;     MMA_TILE(0)
;     LDS_STORE(1, 1)
;     if (VAR != 4) __syncthreads();
;     if (kt + 3 < nk) { GL_LOAD(1, kt + 3) }
;     MMA_TILE(1)
;     if (kt + 2 < nk) { LDS_STORE(0, 0) }
;     if (VAR != 4) __syncthreads();
	ds_write_b128 v17, v[94:97] offset:32768
	v_mfma_f32_16x16x32_f16 v[24:27], v[74:77], v[110:113], v[24:27]
	ds_read_b128 v[74:77], v22 offset:51200
	v_mfma_f32_16x16x32_f16 v[114:117], v[118:121], v[90:93], v[114:117]
	s_waitcnt vmcnt(2)
	ds_write_b128 v18, v[162:165] offset:32768
	v_mfma_f32_16x16x32_f16 v[40:43], v[118:121], v[110:113], v[40:43]
	ds_read_b128 v[118:121], v22 offset:53248
	v_mfma_f32_16x16x32_f16 v[70:73], v[122:125], v[90:93], v[70:73]
	ds_read_b128 v[90:93], v23 offset:16384
	v_mfma_f32_16x16x32_f16 v[48:51], v[122:125], v[110:113], v[48:51]
	ds_read_b128 v[110:113], v23 offset:18432
	s_waitcnt lgkmcnt(1)
	v_mfma_f32_16x16x32_f16 v[36:39], v[62:65], v[90:93], v[36:39]
	ds_read_b128 v[122:125], v22 offset:55296
	s_waitcnt lgkmcnt(1)
	v_mfma_f32_16x16x32_f16 v[66:69], v[62:65], v[110:113], v[66:69]
	s_waitcnt vmcnt(1)
	ds_write_b128 v19, v[166:169] offset:32768
	v_mfma_f32_16x16x32_f16 v[44:47], v[74:77], v[90:93], v[44:47]
	s_waitcnt vmcnt(0)
	ds_write_b128 v20, v[190:193] offset:32768
	v_mfma_f32_16x16x32_f16 v[78:81], v[74:77], v[110:113], v[78:81]
	v_mfma_f32_16x16x32_f16 v[82:85], v[118:121], v[90:93], v[82:85]
	v_mfma_f32_16x16x32_f16 v[86:89], v[118:121], v[110:113], v[86:89]
	s_waitcnt lgkmcnt(2)
	v_mfma_f32_16x16x32_f16 v[28:31], v[122:125], v[90:93], v[28:31]
	ds_read_b128 v[90:93], v23 offset:20480
	v_mfma_f32_16x16x32_f16 v[32:35], v[122:125], v[110:113], v[32:35]
	ds_read_b128 v[110:113], v23 offset:22528
	s_waitcnt lgkmcnt(1)
	v_mfma_f32_16x16x32_f16 v[98:101], v[62:65], v[90:93], v[98:101]
	s_waitcnt lgkmcnt(0)
	v_mfma_f32_16x16x32_f16 v[52:55], v[62:65], v[110:113], v[52:55]
	global_load_dwordx4 v[62:65], v[0:1], off offset:1408
	v_mfma_f32_16x16x32_f16 v[102:105], v[74:77], v[90:93], v[102:105]
	v_mfma_f32_16x16x32_f16 v[24:27], v[74:77], v[110:113], v[24:27]
	v_mfma_f32_16x16x32_f16 v[114:117], v[118:121], v[90:93], v[114:117]
	v_mfma_f32_16x16x32_f16 v[40:43], v[118:121], v[110:113], v[40:43]
	v_mfma_f32_16x16x32_f16 v[70:73], v[122:125], v[90:93], v[70:73]
	global_load_dwordx4 v[90:93], v[2:3], off offset:1408
	global_load_dwordx4 v[126:129], v[4:5], off offset:1408
	global_load_dwordx4 v[130:133], v[14:15], off offset:1408
	global_load_dwordx4 v[74:77], v[10:11], off offset:1408
	global_load_dwordx4 v[138:141], v[12:13], off offset:1408
	global_load_dwordx4 v[142:145], v[8:9], off offset:1408
	global_load_dwordx4 v[154:157], v[6:7], off offset:1408
	s_waitcnt lgkmcnt(0)
	s_barrier
	v_mfma_f32_16x16x32_f16 v[48:51], v[122:125], v[110:113], v[48:51]
	ds_read_b128 v[58:61], v16 offset:32768
	ds_read_b128 v[106:109], v21
	s_waitcnt lgkmcnt(0)
	v_mfma_f32_16x16x32_f16 v[36:39], v[58:61], v[106:109], v[36:39]
	ds_read_b128 v[94:97], v16 offset:34816
	ds_read_b128 v[110:113], v21 offset:2048
	s_waitcnt lgkmcnt(0)
	v_mfma_f32_16x16x32_f16 v[66:69], v[58:61], v[110:113], v[66:69]
	ds_read_b128 v[118:121], v16 offset:36864
	v_mfma_f32_16x16x32_f16 v[44:47], v[94:97], v[106:109], v[44:47]
	ds_read_b128 v[122:125], v16 offset:38912
	v_mfma_f32_16x16x32_f16 v[78:81], v[94:97], v[110:113], v[78:81]
	s_waitcnt vmcnt(7)
	ds_write_b128 v17, v[62:65] offset:16384
	s_waitcnt lgkmcnt(2)
	v_mfma_f32_16x16x32_f16 v[82:85], v[118:121], v[106:109], v[82:85]
	s_waitcnt vmcnt(6)
	ds_write_b128 v18, v[90:93] offset:16384
	v_mfma_f32_16x16x32_f16 v[86:89], v[118:121], v[110:113], v[86:89]
	s_waitcnt vmcnt(5)
	ds_write_b128 v19, v[126:129] offset:16384
	s_waitcnt lgkmcnt(3)
	v_mfma_f32_16x16x32_f16 v[28:31], v[122:125], v[106:109], v[28:31]
	ds_read_b128 v[106:109], v21 offset:4096
	v_mfma_f32_16x16x32_f16 v[32:35], v[122:125], v[110:113], v[32:35]
	ds_read_b128 v[110:113], v21 offset:6144
	s_waitcnt lgkmcnt(1)
	v_mfma_f32_16x16x32_f16 v[98:101], v[58:61], v[106:109], v[98:101]
	s_waitcnt vmcnt(4)
	ds_write_b128 v20, v[130:133] offset:16384
	s_waitcnt lgkmcnt(1)
	v_mfma_f32_16x16x32_f16 v[52:55], v[58:61], v[110:113], v[52:55]
	ds_read_b128 v[58:61], v22 offset:32768
	v_mfma_f32_16x16x32_f16 v[102:105], v[94:97], v[106:109], v[102:105]
	s_waitcnt vmcnt(3)
	ds_write_b128 v17, v[74:77] offset:49152
	v_mfma_f32_16x16x32_f16 v[24:27], v[94:97], v[110:113], v[24:27]
	ds_read_b128 v[94:97], v22 offset:34816
	v_mfma_f32_16x16x32_f16 v[114:117], v[118:121], v[106:109], v[114:117]
	s_waitcnt vmcnt(2)
	ds_write_b128 v18, v[138:141] offset:49152
	v_mfma_f32_16x16x32_f16 v[40:43], v[118:121], v[110:113], v[40:43]
	ds_read_b128 v[118:121], v22 offset:36864
	v_mfma_f32_16x16x32_f16 v[70:73], v[122:125], v[106:109], v[70:73]
	ds_read_b128 v[106:109], v23
	v_mfma_f32_16x16x32_f16 v[48:51], v[122:125], v[110:113], v[48:51]
	ds_read_b128 v[110:113], v23 offset:2048
	s_waitcnt lgkmcnt(1)
	v_mfma_f32_16x16x32_f16 v[36:39], v[58:61], v[106:109], v[36:39]
	ds_read_b128 v[122:125], v22 offset:38912
	s_waitcnt lgkmcnt(1)
	v_mfma_f32_16x16x32_f16 v[66:69], v[58:61], v[110:113], v[66:69]
	s_waitcnt vmcnt(1)
	ds_write_b128 v19, v[142:145] offset:49152
	v_mfma_f32_16x16x32_f16 v[44:47], v[94:97], v[106:109], v[44:47]
	s_waitcnt vmcnt(0)
	ds_write_b128 v20, v[154:157] offset:49152
	v_mfma_f32_16x16x32_f16 v[78:81], v[94:97], v[110:113], v[78:81]
	v_mfma_f32_16x16x32_f16 v[82:85], v[118:121], v[106:109], v[82:85]
	v_mfma_f32_16x16x32_f16 v[86:89], v[118:121], v[110:113], v[86:89]
	s_waitcnt lgkmcnt(2)
	v_mfma_f32_16x16x32_f16 v[28:31], v[122:125], v[106:109], v[28:31]
	ds_read_b128 v[106:109], v23 offset:4096
	v_mfma_f32_16x16x32_f16 v[32:35], v[122:125], v[110:113], v[32:35]
	ds_read_b128 v[110:113], v23 offset:6144
	s_waitcnt lgkmcnt(1)
	v_mfma_f32_16x16x32_f16 v[98:101], v[58:61], v[106:109], v[98:101]
	s_waitcnt lgkmcnt(0)
	v_mfma_f32_16x16x32_f16 v[52:55], v[58:61], v[110:113], v[52:55]
	global_load_dwordx4 v[58:61], v[0:1], off offset:1536
	v_mfma_f32_16x16x32_f16 v[102:105], v[94:97], v[106:109], v[102:105]
	v_mfma_f32_16x16x32_f16 v[24:27], v[94:97], v[110:113], v[24:27]
	v_mfma_f32_16x16x32_f16 v[114:117], v[118:121], v[106:109], v[114:117]
	v_mfma_f32_16x16x32_f16 v[40:43], v[118:121], v[110:113], v[40:43]
	v_mfma_f32_16x16x32_f16 v[70:73], v[122:125], v[106:109], v[70:73]
	global_load_dwordx4 v[106:109], v[2:3], off offset:1536
	global_load_dwordx4 v[134:137], v[4:5], off offset:1536
	global_load_dwordx4 v[158:161], v[14:15], off offset:1536
	global_load_dwordx4 v[94:97], v[10:11], off offset:1536
	global_load_dwordx4 v[162:165], v[12:13], off offset:1536
	global_load_dwordx4 v[166:169], v[8:9], off offset:1536
	global_load_dwordx4 v[190:193], v[6:7], off offset:1536
	s_waitcnt lgkmcnt(0)
	s_barrier
; #define GL_LOAD(s_, kt_) if (VAR != 1) { a##s_##0 = GL_A(0, kt_); a##s_##1 = GL_A(1, kt_); a##s_##2 = GL_A(2, kt_); a##s_##3 = GL_A(3, kt_); b##s_##0 = GL_B(0, kt_); b##s_##1 = GL_B(1, kt_); b##s_##2 = GL_B(2, kt_); b##s_##3 = GL_B(3, kt_); }
; #define LDS_STORE(s_, buf_) if (VAR != 2) { LDS_ST1(sA, 0, buf_, a##s_##0) LDS_ST1(sA, 1, buf_, a##s_##1) LDS_ST1(sA, 2, buf_, a##s_##2) LDS_ST1(sA, 3, buf_, a##s_##3) LDS_ST1(sB, 0, buf_, b##s_##0) LDS_ST1(sB, 1, buf_, b##s_##1) LDS_ST1(sB, 2, buf_, b##s_##2) LDS_ST1(sB, 3, buf_, b##s_##3) }
;     ...
;   GL_LOAD(0, 0)
;   GL_LOAD(1, 1)
;   LDS_STORE(0, 0)
;   if (VAR != 4) __syncthreads();
; #pragma unroll
;   for (int kt = 0; kt < nk; kt += 2) {
;     if (kt + 2 < nk) { GL_LOAD(0, kt + 2) }
;     MMA_TILE(0)
;     LDS_STORE(1, 1)
;     if (VAR != 4) __syncthreads();
;     if (kt + 3 < nk) { GL_LOAD(1, kt + 3) }
;     MMA_TILE(1)
;     if (kt + 2 < nk) { LDS_STORE(0, 0) }
;     if (VAR != 4) __syncthreads();
	v_mfma_f32_16x16x32_f16 v[48:51], v[122:125], v[110:113], v[48:51]
	ds_read_b128 v[62:65], v16 offset:49152
	ds_read_b128 v[90:93], v21 offset:16384
	s_waitcnt lgkmcnt(0)
	v_mfma_f32_16x16x32_f16 v[36:39], v[62:65], v[90:93], v[36:39]
	ds_read_b128 v[74:77], v16 offset:51200
	ds_read_b128 v[110:113], v21 offset:18432
	s_waitcnt lgkmcnt(0)
	v_mfma_f32_16x16x32_f16 v[66:69], v[62:65], v[110:113], v[66:69]
	ds_read_b128 v[118:121], v16 offset:53248
	v_mfma_f32_16x16x32_f16 v[44:47], v[74:77], v[90:93], v[44:47]
	ds_read_b128 v[122:125], v16 offset:55296
	v_mfma_f32_16x16x32_f16 v[78:81], v[74:77], v[110:113], v[78:81]
	s_waitcnt vmcnt(7)
	ds_write_b128 v17, v[58:61]
	s_waitcnt lgkmcnt(2)
	v_mfma_f32_16x16x32_f16 v[82:85], v[118:121], v[90:93], v[82:85]
	s_waitcnt vmcnt(6)
	ds_write_b128 v18, v[106:109]
	v_mfma_f32_16x16x32_f16 v[86:89], v[118:121], v[110:113], v[86:89]
	s_waitcnt vmcnt(5)
	ds_write_b128 v19, v[134:137]
	s_waitcnt lgkmcnt(3)
	v_mfma_f32_16x16x32_f16 v[28:31], v[122:125], v[90:93], v[28:31]
	ds_read_b128 v[90:93], v21 offset:20480
	v_mfma_f32_16x16x32_f16 v[32:35], v[122:125], v[110:113], v[32:35]
	ds_read_b128 v[110:113], v21 offset:22528
	s_waitcnt lgkmcnt(1)
	v_mfma_f32_16x16x32_f16 v[98:101], v[62:65], v[90:93], v[98:101]
	s_waitcnt vmcnt(4)
	ds_write_b128 v20, v[158:161]
	s_waitcnt lgkmcnt(1)
	v_mfma_f32_16x16x32_f16 v[52:55], v[62:65], v[110:113], v[52:55]
	ds_read_b128 v[62:65], v22 offset:49152
	v_mfma_f32_16x16x32_f16 v[102:105], v[74:77], v[90:93], v[102:105]
	s_waitcnt vmcnt(3)
	ds_write_b128 v17, v[94:97] offset:32768
	v_mfma_f32_16x16x32_f16 v[24:27], v[74:77], v[110:113], v[24:27]
	ds_read_b128 v[74:77], v22 offset:51200
	v_mfma_f32_16x16x32_f16 v[114:117], v[118:121], v[90:93], v[114:117]
	s_waitcnt vmcnt(2)
	ds_write_b128 v18, v[162:165] offset:32768
	v_mfma_f32_16x16x32_f16 v[40:43], v[118:121], v[110:113], v[40:43]
	ds_read_b128 v[118:121], v22 offset:53248
	v_mfma_f32_16x16x32_f16 v[70:73], v[122:125], v[90:93], v[70:73]
	ds_read_b128 v[90:93], v23 offset:16384
	v_mfma_f32_16x16x32_f16 v[48:51], v[122:125], v[110:113], v[48:51]
	ds_read_b128 v[110:113], v23 offset:18432
	s_waitcnt lgkmcnt(1)
	v_mfma_f32_16x16x32_f16 v[36:39], v[62:65], v[90:93], v[36:39]
	ds_read_b128 v[122:125], v22 offset:55296
	s_waitcnt lgkmcnt(1)
	v_mfma_f32_16x16x32_f16 v[66:69], v[62:65], v[110:113], v[66:69]
	s_waitcnt vmcnt(1)
	ds_write_b128 v19, v[166:169] offset:32768
	v_mfma_f32_16x16x32_f16 v[44:47], v[74:77], v[90:93], v[44:47]
	s_waitcnt vmcnt(0)
	ds_write_b128 v20, v[190:193] offset:32768
	v_mfma_f32_16x16x32_f16 v[78:81], v[74:77], v[110:113], v[78:81]
	v_mfma_f32_16x16x32_f16 v[82:85], v[118:121], v[90:93], v[82:85]
	v_mfma_f32_16x16x32_f16 v[86:89], v[118:121], v[110:113], v[86:89]
	s_waitcnt lgkmcnt(2)
	v_mfma_f32_16x16x32_f16 v[28:31], v[122:125], v[90:93], v[28:31]
	ds_read_b128 v[90:93], v23 offset:20480
	v_mfma_f32_16x16x32_f16 v[32:35], v[122:125], v[110:113], v[32:35]
	ds_read_b128 v[110:113], v23 offset:22528
	s_waitcnt lgkmcnt(1)
	v_mfma_f32_16x16x32_f16 v[98:101], v[62:65], v[90:93], v[98:101]
	s_waitcnt lgkmcnt(0)
	v_mfma_f32_16x16x32_f16 v[52:55], v[62:65], v[110:113], v[52:55]
	global_load_dwordx4 v[62:65], v[0:1], off offset:1664
	v_mfma_f32_16x16x32_f16 v[102:105], v[74:77], v[90:93], v[102:105]
	v_mfma_f32_16x16x32_f16 v[24:27], v[74:77], v[110:113], v[24:27]
	v_mfma_f32_16x16x32_f16 v[114:117], v[118:121], v[90:93], v[114:117]
	v_mfma_f32_16x16x32_f16 v[40:43], v[118:121], v[110:113], v[40:43]
	v_mfma_f32_16x16x32_f16 v[70:73], v[122:125], v[90:93], v[70:73]
	global_load_dwordx4 v[90:93], v[2:3], off offset:1664
	global_load_dwordx4 v[126:129], v[4:5], off offset:1664
	global_load_dwordx4 v[130:133], v[14:15], off offset:1664
	global_load_dwordx4 v[74:77], v[10:11], off offset:1664
	global_load_dwordx4 v[138:141], v[12:13], off offset:1664
	global_load_dwordx4 v[142:145], v[8:9], off offset:1664
	global_load_dwordx4 v[154:157], v[6:7], off offset:1664
	s_waitcnt lgkmcnt(0)
	s_barrier
	v_mfma_f32_16x16x32_f16 v[48:51], v[122:125], v[110:113], v[48:51]
	ds_read_b128 v[58:61], v16 offset:32768
	ds_read_b128 v[106:109], v21
	s_waitcnt lgkmcnt(0)
	v_mfma_f32_16x16x32_f16 v[36:39], v[58:61], v[106:109], v[36:39]
	ds_read_b128 v[94:97], v16 offset:34816
	ds_read_b128 v[110:113], v21 offset:2048
	s_waitcnt lgkmcnt(0)
	v_mfma_f32_16x16x32_f16 v[66:69], v[58:61], v[110:113], v[66:69]
	ds_read_b128 v[118:121], v16 offset:36864
	v_mfma_f32_16x16x32_f16 v[44:47], v[94:97], v[106:109], v[44:47]
	ds_read_b128 v[122:125], v16 offset:38912
	v_mfma_f32_16x16x32_f16 v[78:81], v[94:97], v[110:113], v[78:81]
	s_waitcnt vmcnt(7)
	ds_write_b128 v17, v[62:65] offset:16384
	s_waitcnt lgkmcnt(2)
	v_mfma_f32_16x16x32_f16 v[82:85], v[118:121], v[106:109], v[82:85]
	s_waitcnt vmcnt(6)
	ds_write_b128 v18, v[90:93] offset:16384
	v_mfma_f32_16x16x32_f16 v[86:89], v[118:121], v[110:113], v[86:89]
	s_waitcnt vmcnt(5)
	ds_write_b128 v19, v[126:129] offset:16384
	s_waitcnt lgkmcnt(3)
	v_mfma_f32_16x16x32_f16 v[28:31], v[122:125], v[106:109], v[28:31]
	ds_read_b128 v[106:109], v21 offset:4096
	v_mfma_f32_16x16x32_f16 v[32:35], v[122:125], v[110:113], v[32:35]
	ds_read_b128 v[110:113], v21 offset:6144
	s_waitcnt lgkmcnt(1)
	v_mfma_f32_16x16x32_f16 v[98:101], v[58:61], v[106:109], v[98:101]
	s_waitcnt vmcnt(4)
	ds_write_b128 v20, v[130:133] offset:16384
	s_waitcnt lgkmcnt(1)
	v_mfma_f32_16x16x32_f16 v[52:55], v[58:61], v[110:113], v[52:55]
	ds_read_b128 v[58:61], v22 offset:32768
	v_mfma_f32_16x16x32_f16 v[102:105], v[94:97], v[106:109], v[102:105]
	s_waitcnt vmcnt(3)
; #define GL_LOAD(s_, kt_) if (VAR != 1) { a##s_##0 = GL_A(0, kt_); a##s_##1 = GL_A(1, kt_); a##s_##2 = GL_A(2, kt_); a##s_##3 = GL_A(3, kt_); b##s_##0 = GL_B(0, kt_); b##s_##1 = GL_B(1, kt_); b##s_##2 = GL_B(2, kt_); b##s_##3 = GL_B(3, kt_); }
; #define LDS_STORE(s_, buf_) if (VAR != 2) { LDS_ST1(sA, 0, buf_, a##s_##0) LDS_ST1(sA, 1, buf_, a##s_##1) LDS_ST1(sA, 2, buf_, a##s_##2) LDS_ST1(sA, 3, buf_, a##s_##3) LDS_ST1(sB, 0, buf_, b##s_##0) LDS_ST1(sB, 1, buf_, b##s_##1) LDS_ST1(sB, 2, buf_, b##s_##2) LDS_ST1(sB, 3, buf_, b##s_##3) }
;     ...
;   GL_LOAD(0, 0)
;   GL_LOAD(1, 1)
;   LDS_STORE(0, 0)
;   if (VAR != 4) __syncthreads();
; #pragma unroll
;   for (int kt = 0; kt < nk; kt += 2) {
;     if (kt + 2 < nk) { GL_LOAD(0, kt + 2) }
;     MMA_TILE(0)
;     LDS_STORE(1, 1)
;     if (VAR != 4) __syncthreads();
;     if (kt + 3 < nk) { GL_LOAD(1, kt + 3) }
;     MMA_TILE(1)
;     if (kt + 2 < nk) { LDS_STORE(0, 0) }
;     if (VAR != 4) __syncthreads();
	ds_write_b128 v17, v[74:77] offset:49152
	v_mfma_f32_16x16x32_f16 v[24:27], v[94:97], v[110:113], v[24:27]
	ds_read_b128 v[94:97], v22 offset:34816
	v_mfma_f32_16x16x32_f16 v[114:117], v[118:121], v[106:109], v[114:117]
	s_waitcnt vmcnt(2)
	ds_write_b128 v18, v[138:141] offset:49152
	v_mfma_f32_16x16x32_f16 v[40:43], v[118:121], v[110:113], v[40:43]
	ds_read_b128 v[118:121], v22 offset:36864
	v_mfma_f32_16x16x32_f16 v[70:73], v[122:125], v[106:109], v[70:73]
	ds_read_b128 v[106:109], v23
	v_mfma_f32_16x16x32_f16 v[48:51], v[122:125], v[110:113], v[48:51]
	ds_read_b128 v[110:113], v23 offset:2048
	s_waitcnt lgkmcnt(1)
	v_mfma_f32_16x16x32_f16 v[36:39], v[58:61], v[106:109], v[36:39]
	ds_read_b128 v[122:125], v22 offset:38912
	s_waitcnt lgkmcnt(1)
	v_mfma_f32_16x16x32_f16 v[66:69], v[58:61], v[110:113], v[66:69]
	s_waitcnt vmcnt(1)
	ds_write_b128 v19, v[142:145] offset:49152
	v_mfma_f32_16x16x32_f16 v[44:47], v[94:97], v[106:109], v[44:47]
	s_waitcnt vmcnt(0)
	ds_write_b128 v20, v[154:157] offset:49152
	v_mfma_f32_16x16x32_f16 v[78:81], v[94:97], v[110:113], v[78:81]
	v_mfma_f32_16x16x32_f16 v[82:85], v[118:121], v[106:109], v[82:85]
	v_mfma_f32_16x16x32_f16 v[86:89], v[118:121], v[110:113], v[86:89]
	s_waitcnt lgkmcnt(2)
	v_mfma_f32_16x16x32_f16 v[28:31], v[122:125], v[106:109], v[28:31]
	ds_read_b128 v[106:109], v23 offset:4096
	v_mfma_f32_16x16x32_f16 v[32:35], v[122:125], v[110:113], v[32:35]
	ds_read_b128 v[110:113], v23 offset:6144
	s_waitcnt lgkmcnt(1)
	v_mfma_f32_16x16x32_f16 v[98:101], v[58:61], v[106:109], v[98:101]
	s_waitcnt lgkmcnt(0)
	v_mfma_f32_16x16x32_f16 v[52:55], v[58:61], v[110:113], v[52:55]
	global_load_dwordx4 v[58:61], v[0:1], off offset:1792
	v_mfma_f32_16x16x32_f16 v[102:105], v[94:97], v[106:109], v[102:105]
	v_mfma_f32_16x16x32_f16 v[24:27], v[94:97], v[110:113], v[24:27]
	v_mfma_f32_16x16x32_f16 v[114:117], v[118:121], v[106:109], v[114:117]
	v_mfma_f32_16x16x32_f16 v[40:43], v[118:121], v[110:113], v[40:43]
	v_mfma_f32_16x16x32_f16 v[70:73], v[122:125], v[106:109], v[70:73]
	global_load_dwordx4 v[106:109], v[2:3], off offset:1792
	global_load_dwordx4 v[134:137], v[4:5], off offset:1792
	global_load_dwordx4 v[158:161], v[14:15], off offset:1792
	global_load_dwordx4 v[94:97], v[10:11], off offset:1792
	global_load_dwordx4 v[162:165], v[12:13], off offset:1792
	global_load_dwordx4 v[166:169], v[8:9], off offset:1792
	global_load_dwordx4 v[190:193], v[6:7], off offset:1792
	s_waitcnt lgkmcnt(0)
	s_barrier
	v_mfma_f32_16x16x32_f16 v[48:51], v[122:125], v[110:113], v[48:51]
	ds_read_b128 v[62:65], v16 offset:49152
	ds_read_b128 v[90:93], v21 offset:16384
	s_waitcnt lgkmcnt(0)
	v_mfma_f32_16x16x32_f16 v[36:39], v[62:65], v[90:93], v[36:39]
	ds_read_b128 v[74:77], v16 offset:51200
	ds_read_b128 v[110:113], v21 offset:18432
	s_waitcnt lgkmcnt(0)
	v_mfma_f32_16x16x32_f16 v[66:69], v[62:65], v[110:113], v[66:69]
	ds_read_b128 v[118:121], v16 offset:53248
	v_mfma_f32_16x16x32_f16 v[44:47], v[74:77], v[90:93], v[44:47]
	ds_read_b128 v[122:125], v16 offset:55296
	v_mfma_f32_16x16x32_f16 v[78:81], v[74:77], v[110:113], v[78:81]
	s_waitcnt vmcnt(7)
	ds_write_b128 v17, v[58:61]
	s_waitcnt lgkmcnt(2)
	v_mfma_f32_16x16x32_f16 v[82:85], v[118:121], v[90:93], v[82:85]
	s_waitcnt vmcnt(6)
	ds_write_b128 v18, v[106:109]
	v_mfma_f32_16x16x32_f16 v[86:89], v[118:121], v[110:113], v[86:89]
	s_waitcnt vmcnt(5)
	ds_write_b128 v19, v[134:137]
	s_waitcnt lgkmcnt(3)
	v_mfma_f32_16x16x32_f16 v[28:31], v[122:125], v[90:93], v[28:31]
	ds_read_b128 v[90:93], v21 offset:20480
	v_mfma_f32_16x16x32_f16 v[32:35], v[122:125], v[110:113], v[32:35]
	ds_read_b128 v[110:113], v21 offset:22528
	s_waitcnt lgkmcnt(1)
	v_mfma_f32_16x16x32_f16 v[98:101], v[62:65], v[90:93], v[98:101]
	s_waitcnt vmcnt(4)
	ds_write_b128 v20, v[158:161]
	s_waitcnt lgkmcnt(1)
	v_mfma_f32_16x16x32_f16 v[52:55], v[62:65], v[110:113], v[52:55]
	ds_read_b128 v[62:65], v22 offset:49152
	v_mfma_f32_16x16x32_f16 v[102:105], v[74:77], v[90:93], v[102:105]
	s_waitcnt vmcnt(3)
	ds_write_b128 v17, v[94:97] offset:32768
	v_mfma_f32_16x16x32_f16 v[24:27], v[74:77], v[110:113], v[24:27]
	ds_read_b128 v[74:77], v22 offset:51200
	v_mfma_f32_16x16x32_f16 v[114:117], v[118:121], v[90:93], v[114:117]
	s_waitcnt vmcnt(2)
	ds_write_b128 v18, v[162:165] offset:32768
	v_mfma_f32_16x16x32_f16 v[40:43], v[118:121], v[110:113], v[40:43]
	ds_read_b128 v[118:121], v22 offset:53248
	v_mfma_f32_16x16x32_f16 v[70:73], v[122:125], v[90:93], v[70:73]
	ds_read_b128 v[90:93], v23 offset:16384
	v_mfma_f32_16x16x32_f16 v[48:51], v[122:125], v[110:113], v[48:51]
	ds_read_b128 v[110:113], v23 offset:18432
	s_waitcnt lgkmcnt(1)
	v_mfma_f32_16x16x32_f16 v[36:39], v[62:65], v[90:93], v[36:39]
	ds_read_b128 v[122:125], v22 offset:55296
	s_waitcnt lgkmcnt(1)
	v_mfma_f32_16x16x32_f16 v[66:69], v[62:65], v[110:113], v[66:69]
	s_waitcnt vmcnt(1)
	ds_write_b128 v19, v[166:169] offset:32768
	v_mfma_f32_16x16x32_f16 v[44:47], v[74:77], v[90:93], v[44:47]
	s_waitcnt vmcnt(0)
	ds_write_b128 v20, v[190:193] offset:32768
	v_mfma_f32_16x16x32_f16 v[78:81], v[74:77], v[110:113], v[78:81]
	v_mfma_f32_16x16x32_f16 v[82:85], v[118:121], v[90:93], v[82:85]
	v_mfma_f32_16x16x32_f16 v[86:89], v[118:121], v[110:113], v[86:89]
	s_waitcnt lgkmcnt(2)
	v_mfma_f32_16x16x32_f16 v[28:31], v[122:125], v[90:93], v[28:31]
	ds_read_b128 v[90:93], v23 offset:20480
	v_mfma_f32_16x16x32_f16 v[32:35], v[122:125], v[110:113], v[32:35]
	ds_read_b128 v[110:113], v23 offset:22528
	s_waitcnt lgkmcnt(1)
	v_mfma_f32_16x16x32_f16 v[98:101], v[62:65], v[90:93], v[98:101]
	s_waitcnt lgkmcnt(0)
	v_mfma_f32_16x16x32_f16 v[52:55], v[62:65], v[110:113], v[52:55]
	global_load_dwordx4 v[62:65], v[0:1], off offset:1920
	v_mfma_f32_16x16x32_f16 v[102:105], v[74:77], v[90:93], v[102:105]
	v_mfma_f32_16x16x32_f16 v[24:27], v[74:77], v[110:113], v[24:27]
	v_mfma_f32_16x16x32_f16 v[114:117], v[118:121], v[90:93], v[114:117]
	v_mfma_f32_16x16x32_f16 v[40:43], v[118:121], v[110:113], v[40:43]
	v_mfma_f32_16x16x32_f16 v[70:73], v[122:125], v[90:93], v[70:73]
	global_load_dwordx4 v[90:93], v[2:3], off offset:1920
	global_load_dwordx4 v[126:129], v[4:5], off offset:1920
	global_load_dwordx4 v[130:133], v[14:15], off offset:1920
	global_load_dwordx4 v[74:77], v[10:11], off offset:1920
	global_load_dwordx4 v[138:141], v[12:13], off offset:1920
	global_load_dwordx4 v[142:145], v[8:9], off offset:1920
	global_load_dwordx4 v[154:157], v[6:7], off offset:1920
	s_waitcnt lgkmcnt(0)
	s_barrier
; #define GL_LOAD(s_, kt_) if (VAR != 1) { a##s_##0 = GL_A(0, kt_); a##s_##1 = GL_A(1, kt_); a##s_##2 = GL_A(2, kt_); a##s_##3 = GL_A(3, kt_); b##s_##0 = GL_B(0, kt_); b##s_##1 = GL_B(1, kt_); b##s_##2 = GL_B(2, kt_); b##s_##3 = GL_B(3, kt_); }
; #define LDS_STORE(s_, buf_) if (VAR != 2) { LDS_ST1(sA, 0, buf_, a##s_##0) LDS_ST1(sA, 1, buf_, a##s_##1) LDS_ST1(sA, 2, buf_, a##s_##2) LDS_ST1(sA, 3, buf_, a##s_##3) LDS_ST1(sB, 0, buf_, b##s_##0) LDS_ST1(sB, 1, buf_, b##s_##1) LDS_ST1(sB, 2, buf_, b##s_##2) LDS_ST1(sB, 3, buf_, b##s_##3) }
;     ...
;   GL_LOAD(0, 0)
;   GL_LOAD(1, 1)
;   LDS_STORE(0, 0)
;   if (VAR != 4) __syncthreads();
; #pragma unroll
;   for (int kt = 0; kt < nk; kt += 2) {
;     if (kt + 2 < nk) { GL_LOAD(0, kt + 2) }
;     MMA_TILE(0)
;     LDS_STORE(1, 1)
;     if (VAR != 4) __syncthreads();
;     if (kt + 3 < nk) { GL_LOAD(1, kt + 3) }
;     MMA_TILE(1)
;     if (kt + 2 < nk) { LDS_STORE(0, 0) }
;     if (VAR != 4) __syncthreads();
	v_mfma_f32_16x16x32_f16 v[48:51], v[122:125], v[110:113], v[48:51]
	ds_read_b128 v[58:61], v16 offset:32768
	ds_read_b128 v[106:109], v21
	s_waitcnt lgkmcnt(0)
	v_mfma_f32_16x16x32_f16 v[36:39], v[58:61], v[106:109], v[36:39]
	ds_read_b128 v[94:97], v16 offset:34816
	ds_read_b128 v[110:113], v21 offset:2048
	s_waitcnt lgkmcnt(0)
	v_mfma_f32_16x16x32_f16 v[66:69], v[58:61], v[110:113], v[66:69]
	ds_read_b128 v[118:121], v16 offset:36864
	v_mfma_f32_16x16x32_f16 v[44:47], v[94:97], v[106:109], v[44:47]
	ds_read_b128 v[122:125], v16 offset:38912
	v_mfma_f32_16x16x32_f16 v[78:81], v[94:97], v[110:113], v[78:81]
	s_waitcnt vmcnt(7)
	ds_write_b128 v17, v[62:65] offset:16384
	s_waitcnt lgkmcnt(2)
	v_mfma_f32_16x16x32_f16 v[82:85], v[118:121], v[106:109], v[82:85]
	s_waitcnt vmcnt(6)
	ds_write_b128 v18, v[90:93] offset:16384
	v_mfma_f32_16x16x32_f16 v[86:89], v[118:121], v[110:113], v[86:89]
	s_waitcnt vmcnt(5)
	ds_write_b128 v19, v[126:129] offset:16384
	s_waitcnt lgkmcnt(3)
	v_mfma_f32_16x16x32_f16 v[28:31], v[122:125], v[106:109], v[28:31]
	ds_read_b128 v[106:109], v21 offset:4096
	v_mfma_f32_16x16x32_f16 v[32:35], v[122:125], v[110:113], v[32:35]
	ds_read_b128 v[110:113], v21 offset:6144
	s_waitcnt lgkmcnt(1)
	v_mfma_f32_16x16x32_f16 v[98:101], v[58:61], v[106:109], v[98:101]
	s_waitcnt vmcnt(4)
	ds_write_b128 v20, v[130:133] offset:16384
	s_waitcnt lgkmcnt(1)
	v_mfma_f32_16x16x32_f16 v[52:55], v[58:61], v[110:113], v[52:55]
	ds_read_b128 v[58:61], v22 offset:32768
	v_mfma_f32_16x16x32_f16 v[102:105], v[94:97], v[106:109], v[102:105]
	s_waitcnt vmcnt(3)
	ds_write_b128 v17, v[74:77] offset:49152
	v_mfma_f32_16x16x32_f16 v[24:27], v[94:97], v[110:113], v[24:27]
	ds_read_b128 v[94:97], v22 offset:34816
	v_mfma_f32_16x16x32_f16 v[114:117], v[118:121], v[106:109], v[114:117]
	s_waitcnt vmcnt(2)
	ds_write_b128 v18, v[138:141] offset:49152
	v_mfma_f32_16x16x32_f16 v[40:43], v[118:121], v[110:113], v[40:43]
	ds_read_b128 v[118:121], v22 offset:36864
	v_mfma_f32_16x16x32_f16 v[70:73], v[122:125], v[106:109], v[70:73]
	ds_read_b128 v[106:109], v23
	v_mfma_f32_16x16x32_f16 v[48:51], v[122:125], v[110:113], v[48:51]
	ds_read_b128 v[110:113], v23 offset:2048
	s_waitcnt lgkmcnt(1)
	v_mfma_f32_16x16x32_f16 v[36:39], v[58:61], v[106:109], v[36:39]
	ds_read_b128 v[122:125], v22 offset:38912
	s_waitcnt lgkmcnt(1)
	v_mfma_f32_16x16x32_f16 v[66:69], v[58:61], v[110:113], v[66:69]
	s_waitcnt vmcnt(1)
	ds_write_b128 v19, v[142:145] offset:49152
	v_mfma_f32_16x16x32_f16 v[44:47], v[94:97], v[106:109], v[44:47]
	s_waitcnt vmcnt(0)
	ds_write_b128 v20, v[154:157] offset:49152
	v_mfma_f32_16x16x32_f16 v[78:81], v[94:97], v[110:113], v[78:81]
	v_mfma_f32_16x16x32_f16 v[82:85], v[118:121], v[106:109], v[82:85]
	v_mfma_f32_16x16x32_f16 v[86:89], v[118:121], v[110:113], v[86:89]
	s_waitcnt lgkmcnt(2)
	v_mfma_f32_16x16x32_f16 v[28:31], v[122:125], v[106:109], v[28:31]
	ds_read_b128 v[106:109], v23 offset:4096
	v_mfma_f32_16x16x32_f16 v[32:35], v[122:125], v[110:113], v[32:35]
	ds_read_b128 v[110:113], v23 offset:6144
	s_waitcnt lgkmcnt(1)
	v_mfma_f32_16x16x32_f16 v[98:101], v[58:61], v[106:109], v[98:101]
	s_waitcnt lgkmcnt(0)
	v_mfma_f32_16x16x32_f16 v[52:55], v[58:61], v[110:113], v[52:55]
	global_load_dwordx4 v[58:61], v[0:1], off offset:2048
	v_mfma_f32_16x16x32_f16 v[102:105], v[94:97], v[106:109], v[102:105]
	v_mfma_f32_16x16x32_f16 v[24:27], v[94:97], v[110:113], v[24:27]
	v_mfma_f32_16x16x32_f16 v[114:117], v[118:121], v[106:109], v[114:117]
	v_mfma_f32_16x16x32_f16 v[40:43], v[118:121], v[110:113], v[40:43]
	v_mfma_f32_16x16x32_f16 v[70:73], v[122:125], v[106:109], v[70:73]
	global_load_dwordx4 v[106:109], v[2:3], off offset:2048
	global_load_dwordx4 v[134:137], v[4:5], off offset:2048
	global_load_dwordx4 v[158:161], v[14:15], off offset:2048
	global_load_dwordx4 v[94:97], v[10:11], off offset:2048
	global_load_dwordx4 v[162:165], v[12:13], off offset:2048
	global_load_dwordx4 v[166:169], v[8:9], off offset:2048
	global_load_dwordx4 v[190:193], v[6:7], off offset:2048
	s_waitcnt lgkmcnt(0)
	s_barrier
	v_mfma_f32_16x16x32_f16 v[48:51], v[122:125], v[110:113], v[48:51]
	ds_read_b128 v[62:65], v16 offset:49152
	ds_read_b128 v[90:93], v21 offset:16384
	s_waitcnt lgkmcnt(0)
	v_mfma_f32_16x16x32_f16 v[36:39], v[62:65], v[90:93], v[36:39]
	ds_read_b128 v[74:77], v16 offset:51200
	ds_read_b128 v[110:113], v21 offset:18432
	s_waitcnt lgkmcnt(0)
	v_mfma_f32_16x16x32_f16 v[66:69], v[62:65], v[110:113], v[66:69]
	ds_read_b128 v[118:121], v16 offset:53248
	v_mfma_f32_16x16x32_f16 v[44:47], v[74:77], v[90:93], v[44:47]
	ds_read_b128 v[122:125], v16 offset:55296
	v_mfma_f32_16x16x32_f16 v[78:81], v[74:77], v[110:113], v[78:81]
	s_waitcnt vmcnt(7)
	ds_write_b128 v17, v[58:61]
	s_waitcnt lgkmcnt(2)
	v_mfma_f32_16x16x32_f16 v[82:85], v[118:121], v[90:93], v[82:85]
	s_waitcnt vmcnt(6)
	ds_write_b128 v18, v[106:109]
	v_mfma_f32_16x16x32_f16 v[86:89], v[118:121], v[110:113], v[86:89]
	s_waitcnt vmcnt(5)
	ds_write_b128 v19, v[134:137]
	s_waitcnt lgkmcnt(3)
	v_mfma_f32_16x16x32_f16 v[28:31], v[122:125], v[90:93], v[28:31]
	ds_read_b128 v[90:93], v21 offset:20480
	v_mfma_f32_16x16x32_f16 v[32:35], v[122:125], v[110:113], v[32:35]
	ds_read_b128 v[110:113], v21 offset:22528
	s_waitcnt lgkmcnt(1)
	v_mfma_f32_16x16x32_f16 v[98:101], v[62:65], v[90:93], v[98:101]
	s_waitcnt vmcnt(4)
	ds_write_b128 v20, v[158:161]
	s_waitcnt lgkmcnt(1)
	v_mfma_f32_16x16x32_f16 v[52:55], v[62:65], v[110:113], v[52:55]
	ds_read_b128 v[62:65], v22 offset:49152
	v_mfma_f32_16x16x32_f16 v[102:105], v[74:77], v[90:93], v[102:105]
	s_waitcnt vmcnt(3)
; #define GL_LOAD(s_, kt_) if (VAR != 1) { a##s_##0 = GL_A(0, kt_); a##s_##1 = GL_A(1, kt_); a##s_##2 = GL_A(2, kt_); a##s_##3 = GL_A(3, kt_); b##s_##0 = GL_B(0, kt_); b##s_##1 = GL_B(1, kt_); b##s_##2 = GL_B(2, kt_); b##s_##3 = GL_B(3, kt_); }
; #define LDS_STORE(s_, buf_) if (VAR != 2) { LDS_ST1(sA, 0, buf_, a##s_##0) LDS_ST1(sA, 1, buf_, a##s_##1) LDS_ST1(sA, 2, buf_, a##s_##2) LDS_ST1(sA, 3, buf_, a##s_##3) LDS_ST1(sB, 0, buf_, b##s_##0) LDS_ST1(sB, 1, buf_, b##s_##1) LDS_ST1(sB, 2, buf_, b##s_##2) LDS_ST1(sB, 3, buf_, b##s_##3) }
;     ...
;   GL_LOAD(0, 0)
;   GL_LOAD(1, 1)
;   LDS_STORE(0, 0)
;   if (VAR != 4) __syncthreads();
; #pragma unroll
;   for (int kt = 0; kt < nk; kt += 2) {
;     if (kt + 2 < nk) { GL_LOAD(0, kt + 2) }
;     MMA_TILE(0)
;     LDS_STORE(1, 1)
;     if (VAR != 4) __syncthreads();
;     if (kt + 3 < nk) { GL_LOAD(1, kt + 3) }
;     MMA_TILE(1)
;     if (kt + 2 < nk) { LDS_STORE(0, 0) }
;     if (VAR != 4) __syncthreads();
	ds_write_b128 v17, v[94:97] offset:32768
	v_mfma_f32_16x16x32_f16 v[24:27], v[74:77], v[110:113], v[24:27]
	ds_read_b128 v[74:77], v22 offset:51200
	v_mfma_f32_16x16x32_f16 v[114:117], v[118:121], v[90:93], v[114:117]
	s_waitcnt vmcnt(2)
	ds_write_b128 v18, v[162:165] offset:32768
	v_mfma_f32_16x16x32_f16 v[40:43], v[118:121], v[110:113], v[40:43]
	ds_read_b128 v[118:121], v22 offset:53248
	v_mfma_f32_16x16x32_f16 v[70:73], v[122:125], v[90:93], v[70:73]
	ds_read_b128 v[90:93], v23 offset:16384
	v_mfma_f32_16x16x32_f16 v[48:51], v[122:125], v[110:113], v[48:51]
	ds_read_b128 v[110:113], v23 offset:18432
	s_waitcnt lgkmcnt(1)
	v_mfma_f32_16x16x32_f16 v[36:39], v[62:65], v[90:93], v[36:39]
	ds_read_b128 v[122:125], v22 offset:55296
	s_waitcnt lgkmcnt(1)
	v_mfma_f32_16x16x32_f16 v[66:69], v[62:65], v[110:113], v[66:69]
	s_waitcnt vmcnt(1)
	ds_write_b128 v19, v[166:169] offset:32768
	v_mfma_f32_16x16x32_f16 v[44:47], v[74:77], v[90:93], v[44:47]
	s_waitcnt vmcnt(0)
	ds_write_b128 v20, v[190:193] offset:32768
	v_mfma_f32_16x16x32_f16 v[78:81], v[74:77], v[110:113], v[78:81]
	v_mfma_f32_16x16x32_f16 v[82:85], v[118:121], v[90:93], v[82:85]
	v_mfma_f32_16x16x32_f16 v[86:89], v[118:121], v[110:113], v[86:89]
	s_waitcnt lgkmcnt(2)
	v_mfma_f32_16x16x32_f16 v[28:31], v[122:125], v[90:93], v[28:31]
	ds_read_b128 v[90:93], v23 offset:20480
	v_mfma_f32_16x16x32_f16 v[32:35], v[122:125], v[110:113], v[32:35]
	ds_read_b128 v[110:113], v23 offset:22528
	s_waitcnt lgkmcnt(1)
	v_mfma_f32_16x16x32_f16 v[98:101], v[62:65], v[90:93], v[98:101]
	s_waitcnt lgkmcnt(0)
	v_mfma_f32_16x16x32_f16 v[52:55], v[62:65], v[110:113], v[52:55]
	global_load_dwordx4 v[62:65], v[0:1], off offset:2176
	v_mfma_f32_16x16x32_f16 v[102:105], v[74:77], v[90:93], v[102:105]
	v_mfma_f32_16x16x32_f16 v[24:27], v[74:77], v[110:113], v[24:27]
	v_mfma_f32_16x16x32_f16 v[114:117], v[118:121], v[90:93], v[114:117]
	v_mfma_f32_16x16x32_f16 v[40:43], v[118:121], v[110:113], v[40:43]
	v_mfma_f32_16x16x32_f16 v[70:73], v[122:125], v[90:93], v[70:73]
	global_load_dwordx4 v[90:93], v[2:3], off offset:2176
	global_load_dwordx4 v[126:129], v[4:5], off offset:2176
	global_load_dwordx4 v[130:133], v[14:15], off offset:2176
	global_load_dwordx4 v[74:77], v[10:11], off offset:2176
	global_load_dwordx4 v[138:141], v[12:13], off offset:2176
	global_load_dwordx4 v[142:145], v[8:9], off offset:2176
	global_load_dwordx4 v[154:157], v[6:7], off offset:2176
	s_waitcnt lgkmcnt(0)
	s_barrier
	v_mfma_f32_16x16x32_f16 v[48:51], v[122:125], v[110:113], v[48:51]
	ds_read_b128 v[58:61], v16 offset:32768
	ds_read_b128 v[106:109], v21
	s_waitcnt lgkmcnt(0)
	v_mfma_f32_16x16x32_f16 v[36:39], v[58:61], v[106:109], v[36:39]
	ds_read_b128 v[94:97], v16 offset:34816
	ds_read_b128 v[110:113], v21 offset:2048
	s_waitcnt lgkmcnt(0)
	v_mfma_f32_16x16x32_f16 v[66:69], v[58:61], v[110:113], v[66:69]
	ds_read_b128 v[118:121], v16 offset:36864
	v_mfma_f32_16x16x32_f16 v[44:47], v[94:97], v[106:109], v[44:47]
	ds_read_b128 v[122:125], v16 offset:38912
	v_mfma_f32_16x16x32_f16 v[78:81], v[94:97], v[110:113], v[78:81]
	s_waitcnt vmcnt(7)
	ds_write_b128 v17, v[62:65] offset:16384
	s_waitcnt lgkmcnt(2)
	v_mfma_f32_16x16x32_f16 v[82:85], v[118:121], v[106:109], v[82:85]
	s_waitcnt vmcnt(6)
	ds_write_b128 v18, v[90:93] offset:16384
	v_mfma_f32_16x16x32_f16 v[86:89], v[118:121], v[110:113], v[86:89]
	s_waitcnt vmcnt(5)
	ds_write_b128 v19, v[126:129] offset:16384
	s_waitcnt lgkmcnt(3)
	v_mfma_f32_16x16x32_f16 v[28:31], v[122:125], v[106:109], v[28:31]
	ds_read_b128 v[106:109], v21 offset:4096
	v_mfma_f32_16x16x32_f16 v[32:35], v[122:125], v[110:113], v[32:35]
	ds_read_b128 v[110:113], v21 offset:6144
	s_waitcnt lgkmcnt(1)
	v_mfma_f32_16x16x32_f16 v[98:101], v[58:61], v[106:109], v[98:101]
	s_waitcnt vmcnt(4)
	ds_write_b128 v20, v[130:133] offset:16384
	s_waitcnt lgkmcnt(1)
	v_mfma_f32_16x16x32_f16 v[52:55], v[58:61], v[110:113], v[52:55]
	ds_read_b128 v[58:61], v22 offset:32768
	v_mfma_f32_16x16x32_f16 v[102:105], v[94:97], v[106:109], v[102:105]
	s_waitcnt vmcnt(3)
	ds_write_b128 v17, v[74:77] offset:49152
	v_mfma_f32_16x16x32_f16 v[24:27], v[94:97], v[110:113], v[24:27]
	ds_read_b128 v[94:97], v22 offset:34816
	v_mfma_f32_16x16x32_f16 v[114:117], v[118:121], v[106:109], v[114:117]
	s_waitcnt vmcnt(2)
	ds_write_b128 v18, v[138:141] offset:49152
	v_mfma_f32_16x16x32_f16 v[40:43], v[118:121], v[110:113], v[40:43]
	ds_read_b128 v[118:121], v22 offset:36864
	v_mfma_f32_16x16x32_f16 v[70:73], v[122:125], v[106:109], v[70:73]
	ds_read_b128 v[106:109], v23
	v_mfma_f32_16x16x32_f16 v[48:51], v[122:125], v[110:113], v[48:51]
	ds_read_b128 v[110:113], v23 offset:2048
	s_waitcnt lgkmcnt(1)
	v_mfma_f32_16x16x32_f16 v[36:39], v[58:61], v[106:109], v[36:39]
	ds_read_b128 v[122:125], v22 offset:38912
	s_waitcnt lgkmcnt(1)
	v_mfma_f32_16x16x32_f16 v[66:69], v[58:61], v[110:113], v[66:69]
	s_waitcnt vmcnt(1)
	ds_write_b128 v19, v[142:145] offset:49152
	v_mfma_f32_16x16x32_f16 v[44:47], v[94:97], v[106:109], v[44:47]
	s_waitcnt vmcnt(0)
	ds_write_b128 v20, v[154:157] offset:49152
	v_mfma_f32_16x16x32_f16 v[78:81], v[94:97], v[110:113], v[78:81]
	v_mfma_f32_16x16x32_f16 v[82:85], v[118:121], v[106:109], v[82:85]
	v_mfma_f32_16x16x32_f16 v[86:89], v[118:121], v[110:113], v[86:89]
	s_waitcnt lgkmcnt(2)
	v_mfma_f32_16x16x32_f16 v[28:31], v[122:125], v[106:109], v[28:31]
	ds_read_b128 v[106:109], v23 offset:4096
	v_mfma_f32_16x16x32_f16 v[32:35], v[122:125], v[110:113], v[32:35]
	ds_read_b128 v[110:113], v23 offset:6144
	s_waitcnt lgkmcnt(1)
	v_mfma_f32_16x16x32_f16 v[98:101], v[58:61], v[106:109], v[98:101]
	s_waitcnt lgkmcnt(0)
	v_mfma_f32_16x16x32_f16 v[52:55], v[58:61], v[110:113], v[52:55]
	global_load_dwordx4 v[58:61], v[0:1], off offset:2304
	v_mfma_f32_16x16x32_f16 v[102:105], v[94:97], v[106:109], v[102:105]
	v_mfma_f32_16x16x32_f16 v[24:27], v[94:97], v[110:113], v[24:27]
	v_mfma_f32_16x16x32_f16 v[114:117], v[118:121], v[106:109], v[114:117]
	v_mfma_f32_16x16x32_f16 v[40:43], v[118:121], v[110:113], v[40:43]
	v_mfma_f32_16x16x32_f16 v[70:73], v[122:125], v[106:109], v[70:73]
	global_load_dwordx4 v[106:109], v[2:3], off offset:2304
	global_load_dwordx4 v[134:137], v[4:5], off offset:2304
	global_load_dwordx4 v[158:161], v[14:15], off offset:2304
	global_load_dwordx4 v[94:97], v[10:11], off offset:2304
	global_load_dwordx4 v[162:165], v[12:13], off offset:2304
	global_load_dwordx4 v[166:169], v[8:9], off offset:2304
	global_load_dwordx4 v[190:193], v[6:7], off offset:2304
	s_waitcnt lgkmcnt(0)
	s_barrier
; #define GL_LOAD(s_, kt_) if (VAR != 1) { a##s_##0 = GL_A(0, kt_); a##s_##1 = GL_A(1, kt_); a##s_##2 = GL_A(2, kt_); a##s_##3 = GL_A(3, kt_); b##s_##0 = GL_B(0, kt_); b##s_##1 = GL_B(1, kt_); b##s_##2 = GL_B(2, kt_); b##s_##3 = GL_B(3, kt_); }
; #define LDS_STORE(s_, buf_) if (VAR != 2) { LDS_ST1(sA, 0, buf_, a##s_##0) LDS_ST1(sA, 1, buf_, a##s_##1) LDS_ST1(sA, 2, buf_, a##s_##2) LDS_ST1(sA, 3, buf_, a##s_##3) LDS_ST1(sB, 0, buf_, b##s_##0) LDS_ST1(sB, 1, buf_, b##s_##1) LDS_ST1(sB, 2, buf_, b##s_##2) LDS_ST1(sB, 3, buf_, b##s_##3) }
;     ...
;   GL_LOAD(0, 0)
;   GL_LOAD(1, 1)
;   LDS_STORE(0, 0)
;   if (VAR != 4) __syncthreads();
; #pragma unroll
;   for (int kt = 0; kt < nk; kt += 2) {
;     if (kt + 2 < nk) { GL_LOAD(0, kt + 2) }
;     MMA_TILE(0)
;     LDS_STORE(1, 1)
;     if (VAR != 4) __syncthreads();
;     if (kt + 3 < nk) { GL_LOAD(1, kt + 3) }
;     MMA_TILE(1)
;     if (kt + 2 < nk) { LDS_STORE(0, 0) }
;     if (VAR != 4) __syncthreads();
	v_mfma_f32_16x16x32_f16 v[48:51], v[122:125], v[110:113], v[48:51]
	ds_read_b128 v[62:65], v16 offset:49152
	ds_read_b128 v[90:93], v21 offset:16384
	s_waitcnt lgkmcnt(0)
	v_mfma_f32_16x16x32_f16 v[36:39], v[62:65], v[90:93], v[36:39]
	ds_read_b128 v[74:77], v16 offset:51200
	ds_read_b128 v[110:113], v21 offset:18432
	s_waitcnt lgkmcnt(0)
	v_mfma_f32_16x16x32_f16 v[66:69], v[62:65], v[110:113], v[66:69]
	ds_read_b128 v[118:121], v16 offset:53248
	v_mfma_f32_16x16x32_f16 v[44:47], v[74:77], v[90:93], v[44:47]
	ds_read_b128 v[122:125], v16 offset:55296
	v_mfma_f32_16x16x32_f16 v[78:81], v[74:77], v[110:113], v[78:81]
	s_waitcnt vmcnt(7)
	ds_write_b128 v17, v[58:61]
	s_waitcnt lgkmcnt(2)
	v_mfma_f32_16x16x32_f16 v[82:85], v[118:121], v[90:93], v[82:85]
	s_waitcnt vmcnt(6)
	ds_write_b128 v18, v[106:109]
	v_mfma_f32_16x16x32_f16 v[86:89], v[118:121], v[110:113], v[86:89]
	s_waitcnt vmcnt(5)
	ds_write_b128 v19, v[134:137]
	s_waitcnt lgkmcnt(3)
	v_mfma_f32_16x16x32_f16 v[28:31], v[122:125], v[90:93], v[28:31]
	ds_read_b128 v[90:93], v21 offset:20480
	v_mfma_f32_16x16x32_f16 v[32:35], v[122:125], v[110:113], v[32:35]
	ds_read_b128 v[110:113], v21 offset:22528
	s_waitcnt lgkmcnt(1)
	v_mfma_f32_16x16x32_f16 v[98:101], v[62:65], v[90:93], v[98:101]
	s_waitcnt vmcnt(4)
	ds_write_b128 v20, v[158:161]
	s_waitcnt lgkmcnt(1)
	v_mfma_f32_16x16x32_f16 v[52:55], v[62:65], v[110:113], v[52:55]
	ds_read_b128 v[62:65], v22 offset:49152
	v_mfma_f32_16x16x32_f16 v[102:105], v[74:77], v[90:93], v[102:105]
	s_waitcnt vmcnt(3)
	ds_write_b128 v17, v[94:97] offset:32768
	v_mfma_f32_16x16x32_f16 v[24:27], v[74:77], v[110:113], v[24:27]
	ds_read_b128 v[74:77], v22 offset:51200
	v_mfma_f32_16x16x32_f16 v[114:117], v[118:121], v[90:93], v[114:117]
	s_waitcnt vmcnt(2)
	ds_write_b128 v18, v[162:165] offset:32768
	v_mfma_f32_16x16x32_f16 v[40:43], v[118:121], v[110:113], v[40:43]
	ds_read_b128 v[118:121], v22 offset:53248
	v_mfma_f32_16x16x32_f16 v[70:73], v[122:125], v[90:93], v[70:73]
	ds_read_b128 v[90:93], v23 offset:16384
	v_mfma_f32_16x16x32_f16 v[48:51], v[122:125], v[110:113], v[48:51]
	ds_read_b128 v[110:113], v23 offset:18432
	s_waitcnt lgkmcnt(1)
	v_mfma_f32_16x16x32_f16 v[36:39], v[62:65], v[90:93], v[36:39]
	ds_read_b128 v[122:125], v22 offset:55296
	s_waitcnt lgkmcnt(1)
	v_mfma_f32_16x16x32_f16 v[66:69], v[62:65], v[110:113], v[66:69]
	s_waitcnt vmcnt(1)
	ds_write_b128 v19, v[166:169] offset:32768
	v_mfma_f32_16x16x32_f16 v[44:47], v[74:77], v[90:93], v[44:47]
	s_waitcnt vmcnt(0)
	ds_write_b128 v20, v[190:193] offset:32768
	v_mfma_f32_16x16x32_f16 v[78:81], v[74:77], v[110:113], v[78:81]
	v_mfma_f32_16x16x32_f16 v[82:85], v[118:121], v[90:93], v[82:85]
	v_mfma_f32_16x16x32_f16 v[86:89], v[118:121], v[110:113], v[86:89]
	s_waitcnt lgkmcnt(2)
	v_mfma_f32_16x16x32_f16 v[28:31], v[122:125], v[90:93], v[28:31]
	ds_read_b128 v[90:93], v23 offset:20480
	v_mfma_f32_16x16x32_f16 v[32:35], v[122:125], v[110:113], v[32:35]
	ds_read_b128 v[110:113], v23 offset:22528
	s_waitcnt lgkmcnt(1)
	v_mfma_f32_16x16x32_f16 v[98:101], v[62:65], v[90:93], v[98:101]
	s_waitcnt lgkmcnt(0)
	v_mfma_f32_16x16x32_f16 v[52:55], v[62:65], v[110:113], v[52:55]
	global_load_dwordx4 v[62:65], v[0:1], off offset:2432
	v_mfma_f32_16x16x32_f16 v[102:105], v[74:77], v[90:93], v[102:105]
	v_mfma_f32_16x16x32_f16 v[24:27], v[74:77], v[110:113], v[24:27]
	v_mfma_f32_16x16x32_f16 v[114:117], v[118:121], v[90:93], v[114:117]
	v_mfma_f32_16x16x32_f16 v[40:43], v[118:121], v[110:113], v[40:43]
	v_mfma_f32_16x16x32_f16 v[70:73], v[122:125], v[90:93], v[70:73]
	global_load_dwordx4 v[90:93], v[2:3], off offset:2432
	global_load_dwordx4 v[126:129], v[4:5], off offset:2432
	global_load_dwordx4 v[130:133], v[14:15], off offset:2432
	global_load_dwordx4 v[74:77], v[10:11], off offset:2432
	global_load_dwordx4 v[138:141], v[12:13], off offset:2432
	global_load_dwordx4 v[142:145], v[8:9], off offset:2432
	global_load_dwordx4 v[154:157], v[6:7], off offset:2432
	s_waitcnt lgkmcnt(0)
	s_barrier
	v_mfma_f32_16x16x32_f16 v[48:51], v[122:125], v[110:113], v[48:51]
	ds_read_b128 v[58:61], v16 offset:32768
	ds_read_b128 v[106:109], v21
	s_waitcnt lgkmcnt(0)
	v_mfma_f32_16x16x32_f16 v[36:39], v[58:61], v[106:109], v[36:39]
	ds_read_b128 v[94:97], v16 offset:34816
	ds_read_b128 v[110:113], v21 offset:2048
	s_waitcnt lgkmcnt(0)
	v_mfma_f32_16x16x32_f16 v[66:69], v[58:61], v[110:113], v[66:69]
	ds_read_b128 v[118:121], v16 offset:36864
	v_mfma_f32_16x16x32_f16 v[44:47], v[94:97], v[106:109], v[44:47]
	ds_read_b128 v[122:125], v16 offset:38912
	v_mfma_f32_16x16x32_f16 v[78:81], v[94:97], v[110:113], v[78:81]
	s_waitcnt vmcnt(7)
	ds_write_b128 v17, v[62:65] offset:16384
	s_waitcnt lgkmcnt(2)
	v_mfma_f32_16x16x32_f16 v[82:85], v[118:121], v[106:109], v[82:85]
	s_waitcnt vmcnt(6)
	ds_write_b128 v18, v[90:93] offset:16384
	v_mfma_f32_16x16x32_f16 v[86:89], v[118:121], v[110:113], v[86:89]
	s_waitcnt vmcnt(5)
	ds_write_b128 v19, v[126:129] offset:16384
	s_waitcnt lgkmcnt(3)
	v_mfma_f32_16x16x32_f16 v[28:31], v[122:125], v[106:109], v[28:31]
	ds_read_b128 v[106:109], v21 offset:4096
	v_mfma_f32_16x16x32_f16 v[32:35], v[122:125], v[110:113], v[32:35]
	ds_read_b128 v[110:113], v21 offset:6144
	s_waitcnt lgkmcnt(1)
	v_mfma_f32_16x16x32_f16 v[98:101], v[58:61], v[106:109], v[98:101]
	s_waitcnt vmcnt(4)
	ds_write_b128 v20, v[130:133] offset:16384
	s_waitcnt lgkmcnt(1)
	v_mfma_f32_16x16x32_f16 v[52:55], v[58:61], v[110:113], v[52:55]
	ds_read_b128 v[58:61], v22 offset:32768
	v_mfma_f32_16x16x32_f16 v[102:105], v[94:97], v[106:109], v[102:105]
	s_waitcnt vmcnt(3)
; #define GL_LOAD(s_, kt_) if (VAR != 1) { a##s_##0 = GL_A(0, kt_); a##s_##1 = GL_A(1, kt_); a##s_##2 = GL_A(2, kt_); a##s_##3 = GL_A(3, kt_); b##s_##0 = GL_B(0, kt_); b##s_##1 = GL_B(1, kt_); b##s_##2 = GL_B(2, kt_); b##s_##3 = GL_B(3, kt_); }
; #define LDS_STORE(s_, buf_) if (VAR != 2) { LDS_ST1(sA, 0, buf_, a##s_##0) LDS_ST1(sA, 1, buf_, a##s_##1) LDS_ST1(sA, 2, buf_, a##s_##2) LDS_ST1(sA, 3, buf_, a##s_##3) LDS_ST1(sB, 0, buf_, b##s_##0) LDS_ST1(sB, 1, buf_, b##s_##1) LDS_ST1(sB, 2, buf_, b##s_##2) LDS_ST1(sB, 3, buf_, b##s_##3) }
;     ...
;   GL_LOAD(0, 0)
;   GL_LOAD(1, 1)
;   LDS_STORE(0, 0)
;   if (VAR != 4) __syncthreads();
; #pragma unroll
;   for (int kt = 0; kt < nk; kt += 2) {
;     if (kt + 2 < nk) { GL_LOAD(0, kt + 2) }
;     MMA_TILE(0)
;     LDS_STORE(1, 1)
;     if (VAR != 4) __syncthreads();
;     if (kt + 3 < nk) { GL_LOAD(1, kt + 3) }
;     MMA_TILE(1)
;     if (kt + 2 < nk) { LDS_STORE(0, 0) }
;     if (VAR != 4) __syncthreads();
	ds_write_b128 v17, v[74:77] offset:49152
	v_mfma_f32_16x16x32_f16 v[24:27], v[94:97], v[110:113], v[24:27]
	ds_read_b128 v[94:97], v22 offset:34816
	v_mfma_f32_16x16x32_f16 v[114:117], v[118:121], v[106:109], v[114:117]
	s_waitcnt vmcnt(2)
	ds_write_b128 v18, v[138:141] offset:49152
	v_mfma_f32_16x16x32_f16 v[40:43], v[118:121], v[110:113], v[40:43]
	ds_read_b128 v[118:121], v22 offset:36864
	v_mfma_f32_16x16x32_f16 v[70:73], v[122:125], v[106:109], v[70:73]
	ds_read_b128 v[106:109], v23
	v_mfma_f32_16x16x32_f16 v[48:51], v[122:125], v[110:113], v[48:51]
	ds_read_b128 v[110:113], v23 offset:2048
	s_waitcnt lgkmcnt(1)
	v_mfma_f32_16x16x32_f16 v[36:39], v[58:61], v[106:109], v[36:39]
	ds_read_b128 v[122:125], v22 offset:38912
	s_waitcnt lgkmcnt(1)
	v_mfma_f32_16x16x32_f16 v[66:69], v[58:61], v[110:113], v[66:69]
	s_waitcnt vmcnt(1)
	ds_write_b128 v19, v[142:145] offset:49152
	v_mfma_f32_16x16x32_f16 v[44:47], v[94:97], v[106:109], v[44:47]
	s_waitcnt vmcnt(0)
	ds_write_b128 v20, v[154:157] offset:49152
	v_mfma_f32_16x16x32_f16 v[78:81], v[94:97], v[110:113], v[78:81]
	v_mfma_f32_16x16x32_f16 v[82:85], v[118:121], v[106:109], v[82:85]
	v_mfma_f32_16x16x32_f16 v[86:89], v[118:121], v[110:113], v[86:89]
	s_waitcnt lgkmcnt(2)
	v_mfma_f32_16x16x32_f16 v[28:31], v[122:125], v[106:109], v[28:31]
	ds_read_b128 v[106:109], v23 offset:4096
	v_mfma_f32_16x16x32_f16 v[32:35], v[122:125], v[110:113], v[32:35]
	ds_read_b128 v[110:113], v23 offset:6144
	s_waitcnt lgkmcnt(1)
	v_mfma_f32_16x16x32_f16 v[98:101], v[58:61], v[106:109], v[98:101]
	s_waitcnt lgkmcnt(0)
	v_mfma_f32_16x16x32_f16 v[52:55], v[58:61], v[110:113], v[52:55]
	global_load_dwordx4 v[58:61], v[0:1], off offset:2560
	v_mfma_f32_16x16x32_f16 v[102:105], v[94:97], v[106:109], v[102:105]
	v_mfma_f32_16x16x32_f16 v[24:27], v[94:97], v[110:113], v[24:27]
	v_mfma_f32_16x16x32_f16 v[114:117], v[118:121], v[106:109], v[114:117]
	v_mfma_f32_16x16x32_f16 v[40:43], v[118:121], v[110:113], v[40:43]
	v_mfma_f32_16x16x32_f16 v[70:73], v[122:125], v[106:109], v[70:73]
	global_load_dwordx4 v[106:109], v[2:3], off offset:2560
	global_load_dwordx4 v[134:137], v[4:5], off offset:2560
	global_load_dwordx4 v[158:161], v[14:15], off offset:2560
	global_load_dwordx4 v[94:97], v[10:11], off offset:2560
	global_load_dwordx4 v[162:165], v[12:13], off offset:2560
	global_load_dwordx4 v[166:169], v[8:9], off offset:2560
	global_load_dwordx4 v[190:193], v[6:7], off offset:2560
	s_waitcnt lgkmcnt(0)
	s_barrier
	v_mfma_f32_16x16x32_f16 v[48:51], v[122:125], v[110:113], v[48:51]
	ds_read_b128 v[62:65], v16 offset:49152
	ds_read_b128 v[90:93], v21 offset:16384
	s_waitcnt lgkmcnt(0)
	v_mfma_f32_16x16x32_f16 v[36:39], v[62:65], v[90:93], v[36:39]
	ds_read_b128 v[74:77], v16 offset:51200
	ds_read_b128 v[110:113], v21 offset:18432
	s_waitcnt lgkmcnt(0)
	v_mfma_f32_16x16x32_f16 v[66:69], v[62:65], v[110:113], v[66:69]
	ds_read_b128 v[118:121], v16 offset:53248
	v_mfma_f32_16x16x32_f16 v[44:47], v[74:77], v[90:93], v[44:47]
	ds_read_b128 v[122:125], v16 offset:55296
	v_mfma_f32_16x16x32_f16 v[78:81], v[74:77], v[110:113], v[78:81]
	s_waitcnt vmcnt(7)
	ds_write_b128 v17, v[58:61]
	s_waitcnt lgkmcnt(2)
	v_mfma_f32_16x16x32_f16 v[82:85], v[118:121], v[90:93], v[82:85]
	s_waitcnt vmcnt(6)
	ds_write_b128 v18, v[106:109]
	v_mfma_f32_16x16x32_f16 v[86:89], v[118:121], v[110:113], v[86:89]
	s_waitcnt vmcnt(5)
	ds_write_b128 v19, v[134:137]
	s_waitcnt lgkmcnt(3)
	v_mfma_f32_16x16x32_f16 v[28:31], v[122:125], v[90:93], v[28:31]
	ds_read_b128 v[90:93], v21 offset:20480
	v_mfma_f32_16x16x32_f16 v[32:35], v[122:125], v[110:113], v[32:35]
	ds_read_b128 v[110:113], v21 offset:22528
	s_waitcnt lgkmcnt(1)
	v_mfma_f32_16x16x32_f16 v[98:101], v[62:65], v[90:93], v[98:101]
	s_waitcnt vmcnt(4)
	ds_write_b128 v20, v[158:161]
	s_waitcnt lgkmcnt(1)
	v_mfma_f32_16x16x32_f16 v[52:55], v[62:65], v[110:113], v[52:55]
	ds_read_b128 v[62:65], v22 offset:49152
	v_mfma_f32_16x16x32_f16 v[102:105], v[74:77], v[90:93], v[102:105]
	s_waitcnt vmcnt(3)
	ds_write_b128 v17, v[94:97] offset:32768
	v_mfma_f32_16x16x32_f16 v[24:27], v[74:77], v[110:113], v[24:27]
	ds_read_b128 v[74:77], v22 offset:51200
	v_mfma_f32_16x16x32_f16 v[114:117], v[118:121], v[90:93], v[114:117]
	s_waitcnt vmcnt(2)
	ds_write_b128 v18, v[162:165] offset:32768
	v_mfma_f32_16x16x32_f16 v[40:43], v[118:121], v[110:113], v[40:43]
	ds_read_b128 v[118:121], v22 offset:53248
	v_mfma_f32_16x16x32_f16 v[70:73], v[122:125], v[90:93], v[70:73]
	ds_read_b128 v[90:93], v23 offset:16384
	v_mfma_f32_16x16x32_f16 v[48:51], v[122:125], v[110:113], v[48:51]
	ds_read_b128 v[110:113], v23 offset:18432
	s_waitcnt lgkmcnt(1)
	v_mfma_f32_16x16x32_f16 v[36:39], v[62:65], v[90:93], v[36:39]
	ds_read_b128 v[122:125], v22 offset:55296
	s_waitcnt lgkmcnt(1)
	v_mfma_f32_16x16x32_f16 v[66:69], v[62:65], v[110:113], v[66:69]
	s_waitcnt vmcnt(1)
	ds_write_b128 v19, v[166:169] offset:32768
	v_mfma_f32_16x16x32_f16 v[44:47], v[74:77], v[90:93], v[44:47]
	s_waitcnt vmcnt(0)
	ds_write_b128 v20, v[190:193] offset:32768
	v_mfma_f32_16x16x32_f16 v[78:81], v[74:77], v[110:113], v[78:81]
	v_mfma_f32_16x16x32_f16 v[82:85], v[118:121], v[90:93], v[82:85]
	v_mfma_f32_16x16x32_f16 v[86:89], v[118:121], v[110:113], v[86:89]
	s_waitcnt lgkmcnt(2)
	v_mfma_f32_16x16x32_f16 v[28:31], v[122:125], v[90:93], v[28:31]
	ds_read_b128 v[90:93], v23 offset:20480
	v_mfma_f32_16x16x32_f16 v[32:35], v[122:125], v[110:113], v[32:35]
	ds_read_b128 v[110:113], v23 offset:22528
	s_waitcnt lgkmcnt(1)
	v_mfma_f32_16x16x32_f16 v[98:101], v[62:65], v[90:93], v[98:101]
	s_waitcnt lgkmcnt(0)
	v_mfma_f32_16x16x32_f16 v[52:55], v[62:65], v[110:113], v[52:55]
	global_load_dwordx4 v[62:65], v[0:1], off offset:2688
	v_mfma_f32_16x16x32_f16 v[102:105], v[74:77], v[90:93], v[102:105]
	v_mfma_f32_16x16x32_f16 v[24:27], v[74:77], v[110:113], v[24:27]
	v_mfma_f32_16x16x32_f16 v[114:117], v[118:121], v[90:93], v[114:117]
	v_mfma_f32_16x16x32_f16 v[40:43], v[118:121], v[110:113], v[40:43]
	v_mfma_f32_16x16x32_f16 v[70:73], v[122:125], v[90:93], v[70:73]
	global_load_dwordx4 v[90:93], v[2:3], off offset:2688
	global_load_dwordx4 v[126:129], v[4:5], off offset:2688
	global_load_dwordx4 v[130:133], v[14:15], off offset:2688
	global_load_dwordx4 v[74:77], v[10:11], off offset:2688
	global_load_dwordx4 v[138:141], v[12:13], off offset:2688
	global_load_dwordx4 v[142:145], v[8:9], off offset:2688
	global_load_dwordx4 v[154:157], v[6:7], off offset:2688
	s_waitcnt lgkmcnt(0)
	s_barrier
; #define GL_LOAD(s_, kt_) if (VAR != 1) { a##s_##0 = GL_A(0, kt_); a##s_##1 = GL_A(1, kt_); a##s_##2 = GL_A(2, kt_); a##s_##3 = GL_A(3, kt_); b##s_##0 = GL_B(0, kt_); b##s_##1 = GL_B(1, kt_); b##s_##2 = GL_B(2, kt_); b##s_##3 = GL_B(3, kt_); }
; #define LDS_STORE(s_, buf_) if (VAR != 2) { LDS_ST1(sA, 0, buf_, a##s_##0) LDS_ST1(sA, 1, buf_, a##s_##1) LDS_ST1(sA, 2, buf_, a##s_##2) LDS_ST1(sA, 3, buf_, a##s_##3) LDS_ST1(sB, 0, buf_, b##s_##0) LDS_ST1(sB, 1, buf_, b##s_##1) LDS_ST1(sB, 2, buf_, b##s_##2) LDS_ST1(sB, 3, buf_, b##s_##3) }
;     ...
;   GL_LOAD(0, 0)
;   GL_LOAD(1, 1)
;   LDS_STORE(0, 0)
;   if (VAR != 4) __syncthreads();
; #pragma unroll
;   for (int kt = 0; kt < nk; kt += 2) {
;     if (kt + 2 < nk) { GL_LOAD(0, kt + 2) }
;     MMA_TILE(0)
;     LDS_STORE(1, 1)
;     if (VAR != 4) __syncthreads();
;     if (kt + 3 < nk) { GL_LOAD(1, kt + 3) }
;     MMA_TILE(1)
;     if (kt + 2 < nk) { LDS_STORE(0, 0) }
;     if (VAR != 4) __syncthreads();
	v_mfma_f32_16x16x32_f16 v[48:51], v[122:125], v[110:113], v[48:51]
	ds_read_b128 v[58:61], v16 offset:32768
	ds_read_b128 v[106:109], v21
	s_waitcnt lgkmcnt(0)
	v_mfma_f32_16x16x32_f16 v[36:39], v[58:61], v[106:109], v[36:39]
	ds_read_b128 v[94:97], v16 offset:34816
	ds_read_b128 v[110:113], v21 offset:2048
	s_waitcnt lgkmcnt(0)
	v_mfma_f32_16x16x32_f16 v[66:69], v[58:61], v[110:113], v[66:69]
	ds_read_b128 v[118:121], v16 offset:36864
	v_mfma_f32_16x16x32_f16 v[44:47], v[94:97], v[106:109], v[44:47]
	ds_read_b128 v[122:125], v16 offset:38912
	v_mfma_f32_16x16x32_f16 v[78:81], v[94:97], v[110:113], v[78:81]
	s_waitcnt vmcnt(7)
	ds_write_b128 v17, v[62:65] offset:16384
	s_waitcnt lgkmcnt(2)
	v_mfma_f32_16x16x32_f16 v[82:85], v[118:121], v[106:109], v[82:85]
	s_waitcnt vmcnt(6)
	ds_write_b128 v18, v[90:93] offset:16384
	v_mfma_f32_16x16x32_f16 v[86:89], v[118:121], v[110:113], v[86:89]
	s_waitcnt vmcnt(5)
	ds_write_b128 v19, v[126:129] offset:16384
	s_waitcnt lgkmcnt(3)
	v_mfma_f32_16x16x32_f16 v[28:31], v[122:125], v[106:109], v[28:31]
	ds_read_b128 v[106:109], v21 offset:4096
	v_mfma_f32_16x16x32_f16 v[32:35], v[122:125], v[110:113], v[32:35]
	ds_read_b128 v[110:113], v21 offset:6144
	s_waitcnt lgkmcnt(1)
	v_mfma_f32_16x16x32_f16 v[98:101], v[58:61], v[106:109], v[98:101]
	s_waitcnt vmcnt(4)
	ds_write_b128 v20, v[130:133] offset:16384
	s_waitcnt lgkmcnt(1)
	v_mfma_f32_16x16x32_f16 v[52:55], v[58:61], v[110:113], v[52:55]
	ds_read_b128 v[58:61], v22 offset:32768
	v_mfma_f32_16x16x32_f16 v[102:105], v[94:97], v[106:109], v[102:105]
	s_waitcnt vmcnt(3)
	ds_write_b128 v17, v[74:77] offset:49152
	v_mfma_f32_16x16x32_f16 v[24:27], v[94:97], v[110:113], v[24:27]
	ds_read_b128 v[94:97], v22 offset:34816
	v_mfma_f32_16x16x32_f16 v[114:117], v[118:121], v[106:109], v[114:117]
	s_waitcnt vmcnt(2)
	ds_write_b128 v18, v[138:141] offset:49152
	v_mfma_f32_16x16x32_f16 v[40:43], v[118:121], v[110:113], v[40:43]
	ds_read_b128 v[118:121], v22 offset:36864
	v_mfma_f32_16x16x32_f16 v[70:73], v[122:125], v[106:109], v[70:73]
	ds_read_b128 v[106:109], v23
	v_mfma_f32_16x16x32_f16 v[48:51], v[122:125], v[110:113], v[48:51]
	ds_read_b128 v[110:113], v23 offset:2048
	s_waitcnt lgkmcnt(1)
	v_mfma_f32_16x16x32_f16 v[36:39], v[58:61], v[106:109], v[36:39]
	ds_read_b128 v[122:125], v22 offset:38912
	s_waitcnt lgkmcnt(1)
	v_mfma_f32_16x16x32_f16 v[66:69], v[58:61], v[110:113], v[66:69]
	s_waitcnt vmcnt(1)
	ds_write_b128 v19, v[142:145] offset:49152
	v_mfma_f32_16x16x32_f16 v[44:47], v[94:97], v[106:109], v[44:47]
	s_waitcnt vmcnt(0)
	ds_write_b128 v20, v[154:157] offset:49152
	v_mfma_f32_16x16x32_f16 v[78:81], v[94:97], v[110:113], v[78:81]
	v_mfma_f32_16x16x32_f16 v[82:85], v[118:121], v[106:109], v[82:85]
	v_mfma_f32_16x16x32_f16 v[86:89], v[118:121], v[110:113], v[86:89]
	s_waitcnt lgkmcnt(2)
	v_mfma_f32_16x16x32_f16 v[28:31], v[122:125], v[106:109], v[28:31]
	ds_read_b128 v[106:109], v23 offset:4096
	v_mfma_f32_16x16x32_f16 v[32:35], v[122:125], v[110:113], v[32:35]
	ds_read_b128 v[110:113], v23 offset:6144
	s_waitcnt lgkmcnt(1)
	v_mfma_f32_16x16x32_f16 v[98:101], v[58:61], v[106:109], v[98:101]
	s_waitcnt lgkmcnt(0)
	v_mfma_f32_16x16x32_f16 v[52:55], v[58:61], v[110:113], v[52:55]
	global_load_dwordx4 v[58:61], v[0:1], off offset:2816
	v_mfma_f32_16x16x32_f16 v[102:105], v[94:97], v[106:109], v[102:105]
	v_mfma_f32_16x16x32_f16 v[24:27], v[94:97], v[110:113], v[24:27]
	v_mfma_f32_16x16x32_f16 v[114:117], v[118:121], v[106:109], v[114:117]
	v_mfma_f32_16x16x32_f16 v[40:43], v[118:121], v[110:113], v[40:43]
	v_mfma_f32_16x16x32_f16 v[70:73], v[122:125], v[106:109], v[70:73]
	global_load_dwordx4 v[106:109], v[2:3], off offset:2816
	global_load_dwordx4 v[134:137], v[4:5], off offset:2816
	global_load_dwordx4 v[158:161], v[14:15], off offset:2816
	global_load_dwordx4 v[94:97], v[10:11], off offset:2816
	global_load_dwordx4 v[162:165], v[12:13], off offset:2816
	global_load_dwordx4 v[166:169], v[8:9], off offset:2816
	global_load_dwordx4 v[190:193], v[6:7], off offset:2816
	s_waitcnt lgkmcnt(0)
	s_barrier
	v_mfma_f32_16x16x32_f16 v[48:51], v[122:125], v[110:113], v[48:51]
	ds_read_b128 v[62:65], v16 offset:49152
	ds_read_b128 v[90:93], v21 offset:16384
	s_waitcnt lgkmcnt(0)
	v_mfma_f32_16x16x32_f16 v[36:39], v[62:65], v[90:93], v[36:39]
	ds_read_b128 v[74:77], v16 offset:51200
	ds_read_b128 v[110:113], v21 offset:18432
	s_waitcnt lgkmcnt(0)
	v_mfma_f32_16x16x32_f16 v[66:69], v[62:65], v[110:113], v[66:69]
	ds_read_b128 v[118:121], v16 offset:53248
	v_mfma_f32_16x16x32_f16 v[44:47], v[74:77], v[90:93], v[44:47]
	ds_read_b128 v[122:125], v16 offset:55296
	v_mfma_f32_16x16x32_f16 v[78:81], v[74:77], v[110:113], v[78:81]
	s_waitcnt vmcnt(7)
	ds_write_b128 v17, v[58:61]
	s_waitcnt lgkmcnt(2)
	v_mfma_f32_16x16x32_f16 v[82:85], v[118:121], v[90:93], v[82:85]
	s_waitcnt vmcnt(6)
	ds_write_b128 v18, v[106:109]
	v_mfma_f32_16x16x32_f16 v[86:89], v[118:121], v[110:113], v[86:89]
	s_waitcnt vmcnt(5)
	ds_write_b128 v19, v[134:137]
	s_waitcnt lgkmcnt(3)
	v_mfma_f32_16x16x32_f16 v[28:31], v[122:125], v[90:93], v[28:31]
	ds_read_b128 v[90:93], v21 offset:20480
	v_mfma_f32_16x16x32_f16 v[32:35], v[122:125], v[110:113], v[32:35]
	ds_read_b128 v[110:113], v21 offset:22528
	s_waitcnt lgkmcnt(1)
	v_mfma_f32_16x16x32_f16 v[98:101], v[62:65], v[90:93], v[98:101]
	s_waitcnt vmcnt(4)
	ds_write_b128 v20, v[158:161]
	s_waitcnt lgkmcnt(1)
	v_mfma_f32_16x16x32_f16 v[52:55], v[62:65], v[110:113], v[52:55]
	ds_read_b128 v[62:65], v22 offset:49152
	v_mfma_f32_16x16x32_f16 v[102:105], v[74:77], v[90:93], v[102:105]
	s_waitcnt vmcnt(3)
; #define GL_LOAD(s_, kt_) if (VAR != 1) { a##s_##0 = GL_A(0, kt_); a##s_##1 = GL_A(1, kt_); a##s_##2 = GL_A(2, kt_); a##s_##3 = GL_A(3, kt_); b##s_##0 = GL_B(0, kt_); b##s_##1 = GL_B(1, kt_); b##s_##2 = GL_B(2, kt_); b##s_##3 = GL_B(3, kt_); }
; #define LDS_STORE(s_, buf_) if (VAR != 2) { LDS_ST1(sA, 0, buf_, a##s_##0) LDS_ST1(sA, 1, buf_, a##s_##1) LDS_ST1(sA, 2, buf_, a##s_##2) LDS_ST1(sA, 3, buf_, a##s_##3) LDS_ST1(sB, 0, buf_, b##s_##0) LDS_ST1(sB, 1, buf_, b##s_##1) LDS_ST1(sB, 2, buf_, b##s_##2) LDS_ST1(sB, 3, buf_, b##s_##3) }
;     ...
;   GL_LOAD(0, 0)
;   GL_LOAD(1, 1)
;   LDS_STORE(0, 0)
;   if (VAR != 4) __syncthreads();
; #pragma unroll
;   for (int kt = 0; kt < nk; kt += 2) {
;     if (kt + 2 < nk) { GL_LOAD(0, kt + 2) }
;     MMA_TILE(0)
;     LDS_STORE(1, 1)
;     if (VAR != 4) __syncthreads();
;     if (kt + 3 < nk) { GL_LOAD(1, kt + 3) }
;     MMA_TILE(1)
;     if (kt + 2 < nk) { LDS_STORE(0, 0) }
;     if (VAR != 4) __syncthreads();
	ds_write_b128 v17, v[94:97] offset:32768
	v_mfma_f32_16x16x32_f16 v[24:27], v[74:77], v[110:113], v[24:27]
	ds_read_b128 v[74:77], v22 offset:51200
	v_mfma_f32_16x16x32_f16 v[114:117], v[118:121], v[90:93], v[114:117]
	s_waitcnt vmcnt(2)
	ds_write_b128 v18, v[162:165] offset:32768
	v_mfma_f32_16x16x32_f16 v[40:43], v[118:121], v[110:113], v[40:43]
	ds_read_b128 v[118:121], v22 offset:53248
	v_mfma_f32_16x16x32_f16 v[70:73], v[122:125], v[90:93], v[70:73]
	ds_read_b128 v[90:93], v23 offset:16384
	v_mfma_f32_16x16x32_f16 v[48:51], v[122:125], v[110:113], v[48:51]
	ds_read_b128 v[110:113], v23 offset:18432
	s_waitcnt lgkmcnt(1)
	v_mfma_f32_16x16x32_f16 v[36:39], v[62:65], v[90:93], v[36:39]
	ds_read_b128 v[122:125], v22 offset:55296
	s_waitcnt lgkmcnt(1)
	v_mfma_f32_16x16x32_f16 v[66:69], v[62:65], v[110:113], v[66:69]
	s_waitcnt vmcnt(1)
	ds_write_b128 v19, v[166:169] offset:32768
	v_mfma_f32_16x16x32_f16 v[44:47], v[74:77], v[90:93], v[44:47]
	s_waitcnt vmcnt(0)
	ds_write_b128 v20, v[190:193] offset:32768
	v_mfma_f32_16x16x32_f16 v[78:81], v[74:77], v[110:113], v[78:81]
	v_mfma_f32_16x16x32_f16 v[82:85], v[118:121], v[90:93], v[82:85]
	v_mfma_f32_16x16x32_f16 v[86:89], v[118:121], v[110:113], v[86:89]
	s_waitcnt lgkmcnt(2)
	v_mfma_f32_16x16x32_f16 v[28:31], v[122:125], v[90:93], v[28:31]
	ds_read_b128 v[90:93], v23 offset:20480
	v_mfma_f32_16x16x32_f16 v[32:35], v[122:125], v[110:113], v[32:35]
	ds_read_b128 v[110:113], v23 offset:22528
	s_waitcnt lgkmcnt(1)
	v_mfma_f32_16x16x32_f16 v[98:101], v[62:65], v[90:93], v[98:101]
	s_waitcnt lgkmcnt(0)
	v_mfma_f32_16x16x32_f16 v[52:55], v[62:65], v[110:113], v[52:55]
	global_load_dwordx4 v[62:65], v[0:1], off offset:2944
	v_mfma_f32_16x16x32_f16 v[102:105], v[74:77], v[90:93], v[102:105]
	v_mfma_f32_16x16x32_f16 v[24:27], v[74:77], v[110:113], v[24:27]
	v_mfma_f32_16x16x32_f16 v[114:117], v[118:121], v[90:93], v[114:117]
	v_mfma_f32_16x16x32_f16 v[40:43], v[118:121], v[110:113], v[40:43]
	v_mfma_f32_16x16x32_f16 v[70:73], v[122:125], v[90:93], v[70:73]
	global_load_dwordx4 v[90:93], v[2:3], off offset:2944
	global_load_dwordx4 v[126:129], v[4:5], off offset:2944
	global_load_dwordx4 v[130:133], v[14:15], off offset:2944
	global_load_dwordx4 v[74:77], v[10:11], off offset:2944
	global_load_dwordx4 v[138:141], v[12:13], off offset:2944
	global_load_dwordx4 v[142:145], v[8:9], off offset:2944
	global_load_dwordx4 v[154:157], v[6:7], off offset:2944
	s_waitcnt lgkmcnt(0)
	s_barrier
	v_mfma_f32_16x16x32_f16 v[48:51], v[122:125], v[110:113], v[48:51]
	ds_read_b128 v[58:61], v16 offset:32768
	ds_read_b128 v[106:109], v21
	s_waitcnt lgkmcnt(0)
	v_mfma_f32_16x16x32_f16 v[36:39], v[58:61], v[106:109], v[36:39]
	ds_read_b128 v[94:97], v16 offset:34816
	ds_read_b128 v[110:113], v21 offset:2048
	s_waitcnt lgkmcnt(0)
	v_mfma_f32_16x16x32_f16 v[66:69], v[58:61], v[110:113], v[66:69]
	ds_read_b128 v[118:121], v16 offset:36864
	v_mfma_f32_16x16x32_f16 v[44:47], v[94:97], v[106:109], v[44:47]
	ds_read_b128 v[122:125], v16 offset:38912
	v_mfma_f32_16x16x32_f16 v[78:81], v[94:97], v[110:113], v[78:81]
	s_waitcnt vmcnt(7)
	ds_write_b128 v17, v[62:65] offset:16384
	s_waitcnt lgkmcnt(2)
	v_mfma_f32_16x16x32_f16 v[82:85], v[118:121], v[106:109], v[82:85]
	s_waitcnt vmcnt(6)
	ds_write_b128 v18, v[90:93] offset:16384
	v_mfma_f32_16x16x32_f16 v[86:89], v[118:121], v[110:113], v[86:89]
	s_waitcnt vmcnt(5)
	ds_write_b128 v19, v[126:129] offset:16384
	s_waitcnt lgkmcnt(3)
	v_mfma_f32_16x16x32_f16 v[28:31], v[122:125], v[106:109], v[28:31]
	ds_read_b128 v[106:109], v21 offset:4096
	v_mfma_f32_16x16x32_f16 v[32:35], v[122:125], v[110:113], v[32:35]
	ds_read_b128 v[110:113], v21 offset:6144
	s_waitcnt lgkmcnt(1)
	v_mfma_f32_16x16x32_f16 v[98:101], v[58:61], v[106:109], v[98:101]
	s_waitcnt vmcnt(4)
	ds_write_b128 v20, v[130:133] offset:16384
	s_waitcnt lgkmcnt(1)
	v_mfma_f32_16x16x32_f16 v[52:55], v[58:61], v[110:113], v[52:55]
	ds_read_b128 v[58:61], v22 offset:32768
	v_mfma_f32_16x16x32_f16 v[102:105], v[94:97], v[106:109], v[102:105]
	s_waitcnt vmcnt(3)
	ds_write_b128 v17, v[74:77] offset:49152
	v_mfma_f32_16x16x32_f16 v[24:27], v[94:97], v[110:113], v[24:27]
	ds_read_b128 v[94:97], v22 offset:34816
	v_mfma_f32_16x16x32_f16 v[114:117], v[118:121], v[106:109], v[114:117]
	s_waitcnt vmcnt(2)
	ds_write_b128 v18, v[138:141] offset:49152
	v_mfma_f32_16x16x32_f16 v[40:43], v[118:121], v[110:113], v[40:43]
	ds_read_b128 v[118:121], v22 offset:36864
	v_mfma_f32_16x16x32_f16 v[70:73], v[122:125], v[106:109], v[70:73]
	ds_read_b128 v[106:109], v23
	v_mfma_f32_16x16x32_f16 v[48:51], v[122:125], v[110:113], v[48:51]
	ds_read_b128 v[110:113], v23 offset:2048
	s_waitcnt lgkmcnt(1)
	v_mfma_f32_16x16x32_f16 v[36:39], v[58:61], v[106:109], v[36:39]
	ds_read_b128 v[122:125], v22 offset:38912
	s_waitcnt lgkmcnt(1)
	v_mfma_f32_16x16x32_f16 v[66:69], v[58:61], v[110:113], v[66:69]
	s_waitcnt vmcnt(1)
	ds_write_b128 v19, v[142:145] offset:49152
	v_mfma_f32_16x16x32_f16 v[44:47], v[94:97], v[106:109], v[44:47]
	s_waitcnt vmcnt(0)
	ds_write_b128 v20, v[154:157] offset:49152
	v_mfma_f32_16x16x32_f16 v[78:81], v[94:97], v[110:113], v[78:81]
	v_mfma_f32_16x16x32_f16 v[82:85], v[118:121], v[106:109], v[82:85]
	v_mfma_f32_16x16x32_f16 v[86:89], v[118:121], v[110:113], v[86:89]
	s_waitcnt lgkmcnt(2)
	v_mfma_f32_16x16x32_f16 v[28:31], v[122:125], v[106:109], v[28:31]
	ds_read_b128 v[106:109], v23 offset:4096
	v_mfma_f32_16x16x32_f16 v[32:35], v[122:125], v[110:113], v[32:35]
	ds_read_b128 v[110:113], v23 offset:6144
	s_waitcnt lgkmcnt(1)
	v_mfma_f32_16x16x32_f16 v[98:101], v[58:61], v[106:109], v[98:101]
	s_waitcnt lgkmcnt(0)
	v_mfma_f32_16x16x32_f16 v[52:55], v[58:61], v[110:113], v[52:55]
	global_load_dwordx4 v[58:61], v[0:1], off offset:3072
	v_mfma_f32_16x16x32_f16 v[102:105], v[94:97], v[106:109], v[102:105]
	v_mfma_f32_16x16x32_f16 v[24:27], v[94:97], v[110:113], v[24:27]
	v_mfma_f32_16x16x32_f16 v[114:117], v[118:121], v[106:109], v[114:117]
	v_mfma_f32_16x16x32_f16 v[40:43], v[118:121], v[110:113], v[40:43]
	v_mfma_f32_16x16x32_f16 v[70:73], v[122:125], v[106:109], v[70:73]
	global_load_dwordx4 v[106:109], v[2:3], off offset:3072
	global_load_dwordx4 v[134:137], v[4:5], off offset:3072
	global_load_dwordx4 v[158:161], v[14:15], off offset:3072
	global_load_dwordx4 v[94:97], v[10:11], off offset:3072
	global_load_dwordx4 v[162:165], v[12:13], off offset:3072
	global_load_dwordx4 v[166:169], v[8:9], off offset:3072
	global_load_dwordx4 v[190:193], v[6:7], off offset:3072
	s_waitcnt lgkmcnt(0)
	s_barrier
; #define GL_LOAD(s_, kt_) if (VAR != 1) { a##s_##0 = GL_A(0, kt_); a##s_##1 = GL_A(1, kt_); a##s_##2 = GL_A(2, kt_); a##s_##3 = GL_A(3, kt_); b##s_##0 = GL_B(0, kt_); b##s_##1 = GL_B(1, kt_); b##s_##2 = GL_B(2, kt_); b##s_##3 = GL_B(3, kt_); }
; #define LDS_STORE(s_, buf_) if (VAR != 2) { LDS_ST1(sA, 0, buf_, a##s_##0) LDS_ST1(sA, 1, buf_, a##s_##1) LDS_ST1(sA, 2, buf_, a##s_##2) LDS_ST1(sA, 3, buf_, a##s_##3) LDS_ST1(sB, 0, buf_, b##s_##0) LDS_ST1(sB, 1, buf_, b##s_##1) LDS_ST1(sB, 2, buf_, b##s_##2) LDS_ST1(sB, 3, buf_, b##s_##3) }
;     ...
;   GL_LOAD(0, 0)
;   GL_LOAD(1, 1)
;   LDS_STORE(0, 0)
;   if (VAR != 4) __syncthreads();
; #pragma unroll
;   for (int kt = 0; kt < nk; kt += 2) {
;     if (kt + 2 < nk) { GL_LOAD(0, kt + 2) }
;     MMA_TILE(0)
;     LDS_STORE(1, 1)
;     if (VAR != 4) __syncthreads();
;     if (kt + 3 < nk) { GL_LOAD(1, kt + 3) }
;     MMA_TILE(1)
;     if (kt + 2 < nk) { LDS_STORE(0, 0) }
;     if (VAR != 4) __syncthreads();
	v_mfma_f32_16x16x32_f16 v[48:51], v[122:125], v[110:113], v[48:51]
	ds_read_b128 v[62:65], v16 offset:49152
	ds_read_b128 v[90:93], v21 offset:16384
	s_waitcnt lgkmcnt(0)
	v_mfma_f32_16x16x32_f16 v[36:39], v[62:65], v[90:93], v[36:39]
	ds_read_b128 v[74:77], v16 offset:51200
	ds_read_b128 v[110:113], v21 offset:18432
	s_waitcnt lgkmcnt(0)
	v_mfma_f32_16x16x32_f16 v[66:69], v[62:65], v[110:113], v[66:69]
	ds_read_b128 v[118:121], v16 offset:53248
	v_mfma_f32_16x16x32_f16 v[44:47], v[74:77], v[90:93], v[44:47]
	ds_read_b128 v[122:125], v16 offset:55296
	v_mfma_f32_16x16x32_f16 v[78:81], v[74:77], v[110:113], v[78:81]
	s_waitcnt vmcnt(7)
	ds_write_b128 v17, v[58:61]
	s_waitcnt lgkmcnt(2)
	v_mfma_f32_16x16x32_f16 v[82:85], v[118:121], v[90:93], v[82:85]
	s_waitcnt vmcnt(6)
	ds_write_b128 v18, v[106:109]
	v_mfma_f32_16x16x32_f16 v[86:89], v[118:121], v[110:113], v[86:89]
	s_waitcnt vmcnt(5)
	ds_write_b128 v19, v[134:137]
	s_waitcnt lgkmcnt(3)
	v_mfma_f32_16x16x32_f16 v[28:31], v[122:125], v[90:93], v[28:31]
	ds_read_b128 v[90:93], v21 offset:20480
	v_mfma_f32_16x16x32_f16 v[32:35], v[122:125], v[110:113], v[32:35]
	ds_read_b128 v[110:113], v21 offset:22528
	s_waitcnt lgkmcnt(1)
	v_mfma_f32_16x16x32_f16 v[98:101], v[62:65], v[90:93], v[98:101]
	s_waitcnt vmcnt(4)
	ds_write_b128 v20, v[158:161]
	s_waitcnt lgkmcnt(1)
	v_mfma_f32_16x16x32_f16 v[52:55], v[62:65], v[110:113], v[52:55]
	ds_read_b128 v[62:65], v22 offset:49152
	v_mfma_f32_16x16x32_f16 v[102:105], v[74:77], v[90:93], v[102:105]
	s_waitcnt vmcnt(3)
	ds_write_b128 v17, v[94:97] offset:32768
	v_mfma_f32_16x16x32_f16 v[24:27], v[74:77], v[110:113], v[24:27]
	ds_read_b128 v[74:77], v22 offset:51200
	v_mfma_f32_16x16x32_f16 v[114:117], v[118:121], v[90:93], v[114:117]
	s_waitcnt vmcnt(2)
	ds_write_b128 v18, v[162:165] offset:32768
	v_mfma_f32_16x16x32_f16 v[40:43], v[118:121], v[110:113], v[40:43]
	ds_read_b128 v[118:121], v22 offset:53248
	v_mfma_f32_16x16x32_f16 v[70:73], v[122:125], v[90:93], v[70:73]
	ds_read_b128 v[90:93], v23 offset:16384
	v_mfma_f32_16x16x32_f16 v[48:51], v[122:125], v[110:113], v[48:51]
	ds_read_b128 v[110:113], v23 offset:18432
	s_waitcnt lgkmcnt(1)
	v_mfma_f32_16x16x32_f16 v[36:39], v[62:65], v[90:93], v[36:39]
	ds_read_b128 v[122:125], v22 offset:55296
	s_waitcnt lgkmcnt(1)
	v_mfma_f32_16x16x32_f16 v[66:69], v[62:65], v[110:113], v[66:69]
	s_waitcnt vmcnt(1)
	ds_write_b128 v19, v[166:169] offset:32768
	v_mfma_f32_16x16x32_f16 v[44:47], v[74:77], v[90:93], v[44:47]
	s_waitcnt vmcnt(0)
	ds_write_b128 v20, v[190:193] offset:32768
	v_mfma_f32_16x16x32_f16 v[78:81], v[74:77], v[110:113], v[78:81]
	v_mfma_f32_16x16x32_f16 v[82:85], v[118:121], v[90:93], v[82:85]
	v_mfma_f32_16x16x32_f16 v[86:89], v[118:121], v[110:113], v[86:89]
	s_waitcnt lgkmcnt(2)
	v_mfma_f32_16x16x32_f16 v[28:31], v[122:125], v[90:93], v[28:31]
	ds_read_b128 v[90:93], v23 offset:20480
	v_mfma_f32_16x16x32_f16 v[32:35], v[122:125], v[110:113], v[32:35]
	ds_read_b128 v[110:113], v23 offset:22528
	s_waitcnt lgkmcnt(1)
	v_mfma_f32_16x16x32_f16 v[98:101], v[62:65], v[90:93], v[98:101]
	s_waitcnt lgkmcnt(0)
	v_mfma_f32_16x16x32_f16 v[52:55], v[62:65], v[110:113], v[52:55]
	global_load_dwordx4 v[62:65], v[0:1], off offset:3200
	v_mfma_f32_16x16x32_f16 v[102:105], v[74:77], v[90:93], v[102:105]
	v_mfma_f32_16x16x32_f16 v[24:27], v[74:77], v[110:113], v[24:27]
	v_mfma_f32_16x16x32_f16 v[114:117], v[118:121], v[90:93], v[114:117]
	v_mfma_f32_16x16x32_f16 v[40:43], v[118:121], v[110:113], v[40:43]
	v_mfma_f32_16x16x32_f16 v[70:73], v[122:125], v[90:93], v[70:73]
	global_load_dwordx4 v[90:93], v[2:3], off offset:3200
	global_load_dwordx4 v[126:129], v[4:5], off offset:3200
	global_load_dwordx4 v[130:133], v[14:15], off offset:3200
	global_load_dwordx4 v[74:77], v[10:11], off offset:3200
	global_load_dwordx4 v[138:141], v[12:13], off offset:3200
	global_load_dwordx4 v[142:145], v[8:9], off offset:3200
	global_load_dwordx4 v[154:157], v[6:7], off offset:3200
	s_waitcnt lgkmcnt(0)
	s_barrier
	v_mfma_f32_16x16x32_f16 v[48:51], v[122:125], v[110:113], v[48:51]
	ds_read_b128 v[58:61], v16 offset:32768
	ds_read_b128 v[106:109], v21
	s_waitcnt lgkmcnt(0)
	v_mfma_f32_16x16x32_f16 v[36:39], v[58:61], v[106:109], v[36:39]
	ds_read_b128 v[94:97], v16 offset:34816
	ds_read_b128 v[110:113], v21 offset:2048
	s_waitcnt lgkmcnt(0)
	v_mfma_f32_16x16x32_f16 v[66:69], v[58:61], v[110:113], v[66:69]
	ds_read_b128 v[118:121], v16 offset:36864
	v_mfma_f32_16x16x32_f16 v[44:47], v[94:97], v[106:109], v[44:47]
	ds_read_b128 v[122:125], v16 offset:38912
	v_mfma_f32_16x16x32_f16 v[78:81], v[94:97], v[110:113], v[78:81]
	s_waitcnt vmcnt(7)
	ds_write_b128 v17, v[62:65] offset:16384
	s_waitcnt lgkmcnt(2)
	v_mfma_f32_16x16x32_f16 v[82:85], v[118:121], v[106:109], v[82:85]
	s_waitcnt vmcnt(6)
	ds_write_b128 v18, v[90:93] offset:16384
	v_mfma_f32_16x16x32_f16 v[86:89], v[118:121], v[110:113], v[86:89]
	s_waitcnt vmcnt(5)
	ds_write_b128 v19, v[126:129] offset:16384
	s_waitcnt lgkmcnt(3)
	v_mfma_f32_16x16x32_f16 v[28:31], v[122:125], v[106:109], v[28:31]
	ds_read_b128 v[106:109], v21 offset:4096
	v_mfma_f32_16x16x32_f16 v[32:35], v[122:125], v[110:113], v[32:35]
	ds_read_b128 v[110:113], v21 offset:6144
	s_waitcnt lgkmcnt(1)
	v_mfma_f32_16x16x32_f16 v[98:101], v[58:61], v[106:109], v[98:101]
	s_waitcnt vmcnt(4)
	ds_write_b128 v20, v[130:133] offset:16384
	s_waitcnt lgkmcnt(1)
	v_mfma_f32_16x16x32_f16 v[52:55], v[58:61], v[110:113], v[52:55]
	ds_read_b128 v[58:61], v22 offset:32768
	v_mfma_f32_16x16x32_f16 v[102:105], v[94:97], v[106:109], v[102:105]
	s_waitcnt vmcnt(3)
; #define GL_LOAD(s_, kt_) if (VAR != 1) { a##s_##0 = GL_A(0, kt_); a##s_##1 = GL_A(1, kt_); a##s_##2 = GL_A(2, kt_); a##s_##3 = GL_A(3, kt_); b##s_##0 = GL_B(0, kt_); b##s_##1 = GL_B(1, kt_); b##s_##2 = GL_B(2, kt_); b##s_##3 = GL_B(3, kt_); }
; #define LDS_STORE(s_, buf_) if (VAR != 2) { LDS_ST1(sA, 0, buf_, a##s_##0) LDS_ST1(sA, 1, buf_, a##s_##1) LDS_ST1(sA, 2, buf_, a##s_##2) LDS_ST1(sA, 3, buf_, a##s_##3) LDS_ST1(sB, 0, buf_, b##s_##0) LDS_ST1(sB, 1, buf_, b##s_##1) LDS_ST1(sB, 2, buf_, b##s_##2) LDS_ST1(sB, 3, buf_, b##s_##3) }
;     ...
;   GL_LOAD(0, 0)
;   GL_LOAD(1, 1)
;   LDS_STORE(0, 0)
;   if (VAR != 4) __syncthreads();
; #pragma unroll
;   for (int kt = 0; kt < nk; kt += 2) {
;     if (kt + 2 < nk) { GL_LOAD(0, kt + 2) }
;     MMA_TILE(0)
;     LDS_STORE(1, 1)
;     if (VAR != 4) __syncthreads();
;     if (kt + 3 < nk) { GL_LOAD(1, kt + 3) }
;     MMA_TILE(1)
;     if (kt + 2 < nk) { LDS_STORE(0, 0) }
;     if (VAR != 4) __syncthreads();
	ds_write_b128 v17, v[74:77] offset:49152
	v_mfma_f32_16x16x32_f16 v[24:27], v[94:97], v[110:113], v[24:27]
	ds_read_b128 v[94:97], v22 offset:34816
	v_mfma_f32_16x16x32_f16 v[114:117], v[118:121], v[106:109], v[114:117]
	s_waitcnt vmcnt(2)
	ds_write_b128 v18, v[138:141] offset:49152
	v_mfma_f32_16x16x32_f16 v[40:43], v[118:121], v[110:113], v[40:43]
	ds_read_b128 v[118:121], v22 offset:36864
	v_mfma_f32_16x16x32_f16 v[70:73], v[122:125], v[106:109], v[70:73]
	ds_read_b128 v[106:109], v23
	v_mfma_f32_16x16x32_f16 v[48:51], v[122:125], v[110:113], v[48:51]
	ds_read_b128 v[110:113], v23 offset:2048
	s_waitcnt lgkmcnt(1)
	v_mfma_f32_16x16x32_f16 v[36:39], v[58:61], v[106:109], v[36:39]
	ds_read_b128 v[122:125], v22 offset:38912
	s_waitcnt lgkmcnt(1)
	v_mfma_f32_16x16x32_f16 v[66:69], v[58:61], v[110:113], v[66:69]
	s_waitcnt vmcnt(1)
	ds_write_b128 v19, v[142:145] offset:49152
	v_mfma_f32_16x16x32_f16 v[44:47], v[94:97], v[106:109], v[44:47]
	s_waitcnt vmcnt(0)
	ds_write_b128 v20, v[154:157] offset:49152
	v_mfma_f32_16x16x32_f16 v[78:81], v[94:97], v[110:113], v[78:81]
	v_mfma_f32_16x16x32_f16 v[82:85], v[118:121], v[106:109], v[82:85]
	v_mfma_f32_16x16x32_f16 v[86:89], v[118:121], v[110:113], v[86:89]
	s_waitcnt lgkmcnt(2)
	v_mfma_f32_16x16x32_f16 v[28:31], v[122:125], v[106:109], v[28:31]
	ds_read_b128 v[106:109], v23 offset:4096
	v_mfma_f32_16x16x32_f16 v[32:35], v[122:125], v[110:113], v[32:35]
	ds_read_b128 v[110:113], v23 offset:6144
	s_waitcnt lgkmcnt(1)
	v_mfma_f32_16x16x32_f16 v[98:101], v[58:61], v[106:109], v[98:101]
	s_waitcnt lgkmcnt(0)
	v_mfma_f32_16x16x32_f16 v[52:55], v[58:61], v[110:113], v[52:55]
	global_load_dwordx4 v[58:61], v[0:1], off offset:3328
	v_mfma_f32_16x16x32_f16 v[102:105], v[94:97], v[106:109], v[102:105]
	v_mfma_f32_16x16x32_f16 v[24:27], v[94:97], v[110:113], v[24:27]
	v_mfma_f32_16x16x32_f16 v[114:117], v[118:121], v[106:109], v[114:117]
	v_mfma_f32_16x16x32_f16 v[40:43], v[118:121], v[110:113], v[40:43]
	v_mfma_f32_16x16x32_f16 v[70:73], v[122:125], v[106:109], v[70:73]
	global_load_dwordx4 v[106:109], v[2:3], off offset:3328
	global_load_dwordx4 v[134:137], v[4:5], off offset:3328
	global_load_dwordx4 v[158:161], v[14:15], off offset:3328
	global_load_dwordx4 v[94:97], v[10:11], off offset:3328
	global_load_dwordx4 v[162:165], v[12:13], off offset:3328
	global_load_dwordx4 v[166:169], v[8:9], off offset:3328
	global_load_dwordx4 v[190:193], v[6:7], off offset:3328
	s_waitcnt lgkmcnt(0)
	s_barrier
	v_mfma_f32_16x16x32_f16 v[48:51], v[122:125], v[110:113], v[48:51]
	ds_read_b128 v[62:65], v16 offset:49152
	ds_read_b128 v[90:93], v21 offset:16384
	s_waitcnt lgkmcnt(0)
	v_mfma_f32_16x16x32_f16 v[36:39], v[62:65], v[90:93], v[36:39]
	ds_read_b128 v[74:77], v16 offset:51200
	ds_read_b128 v[110:113], v21 offset:18432
	s_waitcnt lgkmcnt(0)
	v_mfma_f32_16x16x32_f16 v[66:69], v[62:65], v[110:113], v[66:69]
	ds_read_b128 v[118:121], v16 offset:53248
	v_mfma_f32_16x16x32_f16 v[44:47], v[74:77], v[90:93], v[44:47]
	ds_read_b128 v[122:125], v16 offset:55296
	v_mfma_f32_16x16x32_f16 v[78:81], v[74:77], v[110:113], v[78:81]
	s_waitcnt vmcnt(7)
	ds_write_b128 v17, v[58:61]
	s_waitcnt lgkmcnt(2)
	v_mfma_f32_16x16x32_f16 v[82:85], v[118:121], v[90:93], v[82:85]
	s_waitcnt vmcnt(6)
	ds_write_b128 v18, v[106:109]
	v_mfma_f32_16x16x32_f16 v[86:89], v[118:121], v[110:113], v[86:89]
	s_waitcnt vmcnt(5)
	ds_write_b128 v19, v[134:137]
	s_waitcnt lgkmcnt(3)
	v_mfma_f32_16x16x32_f16 v[28:31], v[122:125], v[90:93], v[28:31]
	ds_read_b128 v[90:93], v21 offset:20480
	v_mfma_f32_16x16x32_f16 v[32:35], v[122:125], v[110:113], v[32:35]
	ds_read_b128 v[110:113], v21 offset:22528
	s_waitcnt lgkmcnt(1)
	v_mfma_f32_16x16x32_f16 v[98:101], v[62:65], v[90:93], v[98:101]
	s_waitcnt vmcnt(4)
	ds_write_b128 v20, v[158:161]
	s_waitcnt lgkmcnt(1)
	v_mfma_f32_16x16x32_f16 v[52:55], v[62:65], v[110:113], v[52:55]
	ds_read_b128 v[62:65], v22 offset:49152
	v_mfma_f32_16x16x32_f16 v[102:105], v[74:77], v[90:93], v[102:105]
	s_waitcnt vmcnt(3)
	ds_write_b128 v17, v[94:97] offset:32768
	v_mfma_f32_16x16x32_f16 v[24:27], v[74:77], v[110:113], v[24:27]
	ds_read_b128 v[74:77], v22 offset:51200
	v_mfma_f32_16x16x32_f16 v[114:117], v[118:121], v[90:93], v[114:117]
	s_waitcnt vmcnt(2)
	ds_write_b128 v18, v[162:165] offset:32768
	v_mfma_f32_16x16x32_f16 v[40:43], v[118:121], v[110:113], v[40:43]
	ds_read_b128 v[118:121], v22 offset:53248
	v_mfma_f32_16x16x32_f16 v[70:73], v[122:125], v[90:93], v[70:73]
	ds_read_b128 v[90:93], v23 offset:16384
	v_mfma_f32_16x16x32_f16 v[48:51], v[122:125], v[110:113], v[48:51]
	ds_read_b128 v[110:113], v23 offset:18432
	s_waitcnt lgkmcnt(1)
	v_mfma_f32_16x16x32_f16 v[36:39], v[62:65], v[90:93], v[36:39]
	ds_read_b128 v[122:125], v22 offset:55296
	s_waitcnt lgkmcnt(1)
	v_mfma_f32_16x16x32_f16 v[66:69], v[62:65], v[110:113], v[66:69]
	s_waitcnt vmcnt(1)
	ds_write_b128 v19, v[166:169] offset:32768
	v_mfma_f32_16x16x32_f16 v[44:47], v[74:77], v[90:93], v[44:47]
	s_waitcnt vmcnt(0)
	ds_write_b128 v20, v[190:193] offset:32768
	v_mfma_f32_16x16x32_f16 v[78:81], v[74:77], v[110:113], v[78:81]
	v_mfma_f32_16x16x32_f16 v[82:85], v[118:121], v[90:93], v[82:85]
	v_mfma_f32_16x16x32_f16 v[86:89], v[118:121], v[110:113], v[86:89]
	s_waitcnt lgkmcnt(2)
	v_mfma_f32_16x16x32_f16 v[28:31], v[122:125], v[90:93], v[28:31]
	ds_read_b128 v[90:93], v23 offset:20480
	v_mfma_f32_16x16x32_f16 v[32:35], v[122:125], v[110:113], v[32:35]
	ds_read_b128 v[110:113], v23 offset:22528
	s_waitcnt lgkmcnt(1)
	v_mfma_f32_16x16x32_f16 v[98:101], v[62:65], v[90:93], v[98:101]
	s_waitcnt lgkmcnt(0)
	v_mfma_f32_16x16x32_f16 v[52:55], v[62:65], v[110:113], v[52:55]
	global_load_dwordx4 v[62:65], v[0:1], off offset:3456
	v_mfma_f32_16x16x32_f16 v[102:105], v[74:77], v[90:93], v[102:105]
	v_mfma_f32_16x16x32_f16 v[24:27], v[74:77], v[110:113], v[24:27]
	v_mfma_f32_16x16x32_f16 v[114:117], v[118:121], v[90:93], v[114:117]
	v_mfma_f32_16x16x32_f16 v[40:43], v[118:121], v[110:113], v[40:43]
	v_mfma_f32_16x16x32_f16 v[70:73], v[122:125], v[90:93], v[70:73]
	global_load_dwordx4 v[90:93], v[2:3], off offset:3456
	global_load_dwordx4 v[126:129], v[4:5], off offset:3456
	global_load_dwordx4 v[130:133], v[14:15], off offset:3456
	global_load_dwordx4 v[74:77], v[10:11], off offset:3456
	global_load_dwordx4 v[138:141], v[12:13], off offset:3456
	global_load_dwordx4 v[142:145], v[8:9], off offset:3456
	global_load_dwordx4 v[154:157], v[6:7], off offset:3456
	s_waitcnt lgkmcnt(0)
	s_barrier
; #define GL_LOAD(s_, kt_) if (VAR != 1) { a##s_##0 = GL_A(0, kt_); a##s_##1 = GL_A(1, kt_); a##s_##2 = GL_A(2, kt_); a##s_##3 = GL_A(3, kt_); b##s_##0 = GL_B(0, kt_); b##s_##1 = GL_B(1, kt_); b##s_##2 = GL_B(2, kt_); b##s_##3 = GL_B(3, kt_); }
; #define LDS_STORE(s_, buf_) if (VAR != 2) { LDS_ST1(sA, 0, buf_, a##s_##0) LDS_ST1(sA, 1, buf_, a##s_##1) LDS_ST1(sA, 2, buf_, a##s_##2) LDS_ST1(sA, 3, buf_, a##s_##3) LDS_ST1(sB, 0, buf_, b##s_##0) LDS_ST1(sB, 1, buf_, b##s_##1) LDS_ST1(sB, 2, buf_, b##s_##2) LDS_ST1(sB, 3, buf_, b##s_##3) }
;     ...
;   GL_LOAD(0, 0)
;   GL_LOAD(1, 1)
;   LDS_STORE(0, 0)
;   if (VAR != 4) __syncthreads();
; #pragma unroll
;   for (int kt = 0; kt < nk; kt += 2) {
;     if (kt + 2 < nk) { GL_LOAD(0, kt + 2) }
;     MMA_TILE(0)
;     LDS_STORE(1, 1)
;     if (VAR != 4) __syncthreads();
;     if (kt + 3 < nk) { GL_LOAD(1, kt + 3) }
;     MMA_TILE(1)
;     if (kt + 2 < nk) { LDS_STORE(0, 0) }
;     if (VAR != 4) __syncthreads();
	v_mfma_f32_16x16x32_f16 v[48:51], v[122:125], v[110:113], v[48:51]
	ds_read_b128 v[58:61], v16 offset:32768
	ds_read_b128 v[106:109], v21
	s_waitcnt lgkmcnt(0)
	v_mfma_f32_16x16x32_f16 v[36:39], v[58:61], v[106:109], v[36:39]
	ds_read_b128 v[94:97], v16 offset:34816
	ds_read_b128 v[110:113], v21 offset:2048
	s_waitcnt lgkmcnt(0)
	v_mfma_f32_16x16x32_f16 v[66:69], v[58:61], v[110:113], v[66:69]
	ds_read_b128 v[118:121], v16 offset:36864
	v_mfma_f32_16x16x32_f16 v[44:47], v[94:97], v[106:109], v[44:47]
	ds_read_b128 v[122:125], v16 offset:38912
	v_mfma_f32_16x16x32_f16 v[78:81], v[94:97], v[110:113], v[78:81]
	s_waitcnt vmcnt(7)
	ds_write_b128 v17, v[62:65] offset:16384
	s_waitcnt lgkmcnt(2)
	v_mfma_f32_16x16x32_f16 v[82:85], v[118:121], v[106:109], v[82:85]
	s_waitcnt vmcnt(6)
	ds_write_b128 v18, v[90:93] offset:16384
	v_mfma_f32_16x16x32_f16 v[86:89], v[118:121], v[110:113], v[86:89]
	s_waitcnt vmcnt(5)
	ds_write_b128 v19, v[126:129] offset:16384
	s_waitcnt lgkmcnt(3)
	v_mfma_f32_16x16x32_f16 v[28:31], v[122:125], v[106:109], v[28:31]
	ds_read_b128 v[106:109], v21 offset:4096
	v_mfma_f32_16x16x32_f16 v[32:35], v[122:125], v[110:113], v[32:35]
	ds_read_b128 v[110:113], v21 offset:6144
	s_waitcnt lgkmcnt(1)
	v_mfma_f32_16x16x32_f16 v[98:101], v[58:61], v[106:109], v[98:101]
	s_waitcnt vmcnt(4)
	ds_write_b128 v20, v[130:133] offset:16384
	s_waitcnt lgkmcnt(1)
	v_mfma_f32_16x16x32_f16 v[52:55], v[58:61], v[110:113], v[52:55]
	ds_read_b128 v[58:61], v22 offset:32768
	v_mfma_f32_16x16x32_f16 v[102:105], v[94:97], v[106:109], v[102:105]
	s_waitcnt vmcnt(3)
	ds_write_b128 v17, v[74:77] offset:49152
	v_mfma_f32_16x16x32_f16 v[24:27], v[94:97], v[110:113], v[24:27]
	ds_read_b128 v[94:97], v22 offset:34816
	v_mfma_f32_16x16x32_f16 v[114:117], v[118:121], v[106:109], v[114:117]
	s_waitcnt vmcnt(2)
	ds_write_b128 v18, v[138:141] offset:49152
	v_mfma_f32_16x16x32_f16 v[40:43], v[118:121], v[110:113], v[40:43]
	ds_read_b128 v[118:121], v22 offset:36864
	v_mfma_f32_16x16x32_f16 v[70:73], v[122:125], v[106:109], v[70:73]
	ds_read_b128 v[106:109], v23
	v_mfma_f32_16x16x32_f16 v[48:51], v[122:125], v[110:113], v[48:51]
	ds_read_b128 v[110:113], v23 offset:2048
	s_waitcnt lgkmcnt(1)
	v_mfma_f32_16x16x32_f16 v[36:39], v[58:61], v[106:109], v[36:39]
	ds_read_b128 v[122:125], v22 offset:38912
	s_waitcnt lgkmcnt(1)
	v_mfma_f32_16x16x32_f16 v[66:69], v[58:61], v[110:113], v[66:69]
	s_waitcnt vmcnt(1)
	ds_write_b128 v19, v[142:145] offset:49152
	v_mfma_f32_16x16x32_f16 v[44:47], v[94:97], v[106:109], v[44:47]
	s_waitcnt vmcnt(0)
	ds_write_b128 v20, v[154:157] offset:49152
	v_mfma_f32_16x16x32_f16 v[78:81], v[94:97], v[110:113], v[78:81]
	v_mfma_f32_16x16x32_f16 v[82:85], v[118:121], v[106:109], v[82:85]
	v_mfma_f32_16x16x32_f16 v[86:89], v[118:121], v[110:113], v[86:89]
	s_waitcnt lgkmcnt(2)
	v_mfma_f32_16x16x32_f16 v[28:31], v[122:125], v[106:109], v[28:31]
	ds_read_b128 v[106:109], v23 offset:4096
	v_mfma_f32_16x16x32_f16 v[32:35], v[122:125], v[110:113], v[32:35]
	ds_read_b128 v[110:113], v23 offset:6144
	s_waitcnt lgkmcnt(1)
	v_mfma_f32_16x16x32_f16 v[98:101], v[58:61], v[106:109], v[98:101]
	s_waitcnt lgkmcnt(0)
	v_mfma_f32_16x16x32_f16 v[52:55], v[58:61], v[110:113], v[52:55]
	global_load_dwordx4 v[58:61], v[0:1], off offset:3584
	v_mfma_f32_16x16x32_f16 v[102:105], v[94:97], v[106:109], v[102:105]
	v_mfma_f32_16x16x32_f16 v[24:27], v[94:97], v[110:113], v[24:27]
	v_mfma_f32_16x16x32_f16 v[114:117], v[118:121], v[106:109], v[114:117]
	v_mfma_f32_16x16x32_f16 v[40:43], v[118:121], v[110:113], v[40:43]
	v_mfma_f32_16x16x32_f16 v[70:73], v[122:125], v[106:109], v[70:73]
	global_load_dwordx4 v[106:109], v[2:3], off offset:3584
	global_load_dwordx4 v[134:137], v[4:5], off offset:3584
	global_load_dwordx4 v[158:161], v[14:15], off offset:3584
	global_load_dwordx4 v[94:97], v[10:11], off offset:3584
	global_load_dwordx4 v[162:165], v[12:13], off offset:3584
	global_load_dwordx4 v[166:169], v[8:9], off offset:3584
	global_load_dwordx4 v[190:193], v[6:7], off offset:3584
	s_waitcnt lgkmcnt(0)
	s_barrier
	v_mfma_f32_16x16x32_f16 v[48:51], v[122:125], v[110:113], v[48:51]
	ds_read_b128 v[62:65], v16 offset:49152
	ds_read_b128 v[90:93], v21 offset:16384
	s_waitcnt lgkmcnt(0)
	v_mfma_f32_16x16x32_f16 v[36:39], v[62:65], v[90:93], v[36:39]
	ds_read_b128 v[74:77], v16 offset:51200
	ds_read_b128 v[110:113], v21 offset:18432
	s_waitcnt lgkmcnt(0)
	v_mfma_f32_16x16x32_f16 v[66:69], v[62:65], v[110:113], v[66:69]
	ds_read_b128 v[118:121], v16 offset:53248
	v_mfma_f32_16x16x32_f16 v[44:47], v[74:77], v[90:93], v[44:47]
	ds_read_b128 v[122:125], v16 offset:55296
	v_mfma_f32_16x16x32_f16 v[78:81], v[74:77], v[110:113], v[78:81]
	s_waitcnt vmcnt(7)
	ds_write_b128 v17, v[58:61]
	s_waitcnt lgkmcnt(2)
	v_mfma_f32_16x16x32_f16 v[82:85], v[118:121], v[90:93], v[82:85]
	s_waitcnt vmcnt(6)
	ds_write_b128 v18, v[106:109]
	v_mfma_f32_16x16x32_f16 v[86:89], v[118:121], v[110:113], v[86:89]
	s_waitcnt vmcnt(5)
	ds_write_b128 v19, v[134:137]
	s_waitcnt lgkmcnt(3)
	v_mfma_f32_16x16x32_f16 v[28:31], v[122:125], v[90:93], v[28:31]
	ds_read_b128 v[90:93], v21 offset:20480
	v_mfma_f32_16x16x32_f16 v[32:35], v[122:125], v[110:113], v[32:35]
	ds_read_b128 v[110:113], v21 offset:22528
	s_waitcnt lgkmcnt(1)
	v_mfma_f32_16x16x32_f16 v[98:101], v[62:65], v[90:93], v[98:101]
	s_waitcnt vmcnt(4)
	ds_write_b128 v20, v[158:161]
	s_waitcnt lgkmcnt(1)
	v_mfma_f32_16x16x32_f16 v[52:55], v[62:65], v[110:113], v[52:55]
	ds_read_b128 v[62:65], v22 offset:49152
	v_mfma_f32_16x16x32_f16 v[102:105], v[74:77], v[90:93], v[102:105]
	s_waitcnt vmcnt(3)
; #define GL_LOAD(s_, kt_) if (VAR != 1) { a##s_##0 = GL_A(0, kt_); a##s_##1 = GL_A(1, kt_); a##s_##2 = GL_A(2, kt_); a##s_##3 = GL_A(3, kt_); b##s_##0 = GL_B(0, kt_); b##s_##1 = GL_B(1, kt_); b##s_##2 = GL_B(2, kt_); b##s_##3 = GL_B(3, kt_); }
; #define LDS_STORE(s_, buf_) if (VAR != 2) { LDS_ST1(sA, 0, buf_, a##s_##0) LDS_ST1(sA, 1, buf_, a##s_##1) LDS_ST1(sA, 2, buf_, a##s_##2) LDS_ST1(sA, 3, buf_, a##s_##3) LDS_ST1(sB, 0, buf_, b##s_##0) LDS_ST1(sB, 1, buf_, b##s_##1) LDS_ST1(sB, 2, buf_, b##s_##2) LDS_ST1(sB, 3, buf_, b##s_##3) }
;     ...
;   GL_LOAD(0, 0)
;   GL_LOAD(1, 1)
;   LDS_STORE(0, 0)
;   if (VAR != 4) __syncthreads();
; #pragma unroll
;   for (int kt = 0; kt < nk; kt += 2) {
;     if (kt + 2 < nk) { GL_LOAD(0, kt + 2) }
;     MMA_TILE(0)
;     LDS_STORE(1, 1)
;     if (VAR != 4) __syncthreads();
;     if (kt + 3 < nk) { GL_LOAD(1, kt + 3) }
;     MMA_TILE(1)
;     if (kt + 2 < nk) { LDS_STORE(0, 0) }
;     if (VAR != 4) __syncthreads();
	ds_write_b128 v17, v[94:97] offset:32768
	v_mfma_f32_16x16x32_f16 v[24:27], v[74:77], v[110:113], v[24:27]
	ds_read_b128 v[74:77], v22 offset:51200
	v_mfma_f32_16x16x32_f16 v[114:117], v[118:121], v[90:93], v[114:117]
	s_waitcnt vmcnt(2)
	ds_write_b128 v18, v[162:165] offset:32768
	v_mfma_f32_16x16x32_f16 v[40:43], v[118:121], v[110:113], v[40:43]
	ds_read_b128 v[118:121], v22 offset:53248
	v_mfma_f32_16x16x32_f16 v[70:73], v[122:125], v[90:93], v[70:73]
	ds_read_b128 v[90:93], v23 offset:16384
	v_mfma_f32_16x16x32_f16 v[48:51], v[122:125], v[110:113], v[48:51]
	ds_read_b128 v[110:113], v23 offset:18432
	s_waitcnt lgkmcnt(1)
	v_mfma_f32_16x16x32_f16 v[36:39], v[62:65], v[90:93], v[36:39]
	ds_read_b128 v[122:125], v22 offset:55296
	s_waitcnt lgkmcnt(1)
	v_mfma_f32_16x16x32_f16 v[66:69], v[62:65], v[110:113], v[66:69]
	s_waitcnt vmcnt(1)
	ds_write_b128 v19, v[166:169] offset:32768
	v_mfma_f32_16x16x32_f16 v[44:47], v[74:77], v[90:93], v[44:47]
	s_waitcnt vmcnt(0)
	ds_write_b128 v20, v[190:193] offset:32768
	v_mfma_f32_16x16x32_f16 v[78:81], v[74:77], v[110:113], v[78:81]
	v_mfma_f32_16x16x32_f16 v[82:85], v[118:121], v[90:93], v[82:85]
	v_mfma_f32_16x16x32_f16 v[86:89], v[118:121], v[110:113], v[86:89]
	s_waitcnt lgkmcnt(2)
	v_mfma_f32_16x16x32_f16 v[28:31], v[122:125], v[90:93], v[28:31]
	ds_read_b128 v[90:93], v23 offset:20480
	v_mfma_f32_16x16x32_f16 v[32:35], v[122:125], v[110:113], v[32:35]
	ds_read_b128 v[110:113], v23 offset:22528
	s_waitcnt lgkmcnt(1)
	v_mfma_f32_16x16x32_f16 v[98:101], v[62:65], v[90:93], v[98:101]
	s_waitcnt lgkmcnt(0)
	v_mfma_f32_16x16x32_f16 v[52:55], v[62:65], v[110:113], v[52:55]
	global_load_dwordx4 v[62:65], v[0:1], off offset:3712
	v_mfma_f32_16x16x32_f16 v[102:105], v[74:77], v[90:93], v[102:105]
	v_mfma_f32_16x16x32_f16 v[24:27], v[74:77], v[110:113], v[24:27]
	v_mfma_f32_16x16x32_f16 v[114:117], v[118:121], v[90:93], v[114:117]
	v_mfma_f32_16x16x32_f16 v[40:43], v[118:121], v[110:113], v[40:43]
	v_mfma_f32_16x16x32_f16 v[70:73], v[122:125], v[90:93], v[70:73]
	global_load_dwordx4 v[90:93], v[2:3], off offset:3712
	global_load_dwordx4 v[126:129], v[4:5], off offset:3712
	global_load_dwordx4 v[130:133], v[14:15], off offset:3712
	global_load_dwordx4 v[74:77], v[10:11], off offset:3712
	global_load_dwordx4 v[138:141], v[12:13], off offset:3712
	global_load_dwordx4 v[142:145], v[8:9], off offset:3712
	global_load_dwordx4 v[154:157], v[6:7], off offset:3712
	s_waitcnt lgkmcnt(0)
	s_barrier
	v_mfma_f32_16x16x32_f16 v[48:51], v[122:125], v[110:113], v[48:51]
	ds_read_b128 v[58:61], v16 offset:32768
	ds_read_b128 v[106:109], v21
	s_waitcnt lgkmcnt(0)
	v_mfma_f32_16x16x32_f16 v[36:39], v[58:61], v[106:109], v[36:39]
	ds_read_b128 v[94:97], v16 offset:34816
	ds_read_b128 v[110:113], v21 offset:2048
	s_waitcnt lgkmcnt(0)
	v_mfma_f32_16x16x32_f16 v[66:69], v[58:61], v[110:113], v[66:69]
	ds_read_b128 v[118:121], v16 offset:36864
	v_mfma_f32_16x16x32_f16 v[44:47], v[94:97], v[106:109], v[44:47]
	ds_read_b128 v[122:125], v16 offset:38912
	v_mfma_f32_16x16x32_f16 v[78:81], v[94:97], v[110:113], v[78:81]
	s_waitcnt vmcnt(7)
	ds_write_b128 v17, v[62:65] offset:16384
	s_waitcnt lgkmcnt(2)
	v_mfma_f32_16x16x32_f16 v[82:85], v[118:121], v[106:109], v[82:85]
	s_waitcnt vmcnt(6)
	ds_write_b128 v18, v[90:93] offset:16384
	v_mfma_f32_16x16x32_f16 v[86:89], v[118:121], v[110:113], v[86:89]
	s_waitcnt vmcnt(5)
	ds_write_b128 v19, v[126:129] offset:16384
	s_waitcnt lgkmcnt(3)
	v_mfma_f32_16x16x32_f16 v[28:31], v[122:125], v[106:109], v[28:31]
	ds_read_b128 v[106:109], v21 offset:4096
	v_mfma_f32_16x16x32_f16 v[32:35], v[122:125], v[110:113], v[32:35]
	ds_read_b128 v[110:113], v21 offset:6144
	s_waitcnt lgkmcnt(1)
	v_mfma_f32_16x16x32_f16 v[98:101], v[58:61], v[106:109], v[98:101]
	s_waitcnt vmcnt(4)
	ds_write_b128 v20, v[130:133] offset:16384
	s_waitcnt lgkmcnt(1)
	v_mfma_f32_16x16x32_f16 v[52:55], v[58:61], v[110:113], v[52:55]
	ds_read_b128 v[58:61], v22 offset:32768
	v_mfma_f32_16x16x32_f16 v[102:105], v[94:97], v[106:109], v[102:105]
	s_waitcnt vmcnt(3)
	ds_write_b128 v17, v[74:77] offset:49152
	v_mfma_f32_16x16x32_f16 v[24:27], v[94:97], v[110:113], v[24:27]
	ds_read_b128 v[94:97], v22 offset:34816
	v_mfma_f32_16x16x32_f16 v[114:117], v[118:121], v[106:109], v[114:117]
	s_waitcnt vmcnt(2)
	ds_write_b128 v18, v[138:141] offset:49152
	v_mfma_f32_16x16x32_f16 v[40:43], v[118:121], v[110:113], v[40:43]
	ds_read_b128 v[118:121], v22 offset:36864
	v_mfma_f32_16x16x32_f16 v[70:73], v[122:125], v[106:109], v[70:73]
	ds_read_b128 v[106:109], v23
	v_mfma_f32_16x16x32_f16 v[48:51], v[122:125], v[110:113], v[48:51]
	ds_read_b128 v[110:113], v23 offset:2048
	s_waitcnt lgkmcnt(1)
	v_mfma_f32_16x16x32_f16 v[36:39], v[58:61], v[106:109], v[36:39]
	ds_read_b128 v[122:125], v22 offset:38912
	s_waitcnt lgkmcnt(1)
	v_mfma_f32_16x16x32_f16 v[66:69], v[58:61], v[110:113], v[66:69]
	s_waitcnt vmcnt(1)
	ds_write_b128 v19, v[142:145] offset:49152
	v_mfma_f32_16x16x32_f16 v[44:47], v[94:97], v[106:109], v[44:47]
	s_waitcnt vmcnt(0)
	ds_write_b128 v20, v[154:157] offset:49152
	v_mfma_f32_16x16x32_f16 v[78:81], v[94:97], v[110:113], v[78:81]
	v_mfma_f32_16x16x32_f16 v[82:85], v[118:121], v[106:109], v[82:85]
	v_mfma_f32_16x16x32_f16 v[86:89], v[118:121], v[110:113], v[86:89]
	s_waitcnt lgkmcnt(2)
	v_mfma_f32_16x16x32_f16 v[28:31], v[122:125], v[106:109], v[28:31]
	ds_read_b128 v[106:109], v23 offset:4096
	v_mfma_f32_16x16x32_f16 v[32:35], v[122:125], v[110:113], v[32:35]
	ds_read_b128 v[110:113], v23 offset:6144
	s_waitcnt lgkmcnt(1)
	v_mfma_f32_16x16x32_f16 v[98:101], v[58:61], v[106:109], v[98:101]
	s_waitcnt lgkmcnt(0)
	v_mfma_f32_16x16x32_f16 v[52:55], v[58:61], v[110:113], v[52:55]
	global_load_dwordx4 v[58:61], v[0:1], off offset:3840
	v_mfma_f32_16x16x32_f16 v[102:105], v[94:97], v[106:109], v[102:105]
	v_mfma_f32_16x16x32_f16 v[24:27], v[94:97], v[110:113], v[24:27]
	v_mfma_f32_16x16x32_f16 v[114:117], v[118:121], v[106:109], v[114:117]
	v_mfma_f32_16x16x32_f16 v[40:43], v[118:121], v[110:113], v[40:43]
	v_mfma_f32_16x16x32_f16 v[70:73], v[122:125], v[106:109], v[70:73]
	global_load_dwordx4 v[106:109], v[2:3], off offset:3840
	global_load_dwordx4 v[134:137], v[4:5], off offset:3840
	global_load_dwordx4 v[158:161], v[14:15], off offset:3840
	global_load_dwordx4 v[94:97], v[10:11], off offset:3840
	global_load_dwordx4 v[162:165], v[12:13], off offset:3840
	global_load_dwordx4 v[166:169], v[8:9], off offset:3840
	global_load_dwordx4 v[190:193], v[6:7], off offset:3840
	s_waitcnt lgkmcnt(0)
	s_barrier
; #define GL_LOAD(s_, kt_) if (VAR != 1) { a##s_##0 = GL_A(0, kt_); a##s_##1 = GL_A(1, kt_); a##s_##2 = GL_A(2, kt_); a##s_##3 = GL_A(3, kt_); b##s_##0 = GL_B(0, kt_); b##s_##1 = GL_B(1, kt_); b##s_##2 = GL_B(2, kt_); b##s_##3 = GL_B(3, kt_); }
; #define LDS_STORE(s_, buf_) if (VAR != 2) { LDS_ST1(sA, 0, buf_, a##s_##0) LDS_ST1(sA, 1, buf_, a##s_##1) LDS_ST1(sA, 2, buf_, a##s_##2) LDS_ST1(sA, 3, buf_, a##s_##3) LDS_ST1(sB, 0, buf_, b##s_##0) LDS_ST1(sB, 1, buf_, b##s_##1) LDS_ST1(sB, 2, buf_, b##s_##2) LDS_ST1(sB, 3, buf_, b##s_##3) }
;     ...
;   GL_LOAD(0, 0)
;   GL_LOAD(1, 1)
;   LDS_STORE(0, 0)
;   if (VAR != 4) __syncthreads();
; #pragma unroll
;   for (int kt = 0; kt < nk; kt += 2) {
;     if (kt + 2 < nk) { GL_LOAD(0, kt + 2) }
;     MMA_TILE(0)
;     LDS_STORE(1, 1)
;     if (VAR != 4) __syncthreads();
;     if (kt + 3 < nk) { GL_LOAD(1, kt + 3) }
;     MMA_TILE(1)
;     if (kt + 2 < nk) { LDS_STORE(0, 0) }
;     if (VAR != 4) __syncthreads();
	v_mfma_f32_16x16x32_f16 v[48:51], v[122:125], v[110:113], v[48:51]
	ds_read_b128 v[62:65], v16 offset:49152
	ds_read_b128 v[90:93], v21 offset:16384
	s_waitcnt lgkmcnt(0)
	v_mfma_f32_16x16x32_f16 v[36:39], v[62:65], v[90:93], v[36:39]
	ds_read_b128 v[74:77], v16 offset:51200
	ds_read_b128 v[110:113], v21 offset:18432
	s_waitcnt lgkmcnt(0)
	v_mfma_f32_16x16x32_f16 v[66:69], v[62:65], v[110:113], v[66:69]
	ds_read_b128 v[118:121], v16 offset:53248
	v_mfma_f32_16x16x32_f16 v[44:47], v[74:77], v[90:93], v[44:47]
	ds_read_b128 v[122:125], v16 offset:55296
	v_mfma_f32_16x16x32_f16 v[78:81], v[74:77], v[110:113], v[78:81]
	s_waitcnt vmcnt(7)
	ds_write_b128 v17, v[58:61]
	s_waitcnt lgkmcnt(2)
	v_mfma_f32_16x16x32_f16 v[82:85], v[118:121], v[90:93], v[82:85]
	s_waitcnt vmcnt(6)
	ds_write_b128 v18, v[106:109]
	v_mfma_f32_16x16x32_f16 v[86:89], v[118:121], v[110:113], v[86:89]
	s_waitcnt vmcnt(5)
	ds_write_b128 v19, v[134:137]
	s_waitcnt lgkmcnt(3)
	v_mfma_f32_16x16x32_f16 v[28:31], v[122:125], v[90:93], v[28:31]
	ds_read_b128 v[90:93], v21 offset:20480
	v_mfma_f32_16x16x32_f16 v[32:35], v[122:125], v[110:113], v[32:35]
	ds_read_b128 v[110:113], v21 offset:22528
	s_waitcnt lgkmcnt(1)
	v_mfma_f32_16x16x32_f16 v[98:101], v[62:65], v[90:93], v[98:101]
	s_waitcnt vmcnt(4)
	ds_write_b128 v20, v[158:161]
	s_waitcnt lgkmcnt(1)
	v_mfma_f32_16x16x32_f16 v[52:55], v[62:65], v[110:113], v[52:55]
	ds_read_b128 v[62:65], v22 offset:49152
	v_mfma_f32_16x16x32_f16 v[102:105], v[74:77], v[90:93], v[102:105]
	s_waitcnt vmcnt(3)
	ds_write_b128 v17, v[94:97] offset:32768
	v_mfma_f32_16x16x32_f16 v[24:27], v[74:77], v[110:113], v[24:27]
	ds_read_b128 v[74:77], v22 offset:51200
	v_mfma_f32_16x16x32_f16 v[114:117], v[118:121], v[90:93], v[114:117]
	s_waitcnt vmcnt(2)
	ds_write_b128 v18, v[162:165] offset:32768
	v_mfma_f32_16x16x32_f16 v[40:43], v[118:121], v[110:113], v[40:43]
	ds_read_b128 v[118:121], v22 offset:53248
	v_mfma_f32_16x16x32_f16 v[70:73], v[122:125], v[90:93], v[70:73]
	ds_read_b128 v[90:93], v23 offset:16384
	v_mfma_f32_16x16x32_f16 v[48:51], v[122:125], v[110:113], v[48:51]
	ds_read_b128 v[110:113], v23 offset:18432
	s_waitcnt lgkmcnt(1)
	v_mfma_f32_16x16x32_f16 v[36:39], v[62:65], v[90:93], v[36:39]
	ds_read_b128 v[122:125], v22 offset:55296
	s_waitcnt lgkmcnt(1)
	v_mfma_f32_16x16x32_f16 v[66:69], v[62:65], v[110:113], v[66:69]
	s_waitcnt vmcnt(1)
	ds_write_b128 v19, v[166:169] offset:32768
	v_mfma_f32_16x16x32_f16 v[44:47], v[74:77], v[90:93], v[44:47]
	s_waitcnt vmcnt(0)
	ds_write_b128 v20, v[190:193] offset:32768
	v_mfma_f32_16x16x32_f16 v[78:81], v[74:77], v[110:113], v[78:81]
	v_mfma_f32_16x16x32_f16 v[82:85], v[118:121], v[90:93], v[82:85]
	v_mfma_f32_16x16x32_f16 v[86:89], v[118:121], v[110:113], v[86:89]
	s_waitcnt lgkmcnt(2)
	v_mfma_f32_16x16x32_f16 v[28:31], v[122:125], v[90:93], v[28:31]
	ds_read_b128 v[90:93], v23 offset:20480
	v_mfma_f32_16x16x32_f16 v[32:35], v[122:125], v[110:113], v[32:35]
	ds_read_b128 v[110:113], v23 offset:22528
	s_waitcnt lgkmcnt(1)
	v_mfma_f32_16x16x32_f16 v[98:101], v[62:65], v[90:93], v[98:101]
	s_waitcnt lgkmcnt(0)
	v_mfma_f32_16x16x32_f16 v[52:55], v[62:65], v[110:113], v[52:55]
	global_load_dwordx4 v[62:65], v[0:1], off offset:3968
	v_add_co_u32_e32 v0, vcc, s1, v0
	v_mfma_f32_16x16x32_f16 v[102:105], v[74:77], v[90:93], v[102:105]
	v_mfma_f32_16x16x32_f16 v[24:27], v[74:77], v[110:113], v[24:27]
	v_mfma_f32_16x16x32_f16 v[114:117], v[118:121], v[90:93], v[114:117]
	v_mfma_f32_16x16x32_f16 v[40:43], v[118:121], v[110:113], v[40:43]
	v_mfma_f32_16x16x32_f16 v[70:73], v[122:125], v[90:93], v[70:73]
	global_load_dwordx4 v[90:93], v[2:3], off offset:3968
	global_load_dwordx4 v[126:129], v[4:5], off offset:3968
	global_load_dwordx4 v[130:133], v[14:15], off offset:3968
	global_load_dwordx4 v[74:77], v[10:11], off offset:3968
	global_load_dwordx4 v[138:141], v[12:13], off offset:3968
	global_load_dwordx4 v[142:145], v[8:9], off offset:3968
	global_load_dwordx4 v[154:157], v[6:7], off offset:3968
	s_waitcnt lgkmcnt(0)
	s_barrier
	v_mfma_f32_16x16x32_f16 v[48:51], v[122:125], v[110:113], v[48:51]
	ds_read_b128 v[58:61], v16 offset:32768
	ds_read_b128 v[106:109], v21
	s_waitcnt lgkmcnt(0)
	v_mfma_f32_16x16x32_f16 v[36:39], v[58:61], v[106:109], v[36:39]
	ds_read_b128 v[94:97], v16 offset:34816
	ds_read_b128 v[110:113], v21 offset:2048
	s_waitcnt lgkmcnt(0)
	v_mfma_f32_16x16x32_f16 v[66:69], v[58:61], v[110:113], v[66:69]
	ds_read_b128 v[118:121], v16 offset:36864
	v_mfma_f32_16x16x32_f16 v[44:47], v[94:97], v[106:109], v[44:47]
	ds_read_b128 v[122:125], v16 offset:38912
	v_mfma_f32_16x16x32_f16 v[78:81], v[94:97], v[110:113], v[78:81]
	ds_read_b128 v[158:161], v23 offset:6144
	s_waitcnt lgkmcnt(2)
	v_mfma_f32_16x16x32_f16 v[82:85], v[118:121], v[106:109], v[82:85]
	v_addc_co_u32_e32 v1, vcc, 0, v1, vcc
	v_mfma_f32_16x16x32_f16 v[86:89], v[118:121], v[110:113], v[86:89]
	v_add_co_u32_e32 v2, vcc, s1, v2
	s_waitcnt lgkmcnt(1)
	v_mfma_f32_16x16x32_f16 v[28:31], v[122:125], v[106:109], v[28:31]
	ds_read_b128 v[106:109], v21 offset:4096
	v_mfma_f32_16x16x32_f16 v[32:35], v[122:125], v[110:113], v[32:35]
	ds_read_b128 v[110:113], v21 offset:6144
	s_waitcnt lgkmcnt(1)
	v_mfma_f32_16x16x32_f16 v[98:101], v[58:61], v[106:109], v[98:101]
	v_addc_co_u32_e32 v3, vcc, 0, v3, vcc
	s_waitcnt lgkmcnt(0)
; #define GL_LOAD(s_, kt_) if (VAR != 1) { a##s_##0 = GL_A(0, kt_); a##s_##1 = GL_A(1, kt_); a##s_##2 = GL_A(2, kt_); a##s_##3 = GL_A(3, kt_); b##s_##0 = GL_B(0, kt_); b##s_##1 = GL_B(1, kt_); b##s_##2 = GL_B(2, kt_); b##s_##3 = GL_B(3, kt_); }
; #define LDS_STORE(s_, buf_) if (VAR != 2) { LDS_ST1(sA, 0, buf_, a##s_##0) LDS_ST1(sA, 1, buf_, a##s_##1) LDS_ST1(sA, 2, buf_, a##s_##2) LDS_ST1(sA, 3, buf_, a##s_##3) LDS_ST1(sB, 0, buf_, b##s_##0) LDS_ST1(sB, 1, buf_, b##s_##1) LDS_ST1(sB, 2, buf_, b##s_##2) LDS_ST1(sB, 3, buf_, b##s_##3) }
;     ...
;   GL_LOAD(0, 0)
;   GL_LOAD(1, 1)
;   LDS_STORE(0, 0)
;   if (VAR != 4) __syncthreads();
; #pragma unroll
;   for (int kt = 0; kt < nk; kt += 2) {
;     if (kt + 2 < nk) { GL_LOAD(0, kt + 2) }
;     MMA_TILE(0)
;     LDS_STORE(1, 1)
;     if (VAR != 4) __syncthreads();
;     if (kt + 3 < nk) { GL_LOAD(1, kt + 3) }
;     MMA_TILE(1)
;     if (kt + 2 < nk) { LDS_STORE(0, 0) }
;     if (VAR != 4) __syncthreads();
	v_mfma_f32_16x16x32_f16 v[52:55], v[58:61], v[110:113], v[52:55]
	ds_read_b128 v[58:61], v22 offset:32768
	v_mfma_f32_16x16x32_f16 v[102:105], v[94:97], v[106:109], v[102:105]
	v_add_co_u32_e32 v4, vcc, s1, v4
	v_mfma_f32_16x16x32_f16 v[24:27], v[94:97], v[110:113], v[24:27]
	ds_read_b128 v[94:97], v22 offset:34816
	v_addc_co_u32_e32 v5, vcc, 0, v5, vcc
	v_mfma_f32_16x16x32_f16 v[114:117], v[118:121], v[106:109], v[114:117]
	v_add_co_u32_e32 v14, vcc, s1, v14
	s_nop 1
	v_addc_co_u32_e32 v15, vcc, 0, v15, vcc
	v_mfma_f32_16x16x32_f16 v[40:43], v[118:121], v[110:113], v[40:43]
	ds_read_b128 v[118:121], v22 offset:36864
	v_add_co_u32_e32 v10, vcc, s1, v10
	v_mfma_f32_16x16x32_f16 v[70:73], v[122:125], v[106:109], v[70:73]
	ds_read_b128 v[106:109], v23
	v_addc_co_u32_e32 v11, vcc, 0, v11, vcc
	v_mfma_f32_16x16x32_f16 v[48:51], v[122:125], v[110:113], v[48:51]
	ds_read_b128 v[110:113], v23 offset:2048
	ds_read_b128 v[122:125], v22 offset:38912
	s_waitcnt lgkmcnt(2)
	v_mfma_f32_16x16x32_f16 v[36:39], v[58:61], v[106:109], v[36:39]
	v_add_co_u32_e32 v12, vcc, s1, v12
	s_nop 1
	v_addc_co_u32_e32 v13, vcc, 0, v13, vcc
	s_waitcnt lgkmcnt(1)
	v_mfma_f32_16x16x32_f16 v[66:69], v[58:61], v[110:113], v[66:69]
	v_add_co_u32_e32 v8, vcc, s1, v8
	s_nop 1
	v_addc_co_u32_e32 v9, vcc, 0, v9, vcc
	v_mfma_f32_16x16x32_f16 v[44:47], v[94:97], v[106:109], v[44:47]
	v_add_co_u32_e32 v6, vcc, s1, v6
	s_nop 1
	v_addc_co_u32_e32 v7, vcc, 0, v7, vcc
	v_mfma_f32_16x16x32_f16 v[78:81], v[94:97], v[110:113], v[78:81]
	s_waitcnt vmcnt(7)
	ds_write_b128 v17, v[62:65] offset:16384
	s_waitcnt vmcnt(6)
	ds_write_b128 v18, v[90:93] offset:16384
	v_mfma_f32_16x16x32_f16 v[52:55], v[58:61], v[158:161], v[52:55]
	s_waitcnt vmcnt(5)
	ds_write_b128 v19, v[126:129] offset:16384
	s_waitcnt vmcnt(4)
	ds_write_b128 v20, v[130:133] offset:16384
	v_mfma_f32_16x16x32_f16 v[24:27], v[94:97], v[158:161], v[24:27]
	s_waitcnt vmcnt(3)
	ds_write_b128 v17, v[74:77] offset:49152
	s_waitcnt vmcnt(2)
	ds_write_b128 v18, v[138:141] offset:49152
	v_mfma_f32_16x16x32_f16 v[82:85], v[118:121], v[106:109], v[82:85]
	s_waitcnt vmcnt(1)
	ds_write_b128 v19, v[142:145] offset:49152
	s_waitcnt vmcnt(0)
	ds_write_b128 v20, v[154:157] offset:49152
	v_mfma_f32_16x16x32_f16 v[86:89], v[118:121], v[110:113], v[86:89]
	s_waitcnt lgkmcnt(8)
	v_mfma_f32_16x16x32_f16 v[28:31], v[122:125], v[106:109], v[28:31]
	ds_read_b128 v[106:109], v23 offset:4096
	v_mfma_f32_16x16x32_f16 v[32:35], v[122:125], v[110:113], v[32:35]
	global_load_dwordx4 v[110:113], v[0:1], off
	global_load_dwordx4 v[134:137], v[2:3], off
	v_mfma_f32_16x16x32_f16 v[40:43], v[118:121], v[158:161], v[40:43]
	global_load_dwordx4 v[162:165], v[4:5], off
	s_waitcnt lgkmcnt(0)
	v_mfma_f32_16x16x32_f16 v[98:101], v[58:61], v[106:109], v[98:101]
	global_load_dwordx4 v[166:169], v[14:15], off
	v_mfma_f32_16x16x32_f16 v[102:105], v[94:97], v[106:109], v[102:105]
	v_mfma_f32_16x16x32_f16 v[114:117], v[118:121], v[106:109], v[114:117]
	v_mfma_f32_16x16x32_f16 v[70:73], v[122:125], v[106:109], v[70:73]
	global_load_dwordx4 v[106:109], v[10:11], off
	global_load_dwordx4 v[190:193], v[12:13], off
	global_load_dwordx4 v[58:61], v[8:9], off
	global_load_dwordx4 v[94:97], v[6:7], off
	s_waitcnt lgkmcnt(0)
	s_barrier
	v_mfma_f32_16x16x32_f16 v[48:51], v[122:125], v[158:161], v[48:51]
	ds_read_b128 v[62:65], v16 offset:49152
	ds_read_b128 v[90:93], v21 offset:16384
	s_waitcnt lgkmcnt(0)
	v_mfma_f32_16x16x32_f16 v[36:39], v[62:65], v[90:93], v[36:39]
	ds_read_b128 v[74:77], v16 offset:51200
	ds_read_b128 v[118:121], v21 offset:18432
	s_waitcnt lgkmcnt(0)
	v_mfma_f32_16x16x32_f16 v[66:69], v[62:65], v[118:121], v[66:69]
	ds_read_b128 v[122:125], v16 offset:53248
	v_mfma_f32_16x16x32_f16 v[44:47], v[74:77], v[90:93], v[44:47]
	ds_read_b128 v[126:129], v16 offset:55296
	v_mfma_f32_16x16x32_f16 v[78:81], v[74:77], v[118:121], v[78:81]
	s_waitcnt vmcnt(7)
	ds_write_b128 v17, v[110:113]
	s_waitcnt lgkmcnt(2)
	v_mfma_f32_16x16x32_f16 v[82:85], v[122:125], v[90:93], v[82:85]
	s_waitcnt vmcnt(6)
	ds_write_b128 v18, v[134:137]
	v_mfma_f32_16x16x32_f16 v[86:89], v[122:125], v[118:121], v[86:89]
	s_waitcnt vmcnt(5)
	ds_write_b128 v19, v[162:165]
	s_waitcnt lgkmcnt(3)
	v_mfma_f32_16x16x32_f16 v[28:31], v[126:129], v[90:93], v[28:31]
	ds_read_b128 v[90:93], v21 offset:20480
	v_mfma_f32_16x16x32_f16 v[32:35], v[126:129], v[118:121], v[32:35]
	ds_read_b128 v[118:121], v21 offset:22528
	s_waitcnt lgkmcnt(1)
	v_mfma_f32_16x16x32_f16 v[98:101], v[62:65], v[90:93], v[98:101]
	s_waitcnt vmcnt(4)
	ds_write_b128 v20, v[166:169]
	s_waitcnt lgkmcnt(1)
	v_mfma_f32_16x16x32_f16 v[52:55], v[62:65], v[118:121], v[52:55]
	ds_read_b128 v[62:65], v22 offset:49152
	v_mfma_f32_16x16x32_f16 v[102:105], v[74:77], v[90:93], v[102:105]
	s_waitcnt vmcnt(3)
	ds_write_b128 v17, v[106:109] offset:32768
	v_mfma_f32_16x16x32_f16 v[24:27], v[74:77], v[118:121], v[24:27]
	ds_read_b128 v[74:77], v22 offset:51200
	v_mfma_f32_16x16x32_f16 v[114:117], v[122:125], v[90:93], v[114:117]
	s_waitcnt vmcnt(2)
	ds_write_b128 v18, v[190:193] offset:32768
	v_mfma_f32_16x16x32_f16 v[40:43], v[122:125], v[118:121], v[40:43]
	ds_read_b128 v[122:125], v22 offset:53248
	v_mfma_f32_16x16x32_f16 v[70:73], v[126:129], v[90:93], v[70:73]
	ds_read_b128 v[90:93], v23 offset:16384
	v_mfma_f32_16x16x32_f16 v[48:51], v[126:129], v[118:121], v[48:51]
	ds_read_b128 v[118:121], v23 offset:18432
	s_waitcnt lgkmcnt(1)
	v_mfma_f32_16x16x32_f16 v[36:39], v[62:65], v[90:93], v[36:39]
	ds_read_b128 v[126:129], v22 offset:55296
	s_waitcnt lgkmcnt(1)
	v_mfma_f32_16x16x32_f16 v[66:69], v[62:65], v[118:121], v[66:69]
	s_waitcnt vmcnt(1)
; #define GL_LOAD(s_, kt_) if (VAR != 1) { a##s_##0 = GL_A(0, kt_); a##s_##1 = GL_A(1, kt_); a##s_##2 = GL_A(2, kt_); a##s_##3 = GL_A(3, kt_); b##s_##0 = GL_B(0, kt_); b##s_##1 = GL_B(1, kt_); b##s_##2 = GL_B(2, kt_); b##s_##3 = GL_B(3, kt_); }
; #define LDS_STORE(s_, buf_) if (VAR != 2) { LDS_ST1(sA, 0, buf_, a##s_##0) LDS_ST1(sA, 1, buf_, a##s_##1) LDS_ST1(sA, 2, buf_, a##s_##2) LDS_ST1(sA, 3, buf_, a##s_##3) LDS_ST1(sB, 0, buf_, b##s_##0) LDS_ST1(sB, 1, buf_, b##s_##1) LDS_ST1(sB, 2, buf_, b##s_##2) LDS_ST1(sB, 3, buf_, b##s_##3) }
;     ...
;   GL_LOAD(0, 0)
;   GL_LOAD(1, 1)
;   LDS_STORE(0, 0)
;   if (VAR != 4) __syncthreads();
; #pragma unroll
;   for (int kt = 0; kt < nk; kt += 2) {
;     if (kt + 2 < nk) { GL_LOAD(0, kt + 2) }
;     MMA_TILE(0)
;     LDS_STORE(1, 1)
;     if (VAR != 4) __syncthreads();
;     if (kt + 3 < nk) { GL_LOAD(1, kt + 3) }
;     MMA_TILE(1)
;     if (kt + 2 < nk) { LDS_STORE(0, 0) }
;     if (VAR != 4) __syncthreads();
	ds_write_b128 v19, v[58:61] offset:32768
	v_mfma_f32_16x16x32_f16 v[44:47], v[74:77], v[90:93], v[44:47]
	s_waitcnt vmcnt(0)
	ds_write_b128 v20, v[94:97] offset:32768
	v_mfma_f32_16x16x32_f16 v[78:81], v[74:77], v[118:121], v[78:81]
	v_mfma_f32_16x16x32_f16 v[82:85], v[122:125], v[90:93], v[82:85]
	v_mfma_f32_16x16x32_f16 v[86:89], v[122:125], v[118:121], v[86:89]
	s_waitcnt lgkmcnt(2)
	v_mfma_f32_16x16x32_f16 v[28:31], v[126:129], v[90:93], v[28:31]
	ds_read_b128 v[90:93], v23 offset:20480
	v_mfma_f32_16x16x32_f16 v[32:35], v[126:129], v[118:121], v[32:35]
	ds_read_b128 v[118:121], v23 offset:22528
	s_waitcnt lgkmcnt(1)
	v_mfma_f32_16x16x32_f16 v[98:101], v[62:65], v[90:93], v[98:101]
	s_waitcnt lgkmcnt(0)
	v_mfma_f32_16x16x32_f16 v[52:55], v[62:65], v[118:121], v[52:55]
	global_load_dwordx4 v[62:65], v[0:1], off offset:128
	v_mfma_f32_16x16x32_f16 v[102:105], v[74:77], v[90:93], v[102:105]
	v_mfma_f32_16x16x32_f16 v[24:27], v[74:77], v[118:121], v[24:27]
	v_mfma_f32_16x16x32_f16 v[114:117], v[122:125], v[90:93], v[114:117]
	v_mfma_f32_16x16x32_f16 v[40:43], v[122:125], v[118:121], v[40:43]
	v_mfma_f32_16x16x32_f16 v[70:73], v[126:129], v[90:93], v[70:73]
	global_load_dwordx4 v[90:93], v[2:3], off offset:128
	global_load_dwordx4 v[130:133], v[4:5], off offset:128
	global_load_dwordx4 v[138:141], v[14:15], off offset:128
	global_load_dwordx4 v[74:77], v[10:11], off offset:128
	global_load_dwordx4 v[142:145], v[12:13], off offset:128
	global_load_dwordx4 v[154:157], v[8:9], off offset:128
	global_load_dwordx4 v[158:161], v[6:7], off offset:128
	s_waitcnt lgkmcnt(0)
	s_barrier
	v_mfma_f32_16x16x32_f16 v[48:51], v[126:129], v[118:121], v[48:51]
	ds_read_b128 v[58:61], v16 offset:32768
	ds_read_b128 v[106:109], v21
	s_waitcnt lgkmcnt(0)
	v_mfma_f32_16x16x32_f16 v[36:39], v[58:61], v[106:109], v[36:39]
	ds_read_b128 v[94:97], v16 offset:34816
	ds_read_b128 v[110:113], v21 offset:2048
	s_waitcnt lgkmcnt(0)
	v_mfma_f32_16x16x32_f16 v[66:69], v[58:61], v[110:113], v[66:69]
	ds_read_b128 v[118:121], v16 offset:36864
	v_mfma_f32_16x16x32_f16 v[44:47], v[94:97], v[106:109], v[44:47]
	ds_read_b128 v[122:125], v16 offset:38912
	v_mfma_f32_16x16x32_f16 v[78:81], v[94:97], v[110:113], v[78:81]
	s_waitcnt vmcnt(7)
	ds_write_b128 v17, v[62:65] offset:16384
	s_waitcnt lgkmcnt(2)
	v_mfma_f32_16x16x32_f16 v[82:85], v[118:121], v[106:109], v[82:85]
	s_waitcnt vmcnt(6)
	ds_write_b128 v18, v[90:93] offset:16384
	v_mfma_f32_16x16x32_f16 v[86:89], v[118:121], v[110:113], v[86:89]
	s_waitcnt vmcnt(5)
	ds_write_b128 v19, v[130:133] offset:16384
	s_waitcnt lgkmcnt(3)
	v_mfma_f32_16x16x32_f16 v[28:31], v[122:125], v[106:109], v[28:31]
	ds_read_b128 v[106:109], v21 offset:4096
	v_mfma_f32_16x16x32_f16 v[32:35], v[122:125], v[110:113], v[32:35]
	ds_read_b128 v[110:113], v21 offset:6144
	s_waitcnt lgkmcnt(1)
	v_mfma_f32_16x16x32_f16 v[98:101], v[58:61], v[106:109], v[98:101]
	s_waitcnt vmcnt(4)
	ds_write_b128 v20, v[138:141] offset:16384
	s_waitcnt lgkmcnt(1)
	v_mfma_f32_16x16x32_f16 v[52:55], v[58:61], v[110:113], v[52:55]
	ds_read_b128 v[58:61], v22 offset:32768
	v_mfma_f32_16x16x32_f16 v[102:105], v[94:97], v[106:109], v[102:105]
	s_waitcnt vmcnt(3)
	ds_write_b128 v17, v[74:77] offset:49152
	v_mfma_f32_16x16x32_f16 v[24:27], v[94:97], v[110:113], v[24:27]
	ds_read_b128 v[94:97], v22 offset:34816
	v_mfma_f32_16x16x32_f16 v[114:117], v[118:121], v[106:109], v[114:117]
	s_waitcnt vmcnt(2)
	ds_write_b128 v18, v[142:145] offset:49152
	v_mfma_f32_16x16x32_f16 v[40:43], v[118:121], v[110:113], v[40:43]
	ds_read_b128 v[118:121], v22 offset:36864
	v_mfma_f32_16x16x32_f16 v[70:73], v[122:125], v[106:109], v[70:73]
	ds_read_b128 v[106:109], v23
	v_mfma_f32_16x16x32_f16 v[48:51], v[122:125], v[110:113], v[48:51]
	ds_read_b128 v[110:113], v23 offset:2048
	s_waitcnt lgkmcnt(1)
	v_mfma_f32_16x16x32_f16 v[36:39], v[58:61], v[106:109], v[36:39]
	ds_read_b128 v[122:125], v22 offset:38912
	s_waitcnt lgkmcnt(1)
	v_mfma_f32_16x16x32_f16 v[66:69], v[58:61], v[110:113], v[66:69]
	s_waitcnt vmcnt(1)
	ds_write_b128 v19, v[154:157] offset:49152
	v_mfma_f32_16x16x32_f16 v[44:47], v[94:97], v[106:109], v[44:47]
	s_waitcnt vmcnt(0)
	ds_write_b128 v20, v[158:161] offset:49152
	v_mfma_f32_16x16x32_f16 v[78:81], v[94:97], v[110:113], v[78:81]
	v_mfma_f32_16x16x32_f16 v[82:85], v[118:121], v[106:109], v[82:85]
	v_mfma_f32_16x16x32_f16 v[86:89], v[118:121], v[110:113], v[86:89]
	s_waitcnt lgkmcnt(2)
	v_mfma_f32_16x16x32_f16 v[28:31], v[122:125], v[106:109], v[28:31]
	ds_read_b128 v[106:109], v23 offset:4096
	v_mfma_f32_16x16x32_f16 v[32:35], v[122:125], v[110:113], v[32:35]
	ds_read_b128 v[110:113], v23 offset:6144
	s_waitcnt lgkmcnt(1)
	v_mfma_f32_16x16x32_f16 v[98:101], v[58:61], v[106:109], v[98:101]
	s_waitcnt lgkmcnt(0)
	v_mfma_f32_16x16x32_f16 v[52:55], v[58:61], v[110:113], v[52:55]
	global_load_dwordx4 v[58:61], v[0:1], off offset:256
	v_mfma_f32_16x16x32_f16 v[102:105], v[94:97], v[106:109], v[102:105]
	v_mfma_f32_16x16x32_f16 v[24:27], v[94:97], v[110:113], v[24:27]
	v_mfma_f32_16x16x32_f16 v[114:117], v[118:121], v[106:109], v[114:117]
	v_mfma_f32_16x16x32_f16 v[40:43], v[118:121], v[110:113], v[40:43]
	v_mfma_f32_16x16x32_f16 v[70:73], v[122:125], v[106:109], v[70:73]
	global_load_dwordx4 v[106:109], v[2:3], off offset:256
	global_load_dwordx4 v[126:129], v[4:5], off offset:256
	global_load_dwordx4 v[134:137], v[14:15], off offset:256
	global_load_dwordx4 v[94:97], v[10:11], off offset:256
	global_load_dwordx4 v[162:165], v[12:13], off offset:256
	global_load_dwordx4 v[166:169], v[8:9], off offset:256
	global_load_dwordx4 v[190:193], v[6:7], off offset:256
	s_waitcnt lgkmcnt(0)
	s_barrier
; #define GL_LOAD(s_, kt_) if (VAR != 1) { a##s_##0 = GL_A(0, kt_); a##s_##1 = GL_A(1, kt_); a##s_##2 = GL_A(2, kt_); a##s_##3 = GL_A(3, kt_); b##s_##0 = GL_B(0, kt_); b##s_##1 = GL_B(1, kt_); b##s_##2 = GL_B(2, kt_); b##s_##3 = GL_B(3, kt_); }
; #define LDS_STORE(s_, buf_) if (VAR != 2) { LDS_ST1(sA, 0, buf_, a##s_##0) LDS_ST1(sA, 1, buf_, a##s_##1) LDS_ST1(sA, 2, buf_, a##s_##2) LDS_ST1(sA, 3, buf_, a##s_##3) LDS_ST1(sB, 0, buf_, b##s_##0) LDS_ST1(sB, 1, buf_, b##s_##1) LDS_ST1(sB, 2, buf_, b##s_##2) LDS_ST1(sB, 3, buf_, b##s_##3) }
;     ...
;   GL_LOAD(0, 0)
;   GL_LOAD(1, 1)
;   LDS_STORE(0, 0)
;   if (VAR != 4) __syncthreads();
; #pragma unroll
;   for (int kt = 0; kt < nk; kt += 2) {
;     if (kt + 2 < nk) { GL_LOAD(0, kt + 2) }
;     MMA_TILE(0)
;     LDS_STORE(1, 1)
;     if (VAR != 4) __syncthreads();
;     if (kt + 3 < nk) { GL_LOAD(1, kt + 3) }
;     MMA_TILE(1)
;     if (kt + 2 < nk) { LDS_STORE(0, 0) }
;     if (VAR != 4) __syncthreads();
	v_mfma_f32_16x16x32_f16 v[48:51], v[122:125], v[110:113], v[48:51]
	ds_read_b128 v[62:65], v16 offset:49152
	ds_read_b128 v[90:93], v21 offset:16384
	s_waitcnt lgkmcnt(0)
	v_mfma_f32_16x16x32_f16 v[36:39], v[62:65], v[90:93], v[36:39]
	ds_read_b128 v[74:77], v16 offset:51200
	ds_read_b128 v[110:113], v21 offset:18432
	s_waitcnt lgkmcnt(0)
	v_mfma_f32_16x16x32_f16 v[66:69], v[62:65], v[110:113], v[66:69]
	ds_read_b128 v[118:121], v16 offset:53248
	v_mfma_f32_16x16x32_f16 v[44:47], v[74:77], v[90:93], v[44:47]
	ds_read_b128 v[122:125], v16 offset:55296
	v_mfma_f32_16x16x32_f16 v[78:81], v[74:77], v[110:113], v[78:81]
	s_waitcnt vmcnt(7)
	ds_write_b128 v17, v[58:61]
	s_waitcnt lgkmcnt(2)
	v_mfma_f32_16x16x32_f16 v[82:85], v[118:121], v[90:93], v[82:85]
	s_waitcnt vmcnt(6)
	ds_write_b128 v18, v[106:109]
	v_mfma_f32_16x16x32_f16 v[86:89], v[118:121], v[110:113], v[86:89]
	s_waitcnt vmcnt(5)
	ds_write_b128 v19, v[126:129]
	s_waitcnt lgkmcnt(3)
	v_mfma_f32_16x16x32_f16 v[28:31], v[122:125], v[90:93], v[28:31]
	ds_read_b128 v[90:93], v21 offset:20480
	v_mfma_f32_16x16x32_f16 v[32:35], v[122:125], v[110:113], v[32:35]
	ds_read_b128 v[110:113], v21 offset:22528
	s_waitcnt lgkmcnt(1)
	v_mfma_f32_16x16x32_f16 v[98:101], v[62:65], v[90:93], v[98:101]
	s_waitcnt vmcnt(4)
	ds_write_b128 v20, v[134:137]
	s_waitcnt lgkmcnt(1)
	v_mfma_f32_16x16x32_f16 v[52:55], v[62:65], v[110:113], v[52:55]
	ds_read_b128 v[62:65], v22 offset:49152
	v_mfma_f32_16x16x32_f16 v[102:105], v[74:77], v[90:93], v[102:105]
	s_waitcnt vmcnt(3)
	ds_write_b128 v17, v[94:97] offset:32768
	v_mfma_f32_16x16x32_f16 v[24:27], v[74:77], v[110:113], v[24:27]
	ds_read_b128 v[74:77], v22 offset:51200
	v_mfma_f32_16x16x32_f16 v[114:117], v[118:121], v[90:93], v[114:117]
	s_waitcnt vmcnt(2)
	ds_write_b128 v18, v[162:165] offset:32768
	v_mfma_f32_16x16x32_f16 v[40:43], v[118:121], v[110:113], v[40:43]
	ds_read_b128 v[118:121], v22 offset:53248
	v_mfma_f32_16x16x32_f16 v[70:73], v[122:125], v[90:93], v[70:73]
	ds_read_b128 v[90:93], v23 offset:16384
	v_mfma_f32_16x16x32_f16 v[48:51], v[122:125], v[110:113], v[48:51]
	ds_read_b128 v[110:113], v23 offset:18432
	s_waitcnt lgkmcnt(1)
	v_mfma_f32_16x16x32_f16 v[36:39], v[62:65], v[90:93], v[36:39]
	ds_read_b128 v[122:125], v22 offset:55296
	s_waitcnt lgkmcnt(1)
	v_mfma_f32_16x16x32_f16 v[66:69], v[62:65], v[110:113], v[66:69]
	s_waitcnt vmcnt(1)
	ds_write_b128 v19, v[166:169] offset:32768
	v_mfma_f32_16x16x32_f16 v[44:47], v[74:77], v[90:93], v[44:47]
	s_waitcnt vmcnt(0)
	ds_write_b128 v20, v[190:193] offset:32768
	v_mfma_f32_16x16x32_f16 v[78:81], v[74:77], v[110:113], v[78:81]
	v_mfma_f32_16x16x32_f16 v[82:85], v[118:121], v[90:93], v[82:85]
	v_mfma_f32_16x16x32_f16 v[86:89], v[118:121], v[110:113], v[86:89]
	s_waitcnt lgkmcnt(2)
	v_mfma_f32_16x16x32_f16 v[28:31], v[122:125], v[90:93], v[28:31]
	ds_read_b128 v[90:93], v23 offset:20480
	v_mfma_f32_16x16x32_f16 v[32:35], v[122:125], v[110:113], v[32:35]
	ds_read_b128 v[110:113], v23 offset:22528
	s_waitcnt lgkmcnt(1)
	v_mfma_f32_16x16x32_f16 v[98:101], v[62:65], v[90:93], v[98:101]
	s_waitcnt lgkmcnt(0)
	v_mfma_f32_16x16x32_f16 v[52:55], v[62:65], v[110:113], v[52:55]
	global_load_dwordx4 v[62:65], v[0:1], off offset:384
	v_mfma_f32_16x16x32_f16 v[102:105], v[74:77], v[90:93], v[102:105]
	v_mfma_f32_16x16x32_f16 v[24:27], v[74:77], v[110:113], v[24:27]
	v_mfma_f32_16x16x32_f16 v[114:117], v[118:121], v[90:93], v[114:117]
	v_mfma_f32_16x16x32_f16 v[40:43], v[118:121], v[110:113], v[40:43]
	v_mfma_f32_16x16x32_f16 v[70:73], v[122:125], v[90:93], v[70:73]
	global_load_dwordx4 v[90:93], v[2:3], off offset:384
	global_load_dwordx4 v[130:133], v[4:5], off offset:384
	global_load_dwordx4 v[138:141], v[14:15], off offset:384
	global_load_dwordx4 v[74:77], v[10:11], off offset:384
	global_load_dwordx4 v[142:145], v[12:13], off offset:384
	global_load_dwordx4 v[154:157], v[8:9], off offset:384
	global_load_dwordx4 v[158:161], v[6:7], off offset:384
	s_waitcnt lgkmcnt(0)
	s_barrier
	v_mfma_f32_16x16x32_f16 v[48:51], v[122:125], v[110:113], v[48:51]
	ds_read_b128 v[58:61], v16 offset:32768
	ds_read_b128 v[106:109], v21
	s_waitcnt lgkmcnt(0)
	v_mfma_f32_16x16x32_f16 v[36:39], v[58:61], v[106:109], v[36:39]
	ds_read_b128 v[94:97], v16 offset:34816
	ds_read_b128 v[110:113], v21 offset:2048
	s_waitcnt lgkmcnt(0)
	v_mfma_f32_16x16x32_f16 v[66:69], v[58:61], v[110:113], v[66:69]
	ds_read_b128 v[118:121], v16 offset:36864
	v_mfma_f32_16x16x32_f16 v[44:47], v[94:97], v[106:109], v[44:47]
	ds_read_b128 v[122:125], v16 offset:38912
	v_mfma_f32_16x16x32_f16 v[78:81], v[94:97], v[110:113], v[78:81]
	s_waitcnt vmcnt(7)
	ds_write_b128 v17, v[62:65] offset:16384
	s_waitcnt lgkmcnt(2)
	v_mfma_f32_16x16x32_f16 v[82:85], v[118:121], v[106:109], v[82:85]
	s_waitcnt vmcnt(6)
	ds_write_b128 v18, v[90:93] offset:16384
	v_mfma_f32_16x16x32_f16 v[86:89], v[118:121], v[110:113], v[86:89]
	s_waitcnt vmcnt(5)
	ds_write_b128 v19, v[130:133] offset:16384
	s_waitcnt lgkmcnt(3)
	v_mfma_f32_16x16x32_f16 v[28:31], v[122:125], v[106:109], v[28:31]
	ds_read_b128 v[106:109], v21 offset:4096
	v_mfma_f32_16x16x32_f16 v[32:35], v[122:125], v[110:113], v[32:35]
	ds_read_b128 v[110:113], v21 offset:6144
	s_waitcnt lgkmcnt(1)
	v_mfma_f32_16x16x32_f16 v[98:101], v[58:61], v[106:109], v[98:101]
	s_waitcnt vmcnt(4)
	ds_write_b128 v20, v[138:141] offset:16384
	s_waitcnt lgkmcnt(1)
	v_mfma_f32_16x16x32_f16 v[52:55], v[58:61], v[110:113], v[52:55]
	ds_read_b128 v[58:61], v22 offset:32768
	v_mfma_f32_16x16x32_f16 v[102:105], v[94:97], v[106:109], v[102:105]
	s_waitcnt vmcnt(3)
; #define GL_LOAD(s_, kt_) if (VAR != 1) { a##s_##0 = GL_A(0, kt_); a##s_##1 = GL_A(1, kt_); a##s_##2 = GL_A(2, kt_); a##s_##3 = GL_A(3, kt_); b##s_##0 = GL_B(0, kt_); b##s_##1 = GL_B(1, kt_); b##s_##2 = GL_B(2, kt_); b##s_##3 = GL_B(3, kt_); }
; #define LDS_STORE(s_, buf_) if (VAR != 2) { LDS_ST1(sA, 0, buf_, a##s_##0) LDS_ST1(sA, 1, buf_, a##s_##1) LDS_ST1(sA, 2, buf_, a##s_##2) LDS_ST1(sA, 3, buf_, a##s_##3) LDS_ST1(sB, 0, buf_, b##s_##0) LDS_ST1(sB, 1, buf_, b##s_##1) LDS_ST1(sB, 2, buf_, b##s_##2) LDS_ST1(sB, 3, buf_, b##s_##3) }
;     ...
;   GL_LOAD(0, 0)
;   GL_LOAD(1, 1)
;   LDS_STORE(0, 0)
;   if (VAR != 4) __syncthreads();
; #pragma unroll
;   for (int kt = 0; kt < nk; kt += 2) {
;     if (kt + 2 < nk) { GL_LOAD(0, kt + 2) }
;     MMA_TILE(0)
;     LDS_STORE(1, 1)
;     if (VAR != 4) __syncthreads();
;     if (kt + 3 < nk) { GL_LOAD(1, kt + 3) }
;     MMA_TILE(1)
;     if (kt + 2 < nk) { LDS_STORE(0, 0) }
;     if (VAR != 4) __syncthreads();
	ds_write_b128 v17, v[74:77] offset:49152
	v_mfma_f32_16x16x32_f16 v[24:27], v[94:97], v[110:113], v[24:27]
	ds_read_b128 v[94:97], v22 offset:34816
	v_mfma_f32_16x16x32_f16 v[114:117], v[118:121], v[106:109], v[114:117]
	s_waitcnt vmcnt(2)
	ds_write_b128 v18, v[142:145] offset:49152
	v_mfma_f32_16x16x32_f16 v[40:43], v[118:121], v[110:113], v[40:43]
	ds_read_b128 v[118:121], v22 offset:36864
	v_mfma_f32_16x16x32_f16 v[70:73], v[122:125], v[106:109], v[70:73]
	ds_read_b128 v[106:109], v23
	v_mfma_f32_16x16x32_f16 v[48:51], v[122:125], v[110:113], v[48:51]
	ds_read_b128 v[110:113], v23 offset:2048
	s_waitcnt lgkmcnt(1)
	v_mfma_f32_16x16x32_f16 v[36:39], v[58:61], v[106:109], v[36:39]
	ds_read_b128 v[122:125], v22 offset:38912
	s_waitcnt lgkmcnt(1)
	v_mfma_f32_16x16x32_f16 v[66:69], v[58:61], v[110:113], v[66:69]
	s_waitcnt vmcnt(1)
	ds_write_b128 v19, v[154:157] offset:49152
	v_mfma_f32_16x16x32_f16 v[44:47], v[94:97], v[106:109], v[44:47]
	s_waitcnt vmcnt(0)
	ds_write_b128 v20, v[158:161] offset:49152
	v_mfma_f32_16x16x32_f16 v[78:81], v[94:97], v[110:113], v[78:81]
	v_mfma_f32_16x16x32_f16 v[82:85], v[118:121], v[106:109], v[82:85]
	v_mfma_f32_16x16x32_f16 v[86:89], v[118:121], v[110:113], v[86:89]
	s_waitcnt lgkmcnt(2)
	v_mfma_f32_16x16x32_f16 v[28:31], v[122:125], v[106:109], v[28:31]
	ds_read_b128 v[106:109], v23 offset:4096
	v_mfma_f32_16x16x32_f16 v[32:35], v[122:125], v[110:113], v[32:35]
	ds_read_b128 v[110:113], v23 offset:6144
	s_waitcnt lgkmcnt(1)
	v_mfma_f32_16x16x32_f16 v[98:101], v[58:61], v[106:109], v[98:101]
	s_waitcnt lgkmcnt(0)
	v_mfma_f32_16x16x32_f16 v[52:55], v[58:61], v[110:113], v[52:55]
	global_load_dwordx4 v[58:61], v[0:1], off offset:512
	v_mfma_f32_16x16x32_f16 v[102:105], v[94:97], v[106:109], v[102:105]
	v_mfma_f32_16x16x32_f16 v[24:27], v[94:97], v[110:113], v[24:27]
	v_mfma_f32_16x16x32_f16 v[114:117], v[118:121], v[106:109], v[114:117]
	v_mfma_f32_16x16x32_f16 v[40:43], v[118:121], v[110:113], v[40:43]
	v_mfma_f32_16x16x32_f16 v[70:73], v[122:125], v[106:109], v[70:73]
	global_load_dwordx4 v[106:109], v[2:3], off offset:512
	global_load_dwordx4 v[126:129], v[4:5], off offset:512
	global_load_dwordx4 v[134:137], v[14:15], off offset:512
	global_load_dwordx4 v[94:97], v[10:11], off offset:512
	global_load_dwordx4 v[162:165], v[12:13], off offset:512
	global_load_dwordx4 v[166:169], v[8:9], off offset:512
	global_load_dwordx4 v[190:193], v[6:7], off offset:512
	s_waitcnt lgkmcnt(0)
	s_barrier
	v_mfma_f32_16x16x32_f16 v[48:51], v[122:125], v[110:113], v[48:51]
	ds_read_b128 v[62:65], v16 offset:49152
	ds_read_b128 v[90:93], v21 offset:16384
	s_waitcnt lgkmcnt(0)
	v_mfma_f32_16x16x32_f16 v[36:39], v[62:65], v[90:93], v[36:39]
	ds_read_b128 v[74:77], v16 offset:51200
	ds_read_b128 v[110:113], v21 offset:18432
	s_waitcnt lgkmcnt(0)
	v_mfma_f32_16x16x32_f16 v[66:69], v[62:65], v[110:113], v[66:69]
	ds_read_b128 v[118:121], v16 offset:53248
	v_mfma_f32_16x16x32_f16 v[44:47], v[74:77], v[90:93], v[44:47]
	ds_read_b128 v[122:125], v16 offset:55296
	v_mfma_f32_16x16x32_f16 v[78:81], v[74:77], v[110:113], v[78:81]
	s_waitcnt vmcnt(7)
	ds_write_b128 v17, v[58:61]
	s_waitcnt lgkmcnt(2)
	v_mfma_f32_16x16x32_f16 v[82:85], v[118:121], v[90:93], v[82:85]
	s_waitcnt vmcnt(6)
	ds_write_b128 v18, v[106:109]
	v_mfma_f32_16x16x32_f16 v[86:89], v[118:121], v[110:113], v[86:89]
	s_waitcnt vmcnt(5)
	ds_write_b128 v19, v[126:129]
	s_waitcnt lgkmcnt(3)
	v_mfma_f32_16x16x32_f16 v[28:31], v[122:125], v[90:93], v[28:31]
	ds_read_b128 v[90:93], v21 offset:20480
	v_mfma_f32_16x16x32_f16 v[32:35], v[122:125], v[110:113], v[32:35]
	ds_read_b128 v[110:113], v21 offset:22528
	s_waitcnt lgkmcnt(1)
	v_mfma_f32_16x16x32_f16 v[98:101], v[62:65], v[90:93], v[98:101]
	s_waitcnt vmcnt(4)
	ds_write_b128 v20, v[134:137]
	s_waitcnt lgkmcnt(1)
	v_mfma_f32_16x16x32_f16 v[52:55], v[62:65], v[110:113], v[52:55]
	ds_read_b128 v[62:65], v22 offset:49152
	v_mfma_f32_16x16x32_f16 v[102:105], v[74:77], v[90:93], v[102:105]
	s_waitcnt vmcnt(3)
	ds_write_b128 v17, v[94:97] offset:32768
	v_mfma_f32_16x16x32_f16 v[24:27], v[74:77], v[110:113], v[24:27]
	ds_read_b128 v[74:77], v22 offset:51200
	v_mfma_f32_16x16x32_f16 v[114:117], v[118:121], v[90:93], v[114:117]
	s_waitcnt vmcnt(2)
	ds_write_b128 v18, v[162:165] offset:32768
	v_mfma_f32_16x16x32_f16 v[40:43], v[118:121], v[110:113], v[40:43]
	ds_read_b128 v[118:121], v22 offset:53248
	v_mfma_f32_16x16x32_f16 v[70:73], v[122:125], v[90:93], v[70:73]
	ds_read_b128 v[90:93], v23 offset:16384
	v_mfma_f32_16x16x32_f16 v[48:51], v[122:125], v[110:113], v[48:51]
	ds_read_b128 v[110:113], v23 offset:18432
	s_waitcnt lgkmcnt(1)
	v_mfma_f32_16x16x32_f16 v[36:39], v[62:65], v[90:93], v[36:39]
	ds_read_b128 v[122:125], v22 offset:55296
	s_waitcnt lgkmcnt(1)
	v_mfma_f32_16x16x32_f16 v[66:69], v[62:65], v[110:113], v[66:69]
	s_waitcnt vmcnt(1)
	ds_write_b128 v19, v[166:169] offset:32768
	v_mfma_f32_16x16x32_f16 v[44:47], v[74:77], v[90:93], v[44:47]
	s_waitcnt vmcnt(0)
	ds_write_b128 v20, v[190:193] offset:32768
	v_mfma_f32_16x16x32_f16 v[78:81], v[74:77], v[110:113], v[78:81]
	v_mfma_f32_16x16x32_f16 v[82:85], v[118:121], v[90:93], v[82:85]
	v_mfma_f32_16x16x32_f16 v[86:89], v[118:121], v[110:113], v[86:89]
	s_waitcnt lgkmcnt(2)
	v_mfma_f32_16x16x32_f16 v[28:31], v[122:125], v[90:93], v[28:31]
	ds_read_b128 v[90:93], v23 offset:20480
	v_mfma_f32_16x16x32_f16 v[32:35], v[122:125], v[110:113], v[32:35]
	ds_read_b128 v[110:113], v23 offset:22528
	s_waitcnt lgkmcnt(1)
	v_mfma_f32_16x16x32_f16 v[98:101], v[62:65], v[90:93], v[98:101]
	s_waitcnt lgkmcnt(0)
	v_mfma_f32_16x16x32_f16 v[52:55], v[62:65], v[110:113], v[52:55]
	global_load_dwordx4 v[62:65], v[0:1], off offset:640
	v_mfma_f32_16x16x32_f16 v[102:105], v[74:77], v[90:93], v[102:105]
	v_mfma_f32_16x16x32_f16 v[24:27], v[74:77], v[110:113], v[24:27]
	v_mfma_f32_16x16x32_f16 v[114:117], v[118:121], v[90:93], v[114:117]
	v_mfma_f32_16x16x32_f16 v[40:43], v[118:121], v[110:113], v[40:43]
	v_mfma_f32_16x16x32_f16 v[70:73], v[122:125], v[90:93], v[70:73]
	global_load_dwordx4 v[90:93], v[2:3], off offset:640
	global_load_dwordx4 v[130:133], v[4:5], off offset:640
	global_load_dwordx4 v[138:141], v[14:15], off offset:640
	global_load_dwordx4 v[74:77], v[10:11], off offset:640
	global_load_dwordx4 v[142:145], v[12:13], off offset:640
	global_load_dwordx4 v[154:157], v[8:9], off offset:640
	global_load_dwordx4 v[158:161], v[6:7], off offset:640
	s_waitcnt lgkmcnt(0)
	s_barrier
; #define GL_LOAD(s_, kt_) if (VAR != 1) { a##s_##0 = GL_A(0, kt_); a##s_##1 = GL_A(1, kt_); a##s_##2 = GL_A(2, kt_); a##s_##3 = GL_A(3, kt_); b##s_##0 = GL_B(0, kt_); b##s_##1 = GL_B(1, kt_); b##s_##2 = GL_B(2, kt_); b##s_##3 = GL_B(3, kt_); }
; #define LDS_STORE(s_, buf_) if (VAR != 2) { LDS_ST1(sA, 0, buf_, a##s_##0) LDS_ST1(sA, 1, buf_, a##s_##1) LDS_ST1(sA, 2, buf_, a##s_##2) LDS_ST1(sA, 3, buf_, a##s_##3) LDS_ST1(sB, 0, buf_, b##s_##0) LDS_ST1(sB, 1, buf_, b##s_##1) LDS_ST1(sB, 2, buf_, b##s_##2) LDS_ST1(sB, 3, buf_, b##s_##3) }
;     ...
;   GL_LOAD(0, 0)
;   GL_LOAD(1, 1)
;   LDS_STORE(0, 0)
;   if (VAR != 4) __syncthreads();
; #pragma unroll
;   for (int kt = 0; kt < nk; kt += 2) {
;     if (kt + 2 < nk) { GL_LOAD(0, kt + 2) }
;     MMA_TILE(0)
;     LDS_STORE(1, 1)
;     if (VAR != 4) __syncthreads();
;     if (kt + 3 < nk) { GL_LOAD(1, kt + 3) }
;     MMA_TILE(1)
;     if (kt + 2 < nk) { LDS_STORE(0, 0) }
;     if (VAR != 4) __syncthreads();
	v_mfma_f32_16x16x32_f16 v[48:51], v[122:125], v[110:113], v[48:51]
	ds_read_b128 v[58:61], v16 offset:32768
	ds_read_b128 v[106:109], v21
	s_waitcnt lgkmcnt(0)
	v_mfma_f32_16x16x32_f16 v[36:39], v[58:61], v[106:109], v[36:39]
	ds_read_b128 v[94:97], v16 offset:34816
	ds_read_b128 v[110:113], v21 offset:2048
	s_waitcnt lgkmcnt(0)
	v_mfma_f32_16x16x32_f16 v[66:69], v[58:61], v[110:113], v[66:69]
	ds_read_b128 v[118:121], v16 offset:36864
	v_mfma_f32_16x16x32_f16 v[44:47], v[94:97], v[106:109], v[44:47]
	ds_read_b128 v[122:125], v16 offset:38912
	v_mfma_f32_16x16x32_f16 v[78:81], v[94:97], v[110:113], v[78:81]
	s_waitcnt vmcnt(7)
	ds_write_b128 v17, v[62:65] offset:16384
	s_waitcnt lgkmcnt(2)
	v_mfma_f32_16x16x32_f16 v[82:85], v[118:121], v[106:109], v[82:85]
	s_waitcnt vmcnt(6)
	ds_write_b128 v18, v[90:93] offset:16384
	v_mfma_f32_16x16x32_f16 v[86:89], v[118:121], v[110:113], v[86:89]
	s_waitcnt vmcnt(5)
	ds_write_b128 v19, v[130:133] offset:16384
	s_waitcnt lgkmcnt(3)
	v_mfma_f32_16x16x32_f16 v[28:31], v[122:125], v[106:109], v[28:31]
	ds_read_b128 v[106:109], v21 offset:4096
	v_mfma_f32_16x16x32_f16 v[32:35], v[122:125], v[110:113], v[32:35]
	ds_read_b128 v[110:113], v21 offset:6144
	s_waitcnt lgkmcnt(1)
	v_mfma_f32_16x16x32_f16 v[98:101], v[58:61], v[106:109], v[98:101]
	s_waitcnt vmcnt(4)
	ds_write_b128 v20, v[138:141] offset:16384
	s_waitcnt lgkmcnt(1)
	v_mfma_f32_16x16x32_f16 v[52:55], v[58:61], v[110:113], v[52:55]
	ds_read_b128 v[58:61], v22 offset:32768
	v_mfma_f32_16x16x32_f16 v[102:105], v[94:97], v[106:109], v[102:105]
	s_waitcnt vmcnt(3)
	ds_write_b128 v17, v[74:77] offset:49152
	v_mfma_f32_16x16x32_f16 v[24:27], v[94:97], v[110:113], v[24:27]
	ds_read_b128 v[94:97], v22 offset:34816
	v_mfma_f32_16x16x32_f16 v[114:117], v[118:121], v[106:109], v[114:117]
	s_waitcnt vmcnt(2)
	ds_write_b128 v18, v[142:145] offset:49152
	v_mfma_f32_16x16x32_f16 v[40:43], v[118:121], v[110:113], v[40:43]
	ds_read_b128 v[118:121], v22 offset:36864
	v_mfma_f32_16x16x32_f16 v[70:73], v[122:125], v[106:109], v[70:73]
	ds_read_b128 v[106:109], v23
	v_mfma_f32_16x16x32_f16 v[48:51], v[122:125], v[110:113], v[48:51]
	ds_read_b128 v[110:113], v23 offset:2048
	s_waitcnt lgkmcnt(1)
	v_mfma_f32_16x16x32_f16 v[36:39], v[58:61], v[106:109], v[36:39]
	ds_read_b128 v[122:125], v22 offset:38912
	s_waitcnt lgkmcnt(1)
	v_mfma_f32_16x16x32_f16 v[66:69], v[58:61], v[110:113], v[66:69]
	s_waitcnt vmcnt(1)
	ds_write_b128 v19, v[154:157] offset:49152
	v_mfma_f32_16x16x32_f16 v[44:47], v[94:97], v[106:109], v[44:47]
	s_waitcnt vmcnt(0)
	ds_write_b128 v20, v[158:161] offset:49152
	v_mfma_f32_16x16x32_f16 v[78:81], v[94:97], v[110:113], v[78:81]
	v_mfma_f32_16x16x32_f16 v[82:85], v[118:121], v[106:109], v[82:85]
	v_mfma_f32_16x16x32_f16 v[86:89], v[118:121], v[110:113], v[86:89]
	s_waitcnt lgkmcnt(2)
	v_mfma_f32_16x16x32_f16 v[28:31], v[122:125], v[106:109], v[28:31]
	ds_read_b128 v[106:109], v23 offset:4096
	v_mfma_f32_16x16x32_f16 v[32:35], v[122:125], v[110:113], v[32:35]
	ds_read_b128 v[110:113], v23 offset:6144
	s_waitcnt lgkmcnt(1)
	v_mfma_f32_16x16x32_f16 v[98:101], v[58:61], v[106:109], v[98:101]
	s_waitcnt lgkmcnt(0)
	v_mfma_f32_16x16x32_f16 v[52:55], v[58:61], v[110:113], v[52:55]
	global_load_dwordx4 v[58:61], v[0:1], off offset:768
	v_mfma_f32_16x16x32_f16 v[102:105], v[94:97], v[106:109], v[102:105]
	v_mfma_f32_16x16x32_f16 v[24:27], v[94:97], v[110:113], v[24:27]
	v_mfma_f32_16x16x32_f16 v[114:117], v[118:121], v[106:109], v[114:117]
	v_mfma_f32_16x16x32_f16 v[40:43], v[118:121], v[110:113], v[40:43]
	v_mfma_f32_16x16x32_f16 v[70:73], v[122:125], v[106:109], v[70:73]
	global_load_dwordx4 v[106:109], v[2:3], off offset:768
	global_load_dwordx4 v[126:129], v[4:5], off offset:768
	global_load_dwordx4 v[134:137], v[14:15], off offset:768
	global_load_dwordx4 v[94:97], v[10:11], off offset:768
	global_load_dwordx4 v[162:165], v[12:13], off offset:768
	global_load_dwordx4 v[166:169], v[8:9], off offset:768
	global_load_dwordx4 v[190:193], v[6:7], off offset:768
	s_waitcnt lgkmcnt(0)
	s_barrier
	v_mfma_f32_16x16x32_f16 v[48:51], v[122:125], v[110:113], v[48:51]
	ds_read_b128 v[62:65], v16 offset:49152
	ds_read_b128 v[90:93], v21 offset:16384
	s_waitcnt lgkmcnt(0)
	v_mfma_f32_16x16x32_f16 v[36:39], v[62:65], v[90:93], v[36:39]
	ds_read_b128 v[74:77], v16 offset:51200
	ds_read_b128 v[110:113], v21 offset:18432
	s_waitcnt lgkmcnt(0)
	v_mfma_f32_16x16x32_f16 v[66:69], v[62:65], v[110:113], v[66:69]
	ds_read_b128 v[118:121], v16 offset:53248
	v_mfma_f32_16x16x32_f16 v[44:47], v[74:77], v[90:93], v[44:47]
	ds_read_b128 v[122:125], v16 offset:55296
	v_mfma_f32_16x16x32_f16 v[78:81], v[74:77], v[110:113], v[78:81]
	s_waitcnt vmcnt(7)
	ds_write_b128 v17, v[58:61]
	s_waitcnt lgkmcnt(2)
	v_mfma_f32_16x16x32_f16 v[82:85], v[118:121], v[90:93], v[82:85]
	s_waitcnt vmcnt(6)
	ds_write_b128 v18, v[106:109]
	v_mfma_f32_16x16x32_f16 v[86:89], v[118:121], v[110:113], v[86:89]
	s_waitcnt vmcnt(5)
	ds_write_b128 v19, v[126:129]
	s_waitcnt lgkmcnt(3)
	v_mfma_f32_16x16x32_f16 v[28:31], v[122:125], v[90:93], v[28:31]
	ds_read_b128 v[90:93], v21 offset:20480
	v_mfma_f32_16x16x32_f16 v[32:35], v[122:125], v[110:113], v[32:35]
	ds_read_b128 v[110:113], v21 offset:22528
	s_waitcnt lgkmcnt(1)
	v_mfma_f32_16x16x32_f16 v[98:101], v[62:65], v[90:93], v[98:101]
	s_waitcnt vmcnt(4)
	ds_write_b128 v20, v[134:137]
	s_waitcnt lgkmcnt(1)
	v_mfma_f32_16x16x32_f16 v[52:55], v[62:65], v[110:113], v[52:55]
	ds_read_b128 v[62:65], v22 offset:49152
	v_mfma_f32_16x16x32_f16 v[102:105], v[74:77], v[90:93], v[102:105]
	s_waitcnt vmcnt(3)
; #define GL_LOAD(s_, kt_) if (VAR != 1) { a##s_##0 = GL_A(0, kt_); a##s_##1 = GL_A(1, kt_); a##s_##2 = GL_A(2, kt_); a##s_##3 = GL_A(3, kt_); b##s_##0 = GL_B(0, kt_); b##s_##1 = GL_B(1, kt_); b##s_##2 = GL_B(2, kt_); b##s_##3 = GL_B(3, kt_); }
; #define LDS_STORE(s_, buf_) if (VAR != 2) { LDS_ST1(sA, 0, buf_, a##s_##0) LDS_ST1(sA, 1, buf_, a##s_##1) LDS_ST1(sA, 2, buf_, a##s_##2) LDS_ST1(sA, 3, buf_, a##s_##3) LDS_ST1(sB, 0, buf_, b##s_##0) LDS_ST1(sB, 1, buf_, b##s_##1) LDS_ST1(sB, 2, buf_, b##s_##2) LDS_ST1(sB, 3, buf_, b##s_##3) }
;     ...
;   GL_LOAD(0, 0)
;   GL_LOAD(1, 1)
;   LDS_STORE(0, 0)
;   if (VAR != 4) __syncthreads();
; #pragma unroll
;   for (int kt = 0; kt < nk; kt += 2) {
;     if (kt + 2 < nk) { GL_LOAD(0, kt + 2) }
;     MMA_TILE(0)
;     LDS_STORE(1, 1)
;     if (VAR != 4) __syncthreads();
;     if (kt + 3 < nk) { GL_LOAD(1, kt + 3) }
;     MMA_TILE(1)
;     if (kt + 2 < nk) { LDS_STORE(0, 0) }
;     if (VAR != 4) __syncthreads();
	ds_write_b128 v17, v[94:97] offset:32768
	v_mfma_f32_16x16x32_f16 v[24:27], v[74:77], v[110:113], v[24:27]
	ds_read_b128 v[74:77], v22 offset:51200
	v_mfma_f32_16x16x32_f16 v[114:117], v[118:121], v[90:93], v[114:117]
	s_waitcnt vmcnt(2)
	ds_write_b128 v18, v[162:165] offset:32768
	v_mfma_f32_16x16x32_f16 v[40:43], v[118:121], v[110:113], v[40:43]
	ds_read_b128 v[118:121], v22 offset:53248
	v_mfma_f32_16x16x32_f16 v[70:73], v[122:125], v[90:93], v[70:73]
	ds_read_b128 v[90:93], v23 offset:16384
	v_mfma_f32_16x16x32_f16 v[48:51], v[122:125], v[110:113], v[48:51]
	ds_read_b128 v[110:113], v23 offset:18432
	s_waitcnt lgkmcnt(1)
	v_mfma_f32_16x16x32_f16 v[36:39], v[62:65], v[90:93], v[36:39]
	ds_read_b128 v[122:125], v22 offset:55296
	s_waitcnt lgkmcnt(1)
	v_mfma_f32_16x16x32_f16 v[66:69], v[62:65], v[110:113], v[66:69]
	s_waitcnt vmcnt(1)
	ds_write_b128 v19, v[166:169] offset:32768
	v_mfma_f32_16x16x32_f16 v[44:47], v[74:77], v[90:93], v[44:47]
	s_waitcnt vmcnt(0)
	ds_write_b128 v20, v[190:193] offset:32768
	v_mfma_f32_16x16x32_f16 v[78:81], v[74:77], v[110:113], v[78:81]
	v_mfma_f32_16x16x32_f16 v[82:85], v[118:121], v[90:93], v[82:85]
	v_mfma_f32_16x16x32_f16 v[86:89], v[118:121], v[110:113], v[86:89]
	s_waitcnt lgkmcnt(2)
	v_mfma_f32_16x16x32_f16 v[28:31], v[122:125], v[90:93], v[28:31]
	ds_read_b128 v[90:93], v23 offset:20480
	v_mfma_f32_16x16x32_f16 v[32:35], v[122:125], v[110:113], v[32:35]
	ds_read_b128 v[110:113], v23 offset:22528
	s_waitcnt lgkmcnt(1)
	v_mfma_f32_16x16x32_f16 v[98:101], v[62:65], v[90:93], v[98:101]
	s_waitcnt lgkmcnt(0)
	v_mfma_f32_16x16x32_f16 v[52:55], v[62:65], v[110:113], v[52:55]
	global_load_dwordx4 v[62:65], v[0:1], off offset:896
	v_mfma_f32_16x16x32_f16 v[102:105], v[74:77], v[90:93], v[102:105]
	v_mfma_f32_16x16x32_f16 v[24:27], v[74:77], v[110:113], v[24:27]
	v_mfma_f32_16x16x32_f16 v[114:117], v[118:121], v[90:93], v[114:117]
	v_mfma_f32_16x16x32_f16 v[40:43], v[118:121], v[110:113], v[40:43]
	v_mfma_f32_16x16x32_f16 v[70:73], v[122:125], v[90:93], v[70:73]
	global_load_dwordx4 v[90:93], v[2:3], off offset:896
	global_load_dwordx4 v[130:133], v[4:5], off offset:896
	global_load_dwordx4 v[138:141], v[14:15], off offset:896
	global_load_dwordx4 v[74:77], v[10:11], off offset:896
	global_load_dwordx4 v[142:145], v[12:13], off offset:896
	global_load_dwordx4 v[154:157], v[8:9], off offset:896
	global_load_dwordx4 v[158:161], v[6:7], off offset:896
	s_waitcnt lgkmcnt(0)
	s_barrier
	v_mfma_f32_16x16x32_f16 v[48:51], v[122:125], v[110:113], v[48:51]
	ds_read_b128 v[58:61], v16 offset:32768
	ds_read_b128 v[106:109], v21
	s_waitcnt lgkmcnt(0)
	v_mfma_f32_16x16x32_f16 v[36:39], v[58:61], v[106:109], v[36:39]
	ds_read_b128 v[94:97], v16 offset:34816
	ds_read_b128 v[110:113], v21 offset:2048
	s_waitcnt lgkmcnt(0)
	v_mfma_f32_16x16x32_f16 v[66:69], v[58:61], v[110:113], v[66:69]
	ds_read_b128 v[118:121], v16 offset:36864
	v_mfma_f32_16x16x32_f16 v[44:47], v[94:97], v[106:109], v[44:47]
	ds_read_b128 v[122:125], v16 offset:38912
	v_mfma_f32_16x16x32_f16 v[78:81], v[94:97], v[110:113], v[78:81]
	s_waitcnt vmcnt(7)
	ds_write_b128 v17, v[62:65] offset:16384
	s_waitcnt lgkmcnt(2)
	v_mfma_f32_16x16x32_f16 v[82:85], v[118:121], v[106:109], v[82:85]
	s_waitcnt vmcnt(6)
	ds_write_b128 v18, v[90:93] offset:16384
	v_mfma_f32_16x16x32_f16 v[86:89], v[118:121], v[110:113], v[86:89]
	s_waitcnt vmcnt(5)
	ds_write_b128 v19, v[130:133] offset:16384
	s_waitcnt lgkmcnt(3)
	v_mfma_f32_16x16x32_f16 v[28:31], v[122:125], v[106:109], v[28:31]
	ds_read_b128 v[106:109], v21 offset:4096
	v_mfma_f32_16x16x32_f16 v[32:35], v[122:125], v[110:113], v[32:35]
	ds_read_b128 v[110:113], v21 offset:6144
	s_waitcnt lgkmcnt(1)
	v_mfma_f32_16x16x32_f16 v[98:101], v[58:61], v[106:109], v[98:101]
	s_waitcnt vmcnt(4)
	ds_write_b128 v20, v[138:141] offset:16384
	s_waitcnt lgkmcnt(1)
	v_mfma_f32_16x16x32_f16 v[52:55], v[58:61], v[110:113], v[52:55]
	ds_read_b128 v[58:61], v22 offset:32768
	v_mfma_f32_16x16x32_f16 v[102:105], v[94:97], v[106:109], v[102:105]
	s_waitcnt vmcnt(3)
	ds_write_b128 v17, v[74:77] offset:49152
	v_mfma_f32_16x16x32_f16 v[24:27], v[94:97], v[110:113], v[24:27]
	ds_read_b128 v[94:97], v22 offset:34816
	v_mfma_f32_16x16x32_f16 v[114:117], v[118:121], v[106:109], v[114:117]
	s_waitcnt vmcnt(2)
	ds_write_b128 v18, v[142:145] offset:49152
	v_mfma_f32_16x16x32_f16 v[40:43], v[118:121], v[110:113], v[40:43]
	ds_read_b128 v[118:121], v22 offset:36864
	v_mfma_f32_16x16x32_f16 v[70:73], v[122:125], v[106:109], v[70:73]
	ds_read_b128 v[106:109], v23
	v_mfma_f32_16x16x32_f16 v[48:51], v[122:125], v[110:113], v[48:51]
	ds_read_b128 v[110:113], v23 offset:2048
	s_waitcnt lgkmcnt(1)
	v_mfma_f32_16x16x32_f16 v[36:39], v[58:61], v[106:109], v[36:39]
	ds_read_b128 v[122:125], v22 offset:38912
	s_waitcnt lgkmcnt(1)
	v_mfma_f32_16x16x32_f16 v[66:69], v[58:61], v[110:113], v[66:69]
	s_waitcnt vmcnt(1)
	ds_write_b128 v19, v[154:157] offset:49152
	v_mfma_f32_16x16x32_f16 v[44:47], v[94:97], v[106:109], v[44:47]
	s_waitcnt vmcnt(0)
	ds_write_b128 v20, v[158:161] offset:49152
	v_mfma_f32_16x16x32_f16 v[78:81], v[94:97], v[110:113], v[78:81]
	v_mfma_f32_16x16x32_f16 v[82:85], v[118:121], v[106:109], v[82:85]
	v_mfma_f32_16x16x32_f16 v[86:89], v[118:121], v[110:113], v[86:89]
	s_waitcnt lgkmcnt(2)
	v_mfma_f32_16x16x32_f16 v[28:31], v[122:125], v[106:109], v[28:31]
	ds_read_b128 v[106:109], v23 offset:4096
	v_mfma_f32_16x16x32_f16 v[32:35], v[122:125], v[110:113], v[32:35]
	ds_read_b128 v[110:113], v23 offset:6144
	s_waitcnt lgkmcnt(1)
	v_mfma_f32_16x16x32_f16 v[98:101], v[58:61], v[106:109], v[98:101]
	s_waitcnt lgkmcnt(0)
	v_mfma_f32_16x16x32_f16 v[52:55], v[58:61], v[110:113], v[52:55]
	global_load_dwordx4 v[58:61], v[0:1], off offset:1024
	v_mfma_f32_16x16x32_f16 v[102:105], v[94:97], v[106:109], v[102:105]
	v_mfma_f32_16x16x32_f16 v[24:27], v[94:97], v[110:113], v[24:27]
	v_mfma_f32_16x16x32_f16 v[114:117], v[118:121], v[106:109], v[114:117]
	v_mfma_f32_16x16x32_f16 v[40:43], v[118:121], v[110:113], v[40:43]
	v_mfma_f32_16x16x32_f16 v[70:73], v[122:125], v[106:109], v[70:73]
	global_load_dwordx4 v[106:109], v[2:3], off offset:1024
	global_load_dwordx4 v[126:129], v[4:5], off offset:1024
	global_load_dwordx4 v[134:137], v[14:15], off offset:1024
	global_load_dwordx4 v[94:97], v[10:11], off offset:1024
	global_load_dwordx4 v[162:165], v[12:13], off offset:1024
	global_load_dwordx4 v[166:169], v[8:9], off offset:1024
	global_load_dwordx4 v[190:193], v[6:7], off offset:1024
	s_waitcnt lgkmcnt(0)
	s_barrier
; #define GL_LOAD(s_, kt_) if (VAR != 1) { a##s_##0 = GL_A(0, kt_); a##s_##1 = GL_A(1, kt_); a##s_##2 = GL_A(2, kt_); a##s_##3 = GL_A(3, kt_); b##s_##0 = GL_B(0, kt_); b##s_##1 = GL_B(1, kt_); b##s_##2 = GL_B(2, kt_); b##s_##3 = GL_B(3, kt_); }
; #define LDS_STORE(s_, buf_) if (VAR != 2) { LDS_ST1(sA, 0, buf_, a##s_##0) LDS_ST1(sA, 1, buf_, a##s_##1) LDS_ST1(sA, 2, buf_, a##s_##2) LDS_ST1(sA, 3, buf_, a##s_##3) LDS_ST1(sB, 0, buf_, b##s_##0) LDS_ST1(sB, 1, buf_, b##s_##1) LDS_ST1(sB, 2, buf_, b##s_##2) LDS_ST1(sB, 3, buf_, b##s_##3) }
;     ...
;   GL_LOAD(0, 0)
;   GL_LOAD(1, 1)
;   LDS_STORE(0, 0)
;   if (VAR != 4) __syncthreads();
; #pragma unroll
;   for (int kt = 0; kt < nk; kt += 2) {
;     if (kt + 2 < nk) { GL_LOAD(0, kt + 2) }
;     MMA_TILE(0)
;     LDS_STORE(1, 1)
;     if (VAR != 4) __syncthreads();
;     if (kt + 3 < nk) { GL_LOAD(1, kt + 3) }
;     MMA_TILE(1)
;     if (kt + 2 < nk) { LDS_STORE(0, 0) }
;     if (VAR != 4) __syncthreads();
	v_mfma_f32_16x16x32_f16 v[48:51], v[122:125], v[110:113], v[48:51]
	ds_read_b128 v[62:65], v16 offset:49152
	ds_read_b128 v[90:93], v21 offset:16384
	s_waitcnt lgkmcnt(0)
	v_mfma_f32_16x16x32_f16 v[36:39], v[62:65], v[90:93], v[36:39]
	ds_read_b128 v[74:77], v16 offset:51200
	ds_read_b128 v[110:113], v21 offset:18432
	s_waitcnt lgkmcnt(0)
	v_mfma_f32_16x16x32_f16 v[66:69], v[62:65], v[110:113], v[66:69]
	ds_read_b128 v[118:121], v16 offset:53248
	v_mfma_f32_16x16x32_f16 v[44:47], v[74:77], v[90:93], v[44:47]
	ds_read_b128 v[122:125], v16 offset:55296
	v_mfma_f32_16x16x32_f16 v[78:81], v[74:77], v[110:113], v[78:81]
	s_waitcnt vmcnt(7)
	ds_write_b128 v17, v[58:61]
	s_waitcnt lgkmcnt(2)
	v_mfma_f32_16x16x32_f16 v[82:85], v[118:121], v[90:93], v[82:85]
	s_waitcnt vmcnt(6)
	ds_write_b128 v18, v[106:109]
	v_mfma_f32_16x16x32_f16 v[86:89], v[118:121], v[110:113], v[86:89]
	s_waitcnt vmcnt(5)
	ds_write_b128 v19, v[126:129]
	s_waitcnt lgkmcnt(3)
	v_mfma_f32_16x16x32_f16 v[28:31], v[122:125], v[90:93], v[28:31]
	ds_read_b128 v[90:93], v21 offset:20480
	v_mfma_f32_16x16x32_f16 v[32:35], v[122:125], v[110:113], v[32:35]
	ds_read_b128 v[110:113], v21 offset:22528
	s_waitcnt lgkmcnt(1)
	v_mfma_f32_16x16x32_f16 v[98:101], v[62:65], v[90:93], v[98:101]
	s_waitcnt vmcnt(4)
	ds_write_b128 v20, v[134:137]
	s_waitcnt lgkmcnt(1)
	v_mfma_f32_16x16x32_f16 v[52:55], v[62:65], v[110:113], v[52:55]
	ds_read_b128 v[62:65], v22 offset:49152
	v_mfma_f32_16x16x32_f16 v[102:105], v[74:77], v[90:93], v[102:105]
	s_waitcnt vmcnt(3)
	ds_write_b128 v17, v[94:97] offset:32768
	v_mfma_f32_16x16x32_f16 v[24:27], v[74:77], v[110:113], v[24:27]
	ds_read_b128 v[74:77], v22 offset:51200
	v_mfma_f32_16x16x32_f16 v[114:117], v[118:121], v[90:93], v[114:117]
	s_waitcnt vmcnt(2)
	ds_write_b128 v18, v[162:165] offset:32768
	v_mfma_f32_16x16x32_f16 v[40:43], v[118:121], v[110:113], v[40:43]
	ds_read_b128 v[118:121], v22 offset:53248
	v_mfma_f32_16x16x32_f16 v[70:73], v[122:125], v[90:93], v[70:73]
	ds_read_b128 v[90:93], v23 offset:16384
	v_mfma_f32_16x16x32_f16 v[48:51], v[122:125], v[110:113], v[48:51]
	ds_read_b128 v[110:113], v23 offset:18432
	s_waitcnt lgkmcnt(1)
	v_mfma_f32_16x16x32_f16 v[36:39], v[62:65], v[90:93], v[36:39]
	ds_read_b128 v[122:125], v22 offset:55296
	s_waitcnt lgkmcnt(1)
	v_mfma_f32_16x16x32_f16 v[66:69], v[62:65], v[110:113], v[66:69]
	s_waitcnt vmcnt(1)
	ds_write_b128 v19, v[166:169] offset:32768
	v_mfma_f32_16x16x32_f16 v[44:47], v[74:77], v[90:93], v[44:47]
	s_waitcnt vmcnt(0)
	ds_write_b128 v20, v[190:193] offset:32768
	v_mfma_f32_16x16x32_f16 v[78:81], v[74:77], v[110:113], v[78:81]
	v_mfma_f32_16x16x32_f16 v[82:85], v[118:121], v[90:93], v[82:85]
	v_mfma_f32_16x16x32_f16 v[86:89], v[118:121], v[110:113], v[86:89]
	s_waitcnt lgkmcnt(2)
	v_mfma_f32_16x16x32_f16 v[28:31], v[122:125], v[90:93], v[28:31]
	ds_read_b128 v[90:93], v23 offset:20480
	v_mfma_f32_16x16x32_f16 v[32:35], v[122:125], v[110:113], v[32:35]
	ds_read_b128 v[110:113], v23 offset:22528
	s_waitcnt lgkmcnt(1)
	v_mfma_f32_16x16x32_f16 v[98:101], v[62:65], v[90:93], v[98:101]
	s_waitcnt lgkmcnt(0)
	v_mfma_f32_16x16x32_f16 v[52:55], v[62:65], v[110:113], v[52:55]
	global_load_dwordx4 v[62:65], v[0:1], off offset:1152
	v_mfma_f32_16x16x32_f16 v[102:105], v[74:77], v[90:93], v[102:105]
	v_mfma_f32_16x16x32_f16 v[24:27], v[74:77], v[110:113], v[24:27]
	v_mfma_f32_16x16x32_f16 v[114:117], v[118:121], v[90:93], v[114:117]
	v_mfma_f32_16x16x32_f16 v[40:43], v[118:121], v[110:113], v[40:43]
	v_mfma_f32_16x16x32_f16 v[70:73], v[122:125], v[90:93], v[70:73]
	global_load_dwordx4 v[90:93], v[2:3], off offset:1152
	global_load_dwordx4 v[130:133], v[4:5], off offset:1152
	global_load_dwordx4 v[138:141], v[14:15], off offset:1152
	global_load_dwordx4 v[74:77], v[10:11], off offset:1152
	global_load_dwordx4 v[142:145], v[12:13], off offset:1152
	global_load_dwordx4 v[154:157], v[8:9], off offset:1152
	global_load_dwordx4 v[158:161], v[6:7], off offset:1152
	s_waitcnt lgkmcnt(0)
	s_barrier
	v_mfma_f32_16x16x32_f16 v[48:51], v[122:125], v[110:113], v[48:51]
	ds_read_b128 v[58:61], v16 offset:32768
	ds_read_b128 v[106:109], v21
	s_waitcnt lgkmcnt(0)
	v_mfma_f32_16x16x32_f16 v[36:39], v[58:61], v[106:109], v[36:39]
	ds_read_b128 v[94:97], v16 offset:34816
	ds_read_b128 v[110:113], v21 offset:2048
	s_waitcnt lgkmcnt(0)
	v_mfma_f32_16x16x32_f16 v[66:69], v[58:61], v[110:113], v[66:69]
	ds_read_b128 v[118:121], v16 offset:36864
	v_mfma_f32_16x16x32_f16 v[44:47], v[94:97], v[106:109], v[44:47]
	ds_read_b128 v[122:125], v16 offset:38912
	v_mfma_f32_16x16x32_f16 v[78:81], v[94:97], v[110:113], v[78:81]
	s_waitcnt vmcnt(7)
	ds_write_b128 v17, v[62:65] offset:16384
	s_waitcnt lgkmcnt(2)
	v_mfma_f32_16x16x32_f16 v[82:85], v[118:121], v[106:109], v[82:85]
	s_waitcnt vmcnt(6)
	ds_write_b128 v18, v[90:93] offset:16384
	v_mfma_f32_16x16x32_f16 v[86:89], v[118:121], v[110:113], v[86:89]
	s_waitcnt vmcnt(5)
	ds_write_b128 v19, v[130:133] offset:16384
	s_waitcnt lgkmcnt(3)
	v_mfma_f32_16x16x32_f16 v[28:31], v[122:125], v[106:109], v[28:31]
	ds_read_b128 v[106:109], v21 offset:4096
	v_mfma_f32_16x16x32_f16 v[32:35], v[122:125], v[110:113], v[32:35]
	ds_read_b128 v[110:113], v21 offset:6144
	s_waitcnt lgkmcnt(1)
	v_mfma_f32_16x16x32_f16 v[98:101], v[58:61], v[106:109], v[98:101]
	s_waitcnt vmcnt(4)
	ds_write_b128 v20, v[138:141] offset:16384
	s_waitcnt lgkmcnt(1)
	v_mfma_f32_16x16x32_f16 v[52:55], v[58:61], v[110:113], v[52:55]
	ds_read_b128 v[58:61], v22 offset:32768
	v_mfma_f32_16x16x32_f16 v[102:105], v[94:97], v[106:109], v[102:105]
	s_waitcnt vmcnt(3)
; #define GL_LOAD(s_, kt_) if (VAR != 1) { a##s_##0 = GL_A(0, kt_); a##s_##1 = GL_A(1, kt_); a##s_##2 = GL_A(2, kt_); a##s_##3 = GL_A(3, kt_); b##s_##0 = GL_B(0, kt_); b##s_##1 = GL_B(1, kt_); b##s_##2 = GL_B(2, kt_); b##s_##3 = GL_B(3, kt_); }
; #define LDS_STORE(s_, buf_) if (VAR != 2) { LDS_ST1(sA, 0, buf_, a##s_##0) LDS_ST1(sA, 1, buf_, a##s_##1) LDS_ST1(sA, 2, buf_, a##s_##2) LDS_ST1(sA, 3, buf_, a##s_##3) LDS_ST1(sB, 0, buf_, b##s_##0) LDS_ST1(sB, 1, buf_, b##s_##1) LDS_ST1(sB, 2, buf_, b##s_##2) LDS_ST1(sB, 3, buf_, b##s_##3) }
;     ...
;   GL_LOAD(0, 0)
;   GL_LOAD(1, 1)
;   LDS_STORE(0, 0)
;   if (VAR != 4) __syncthreads();
; #pragma unroll
;   for (int kt = 0; kt < nk; kt += 2) {
;     if (kt + 2 < nk) { GL_LOAD(0, kt + 2) }
;     MMA_TILE(0)
;     LDS_STORE(1, 1)
;     if (VAR != 4) __syncthreads();
;     if (kt + 3 < nk) { GL_LOAD(1, kt + 3) }
;     MMA_TILE(1)
;     if (kt + 2 < nk) { LDS_STORE(0, 0) }
;     if (VAR != 4) __syncthreads();
	ds_write_b128 v17, v[74:77] offset:49152
	v_mfma_f32_16x16x32_f16 v[24:27], v[94:97], v[110:113], v[24:27]
	ds_read_b128 v[94:97], v22 offset:34816
	v_mfma_f32_16x16x32_f16 v[114:117], v[118:121], v[106:109], v[114:117]
	s_waitcnt vmcnt(2)
	ds_write_b128 v18, v[142:145] offset:49152
	v_mfma_f32_16x16x32_f16 v[40:43], v[118:121], v[110:113], v[40:43]
	ds_read_b128 v[118:121], v22 offset:36864
	v_mfma_f32_16x16x32_f16 v[70:73], v[122:125], v[106:109], v[70:73]
	ds_read_b128 v[106:109], v23
	v_mfma_f32_16x16x32_f16 v[48:51], v[122:125], v[110:113], v[48:51]
	ds_read_b128 v[110:113], v23 offset:2048
	s_waitcnt lgkmcnt(1)
	v_mfma_f32_16x16x32_f16 v[36:39], v[58:61], v[106:109], v[36:39]
	ds_read_b128 v[122:125], v22 offset:38912
	s_waitcnt lgkmcnt(1)
	v_mfma_f32_16x16x32_f16 v[66:69], v[58:61], v[110:113], v[66:69]
	s_waitcnt vmcnt(1)
	ds_write_b128 v19, v[154:157] offset:49152
	v_mfma_f32_16x16x32_f16 v[44:47], v[94:97], v[106:109], v[44:47]
	s_waitcnt vmcnt(0)
	ds_write_b128 v20, v[158:161] offset:49152
	v_mfma_f32_16x16x32_f16 v[78:81], v[94:97], v[110:113], v[78:81]
	v_mfma_f32_16x16x32_f16 v[82:85], v[118:121], v[106:109], v[82:85]
	v_mfma_f32_16x16x32_f16 v[86:89], v[118:121], v[110:113], v[86:89]
	s_waitcnt lgkmcnt(2)
	v_mfma_f32_16x16x32_f16 v[28:31], v[122:125], v[106:109], v[28:31]
	ds_read_b128 v[106:109], v23 offset:4096
	v_mfma_f32_16x16x32_f16 v[32:35], v[122:125], v[110:113], v[32:35]
	ds_read_b128 v[110:113], v23 offset:6144
	s_waitcnt lgkmcnt(1)
	v_mfma_f32_16x16x32_f16 v[98:101], v[58:61], v[106:109], v[98:101]
	s_waitcnt lgkmcnt(0)
	v_mfma_f32_16x16x32_f16 v[52:55], v[58:61], v[110:113], v[52:55]
	global_load_dwordx4 v[58:61], v[0:1], off offset:1280
	v_mfma_f32_16x16x32_f16 v[102:105], v[94:97], v[106:109], v[102:105]
	v_mfma_f32_16x16x32_f16 v[24:27], v[94:97], v[110:113], v[24:27]
	v_mfma_f32_16x16x32_f16 v[114:117], v[118:121], v[106:109], v[114:117]
	v_mfma_f32_16x16x32_f16 v[40:43], v[118:121], v[110:113], v[40:43]
	v_mfma_f32_16x16x32_f16 v[70:73], v[122:125], v[106:109], v[70:73]
	global_load_dwordx4 v[106:109], v[2:3], off offset:1280
	global_load_dwordx4 v[126:129], v[4:5], off offset:1280
	global_load_dwordx4 v[134:137], v[14:15], off offset:1280
	global_load_dwordx4 v[94:97], v[10:11], off offset:1280
	global_load_dwordx4 v[162:165], v[12:13], off offset:1280
	global_load_dwordx4 v[166:169], v[8:9], off offset:1280
	global_load_dwordx4 v[190:193], v[6:7], off offset:1280
	s_waitcnt lgkmcnt(0)
	s_barrier
	v_mfma_f32_16x16x32_f16 v[48:51], v[122:125], v[110:113], v[48:51]
	ds_read_b128 v[62:65], v16 offset:49152
	ds_read_b128 v[90:93], v21 offset:16384
	s_waitcnt lgkmcnt(0)
	v_mfma_f32_16x16x32_f16 v[36:39], v[62:65], v[90:93], v[36:39]
	ds_read_b128 v[74:77], v16 offset:51200
	ds_read_b128 v[110:113], v21 offset:18432
	s_waitcnt lgkmcnt(0)
	v_mfma_f32_16x16x32_f16 v[66:69], v[62:65], v[110:113], v[66:69]
	ds_read_b128 v[118:121], v16 offset:53248
	v_mfma_f32_16x16x32_f16 v[44:47], v[74:77], v[90:93], v[44:47]
	ds_read_b128 v[122:125], v16 offset:55296
	v_mfma_f32_16x16x32_f16 v[78:81], v[74:77], v[110:113], v[78:81]
	s_waitcnt vmcnt(7)
	ds_write_b128 v17, v[58:61]
	s_waitcnt lgkmcnt(2)
	v_mfma_f32_16x16x32_f16 v[82:85], v[118:121], v[90:93], v[82:85]
	s_waitcnt vmcnt(6)
	ds_write_b128 v18, v[106:109]
	v_mfma_f32_16x16x32_f16 v[86:89], v[118:121], v[110:113], v[86:89]
	s_waitcnt vmcnt(5)
	ds_write_b128 v19, v[126:129]
	s_waitcnt lgkmcnt(3)
	v_mfma_f32_16x16x32_f16 v[28:31], v[122:125], v[90:93], v[28:31]
	ds_read_b128 v[90:93], v21 offset:20480
	v_mfma_f32_16x16x32_f16 v[32:35], v[122:125], v[110:113], v[32:35]
	ds_read_b128 v[110:113], v21 offset:22528
	s_waitcnt lgkmcnt(1)
	v_mfma_f32_16x16x32_f16 v[98:101], v[62:65], v[90:93], v[98:101]
	s_waitcnt vmcnt(4)
	ds_write_b128 v20, v[134:137]
	s_waitcnt lgkmcnt(1)
	v_mfma_f32_16x16x32_f16 v[52:55], v[62:65], v[110:113], v[52:55]
	ds_read_b128 v[62:65], v22 offset:49152
	v_mfma_f32_16x16x32_f16 v[102:105], v[74:77], v[90:93], v[102:105]
	s_waitcnt vmcnt(3)
	ds_write_b128 v17, v[94:97] offset:32768
	v_mfma_f32_16x16x32_f16 v[24:27], v[74:77], v[110:113], v[24:27]
	ds_read_b128 v[74:77], v22 offset:51200
	v_mfma_f32_16x16x32_f16 v[114:117], v[118:121], v[90:93], v[114:117]
	s_waitcnt vmcnt(2)
	ds_write_b128 v18, v[162:165] offset:32768
	v_mfma_f32_16x16x32_f16 v[40:43], v[118:121], v[110:113], v[40:43]
	ds_read_b128 v[118:121], v22 offset:53248
	v_mfma_f32_16x16x32_f16 v[70:73], v[122:125], v[90:93], v[70:73]
	ds_read_b128 v[90:93], v23 offset:16384
	v_mfma_f32_16x16x32_f16 v[48:51], v[122:125], v[110:113], v[48:51]
	ds_read_b128 v[110:113], v23 offset:18432
	s_waitcnt lgkmcnt(1)
	v_mfma_f32_16x16x32_f16 v[36:39], v[62:65], v[90:93], v[36:39]
	ds_read_b128 v[122:125], v22 offset:55296
	s_waitcnt lgkmcnt(1)
	v_mfma_f32_16x16x32_f16 v[66:69], v[62:65], v[110:113], v[66:69]
	s_waitcnt vmcnt(1)
	ds_write_b128 v19, v[166:169] offset:32768
	v_mfma_f32_16x16x32_f16 v[44:47], v[74:77], v[90:93], v[44:47]
	s_waitcnt vmcnt(0)
	ds_write_b128 v20, v[190:193] offset:32768
	v_mfma_f32_16x16x32_f16 v[78:81], v[74:77], v[110:113], v[78:81]
	v_mfma_f32_16x16x32_f16 v[82:85], v[118:121], v[90:93], v[82:85]
	v_mfma_f32_16x16x32_f16 v[86:89], v[118:121], v[110:113], v[86:89]
	s_waitcnt lgkmcnt(2)
	v_mfma_f32_16x16x32_f16 v[28:31], v[122:125], v[90:93], v[28:31]
	ds_read_b128 v[90:93], v23 offset:20480
	v_mfma_f32_16x16x32_f16 v[32:35], v[122:125], v[110:113], v[32:35]
	ds_read_b128 v[110:113], v23 offset:22528
	s_waitcnt lgkmcnt(1)
	v_mfma_f32_16x16x32_f16 v[98:101], v[62:65], v[90:93], v[98:101]
	s_waitcnt lgkmcnt(0)
	v_mfma_f32_16x16x32_f16 v[52:55], v[62:65], v[110:113], v[52:55]
	global_load_dwordx4 v[62:65], v[0:1], off offset:1408
	v_mfma_f32_16x16x32_f16 v[102:105], v[74:77], v[90:93], v[102:105]
	v_mfma_f32_16x16x32_f16 v[24:27], v[74:77], v[110:113], v[24:27]
	v_mfma_f32_16x16x32_f16 v[114:117], v[118:121], v[90:93], v[114:117]
	v_mfma_f32_16x16x32_f16 v[40:43], v[118:121], v[110:113], v[40:43]
	v_mfma_f32_16x16x32_f16 v[70:73], v[122:125], v[90:93], v[70:73]
	global_load_dwordx4 v[90:93], v[2:3], off offset:1408
	global_load_dwordx4 v[130:133], v[4:5], off offset:1408
	global_load_dwordx4 v[138:141], v[14:15], off offset:1408
	global_load_dwordx4 v[74:77], v[10:11], off offset:1408
	global_load_dwordx4 v[142:145], v[12:13], off offset:1408
	global_load_dwordx4 v[154:157], v[8:9], off offset:1408
	global_load_dwordx4 v[158:161], v[6:7], off offset:1408
	s_waitcnt lgkmcnt(0)
	s_barrier
; #define GL_LOAD(s_, kt_) if (VAR != 1) { a##s_##0 = GL_A(0, kt_); a##s_##1 = GL_A(1, kt_); a##s_##2 = GL_A(2, kt_); a##s_##3 = GL_A(3, kt_); b##s_##0 = GL_B(0, kt_); b##s_##1 = GL_B(1, kt_); b##s_##2 = GL_B(2, kt_); b##s_##3 = GL_B(3, kt_); }
; #define LDS_STORE(s_, buf_) if (VAR != 2) { LDS_ST1(sA, 0, buf_, a##s_##0) LDS_ST1(sA, 1, buf_, a##s_##1) LDS_ST1(sA, 2, buf_, a##s_##2) LDS_ST1(sA, 3, buf_, a##s_##3) LDS_ST1(sB, 0, buf_, b##s_##0) LDS_ST1(sB, 1, buf_, b##s_##1) LDS_ST1(sB, 2, buf_, b##s_##2) LDS_ST1(sB, 3, buf_, b##s_##3) }
;     ...
;   GL_LOAD(0, 0)
;   GL_LOAD(1, 1)
;   LDS_STORE(0, 0)
;   if (VAR != 4) __syncthreads();
; #pragma unroll
;   for (int kt = 0; kt < nk; kt += 2) {
;     if (kt + 2 < nk) { GL_LOAD(0, kt + 2) }
;     MMA_TILE(0)
;     LDS_STORE(1, 1)
;     if (VAR != 4) __syncthreads();
;     if (kt + 3 < nk) { GL_LOAD(1, kt + 3) }
;     MMA_TILE(1)
;     if (kt + 2 < nk) { LDS_STORE(0, 0) }
;     if (VAR != 4) __syncthreads();
	v_mfma_f32_16x16x32_f16 v[48:51], v[122:125], v[110:113], v[48:51]
	ds_read_b128 v[58:61], v16 offset:32768
	ds_read_b128 v[106:109], v21
	s_waitcnt lgkmcnt(0)
	v_mfma_f32_16x16x32_f16 v[36:39], v[58:61], v[106:109], v[36:39]
	ds_read_b128 v[94:97], v16 offset:34816
	ds_read_b128 v[110:113], v21 offset:2048
	s_waitcnt lgkmcnt(0)
	v_mfma_f32_16x16x32_f16 v[66:69], v[58:61], v[110:113], v[66:69]
	ds_read_b128 v[118:121], v16 offset:36864
	v_mfma_f32_16x16x32_f16 v[44:47], v[94:97], v[106:109], v[44:47]
	ds_read_b128 v[122:125], v16 offset:38912
	v_mfma_f32_16x16x32_f16 v[78:81], v[94:97], v[110:113], v[78:81]
	s_waitcnt vmcnt(7)
	ds_write_b128 v17, v[62:65] offset:16384
	s_waitcnt lgkmcnt(2)
	v_mfma_f32_16x16x32_f16 v[82:85], v[118:121], v[106:109], v[82:85]
	s_waitcnt vmcnt(6)
	ds_write_b128 v18, v[90:93] offset:16384
	v_mfma_f32_16x16x32_f16 v[86:89], v[118:121], v[110:113], v[86:89]
	s_waitcnt vmcnt(5)
	ds_write_b128 v19, v[130:133] offset:16384
	s_waitcnt lgkmcnt(3)
	v_mfma_f32_16x16x32_f16 v[28:31], v[122:125], v[106:109], v[28:31]
	ds_read_b128 v[106:109], v21 offset:4096
	v_mfma_f32_16x16x32_f16 v[32:35], v[122:125], v[110:113], v[32:35]
	ds_read_b128 v[110:113], v21 offset:6144
	s_waitcnt lgkmcnt(1)
	v_mfma_f32_16x16x32_f16 v[98:101], v[58:61], v[106:109], v[98:101]
	s_waitcnt vmcnt(4)
	ds_write_b128 v20, v[138:141] offset:16384
	s_waitcnt lgkmcnt(1)
	v_mfma_f32_16x16x32_f16 v[52:55], v[58:61], v[110:113], v[52:55]
	ds_read_b128 v[58:61], v22 offset:32768
	v_mfma_f32_16x16x32_f16 v[102:105], v[94:97], v[106:109], v[102:105]
	s_waitcnt vmcnt(3)
	ds_write_b128 v17, v[74:77] offset:49152
	v_mfma_f32_16x16x32_f16 v[24:27], v[94:97], v[110:113], v[24:27]
	ds_read_b128 v[94:97], v22 offset:34816
	v_mfma_f32_16x16x32_f16 v[114:117], v[118:121], v[106:109], v[114:117]
	s_waitcnt vmcnt(2)
	ds_write_b128 v18, v[142:145] offset:49152
	v_mfma_f32_16x16x32_f16 v[40:43], v[118:121], v[110:113], v[40:43]
	ds_read_b128 v[118:121], v22 offset:36864
	v_mfma_f32_16x16x32_f16 v[70:73], v[122:125], v[106:109], v[70:73]
	ds_read_b128 v[106:109], v23
	v_mfma_f32_16x16x32_f16 v[48:51], v[122:125], v[110:113], v[48:51]
	ds_read_b128 v[110:113], v23 offset:2048
	s_waitcnt lgkmcnt(1)
	v_mfma_f32_16x16x32_f16 v[36:39], v[58:61], v[106:109], v[36:39]
	ds_read_b128 v[122:125], v22 offset:38912
	s_waitcnt lgkmcnt(1)
	v_mfma_f32_16x16x32_f16 v[66:69], v[58:61], v[110:113], v[66:69]
	s_waitcnt vmcnt(1)
	ds_write_b128 v19, v[154:157] offset:49152
	v_mfma_f32_16x16x32_f16 v[44:47], v[94:97], v[106:109], v[44:47]
	s_waitcnt vmcnt(0)
	ds_write_b128 v20, v[158:161] offset:49152
	v_mfma_f32_16x16x32_f16 v[78:81], v[94:97], v[110:113], v[78:81]
	v_mfma_f32_16x16x32_f16 v[82:85], v[118:121], v[106:109], v[82:85]
	v_mfma_f32_16x16x32_f16 v[86:89], v[118:121], v[110:113], v[86:89]
	s_waitcnt lgkmcnt(2)
	v_mfma_f32_16x16x32_f16 v[28:31], v[122:125], v[106:109], v[28:31]
	ds_read_b128 v[106:109], v23 offset:4096
	v_mfma_f32_16x16x32_f16 v[32:35], v[122:125], v[110:113], v[32:35]
	ds_read_b128 v[110:113], v23 offset:6144
	s_waitcnt lgkmcnt(1)
	v_mfma_f32_16x16x32_f16 v[98:101], v[58:61], v[106:109], v[98:101]
	s_waitcnt lgkmcnt(0)
	v_mfma_f32_16x16x32_f16 v[52:55], v[58:61], v[110:113], v[52:55]
	global_load_dwordx4 v[58:61], v[0:1], off offset:1536
	v_mfma_f32_16x16x32_f16 v[102:105], v[94:97], v[106:109], v[102:105]
	v_mfma_f32_16x16x32_f16 v[24:27], v[94:97], v[110:113], v[24:27]
	v_mfma_f32_16x16x32_f16 v[114:117], v[118:121], v[106:109], v[114:117]
	v_mfma_f32_16x16x32_f16 v[40:43], v[118:121], v[110:113], v[40:43]
	v_mfma_f32_16x16x32_f16 v[70:73], v[122:125], v[106:109], v[70:73]
	global_load_dwordx4 v[106:109], v[2:3], off offset:1536
	global_load_dwordx4 v[126:129], v[4:5], off offset:1536
	global_load_dwordx4 v[134:137], v[14:15], off offset:1536
	global_load_dwordx4 v[94:97], v[10:11], off offset:1536
	global_load_dwordx4 v[162:165], v[12:13], off offset:1536
	global_load_dwordx4 v[166:169], v[8:9], off offset:1536
	global_load_dwordx4 v[190:193], v[6:7], off offset:1536
	s_waitcnt lgkmcnt(0)
	s_barrier
	v_mfma_f32_16x16x32_f16 v[48:51], v[122:125], v[110:113], v[48:51]
	ds_read_b128 v[62:65], v16 offset:49152
	ds_read_b128 v[90:93], v21 offset:16384
	s_waitcnt lgkmcnt(0)
	v_mfma_f32_16x16x32_f16 v[36:39], v[62:65], v[90:93], v[36:39]
	ds_read_b128 v[74:77], v16 offset:51200
	ds_read_b128 v[110:113], v21 offset:18432
	s_waitcnt lgkmcnt(0)
	v_mfma_f32_16x16x32_f16 v[66:69], v[62:65], v[110:113], v[66:69]
	ds_read_b128 v[118:121], v16 offset:53248
	v_mfma_f32_16x16x32_f16 v[44:47], v[74:77], v[90:93], v[44:47]
	ds_read_b128 v[122:125], v16 offset:55296
	v_mfma_f32_16x16x32_f16 v[78:81], v[74:77], v[110:113], v[78:81]
	s_waitcnt vmcnt(7)
	ds_write_b128 v17, v[58:61]
	s_waitcnt lgkmcnt(2)
	v_mfma_f32_16x16x32_f16 v[82:85], v[118:121], v[90:93], v[82:85]
	s_waitcnt vmcnt(6)
	ds_write_b128 v18, v[106:109]
	v_mfma_f32_16x16x32_f16 v[86:89], v[118:121], v[110:113], v[86:89]
	s_waitcnt vmcnt(5)
	ds_write_b128 v19, v[126:129]
	s_waitcnt lgkmcnt(3)
	v_mfma_f32_16x16x32_f16 v[28:31], v[122:125], v[90:93], v[28:31]
	ds_read_b128 v[90:93], v21 offset:20480
	v_mfma_f32_16x16x32_f16 v[32:35], v[122:125], v[110:113], v[32:35]
	ds_read_b128 v[110:113], v21 offset:22528
	s_waitcnt lgkmcnt(1)
	v_mfma_f32_16x16x32_f16 v[98:101], v[62:65], v[90:93], v[98:101]
	s_waitcnt vmcnt(4)
	ds_write_b128 v20, v[134:137]
	s_waitcnt lgkmcnt(1)
	v_mfma_f32_16x16x32_f16 v[52:55], v[62:65], v[110:113], v[52:55]
	ds_read_b128 v[62:65], v22 offset:49152
	v_mfma_f32_16x16x32_f16 v[102:105], v[74:77], v[90:93], v[102:105]
	s_waitcnt vmcnt(3)
; #define GL_LOAD(s_, kt_) if (VAR != 1) { a##s_##0 = GL_A(0, kt_); a##s_##1 = GL_A(1, kt_); a##s_##2 = GL_A(2, kt_); a##s_##3 = GL_A(3, kt_); b##s_##0 = GL_B(0, kt_); b##s_##1 = GL_B(1, kt_); b##s_##2 = GL_B(2, kt_); b##s_##3 = GL_B(3, kt_); }
; #define LDS_STORE(s_, buf_) if (VAR != 2) { LDS_ST1(sA, 0, buf_, a##s_##0) LDS_ST1(sA, 1, buf_, a##s_##1) LDS_ST1(sA, 2, buf_, a##s_##2) LDS_ST1(sA, 3, buf_, a##s_##3) LDS_ST1(sB, 0, buf_, b##s_##0) LDS_ST1(sB, 1, buf_, b##s_##1) LDS_ST1(sB, 2, buf_, b##s_##2) LDS_ST1(sB, 3, buf_, b##s_##3) }
;     ...
;   GL_LOAD(0, 0)
;   GL_LOAD(1, 1)
;   LDS_STORE(0, 0)
;   if (VAR != 4) __syncthreads();
; #pragma unroll
;   for (int kt = 0; kt < nk; kt += 2) {
;     if (kt + 2 < nk) { GL_LOAD(0, kt + 2) }
;     MMA_TILE(0)
;     LDS_STORE(1, 1)
;     if (VAR != 4) __syncthreads();
;     if (kt + 3 < nk) { GL_LOAD(1, kt + 3) }
;     MMA_TILE(1)
;     if (kt + 2 < nk) { LDS_STORE(0, 0) }
;     if (VAR != 4) __syncthreads();
	ds_write_b128 v17, v[94:97] offset:32768
	v_mfma_f32_16x16x32_f16 v[24:27], v[74:77], v[110:113], v[24:27]
	ds_read_b128 v[74:77], v22 offset:51200
	v_mfma_f32_16x16x32_f16 v[114:117], v[118:121], v[90:93], v[114:117]
	s_waitcnt vmcnt(2)
	ds_write_b128 v18, v[162:165] offset:32768
	v_mfma_f32_16x16x32_f16 v[40:43], v[118:121], v[110:113], v[40:43]
	ds_read_b128 v[118:121], v22 offset:53248
	v_mfma_f32_16x16x32_f16 v[70:73], v[122:125], v[90:93], v[70:73]
	ds_read_b128 v[90:93], v23 offset:16384
	v_mfma_f32_16x16x32_f16 v[48:51], v[122:125], v[110:113], v[48:51]
	ds_read_b128 v[110:113], v23 offset:18432
	s_waitcnt lgkmcnt(1)
	v_mfma_f32_16x16x32_f16 v[36:39], v[62:65], v[90:93], v[36:39]
	ds_read_b128 v[122:125], v22 offset:55296
	s_waitcnt lgkmcnt(1)
	v_mfma_f32_16x16x32_f16 v[66:69], v[62:65], v[110:113], v[66:69]
	s_waitcnt vmcnt(1)
	ds_write_b128 v19, v[166:169] offset:32768
	v_mfma_f32_16x16x32_f16 v[44:47], v[74:77], v[90:93], v[44:47]
	s_waitcnt vmcnt(0)
	ds_write_b128 v20, v[190:193] offset:32768
	v_mfma_f32_16x16x32_f16 v[78:81], v[74:77], v[110:113], v[78:81]
	v_mfma_f32_16x16x32_f16 v[82:85], v[118:121], v[90:93], v[82:85]
	v_mfma_f32_16x16x32_f16 v[86:89], v[118:121], v[110:113], v[86:89]
	s_waitcnt lgkmcnt(2)
	v_mfma_f32_16x16x32_f16 v[28:31], v[122:125], v[90:93], v[28:31]
	ds_read_b128 v[90:93], v23 offset:20480
	v_mfma_f32_16x16x32_f16 v[32:35], v[122:125], v[110:113], v[32:35]
	ds_read_b128 v[110:113], v23 offset:22528
	s_waitcnt lgkmcnt(1)
	v_mfma_f32_16x16x32_f16 v[98:101], v[62:65], v[90:93], v[98:101]
	s_waitcnt lgkmcnt(0)
	v_mfma_f32_16x16x32_f16 v[52:55], v[62:65], v[110:113], v[52:55]
	global_load_dwordx4 v[62:65], v[0:1], off offset:1664
	v_mfma_f32_16x16x32_f16 v[102:105], v[74:77], v[90:93], v[102:105]
	v_mfma_f32_16x16x32_f16 v[24:27], v[74:77], v[110:113], v[24:27]
	v_mfma_f32_16x16x32_f16 v[114:117], v[118:121], v[90:93], v[114:117]
	v_mfma_f32_16x16x32_f16 v[40:43], v[118:121], v[110:113], v[40:43]
	v_mfma_f32_16x16x32_f16 v[70:73], v[122:125], v[90:93], v[70:73]
	global_load_dwordx4 v[90:93], v[2:3], off offset:1664
	global_load_dwordx4 v[130:133], v[4:5], off offset:1664
	global_load_dwordx4 v[138:141], v[14:15], off offset:1664
	global_load_dwordx4 v[74:77], v[10:11], off offset:1664
	global_load_dwordx4 v[142:145], v[12:13], off offset:1664
	global_load_dwordx4 v[154:157], v[8:9], off offset:1664
	global_load_dwordx4 v[158:161], v[6:7], off offset:1664
	s_waitcnt lgkmcnt(0)
	s_barrier
	v_mfma_f32_16x16x32_f16 v[48:51], v[122:125], v[110:113], v[48:51]
	ds_read_b128 v[58:61], v16 offset:32768
	ds_read_b128 v[106:109], v21
	s_waitcnt lgkmcnt(0)
	v_mfma_f32_16x16x32_f16 v[36:39], v[58:61], v[106:109], v[36:39]
	ds_read_b128 v[94:97], v16 offset:34816
	ds_read_b128 v[110:113], v21 offset:2048
	s_waitcnt lgkmcnt(0)
	v_mfma_f32_16x16x32_f16 v[66:69], v[58:61], v[110:113], v[66:69]
	ds_read_b128 v[118:121], v16 offset:36864
	v_mfma_f32_16x16x32_f16 v[44:47], v[94:97], v[106:109], v[44:47]
	ds_read_b128 v[122:125], v16 offset:38912
	v_mfma_f32_16x16x32_f16 v[78:81], v[94:97], v[110:113], v[78:81]
	s_waitcnt vmcnt(7)
	ds_write_b128 v17, v[62:65] offset:16384
	s_waitcnt lgkmcnt(2)
	v_mfma_f32_16x16x32_f16 v[82:85], v[118:121], v[106:109], v[82:85]
	s_waitcnt vmcnt(6)
	ds_write_b128 v18, v[90:93] offset:16384
	v_mfma_f32_16x16x32_f16 v[86:89], v[118:121], v[110:113], v[86:89]
	s_waitcnt vmcnt(5)
	ds_write_b128 v19, v[130:133] offset:16384
	s_waitcnt lgkmcnt(3)
	v_mfma_f32_16x16x32_f16 v[28:31], v[122:125], v[106:109], v[28:31]
	ds_read_b128 v[106:109], v21 offset:4096
	v_mfma_f32_16x16x32_f16 v[32:35], v[122:125], v[110:113], v[32:35]
	ds_read_b128 v[110:113], v21 offset:6144
	s_waitcnt lgkmcnt(1)
	v_mfma_f32_16x16x32_f16 v[98:101], v[58:61], v[106:109], v[98:101]
	s_waitcnt vmcnt(4)
	ds_write_b128 v20, v[138:141] offset:16384
	s_waitcnt lgkmcnt(1)
	v_mfma_f32_16x16x32_f16 v[52:55], v[58:61], v[110:113], v[52:55]
	ds_read_b128 v[58:61], v22 offset:32768
	v_mfma_f32_16x16x32_f16 v[102:105], v[94:97], v[106:109], v[102:105]
	s_waitcnt vmcnt(3)
	ds_write_b128 v17, v[74:77] offset:49152
	v_mfma_f32_16x16x32_f16 v[24:27], v[94:97], v[110:113], v[24:27]
	ds_read_b128 v[94:97], v22 offset:34816
	v_mfma_f32_16x16x32_f16 v[114:117], v[118:121], v[106:109], v[114:117]
	s_waitcnt vmcnt(2)
	ds_write_b128 v18, v[142:145] offset:49152
	v_mfma_f32_16x16x32_f16 v[40:43], v[118:121], v[110:113], v[40:43]
	ds_read_b128 v[118:121], v22 offset:36864
	v_mfma_f32_16x16x32_f16 v[70:73], v[122:125], v[106:109], v[70:73]
	ds_read_b128 v[106:109], v23
	v_mfma_f32_16x16x32_f16 v[48:51], v[122:125], v[110:113], v[48:51]
	ds_read_b128 v[110:113], v23 offset:2048
	s_waitcnt lgkmcnt(1)
	v_mfma_f32_16x16x32_f16 v[36:39], v[58:61], v[106:109], v[36:39]
	ds_read_b128 v[122:125], v22 offset:38912
	s_waitcnt lgkmcnt(1)
	v_mfma_f32_16x16x32_f16 v[66:69], v[58:61], v[110:113], v[66:69]
	s_waitcnt vmcnt(1)
	ds_write_b128 v19, v[154:157] offset:49152
	v_mfma_f32_16x16x32_f16 v[44:47], v[94:97], v[106:109], v[44:47]
	s_waitcnt vmcnt(0)
	ds_write_b128 v20, v[158:161] offset:49152
	v_mfma_f32_16x16x32_f16 v[78:81], v[94:97], v[110:113], v[78:81]
	v_mfma_f32_16x16x32_f16 v[82:85], v[118:121], v[106:109], v[82:85]
	v_mfma_f32_16x16x32_f16 v[86:89], v[118:121], v[110:113], v[86:89]
	s_waitcnt lgkmcnt(2)
	v_mfma_f32_16x16x32_f16 v[28:31], v[122:125], v[106:109], v[28:31]
	ds_read_b128 v[106:109], v23 offset:4096
	v_mfma_f32_16x16x32_f16 v[32:35], v[122:125], v[110:113], v[32:35]
	ds_read_b128 v[110:113], v23 offset:6144
	s_waitcnt lgkmcnt(1)
	v_mfma_f32_16x16x32_f16 v[98:101], v[58:61], v[106:109], v[98:101]
	s_waitcnt lgkmcnt(0)
	v_mfma_f32_16x16x32_f16 v[52:55], v[58:61], v[110:113], v[52:55]
	global_load_dwordx4 v[58:61], v[0:1], off offset:1792
	v_mfma_f32_16x16x32_f16 v[102:105], v[94:97], v[106:109], v[102:105]
	v_mfma_f32_16x16x32_f16 v[24:27], v[94:97], v[110:113], v[24:27]
	v_mfma_f32_16x16x32_f16 v[114:117], v[118:121], v[106:109], v[114:117]
	v_mfma_f32_16x16x32_f16 v[40:43], v[118:121], v[110:113], v[40:43]
	v_mfma_f32_16x16x32_f16 v[70:73], v[122:125], v[106:109], v[70:73]
	global_load_dwordx4 v[106:109], v[2:3], off offset:1792
	global_load_dwordx4 v[126:129], v[4:5], off offset:1792
	global_load_dwordx4 v[134:137], v[14:15], off offset:1792
	global_load_dwordx4 v[94:97], v[10:11], off offset:1792
	global_load_dwordx4 v[162:165], v[12:13], off offset:1792
	global_load_dwordx4 v[166:169], v[8:9], off offset:1792
	global_load_dwordx4 v[190:193], v[6:7], off offset:1792
	s_waitcnt lgkmcnt(0)
	s_barrier
; #define GL_LOAD(s_, kt_) if (VAR != 1) { a##s_##0 = GL_A(0, kt_); a##s_##1 = GL_A(1, kt_); a##s_##2 = GL_A(2, kt_); a##s_##3 = GL_A(3, kt_); b##s_##0 = GL_B(0, kt_); b##s_##1 = GL_B(1, kt_); b##s_##2 = GL_B(2, kt_); b##s_##3 = GL_B(3, kt_); }
; #define LDS_STORE(s_, buf_) if (VAR != 2) { LDS_ST1(sA, 0, buf_, a##s_##0) LDS_ST1(sA, 1, buf_, a##s_##1) LDS_ST1(sA, 2, buf_, a##s_##2) LDS_ST1(sA, 3, buf_, a##s_##3) LDS_ST1(sB, 0, buf_, b##s_##0) LDS_ST1(sB, 1, buf_, b##s_##1) LDS_ST1(sB, 2, buf_, b##s_##2) LDS_ST1(sB, 3, buf_, b##s_##3) }
;     ...
;   GL_LOAD(0, 0)
;   GL_LOAD(1, 1)
;   LDS_STORE(0, 0)
;   if (VAR != 4) __syncthreads();
; #pragma unroll
;   for (int kt = 0; kt < nk; kt += 2) {
;     if (kt + 2 < nk) { GL_LOAD(0, kt + 2) }
;     MMA_TILE(0)
;     LDS_STORE(1, 1)
;     if (VAR != 4) __syncthreads();
;     if (kt + 3 < nk) { GL_LOAD(1, kt + 3) }
;     MMA_TILE(1)
;     if (kt + 2 < nk) { LDS_STORE(0, 0) }
;     if (VAR != 4) __syncthreads();
	v_mfma_f32_16x16x32_f16 v[48:51], v[122:125], v[110:113], v[48:51]
	ds_read_b128 v[62:65], v16 offset:49152
	ds_read_b128 v[90:93], v21 offset:16384
	s_waitcnt lgkmcnt(0)
	v_mfma_f32_16x16x32_f16 v[36:39], v[62:65], v[90:93], v[36:39]
	ds_read_b128 v[74:77], v16 offset:51200
	ds_read_b128 v[110:113], v21 offset:18432
	s_waitcnt lgkmcnt(0)
	v_mfma_f32_16x16x32_f16 v[66:69], v[62:65], v[110:113], v[66:69]
	ds_read_b128 v[118:121], v16 offset:53248
	v_mfma_f32_16x16x32_f16 v[44:47], v[74:77], v[90:93], v[44:47]
	ds_read_b128 v[122:125], v16 offset:55296
	v_mfma_f32_16x16x32_f16 v[78:81], v[74:77], v[110:113], v[78:81]
	s_waitcnt vmcnt(7)
	ds_write_b128 v17, v[58:61]
	s_waitcnt lgkmcnt(2)
	v_mfma_f32_16x16x32_f16 v[82:85], v[118:121], v[90:93], v[82:85]
	s_waitcnt vmcnt(6)
	ds_write_b128 v18, v[106:109]
	v_mfma_f32_16x16x32_f16 v[86:89], v[118:121], v[110:113], v[86:89]
	s_waitcnt vmcnt(5)
	ds_write_b128 v19, v[126:129]
	s_waitcnt lgkmcnt(3)
	v_mfma_f32_16x16x32_f16 v[28:31], v[122:125], v[90:93], v[28:31]
	ds_read_b128 v[90:93], v21 offset:20480
	v_mfma_f32_16x16x32_f16 v[32:35], v[122:125], v[110:113], v[32:35]
	ds_read_b128 v[110:113], v21 offset:22528
	s_waitcnt lgkmcnt(1)
	v_mfma_f32_16x16x32_f16 v[98:101], v[62:65], v[90:93], v[98:101]
	s_waitcnt vmcnt(4)
	ds_write_b128 v20, v[134:137]
	s_waitcnt lgkmcnt(1)
	v_mfma_f32_16x16x32_f16 v[52:55], v[62:65], v[110:113], v[52:55]
	ds_read_b128 v[62:65], v22 offset:49152
	v_mfma_f32_16x16x32_f16 v[102:105], v[74:77], v[90:93], v[102:105]
	s_waitcnt vmcnt(3)
	ds_write_b128 v17, v[94:97] offset:32768
	v_mfma_f32_16x16x32_f16 v[24:27], v[74:77], v[110:113], v[24:27]
	ds_read_b128 v[74:77], v22 offset:51200
	v_mfma_f32_16x16x32_f16 v[114:117], v[118:121], v[90:93], v[114:117]
	s_waitcnt vmcnt(2)
	ds_write_b128 v18, v[162:165] offset:32768
	v_mfma_f32_16x16x32_f16 v[40:43], v[118:121], v[110:113], v[40:43]
	ds_read_b128 v[118:121], v22 offset:53248
	v_mfma_f32_16x16x32_f16 v[70:73], v[122:125], v[90:93], v[70:73]
	ds_read_b128 v[90:93], v23 offset:16384
	v_mfma_f32_16x16x32_f16 v[48:51], v[122:125], v[110:113], v[48:51]
	ds_read_b128 v[110:113], v23 offset:18432
	s_waitcnt lgkmcnt(1)
	v_mfma_f32_16x16x32_f16 v[36:39], v[62:65], v[90:93], v[36:39]
	ds_read_b128 v[122:125], v22 offset:55296
	s_waitcnt lgkmcnt(1)
	v_mfma_f32_16x16x32_f16 v[66:69], v[62:65], v[110:113], v[66:69]
	s_waitcnt vmcnt(1)
	ds_write_b128 v19, v[166:169] offset:32768
	v_mfma_f32_16x16x32_f16 v[44:47], v[74:77], v[90:93], v[44:47]
	s_waitcnt vmcnt(0)
	ds_write_b128 v20, v[190:193] offset:32768
	v_mfma_f32_16x16x32_f16 v[78:81], v[74:77], v[110:113], v[78:81]
	v_mfma_f32_16x16x32_f16 v[82:85], v[118:121], v[90:93], v[82:85]
	v_mfma_f32_16x16x32_f16 v[86:89], v[118:121], v[110:113], v[86:89]
	s_waitcnt lgkmcnt(2)
	v_mfma_f32_16x16x32_f16 v[28:31], v[122:125], v[90:93], v[28:31]
	ds_read_b128 v[90:93], v23 offset:20480
	v_mfma_f32_16x16x32_f16 v[32:35], v[122:125], v[110:113], v[32:35]
	ds_read_b128 v[110:113], v23 offset:22528
	s_waitcnt lgkmcnt(1)
	v_mfma_f32_16x16x32_f16 v[98:101], v[62:65], v[90:93], v[98:101]
	s_waitcnt lgkmcnt(0)
	v_mfma_f32_16x16x32_f16 v[52:55], v[62:65], v[110:113], v[52:55]
	global_load_dwordx4 v[62:65], v[0:1], off offset:1920
	v_mfma_f32_16x16x32_f16 v[102:105], v[74:77], v[90:93], v[102:105]
	v_mfma_f32_16x16x32_f16 v[24:27], v[74:77], v[110:113], v[24:27]
	v_mfma_f32_16x16x32_f16 v[114:117], v[118:121], v[90:93], v[114:117]
	v_mfma_f32_16x16x32_f16 v[40:43], v[118:121], v[110:113], v[40:43]
	v_mfma_f32_16x16x32_f16 v[70:73], v[122:125], v[90:93], v[70:73]
	global_load_dwordx4 v[90:93], v[2:3], off offset:1920
	global_load_dwordx4 v[130:133], v[4:5], off offset:1920
	global_load_dwordx4 v[138:141], v[14:15], off offset:1920
	global_load_dwordx4 v[74:77], v[10:11], off offset:1920
	global_load_dwordx4 v[142:145], v[12:13], off offset:1920
	global_load_dwordx4 v[154:157], v[8:9], off offset:1920
	global_load_dwordx4 v[158:161], v[6:7], off offset:1920
	s_waitcnt lgkmcnt(0)
	s_barrier
	v_mfma_f32_16x16x32_f16 v[48:51], v[122:125], v[110:113], v[48:51]
	ds_read_b128 v[58:61], v16 offset:32768
	ds_read_b128 v[106:109], v21
	s_waitcnt lgkmcnt(0)
	v_mfma_f32_16x16x32_f16 v[36:39], v[58:61], v[106:109], v[36:39]
	ds_read_b128 v[94:97], v16 offset:34816
	ds_read_b128 v[110:113], v21 offset:2048
	s_waitcnt lgkmcnt(0)
	v_mfma_f32_16x16x32_f16 v[66:69], v[58:61], v[110:113], v[66:69]
	ds_read_b128 v[118:121], v16 offset:36864
	v_mfma_f32_16x16x32_f16 v[44:47], v[94:97], v[106:109], v[44:47]
	ds_read_b128 v[122:125], v16 offset:38912
	v_mfma_f32_16x16x32_f16 v[78:81], v[94:97], v[110:113], v[78:81]
	s_waitcnt vmcnt(7)
	ds_write_b128 v17, v[62:65] offset:16384
	s_waitcnt lgkmcnt(2)
	v_mfma_f32_16x16x32_f16 v[82:85], v[118:121], v[106:109], v[82:85]
	s_waitcnt vmcnt(6)
	ds_write_b128 v18, v[90:93] offset:16384
	v_mfma_f32_16x16x32_f16 v[86:89], v[118:121], v[110:113], v[86:89]
	s_waitcnt vmcnt(5)
	ds_write_b128 v19, v[130:133] offset:16384
	s_waitcnt lgkmcnt(3)
	v_mfma_f32_16x16x32_f16 v[28:31], v[122:125], v[106:109], v[28:31]
	ds_read_b128 v[106:109], v21 offset:4096
	v_mfma_f32_16x16x32_f16 v[32:35], v[122:125], v[110:113], v[32:35]
	ds_read_b128 v[110:113], v21 offset:6144
	s_waitcnt lgkmcnt(1)
	v_mfma_f32_16x16x32_f16 v[98:101], v[58:61], v[106:109], v[98:101]
	s_waitcnt vmcnt(4)
	ds_write_b128 v20, v[138:141] offset:16384
	s_waitcnt lgkmcnt(1)
	v_mfma_f32_16x16x32_f16 v[52:55], v[58:61], v[110:113], v[52:55]
	ds_read_b128 v[58:61], v22 offset:32768
	v_mfma_f32_16x16x32_f16 v[102:105], v[94:97], v[106:109], v[102:105]
	s_waitcnt vmcnt(3)
; #define GL_LOAD(s_, kt_) if (VAR != 1) { a##s_##0 = GL_A(0, kt_); a##s_##1 = GL_A(1, kt_); a##s_##2 = GL_A(2, kt_); a##s_##3 = GL_A(3, kt_); b##s_##0 = GL_B(0, kt_); b##s_##1 = GL_B(1, kt_); b##s_##2 = GL_B(2, kt_); b##s_##3 = GL_B(3, kt_); }
; #define LDS_STORE(s_, buf_) if (VAR != 2) { LDS_ST1(sA, 0, buf_, a##s_##0) LDS_ST1(sA, 1, buf_, a##s_##1) LDS_ST1(sA, 2, buf_, a##s_##2) LDS_ST1(sA, 3, buf_, a##s_##3) LDS_ST1(sB, 0, buf_, b##s_##0) LDS_ST1(sB, 1, buf_, b##s_##1) LDS_ST1(sB, 2, buf_, b##s_##2) LDS_ST1(sB, 3, buf_, b##s_##3) }
;     ...
;   GL_LOAD(0, 0)
;   GL_LOAD(1, 1)
;   LDS_STORE(0, 0)
;   if (VAR != 4) __syncthreads();
; #pragma unroll
;   for (int kt = 0; kt < nk; kt += 2) {
;     if (kt + 2 < nk) { GL_LOAD(0, kt + 2) }
;     MMA_TILE(0)
;     LDS_STORE(1, 1)
;     if (VAR != 4) __syncthreads();
;     if (kt + 3 < nk) { GL_LOAD(1, kt + 3) }
;     MMA_TILE(1)
;     if (kt + 2 < nk) { LDS_STORE(0, 0) }
;     if (VAR != 4) __syncthreads();
	ds_write_b128 v17, v[74:77] offset:49152
	v_mfma_f32_16x16x32_f16 v[24:27], v[94:97], v[110:113], v[24:27]
	ds_read_b128 v[94:97], v22 offset:34816
	v_mfma_f32_16x16x32_f16 v[114:117], v[118:121], v[106:109], v[114:117]
	s_waitcnt vmcnt(2)
	ds_write_b128 v18, v[142:145] offset:49152
	v_mfma_f32_16x16x32_f16 v[40:43], v[118:121], v[110:113], v[40:43]
	ds_read_b128 v[118:121], v22 offset:36864
	v_mfma_f32_16x16x32_f16 v[70:73], v[122:125], v[106:109], v[70:73]
	ds_read_b128 v[106:109], v23
	v_mfma_f32_16x16x32_f16 v[48:51], v[122:125], v[110:113], v[48:51]
	ds_read_b128 v[110:113], v23 offset:2048
	s_waitcnt lgkmcnt(1)
	v_mfma_f32_16x16x32_f16 v[36:39], v[58:61], v[106:109], v[36:39]
	ds_read_b128 v[122:125], v22 offset:38912
	s_waitcnt lgkmcnt(1)
	v_mfma_f32_16x16x32_f16 v[66:69], v[58:61], v[110:113], v[66:69]
	s_waitcnt vmcnt(1)
	ds_write_b128 v19, v[154:157] offset:49152
	v_mfma_f32_16x16x32_f16 v[44:47], v[94:97], v[106:109], v[44:47]
	s_waitcnt vmcnt(0)
	ds_write_b128 v20, v[158:161] offset:49152
	v_mfma_f32_16x16x32_f16 v[78:81], v[94:97], v[110:113], v[78:81]
	v_mfma_f32_16x16x32_f16 v[82:85], v[118:121], v[106:109], v[82:85]
	v_mfma_f32_16x16x32_f16 v[86:89], v[118:121], v[110:113], v[86:89]
	s_waitcnt lgkmcnt(2)
	v_mfma_f32_16x16x32_f16 v[28:31], v[122:125], v[106:109], v[28:31]
	ds_read_b128 v[106:109], v23 offset:4096
	v_mfma_f32_16x16x32_f16 v[32:35], v[122:125], v[110:113], v[32:35]
	ds_read_b128 v[110:113], v23 offset:6144
	s_waitcnt lgkmcnt(1)
	v_mfma_f32_16x16x32_f16 v[98:101], v[58:61], v[106:109], v[98:101]
	s_waitcnt lgkmcnt(0)
	v_mfma_f32_16x16x32_f16 v[52:55], v[58:61], v[110:113], v[52:55]
	global_load_dwordx4 v[58:61], v[0:1], off offset:2048
	v_mfma_f32_16x16x32_f16 v[102:105], v[94:97], v[106:109], v[102:105]
	v_mfma_f32_16x16x32_f16 v[24:27], v[94:97], v[110:113], v[24:27]
	v_mfma_f32_16x16x32_f16 v[114:117], v[118:121], v[106:109], v[114:117]
	v_mfma_f32_16x16x32_f16 v[40:43], v[118:121], v[110:113], v[40:43]
	v_mfma_f32_16x16x32_f16 v[70:73], v[122:125], v[106:109], v[70:73]
	global_load_dwordx4 v[106:109], v[2:3], off offset:2048
	global_load_dwordx4 v[126:129], v[4:5], off offset:2048
	global_load_dwordx4 v[134:137], v[14:15], off offset:2048
	global_load_dwordx4 v[94:97], v[10:11], off offset:2048
	global_load_dwordx4 v[162:165], v[12:13], off offset:2048
	global_load_dwordx4 v[166:169], v[8:9], off offset:2048
	global_load_dwordx4 v[190:193], v[6:7], off offset:2048
	s_waitcnt lgkmcnt(0)
	s_barrier
	v_mfma_f32_16x16x32_f16 v[48:51], v[122:125], v[110:113], v[48:51]
	ds_read_b128 v[62:65], v16 offset:49152
	ds_read_b128 v[90:93], v21 offset:16384
	s_waitcnt lgkmcnt(0)
	v_mfma_f32_16x16x32_f16 v[36:39], v[62:65], v[90:93], v[36:39]
	ds_read_b128 v[74:77], v16 offset:51200
	ds_read_b128 v[110:113], v21 offset:18432
	s_waitcnt lgkmcnt(0)
	v_mfma_f32_16x16x32_f16 v[66:69], v[62:65], v[110:113], v[66:69]
	ds_read_b128 v[118:121], v16 offset:53248
	v_mfma_f32_16x16x32_f16 v[44:47], v[74:77], v[90:93], v[44:47]
	ds_read_b128 v[122:125], v16 offset:55296
	v_mfma_f32_16x16x32_f16 v[78:81], v[74:77], v[110:113], v[78:81]
	s_waitcnt vmcnt(7)
	ds_write_b128 v17, v[58:61]
	s_waitcnt lgkmcnt(2)
	v_mfma_f32_16x16x32_f16 v[82:85], v[118:121], v[90:93], v[82:85]
	s_waitcnt vmcnt(6)
	ds_write_b128 v18, v[106:109]
	v_mfma_f32_16x16x32_f16 v[86:89], v[118:121], v[110:113], v[86:89]
	s_waitcnt vmcnt(5)
	ds_write_b128 v19, v[126:129]
	s_waitcnt lgkmcnt(3)
	v_mfma_f32_16x16x32_f16 v[28:31], v[122:125], v[90:93], v[28:31]
	ds_read_b128 v[90:93], v21 offset:20480
	v_mfma_f32_16x16x32_f16 v[32:35], v[122:125], v[110:113], v[32:35]
	ds_read_b128 v[110:113], v21 offset:22528
	s_waitcnt lgkmcnt(1)
	v_mfma_f32_16x16x32_f16 v[98:101], v[62:65], v[90:93], v[98:101]
	s_waitcnt vmcnt(4)
	ds_write_b128 v20, v[134:137]
	s_waitcnt lgkmcnt(1)
	v_mfma_f32_16x16x32_f16 v[52:55], v[62:65], v[110:113], v[52:55]
	ds_read_b128 v[62:65], v22 offset:49152
	v_mfma_f32_16x16x32_f16 v[102:105], v[74:77], v[90:93], v[102:105]
	s_waitcnt vmcnt(3)
	ds_write_b128 v17, v[94:97] offset:32768
	v_mfma_f32_16x16x32_f16 v[24:27], v[74:77], v[110:113], v[24:27]
	ds_read_b128 v[74:77], v22 offset:51200
	v_mfma_f32_16x16x32_f16 v[114:117], v[118:121], v[90:93], v[114:117]
	s_waitcnt vmcnt(2)
	ds_write_b128 v18, v[162:165] offset:32768
	v_mfma_f32_16x16x32_f16 v[40:43], v[118:121], v[110:113], v[40:43]
	ds_read_b128 v[118:121], v22 offset:53248
	v_mfma_f32_16x16x32_f16 v[70:73], v[122:125], v[90:93], v[70:73]
	ds_read_b128 v[90:93], v23 offset:16384
	v_mfma_f32_16x16x32_f16 v[48:51], v[122:125], v[110:113], v[48:51]
	ds_read_b128 v[110:113], v23 offset:18432
	s_waitcnt lgkmcnt(1)
	v_mfma_f32_16x16x32_f16 v[36:39], v[62:65], v[90:93], v[36:39]
	ds_read_b128 v[122:125], v22 offset:55296
	s_waitcnt lgkmcnt(1)
	v_mfma_f32_16x16x32_f16 v[66:69], v[62:65], v[110:113], v[66:69]
	s_waitcnt vmcnt(1)
	ds_write_b128 v19, v[166:169] offset:32768
	v_mfma_f32_16x16x32_f16 v[44:47], v[74:77], v[90:93], v[44:47]
	s_waitcnt vmcnt(0)
	ds_write_b128 v20, v[190:193] offset:32768
	v_mfma_f32_16x16x32_f16 v[78:81], v[74:77], v[110:113], v[78:81]
	v_mfma_f32_16x16x32_f16 v[82:85], v[118:121], v[90:93], v[82:85]
	v_mfma_f32_16x16x32_f16 v[86:89], v[118:121], v[110:113], v[86:89]
	s_waitcnt lgkmcnt(2)
	v_mfma_f32_16x16x32_f16 v[28:31], v[122:125], v[90:93], v[28:31]
	ds_read_b128 v[90:93], v23 offset:20480
	v_mfma_f32_16x16x32_f16 v[32:35], v[122:125], v[110:113], v[32:35]
	ds_read_b128 v[110:113], v23 offset:22528
	s_waitcnt lgkmcnt(1)
	v_mfma_f32_16x16x32_f16 v[98:101], v[62:65], v[90:93], v[98:101]
	s_waitcnt lgkmcnt(0)
	v_mfma_f32_16x16x32_f16 v[52:55], v[62:65], v[110:113], v[52:55]
	global_load_dwordx4 v[62:65], v[0:1], off offset:2176
	v_mfma_f32_16x16x32_f16 v[102:105], v[74:77], v[90:93], v[102:105]
	v_mfma_f32_16x16x32_f16 v[24:27], v[74:77], v[110:113], v[24:27]
	v_mfma_f32_16x16x32_f16 v[114:117], v[118:121], v[90:93], v[114:117]
	v_mfma_f32_16x16x32_f16 v[40:43], v[118:121], v[110:113], v[40:43]
	v_mfma_f32_16x16x32_f16 v[70:73], v[122:125], v[90:93], v[70:73]
	global_load_dwordx4 v[90:93], v[2:3], off offset:2176
	global_load_dwordx4 v[130:133], v[4:5], off offset:2176
	global_load_dwordx4 v[138:141], v[14:15], off offset:2176
	global_load_dwordx4 v[74:77], v[10:11], off offset:2176
	global_load_dwordx4 v[142:145], v[12:13], off offset:2176
	global_load_dwordx4 v[154:157], v[8:9], off offset:2176
	global_load_dwordx4 v[158:161], v[6:7], off offset:2176
	s_waitcnt lgkmcnt(0)
	s_barrier
; #define GL_LOAD(s_, kt_) if (VAR != 1) { a##s_##0 = GL_A(0, kt_); a##s_##1 = GL_A(1, kt_); a##s_##2 = GL_A(2, kt_); a##s_##3 = GL_A(3, kt_); b##s_##0 = GL_B(0, kt_); b##s_##1 = GL_B(1, kt_); b##s_##2 = GL_B(2, kt_); b##s_##3 = GL_B(3, kt_); }
; #define LDS_STORE(s_, buf_) if (VAR != 2) { LDS_ST1(sA, 0, buf_, a##s_##0) LDS_ST1(sA, 1, buf_, a##s_##1) LDS_ST1(sA, 2, buf_, a##s_##2) LDS_ST1(sA, 3, buf_, a##s_##3) LDS_ST1(sB, 0, buf_, b##s_##0) LDS_ST1(sB, 1, buf_, b##s_##1) LDS_ST1(sB, 2, buf_, b##s_##2) LDS_ST1(sB, 3, buf_, b##s_##3) }
;     ...
;   GL_LOAD(0, 0)
;   GL_LOAD(1, 1)
;   LDS_STORE(0, 0)
;   if (VAR != 4) __syncthreads();
; #pragma unroll
;   for (int kt = 0; kt < nk; kt += 2) {
;     if (kt + 2 < nk) { GL_LOAD(0, kt + 2) }
;     MMA_TILE(0)
;     LDS_STORE(1, 1)
;     if (VAR != 4) __syncthreads();
;     if (kt + 3 < nk) { GL_LOAD(1, kt + 3) }
;     MMA_TILE(1)
;     if (kt + 2 < nk) { LDS_STORE(0, 0) }
;     if (VAR != 4) __syncthreads();
	v_mfma_f32_16x16x32_f16 v[48:51], v[122:125], v[110:113], v[48:51]
	ds_read_b128 v[58:61], v16 offset:32768
	ds_read_b128 v[106:109], v21
	s_waitcnt lgkmcnt(0)
	v_mfma_f32_16x16x32_f16 v[36:39], v[58:61], v[106:109], v[36:39]
	ds_read_b128 v[94:97], v16 offset:34816
	ds_read_b128 v[110:113], v21 offset:2048
	s_waitcnt lgkmcnt(0)
	v_mfma_f32_16x16x32_f16 v[66:69], v[58:61], v[110:113], v[66:69]
	ds_read_b128 v[118:121], v16 offset:36864
	v_mfma_f32_16x16x32_f16 v[44:47], v[94:97], v[106:109], v[44:47]
	ds_read_b128 v[122:125], v16 offset:38912
	v_mfma_f32_16x16x32_f16 v[78:81], v[94:97], v[110:113], v[78:81]
	s_waitcnt vmcnt(7)
	ds_write_b128 v17, v[62:65] offset:16384
	s_waitcnt lgkmcnt(2)
	v_mfma_f32_16x16x32_f16 v[82:85], v[118:121], v[106:109], v[82:85]
	s_waitcnt vmcnt(6)
	ds_write_b128 v18, v[90:93] offset:16384
	v_mfma_f32_16x16x32_f16 v[86:89], v[118:121], v[110:113], v[86:89]
	s_waitcnt vmcnt(5)
	ds_write_b128 v19, v[130:133] offset:16384
	s_waitcnt lgkmcnt(3)
	v_mfma_f32_16x16x32_f16 v[28:31], v[122:125], v[106:109], v[28:31]
	ds_read_b128 v[106:109], v21 offset:4096
	v_mfma_f32_16x16x32_f16 v[32:35], v[122:125], v[110:113], v[32:35]
	ds_read_b128 v[110:113], v21 offset:6144
	s_waitcnt lgkmcnt(1)
	v_mfma_f32_16x16x32_f16 v[98:101], v[58:61], v[106:109], v[98:101]
	s_waitcnt vmcnt(4)
	ds_write_b128 v20, v[138:141] offset:16384
	s_waitcnt lgkmcnt(1)
	v_mfma_f32_16x16x32_f16 v[52:55], v[58:61], v[110:113], v[52:55]
	ds_read_b128 v[58:61], v22 offset:32768
	v_mfma_f32_16x16x32_f16 v[102:105], v[94:97], v[106:109], v[102:105]
	s_waitcnt vmcnt(3)
	ds_write_b128 v17, v[74:77] offset:49152
	v_mfma_f32_16x16x32_f16 v[24:27], v[94:97], v[110:113], v[24:27]
	ds_read_b128 v[94:97], v22 offset:34816
	v_mfma_f32_16x16x32_f16 v[114:117], v[118:121], v[106:109], v[114:117]
	s_waitcnt vmcnt(2)
	ds_write_b128 v18, v[142:145] offset:49152
	v_mfma_f32_16x16x32_f16 v[40:43], v[118:121], v[110:113], v[40:43]
	ds_read_b128 v[118:121], v22 offset:36864
	v_mfma_f32_16x16x32_f16 v[70:73], v[122:125], v[106:109], v[70:73]
	ds_read_b128 v[106:109], v23
	v_mfma_f32_16x16x32_f16 v[48:51], v[122:125], v[110:113], v[48:51]
	ds_read_b128 v[110:113], v23 offset:2048
	s_waitcnt lgkmcnt(1)
	v_mfma_f32_16x16x32_f16 v[36:39], v[58:61], v[106:109], v[36:39]
	ds_read_b128 v[122:125], v22 offset:38912
	s_waitcnt lgkmcnt(1)
	v_mfma_f32_16x16x32_f16 v[66:69], v[58:61], v[110:113], v[66:69]
	s_waitcnt vmcnt(1)
	ds_write_b128 v19, v[154:157] offset:49152
	v_mfma_f32_16x16x32_f16 v[44:47], v[94:97], v[106:109], v[44:47]
	s_waitcnt vmcnt(0)
	ds_write_b128 v20, v[158:161] offset:49152
	v_mfma_f32_16x16x32_f16 v[78:81], v[94:97], v[110:113], v[78:81]
	v_mfma_f32_16x16x32_f16 v[82:85], v[118:121], v[106:109], v[82:85]
	v_mfma_f32_16x16x32_f16 v[86:89], v[118:121], v[110:113], v[86:89]
	s_waitcnt lgkmcnt(2)
	v_mfma_f32_16x16x32_f16 v[28:31], v[122:125], v[106:109], v[28:31]
	ds_read_b128 v[106:109], v23 offset:4096
	v_mfma_f32_16x16x32_f16 v[32:35], v[122:125], v[110:113], v[32:35]
	ds_read_b128 v[110:113], v23 offset:6144
	s_waitcnt lgkmcnt(1)
	v_mfma_f32_16x16x32_f16 v[98:101], v[58:61], v[106:109], v[98:101]
	s_waitcnt lgkmcnt(0)
	v_mfma_f32_16x16x32_f16 v[52:55], v[58:61], v[110:113], v[52:55]
	global_load_dwordx4 v[58:61], v[0:1], off offset:2304
	v_mfma_f32_16x16x32_f16 v[102:105], v[94:97], v[106:109], v[102:105]
	v_mfma_f32_16x16x32_f16 v[24:27], v[94:97], v[110:113], v[24:27]
	v_mfma_f32_16x16x32_f16 v[114:117], v[118:121], v[106:109], v[114:117]
	v_mfma_f32_16x16x32_f16 v[40:43], v[118:121], v[110:113], v[40:43]
	v_mfma_f32_16x16x32_f16 v[70:73], v[122:125], v[106:109], v[70:73]
	global_load_dwordx4 v[106:109], v[2:3], off offset:2304
	global_load_dwordx4 v[126:129], v[4:5], off offset:2304
	global_load_dwordx4 v[134:137], v[14:15], off offset:2304
	global_load_dwordx4 v[94:97], v[10:11], off offset:2304
	global_load_dwordx4 v[162:165], v[12:13], off offset:2304
	global_load_dwordx4 v[166:169], v[8:9], off offset:2304
	global_load_dwordx4 v[190:193], v[6:7], off offset:2304
	s_waitcnt lgkmcnt(0)
	s_barrier
	v_mfma_f32_16x16x32_f16 v[48:51], v[122:125], v[110:113], v[48:51]
	ds_read_b128 v[62:65], v16 offset:49152
	ds_read_b128 v[90:93], v21 offset:16384
	s_waitcnt lgkmcnt(0)
	v_mfma_f32_16x16x32_f16 v[36:39], v[62:65], v[90:93], v[36:39]
	ds_read_b128 v[74:77], v16 offset:51200
	ds_read_b128 v[110:113], v21 offset:18432
	s_waitcnt lgkmcnt(0)
	v_mfma_f32_16x16x32_f16 v[66:69], v[62:65], v[110:113], v[66:69]
	ds_read_b128 v[118:121], v16 offset:53248
	v_mfma_f32_16x16x32_f16 v[44:47], v[74:77], v[90:93], v[44:47]
	ds_read_b128 v[122:125], v16 offset:55296
	v_mfma_f32_16x16x32_f16 v[78:81], v[74:77], v[110:113], v[78:81]
	s_waitcnt vmcnt(7)
	ds_write_b128 v17, v[58:61]
	s_waitcnt lgkmcnt(2)
	v_mfma_f32_16x16x32_f16 v[82:85], v[118:121], v[90:93], v[82:85]
	s_waitcnt vmcnt(6)
	ds_write_b128 v18, v[106:109]
	v_mfma_f32_16x16x32_f16 v[86:89], v[118:121], v[110:113], v[86:89]
	s_waitcnt vmcnt(5)
	ds_write_b128 v19, v[126:129]
	s_waitcnt lgkmcnt(3)
	v_mfma_f32_16x16x32_f16 v[28:31], v[122:125], v[90:93], v[28:31]
	ds_read_b128 v[90:93], v21 offset:20480
	v_mfma_f32_16x16x32_f16 v[32:35], v[122:125], v[110:113], v[32:35]
	ds_read_b128 v[110:113], v21 offset:22528
	s_waitcnt lgkmcnt(1)
	v_mfma_f32_16x16x32_f16 v[98:101], v[62:65], v[90:93], v[98:101]
	s_waitcnt vmcnt(4)
	ds_write_b128 v20, v[134:137]
	s_waitcnt lgkmcnt(1)
	v_mfma_f32_16x16x32_f16 v[52:55], v[62:65], v[110:113], v[52:55]
	ds_read_b128 v[62:65], v22 offset:49152
	v_mfma_f32_16x16x32_f16 v[102:105], v[74:77], v[90:93], v[102:105]
	s_waitcnt vmcnt(3)
; #define GL_LOAD(s_, kt_) if (VAR != 1) { a##s_##0 = GL_A(0, kt_); a##s_##1 = GL_A(1, kt_); a##s_##2 = GL_A(2, kt_); a##s_##3 = GL_A(3, kt_); b##s_##0 = GL_B(0, kt_); b##s_##1 = GL_B(1, kt_); b##s_##2 = GL_B(2, kt_); b##s_##3 = GL_B(3, kt_); }
; #define LDS_STORE(s_, buf_) if (VAR != 2) { LDS_ST1(sA, 0, buf_, a##s_##0) LDS_ST1(sA, 1, buf_, a##s_##1) LDS_ST1(sA, 2, buf_, a##s_##2) LDS_ST1(sA, 3, buf_, a##s_##3) LDS_ST1(sB, 0, buf_, b##s_##0) LDS_ST1(sB, 1, buf_, b##s_##1) LDS_ST1(sB, 2, buf_, b##s_##2) LDS_ST1(sB, 3, buf_, b##s_##3) }
;     ...
;   GL_LOAD(0, 0)
;   GL_LOAD(1, 1)
;   LDS_STORE(0, 0)
;   if (VAR != 4) __syncthreads();
; #pragma unroll
;   for (int kt = 0; kt < nk; kt += 2) {
;     if (kt + 2 < nk) { GL_LOAD(0, kt + 2) }
;     MMA_TILE(0)
;     LDS_STORE(1, 1)
;     if (VAR != 4) __syncthreads();
;     if (kt + 3 < nk) { GL_LOAD(1, kt + 3) }
;     MMA_TILE(1)
;     if (kt + 2 < nk) { LDS_STORE(0, 0) }
;     if (VAR != 4) __syncthreads();
	ds_write_b128 v17, v[94:97] offset:32768
	v_mfma_f32_16x16x32_f16 v[24:27], v[74:77], v[110:113], v[24:27]
	ds_read_b128 v[74:77], v22 offset:51200
	v_mfma_f32_16x16x32_f16 v[114:117], v[118:121], v[90:93], v[114:117]
	s_waitcnt vmcnt(2)
	ds_write_b128 v18, v[162:165] offset:32768
	v_mfma_f32_16x16x32_f16 v[40:43], v[118:121], v[110:113], v[40:43]
	ds_read_b128 v[118:121], v22 offset:53248
	v_mfma_f32_16x16x32_f16 v[70:73], v[122:125], v[90:93], v[70:73]
	ds_read_b128 v[90:93], v23 offset:16384
	v_mfma_f32_16x16x32_f16 v[48:51], v[122:125], v[110:113], v[48:51]
	ds_read_b128 v[110:113], v23 offset:18432
	s_waitcnt lgkmcnt(1)
	v_mfma_f32_16x16x32_f16 v[36:39], v[62:65], v[90:93], v[36:39]
	ds_read_b128 v[122:125], v22 offset:55296
	s_waitcnt lgkmcnt(1)
	v_mfma_f32_16x16x32_f16 v[66:69], v[62:65], v[110:113], v[66:69]
	s_waitcnt vmcnt(1)
	ds_write_b128 v19, v[166:169] offset:32768
	v_mfma_f32_16x16x32_f16 v[44:47], v[74:77], v[90:93], v[44:47]
	s_waitcnt vmcnt(0)
	ds_write_b128 v20, v[190:193] offset:32768
	v_mfma_f32_16x16x32_f16 v[78:81], v[74:77], v[110:113], v[78:81]
	v_mfma_f32_16x16x32_f16 v[82:85], v[118:121], v[90:93], v[82:85]
	v_mfma_f32_16x16x32_f16 v[86:89], v[118:121], v[110:113], v[86:89]
	s_waitcnt lgkmcnt(2)
	v_mfma_f32_16x16x32_f16 v[28:31], v[122:125], v[90:93], v[28:31]
	ds_read_b128 v[90:93], v23 offset:20480
	v_mfma_f32_16x16x32_f16 v[32:35], v[122:125], v[110:113], v[32:35]
	ds_read_b128 v[110:113], v23 offset:22528
	s_waitcnt lgkmcnt(1)
	v_mfma_f32_16x16x32_f16 v[98:101], v[62:65], v[90:93], v[98:101]
	s_waitcnt lgkmcnt(0)
	v_mfma_f32_16x16x32_f16 v[52:55], v[62:65], v[110:113], v[52:55]
	global_load_dwordx4 v[62:65], v[0:1], off offset:2432
	v_mfma_f32_16x16x32_f16 v[102:105], v[74:77], v[90:93], v[102:105]
	v_mfma_f32_16x16x32_f16 v[24:27], v[74:77], v[110:113], v[24:27]
	v_mfma_f32_16x16x32_f16 v[114:117], v[118:121], v[90:93], v[114:117]
	v_mfma_f32_16x16x32_f16 v[40:43], v[118:121], v[110:113], v[40:43]
	v_mfma_f32_16x16x32_f16 v[70:73], v[122:125], v[90:93], v[70:73]
	global_load_dwordx4 v[90:93], v[2:3], off offset:2432
	global_load_dwordx4 v[130:133], v[4:5], off offset:2432
	global_load_dwordx4 v[138:141], v[14:15], off offset:2432
	global_load_dwordx4 v[74:77], v[10:11], off offset:2432
	global_load_dwordx4 v[142:145], v[12:13], off offset:2432
	global_load_dwordx4 v[154:157], v[8:9], off offset:2432
	global_load_dwordx4 v[158:161], v[6:7], off offset:2432
	s_waitcnt lgkmcnt(0)
	s_barrier
	v_mfma_f32_16x16x32_f16 v[48:51], v[122:125], v[110:113], v[48:51]
	ds_read_b128 v[58:61], v16 offset:32768
	ds_read_b128 v[106:109], v21
	s_waitcnt lgkmcnt(0)
	v_mfma_f32_16x16x32_f16 v[36:39], v[58:61], v[106:109], v[36:39]
	ds_read_b128 v[94:97], v16 offset:34816
	ds_read_b128 v[110:113], v21 offset:2048
	s_waitcnt lgkmcnt(0)
	v_mfma_f32_16x16x32_f16 v[66:69], v[58:61], v[110:113], v[66:69]
	ds_read_b128 v[118:121], v16 offset:36864
	v_mfma_f32_16x16x32_f16 v[44:47], v[94:97], v[106:109], v[44:47]
	ds_read_b128 v[122:125], v16 offset:38912
	v_mfma_f32_16x16x32_f16 v[78:81], v[94:97], v[110:113], v[78:81]
	s_waitcnt vmcnt(7)
	ds_write_b128 v17, v[62:65] offset:16384
	s_waitcnt lgkmcnt(2)
	v_mfma_f32_16x16x32_f16 v[82:85], v[118:121], v[106:109], v[82:85]
	s_waitcnt vmcnt(6)
	ds_write_b128 v18, v[90:93] offset:16384
	v_mfma_f32_16x16x32_f16 v[86:89], v[118:121], v[110:113], v[86:89]
	s_waitcnt vmcnt(5)
	ds_write_b128 v19, v[130:133] offset:16384
	s_waitcnt lgkmcnt(3)
	v_mfma_f32_16x16x32_f16 v[28:31], v[122:125], v[106:109], v[28:31]
	ds_read_b128 v[106:109], v21 offset:4096
	v_mfma_f32_16x16x32_f16 v[32:35], v[122:125], v[110:113], v[32:35]
	ds_read_b128 v[110:113], v21 offset:6144
	s_waitcnt lgkmcnt(1)
	v_mfma_f32_16x16x32_f16 v[98:101], v[58:61], v[106:109], v[98:101]
	s_waitcnt vmcnt(4)
	ds_write_b128 v20, v[138:141] offset:16384
	s_waitcnt lgkmcnt(1)
	v_mfma_f32_16x16x32_f16 v[52:55], v[58:61], v[110:113], v[52:55]
	ds_read_b128 v[58:61], v22 offset:32768
	v_mfma_f32_16x16x32_f16 v[102:105], v[94:97], v[106:109], v[102:105]
	s_waitcnt vmcnt(3)
	ds_write_b128 v17, v[74:77] offset:49152
	v_mfma_f32_16x16x32_f16 v[24:27], v[94:97], v[110:113], v[24:27]
	ds_read_b128 v[94:97], v22 offset:34816
	v_mfma_f32_16x16x32_f16 v[114:117], v[118:121], v[106:109], v[114:117]
	s_waitcnt vmcnt(2)
	ds_write_b128 v18, v[142:145] offset:49152
	v_mfma_f32_16x16x32_f16 v[40:43], v[118:121], v[110:113], v[40:43]
	ds_read_b128 v[118:121], v22 offset:36864
	v_mfma_f32_16x16x32_f16 v[70:73], v[122:125], v[106:109], v[70:73]
	ds_read_b128 v[106:109], v23
	v_mfma_f32_16x16x32_f16 v[48:51], v[122:125], v[110:113], v[48:51]
	ds_read_b128 v[110:113], v23 offset:2048
	s_waitcnt lgkmcnt(1)
	v_mfma_f32_16x16x32_f16 v[36:39], v[58:61], v[106:109], v[36:39]
	ds_read_b128 v[122:125], v22 offset:38912
	s_waitcnt lgkmcnt(1)
	v_mfma_f32_16x16x32_f16 v[66:69], v[58:61], v[110:113], v[66:69]
	s_waitcnt vmcnt(1)
	ds_write_b128 v19, v[154:157] offset:49152
	v_mfma_f32_16x16x32_f16 v[44:47], v[94:97], v[106:109], v[44:47]
	s_waitcnt vmcnt(0)
	ds_write_b128 v20, v[158:161] offset:49152
	v_mfma_f32_16x16x32_f16 v[78:81], v[94:97], v[110:113], v[78:81]
	v_mfma_f32_16x16x32_f16 v[82:85], v[118:121], v[106:109], v[82:85]
	v_mfma_f32_16x16x32_f16 v[86:89], v[118:121], v[110:113], v[86:89]
	s_waitcnt lgkmcnt(2)
	v_mfma_f32_16x16x32_f16 v[28:31], v[122:125], v[106:109], v[28:31]
	ds_read_b128 v[106:109], v23 offset:4096
	v_mfma_f32_16x16x32_f16 v[32:35], v[122:125], v[110:113], v[32:35]
	ds_read_b128 v[110:113], v23 offset:6144
	s_waitcnt lgkmcnt(1)
	v_mfma_f32_16x16x32_f16 v[98:101], v[58:61], v[106:109], v[98:101]
	s_waitcnt lgkmcnt(0)
	v_mfma_f32_16x16x32_f16 v[52:55], v[58:61], v[110:113], v[52:55]
	global_load_dwordx4 v[58:61], v[0:1], off offset:2560
	v_mfma_f32_16x16x32_f16 v[102:105], v[94:97], v[106:109], v[102:105]
	v_mfma_f32_16x16x32_f16 v[24:27], v[94:97], v[110:113], v[24:27]
	v_mfma_f32_16x16x32_f16 v[114:117], v[118:121], v[106:109], v[114:117]
	v_mfma_f32_16x16x32_f16 v[40:43], v[118:121], v[110:113], v[40:43]
	v_mfma_f32_16x16x32_f16 v[70:73], v[122:125], v[106:109], v[70:73]
	global_load_dwordx4 v[106:109], v[2:3], off offset:2560
	global_load_dwordx4 v[126:129], v[4:5], off offset:2560
	global_load_dwordx4 v[134:137], v[14:15], off offset:2560
	global_load_dwordx4 v[94:97], v[10:11], off offset:2560
	global_load_dwordx4 v[162:165], v[12:13], off offset:2560
	global_load_dwordx4 v[166:169], v[8:9], off offset:2560
	global_load_dwordx4 v[190:193], v[6:7], off offset:2560
	s_waitcnt lgkmcnt(0)
	s_barrier
; #define GL_LOAD(s_, kt_) if (VAR != 1) { a##s_##0 = GL_A(0, kt_); a##s_##1 = GL_A(1, kt_); a##s_##2 = GL_A(2, kt_); a##s_##3 = GL_A(3, kt_); b##s_##0 = GL_B(0, kt_); b##s_##1 = GL_B(1, kt_); b##s_##2 = GL_B(2, kt_); b##s_##3 = GL_B(3, kt_); }
; #define LDS_STORE(s_, buf_) if (VAR != 2) { LDS_ST1(sA, 0, buf_, a##s_##0) LDS_ST1(sA, 1, buf_, a##s_##1) LDS_ST1(sA, 2, buf_, a##s_##2) LDS_ST1(sA, 3, buf_, a##s_##3) LDS_ST1(sB, 0, buf_, b##s_##0) LDS_ST1(sB, 1, buf_, b##s_##1) LDS_ST1(sB, 2, buf_, b##s_##2) LDS_ST1(sB, 3, buf_, b##s_##3) }
;     ...
;   GL_LOAD(0, 0)
;   GL_LOAD(1, 1)
;   LDS_STORE(0, 0)
;   if (VAR != 4) __syncthreads();
; #pragma unroll
;   for (int kt = 0; kt < nk; kt += 2) {
;     if (kt + 2 < nk) { GL_LOAD(0, kt + 2) }
;     MMA_TILE(0)
;     LDS_STORE(1, 1)
;     if (VAR != 4) __syncthreads();
;     if (kt + 3 < nk) { GL_LOAD(1, kt + 3) }
;     MMA_TILE(1)
;     if (kt + 2 < nk) { LDS_STORE(0, 0) }
;     if (VAR != 4) __syncthreads();
	v_mfma_f32_16x16x32_f16 v[48:51], v[122:125], v[110:113], v[48:51]
	ds_read_b128 v[62:65], v16 offset:49152
	ds_read_b128 v[90:93], v21 offset:16384
	s_waitcnt lgkmcnt(0)
	v_mfma_f32_16x16x32_f16 v[36:39], v[62:65], v[90:93], v[36:39]
	ds_read_b128 v[74:77], v16 offset:51200
	ds_read_b128 v[110:113], v21 offset:18432
	s_waitcnt lgkmcnt(0)
	v_mfma_f32_16x16x32_f16 v[66:69], v[62:65], v[110:113], v[66:69]
	ds_read_b128 v[118:121], v16 offset:53248
	v_mfma_f32_16x16x32_f16 v[44:47], v[74:77], v[90:93], v[44:47]
	ds_read_b128 v[122:125], v16 offset:55296
	v_mfma_f32_16x16x32_f16 v[78:81], v[74:77], v[110:113], v[78:81]
	s_waitcnt vmcnt(7)
	ds_write_b128 v17, v[58:61]
	s_waitcnt lgkmcnt(2)
	v_mfma_f32_16x16x32_f16 v[82:85], v[118:121], v[90:93], v[82:85]
	s_waitcnt vmcnt(6)
	ds_write_b128 v18, v[106:109]
	v_mfma_f32_16x16x32_f16 v[86:89], v[118:121], v[110:113], v[86:89]
	s_waitcnt vmcnt(5)
	ds_write_b128 v19, v[126:129]
	s_waitcnt lgkmcnt(3)
	v_mfma_f32_16x16x32_f16 v[28:31], v[122:125], v[90:93], v[28:31]
	ds_read_b128 v[90:93], v21 offset:20480
	v_mfma_f32_16x16x32_f16 v[32:35], v[122:125], v[110:113], v[32:35]
	ds_read_b128 v[110:113], v21 offset:22528
	s_waitcnt lgkmcnt(1)
	v_mfma_f32_16x16x32_f16 v[98:101], v[62:65], v[90:93], v[98:101]
	s_waitcnt vmcnt(4)
	ds_write_b128 v20, v[134:137]
	s_waitcnt lgkmcnt(1)
	v_mfma_f32_16x16x32_f16 v[52:55], v[62:65], v[110:113], v[52:55]
	ds_read_b128 v[62:65], v22 offset:49152
	v_mfma_f32_16x16x32_f16 v[102:105], v[74:77], v[90:93], v[102:105]
	s_waitcnt vmcnt(3)
	ds_write_b128 v17, v[94:97] offset:32768
	v_mfma_f32_16x16x32_f16 v[24:27], v[74:77], v[110:113], v[24:27]
	ds_read_b128 v[74:77], v22 offset:51200
	v_mfma_f32_16x16x32_f16 v[114:117], v[118:121], v[90:93], v[114:117]
	s_waitcnt vmcnt(2)
	ds_write_b128 v18, v[162:165] offset:32768
	v_mfma_f32_16x16x32_f16 v[40:43], v[118:121], v[110:113], v[40:43]
	ds_read_b128 v[118:121], v22 offset:53248
	v_mfma_f32_16x16x32_f16 v[70:73], v[122:125], v[90:93], v[70:73]
	ds_read_b128 v[90:93], v23 offset:16384
	v_mfma_f32_16x16x32_f16 v[48:51], v[122:125], v[110:113], v[48:51]
	ds_read_b128 v[110:113], v23 offset:18432
	s_waitcnt lgkmcnt(1)
	v_mfma_f32_16x16x32_f16 v[36:39], v[62:65], v[90:93], v[36:39]
	ds_read_b128 v[122:125], v22 offset:55296
	s_waitcnt lgkmcnt(1)
	v_mfma_f32_16x16x32_f16 v[66:69], v[62:65], v[110:113], v[66:69]
	s_waitcnt vmcnt(1)
	ds_write_b128 v19, v[166:169] offset:32768
	v_mfma_f32_16x16x32_f16 v[44:47], v[74:77], v[90:93], v[44:47]
	s_waitcnt vmcnt(0)
	ds_write_b128 v20, v[190:193] offset:32768
	v_mfma_f32_16x16x32_f16 v[78:81], v[74:77], v[110:113], v[78:81]
	v_mfma_f32_16x16x32_f16 v[82:85], v[118:121], v[90:93], v[82:85]
	v_mfma_f32_16x16x32_f16 v[86:89], v[118:121], v[110:113], v[86:89]
	s_waitcnt lgkmcnt(2)
	v_mfma_f32_16x16x32_f16 v[28:31], v[122:125], v[90:93], v[28:31]
	ds_read_b128 v[90:93], v23 offset:20480
	v_mfma_f32_16x16x32_f16 v[32:35], v[122:125], v[110:113], v[32:35]
	ds_read_b128 v[110:113], v23 offset:22528
	s_waitcnt lgkmcnt(1)
	v_mfma_f32_16x16x32_f16 v[98:101], v[62:65], v[90:93], v[98:101]
	s_waitcnt lgkmcnt(0)
	v_mfma_f32_16x16x32_f16 v[52:55], v[62:65], v[110:113], v[52:55]
	global_load_dwordx4 v[62:65], v[0:1], off offset:2688
	v_mfma_f32_16x16x32_f16 v[102:105], v[74:77], v[90:93], v[102:105]
	v_mfma_f32_16x16x32_f16 v[24:27], v[74:77], v[110:113], v[24:27]
	v_mfma_f32_16x16x32_f16 v[114:117], v[118:121], v[90:93], v[114:117]
	v_mfma_f32_16x16x32_f16 v[40:43], v[118:121], v[110:113], v[40:43]
	v_mfma_f32_16x16x32_f16 v[70:73], v[122:125], v[90:93], v[70:73]
	global_load_dwordx4 v[90:93], v[2:3], off offset:2688
	global_load_dwordx4 v[130:133], v[4:5], off offset:2688
	global_load_dwordx4 v[138:141], v[14:15], off offset:2688
	global_load_dwordx4 v[74:77], v[10:11], off offset:2688
	global_load_dwordx4 v[142:145], v[12:13], off offset:2688
	global_load_dwordx4 v[154:157], v[8:9], off offset:2688
	global_load_dwordx4 v[158:161], v[6:7], off offset:2688
	s_waitcnt lgkmcnt(0)
	s_barrier
	v_mfma_f32_16x16x32_f16 v[48:51], v[122:125], v[110:113], v[48:51]
	ds_read_b128 v[58:61], v16 offset:32768
	ds_read_b128 v[106:109], v21
	s_waitcnt lgkmcnt(0)
	v_mfma_f32_16x16x32_f16 v[36:39], v[58:61], v[106:109], v[36:39]
	ds_read_b128 v[94:97], v16 offset:34816
	ds_read_b128 v[110:113], v21 offset:2048
	s_waitcnt lgkmcnt(0)
	v_mfma_f32_16x16x32_f16 v[66:69], v[58:61], v[110:113], v[66:69]
	ds_read_b128 v[118:121], v16 offset:36864
	v_mfma_f32_16x16x32_f16 v[44:47], v[94:97], v[106:109], v[44:47]
	ds_read_b128 v[122:125], v16 offset:38912
	v_mfma_f32_16x16x32_f16 v[78:81], v[94:97], v[110:113], v[78:81]
	s_waitcnt vmcnt(7)
	ds_write_b128 v17, v[62:65] offset:16384
	s_waitcnt lgkmcnt(2)
	v_mfma_f32_16x16x32_f16 v[82:85], v[118:121], v[106:109], v[82:85]
	s_waitcnt vmcnt(6)
	ds_write_b128 v18, v[90:93] offset:16384
	v_mfma_f32_16x16x32_f16 v[86:89], v[118:121], v[110:113], v[86:89]
	s_waitcnt vmcnt(5)
	ds_write_b128 v19, v[130:133] offset:16384
	s_waitcnt lgkmcnt(3)
	v_mfma_f32_16x16x32_f16 v[28:31], v[122:125], v[106:109], v[28:31]
	ds_read_b128 v[106:109], v21 offset:4096
	v_mfma_f32_16x16x32_f16 v[32:35], v[122:125], v[110:113], v[32:35]
	ds_read_b128 v[110:113], v21 offset:6144
	s_waitcnt lgkmcnt(1)
	v_mfma_f32_16x16x32_f16 v[98:101], v[58:61], v[106:109], v[98:101]
	s_waitcnt vmcnt(4)
	ds_write_b128 v20, v[138:141] offset:16384
	s_waitcnt lgkmcnt(1)
	v_mfma_f32_16x16x32_f16 v[52:55], v[58:61], v[110:113], v[52:55]
	ds_read_b128 v[58:61], v22 offset:32768
	v_mfma_f32_16x16x32_f16 v[102:105], v[94:97], v[106:109], v[102:105]
	s_waitcnt vmcnt(3)
; #define GL_LOAD(s_, kt_) if (VAR != 1) { a##s_##0 = GL_A(0, kt_); a##s_##1 = GL_A(1, kt_); a##s_##2 = GL_A(2, kt_); a##s_##3 = GL_A(3, kt_); b##s_##0 = GL_B(0, kt_); b##s_##1 = GL_B(1, kt_); b##s_##2 = GL_B(2, kt_); b##s_##3 = GL_B(3, kt_); }
; #define LDS_STORE(s_, buf_) if (VAR != 2) { LDS_ST1(sA, 0, buf_, a##s_##0) LDS_ST1(sA, 1, buf_, a##s_##1) LDS_ST1(sA, 2, buf_, a##s_##2) LDS_ST1(sA, 3, buf_, a##s_##3) LDS_ST1(sB, 0, buf_, b##s_##0) LDS_ST1(sB, 1, buf_, b##s_##1) LDS_ST1(sB, 2, buf_, b##s_##2) LDS_ST1(sB, 3, buf_, b##s_##3) }
;     ...
;   GL_LOAD(0, 0)
;   GL_LOAD(1, 1)
;   LDS_STORE(0, 0)
;   if (VAR != 4) __syncthreads();
; #pragma unroll
;   for (int kt = 0; kt < nk; kt += 2) {
;     if (kt + 2 < nk) { GL_LOAD(0, kt + 2) }
;     MMA_TILE(0)
;     LDS_STORE(1, 1)
;     if (VAR != 4) __syncthreads();
;     if (kt + 3 < nk) { GL_LOAD(1, kt + 3) }
;     MMA_TILE(1)
;     if (kt + 2 < nk) { LDS_STORE(0, 0) }
;     if (VAR != 4) __syncthreads();
	ds_write_b128 v17, v[74:77] offset:49152
	v_mfma_f32_16x16x32_f16 v[24:27], v[94:97], v[110:113], v[24:27]
	ds_read_b128 v[94:97], v22 offset:34816
	v_mfma_f32_16x16x32_f16 v[114:117], v[118:121], v[106:109], v[114:117]
	s_waitcnt vmcnt(2)
	ds_write_b128 v18, v[142:145] offset:49152
	v_mfma_f32_16x16x32_f16 v[40:43], v[118:121], v[110:113], v[40:43]
	ds_read_b128 v[118:121], v22 offset:36864
	v_mfma_f32_16x16x32_f16 v[70:73], v[122:125], v[106:109], v[70:73]
	ds_read_b128 v[106:109], v23
	v_mfma_f32_16x16x32_f16 v[48:51], v[122:125], v[110:113], v[48:51]
	ds_read_b128 v[110:113], v23 offset:2048
	s_waitcnt lgkmcnt(1)
	v_mfma_f32_16x16x32_f16 v[36:39], v[58:61], v[106:109], v[36:39]
	ds_read_b128 v[122:125], v22 offset:38912
	s_waitcnt lgkmcnt(1)
	v_mfma_f32_16x16x32_f16 v[66:69], v[58:61], v[110:113], v[66:69]
	s_waitcnt vmcnt(1)
	ds_write_b128 v19, v[154:157] offset:49152
	v_mfma_f32_16x16x32_f16 v[44:47], v[94:97], v[106:109], v[44:47]
	s_waitcnt vmcnt(0)
	ds_write_b128 v20, v[158:161] offset:49152
	v_mfma_f32_16x16x32_f16 v[78:81], v[94:97], v[110:113], v[78:81]
	v_mfma_f32_16x16x32_f16 v[82:85], v[118:121], v[106:109], v[82:85]
	v_mfma_f32_16x16x32_f16 v[86:89], v[118:121], v[110:113], v[86:89]
	s_waitcnt lgkmcnt(2)
	v_mfma_f32_16x16x32_f16 v[28:31], v[122:125], v[106:109], v[28:31]
	ds_read_b128 v[106:109], v23 offset:4096
	v_mfma_f32_16x16x32_f16 v[32:35], v[122:125], v[110:113], v[32:35]
	ds_read_b128 v[110:113], v23 offset:6144
	s_waitcnt lgkmcnt(1)
	v_mfma_f32_16x16x32_f16 v[98:101], v[58:61], v[106:109], v[98:101]
	s_waitcnt lgkmcnt(0)
	v_mfma_f32_16x16x32_f16 v[52:55], v[58:61], v[110:113], v[52:55]
	global_load_dwordx4 v[58:61], v[0:1], off offset:2816
	v_mfma_f32_16x16x32_f16 v[102:105], v[94:97], v[106:109], v[102:105]
	v_mfma_f32_16x16x32_f16 v[24:27], v[94:97], v[110:113], v[24:27]
	v_mfma_f32_16x16x32_f16 v[114:117], v[118:121], v[106:109], v[114:117]
	v_mfma_f32_16x16x32_f16 v[40:43], v[118:121], v[110:113], v[40:43]
	v_mfma_f32_16x16x32_f16 v[70:73], v[122:125], v[106:109], v[70:73]
	global_load_dwordx4 v[106:109], v[2:3], off offset:2816
	global_load_dwordx4 v[126:129], v[4:5], off offset:2816
	global_load_dwordx4 v[134:137], v[14:15], off offset:2816
	global_load_dwordx4 v[94:97], v[10:11], off offset:2816
	global_load_dwordx4 v[162:165], v[12:13], off offset:2816
	global_load_dwordx4 v[166:169], v[8:9], off offset:2816
	global_load_dwordx4 v[190:193], v[6:7], off offset:2816
	s_waitcnt lgkmcnt(0)
	s_barrier
	v_mfma_f32_16x16x32_f16 v[48:51], v[122:125], v[110:113], v[48:51]
	ds_read_b128 v[62:65], v16 offset:49152
	ds_read_b128 v[90:93], v21 offset:16384
	s_waitcnt lgkmcnt(0)
	v_mfma_f32_16x16x32_f16 v[36:39], v[62:65], v[90:93], v[36:39]
	ds_read_b128 v[74:77], v16 offset:51200
	ds_read_b128 v[110:113], v21 offset:18432
	s_waitcnt lgkmcnt(0)
	v_mfma_f32_16x16x32_f16 v[66:69], v[62:65], v[110:113], v[66:69]
	ds_read_b128 v[118:121], v16 offset:53248
	v_mfma_f32_16x16x32_f16 v[44:47], v[74:77], v[90:93], v[44:47]
	ds_read_b128 v[122:125], v16 offset:55296
	v_mfma_f32_16x16x32_f16 v[78:81], v[74:77], v[110:113], v[78:81]
	s_waitcnt vmcnt(7)
	ds_write_b128 v17, v[58:61]
	s_waitcnt lgkmcnt(2)
	v_mfma_f32_16x16x32_f16 v[82:85], v[118:121], v[90:93], v[82:85]
	s_waitcnt vmcnt(6)
	ds_write_b128 v18, v[106:109]
	v_mfma_f32_16x16x32_f16 v[86:89], v[118:121], v[110:113], v[86:89]
	s_waitcnt vmcnt(5)
	ds_write_b128 v19, v[126:129]
	s_waitcnt lgkmcnt(3)
	v_mfma_f32_16x16x32_f16 v[28:31], v[122:125], v[90:93], v[28:31]
	ds_read_b128 v[90:93], v21 offset:20480
	v_mfma_f32_16x16x32_f16 v[32:35], v[122:125], v[110:113], v[32:35]
	ds_read_b128 v[110:113], v21 offset:22528
	s_waitcnt lgkmcnt(1)
	v_mfma_f32_16x16x32_f16 v[98:101], v[62:65], v[90:93], v[98:101]
	s_waitcnt vmcnt(4)
	ds_write_b128 v20, v[134:137]
	s_waitcnt lgkmcnt(1)
	v_mfma_f32_16x16x32_f16 v[52:55], v[62:65], v[110:113], v[52:55]
	ds_read_b128 v[62:65], v22 offset:49152
	v_mfma_f32_16x16x32_f16 v[102:105], v[74:77], v[90:93], v[102:105]
	s_waitcnt vmcnt(3)
	ds_write_b128 v17, v[94:97] offset:32768
	v_mfma_f32_16x16x32_f16 v[24:27], v[74:77], v[110:113], v[24:27]
	ds_read_b128 v[74:77], v22 offset:51200
	v_mfma_f32_16x16x32_f16 v[114:117], v[118:121], v[90:93], v[114:117]
	s_waitcnt vmcnt(2)
	ds_write_b128 v18, v[162:165] offset:32768
	v_mfma_f32_16x16x32_f16 v[40:43], v[118:121], v[110:113], v[40:43]
	ds_read_b128 v[118:121], v22 offset:53248
	v_mfma_f32_16x16x32_f16 v[70:73], v[122:125], v[90:93], v[70:73]
	ds_read_b128 v[90:93], v23 offset:16384
	v_mfma_f32_16x16x32_f16 v[48:51], v[122:125], v[110:113], v[48:51]
	ds_read_b128 v[110:113], v23 offset:18432
	s_waitcnt lgkmcnt(1)
	v_mfma_f32_16x16x32_f16 v[36:39], v[62:65], v[90:93], v[36:39]
	ds_read_b128 v[122:125], v22 offset:55296
	s_waitcnt lgkmcnt(1)
	v_mfma_f32_16x16x32_f16 v[66:69], v[62:65], v[110:113], v[66:69]
	s_waitcnt vmcnt(1)
	ds_write_b128 v19, v[166:169] offset:32768
	v_mfma_f32_16x16x32_f16 v[44:47], v[74:77], v[90:93], v[44:47]
	s_waitcnt vmcnt(0)
	ds_write_b128 v20, v[190:193] offset:32768
	v_mfma_f32_16x16x32_f16 v[78:81], v[74:77], v[110:113], v[78:81]
	v_mfma_f32_16x16x32_f16 v[82:85], v[118:121], v[90:93], v[82:85]
	v_mfma_f32_16x16x32_f16 v[86:89], v[118:121], v[110:113], v[86:89]
	s_waitcnt lgkmcnt(2)
	v_mfma_f32_16x16x32_f16 v[28:31], v[122:125], v[90:93], v[28:31]
	ds_read_b128 v[90:93], v23 offset:20480
	v_mfma_f32_16x16x32_f16 v[32:35], v[122:125], v[110:113], v[32:35]
	ds_read_b128 v[110:113], v23 offset:22528
	s_waitcnt lgkmcnt(1)
	v_mfma_f32_16x16x32_f16 v[98:101], v[62:65], v[90:93], v[98:101]
	s_waitcnt lgkmcnt(0)
	v_mfma_f32_16x16x32_f16 v[52:55], v[62:65], v[110:113], v[52:55]
	global_load_dwordx4 v[62:65], v[0:1], off offset:2944
	v_mfma_f32_16x16x32_f16 v[102:105], v[74:77], v[90:93], v[102:105]
	v_mfma_f32_16x16x32_f16 v[24:27], v[74:77], v[110:113], v[24:27]
	v_mfma_f32_16x16x32_f16 v[114:117], v[118:121], v[90:93], v[114:117]
	v_mfma_f32_16x16x32_f16 v[40:43], v[118:121], v[110:113], v[40:43]
	v_mfma_f32_16x16x32_f16 v[70:73], v[122:125], v[90:93], v[70:73]
	global_load_dwordx4 v[90:93], v[2:3], off offset:2944
	global_load_dwordx4 v[130:133], v[4:5], off offset:2944
	global_load_dwordx4 v[138:141], v[14:15], off offset:2944
	global_load_dwordx4 v[74:77], v[10:11], off offset:2944
	global_load_dwordx4 v[142:145], v[12:13], off offset:2944
	global_load_dwordx4 v[154:157], v[8:9], off offset:2944
	global_load_dwordx4 v[158:161], v[6:7], off offset:2944
	s_waitcnt lgkmcnt(0)
	s_barrier
; #define GL_LOAD(s_, kt_) if (VAR != 1) { a##s_##0 = GL_A(0, kt_); a##s_##1 = GL_A(1, kt_); a##s_##2 = GL_A(2, kt_); a##s_##3 = GL_A(3, kt_); b##s_##0 = GL_B(0, kt_); b##s_##1 = GL_B(1, kt_); b##s_##2 = GL_B(2, kt_); b##s_##3 = GL_B(3, kt_); }
; #define LDS_STORE(s_, buf_) if (VAR != 2) { LDS_ST1(sA, 0, buf_, a##s_##0) LDS_ST1(sA, 1, buf_, a##s_##1) LDS_ST1(sA, 2, buf_, a##s_##2) LDS_ST1(sA, 3, buf_, a##s_##3) LDS_ST1(sB, 0, buf_, b##s_##0) LDS_ST1(sB, 1, buf_, b##s_##1) LDS_ST1(sB, 2, buf_, b##s_##2) LDS_ST1(sB, 3, buf_, b##s_##3) }
;     ...
;   GL_LOAD(0, 0)
;   GL_LOAD(1, 1)
;   LDS_STORE(0, 0)
;   if (VAR != 4) __syncthreads();
; #pragma unroll
;   for (int kt = 0; kt < nk; kt += 2) {
;     if (kt + 2 < nk) { GL_LOAD(0, kt + 2) }
;     MMA_TILE(0)
;     LDS_STORE(1, 1)
;     if (VAR != 4) __syncthreads();
;     if (kt + 3 < nk) { GL_LOAD(1, kt + 3) }
;     MMA_TILE(1)
;     if (kt + 2 < nk) { LDS_STORE(0, 0) }
;     if (VAR != 4) __syncthreads();
	v_mfma_f32_16x16x32_f16 v[48:51], v[122:125], v[110:113], v[48:51]
	ds_read_b128 v[58:61], v16 offset:32768
	ds_read_b128 v[106:109], v21
	s_waitcnt lgkmcnt(0)
	v_mfma_f32_16x16x32_f16 v[36:39], v[58:61], v[106:109], v[36:39]
	ds_read_b128 v[94:97], v16 offset:34816
	ds_read_b128 v[110:113], v21 offset:2048
	s_waitcnt lgkmcnt(0)
	v_mfma_f32_16x16x32_f16 v[66:69], v[58:61], v[110:113], v[66:69]
	ds_read_b128 v[118:121], v16 offset:36864
	v_mfma_f32_16x16x32_f16 v[44:47], v[94:97], v[106:109], v[44:47]
	ds_read_b128 v[122:125], v16 offset:38912
	v_mfma_f32_16x16x32_f16 v[78:81], v[94:97], v[110:113], v[78:81]
	s_waitcnt vmcnt(7)
	ds_write_b128 v17, v[62:65] offset:16384
	s_waitcnt lgkmcnt(2)
	v_mfma_f32_16x16x32_f16 v[82:85], v[118:121], v[106:109], v[82:85]
	s_waitcnt vmcnt(6)
	ds_write_b128 v18, v[90:93] offset:16384
	v_mfma_f32_16x16x32_f16 v[86:89], v[118:121], v[110:113], v[86:89]
	s_waitcnt vmcnt(5)
	ds_write_b128 v19, v[130:133] offset:16384
	s_waitcnt lgkmcnt(3)
	v_mfma_f32_16x16x32_f16 v[28:31], v[122:125], v[106:109], v[28:31]
	ds_read_b128 v[106:109], v21 offset:4096
	v_mfma_f32_16x16x32_f16 v[32:35], v[122:125], v[110:113], v[32:35]
	ds_read_b128 v[110:113], v21 offset:6144
	s_waitcnt lgkmcnt(1)
	v_mfma_f32_16x16x32_f16 v[98:101], v[58:61], v[106:109], v[98:101]
	s_waitcnt vmcnt(4)
	ds_write_b128 v20, v[138:141] offset:16384
	s_waitcnt lgkmcnt(1)
	v_mfma_f32_16x16x32_f16 v[52:55], v[58:61], v[110:113], v[52:55]
	ds_read_b128 v[58:61], v22 offset:32768
	v_mfma_f32_16x16x32_f16 v[102:105], v[94:97], v[106:109], v[102:105]
	s_waitcnt vmcnt(3)
	ds_write_b128 v17, v[74:77] offset:49152
	v_mfma_f32_16x16x32_f16 v[24:27], v[94:97], v[110:113], v[24:27]
	ds_read_b128 v[94:97], v22 offset:34816
	v_mfma_f32_16x16x32_f16 v[114:117], v[118:121], v[106:109], v[114:117]
	s_waitcnt vmcnt(2)
	ds_write_b128 v18, v[142:145] offset:49152
	v_mfma_f32_16x16x32_f16 v[40:43], v[118:121], v[110:113], v[40:43]
	ds_read_b128 v[118:121], v22 offset:36864
	v_mfma_f32_16x16x32_f16 v[70:73], v[122:125], v[106:109], v[70:73]
	ds_read_b128 v[106:109], v23
	v_mfma_f32_16x16x32_f16 v[48:51], v[122:125], v[110:113], v[48:51]
	ds_read_b128 v[110:113], v23 offset:2048
	s_waitcnt lgkmcnt(1)
	v_mfma_f32_16x16x32_f16 v[36:39], v[58:61], v[106:109], v[36:39]
	ds_read_b128 v[122:125], v22 offset:38912
	s_waitcnt lgkmcnt(1)
	v_mfma_f32_16x16x32_f16 v[66:69], v[58:61], v[110:113], v[66:69]
	s_waitcnt vmcnt(1)
	ds_write_b128 v19, v[154:157] offset:49152
	v_mfma_f32_16x16x32_f16 v[44:47], v[94:97], v[106:109], v[44:47]
	s_waitcnt vmcnt(0)
	ds_write_b128 v20, v[158:161] offset:49152
	v_mfma_f32_16x16x32_f16 v[78:81], v[94:97], v[110:113], v[78:81]
	v_mfma_f32_16x16x32_f16 v[82:85], v[118:121], v[106:109], v[82:85]
	v_mfma_f32_16x16x32_f16 v[86:89], v[118:121], v[110:113], v[86:89]
	s_waitcnt lgkmcnt(2)
	v_mfma_f32_16x16x32_f16 v[28:31], v[122:125], v[106:109], v[28:31]
	ds_read_b128 v[106:109], v23 offset:4096
	v_mfma_f32_16x16x32_f16 v[32:35], v[122:125], v[110:113], v[32:35]
	ds_read_b128 v[110:113], v23 offset:6144
	s_waitcnt lgkmcnt(1)
	v_mfma_f32_16x16x32_f16 v[98:101], v[58:61], v[106:109], v[98:101]
	s_waitcnt lgkmcnt(0)
	v_mfma_f32_16x16x32_f16 v[52:55], v[58:61], v[110:113], v[52:55]
	global_load_dwordx4 v[58:61], v[0:1], off offset:3072
	v_mfma_f32_16x16x32_f16 v[102:105], v[94:97], v[106:109], v[102:105]
	v_mfma_f32_16x16x32_f16 v[24:27], v[94:97], v[110:113], v[24:27]
	v_mfma_f32_16x16x32_f16 v[114:117], v[118:121], v[106:109], v[114:117]
	v_mfma_f32_16x16x32_f16 v[40:43], v[118:121], v[110:113], v[40:43]
	v_mfma_f32_16x16x32_f16 v[70:73], v[122:125], v[106:109], v[70:73]
	global_load_dwordx4 v[106:109], v[2:3], off offset:3072
	global_load_dwordx4 v[126:129], v[4:5], off offset:3072
	global_load_dwordx4 v[134:137], v[14:15], off offset:3072
	global_load_dwordx4 v[94:97], v[10:11], off offset:3072
	global_load_dwordx4 v[162:165], v[12:13], off offset:3072
	global_load_dwordx4 v[166:169], v[8:9], off offset:3072
	global_load_dwordx4 v[190:193], v[6:7], off offset:3072
	s_waitcnt lgkmcnt(0)
	s_barrier
	v_mfma_f32_16x16x32_f16 v[48:51], v[122:125], v[110:113], v[48:51]
	ds_read_b128 v[62:65], v16 offset:49152
	ds_read_b128 v[90:93], v21 offset:16384
	s_waitcnt lgkmcnt(0)
	v_mfma_f32_16x16x32_f16 v[36:39], v[62:65], v[90:93], v[36:39]
	ds_read_b128 v[74:77], v16 offset:51200
	ds_read_b128 v[110:113], v21 offset:18432
	s_waitcnt lgkmcnt(0)
	v_mfma_f32_16x16x32_f16 v[66:69], v[62:65], v[110:113], v[66:69]
	ds_read_b128 v[118:121], v16 offset:53248
	v_mfma_f32_16x16x32_f16 v[44:47], v[74:77], v[90:93], v[44:47]
	ds_read_b128 v[122:125], v16 offset:55296
	v_mfma_f32_16x16x32_f16 v[78:81], v[74:77], v[110:113], v[78:81]
	s_waitcnt vmcnt(7)
	ds_write_b128 v17, v[58:61]
	s_waitcnt lgkmcnt(2)
	v_mfma_f32_16x16x32_f16 v[82:85], v[118:121], v[90:93], v[82:85]
	s_waitcnt vmcnt(6)
	ds_write_b128 v18, v[106:109]
	v_mfma_f32_16x16x32_f16 v[86:89], v[118:121], v[110:113], v[86:89]
	s_waitcnt vmcnt(5)
	ds_write_b128 v19, v[126:129]
	s_waitcnt lgkmcnt(3)
	v_mfma_f32_16x16x32_f16 v[28:31], v[122:125], v[90:93], v[28:31]
	ds_read_b128 v[90:93], v21 offset:20480
	v_mfma_f32_16x16x32_f16 v[32:35], v[122:125], v[110:113], v[32:35]
	ds_read_b128 v[110:113], v21 offset:22528
	s_waitcnt lgkmcnt(1)
	v_mfma_f32_16x16x32_f16 v[98:101], v[62:65], v[90:93], v[98:101]
	s_waitcnt vmcnt(4)
	ds_write_b128 v20, v[134:137]
	s_waitcnt lgkmcnt(1)
	v_mfma_f32_16x16x32_f16 v[52:55], v[62:65], v[110:113], v[52:55]
	ds_read_b128 v[62:65], v22 offset:49152
	v_mfma_f32_16x16x32_f16 v[102:105], v[74:77], v[90:93], v[102:105]
	s_waitcnt vmcnt(3)
; #define GL_LOAD(s_, kt_) if (VAR != 1) { a##s_##0 = GL_A(0, kt_); a##s_##1 = GL_A(1, kt_); a##s_##2 = GL_A(2, kt_); a##s_##3 = GL_A(3, kt_); b##s_##0 = GL_B(0, kt_); b##s_##1 = GL_B(1, kt_); b##s_##2 = GL_B(2, kt_); b##s_##3 = GL_B(3, kt_); }
; #define LDS_STORE(s_, buf_) if (VAR != 2) { LDS_ST1(sA, 0, buf_, a##s_##0) LDS_ST1(sA, 1, buf_, a##s_##1) LDS_ST1(sA, 2, buf_, a##s_##2) LDS_ST1(sA, 3, buf_, a##s_##3) LDS_ST1(sB, 0, buf_, b##s_##0) LDS_ST1(sB, 1, buf_, b##s_##1) LDS_ST1(sB, 2, buf_, b##s_##2) LDS_ST1(sB, 3, buf_, b##s_##3) }
;     ...
;   GL_LOAD(0, 0)
;   GL_LOAD(1, 1)
;   LDS_STORE(0, 0)
;   if (VAR != 4) __syncthreads();
; #pragma unroll
;   for (int kt = 0; kt < nk; kt += 2) {
;     if (kt + 2 < nk) { GL_LOAD(0, kt + 2) }
;     MMA_TILE(0)
;     LDS_STORE(1, 1)
;     if (VAR != 4) __syncthreads();
;     if (kt + 3 < nk) { GL_LOAD(1, kt + 3) }
;     MMA_TILE(1)
;     if (kt + 2 < nk) { LDS_STORE(0, 0) }
;     if (VAR != 4) __syncthreads();
	ds_write_b128 v17, v[94:97] offset:32768
	v_mfma_f32_16x16x32_f16 v[24:27], v[74:77], v[110:113], v[24:27]
	ds_read_b128 v[74:77], v22 offset:51200
	v_mfma_f32_16x16x32_f16 v[114:117], v[118:121], v[90:93], v[114:117]
	s_waitcnt vmcnt(2)
	ds_write_b128 v18, v[162:165] offset:32768
	v_mfma_f32_16x16x32_f16 v[40:43], v[118:121], v[110:113], v[40:43]
	ds_read_b128 v[118:121], v22 offset:53248
	v_mfma_f32_16x16x32_f16 v[70:73], v[122:125], v[90:93], v[70:73]
	ds_read_b128 v[90:93], v23 offset:16384
	v_mfma_f32_16x16x32_f16 v[48:51], v[122:125], v[110:113], v[48:51]
	ds_read_b128 v[110:113], v23 offset:18432
	s_waitcnt lgkmcnt(1)
	v_mfma_f32_16x16x32_f16 v[36:39], v[62:65], v[90:93], v[36:39]
	ds_read_b128 v[122:125], v22 offset:55296
	s_waitcnt lgkmcnt(1)
	v_mfma_f32_16x16x32_f16 v[66:69], v[62:65], v[110:113], v[66:69]
	s_waitcnt vmcnt(1)
	ds_write_b128 v19, v[166:169] offset:32768
	v_mfma_f32_16x16x32_f16 v[44:47], v[74:77], v[90:93], v[44:47]
	s_waitcnt vmcnt(0)
	ds_write_b128 v20, v[190:193] offset:32768
	v_mfma_f32_16x16x32_f16 v[78:81], v[74:77], v[110:113], v[78:81]
	v_mfma_f32_16x16x32_f16 v[82:85], v[118:121], v[90:93], v[82:85]
	v_mfma_f32_16x16x32_f16 v[86:89], v[118:121], v[110:113], v[86:89]
	s_waitcnt lgkmcnt(2)
	v_mfma_f32_16x16x32_f16 v[28:31], v[122:125], v[90:93], v[28:31]
	ds_read_b128 v[90:93], v23 offset:20480
	v_mfma_f32_16x16x32_f16 v[32:35], v[122:125], v[110:113], v[32:35]
	ds_read_b128 v[110:113], v23 offset:22528
	s_waitcnt lgkmcnt(1)
	v_mfma_f32_16x16x32_f16 v[98:101], v[62:65], v[90:93], v[98:101]
	s_waitcnt lgkmcnt(0)
	v_mfma_f32_16x16x32_f16 v[52:55], v[62:65], v[110:113], v[52:55]
	global_load_dwordx4 v[62:65], v[0:1], off offset:3200
	v_mfma_f32_16x16x32_f16 v[102:105], v[74:77], v[90:93], v[102:105]
	v_mfma_f32_16x16x32_f16 v[24:27], v[74:77], v[110:113], v[24:27]
	v_mfma_f32_16x16x32_f16 v[114:117], v[118:121], v[90:93], v[114:117]
	v_mfma_f32_16x16x32_f16 v[40:43], v[118:121], v[110:113], v[40:43]
	v_mfma_f32_16x16x32_f16 v[70:73], v[122:125], v[90:93], v[70:73]
	global_load_dwordx4 v[90:93], v[2:3], off offset:3200
	global_load_dwordx4 v[130:133], v[4:5], off offset:3200
	global_load_dwordx4 v[138:141], v[14:15], off offset:3200
	global_load_dwordx4 v[74:77], v[10:11], off offset:3200
	global_load_dwordx4 v[142:145], v[12:13], off offset:3200
	global_load_dwordx4 v[154:157], v[8:9], off offset:3200
	global_load_dwordx4 v[158:161], v[6:7], off offset:3200
	s_waitcnt lgkmcnt(0)
	s_barrier
	v_mfma_f32_16x16x32_f16 v[48:51], v[122:125], v[110:113], v[48:51]
	ds_read_b128 v[58:61], v16 offset:32768
	ds_read_b128 v[106:109], v21
	s_waitcnt lgkmcnt(0)
	v_mfma_f32_16x16x32_f16 v[36:39], v[58:61], v[106:109], v[36:39]
	ds_read_b128 v[94:97], v16 offset:34816
	ds_read_b128 v[110:113], v21 offset:2048
	s_waitcnt lgkmcnt(0)
	v_mfma_f32_16x16x32_f16 v[66:69], v[58:61], v[110:113], v[66:69]
	ds_read_b128 v[118:121], v16 offset:36864
	v_mfma_f32_16x16x32_f16 v[44:47], v[94:97], v[106:109], v[44:47]
	ds_read_b128 v[122:125], v16 offset:38912
	v_mfma_f32_16x16x32_f16 v[78:81], v[94:97], v[110:113], v[78:81]
	s_waitcnt vmcnt(7)
	ds_write_b128 v17, v[62:65] offset:16384
	s_waitcnt lgkmcnt(2)
	v_mfma_f32_16x16x32_f16 v[82:85], v[118:121], v[106:109], v[82:85]
	s_waitcnt vmcnt(6)
	ds_write_b128 v18, v[90:93] offset:16384
	v_mfma_f32_16x16x32_f16 v[86:89], v[118:121], v[110:113], v[86:89]
	s_waitcnt vmcnt(5)
	ds_write_b128 v19, v[130:133] offset:16384
	s_waitcnt lgkmcnt(3)
	v_mfma_f32_16x16x32_f16 v[28:31], v[122:125], v[106:109], v[28:31]
	ds_read_b128 v[106:109], v21 offset:4096
	v_mfma_f32_16x16x32_f16 v[32:35], v[122:125], v[110:113], v[32:35]
	ds_read_b128 v[110:113], v21 offset:6144
	s_waitcnt lgkmcnt(1)
	v_mfma_f32_16x16x32_f16 v[98:101], v[58:61], v[106:109], v[98:101]
	s_waitcnt vmcnt(4)
	ds_write_b128 v20, v[138:141] offset:16384
	s_waitcnt lgkmcnt(1)
	v_mfma_f32_16x16x32_f16 v[52:55], v[58:61], v[110:113], v[52:55]
	ds_read_b128 v[58:61], v22 offset:32768
	v_mfma_f32_16x16x32_f16 v[102:105], v[94:97], v[106:109], v[102:105]
	s_waitcnt vmcnt(3)
	ds_write_b128 v17, v[74:77] offset:49152
	v_mfma_f32_16x16x32_f16 v[24:27], v[94:97], v[110:113], v[24:27]
	ds_read_b128 v[94:97], v22 offset:34816
	v_mfma_f32_16x16x32_f16 v[114:117], v[118:121], v[106:109], v[114:117]
	s_waitcnt vmcnt(2)
	ds_write_b128 v18, v[142:145] offset:49152
	v_mfma_f32_16x16x32_f16 v[40:43], v[118:121], v[110:113], v[40:43]
	ds_read_b128 v[118:121], v22 offset:36864
	v_mfma_f32_16x16x32_f16 v[70:73], v[122:125], v[106:109], v[70:73]
	ds_read_b128 v[106:109], v23
	v_mfma_f32_16x16x32_f16 v[48:51], v[122:125], v[110:113], v[48:51]
	ds_read_b128 v[110:113], v23 offset:2048
	s_waitcnt lgkmcnt(1)
	v_mfma_f32_16x16x32_f16 v[36:39], v[58:61], v[106:109], v[36:39]
	ds_read_b128 v[122:125], v22 offset:38912
	s_waitcnt lgkmcnt(1)
	v_mfma_f32_16x16x32_f16 v[66:69], v[58:61], v[110:113], v[66:69]
	s_waitcnt vmcnt(1)
	ds_write_b128 v19, v[154:157] offset:49152
	v_mfma_f32_16x16x32_f16 v[44:47], v[94:97], v[106:109], v[44:47]
	s_waitcnt vmcnt(0)
	ds_write_b128 v20, v[158:161] offset:49152
	v_mfma_f32_16x16x32_f16 v[78:81], v[94:97], v[110:113], v[78:81]
	v_mfma_f32_16x16x32_f16 v[82:85], v[118:121], v[106:109], v[82:85]
	v_mfma_f32_16x16x32_f16 v[86:89], v[118:121], v[110:113], v[86:89]
	s_waitcnt lgkmcnt(2)
	v_mfma_f32_16x16x32_f16 v[28:31], v[122:125], v[106:109], v[28:31]
	ds_read_b128 v[106:109], v23 offset:4096
	v_mfma_f32_16x16x32_f16 v[32:35], v[122:125], v[110:113], v[32:35]
	ds_read_b128 v[110:113], v23 offset:6144
	s_waitcnt lgkmcnt(1)
	v_mfma_f32_16x16x32_f16 v[98:101], v[58:61], v[106:109], v[98:101]
	s_waitcnt lgkmcnt(0)
	v_mfma_f32_16x16x32_f16 v[52:55], v[58:61], v[110:113], v[52:55]
	global_load_dwordx4 v[58:61], v[0:1], off offset:3328
	v_mfma_f32_16x16x32_f16 v[102:105], v[94:97], v[106:109], v[102:105]
	v_mfma_f32_16x16x32_f16 v[24:27], v[94:97], v[110:113], v[24:27]
	v_mfma_f32_16x16x32_f16 v[114:117], v[118:121], v[106:109], v[114:117]
	v_mfma_f32_16x16x32_f16 v[40:43], v[118:121], v[110:113], v[40:43]
	v_mfma_f32_16x16x32_f16 v[70:73], v[122:125], v[106:109], v[70:73]
	global_load_dwordx4 v[106:109], v[2:3], off offset:3328
	global_load_dwordx4 v[126:129], v[4:5], off offset:3328
	global_load_dwordx4 v[134:137], v[14:15], off offset:3328
	global_load_dwordx4 v[94:97], v[10:11], off offset:3328
	global_load_dwordx4 v[162:165], v[12:13], off offset:3328
	global_load_dwordx4 v[166:169], v[8:9], off offset:3328
	global_load_dwordx4 v[190:193], v[6:7], off offset:3328
	s_waitcnt lgkmcnt(0)
	s_barrier
; #define GL_LOAD(s_, kt_) if (VAR != 1) { a##s_##0 = GL_A(0, kt_); a##s_##1 = GL_A(1, kt_); a##s_##2 = GL_A(2, kt_); a##s_##3 = GL_A(3, kt_); b##s_##0 = GL_B(0, kt_); b##s_##1 = GL_B(1, kt_); b##s_##2 = GL_B(2, kt_); b##s_##3 = GL_B(3, kt_); }
; #define LDS_STORE(s_, buf_) if (VAR != 2) { LDS_ST1(sA, 0, buf_, a##s_##0) LDS_ST1(sA, 1, buf_, a##s_##1) LDS_ST1(sA, 2, buf_, a##s_##2) LDS_ST1(sA, 3, buf_, a##s_##3) LDS_ST1(sB, 0, buf_, b##s_##0) LDS_ST1(sB, 1, buf_, b##s_##1) LDS_ST1(sB, 2, buf_, b##s_##2) LDS_ST1(sB, 3, buf_, b##s_##3) }
;     ...
;   GL_LOAD(0, 0)
;   GL_LOAD(1, 1)
;   LDS_STORE(0, 0)
;   if (VAR != 4) __syncthreads();
; #pragma unroll
;   for (int kt = 0; kt < nk; kt += 2) {
;     if (kt + 2 < nk) { GL_LOAD(0, kt + 2) }
;     MMA_TILE(0)
;     LDS_STORE(1, 1)
;     if (VAR != 4) __syncthreads();
;     if (kt + 3 < nk) { GL_LOAD(1, kt + 3) }
;     MMA_TILE(1)
;     if (kt + 2 < nk) { LDS_STORE(0, 0) }
;     if (VAR != 4) __syncthreads();
	v_mfma_f32_16x16x32_f16 v[48:51], v[122:125], v[110:113], v[48:51]
	ds_read_b128 v[62:65], v16 offset:49152
	ds_read_b128 v[90:93], v21 offset:16384
	s_waitcnt lgkmcnt(0)
	v_mfma_f32_16x16x32_f16 v[36:39], v[62:65], v[90:93], v[36:39]
	ds_read_b128 v[74:77], v16 offset:51200
	ds_read_b128 v[110:113], v21 offset:18432
	s_waitcnt lgkmcnt(0)
	v_mfma_f32_16x16x32_f16 v[66:69], v[62:65], v[110:113], v[66:69]
	ds_read_b128 v[118:121], v16 offset:53248
	v_mfma_f32_16x16x32_f16 v[44:47], v[74:77], v[90:93], v[44:47]
	ds_read_b128 v[122:125], v16 offset:55296
	v_mfma_f32_16x16x32_f16 v[78:81], v[74:77], v[110:113], v[78:81]
	s_waitcnt vmcnt(7)
	ds_write_b128 v17, v[58:61]
	s_waitcnt lgkmcnt(2)
	v_mfma_f32_16x16x32_f16 v[82:85], v[118:121], v[90:93], v[82:85]
	s_waitcnt vmcnt(6)
	ds_write_b128 v18, v[106:109]
	v_mfma_f32_16x16x32_f16 v[86:89], v[118:121], v[110:113], v[86:89]
	s_waitcnt vmcnt(5)
	ds_write_b128 v19, v[126:129]
	s_waitcnt lgkmcnt(3)
	v_mfma_f32_16x16x32_f16 v[28:31], v[122:125], v[90:93], v[28:31]
	ds_read_b128 v[90:93], v21 offset:20480
	v_mfma_f32_16x16x32_f16 v[32:35], v[122:125], v[110:113], v[32:35]
	ds_read_b128 v[110:113], v21 offset:22528
	s_waitcnt lgkmcnt(1)
	v_mfma_f32_16x16x32_f16 v[98:101], v[62:65], v[90:93], v[98:101]
	s_waitcnt vmcnt(4)
	ds_write_b128 v20, v[134:137]
	s_waitcnt lgkmcnt(1)
	v_mfma_f32_16x16x32_f16 v[52:55], v[62:65], v[110:113], v[52:55]
	ds_read_b128 v[62:65], v22 offset:49152
	v_mfma_f32_16x16x32_f16 v[102:105], v[74:77], v[90:93], v[102:105]
	s_waitcnt vmcnt(3)
	ds_write_b128 v17, v[94:97] offset:32768
	v_mfma_f32_16x16x32_f16 v[24:27], v[74:77], v[110:113], v[24:27]
	ds_read_b128 v[74:77], v22 offset:51200
	v_mfma_f32_16x16x32_f16 v[114:117], v[118:121], v[90:93], v[114:117]
	s_waitcnt vmcnt(2)
	ds_write_b128 v18, v[162:165] offset:32768
	v_mfma_f32_16x16x32_f16 v[40:43], v[118:121], v[110:113], v[40:43]
	ds_read_b128 v[118:121], v22 offset:53248
	v_mfma_f32_16x16x32_f16 v[70:73], v[122:125], v[90:93], v[70:73]
	ds_read_b128 v[90:93], v23 offset:16384
	v_mfma_f32_16x16x32_f16 v[48:51], v[122:125], v[110:113], v[48:51]
	ds_read_b128 v[110:113], v23 offset:18432
	s_waitcnt lgkmcnt(1)
	v_mfma_f32_16x16x32_f16 v[36:39], v[62:65], v[90:93], v[36:39]
	ds_read_b128 v[122:125], v22 offset:55296
	s_waitcnt lgkmcnt(1)
	v_mfma_f32_16x16x32_f16 v[66:69], v[62:65], v[110:113], v[66:69]
	s_waitcnt vmcnt(1)
	ds_write_b128 v19, v[166:169] offset:32768
	v_mfma_f32_16x16x32_f16 v[44:47], v[74:77], v[90:93], v[44:47]
	s_waitcnt vmcnt(0)
	ds_write_b128 v20, v[190:193] offset:32768
	v_mfma_f32_16x16x32_f16 v[78:81], v[74:77], v[110:113], v[78:81]
	v_mfma_f32_16x16x32_f16 v[82:85], v[118:121], v[90:93], v[82:85]
	v_mfma_f32_16x16x32_f16 v[86:89], v[118:121], v[110:113], v[86:89]
	s_waitcnt lgkmcnt(2)
	v_mfma_f32_16x16x32_f16 v[28:31], v[122:125], v[90:93], v[28:31]
	ds_read_b128 v[90:93], v23 offset:20480
	v_mfma_f32_16x16x32_f16 v[32:35], v[122:125], v[110:113], v[32:35]
	ds_read_b128 v[110:113], v23 offset:22528
	s_waitcnt lgkmcnt(1)
	v_mfma_f32_16x16x32_f16 v[98:101], v[62:65], v[90:93], v[98:101]
	s_waitcnt lgkmcnt(0)
	v_mfma_f32_16x16x32_f16 v[52:55], v[62:65], v[110:113], v[52:55]
	global_load_dwordx4 v[62:65], v[0:1], off offset:3456
	v_mfma_f32_16x16x32_f16 v[102:105], v[74:77], v[90:93], v[102:105]
	v_mfma_f32_16x16x32_f16 v[24:27], v[74:77], v[110:113], v[24:27]
	v_mfma_f32_16x16x32_f16 v[114:117], v[118:121], v[90:93], v[114:117]
	v_mfma_f32_16x16x32_f16 v[40:43], v[118:121], v[110:113], v[40:43]
	v_mfma_f32_16x16x32_f16 v[70:73], v[122:125], v[90:93], v[70:73]
	global_load_dwordx4 v[90:93], v[2:3], off offset:3456
	global_load_dwordx4 v[130:133], v[4:5], off offset:3456
	global_load_dwordx4 v[138:141], v[14:15], off offset:3456
	global_load_dwordx4 v[74:77], v[10:11], off offset:3456
	global_load_dwordx4 v[142:145], v[12:13], off offset:3456
	global_load_dwordx4 v[154:157], v[8:9], off offset:3456
	global_load_dwordx4 v[158:161], v[6:7], off offset:3456
	s_waitcnt lgkmcnt(0)
	s_barrier
	v_mfma_f32_16x16x32_f16 v[48:51], v[122:125], v[110:113], v[48:51]
	ds_read_b128 v[58:61], v16 offset:32768
	ds_read_b128 v[106:109], v21
	s_waitcnt lgkmcnt(0)
	v_mfma_f32_16x16x32_f16 v[36:39], v[58:61], v[106:109], v[36:39]
	ds_read_b128 v[94:97], v16 offset:34816
	ds_read_b128 v[110:113], v21 offset:2048
	s_waitcnt lgkmcnt(0)
	v_mfma_f32_16x16x32_f16 v[66:69], v[58:61], v[110:113], v[66:69]
	ds_read_b128 v[118:121], v16 offset:36864
	v_mfma_f32_16x16x32_f16 v[44:47], v[94:97], v[106:109], v[44:47]
	ds_read_b128 v[122:125], v16 offset:38912
	v_mfma_f32_16x16x32_f16 v[78:81], v[94:97], v[110:113], v[78:81]
	s_waitcnt vmcnt(7)
	ds_write_b128 v17, v[62:65] offset:16384
	s_waitcnt lgkmcnt(2)
	v_mfma_f32_16x16x32_f16 v[82:85], v[118:121], v[106:109], v[82:85]
	s_waitcnt vmcnt(6)
	ds_write_b128 v18, v[90:93] offset:16384
	v_mfma_f32_16x16x32_f16 v[86:89], v[118:121], v[110:113], v[86:89]
	s_waitcnt vmcnt(5)
	ds_write_b128 v19, v[130:133] offset:16384
	s_waitcnt lgkmcnt(3)
	v_mfma_f32_16x16x32_f16 v[28:31], v[122:125], v[106:109], v[28:31]
	ds_read_b128 v[106:109], v21 offset:4096
	v_mfma_f32_16x16x32_f16 v[32:35], v[122:125], v[110:113], v[32:35]
	ds_read_b128 v[110:113], v21 offset:6144
	s_waitcnt lgkmcnt(1)
	v_mfma_f32_16x16x32_f16 v[98:101], v[58:61], v[106:109], v[98:101]
	s_waitcnt vmcnt(4)
	ds_write_b128 v20, v[138:141] offset:16384
	s_waitcnt lgkmcnt(1)
	v_mfma_f32_16x16x32_f16 v[52:55], v[58:61], v[110:113], v[52:55]
	ds_read_b128 v[58:61], v22 offset:32768
	v_mfma_f32_16x16x32_f16 v[102:105], v[94:97], v[106:109], v[102:105]
	s_waitcnt vmcnt(3)
; #define GL_LOAD(s_, kt_) if (VAR != 1) { a##s_##0 = GL_A(0, kt_); a##s_##1 = GL_A(1, kt_); a##s_##2 = GL_A(2, kt_); a##s_##3 = GL_A(3, kt_); b##s_##0 = GL_B(0, kt_); b##s_##1 = GL_B(1, kt_); b##s_##2 = GL_B(2, kt_); b##s_##3 = GL_B(3, kt_); }
; #define LDS_STORE(s_, buf_) if (VAR != 2) { LDS_ST1(sA, 0, buf_, a##s_##0) LDS_ST1(sA, 1, buf_, a##s_##1) LDS_ST1(sA, 2, buf_, a##s_##2) LDS_ST1(sA, 3, buf_, a##s_##3) LDS_ST1(sB, 0, buf_, b##s_##0) LDS_ST1(sB, 1, buf_, b##s_##1) LDS_ST1(sB, 2, buf_, b##s_##2) LDS_ST1(sB, 3, buf_, b##s_##3) }
;     ...
;   GL_LOAD(0, 0)
;   GL_LOAD(1, 1)
;   LDS_STORE(0, 0)
;   if (VAR != 4) __syncthreads();
; #pragma unroll
;   for (int kt = 0; kt < nk; kt += 2) {
;     if (kt + 2 < nk) { GL_LOAD(0, kt + 2) }
;     MMA_TILE(0)
;     LDS_STORE(1, 1)
;     if (VAR != 4) __syncthreads();
;     if (kt + 3 < nk) { GL_LOAD(1, kt + 3) }
;     MMA_TILE(1)
;     if (kt + 2 < nk) { LDS_STORE(0, 0) }
;     if (VAR != 4) __syncthreads();
	ds_write_b128 v17, v[74:77] offset:49152
	v_mfma_f32_16x16x32_f16 v[24:27], v[94:97], v[110:113], v[24:27]
	ds_read_b128 v[94:97], v22 offset:34816
	v_mfma_f32_16x16x32_f16 v[114:117], v[118:121], v[106:109], v[114:117]
	s_waitcnt vmcnt(2)
	ds_write_b128 v18, v[142:145] offset:49152
	v_mfma_f32_16x16x32_f16 v[40:43], v[118:121], v[110:113], v[40:43]
	ds_read_b128 v[118:121], v22 offset:36864
	v_mfma_f32_16x16x32_f16 v[70:73], v[122:125], v[106:109], v[70:73]
	ds_read_b128 v[106:109], v23
	v_mfma_f32_16x16x32_f16 v[48:51], v[122:125], v[110:113], v[48:51]
	ds_read_b128 v[110:113], v23 offset:2048
	s_waitcnt lgkmcnt(1)
	v_mfma_f32_16x16x32_f16 v[36:39], v[58:61], v[106:109], v[36:39]
	ds_read_b128 v[122:125], v22 offset:38912
	s_waitcnt lgkmcnt(1)
	v_mfma_f32_16x16x32_f16 v[66:69], v[58:61], v[110:113], v[66:69]
	s_waitcnt vmcnt(1)
	ds_write_b128 v19, v[154:157] offset:49152
	v_mfma_f32_16x16x32_f16 v[44:47], v[94:97], v[106:109], v[44:47]
	s_waitcnt vmcnt(0)
	ds_write_b128 v20, v[158:161] offset:49152
	v_mfma_f32_16x16x32_f16 v[78:81], v[94:97], v[110:113], v[78:81]
	v_mfma_f32_16x16x32_f16 v[82:85], v[118:121], v[106:109], v[82:85]
	v_mfma_f32_16x16x32_f16 v[86:89], v[118:121], v[110:113], v[86:89]
	s_waitcnt lgkmcnt(2)
	v_mfma_f32_16x16x32_f16 v[28:31], v[122:125], v[106:109], v[28:31]
	ds_read_b128 v[106:109], v23 offset:4096
	v_mfma_f32_16x16x32_f16 v[32:35], v[122:125], v[110:113], v[32:35]
	ds_read_b128 v[110:113], v23 offset:6144
	s_waitcnt lgkmcnt(1)
	v_mfma_f32_16x16x32_f16 v[98:101], v[58:61], v[106:109], v[98:101]
	s_waitcnt lgkmcnt(0)
	v_mfma_f32_16x16x32_f16 v[52:55], v[58:61], v[110:113], v[52:55]
	global_load_dwordx4 v[58:61], v[0:1], off offset:3584
	v_mfma_f32_16x16x32_f16 v[102:105], v[94:97], v[106:109], v[102:105]
	v_mfma_f32_16x16x32_f16 v[24:27], v[94:97], v[110:113], v[24:27]
	v_mfma_f32_16x16x32_f16 v[114:117], v[118:121], v[106:109], v[114:117]
	v_mfma_f32_16x16x32_f16 v[40:43], v[118:121], v[110:113], v[40:43]
	v_mfma_f32_16x16x32_f16 v[70:73], v[122:125], v[106:109], v[70:73]
	global_load_dwordx4 v[106:109], v[2:3], off offset:3584
	global_load_dwordx4 v[126:129], v[4:5], off offset:3584
	global_load_dwordx4 v[134:137], v[14:15], off offset:3584
	global_load_dwordx4 v[94:97], v[10:11], off offset:3584
	global_load_dwordx4 v[162:165], v[12:13], off offset:3584
	global_load_dwordx4 v[166:169], v[8:9], off offset:3584
	global_load_dwordx4 v[190:193], v[6:7], off offset:3584
	s_waitcnt lgkmcnt(0)
	s_barrier
	v_mfma_f32_16x16x32_f16 v[48:51], v[122:125], v[110:113], v[48:51]
	ds_read_b128 v[62:65], v16 offset:49152
	ds_read_b128 v[90:93], v21 offset:16384
	s_waitcnt lgkmcnt(0)
	v_mfma_f32_16x16x32_f16 v[36:39], v[62:65], v[90:93], v[36:39]
	ds_read_b128 v[74:77], v16 offset:51200
	ds_read_b128 v[110:113], v21 offset:18432
	s_waitcnt lgkmcnt(0)
	v_mfma_f32_16x16x32_f16 v[66:69], v[62:65], v[110:113], v[66:69]
	ds_read_b128 v[118:121], v16 offset:53248
	v_mfma_f32_16x16x32_f16 v[44:47], v[74:77], v[90:93], v[44:47]
	ds_read_b128 v[122:125], v16 offset:55296
	v_mfma_f32_16x16x32_f16 v[78:81], v[74:77], v[110:113], v[78:81]
	s_waitcnt vmcnt(7)
	ds_write_b128 v17, v[58:61]
	s_waitcnt lgkmcnt(2)
	v_mfma_f32_16x16x32_f16 v[82:85], v[118:121], v[90:93], v[82:85]
	s_waitcnt vmcnt(6)
	ds_write_b128 v18, v[106:109]
	v_mfma_f32_16x16x32_f16 v[86:89], v[118:121], v[110:113], v[86:89]
	s_waitcnt vmcnt(5)
	ds_write_b128 v19, v[126:129]
	s_waitcnt lgkmcnt(3)
	v_mfma_f32_16x16x32_f16 v[28:31], v[122:125], v[90:93], v[28:31]
	ds_read_b128 v[90:93], v21 offset:20480
	v_mfma_f32_16x16x32_f16 v[32:35], v[122:125], v[110:113], v[32:35]
	ds_read_b128 v[110:113], v21 offset:22528
	s_waitcnt lgkmcnt(1)
	v_mfma_f32_16x16x32_f16 v[98:101], v[62:65], v[90:93], v[98:101]
	s_waitcnt vmcnt(4)
	ds_write_b128 v20, v[134:137]
	s_waitcnt lgkmcnt(1)
	v_mfma_f32_16x16x32_f16 v[52:55], v[62:65], v[110:113], v[52:55]
	ds_read_b128 v[62:65], v22 offset:49152
	v_mfma_f32_16x16x32_f16 v[102:105], v[74:77], v[90:93], v[102:105]
	s_waitcnt vmcnt(3)
	ds_write_b128 v17, v[94:97] offset:32768
	v_mfma_f32_16x16x32_f16 v[24:27], v[74:77], v[110:113], v[24:27]
	ds_read_b128 v[74:77], v22 offset:51200
	v_mfma_f32_16x16x32_f16 v[114:117], v[118:121], v[90:93], v[114:117]
	s_waitcnt vmcnt(2)
	ds_write_b128 v18, v[162:165] offset:32768
	v_mfma_f32_16x16x32_f16 v[40:43], v[118:121], v[110:113], v[40:43]
	ds_read_b128 v[118:121], v22 offset:53248
	v_mfma_f32_16x16x32_f16 v[70:73], v[122:125], v[90:93], v[70:73]
	ds_read_b128 v[90:93], v23 offset:16384
	v_mfma_f32_16x16x32_f16 v[48:51], v[122:125], v[110:113], v[48:51]
	ds_read_b128 v[110:113], v23 offset:18432
	s_waitcnt lgkmcnt(1)
	v_mfma_f32_16x16x32_f16 v[36:39], v[62:65], v[90:93], v[36:39]
	ds_read_b128 v[122:125], v22 offset:55296
	s_waitcnt lgkmcnt(1)
	v_mfma_f32_16x16x32_f16 v[66:69], v[62:65], v[110:113], v[66:69]
	s_waitcnt vmcnt(1)
	ds_write_b128 v19, v[166:169] offset:32768
	v_mfma_f32_16x16x32_f16 v[44:47], v[74:77], v[90:93], v[44:47]
	s_waitcnt vmcnt(0)
	ds_write_b128 v20, v[190:193] offset:32768
	v_mfma_f32_16x16x32_f16 v[78:81], v[74:77], v[110:113], v[78:81]
	v_mfma_f32_16x16x32_f16 v[82:85], v[118:121], v[90:93], v[82:85]
	v_mfma_f32_16x16x32_f16 v[86:89], v[118:121], v[110:113], v[86:89]
	s_waitcnt lgkmcnt(2)
	v_mfma_f32_16x16x32_f16 v[28:31], v[122:125], v[90:93], v[28:31]
	ds_read_b128 v[90:93], v23 offset:20480
	v_mfma_f32_16x16x32_f16 v[32:35], v[122:125], v[110:113], v[32:35]
	ds_read_b128 v[110:113], v23 offset:22528
	s_waitcnt lgkmcnt(1)
	v_mfma_f32_16x16x32_f16 v[98:101], v[62:65], v[90:93], v[98:101]
	s_waitcnt lgkmcnt(0)
	v_mfma_f32_16x16x32_f16 v[52:55], v[62:65], v[110:113], v[52:55]
	global_load_dwordx4 v[62:65], v[0:1], off offset:3712
	v_mfma_f32_16x16x32_f16 v[102:105], v[74:77], v[90:93], v[102:105]
	v_mfma_f32_16x16x32_f16 v[24:27], v[74:77], v[110:113], v[24:27]
	v_mfma_f32_16x16x32_f16 v[114:117], v[118:121], v[90:93], v[114:117]
	v_mfma_f32_16x16x32_f16 v[40:43], v[118:121], v[110:113], v[40:43]
	v_mfma_f32_16x16x32_f16 v[70:73], v[122:125], v[90:93], v[70:73]
	global_load_dwordx4 v[90:93], v[2:3], off offset:3712
	global_load_dwordx4 v[130:133], v[4:5], off offset:3712
	global_load_dwordx4 v[138:141], v[14:15], off offset:3712
	global_load_dwordx4 v[74:77], v[10:11], off offset:3712
	global_load_dwordx4 v[142:145], v[12:13], off offset:3712
	global_load_dwordx4 v[154:157], v[8:9], off offset:3712
	global_load_dwordx4 v[158:161], v[6:7], off offset:3712
	s_waitcnt lgkmcnt(0)
	s_barrier
; #define GL_LOAD(s_, kt_) if (VAR != 1) { a##s_##0 = GL_A(0, kt_); a##s_##1 = GL_A(1, kt_); a##s_##2 = GL_A(2, kt_); a##s_##3 = GL_A(3, kt_); b##s_##0 = GL_B(0, kt_); b##s_##1 = GL_B(1, kt_); b##s_##2 = GL_B(2, kt_); b##s_##3 = GL_B(3, kt_); }
; #define LDS_STORE(s_, buf_) if (VAR != 2) { LDS_ST1(sA, 0, buf_, a##s_##0) LDS_ST1(sA, 1, buf_, a##s_##1) LDS_ST1(sA, 2, buf_, a##s_##2) LDS_ST1(sA, 3, buf_, a##s_##3) LDS_ST1(sB, 0, buf_, b##s_##0) LDS_ST1(sB, 1, buf_, b##s_##1) LDS_ST1(sB, 2, buf_, b##s_##2) LDS_ST1(sB, 3, buf_, b##s_##3) }
;     ...
;   GL_LOAD(0, 0)
;   GL_LOAD(1, 1)
;   LDS_STORE(0, 0)
;   if (VAR != 4) __syncthreads();
; #pragma unroll
;   for (int kt = 0; kt < nk; kt += 2) {
;     if (kt + 2 < nk) { GL_LOAD(0, kt + 2) }
;     MMA_TILE(0)
;     LDS_STORE(1, 1)
;     if (VAR != 4) __syncthreads();
;     if (kt + 3 < nk) { GL_LOAD(1, kt + 3) }
;     MMA_TILE(1)
;     if (kt + 2 < nk) { LDS_STORE(0, 0) }
;     if (VAR != 4) __syncthreads();
	v_mfma_f32_16x16x32_f16 v[48:51], v[122:125], v[110:113], v[48:51]
	ds_read_b128 v[58:61], v16 offset:32768
	ds_read_b128 v[106:109], v21
	s_waitcnt lgkmcnt(0)
	v_mfma_f32_16x16x32_f16 v[36:39], v[58:61], v[106:109], v[36:39]
	ds_read_b128 v[94:97], v16 offset:34816
	ds_read_b128 v[110:113], v21 offset:2048
	s_waitcnt lgkmcnt(0)
	v_mfma_f32_16x16x32_f16 v[66:69], v[58:61], v[110:113], v[66:69]
	ds_read_b128 v[118:121], v16 offset:36864
	v_mfma_f32_16x16x32_f16 v[44:47], v[94:97], v[106:109], v[44:47]
	ds_read_b128 v[122:125], v16 offset:38912
	v_mfma_f32_16x16x32_f16 v[78:81], v[94:97], v[110:113], v[78:81]
	s_waitcnt vmcnt(7)
	ds_write_b128 v17, v[62:65] offset:16384
	s_waitcnt lgkmcnt(2)
	v_mfma_f32_16x16x32_f16 v[82:85], v[118:121], v[106:109], v[82:85]
	s_waitcnt vmcnt(6)
	ds_write_b128 v18, v[90:93] offset:16384
	v_mfma_f32_16x16x32_f16 v[86:89], v[118:121], v[110:113], v[86:89]
	s_waitcnt vmcnt(5)
	ds_write_b128 v19, v[130:133] offset:16384
	s_waitcnt lgkmcnt(3)
	v_mfma_f32_16x16x32_f16 v[28:31], v[122:125], v[106:109], v[28:31]
	ds_read_b128 v[106:109], v21 offset:4096
	v_mfma_f32_16x16x32_f16 v[32:35], v[122:125], v[110:113], v[32:35]
	ds_read_b128 v[110:113], v21 offset:6144
	s_waitcnt lgkmcnt(1)
	v_mfma_f32_16x16x32_f16 v[98:101], v[58:61], v[106:109], v[98:101]
	s_waitcnt vmcnt(4)
	ds_write_b128 v20, v[138:141] offset:16384
	s_waitcnt lgkmcnt(1)
	v_mfma_f32_16x16x32_f16 v[52:55], v[58:61], v[110:113], v[52:55]
	ds_read_b128 v[58:61], v22 offset:32768
	v_mfma_f32_16x16x32_f16 v[102:105], v[94:97], v[106:109], v[102:105]
	s_waitcnt vmcnt(3)
	ds_write_b128 v17, v[74:77] offset:49152
	v_mfma_f32_16x16x32_f16 v[24:27], v[94:97], v[110:113], v[24:27]
	ds_read_b128 v[94:97], v22 offset:34816
	v_mfma_f32_16x16x32_f16 v[114:117], v[118:121], v[106:109], v[114:117]
	s_waitcnt vmcnt(2)
	ds_write_b128 v18, v[142:145] offset:49152
	v_mfma_f32_16x16x32_f16 v[40:43], v[118:121], v[110:113], v[40:43]
	ds_read_b128 v[118:121], v22 offset:36864
	v_mfma_f32_16x16x32_f16 v[70:73], v[122:125], v[106:109], v[70:73]
	ds_read_b128 v[106:109], v23
	v_mfma_f32_16x16x32_f16 v[48:51], v[122:125], v[110:113], v[48:51]
	ds_read_b128 v[110:113], v23 offset:2048
	s_waitcnt lgkmcnt(1)
	v_mfma_f32_16x16x32_f16 v[36:39], v[58:61], v[106:109], v[36:39]
	ds_read_b128 v[122:125], v22 offset:38912
	s_waitcnt lgkmcnt(1)
	v_mfma_f32_16x16x32_f16 v[66:69], v[58:61], v[110:113], v[66:69]
	s_waitcnt vmcnt(1)
	ds_write_b128 v19, v[154:157] offset:49152
	v_mfma_f32_16x16x32_f16 v[44:47], v[94:97], v[106:109], v[44:47]
	s_waitcnt vmcnt(0)
	ds_write_b128 v20, v[158:161] offset:49152
	v_mfma_f32_16x16x32_f16 v[78:81], v[94:97], v[110:113], v[78:81]
	v_mfma_f32_16x16x32_f16 v[82:85], v[118:121], v[106:109], v[82:85]
	v_mfma_f32_16x16x32_f16 v[86:89], v[118:121], v[110:113], v[86:89]
	s_waitcnt lgkmcnt(2)
	v_mfma_f32_16x16x32_f16 v[28:31], v[122:125], v[106:109], v[28:31]
	ds_read_b128 v[106:109], v23 offset:4096
	v_mfma_f32_16x16x32_f16 v[32:35], v[122:125], v[110:113], v[32:35]
	ds_read_b128 v[110:113], v23 offset:6144
	s_waitcnt lgkmcnt(1)
	v_mfma_f32_16x16x32_f16 v[98:101], v[58:61], v[106:109], v[98:101]
	s_waitcnt lgkmcnt(0)
	v_mfma_f32_16x16x32_f16 v[52:55], v[58:61], v[110:113], v[52:55]
	global_load_dwordx4 v[58:61], v[0:1], off offset:3840
	v_mfma_f32_16x16x32_f16 v[102:105], v[94:97], v[106:109], v[102:105]
	v_mfma_f32_16x16x32_f16 v[24:27], v[94:97], v[110:113], v[24:27]
	v_mfma_f32_16x16x32_f16 v[114:117], v[118:121], v[106:109], v[114:117]
	v_mfma_f32_16x16x32_f16 v[40:43], v[118:121], v[110:113], v[40:43]
	v_mfma_f32_16x16x32_f16 v[70:73], v[122:125], v[106:109], v[70:73]
	global_load_dwordx4 v[106:109], v[2:3], off offset:3840
	global_load_dwordx4 v[126:129], v[4:5], off offset:3840
	global_load_dwordx4 v[134:137], v[14:15], off offset:3840
	global_load_dwordx4 v[94:97], v[10:11], off offset:3840
	global_load_dwordx4 v[162:165], v[12:13], off offset:3840
	global_load_dwordx4 v[166:169], v[8:9], off offset:3840
	global_load_dwordx4 v[190:193], v[6:7], off offset:3840
	s_waitcnt lgkmcnt(0)
	s_barrier
	v_mfma_f32_16x16x32_f16 v[48:51], v[122:125], v[110:113], v[48:51]
	ds_read_b128 v[62:65], v16 offset:49152
	ds_read_b128 v[90:93], v21 offset:16384
	s_waitcnt lgkmcnt(0)
	v_mfma_f32_16x16x32_f16 v[36:39], v[62:65], v[90:93], v[36:39]
	ds_read_b128 v[74:77], v16 offset:51200
	ds_read_b128 v[110:113], v21 offset:18432
	s_waitcnt lgkmcnt(0)
	v_mfma_f32_16x16x32_f16 v[66:69], v[62:65], v[110:113], v[66:69]
	ds_read_b128 v[118:121], v16 offset:53248
	v_mfma_f32_16x16x32_f16 v[44:47], v[74:77], v[90:93], v[44:47]
	ds_read_b128 v[122:125], v16 offset:55296
	v_mfma_f32_16x16x32_f16 v[78:81], v[74:77], v[110:113], v[78:81]
	s_waitcnt vmcnt(7)
	ds_write_b128 v17, v[58:61]
	s_waitcnt lgkmcnt(2)
	v_mfma_f32_16x16x32_f16 v[82:85], v[118:121], v[90:93], v[82:85]
	s_waitcnt vmcnt(6)
	ds_write_b128 v18, v[106:109]
	v_mfma_f32_16x16x32_f16 v[86:89], v[118:121], v[110:113], v[86:89]
	s_waitcnt vmcnt(5)
	ds_write_b128 v19, v[126:129]
	s_waitcnt lgkmcnt(3)
	v_mfma_f32_16x16x32_f16 v[28:31], v[122:125], v[90:93], v[28:31]
	ds_read_b128 v[90:93], v21 offset:20480
	v_mfma_f32_16x16x32_f16 v[32:35], v[122:125], v[110:113], v[32:35]
	ds_read_b128 v[110:113], v21 offset:22528
	s_waitcnt lgkmcnt(1)
	v_mfma_f32_16x16x32_f16 v[98:101], v[62:65], v[90:93], v[98:101]
	s_waitcnt vmcnt(4)
	ds_write_b128 v20, v[134:137]
	s_waitcnt lgkmcnt(1)
	v_mfma_f32_16x16x32_f16 v[52:55], v[62:65], v[110:113], v[52:55]
	ds_read_b128 v[62:65], v22 offset:49152
	v_mfma_f32_16x16x32_f16 v[102:105], v[74:77], v[90:93], v[102:105]
	s_waitcnt vmcnt(3)
; #define GL_LOAD(s_, kt_) if (VAR != 1) { a##s_##0 = GL_A(0, kt_); a##s_##1 = GL_A(1, kt_); a##s_##2 = GL_A(2, kt_); a##s_##3 = GL_A(3, kt_); b##s_##0 = GL_B(0, kt_); b##s_##1 = GL_B(1, kt_); b##s_##2 = GL_B(2, kt_); b##s_##3 = GL_B(3, kt_); }
; #define LDS_STORE(s_, buf_) if (VAR != 2) { LDS_ST1(sA, 0, buf_, a##s_##0) LDS_ST1(sA, 1, buf_, a##s_##1) LDS_ST1(sA, 2, buf_, a##s_##2) LDS_ST1(sA, 3, buf_, a##s_##3) LDS_ST1(sB, 0, buf_, b##s_##0) LDS_ST1(sB, 1, buf_, b##s_##1) LDS_ST1(sB, 2, buf_, b##s_##2) LDS_ST1(sB, 3, buf_, b##s_##3) }
;     ...
;   for (int kt = 0; kt < nk; kt += 2) {
;     if (kt + 2 < nk) { GL_LOAD(0, kt + 2) }
;     MMA_TILE(0)
;     LDS_STORE(1, 1)
;     if (VAR != 4) __syncthreads();
;     if (kt + 3 < nk) { GL_LOAD(1, kt + 3) }
;     MMA_TILE(1)
;     if (kt + 2 < nk) { LDS_STORE(0, 0) }
;     if (VAR != 4) __syncthreads();
	ds_write_b128 v17, v[94:97] offset:32768
	v_mfma_f32_16x16x32_f16 v[24:27], v[74:77], v[110:113], v[24:27]
	ds_read_b128 v[74:77], v22 offset:51200
	v_mfma_f32_16x16x32_f16 v[114:117], v[118:121], v[90:93], v[114:117]
	s_waitcnt vmcnt(2)
	ds_write_b128 v18, v[162:165] offset:32768
	v_mfma_f32_16x16x32_f16 v[40:43], v[118:121], v[110:113], v[40:43]
	ds_read_b128 v[118:121], v22 offset:53248
	v_mfma_f32_16x16x32_f16 v[70:73], v[122:125], v[90:93], v[70:73]
	ds_read_b128 v[90:93], v23 offset:16384
	v_mfma_f32_16x16x32_f16 v[48:51], v[122:125], v[110:113], v[48:51]
	ds_read_b128 v[110:113], v23 offset:18432
	s_waitcnt lgkmcnt(1)
	v_mfma_f32_16x16x32_f16 v[36:39], v[62:65], v[90:93], v[36:39]
	ds_read_b128 v[122:125], v22 offset:55296
	s_waitcnt lgkmcnt(1)
	v_mfma_f32_16x16x32_f16 v[66:69], v[62:65], v[110:113], v[66:69]
	s_waitcnt vmcnt(1)
	ds_write_b128 v19, v[166:169] offset:32768
	v_mfma_f32_16x16x32_f16 v[44:47], v[74:77], v[90:93], v[44:47]
	s_waitcnt vmcnt(0)
	ds_write_b128 v20, v[190:193] offset:32768
	v_mfma_f32_16x16x32_f16 v[78:81], v[74:77], v[110:113], v[78:81]
	v_mfma_f32_16x16x32_f16 v[82:85], v[118:121], v[90:93], v[82:85]
	v_mfma_f32_16x16x32_f16 v[86:89], v[118:121], v[110:113], v[86:89]
	s_waitcnt lgkmcnt(2)
	v_mfma_f32_16x16x32_f16 v[28:31], v[122:125], v[90:93], v[28:31]
	ds_read_b128 v[90:93], v23 offset:20480
	v_mfma_f32_16x16x32_f16 v[32:35], v[122:125], v[110:113], v[32:35]
	ds_read_b128 v[110:113], v23 offset:22528
	s_waitcnt lgkmcnt(1)
	v_mfma_f32_16x16x32_f16 v[98:101], v[62:65], v[90:93], v[98:101]
	s_waitcnt lgkmcnt(0)
	v_mfma_f32_16x16x32_f16 v[52:55], v[62:65], v[110:113], v[52:55]
	global_load_dwordx4 v[62:65], v[0:1], off offset:3968
	global_load_dwordx4 v[0:3], v[2:3], off offset:3968
	v_mfma_f32_16x16x32_f16 v[102:105], v[74:77], v[90:93], v[102:105]
	v_mfma_f32_16x16x32_f16 v[24:27], v[74:77], v[110:113], v[24:27]
	v_mfma_f32_16x16x32_f16 v[114:117], v[118:121], v[90:93], v[114:117]
	v_mfma_f32_16x16x32_f16 v[40:43], v[118:121], v[110:113], v[40:43]
	v_mfma_f32_16x16x32_f16 v[70:73], v[122:125], v[90:93], v[70:73]
	global_load_dwordx4 v[90:93], v[4:5], off offset:3968
	global_load_dwordx4 v[130:133], v[14:15], off offset:3968
	global_load_dwordx4 v[74:77], v[10:11], off offset:3968
	global_load_dwordx4 v[10:13], v[12:13], off offset:3968
	global_load_dwordx4 v[138:141], v[8:9], off offset:3968
	global_load_dwordx4 v[4:7], v[6:7], off offset:3968
	s_waitcnt lgkmcnt(0)
	s_barrier
	ds_read_b128 v[58:61], v16 offset:32768
	v_mfma_f32_16x16x32_f16 v[48:51], v[122:125], v[110:113], v[48:51]
	ds_read_b128 v[94:97], v16 offset:34816
	ds_read_b128 v[106:109], v21
	ds_read_b128 v[110:113], v21 offset:2048
	ds_read_b128 v[118:121], v16 offset:36864
	ds_read_b128 v[122:125], v16 offset:38912
	s_waitcnt lgkmcnt(3)
	v_mfma_f32_16x16x32_f16 v[36:39], v[58:61], v[106:109], v[36:39]
	v_mfma_f32_16x16x32_f16 v[44:47], v[94:97], v[106:109], v[44:47]
	s_waitcnt lgkmcnt(1)
	v_mfma_f32_16x16x32_f16 v[82:85], v[118:121], v[106:109], v[82:85]
	s_waitcnt lgkmcnt(0)
	v_mfma_f32_16x16x32_f16 v[28:31], v[122:125], v[106:109], v[28:31]
	v_mfma_f32_16x16x32_f16 v[66:69], v[58:61], v[110:113], v[66:69]
	v_mfma_f32_16x16x32_f16 v[78:81], v[94:97], v[110:113], v[78:81]
	v_mfma_f32_16x16x32_f16 v[86:89], v[118:121], v[110:113], v[86:89]
	v_mfma_f32_16x16x32_f16 v[32:35], v[122:125], v[110:113], v[32:35]
	ds_read_b128 v[106:109], v21 offset:4096
	ds_read_b128 v[110:113], v21 offset:6144
	s_waitcnt lgkmcnt(1)
	v_mfma_f32_16x16x32_f16 v[98:101], v[58:61], v[106:109], v[98:101]
	v_mfma_f32_16x16x32_f16 v[102:105], v[94:97], v[106:109], v[102:105]
	v_mfma_f32_16x16x32_f16 v[114:117], v[118:121], v[106:109], v[114:117]
	v_mfma_f32_16x16x32_f16 v[70:73], v[122:125], v[106:109], v[70:73]
	s_waitcnt lgkmcnt(0)
	v_mfma_f32_16x16x32_f16 v[52:55], v[58:61], v[110:113], v[52:55]
	ds_read_b128 v[58:61], v22 offset:32768
	v_mfma_f32_16x16x32_f16 v[24:27], v[94:97], v[110:113], v[24:27]
	v_mfma_f32_16x16x32_f16 v[40:43], v[118:121], v[110:113], v[40:43]
	v_mfma_f32_16x16x32_f16 v[48:51], v[122:125], v[110:113], v[48:51]
	ds_read_b128 v[94:97], v22 offset:34816
	ds_read_b128 v[106:109], v23
	ds_read_b128 v[110:113], v23 offset:2048
	ds_read_b128 v[118:121], v22 offset:36864
	ds_read_b128 v[122:125], v22 offset:38912
	s_waitcnt lgkmcnt(3)
	v_mfma_f32_16x16x32_f16 v[36:39], v[58:61], v[106:109], v[36:39]
	v_mfma_f32_16x16x32_f16 v[44:47], v[94:97], v[106:109], v[44:47]
	s_waitcnt lgkmcnt(1)
	v_mfma_f32_16x16x32_f16 v[82:85], v[118:121], v[106:109], v[82:85]
	s_waitcnt lgkmcnt(0)
	v_mfma_f32_16x16x32_f16 v[28:31], v[122:125], v[106:109], v[28:31]
	v_mfma_f32_16x16x32_f16 v[66:69], v[58:61], v[110:113], v[66:69]
	v_mfma_f32_16x16x32_f16 v[78:81], v[94:97], v[110:113], v[78:81]
	v_mfma_f32_16x16x32_f16 v[86:89], v[118:121], v[110:113], v[86:89]
	v_mfma_f32_16x16x32_f16 v[32:35], v[122:125], v[110:113], v[32:35]
	ds_read_b128 v[106:109], v23 offset:4096
	ds_read_b128 v[110:113], v23 offset:6144
	s_waitcnt vmcnt(7)
	ds_write_b128 v17, v[62:65] offset:16384
	s_waitcnt vmcnt(6)
	ds_write_b128 v18, v[0:3] offset:16384
	s_waitcnt vmcnt(5)
	ds_write_b128 v19, v[90:93] offset:16384
	s_waitcnt vmcnt(4)
	ds_write_b128 v20, v[130:133] offset:16384
	s_waitcnt lgkmcnt(5)
	v_mfma_f32_16x16x32_f16 v[98:101], v[58:61], v[106:109], v[98:101]
	s_waitcnt vmcnt(3)
	ds_write_b128 v17, v[74:77] offset:49152
	s_waitcnt vmcnt(2)
	ds_write_b128 v18, v[10:13] offset:49152
	s_waitcnt vmcnt(1)
	ds_write_b128 v19, v[138:141] offset:49152
	s_waitcnt vmcnt(0)
	ds_write_b128 v20, v[4:7] offset:49152
	s_waitcnt lgkmcnt(0)
	s_barrier
; #define GL_LOAD(s_, kt_) if (VAR != 1) { a##s_##0 = GL_A(0, kt_); a##s_##1 = GL_A(1, kt_); a##s_##2 = GL_A(2, kt_); a##s_##3 = GL_A(3, kt_); b##s_##0 = GL_B(0, kt_); b##s_##1 = GL_B(1, kt_); b##s_##2 = GL_B(2, kt_); b##s_##3 = GL_B(3, kt_); }
; #define LDS_STORE(s_, buf_) if (VAR != 2) { LDS_ST1(sA, 0, buf_, a##s_##0) LDS_ST1(sA, 1, buf_, a##s_##1) LDS_ST1(sA, 2, buf_, a##s_##2) LDS_ST1(sA, 3, buf_, a##s_##3) LDS_ST1(sB, 0, buf_, b##s_##0) LDS_ST1(sB, 1, buf_, b##s_##1) LDS_ST1(sB, 2, buf_, b##s_##2) LDS_ST1(sB, 3, buf_, b##s_##3) }
;     ...
;   GL_LOAD(0, 0)
;   GL_LOAD(1, 1)
;   LDS_STORE(0, 0)
;   if (VAR != 4) __syncthreads();
; #pragma unroll
;   for (int kt = 0; kt < nk; kt += 2) {
;     if (kt + 2 < nk) { GL_LOAD(0, kt + 2) }
;     MMA_TILE(0)
;     LDS_STORE(1, 1)
;     if (VAR != 4) __syncthreads();
;     if (kt + 3 < nk) { GL_LOAD(1, kt + 3) }
;     MMA_TILE(1)
;     if (kt + 2 < nk) { LDS_STORE(0, 0) }
;     if (VAR != 4) __syncthreads();
	v_mfma_f32_16x16x32_f16 v[52:55], v[58:61], v[110:113], v[52:55]
	ds_read_b128 v[4:7], v16 offset:49152
	v_add_u32_e32 v130, s4, v57
	v_mfma_f32_16x16x32_f16 v[0:3], v[118:121], v[110:113], v[40:43]
	v_readlane_b32 s4, v254, 45
	v_readlane_b32 s5, v254, 46
	v_mfma_f32_16x16x32_f16 v[8:11], v[122:125], v[110:113], v[48:51]
	ds_read_b128 v[12:15], v16 offset:51200
	ds_read_b128 v[40:43], v21 offset:16384
	s_nop 0
	ds_read_b128 v[48:51], v21 offset:18432
	ds_read_b128 v[58:61], v16 offset:53248
	ds_read_b128 v[16:19], v16 offset:55296
	v_mfma_f32_16x16x32_f16 v[102:105], v[94:97], v[106:109], v[102:105]
	v_mfma_f32_16x16x32_f16 v[114:117], v[118:121], v[106:109], v[114:117]
	v_mfma_f32_16x16x32_f16 v[70:73], v[122:125], v[106:109], v[70:73]
	v_mfma_f32_16x16x32_f16 v[24:27], v[94:97], v[110:113], v[24:27]
	s_waitcnt lgkmcnt(3)
	v_mfma_f32_16x16x32_f16 v[36:39], v[4:7], v[40:43], v[36:39]
	v_mfma_f32_16x16x32_f16 v[44:47], v[12:15], v[40:43], v[44:47]
	s_waitcnt lgkmcnt(1)
	v_mfma_f32_16x16x32_f16 v[62:65], v[58:61], v[40:43], v[82:85]
	s_waitcnt lgkmcnt(0)
	v_mfma_f32_16x16x32_f16 v[28:31], v[16:19], v[40:43], v[28:31]
	ds_read_b128 v[40:43], v21 offset:20480
	ds_read_b128 v[74:77], v21 offset:22528
	ds_read_b128 v[82:85], v23 offset:16384
	ds_read_b128 v[90:93], v23 offset:18432
	ds_read_b128 v[94:97], v22 offset:49152
	ds_read_b128 v[106:109], v22 offset:51200
	ds_read_b128 v[110:113], v23 offset:20480
	ds_read_b128 v[118:121], v23 offset:22528
	ds_read_b128 v[122:125], v22 offset:53248
	ds_read_b128 v[126:129], v22 offset:55296
	v_mfma_f32_16x16x32_f16 v[66:69], v[4:7], v[48:51], v[66:69]
	s_waitcnt lgkmcnt(0)
	s_barrier
; DI int TIDX() { int t = threadIdx.x; asm volatile("" : "+v"(t)); return t; }
; DI unsigned pack2(float lo, float hi) { f2_t v = {lo, hi}; h2_t b = __builtin_convertvector(v, h2_t); return __builtin_bit_cast(unsigned, b); }
; DI void epi_residual(const f32x4 (&v)[4][4], int row0, int col0, const float* xsrc, float* x, bf16_t* xb, float* ssq_out, bool write_xb, bool write_ssq) {
;   const int lane = TIDX() & 63, lr = lane & 15, g = lane >> 4;
; #pragma unroll
;   for (int mt = 0; mt < 4; ++mt) {
;     const int row = row0 + mt * 16 + lr;
;     float ss = 0.f;
; #pragma unroll
;     for (int nt = 0; nt < 4; ++nt) {
;       const int col = col0 + nt * 16 + 4 * g;
;       float4* px = (float4*)(x + (size_t)row * DM + col);
;       float4 o = *(const float4*)(xsrc + (size_t)row * DM + col);
;       o.x += v[mt][nt][0]; o.y += v[mt][nt][1]; o.z += v[mt][nt][2]; o.w += v[mt][nt][3];
;       *px = o;
;       ss += (o.x * o.x + o.y * o.y) + (o.z * o.z + o.w * o.w);
;       if (write_xb) *(uint2*)(xb + (size_t)row * DM + col) = make_uint2(pack2(o.x, o.y), pack2(o.z, o.w));
;     }
;     if (write_ssq) {
;       ss += __shfl_xor(ss, 16); ss += __shfl_xor(ss, 32);
;       if (g == 0) ssq_out[(size_t)row * 16 + (col0 >> 6)] = ss;
;     }
	s_setprio 0
	v_mfma_f32_16x16x32_f16 v[78:81], v[12:15], v[48:51], v[78:81]
	v_mfma_f32_16x16x32_f16 v[20:23], v[58:61], v[48:51], v[86:89]
	v_mfma_f32_16x16x32_f16 v[32:35], v[16:19], v[48:51], v[32:35]
	v_mov_b32_e32 v49, v148
	v_or_b32_e32 v48, s10, v56
	v_and_or_b32 v50, v49, 15, v130
	v_bfe_u32 v134, v49, 4, 2
	v_ashrrev_i32_e32 v51, 31, v50
	v_mfma_f32_16x16x32_f16 v[86:89], v[4:7], v[40:43], v[98:101]
	v_lshl_or_b32 v135, v134, 2, v48
	v_lshrrev_b32_e32 v150, 4, v48
	v_lshl_add_u64 v[48:49], s[4:5], 0, v[150:151]
	v_mfma_f32_16x16x32_f16 v[98:101], v[12:15], v[40:43], v[102:105]
	v_lshlrev_b32_e32 v150, 2, v135
	v_readlane_b32 s4, v254, 43
	v_readlane_b32 s5, v254, 44
	v_mfma_f32_16x16x32_f16 v[102:105], v[58:61], v[40:43], v[114:117]
	v_cmp_eq_u32_e32 vcc, 0, v134
	s_nop 1
	v_lshlrev_b64 v[114:115], 12, v[50:51]
	v_lshl_add_u64 v[114:115], s[12:13], 0, v[114:115]
	v_lshl_add_u64 v[130:131], v[114:115], 0, v[150:151]
	v_mfma_f32_16x16x32_f16 v[70:73], v[16:19], v[40:43], v[70:73]
	global_load_dwordx4 v[40:43], v[130:131], off
	v_lshlrev_b64 v[114:115], 11, v[50:51]
	v_lshl_add_u64 v[132:133], s[4:5], 0, v[114:115]
	v_mfma_f32_16x16x32_f16 v[36:39], v[94:97], v[82:85], v[36:39]
	v_mfma_f32_16x16x32_f16 v[4:7], v[4:7], v[74:77], v[52:55]
	s_nop 2
	v_lshlrev_b32_e32 v52, 1, v135
	v_mov_b32_e32 v53, v151
	v_lshl_add_u64 v[54:55], v[132:133], 0, v[52:53]
	v_mfma_f32_16x16x32_f16 v[114:117], v[12:15], v[74:77], v[24:27]
	s_waitcnt vmcnt(0)
	v_pk_add_f32 v[36:37], v[36:37], v[40:41]
	v_pk_add_f32 v[38:39], v[38:39], v[42:43]
	v_cvt_pk_f16_f32 v40, v36, v37
	v_cvt_pk_f16_f32 v41, v38, v39
	global_store_dwordx4 v[130:131], v[36:39], off
	v_mov_b32_e32 v136, v40
	v_mov_b32_e32 v137, v41
	global_load_dwordx4 v[24:27], v[130:131], off offset:64
	v_mfma_f32_16x16x32_f16 v[12:15], v[106:109], v[82:85], v[44:47]
	v_mfma_f32_16x16x32_f16 v[0:3], v[58:61], v[74:77], v[0:3]
	v_mfma_f32_16x16x32_f16 v[58:61], v[16:19], v[74:77], v[8:11]
	s_waitcnt vmcnt(0)
	s_nop 4
	v_pk_add_f32 v[12:13], v[12:13], v[24:25]
	v_pk_add_f32 v[14:15], v[14:15], v[26:27]
	v_cvt_pk_f16_f32 v24, v12, v13
	v_cvt_pk_f16_f32 v25, v14, v15
	global_store_dwordx4 v[130:131], v[12:15], off offset:64
	v_mov_b32_e32 v138, v24
	v_mov_b32_e32 v139, v25
	v_and_b32_e32 v144, 16, v148
	v_lshrrev_b32_e32 v145, 1, v144
	v_add_u32_e32 v144, v144, v145
	v_mov_b32_e32 v145, 0
	v_lshl_add_u64 v[144:145], v[144:145], 0, v[54:55]
	v_permlane16_swap_b32_e32 v136, v138
	v_permlane16_swap_b32_e32 v137, v139
	global_store_dwordx4 v[144:145], v[136:139], off
	global_load_dwordx4 v[8:11], v[130:131], off offset:128
	v_mfma_f32_16x16x32_f16 v[16:19], v[122:125], v[82:85], v[62:65]
	v_mul_f32_e64 v12, v12, v12
	v_mul_f32_e64 v13, v13, v13
	v_pk_mul_f32 v[14:15], v[14:15], v[14:15]
	v_add_f32_e32 v12, v12, v13
	v_mfma_f32_16x16x32_f16 v[44:47], v[94:97], v[90:93], v[66:69]
	v_add_f32_e32 v14, v14, v15
	v_add_f32_e32 v12, v12, v14
	s_waitcnt vmcnt(0)
	v_pk_add_f32 v[8:9], v[16:17], v[8:9]
	v_pk_add_f32 v[10:11], v[18:19], v[10:11]
	v_cvt_pk_f16_f32 v24, v8, v9
	v_cvt_pk_f16_f32 v25, v10, v11
	global_store_dwordx4 v[130:131], v[8:11], off offset:128
	v_mov_b32_e32 v140, v24
	v_mov_b32_e32 v141, v25
	global_load_dwordx4 v[24:27], v[130:131], off offset:192
	v_mfma_f32_16x16x32_f16 v[16:19], v[126:129], v[82:85], v[28:31]
	v_mul_f32_e64 v66, v36, v36
	v_mul_f32_e64 v67, v37, v37
	v_pk_mul_f32 v[68:69], v[38:39], v[38:39]
	v_pk_mul_f32 v[8:9], v[8:9], v[8:9]
	v_pk_mul_f32 v[10:11], v[10:11], v[10:11]
	v_add_f32_e32 v8, v8, v9
	v_add_f32_e32 v10, v10, v11
	v_add_f32_e32 v8, v8, v10
	v_mfma_f32_16x16x32_f16 v[40:43], v[106:109], v[90:93], v[78:81]
	s_waitcnt vmcnt(0)
	v_pk_add_f32 v[62:63], v[16:17], v[24:25]
	v_add_f32_e32 v16, v68, v69
	v_add_f32_e32 v17, v66, v67
	v_pk_add_f32 v[64:65], v[18:19], v[26:27]
	v_add_f32_e32 v16, v17, v16
	v_pk_mul_f32 v[74:75], v[62:63], v[62:63]
	v_pk_mul_f32 v[76:77], v[64:65], v[64:65]
	v_add_f32_e32 v12, v16, v12
	v_add_f32_e32 v66, v12, v8
	v_mfma_f32_16x16x32_f16 v[12:15], v[94:97], v[118:121], v[4:7]
	global_store_dwordx4 v[130:131], v[62:65], off offset:192
	s_nop 1
	v_add_f32_e32 v4, v76, v77
	v_add_f32_e32 v5, v74, v75
	v_add_f32_e32 v4, v5, v4
	v_add_f32_e32 v66, v66, v4
	ds_bpermute_b32 v67, v189, v66
	v_cvt_pk_f16_f32 v62, v62, v63
	v_cvt_pk_f16_f32 v63, v64, v65
	v_mov_b32_e32 v142, v62
	v_mov_b32_e32 v143, v63
	v_and_b32_e32 v144, 16, v148
	v_lshrrev_b32_e32 v145, 1, v144
	v_add_u32_e32 v144, v144, v145
	v_mov_b32_e32 v145, 0
	v_lshl_add_u64 v[144:145], v[144:145], 0, v[54:55]
	v_permlane16_swap_b32_e32 v140, v142
	v_permlane16_swap_b32_e32 v141, v143
	global_store_dwordx4 v[144:145], v[140:143], off offset:64
	v_mfma_f32_16x16x32_f16 v[36:39], v[122:125], v[90:93], v[20:23]
	s_waitcnt lgkmcnt(0)
	v_add_f32_e32 v54, v66, v67
	ds_bpermute_b32 v55, v188, v54
	v_mfma_f32_16x16x32_f16 v[32:35], v[126:129], v[90:93], v[32:35]
	v_mfma_f32_16x16x32_f16 v[28:31], v[94:97], v[110:113], v[86:89]
	v_mfma_f32_16x16x32_f16 v[24:27], v[106:109], v[110:113], v[98:101]
	v_mfma_f32_16x16x32_f16 v[20:23], v[122:125], v[110:113], v[102:105]
	v_mfma_f32_16x16x32_f16 v[16:19], v[126:129], v[110:113], v[70:73]
	v_mfma_f32_16x16x32_f16 v[8:11], v[106:109], v[118:121], v[114:117]
	v_mfma_f32_16x16x32_f16 v[4:7], v[122:125], v[118:121], v[0:3]
	v_mfma_f32_16x16x32_f16 v[0:3], v[126:129], v[118:121], v[58:61]
	s_and_saveexec_b64 s[4:5], vcc
	s_cbranch_execz .LBB0_1374
	s_waitcnt lgkmcnt(0)
	v_add_f32_e32 v58, v54, v55
	v_lshlrev_b64 v[54:55], 6, v[50:51]
	v_lshl_add_u64 v[54:55], v[48:49], 0, v[54:55]
	global_store_dword v[54:55], v58, off

; #define GL_LOAD(s_, kt_) if (VAR != 1) { a##s_##0 = GL_A(0, kt_); a##s_##1 = GL_A(1, kt_); a##s_##2 = GL_A(2, kt_); a##s_##3 = GL_A(3, kt_); b##s_##0 = GL_B(0, kt_); b##s_##1 = GL_B(1, kt_); b##s_##2 = GL_B(2, kt_); b##s_##3 = GL_B(3, kt_); }
; #define LDS_STORE(s_, buf_) if (VAR != 2) { LDS_ST1(sA, 0, buf_, a##s_##0) LDS_ST1(sA, 1, buf_, a##s_##1) LDS_ST1(sA, 2, buf_, a##s_##2) LDS_ST1(sA, 3, buf_, a##s_##3) LDS_ST1(sB, 0, buf_, b##s_##0) LDS_ST1(sB, 1, buf_, b##s_##1) LDS_ST1(sB, 2, buf_, b##s_##2) LDS_ST1(sB, 3, buf_, b##s_##3) }
;     ...
;   GL_LOAD(0, 0)
;   GL_LOAD(1, 1)
;   LDS_STORE(0, 0)
;   if (VAR != 4) __syncthreads();
; #pragma unroll
;   for (int kt = 0; kt < nk; kt += 2) {
;     if (kt + 2 < nk) { GL_LOAD(0, kt + 2) }
;     MMA_TILE(0)
;     LDS_STORE(1, 1)
;     if (VAR != 4) __syncthreads();
;     if (kt + 3 < nk) { GL_LOAD(1, kt + 3) }
.LBB0_1435:
	s_ashr_i32 s1, s8, 3
	s_andn2_b32 s1, s1, 63
	s_and_b32 s2, s14, 56
	s_or_b32 s1, s1, s2
	s_bfe_u32 s2, s8, 0x30003
	s_or_b32 s1, s1, s2
	s_cmpk_gt_i32 s1, 0x7f
	s_cbranch_scc1 .LBB0_1434
	s_lshl_b32 s6, s1, 7
	v_readlane_b32 s1, v253, 0
	s_mov_b32 s16, s1
	s_ashr_i32 s17, s16, 31
	s_lshl_b64 s[16:17], s[16:17], 15
	s_ashr_i32 s7, s6, 31
	v_mov_b32_e32 v88, v148
	s_and_b32 s2, s13, 0x380
	v_lshl_add_u64 v[102:103], v[96:97], 0, s[16:17]
	s_lshl_b64 s[16:17], s[6:7], 9
	v_readlane_b32 s18, v254, 39
	v_readlane_b32 s19, v254, 40
	s_waitcnt vmcnt(5)
	v_ashrrev_i32_e32 v80, 3, v88
	s_add_u32 s16, s18, s16
	v_ashrrev_i32_e32 v81, 31, v80
	s_addc_u32 s17, s19, s17
	v_lshlrev_b32_e32 v0, 3, v88
	v_and_b32_e32 v91, 48, v88
	v_lshlrev_b64 v[16:17], 9, v[80:81]
	v_lshlrev_b32_e32 v81, 4, v88
	v_and_b32_e32 v90, 0x70, v0
	v_bitop3_b32 v170, v0, v91, s23 bitop3:0x6c
	s_waitcnt lgkmcnt(0)
	v_lshl_add_u64 v[0:1], s[16:17], 0, v[16:17]
	v_and_b32_e32 v150, 0x70, v81
	v_add_u32_e32 v82, 32, v80
	s_waitcnt vmcnt(4)
	v_add_u32_e32 v84, 64, v80
	v_add_u32_e32 v86, 0x60, v80
	s_lshl_b32 s1, s2, 9
	s_waitcnt vmcnt(1)
	v_lshl_add_u64 v[64:65], v[0:1], 0, v[150:151]
	v_ashrrev_i32_e32 v83, 31, v82
	v_ashrrev_i32_e32 v85, 31, v84
	v_ashrrev_i32_e32 v87, 31, v86
	s_add_u32 s18, s9, s1
	global_load_dwordx4 v[0:3], v[64:65], off
	v_lshlrev_b64 v[20:21], 9, v[82:83]
	v_lshlrev_b64 v[24:25], 9, v[84:85]
	v_lshlrev_b64 v[28:29], 9, v[86:87]
	s_addc_u32 s19, s10, 0
	v_lshl_add_u64 v[4:5], s[16:17], 0, v[20:21]
	v_lshl_add_u64 v[8:9], s[16:17], 0, v[24:25]
	v_lshl_add_u64 v[12:13], s[16:17], 0, v[28:29]
	v_lshl_add_u64 v[66:67], v[4:5], 0, v[150:151]
	s_waitcnt vmcnt(1)
	v_lshl_add_u64 v[68:69], v[8:9], 0, v[150:151]
	v_lshl_add_u64 v[70:71], v[12:13], 0, v[150:151]
	v_lshl_add_u64 v[16:17], s[18:19], 0, v[16:17]
	global_load_dwordx4 v[4:7], v[66:67], off
	global_load_dwordx4 v[8:11], v[68:69], off
	global_load_dwordx4 v[12:15], v[70:71], off
	v_lshl_add_u64 v[72:73], v[16:17], 0, v[150:151]
	v_lshl_add_u64 v[20:21], s[18:19], 0, v[20:21]
	global_load_dwordx4 v[16:19], v[72:73], off
	v_lshl_add_u64 v[74:75], v[20:21], 0, v[150:151]
	v_lshl_add_u64 v[24:25], s[18:19], 0, v[24:25]
	global_load_dwordx4 v[20:23], v[74:75], off
	v_lshl_add_u64 v[76:77], v[24:25], 0, v[150:151]
	global_load_dwordx4 v[24:27], v[76:77], off
	v_lshl_add_u64 v[28:29], s[18:19], 0, v[28:29]
	v_lshl_add_u64 v[78:79], v[28:29], 0, v[150:151]
	global_load_dwordx4 v[28:31], v[78:79], off
	global_load_dwordx4 v[32:35], v[64:65], off offset:128
	global_load_dwordx4 v[36:39], v[66:67], off offset:128
	global_load_dwordx4 v[40:43], v[68:69], off offset:128
	global_load_dwordx4 v[44:47], v[70:71], off offset:128
	global_load_dwordx4 v[48:51], v[72:73], off offset:128
	global_load_dwordx4 v[52:55], v[74:75], off offset:128
	global_load_dwordx4 v[56:59], v[76:77], off offset:128
	global_load_dwordx4 v[60:63], v[78:79], off offset:128
	v_bitop3_b32 v83, v81, s23, v88 bitop3:0x48
	v_lshl_or_b32 v80, v80, 7, v83
	v_and_b32_e32 v89, 15, v88
	v_lshl_or_b32 v81, v82, 7, v83
	v_lshl_or_b32 v82, v84, 7, v83
	v_lshl_or_b32 v83, v86, 7, v83
	v_xor_b32_e32 v171, 64, v170
	v_add_u32_e32 v123, s6, v122
	v_readlane_b32 s16, v254, 45
	v_readlane_b32 s17, v254, 46
	s_mov_b32 s18, 0x358637bd
	s_mov_b32 s1, 0x800000
	s_lshl_b64 s[6:7], s[6:7], 11
	s_waitcnt vmcnt(15)
	ds_write_b128 v80, v[0:3]
	v_lshrrev_b32_e32 v0, 1, v88
	v_and_or_b32 v0, v0, s24, v89
	v_lshlrev_b32_e32 v150, 7, v0
	v_lshlrev_b32_e32 v0, 7, v88
	v_and_b32_e32 v194, 0x2780, v0
	v_bitop3_b32 v84, v150, v90, v91 bitop3:0xf6
	v_or_b32_e32 v85, v194, v170
	s_waitcnt vmcnt(14)
	ds_write_b128 v81, v[4:7]
	s_waitcnt vmcnt(13)
	ds_write_b128 v82, v[8:11]
	s_waitcnt vmcnt(12)
	ds_write_b128 v83, v[12:15]
	s_waitcnt vmcnt(11)
	ds_write_b128 v80, v[16:19] offset:32768
	s_waitcnt vmcnt(10)
	ds_write_b128 v81, v[20:23] offset:32768
	s_waitcnt vmcnt(9)
	ds_write_b128 v82, v[24:27] offset:32768
	s_waitcnt vmcnt(8)
	ds_write_b128 v83, v[28:31] offset:32768
	s_waitcnt lgkmcnt(0)
	s_barrier
	s_setprio 2
	global_load_dwordx4 v[0:3], v[64:65], off offset:256
	global_load_dwordx4 v[4:7], v[66:67], off offset:256
	global_load_dwordx4 v[8:11], v[68:69], off offset:256
	global_load_dwordx4 v[12:15], v[70:71], off offset:256
	global_load_dwordx4 v[16:19], v[72:73], off offset:256
	global_load_dwordx4 v[20:23], v[74:75], off offset:256
	global_load_dwordx4 v[24:27], v[76:77], off offset:256
	global_load_dwordx4 v[28:31], v[78:79], off offset:256
	ds_read_b128 v[86:89], v84
	ds_read_b128 v[90:93], v85 offset:32768
	ds_read_b128 v[98:101], v84 offset:2048
	ds_read_b128 v[104:107], v85 offset:34816
	ds_read_b128 v[108:111], v84 offset:4096
	ds_read_b128 v[112:115], v85 offset:36864
	ds_read_b128 v[116:119], v84 offset:6144
	ds_read_b128 v[124:127], v85 offset:38912
	s_waitcnt lgkmcnt(6)
	v_mfma_f32_16x16x32_f16 v[128:131], v[90:93], v[86:89], 0
	s_waitcnt lgkmcnt(4)
	v_mfma_f32_16x16x32_f16 v[132:135], v[104:107], v[86:89], 0
	s_waitcnt lgkmcnt(2)
	v_mfma_f32_16x16x32_f16 v[136:139], v[112:115], v[86:89], 0
	s_waitcnt lgkmcnt(0)
	v_mfma_f32_16x16x32_f16 v[140:143], v[124:127], v[86:89], 0
	v_bitop3_b32 v86, v150, v170, 64 bitop3:0xf6
	v_or_b32_e32 v87, v194, v171
	v_mfma_f32_16x16x32_f16 v[144:147], v[90:93], v[98:101], 0
	v_mfma_f32_16x16x32_f16 v[154:157], v[104:107], v[98:101], 0
	v_mfma_f32_16x16x32_f16 v[158:161], v[112:115], v[98:101], 0
	v_mfma_f32_16x16x32_f16 v[98:101], v[124:127], v[98:101], 0
	v_mfma_f32_16x16x32_f16 v[162:165], v[90:93], v[108:111], 0
	v_mfma_f32_16x16x32_f16 v[166:169], v[104:107], v[108:111], 0
	v_mfma_f32_16x16x32_f16 v[190:193], v[112:115], v[108:111], 0
	v_mfma_f32_16x16x32_f16 v[108:111], v[124:127], v[108:111], 0
	v_mfma_f32_16x16x32_f16 v[88:91], v[90:93], v[116:119], 0
	v_mfma_f32_16x16x32_f16 v[92:95], v[104:107], v[116:119], 0
	v_mfma_f32_16x16x32_f16 v[104:107], v[112:115], v[116:119], 0
	v_mfma_f32_16x16x32_f16 v[112:115], v[124:127], v[116:119], 0
	ds_read_b128 v[116:119], v86
	ds_read_b128 v[124:127], v87 offset:32768
	ds_read_b128 v[194:197], v86 offset:2048
	ds_read_b128 v[198:201], v87 offset:34816
	ds_read_b128 v[202:205], v86 offset:4096
	ds_read_b128 v[206:209], v87 offset:36864
	ds_read_b128 v[210:213], v86 offset:6144
	ds_read_b128 v[220:223], v87 offset:38912
	s_waitcnt vmcnt(15)
	ds_write_b128 v80, v[32:35] offset:16384
	s_waitcnt vmcnt(14)
	ds_write_b128 v81, v[36:39] offset:16384
	s_waitcnt vmcnt(13)
	ds_write_b128 v82, v[40:43] offset:16384
	s_waitcnt vmcnt(12)
	ds_write_b128 v83, v[44:47] offset:16384
	s_waitcnt vmcnt(11)
	ds_write_b128 v80, v[48:51] offset:49152
	s_waitcnt vmcnt(10)
	ds_write_b128 v81, v[52:55] offset:49152
	s_waitcnt vmcnt(9)
	ds_write_b128 v82, v[56:59] offset:49152
	s_waitcnt vmcnt(8)
	ds_write_b128 v83, v[60:63] offset:49152
	s_waitcnt lgkmcnt(0)
	s_barrier
; #define GL_LOAD(s_, kt_) if (VAR != 1) { a##s_##0 = GL_A(0, kt_); a##s_##1 = GL_A(1, kt_); a##s_##2 = GL_A(2, kt_); a##s_##3 = GL_A(3, kt_); b##s_##0 = GL_B(0, kt_); b##s_##1 = GL_B(1, kt_); b##s_##2 = GL_B(2, kt_); b##s_##3 = GL_B(3, kt_); }
; #define LDS_STORE(s_, buf_) if (VAR != 2) { LDS_ST1(sA, 0, buf_, a##s_##0) LDS_ST1(sA, 1, buf_, a##s_##1) LDS_ST1(sA, 2, buf_, a##s_##2) LDS_ST1(sA, 3, buf_, a##s_##3) LDS_ST1(sB, 0, buf_, b##s_##0) LDS_ST1(sB, 1, buf_, b##s_##1) LDS_ST1(sB, 2, buf_, b##s_##2) LDS_ST1(sB, 3, buf_, b##s_##3) }
;     ...
;   for (int kt = 0; kt < nk; kt += 2) {
;     if (kt + 2 < nk) { GL_LOAD(0, kt + 2) }
;     MMA_TILE(0)
;     LDS_STORE(1, 1)
;     if (VAR != 4) __syncthreads();
;     if (kt + 3 < nk) { GL_LOAD(1, kt + 3) }
;     MMA_TILE(1)
;     if (kt + 2 < nk) { LDS_STORE(0, 0) }
;     if (VAR != 4) __syncthreads();
	v_mfma_f32_16x16x32_f16 v[128:131], v[124:127], v[116:119], v[128:131]
	global_load_dwordx4 v[32:35], v[64:65], off offset:384
	v_mfma_f32_16x16x32_f16 v[132:135], v[198:201], v[116:119], v[132:135]
	v_mfma_f32_16x16x32_f16 v[136:139], v[206:209], v[116:119], v[136:139]
	v_mfma_f32_16x16x32_f16 v[116:119], v[220:223], v[116:119], v[140:143]
	v_mfma_f32_16x16x32_f16 v[140:143], v[124:127], v[194:197], v[144:147]
	global_load_dwordx4 v[36:39], v[66:67], off offset:384
	ds_read_b128 v[64:67], v84 offset:16384
	global_load_dwordx4 v[40:43], v[68:69], off offset:384
	v_mfma_f32_16x16x32_f16 v[144:147], v[198:201], v[194:197], v[154:157]
	global_load_dwordx4 v[44:47], v[70:71], off offset:384
	v_mfma_f32_16x16x32_f16 v[154:157], v[206:209], v[194:197], v[158:161]
	v_mfma_f32_16x16x32_f16 v[158:161], v[124:127], v[202:205], v[162:165]
	ds_read_b128 v[68:71], v85 offset:49152
	global_load_dwordx4 v[48:51], v[72:73], off offset:384
	v_mfma_f32_16x16x32_f16 v[88:91], v[124:127], v[210:213], v[88:91]
	ds_read_b128 v[124:127], v84 offset:20480
	v_mfma_f32_16x16x32_f16 v[162:165], v[198:201], v[202:205], v[166:169]
	global_load_dwordx4 v[52:55], v[74:75], off offset:384
	v_mfma_f32_16x16x32_f16 v[92:95], v[198:201], v[210:213], v[92:95]
	ds_read_b128 v[72:75], v84 offset:18432
	ds_read_b128 v[198:201], v85 offset:55296
	global_load_dwordx4 v[56:59], v[76:77], off offset:384
	global_load_dwordx4 v[60:63], v[78:79], off offset:384
	v_mfma_f32_16x16x32_f16 v[98:101], v[220:223], v[194:197], v[98:101]
	ds_read_b128 v[76:79], v85 offset:51200
	v_mfma_f32_16x16x32_f16 v[166:169], v[206:209], v[202:205], v[190:193]
	s_nop 2
	ds_read_b128 v[190:193], v85 offset:53248
	v_mfma_f32_16x16x32_f16 v[104:107], v[206:209], v[210:213], v[104:107]
	ds_read_b128 v[194:197], v84 offset:22528
	v_mfma_f32_16x16x32_f16 v[108:111], v[220:223], v[202:205], v[108:111]
	s_waitcnt vmcnt(15)
	ds_write_b128 v80, v[0:3]
	v_mfma_f32_16x16x32_f16 v[112:115], v[220:223], v[210:213], v[112:115]
	s_waitcnt vmcnt(14)
	ds_write_b128 v81, v[4:7]
	s_waitcnt lgkmcnt(8)
	v_mfma_f32_16x16x32_f16 v[128:131], v[68:71], v[64:67], v[128:131]
	s_waitcnt vmcnt(13)
	ds_write_b128 v82, v[8:11]
	s_waitcnt lgkmcnt(5)
	v_mfma_f32_16x16x32_f16 v[132:135], v[76:79], v[64:67], v[132:135]
	s_waitcnt lgkmcnt(4)
	v_mfma_f32_16x16x32_f16 v[136:139], v[190:193], v[64:67], v[136:139]
	v_mfma_f32_16x16x32_f16 v[64:67], v[198:201], v[64:67], v[116:119]
	v_mfma_f32_16x16x32_f16 v[116:119], v[68:71], v[72:75], v[140:143]
	s_waitcnt vmcnt(12)
	ds_write_b128 v83, v[12:15]
	s_waitcnt vmcnt(11)
	ds_write_b128 v80, v[16:19] offset:32768
	v_mfma_f32_16x16x32_f16 v[140:143], v[76:79], v[72:75], v[144:147]
	s_waitcnt vmcnt(10)
	ds_write_b128 v81, v[20:23] offset:32768
	v_mfma_f32_16x16x32_f16 v[144:147], v[190:193], v[72:75], v[154:157]
	v_mfma_f32_16x16x32_f16 v[72:75], v[198:201], v[72:75], v[98:101]
	v_mfma_f32_16x16x32_f16 v[98:101], v[68:71], v[124:127], v[158:161]
	s_waitcnt vmcnt(9)
	ds_write_b128 v82, v[24:27] offset:32768
	s_waitcnt vmcnt(8)
	ds_write_b128 v83, v[28:31] offset:32768
	s_waitcnt lgkmcnt(8)
	v_mfma_f32_16x16x32_f16 v[68:71], v[68:71], v[194:197], v[88:91]
	v_mfma_f32_16x16x32_f16 v[154:157], v[76:79], v[124:127], v[162:165]
	s_nop 2
	ds_read_b128 v[162:165], v87 offset:51200
	v_mfma_f32_16x16x32_f16 v[76:79], v[76:79], v[194:197], v[92:95]
	v_mfma_f32_16x16x32_f16 v[158:161], v[190:193], v[124:127], v[166:169]
	s_nop 2
	ds_read_b128 v[166:169], v86 offset:20480
	v_mfma_f32_16x16x32_f16 v[88:91], v[190:193], v[194:197], v[104:107]
	s_nop 2
	ds_read_b128 v[104:107], v86 offset:16384
	ds_read_b128 v[190:193], v87 offset:53248
	v_mfma_f32_16x16x32_f16 v[108:111], v[198:201], v[124:127], v[108:111]
	ds_read_b128 v[124:127], v86 offset:18432
	v_mfma_f32_16x16x32_f16 v[92:95], v[198:201], v[194:197], v[112:115]
	s_nop 2
	ds_read_b128 v[112:115], v87 offset:49152
	ds_read_b128 v[194:197], v86 offset:22528
	ds_read_b128 v[198:201], v87 offset:55296
	s_waitcnt lgkmcnt(0)
	s_barrier
	ds_read_b128 v[0:3], v84
	ds_read_b128 v[4:7], v85 offset:32768
	ds_read_b128 v[8:11], v84 offset:2048
	ds_read_b128 v[12:15], v85 offset:34816
	ds_read_b128 v[16:19], v84 offset:4096
	ds_read_b128 v[20:23], v85 offset:36864
	ds_read_b128 v[24:27], v84 offset:6144
	ds_read_b128 v[28:31], v85 offset:38912
	v_mfma_f32_16x16x32_f16 v[128:131], v[112:115], v[104:107], v[128:131]
	v_mfma_f32_16x16x32_f16 v[132:135], v[162:165], v[104:107], v[132:135]
	v_mfma_f32_16x16x32_f16 v[136:139], v[190:193], v[104:107], v[136:139]
	v_mfma_f32_16x16x32_f16 v[64:67], v[198:201], v[104:107], v[64:67]
	v_mfma_f32_16x16x32_f16 v[104:107], v[112:115], v[124:127], v[116:119]
	v_mfma_f32_16x16x32_f16 v[116:119], v[162:165], v[124:127], v[140:143]
	v_mfma_f32_16x16x32_f16 v[140:143], v[190:193], v[124:127], v[144:147]
	v_mfma_f32_16x16x32_f16 v[72:75], v[198:201], v[124:127], v[72:75]
	v_mfma_f32_16x16x32_f16 v[98:101], v[112:115], v[166:169], v[98:101]
	v_mfma_f32_16x16x32_f16 v[124:127], v[162:165], v[166:169], v[154:157]
	v_mfma_f32_16x16x32_f16 v[144:147], v[190:193], v[166:169], v[158:161]
	v_mfma_f32_16x16x32_f16 v[108:111], v[198:201], v[166:169], v[108:111]
	v_mfma_f32_16x16x32_f16 v[68:71], v[112:115], v[194:197], v[68:71]
	v_mfma_f32_16x16x32_f16 v[76:79], v[162:165], v[194:197], v[76:79]
	v_mfma_f32_16x16x32_f16 v[88:91], v[190:193], v[194:197], v[88:91]
	v_mfma_f32_16x16x32_f16 v[92:95], v[198:201], v[194:197], v[92:95]
	s_waitcnt lgkmcnt(6)
	v_mfma_f32_16x16x32_f16 v[112:115], v[4:7], v[0:3], v[128:131]
	s_waitcnt lgkmcnt(4)
	v_mfma_f32_16x16x32_f16 v[128:131], v[12:15], v[0:3], v[132:135]
	s_waitcnt lgkmcnt(2)
; #define GL_LOAD(s_, kt_) if (VAR != 1) { a##s_##0 = GL_A(0, kt_); a##s_##1 = GL_A(1, kt_); a##s_##2 = GL_A(2, kt_); a##s_##3 = GL_A(3, kt_); b##s_##0 = GL_B(0, kt_); b##s_##1 = GL_B(1, kt_); b##s_##2 = GL_B(2, kt_); b##s_##3 = GL_B(3, kt_); }
; #define LDS_STORE(s_, buf_) if (VAR != 2) { LDS_ST1(sA, 0, buf_, a##s_##0) LDS_ST1(sA, 1, buf_, a##s_##1) LDS_ST1(sA, 2, buf_, a##s_##2) LDS_ST1(sA, 3, buf_, a##s_##3) LDS_ST1(sB, 0, buf_, b##s_##0) LDS_ST1(sB, 1, buf_, b##s_##1) LDS_ST1(sB, 2, buf_, b##s_##2) LDS_ST1(sB, 3, buf_, b##s_##3) }
;     ...
;   for (int kt = 0; kt < nk; kt += 2) {
;     if (kt + 2 < nk) { GL_LOAD(0, kt + 2) }
;     MMA_TILE(0)
;     LDS_STORE(1, 1)
;     if (VAR != 4) __syncthreads();
;     if (kt + 3 < nk) { GL_LOAD(1, kt + 3) }
;     MMA_TILE(1)
;     if (kt + 2 < nk) { LDS_STORE(0, 0) }
;     if (VAR != 4) __syncthreads();
	v_mfma_f32_16x16x32_f16 v[132:135], v[20:23], v[0:3], v[136:139]
	s_waitcnt lgkmcnt(0)
	v_mfma_f32_16x16x32_f16 v[0:3], v[28:31], v[0:3], v[64:67]
	v_mfma_f32_16x16x32_f16 v[64:67], v[4:7], v[8:11], v[104:107]
	v_mfma_f32_16x16x32_f16 v[104:107], v[12:15], v[8:11], v[116:119]
	v_mfma_f32_16x16x32_f16 v[116:119], v[20:23], v[8:11], v[140:143]
	v_mfma_f32_16x16x32_f16 v[8:11], v[28:31], v[8:11], v[72:75]
	v_mfma_f32_16x16x32_f16 v[72:75], v[4:7], v[16:19], v[98:101]
	v_mfma_f32_16x16x32_f16 v[98:101], v[12:15], v[16:19], v[124:127]
	v_mfma_f32_16x16x32_f16 v[124:127], v[20:23], v[16:19], v[144:147]
	v_mfma_f32_16x16x32_f16 v[16:19], v[28:31], v[16:19], v[108:111]
	v_mfma_f32_16x16x32_f16 v[4:7], v[4:7], v[24:27], v[68:71]
	v_mfma_f32_16x16x32_f16 v[12:15], v[12:15], v[24:27], v[76:79]
	v_mfma_f32_16x16x32_f16 v[20:23], v[20:23], v[24:27], v[88:91]
	v_mfma_f32_16x16x32_f16 v[24:27], v[28:31], v[24:27], v[92:95]
	ds_read_b128 v[28:31], v86
	ds_read_b128 v[68:71], v87 offset:32768
	ds_read_b128 v[76:79], v86 offset:2048
	ds_read_b128 v[88:91], v87 offset:34816
	ds_read_b128 v[92:95], v86 offset:4096
	ds_read_b128 v[108:111], v87 offset:36864
	ds_read_b128 v[136:139], v86 offset:6144
	ds_read_b128 v[140:143], v87 offset:38912
	s_waitcnt vmcnt(7)
	ds_write_b128 v80, v[32:35] offset:16384
	s_waitcnt vmcnt(6)
	ds_write_b128 v81, v[36:39] offset:16384
	s_waitcnt vmcnt(5)
	ds_write_b128 v82, v[40:43] offset:16384
	s_waitcnt vmcnt(4)
	ds_write_b128 v83, v[44:47] offset:16384
	s_waitcnt vmcnt(3)
	ds_write_b128 v80, v[48:51] offset:49152
	s_waitcnt vmcnt(2)
	ds_write_b128 v81, v[52:55] offset:49152
	s_waitcnt vmcnt(1)
	ds_write_b128 v82, v[56:59] offset:49152
	s_waitcnt vmcnt(0)
	ds_write_b128 v83, v[60:63] offset:49152
	s_waitcnt lgkmcnt(0)
	s_barrier
	ds_read_b128 v[32:35], v84 offset:16384
	ds_read_b128 v[36:39], v85 offset:49152
	ds_read_b128 v[40:43], v84 offset:18432
	ds_read_b128 v[44:47], v85 offset:51200
	ds_read_b128 v[48:51], v84 offset:20480
	ds_read_b128 v[52:55], v85 offset:53248
	ds_read_b128 v[56:59], v84 offset:22528
	ds_read_b128 v[60:63], v85 offset:55296
	v_mfma_f32_16x16x32_f16 v[112:115], v[68:71], v[28:31], v[112:115]
	v_mfma_f32_16x16x32_f16 v[128:131], v[88:91], v[28:31], v[128:131]
	v_mfma_f32_16x16x32_f16 v[132:135], v[108:111], v[28:31], v[132:135]
	v_mfma_f32_16x16x32_f16 v[0:3], v[140:143], v[28:31], v[0:3]
	v_mfma_f32_16x16x32_f16 v[28:31], v[68:71], v[76:79], v[64:67]
	v_mfma_f32_16x16x32_f16 v[64:67], v[88:91], v[76:79], v[104:107]
	v_mfma_f32_16x16x32_f16 v[104:107], v[108:111], v[76:79], v[116:119]
	v_mfma_f32_16x16x32_f16 v[8:11], v[140:143], v[76:79], v[8:11]
	v_mfma_f32_16x16x32_f16 v[72:75], v[68:71], v[92:95], v[72:75]
	v_mfma_f32_16x16x32_f16 v[76:79], v[88:91], v[92:95], v[98:101]
	v_mfma_f32_16x16x32_f16 v[98:101], v[108:111], v[92:95], v[124:127]
	v_mfma_f32_16x16x32_f16 v[16:19], v[140:143], v[92:95], v[16:19]
	v_mfma_f32_16x16x32_f16 v[4:7], v[68:71], v[136:139], v[4:7]
	v_mfma_f32_16x16x32_f16 v[12:15], v[88:91], v[136:139], v[12:15]
	v_mfma_f32_16x16x32_f16 v[20:23], v[108:111], v[136:139], v[20:23]
	v_mfma_f32_16x16x32_f16 v[24:27], v[140:143], v[136:139], v[24:27]
	s_waitcnt lgkmcnt(6)
	v_mfma_f32_16x16x32_f16 v[68:71], v[36:39], v[32:35], v[112:115]
	s_waitcnt lgkmcnt(4)
	v_mfma_f32_16x16x32_f16 v[80:83], v[44:47], v[32:35], v[128:131]
	s_waitcnt lgkmcnt(2)
	v_mfma_f32_16x16x32_f16 v[88:91], v[52:55], v[32:35], v[132:135]
	s_waitcnt lgkmcnt(0)
	v_mfma_f32_16x16x32_f16 v[0:3], v[60:63], v[32:35], v[0:3]
	v_mfma_f32_16x16x32_f16 v[28:31], v[36:39], v[40:43], v[28:31]
	v_mfma_f32_16x16x32_f16 v[32:35], v[44:47], v[40:43], v[64:67]
	v_mfma_f32_16x16x32_f16 v[64:67], v[52:55], v[40:43], v[104:107]
	v_mfma_f32_16x16x32_f16 v[8:11], v[60:63], v[40:43], v[8:11]
	v_mfma_f32_16x16x32_f16 v[40:43], v[36:39], v[48:51], v[72:75]
	v_mfma_f32_16x16x32_f16 v[72:75], v[44:47], v[48:51], v[76:79]
	v_mfma_f32_16x16x32_f16 v[76:79], v[52:55], v[48:51], v[98:101]
	v_mfma_f32_16x16x32_f16 v[16:19], v[60:63], v[48:51], v[16:19]
	v_mfma_f32_16x16x32_f16 v[4:7], v[36:39], v[56:59], v[4:7]
	v_mfma_f32_16x16x32_f16 v[12:15], v[44:47], v[56:59], v[12:15]
	v_mfma_f32_16x16x32_f16 v[20:23], v[52:55], v[56:59], v[20:23]
	v_mfma_f32_16x16x32_f16 v[24:27], v[60:63], v[56:59], v[24:27]
	ds_read_b128 v[36:39], v86 offset:16384
	ds_read_b128 v[44:47], v87 offset:49152
	ds_read_b128 v[48:51], v86 offset:18432
	ds_read_b128 v[52:55], v87 offset:51200
	ds_read_b128 v[56:59], v86 offset:20480
	ds_read_b128 v[60:63], v87 offset:53248
	ds_read_b128 v[92:95], v86 offset:22528
	ds_read_b128 v[84:87], v87 offset:55296
	s_waitcnt lgkmcnt(0)
	s_barrier
; DI unsigned pack2(float lo, float hi) { f2_t v = {lo, hi}; h2_t b = __builtin_convertvector(v, h2_t); return __builtin_bit_cast(unsigned, b); }
; DI void load_rstd(float (&rs)[4], const float* ssq, int row0, int lr) {
; #pragma unroll
;   for (int mt = 0; mt < 4; ++mt) {
;     const float4* q = (const float4*)(ssq + (size_t)(row0 + mt * 16 + lr) * 16);
;     const float4 a = q[0], b = q[1], c = q[2], d = q[3];
;     const float s = ((a.x + a.y) + (a.z + a.w)) + ((b.x + b.y) + (b.z + b.w)) + ((c.x + c.y) + (c.z + c.w)) + ((d.x + d.y) + (d.z + d.w));
;     rs[mt] = rsqrtf(s * (1.0f / 1024.0f) + EPS);
;   }
; DI void phase_ple(const Params& P, int l, char* smem) {
;     ...
;       gemm_kloop<false, true, 4>(pp, pl + (size_t)m0 * PLE, PLE, W + WO_PP + (size_t)n0 * PLE, PLE, smem);
; #pragma unroll
;       for (int mt = 0; mt < 4; ++mt)
; #pragma unroll
;         for (int h = 0; h < 2; ++h)
;           park[mt * 2 + h] = make_uint4(pack2(pp[mt][2 * h][0], pp[mt][2 * h][1]), pack2(pp[mt][2 * h][2], pp[mt][2 * h][3]), pack2(pp[mt][2 * h + 1][0], pp[mt][2 * h + 1][1]), pack2(pp[mt][2 * h + 1][2], pp[mt][2 * h + 1][3]));
;     }
;     f32x4 acc[4][4]; zero_acc(acc);
;     float rs[4]; load_rstd(rs, ssq, row0, lr);
	v_mfma_f32_16x16x32_f16 v[68:71], v[44:47], v[36:39], v[68:71]
	v_mfma_f32_16x16x32_f16 v[80:83], v[52:55], v[36:39], v[80:83]
	v_mfma_f32_16x16x32_f16 v[0:3], v[84:87], v[36:39], v[0:3]
	v_mfma_f32_16x16x32_f16 v[28:31], v[44:47], v[48:51], v[28:31]
	v_mfma_f32_16x16x32_f16 v[32:35], v[52:55], v[48:51], v[32:35]
	v_mfma_f32_16x16x32_f16 v[88:91], v[60:63], v[36:39], v[88:91]
	v_mfma_f32_16x16x32_f16 v[36:39], v[60:63], v[48:51], v[64:67]
	v_mfma_f32_16x16x32_f16 v[8:11], v[84:87], v[48:51], v[8:11]
	v_mfma_f32_16x16x32_f16 v[40:43], v[44:47], v[56:59], v[40:43]
	v_mfma_f32_16x16x32_f16 v[48:51], v[52:55], v[56:59], v[72:75]
	v_mfma_f32_16x16x32_f16 v[64:67], v[60:63], v[56:59], v[76:79]
	s_nop 1
	v_mov_b32_e32 v72, v148
	v_mfma_f32_16x16x32_f16 v[16:19], v[84:87], v[56:59], v[16:19]
	v_mfma_f32_16x16x32_f16 v[4:7], v[44:47], v[92:95], v[4:7]
	v_cvt_pk_f16_f32 v44, v68, v69
	v_cvt_pk_f16_f32 v45, v70, v71
	v_cvt_pk_f16_f32 v46, v80, v81
	v_cvt_pk_f16_f32 v47, v82, v83
	v_mfma_f32_16x16x32_f16 v[12:15], v[52:55], v[92:95], v[12:15]
	global_store_dwordx4 v[102:103], v[44:47], off
	s_nop 1
	v_cvt_pk_f16_f32 v46, v0, v1
	v_cvt_pk_f16_f32 v47, v2, v3
	v_cvt_pk_f16_f32 v0, v28, v29
	v_cvt_pk_f16_f32 v1, v30, v31
	v_cvt_pk_f16_f32 v2, v32, v33
	v_cvt_pk_f16_f32 v3, v34, v35
	v_mfma_f32_16x16x32_f16 v[20:23], v[60:63], v[92:95], v[20:23]
	global_store_dwordx4 v[102:103], v[0:3], off offset:32
	v_cvt_pk_f16_f32 v44, v88, v89
	v_cvt_pk_f16_f32 v45, v90, v91
	v_mfma_f32_16x16x32_f16 v[24:27], v[84:87], v[92:95], v[24:27]
	v_cvt_pk_f16_f32 v0, v36, v37
	v_cvt_pk_f16_f32 v1, v38, v39
	v_cvt_pk_f16_f32 v2, v8, v9
	v_cvt_pk_f16_f32 v3, v10, v11
	global_store_dwordx4 v[102:103], v[0:3], off offset:48
	global_store_dwordx4 v[102:103], v[44:47], off offset:16
	s_nop 0
	v_cvt_pk_f16_f32 v0, v40, v41
	v_cvt_pk_f16_f32 v1, v42, v43
	v_cvt_pk_f16_f32 v2, v48, v49
	v_cvt_pk_f16_f32 v3, v50, v51
	global_store_dwordx4 v[102:103], v[0:3], off offset:64
	s_nop 1
	v_cvt_pk_f16_f32 v0, v64, v65
	v_cvt_pk_f16_f32 v1, v66, v67
	v_cvt_pk_f16_f32 v2, v16, v17
	v_cvt_pk_f16_f32 v3, v18, v19
	global_store_dwordx4 v[102:103], v[0:3], off offset:80
	s_nop 1
	v_cvt_pk_f16_f32 v0, v4, v5
	v_cvt_pk_f16_f32 v1, v6, v7
	v_cvt_pk_f16_f32 v2, v12, v13
	v_cvt_pk_f16_f32 v3, v14, v15
	global_store_dwordx4 v[102:103], v[0:3], off offset:96
	s_nop 1
	v_cvt_pk_f16_f32 v0, v20, v21
	v_cvt_pk_f16_f32 v1, v22, v23
	v_cvt_pk_f16_f32 v2, v24, v25
	v_cvt_pk_f16_f32 v3, v26, v27
	global_store_dwordx4 v[102:103], v[0:3], off offset:112
	s_nop 1
	v_or_b32_e32 v0, v123, v121
	v_ashrrev_i32_e32 v1, 31, v0
	v_lshlrev_b64 v[2:3], 6, v[0:1]
	v_lshl_add_u64 v[14:15], s[16:17], 0, v[2:3]
	global_load_dwordx4 v[2:5], v[14:15], off offset:32
	global_load_dwordx4 v[6:9], v[14:15], off offset:16
	global_load_dwordx4 v[10:13], v[14:15], off
	s_nop 0
	global_load_dwordx4 v[14:17], v[14:15], off offset:48
	s_waitcnt vmcnt(2)
	v_mov_b32_e32 v20, v7
	s_waitcnt vmcnt(1)
	v_mov_b32_e32 v18, v11
	v_mov_b32_e32 v19, v12
	v_mov_b32_e32 v21, v8
	v_mov_b32_e32 v11, v13
	v_mov_b32_e32 v7, v9
	v_mov_b32_e32 v8, v3
	v_pk_add_f32 v[10:11], v[18:19], v[10:11]
	v_pk_add_f32 v[6:7], v[20:21], v[6:7]
	v_pk_add_f32 v[2:3], v[2:3], v[8:9]
	v_mov_b32_e32 v8, v5
	v_pk_add_f32 v[10:11], v[10:11], v[10:11] op_sel:[0,1] op_sel_hi:[1,0]
	v_pk_add_f32 v[6:7], v[6:7], v[6:7] op_sel:[0,1] op_sel_hi:[1,0]
	v_pk_add_f32 v[4:5], v[4:5], v[8:9]
	s_waitcnt vmcnt(0)
	v_mov_b32_e32 v11, v14
	v_mov_b32_e32 v7, v15
	v_mov_b32_e32 v3, v16
	v_mov_b32_e32 v5, v17
	v_pk_add_f32 v[6:7], v[10:11], v[6:7]
	v_pk_add_f32 v[2:3], v[2:3], v[4:5]
	s_nop 0
	v_pk_add_f32 v[18:19], v[6:7], v[2:3]
	v_or_b32_e32 v2, 16, v0
	v_ashrrev_i32_e32 v3, 31, v2
	v_lshlrev_b64 v[2:3], 6, v[2:3]
	v_lshl_add_u64 v[14:15], s[16:17], 0, v[2:3]
	global_load_dwordx4 v[2:5], v[14:15], off offset:32
	global_load_dwordx4 v[6:9], v[14:15], off offset:16
	global_load_dwordx4 v[10:13], v[14:15], off
	s_nop 0
	global_load_dwordx4 v[14:17], v[14:15], off offset:48
	s_waitcnt vmcnt(2)
	v_mov_b32_e32 v22, v7
	s_waitcnt vmcnt(1)
	v_mov_b32_e32 v20, v11
	v_mov_b32_e32 v21, v12
	v_mov_b32_e32 v23, v8
	v_mov_b32_e32 v11, v13
	v_mov_b32_e32 v7, v9
	v_mov_b32_e32 v8, v3
	v_pk_add_f32 v[10:11], v[20:21], v[10:11]
	v_pk_add_f32 v[6:7], v[22:23], v[6:7]
	v_pk_add_f32 v[2:3], v[2:3], v[8:9]
	v_mov_b32_e32 v8, v5
	v_pk_add_f32 v[10:11], v[10:11], v[10:11] op_sel:[0,1] op_sel_hi:[1,0]
	v_pk_add_f32 v[6:7], v[6:7], v[6:7] op_sel:[0,1] op_sel_hi:[1,0]
	v_pk_add_f32 v[4:5], v[4:5], v[8:9]
	s_waitcnt vmcnt(0)
	v_mov_b32_e32 v11, v14
	v_mov_b32_e32 v7, v15
	v_mov_b32_e32 v3, v16
	v_mov_b32_e32 v5, v17
	v_pk_add_f32 v[6:7], v[10:11], v[6:7]
	v_pk_add_f32 v[2:3], v[2:3], v[4:5]
	v_mov_b32_e32 v5, v18
	v_pk_add_f32 v[2:3], v[6:7], v[2:3]
	s_nop 0
	v_mov_b32_e32 v4, v2
	v_mov_b32_e32 v18, v3
	v_pk_add_f32 v[4:5], v[4:5], v[18:19]
	v_mov_b64_e32 v[2:3], s[18:19]
	s_mov_b32 s18, 0x3a800000
	v_pk_fma_f32 v[100:101], v[4:5], s[18:19], v[2:3] op_sel_hi:[1,0,0]
	s_nop 0
	v_mul_f32_e32 v1, 0x4b800000, v101
	v_cmp_gt_f32_e32 vcc, s1, v101
	v_cmp_gt_f32_e64 s[44:45], s1, v100
	s_nop 0
	v_cndmask_b32_e32 v1, v101, v1, vcc
	v_rsq_f32_e32 v1, v1
	s_nop 0
	v_mul_f32_e32 v4, 0x45800000, v1
	v_cndmask_b32_e32 v101, v1, v4, vcc
	v_or_b32_e32 v4, 32, v0
	v_ashrrev_i32_e32 v5, 31, v4
	v_lshlrev_b64 v[4:5], 6, v[4:5]
	v_lshl_add_u64 v[16:17], s[16:17], 0, v[4:5]
	global_load_dwordx4 v[4:7], v[16:17], off offset:32
	global_load_dwordx4 v[8:11], v[16:17], off offset:16
	global_load_dwordx4 v[12:15], v[16:17], off
	s_nop 0
	global_load_dwordx4 v[16:19], v[16:17], off offset:48
	v_or_b32_e32 v0, 48, v0
	v_ashrrev_i32_e32 v1, 31, v0
	v_lshlrev_b64 v[0:1], 6, v[0:1]
	v_lshl_add_u64 v[0:1], s[16:17], 0, v[0:1]
	v_readlane_b32 s16, v254, 43
	v_readlane_b32 s17, v254, 44
	s_add_u32 s6, s16, s6
	s_addc_u32 s7, s17, s7
	s_waitcnt vmcnt(2)
; #define GL_LOAD(s_, kt_) if (VAR != 1) { a##s_##0 = GL_A(0, kt_); a##s_##1 = GL_A(1, kt_); a##s_##2 = GL_A(2, kt_); a##s_##3 = GL_A(3, kt_); b##s_##0 = GL_B(0, kt_); b##s_##1 = GL_B(1, kt_); b##s_##2 = GL_B(2, kt_); b##s_##3 = GL_B(3, kt_); }
; #define LDS_STORE(s_, buf_) if (VAR != 2) { LDS_ST1(sA, 0, buf_, a##s_##0) LDS_ST1(sA, 1, buf_, a##s_##1) LDS_ST1(sA, 2, buf_, a##s_##2) LDS_ST1(sA, 3, buf_, a##s_##3) LDS_ST1(sB, 0, buf_, b##s_##0) LDS_ST1(sB, 1, buf_, b##s_##1) LDS_ST1(sB, 2, buf_, b##s_##2) LDS_ST1(sB, 3, buf_, b##s_##3) }
;     ...
;   GL_LOAD(0, 0)
;   GL_LOAD(1, 1)
;   LDS_STORE(0, 0)
;   if (VAR != 4) __syncthreads();
; DI void load_rstd(float (&rs)[4], const float* ssq, int row0, int lr) {
; #pragma unroll
;   for (int mt = 0; mt < 4; ++mt) {
;     const float4* q = (const float4*)(ssq + (size_t)(row0 + mt * 16 + lr) * 16);
;     const float4 a = q[0], b = q[1], c = q[2], d = q[3];
;     const float s = ((a.x + a.y) + (a.z + a.w)) + ((b.x + b.y) + (b.z + b.w)) + ((c.x + c.y) + (c.z + c.w)) + ((d.x + d.y) + (d.z + d.w));
;     rs[mt] = rsqrtf(s * (1.0f / 1024.0f) + EPS);
;   }
	v_mov_b32_e32 v22, v9
	s_waitcnt vmcnt(1)
	v_mov_b32_e32 v20, v13
	v_mov_b32_e32 v21, v14
	v_mov_b32_e32 v23, v10
	v_mov_b32_e32 v13, v15
	v_mov_b32_e32 v9, v11
	v_mov_b32_e32 v10, v5
	v_pk_add_f32 v[12:13], v[20:21], v[12:13]
	v_pk_add_f32 v[8:9], v[22:23], v[8:9]
	v_pk_add_f32 v[4:5], v[4:5], v[10:11]
	v_mov_b32_e32 v10, v7
	v_pk_add_f32 v[12:13], v[12:13], v[12:13] op_sel:[0,1] op_sel_hi:[1,0]
	v_pk_add_f32 v[8:9], v[8:9], v[8:9] op_sel:[0,1] op_sel_hi:[1,0]
	v_pk_add_f32 v[6:7], v[6:7], v[10:11]
	s_waitcnt vmcnt(0)
	v_mov_b32_e32 v13, v16
	v_mov_b32_e32 v9, v17
	v_mov_b32_e32 v5, v18
	v_mov_b32_e32 v7, v19
	v_pk_add_f32 v[8:9], v[12:13], v[8:9]
	v_pk_add_f32 v[4:5], v[4:5], v[6:7]
	s_nop 0
	v_pk_add_f32 v[20:21], v[8:9], v[4:5]
	global_load_dwordx4 v[4:7], v[0:1], off offset:32
	global_load_dwordx4 v[8:11], v[0:1], off offset:16
	global_load_dwordx4 v[12:15], v[0:1], off
	global_load_dwordx4 v[16:19], v[0:1], off offset:48
	s_waitcnt vmcnt(2)
	v_mov_b32_e32 v22, v9
	s_waitcnt vmcnt(1)
	v_mov_b32_e32 v0, v13
	v_mov_b32_e32 v1, v14
	v_mov_b32_e32 v23, v10
	v_mov_b32_e32 v13, v15
	v_mov_b32_e32 v9, v11
	v_mov_b32_e32 v10, v5
	v_pk_add_f32 v[0:1], v[0:1], v[12:13]
	v_pk_add_f32 v[8:9], v[22:23], v[8:9]
	v_pk_add_f32 v[4:5], v[4:5], v[10:11]
	v_mov_b32_e32 v10, v7
	v_pk_add_f32 v[0:1], v[0:1], v[0:1] op_sel:[0,1] op_sel_hi:[1,0]
	v_pk_add_f32 v[8:9], v[8:9], v[8:9] op_sel:[0,1] op_sel_hi:[1,0]
	v_pk_add_f32 v[6:7], v[6:7], v[10:11]
	s_waitcnt vmcnt(0)
	v_mov_b32_e32 v1, v16
	v_mov_b32_e32 v9, v17
	v_mov_b32_e32 v5, v18
	v_mov_b32_e32 v7, v19
	v_pk_add_f32 v[0:1], v[0:1], v[8:9]
	v_pk_add_f32 v[4:5], v[4:5], v[6:7]
	v_ashrrev_i32_e32 v64, 3, v72
	v_pk_add_f32 v[0:1], v[0:1], v[4:5]
	v_mov_b32_e32 v5, v20
	v_mov_b32_e32 v4, v0
	v_mov_b32_e32 v20, v1
	v_pk_add_f32 v[0:1], v[4:5], v[20:21]
	v_ashrrev_i32_e32 v65, 31, v64
	v_pk_fma_f32 v[98:99], v[0:1], s[18:19], v[2:3] op_sel_hi:[1,0,0]
	v_lshlrev_b32_e32 v0, 3, v72
	v_and_b32_e32 v75, 48, v72
	v_lshlrev_b64 v[16:17], 11, v[64:65]
	v_lshlrev_b32_e32 v65, 4, v72
	v_and_b32_e32 v74, 0x70, v0
	v_bitop3_b32 v129, v0, v75, s23 bitop3:0x6c
	v_lshl_add_u64 v[0:1], s[6:7], 0, v[16:17]
	v_and_b32_e32 v150, 0x70, v65
	v_add_u32_e32 v66, 32, v64
	v_add_u32_e32 v68, 64, v64
	v_add_u32_e32 v70, 0x60, v64
	v_cmp_gt_f32_e64 s[38:39], s1, v98
	v_cmp_gt_f32_e64 s[40:41], s1, v99
	s_lshl_b32 s1, s2, 11
	v_lshl_add_u64 v[104:105], v[0:1], 0, v[150:151]
	v_ashrrev_i32_e32 v67, 31, v66
	v_ashrrev_i32_e32 v69, 31, v68
	v_ashrrev_i32_e32 v71, 31, v70
	s_add_u32 s16, s11, s1
	global_load_dwordx4 v[0:3], v[104:105], off
	v_lshlrev_b64 v[20:21], 11, v[66:67]
	v_lshlrev_b64 v[24:25], 11, v[68:69]
	v_lshlrev_b64 v[28:29], 11, v[70:71]
	s_addc_u32 s17, s12, 0
	v_lshl_add_u64 v[4:5], s[6:7], 0, v[20:21]
	v_lshl_add_u64 v[8:9], s[6:7], 0, v[24:25]
	v_lshl_add_u64 v[12:13], s[6:7], 0, v[28:29]
	v_lshl_add_u64 v[106:107], v[4:5], 0, v[150:151]
	v_lshl_add_u64 v[108:109], v[8:9], 0, v[150:151]
	v_lshl_add_u64 v[110:111], v[12:13], 0, v[150:151]
	v_lshl_add_u64 v[16:17], s[16:17], 0, v[16:17]
	global_load_dwordx4 v[4:7], v[106:107], off
	global_load_dwordx4 v[8:11], v[108:109], off
	global_load_dwordx4 v[12:15], v[110:111], off
	v_lshl_add_u64 v[112:113], v[16:17], 0, v[150:151]
	v_lshl_add_u64 v[20:21], s[16:17], 0, v[20:21]
	global_load_dwordx4 v[16:19], v[112:113], off
	v_lshl_add_u64 v[114:115], v[20:21], 0, v[150:151]
	v_lshl_add_u64 v[24:25], s[16:17], 0, v[24:25]
	global_load_dwordx4 v[20:23], v[114:115], off
	v_lshl_add_u64 v[116:117], v[24:25], 0, v[150:151]
	global_load_dwordx4 v[24:27], v[116:117], off
	v_lshl_add_u64 v[28:29], s[16:17], 0, v[28:29]
	v_lshl_add_u64 v[118:119], v[28:29], 0, v[150:151]
	global_load_dwordx4 v[28:31], v[118:119], off
	global_load_dwordx4 v[32:35], v[104:105], off offset:128
	global_load_dwordx4 v[36:39], v[106:107], off offset:128
	global_load_dwordx4 v[40:43], v[108:109], off offset:128
	global_load_dwordx4 v[44:47], v[110:111], off offset:128
	global_load_dwordx4 v[48:51], v[112:113], off offset:128
	global_load_dwordx4 v[52:55], v[114:115], off offset:128
	global_load_dwordx4 v[56:59], v[116:117], off offset:128
	global_load_dwordx4 v[60:63], v[118:119], off offset:128
	v_bitop3_b32 v65, v65, s23, v72 bitop3:0x48
	v_lshl_or_b32 v126, v64, 7, v65
	v_and_b32_e32 v73, 15, v72
	v_lshl_or_b32 v124, v66, 7, v65
	v_lshl_or_b32 v125, v68, 7, v65
	v_lshl_or_b32 v127, v70, 7, v65
	v_xor_b32_e32 v130, 64, v129
	v_readlane_b32 s16, v254, 55
	v_readlane_b32 s6, v253, 11
	v_readlane_b32 s17, v254, 56
	v_readlane_b32 s7, v253, 12
	v_readlane_b32 s18, v254, 57
	v_readlane_b32 s19, v254, 58
	s_waitcnt vmcnt(15)
	ds_write_b128 v126, v[0:3]
	v_lshrrev_b32_e32 v0, 1, v72
	v_and_or_b32 v0, v0, s24, v73
	v_lshlrev_b32_e32 v150, 7, v0
	v_lshlrev_b32_e32 v0, 7, v72
	v_and_b32_e32 v170, 0x2780, v0
	v_bitop3_b32 v128, v150, v74, v75 bitop3:0xf6
	v_or_b32_e32 v131, v170, v129
	v_bitop3_b32 v129, v150, v129, 64 bitop3:0xf6
	v_or_b32_e32 v130, v170, v130
	s_waitcnt vmcnt(14)
	ds_write_b128 v124, v[4:7]
	s_waitcnt vmcnt(13)
	ds_write_b128 v125, v[8:11]
	s_waitcnt vmcnt(12)
	ds_write_b128 v127, v[12:15]
	s_waitcnt vmcnt(11)
	ds_write_b128 v126, v[16:19] offset:32768
	s_waitcnt vmcnt(10)
	ds_write_b128 v124, v[20:23] offset:32768
	s_waitcnt vmcnt(9)
	ds_write_b128 v125, v[24:27] offset:32768
	s_waitcnt vmcnt(8)
	ds_write_b128 v127, v[28:31] offset:32768
	s_waitcnt lgkmcnt(0)
	s_barrier
; #define GL_LOAD(s_, kt_) if (VAR != 1) { a##s_##0 = GL_A(0, kt_); a##s_##1 = GL_A(1, kt_); a##s_##2 = GL_A(2, kt_); a##s_##3 = GL_A(3, kt_); b##s_##0 = GL_B(0, kt_); b##s_##1 = GL_B(1, kt_); b##s_##2 = GL_B(2, kt_); b##s_##3 = GL_B(3, kt_); }
; #define LDS_STORE(s_, buf_) if (VAR != 2) { LDS_ST1(sA, 0, buf_, a##s_##0) LDS_ST1(sA, 1, buf_, a##s_##1) LDS_ST1(sA, 2, buf_, a##s_##2) LDS_ST1(sA, 3, buf_, a##s_##3) LDS_ST1(sB, 0, buf_, b##s_##0) LDS_ST1(sB, 1, buf_, b##s_##1) LDS_ST1(sB, 2, buf_, b##s_##2) LDS_ST1(sB, 3, buf_, b##s_##3) }
;     ...
;   for (int kt = 0; kt < nk; kt += 2) {
;     if (kt + 2 < nk) { GL_LOAD(0, kt + 2) }
;     MMA_TILE(0)
;     LDS_STORE(1, 1)
;     if (VAR != 4) __syncthreads();
;     if (kt + 3 < nk) { GL_LOAD(1, kt + 3) }
;     MMA_TILE(1)
;     if (kt + 2 < nk) { LDS_STORE(0, 0) }
;     if (VAR != 4) __syncthreads();
	global_load_dwordx4 v[0:3], v[104:105], off offset:256
	global_load_dwordx4 v[4:7], v[106:107], off offset:256
	global_load_dwordx4 v[8:11], v[108:109], off offset:256
	global_load_dwordx4 v[12:15], v[110:111], off offset:256
	global_load_dwordx4 v[16:19], v[112:113], off offset:256
	global_load_dwordx4 v[20:23], v[114:115], off offset:256
	global_load_dwordx4 v[24:27], v[116:117], off offset:256
	global_load_dwordx4 v[28:31], v[118:119], off offset:256
	ds_read_b128 v[64:67], v128
	ds_read_b128 v[68:71], v131 offset:32768
	ds_read_b128 v[72:75], v128 offset:2048
	ds_read_b128 v[76:79], v131 offset:34816
	ds_read_b128 v[80:83], v128 offset:4096
	ds_read_b128 v[84:87], v131 offset:36864
	ds_read_b128 v[88:91], v128 offset:6144
	ds_read_b128 v[92:95], v131 offset:38912
	s_waitcnt lgkmcnt(6)
	v_mfma_f32_16x16x32_f16 v[132:135], v[68:71], v[64:67], 0
	s_waitcnt lgkmcnt(4)
	v_mfma_f32_16x16x32_f16 v[136:139], v[76:79], v[64:67], 0
	s_waitcnt lgkmcnt(2)
	v_mfma_f32_16x16x32_f16 v[140:143], v[84:87], v[64:67], 0
	s_waitcnt lgkmcnt(0)
	v_mfma_f32_16x16x32_f16 v[64:67], v[92:95], v[64:67], 0
	v_mfma_f32_16x16x32_f16 v[144:147], v[68:71], v[72:75], 0
	v_mfma_f32_16x16x32_f16 v[154:157], v[76:79], v[72:75], 0
	v_mfma_f32_16x16x32_f16 v[158:161], v[84:87], v[72:75], 0
	v_mfma_f32_16x16x32_f16 v[72:75], v[92:95], v[72:75], 0
	v_mfma_f32_16x16x32_f16 v[162:165], v[68:71], v[80:83], 0
	v_mfma_f32_16x16x32_f16 v[166:169], v[76:79], v[80:83], 0
	v_mfma_f32_16x16x32_f16 v[190:193], v[84:87], v[80:83], 0
	v_mfma_f32_16x16x32_f16 v[80:83], v[92:95], v[80:83], 0
	v_mfma_f32_16x16x32_f16 v[68:71], v[68:71], v[88:91], 0
	v_mfma_f32_16x16x32_f16 v[76:79], v[76:79], v[88:91], 0
	v_mfma_f32_16x16x32_f16 v[84:87], v[84:87], v[88:91], 0
	v_mfma_f32_16x16x32_f16 v[88:91], v[92:95], v[88:91], 0
	ds_read_b128 v[92:95], v129
	ds_read_b128 v[194:197], v130 offset:32768
	ds_read_b128 v[198:201], v129 offset:2048
	ds_read_b128 v[202:205], v130 offset:34816
	ds_read_b128 v[206:209], v129 offset:4096
	ds_read_b128 v[210:213], v130 offset:36864
	ds_read_b128 v[220:223], v129 offset:6144
	ds_read_b128 v[224:227], v130 offset:38912
	s_waitcnt vmcnt(15)
	ds_write_b128 v126, v[32:35] offset:16384
	s_waitcnt vmcnt(14)
	ds_write_b128 v124, v[36:39] offset:16384
	s_waitcnt vmcnt(13)
	ds_write_b128 v125, v[40:43] offset:16384
	s_waitcnt vmcnt(12)
	ds_write_b128 v127, v[44:47] offset:16384
	s_waitcnt vmcnt(11)
	ds_write_b128 v126, v[48:51] offset:49152
	s_waitcnt vmcnt(10)
	ds_write_b128 v124, v[52:55] offset:49152
	s_waitcnt vmcnt(9)
	ds_write_b128 v125, v[56:59] offset:49152
	s_waitcnt vmcnt(8)
	ds_write_b128 v127, v[60:63] offset:49152
	s_waitcnt lgkmcnt(0)
	s_barrier
	v_mfma_f32_16x16x32_f16 v[132:135], v[194:197], v[92:95], v[132:135]
	global_load_dwordx4 v[32:35], v[104:105], off offset:384
	v_mfma_f32_16x16x32_f16 v[136:139], v[202:205], v[92:95], v[136:139]
	v_mfma_f32_16x16x32_f16 v[140:143], v[210:213], v[92:95], v[140:143]
	v_mfma_f32_16x16x32_f16 v[64:67], v[224:227], v[92:95], v[64:67]
	v_mfma_f32_16x16x32_f16 v[92:95], v[194:197], v[198:201], v[144:147]
	global_load_dwordx4 v[36:39], v[106:107], off offset:384
	global_load_dwordx4 v[40:43], v[108:109], off offset:384
	global_load_dwordx4 v[44:47], v[110:111], off offset:384
	v_mfma_f32_16x16x32_f16 v[144:147], v[202:205], v[198:201], v[154:157]
	global_load_dwordx4 v[48:51], v[112:113], off offset:384
	v_mfma_f32_16x16x32_f16 v[154:157], v[210:213], v[198:201], v[158:161]
	v_mfma_f32_16x16x32_f16 v[158:161], v[194:197], v[206:209], v[162:165]
	global_load_dwordx4 v[52:55], v[114:115], off offset:384
	global_load_dwordx4 v[56:59], v[116:117], off offset:384
	v_mfma_f32_16x16x32_f16 v[68:71], v[194:197], v[220:223], v[68:71]
	ds_read_b128 v[194:197], v131 offset:49152
	v_mfma_f32_16x16x32_f16 v[162:165], v[202:205], v[206:209], v[166:169]
	global_load_dwordx4 v[60:63], v[118:119], off offset:384
	v_mfma_f32_16x16x32_f16 v[76:79], v[202:205], v[220:223], v[76:79]
	ds_read_b128 v[202:205], v131 offset:51200
	s_waitcnt vmcnt(15)
	ds_write_b128 v126, v[0:3]
	s_waitcnt vmcnt(14)
	ds_write_b128 v124, v[4:7]
	s_waitcnt vmcnt(13)
	ds_write_b128 v125, v[8:11]
	v_mfma_f32_16x16x32_f16 v[72:75], v[224:227], v[198:201], v[72:75]
	ds_read_b128 v[198:201], v128 offset:18432
	v_mfma_f32_16x16x32_f16 v[166:169], v[210:213], v[206:209], v[190:193]
	s_nop 2
	ds_read_b128 v[190:193], v128 offset:16384
	v_mfma_f32_16x16x32_f16 v[84:87], v[210:213], v[220:223], v[84:87]
	ds_read_b128 v[210:213], v131 offset:53248
	v_mfma_f32_16x16x32_f16 v[80:83], v[224:227], v[206:209], v[80:83]
	ds_read_b128 v[206:209], v128 offset:20480
	v_mfma_f32_16x16x32_f16 v[88:91], v[224:227], v[220:223], v[88:91]
	ds_read_b128 v[220:223], v128 offset:22528
	s_waitcnt lgkmcnt(3)
	v_mfma_f32_16x16x32_f16 v[132:135], v[194:197], v[190:193], v[132:135]
	ds_read_b128 v[224:227], v131 offset:55296
	v_mfma_f32_16x16x32_f16 v[92:95], v[194:197], v[198:201], v[92:95]
	s_waitcnt vmcnt(12)
	ds_write_b128 v127, v[12:15]
	v_mfma_f32_16x16x32_f16 v[136:139], v[202:205], v[190:193], v[136:139]
	s_waitcnt vmcnt(11)
	ds_write_b128 v126, v[16:19] offset:32768
	v_mfma_f32_16x16x32_f16 v[144:147], v[202:205], v[198:201], v[144:147]
	s_waitcnt vmcnt(10)
	ds_write_b128 v124, v[20:23] offset:32768
	s_waitcnt lgkmcnt(5)
	v_mfma_f32_16x16x32_f16 v[158:161], v[194:197], v[206:209], v[158:161]
	s_waitcnt vmcnt(9)
	ds_write_b128 v125, v[24:27] offset:32768
	s_waitcnt lgkmcnt(5)
	v_mfma_f32_16x16x32_f16 v[68:71], v[194:197], v[220:223], v[68:71]
	ds_read_b128 v[194:197], v130 offset:49152
	v_mfma_f32_16x16x32_f16 v[162:165], v[202:205], v[206:209], v[162:165]
	s_waitcnt vmcnt(8)
	ds_write_b128 v127, v[28:31] offset:32768
	v_mfma_f32_16x16x32_f16 v[76:79], v[202:205], v[220:223], v[76:79]
	ds_read_b128 v[202:205], v130 offset:51200
	v_mfma_f32_16x16x32_f16 v[140:143], v[210:213], v[190:193], v[140:143]
	v_mfma_f32_16x16x32_f16 v[154:157], v[210:213], v[198:201], v[154:157]
	s_waitcnt lgkmcnt(7)
	v_mfma_f32_16x16x32_f16 v[64:67], v[224:227], v[190:193], v[64:67]
	ds_read_b128 v[190:193], v129 offset:16384
	v_mfma_f32_16x16x32_f16 v[72:75], v[224:227], v[198:201], v[72:75]
	ds_read_b128 v[198:201], v129 offset:18432
	v_mfma_f32_16x16x32_f16 v[166:169], v[210:213], v[206:209], v[166:169]
	v_mfma_f32_16x16x32_f16 v[84:87], v[210:213], v[220:223], v[84:87]
	ds_read_b128 v[210:213], v130 offset:53248
	v_mfma_f32_16x16x32_f16 v[80:83], v[224:227], v[206:209], v[80:83]
	ds_read_b128 v[206:209], v129 offset:20480
	v_mfma_f32_16x16x32_f16 v[88:91], v[224:227], v[220:223], v[88:91]
	ds_read_b128 v[220:223], v129 offset:22528
	ds_read_b128 v[224:227], v130 offset:55296
	s_waitcnt lgkmcnt(0)
	s_barrier
; #define GL_LOAD(s_, kt_) if (VAR != 1) { a##s_##0 = GL_A(0, kt_); a##s_##1 = GL_A(1, kt_); a##s_##2 = GL_A(2, kt_); a##s_##3 = GL_A(3, kt_); b##s_##0 = GL_B(0, kt_); b##s_##1 = GL_B(1, kt_); b##s_##2 = GL_B(2, kt_); b##s_##3 = GL_B(3, kt_); }
; #define LDS_STORE(s_, buf_) if (VAR != 2) { LDS_ST1(sA, 0, buf_, a##s_##0) LDS_ST1(sA, 1, buf_, a##s_##1) LDS_ST1(sA, 2, buf_, a##s_##2) LDS_ST1(sA, 3, buf_, a##s_##3) LDS_ST1(sB, 0, buf_, b##s_##0) LDS_ST1(sB, 1, buf_, b##s_##1) LDS_ST1(sB, 2, buf_, b##s_##2) LDS_ST1(sB, 3, buf_, b##s_##3) }
;     ...
;   for (int kt = 0; kt < nk; kt += 2) {
;     if (kt + 2 < nk) { GL_LOAD(0, kt + 2) }
;     MMA_TILE(0)
;     LDS_STORE(1, 1)
;     if (VAR != 4) __syncthreads();
;     if (kt + 3 < nk) { GL_LOAD(1, kt + 3) }
;     MMA_TILE(1)
;     if (kt + 2 < nk) { LDS_STORE(0, 0) }
;     if (VAR != 4) __syncthreads();
	v_mfma_f32_16x16x32_f16 v[132:135], v[194:197], v[190:193], v[132:135]
	global_load_dwordx4 v[0:3], v[104:105], off offset:512
	v_mfma_f32_16x16x32_f16 v[92:95], v[194:197], v[198:201], v[92:95]
	global_load_dwordx4 v[4:7], v[106:107], off offset:512
	v_mfma_f32_16x16x32_f16 v[136:139], v[202:205], v[190:193], v[136:139]
	global_load_dwordx4 v[8:11], v[108:109], off offset:512
	v_mfma_f32_16x16x32_f16 v[144:147], v[202:205], v[198:201], v[144:147]
	global_load_dwordx4 v[12:15], v[110:111], off offset:512
	v_mfma_f32_16x16x32_f16 v[158:161], v[194:197], v[206:209], v[158:161]
	global_load_dwordx4 v[16:19], v[112:113], off offset:512
	v_mfma_f32_16x16x32_f16 v[68:71], v[194:197], v[220:223], v[68:71]
	ds_read_b128 v[194:197], v131 offset:32768
	v_mfma_f32_16x16x32_f16 v[162:165], v[202:205], v[206:209], v[162:165]
	global_load_dwordx4 v[20:23], v[114:115], off offset:512
	v_mfma_f32_16x16x32_f16 v[76:79], v[202:205], v[220:223], v[76:79]
	ds_read_b128 v[202:205], v131 offset:34816
	v_mfma_f32_16x16x32_f16 v[140:143], v[210:213], v[190:193], v[140:143]
	global_load_dwordx4 v[24:27], v[116:117], off offset:512
	v_mfma_f32_16x16x32_f16 v[154:157], v[210:213], v[198:201], v[154:157]
	global_load_dwordx4 v[28:31], v[118:119], off offset:512
	v_mfma_f32_16x16x32_f16 v[64:67], v[224:227], v[190:193], v[64:67]
	ds_read_b128 v[190:193], v128
	v_mfma_f32_16x16x32_f16 v[72:75], v[224:227], v[198:201], v[72:75]
	ds_read_b128 v[198:201], v128 offset:2048
	v_mfma_f32_16x16x32_f16 v[166:169], v[210:213], v[206:209], v[166:169]
	s_waitcnt vmcnt(15)
	ds_write_b128 v126, v[32:35] offset:16384
	v_mfma_f32_16x16x32_f16 v[84:87], v[210:213], v[220:223], v[84:87]
	ds_read_b128 v[210:213], v131 offset:36864
	v_mfma_f32_16x16x32_f16 v[80:83], v[224:227], v[206:209], v[80:83]
	ds_read_b128 v[206:209], v128 offset:4096
	v_mfma_f32_16x16x32_f16 v[88:91], v[224:227], v[220:223], v[88:91]
	ds_read_b128 v[220:223], v128 offset:6144
	s_waitcnt lgkmcnt(5)
	v_mfma_f32_16x16x32_f16 v[132:135], v[194:197], v[190:193], v[132:135]
	ds_read_b128 v[224:227], v131 offset:38912
	s_waitcnt lgkmcnt(5)
	v_mfma_f32_16x16x32_f16 v[92:95], v[194:197], v[198:201], v[92:95]
	s_waitcnt vmcnt(14)
	ds_write_b128 v124, v[36:39] offset:16384
	v_mfma_f32_16x16x32_f16 v[136:139], v[202:205], v[190:193], v[136:139]
	s_waitcnt vmcnt(13)
	ds_write_b128 v125, v[40:43] offset:16384
	v_mfma_f32_16x16x32_f16 v[144:147], v[202:205], v[198:201], v[144:147]
	s_waitcnt vmcnt(12)
	ds_write_b128 v127, v[44:47] offset:16384
	s_waitcnt lgkmcnt(5)
	v_mfma_f32_16x16x32_f16 v[158:161], v[194:197], v[206:209], v[158:161]
	s_waitcnt vmcnt(11)
	ds_write_b128 v126, v[48:51] offset:49152
	s_waitcnt lgkmcnt(5)
	v_mfma_f32_16x16x32_f16 v[68:71], v[194:197], v[220:223], v[68:71]
	ds_read_b128 v[194:197], v130 offset:32768
	v_mfma_f32_16x16x32_f16 v[162:165], v[202:205], v[206:209], v[162:165]
	s_waitcnt vmcnt(10)
	ds_write_b128 v124, v[52:55] offset:49152
	v_mfma_f32_16x16x32_f16 v[76:79], v[202:205], v[220:223], v[76:79]
	ds_read_b128 v[202:205], v130 offset:34816
	v_mfma_f32_16x16x32_f16 v[140:143], v[210:213], v[190:193], v[140:143]
	s_waitcnt vmcnt(9)
	ds_write_b128 v125, v[56:59] offset:49152
	v_mfma_f32_16x16x32_f16 v[154:157], v[210:213], v[198:201], v[154:157]
	s_waitcnt vmcnt(8)
	ds_write_b128 v127, v[60:63] offset:49152
	s_waitcnt lgkmcnt(9)
	v_mfma_f32_16x16x32_f16 v[64:67], v[224:227], v[190:193], v[64:67]
	ds_read_b128 v[190:193], v129
	v_mfma_f32_16x16x32_f16 v[72:75], v[224:227], v[198:201], v[72:75]
	ds_read_b128 v[198:201], v129 offset:2048
	v_mfma_f32_16x16x32_f16 v[166:169], v[210:213], v[206:209], v[166:169]
	v_mfma_f32_16x16x32_f16 v[84:87], v[210:213], v[220:223], v[84:87]
	ds_read_b128 v[210:213], v130 offset:36864
	v_mfma_f32_16x16x32_f16 v[80:83], v[224:227], v[206:209], v[80:83]
	ds_read_b128 v[206:209], v129 offset:4096
	v_mfma_f32_16x16x32_f16 v[88:91], v[224:227], v[220:223], v[88:91]
	ds_read_b128 v[220:223], v129 offset:6144
	ds_read_b128 v[224:227], v130 offset:38912
	s_waitcnt lgkmcnt(0)
	s_barrier
	v_mfma_f32_16x16x32_f16 v[132:135], v[194:197], v[190:193], v[132:135]
	global_load_dwordx4 v[32:35], v[104:105], off offset:640
	v_mfma_f32_16x16x32_f16 v[92:95], v[194:197], v[198:201], v[92:95]
	global_load_dwordx4 v[36:39], v[106:107], off offset:640
	v_mfma_f32_16x16x32_f16 v[136:139], v[202:205], v[190:193], v[136:139]
	global_load_dwordx4 v[40:43], v[108:109], off offset:640
	v_mfma_f32_16x16x32_f16 v[144:147], v[202:205], v[198:201], v[144:147]
	global_load_dwordx4 v[44:47], v[110:111], off offset:640
	v_mfma_f32_16x16x32_f16 v[158:161], v[194:197], v[206:209], v[158:161]
	global_load_dwordx4 v[48:51], v[112:113], off offset:640
	v_mfma_f32_16x16x32_f16 v[68:71], v[194:197], v[220:223], v[68:71]
	ds_read_b128 v[194:197], v131 offset:49152
	v_mfma_f32_16x16x32_f16 v[162:165], v[202:205], v[206:209], v[162:165]
	global_load_dwordx4 v[52:55], v[114:115], off offset:640
	v_mfma_f32_16x16x32_f16 v[76:79], v[202:205], v[220:223], v[76:79]
	ds_read_b128 v[202:205], v131 offset:51200
	v_mfma_f32_16x16x32_f16 v[140:143], v[210:213], v[190:193], v[140:143]
	global_load_dwordx4 v[56:59], v[116:117], off offset:640
	v_mfma_f32_16x16x32_f16 v[154:157], v[210:213], v[198:201], v[154:157]
	global_load_dwordx4 v[60:63], v[118:119], off offset:640
	v_mfma_f32_16x16x32_f16 v[64:67], v[224:227], v[190:193], v[64:67]
	ds_read_b128 v[190:193], v128 offset:16384
	v_mfma_f32_16x16x32_f16 v[72:75], v[224:227], v[198:201], v[72:75]
	ds_read_b128 v[198:201], v128 offset:18432
	v_mfma_f32_16x16x32_f16 v[166:169], v[210:213], v[206:209], v[166:169]
	s_waitcnt vmcnt(15)
; #define GL_LOAD(s_, kt_) if (VAR != 1) { a##s_##0 = GL_A(0, kt_); a##s_##1 = GL_A(1, kt_); a##s_##2 = GL_A(2, kt_); a##s_##3 = GL_A(3, kt_); b##s_##0 = GL_B(0, kt_); b##s_##1 = GL_B(1, kt_); b##s_##2 = GL_B(2, kt_); b##s_##3 = GL_B(3, kt_); }
; #define LDS_STORE(s_, buf_) if (VAR != 2) { LDS_ST1(sA, 0, buf_, a##s_##0) LDS_ST1(sA, 1, buf_, a##s_##1) LDS_ST1(sA, 2, buf_, a##s_##2) LDS_ST1(sA, 3, buf_, a##s_##3) LDS_ST1(sB, 0, buf_, b##s_##0) LDS_ST1(sB, 1, buf_, b##s_##1) LDS_ST1(sB, 2, buf_, b##s_##2) LDS_ST1(sB, 3, buf_, b##s_##3) }
;     ...
;   for (int kt = 0; kt < nk; kt += 2) {
;     if (kt + 2 < nk) { GL_LOAD(0, kt + 2) }
;     MMA_TILE(0)
;     LDS_STORE(1, 1)
;     if (VAR != 4) __syncthreads();
;     if (kt + 3 < nk) { GL_LOAD(1, kt + 3) }
;     MMA_TILE(1)
;     if (kt + 2 < nk) { LDS_STORE(0, 0) }
;     if (VAR != 4) __syncthreads();
	ds_write_b128 v126, v[0:3]
	v_mfma_f32_16x16x32_f16 v[84:87], v[210:213], v[220:223], v[84:87]
	ds_read_b128 v[210:213], v131 offset:53248
	v_mfma_f32_16x16x32_f16 v[80:83], v[224:227], v[206:209], v[80:83]
	ds_read_b128 v[206:209], v128 offset:20480
	v_mfma_f32_16x16x32_f16 v[88:91], v[224:227], v[220:223], v[88:91]
	ds_read_b128 v[220:223], v128 offset:22528
	s_waitcnt lgkmcnt(5)
	v_mfma_f32_16x16x32_f16 v[132:135], v[194:197], v[190:193], v[132:135]
	ds_read_b128 v[224:227], v131 offset:55296
	s_waitcnt lgkmcnt(5)
	v_mfma_f32_16x16x32_f16 v[92:95], v[194:197], v[198:201], v[92:95]
	s_waitcnt vmcnt(14)
	ds_write_b128 v124, v[4:7]
	v_mfma_f32_16x16x32_f16 v[136:139], v[202:205], v[190:193], v[136:139]
	s_waitcnt vmcnt(13)
	ds_write_b128 v125, v[8:11]
	v_mfma_f32_16x16x32_f16 v[144:147], v[202:205], v[198:201], v[144:147]
	s_waitcnt vmcnt(12)
	ds_write_b128 v127, v[12:15]
	s_waitcnt lgkmcnt(5)
	v_mfma_f32_16x16x32_f16 v[158:161], v[194:197], v[206:209], v[158:161]
	s_waitcnt vmcnt(11)
	ds_write_b128 v126, v[16:19] offset:32768
	s_waitcnt lgkmcnt(5)
	v_mfma_f32_16x16x32_f16 v[68:71], v[194:197], v[220:223], v[68:71]
	ds_read_b128 v[194:197], v130 offset:49152
	v_mfma_f32_16x16x32_f16 v[162:165], v[202:205], v[206:209], v[162:165]
	s_waitcnt vmcnt(10)
	ds_write_b128 v124, v[20:23] offset:32768
	v_mfma_f32_16x16x32_f16 v[76:79], v[202:205], v[220:223], v[76:79]
	ds_read_b128 v[202:205], v130 offset:51200
	v_mfma_f32_16x16x32_f16 v[140:143], v[210:213], v[190:193], v[140:143]
	s_waitcnt vmcnt(9)
	ds_write_b128 v125, v[24:27] offset:32768
	v_mfma_f32_16x16x32_f16 v[154:157], v[210:213], v[198:201], v[154:157]
	s_waitcnt vmcnt(8)
	ds_write_b128 v127, v[28:31] offset:32768
	s_waitcnt lgkmcnt(9)
	v_mfma_f32_16x16x32_f16 v[64:67], v[224:227], v[190:193], v[64:67]
	ds_read_b128 v[190:193], v129 offset:16384
	v_mfma_f32_16x16x32_f16 v[72:75], v[224:227], v[198:201], v[72:75]
	ds_read_b128 v[198:201], v129 offset:18432
	v_mfma_f32_16x16x32_f16 v[166:169], v[210:213], v[206:209], v[166:169]
	v_mfma_f32_16x16x32_f16 v[84:87], v[210:213], v[220:223], v[84:87]
	ds_read_b128 v[210:213], v130 offset:53248
	v_mfma_f32_16x16x32_f16 v[80:83], v[224:227], v[206:209], v[80:83]
	ds_read_b128 v[206:209], v129 offset:20480
	v_mfma_f32_16x16x32_f16 v[88:91], v[224:227], v[220:223], v[88:91]
	ds_read_b128 v[220:223], v129 offset:22528
	ds_read_b128 v[224:227], v130 offset:55296
	s_waitcnt lgkmcnt(0)
	s_barrier
	v_mfma_f32_16x16x32_f16 v[132:135], v[194:197], v[190:193], v[132:135]
	global_load_dwordx4 v[0:3], v[104:105], off offset:768
	v_mfma_f32_16x16x32_f16 v[92:95], v[194:197], v[198:201], v[92:95]
	global_load_dwordx4 v[4:7], v[106:107], off offset:768
	v_mfma_f32_16x16x32_f16 v[136:139], v[202:205], v[190:193], v[136:139]
	global_load_dwordx4 v[8:11], v[108:109], off offset:768
	v_mfma_f32_16x16x32_f16 v[144:147], v[202:205], v[198:201], v[144:147]
	global_load_dwordx4 v[12:15], v[110:111], off offset:768
	v_mfma_f32_16x16x32_f16 v[158:161], v[194:197], v[206:209], v[158:161]
	global_load_dwordx4 v[16:19], v[112:113], off offset:768
	v_mfma_f32_16x16x32_f16 v[68:71], v[194:197], v[220:223], v[68:71]
	ds_read_b128 v[194:197], v131 offset:32768
	v_mfma_f32_16x16x32_f16 v[162:165], v[202:205], v[206:209], v[162:165]
	global_load_dwordx4 v[20:23], v[114:115], off offset:768
	v_mfma_f32_16x16x32_f16 v[76:79], v[202:205], v[220:223], v[76:79]
	ds_read_b128 v[202:205], v131 offset:34816
	v_mfma_f32_16x16x32_f16 v[140:143], v[210:213], v[190:193], v[140:143]
	global_load_dwordx4 v[24:27], v[116:117], off offset:768
	v_mfma_f32_16x16x32_f16 v[154:157], v[210:213], v[198:201], v[154:157]
	global_load_dwordx4 v[28:31], v[118:119], off offset:768
	v_mfma_f32_16x16x32_f16 v[64:67], v[224:227], v[190:193], v[64:67]
	ds_read_b128 v[190:193], v128
	v_mfma_f32_16x16x32_f16 v[72:75], v[224:227], v[198:201], v[72:75]
	ds_read_b128 v[198:201], v128 offset:2048
	v_mfma_f32_16x16x32_f16 v[166:169], v[210:213], v[206:209], v[166:169]
	s_waitcnt vmcnt(15)
	ds_write_b128 v126, v[32:35] offset:16384
	v_mfma_f32_16x16x32_f16 v[84:87], v[210:213], v[220:223], v[84:87]
	ds_read_b128 v[210:213], v131 offset:36864
	v_mfma_f32_16x16x32_f16 v[80:83], v[224:227], v[206:209], v[80:83]
	ds_read_b128 v[206:209], v128 offset:4096
	v_mfma_f32_16x16x32_f16 v[88:91], v[224:227], v[220:223], v[88:91]
	ds_read_b128 v[220:223], v128 offset:6144
	s_waitcnt lgkmcnt(5)
	v_mfma_f32_16x16x32_f16 v[132:135], v[194:197], v[190:193], v[132:135]
	ds_read_b128 v[224:227], v131 offset:38912
	s_waitcnt lgkmcnt(5)
	v_mfma_f32_16x16x32_f16 v[92:95], v[194:197], v[198:201], v[92:95]
	s_waitcnt vmcnt(14)
	ds_write_b128 v124, v[36:39] offset:16384
	v_mfma_f32_16x16x32_f16 v[136:139], v[202:205], v[190:193], v[136:139]
	s_waitcnt vmcnt(13)
	ds_write_b128 v125, v[40:43] offset:16384
	v_mfma_f32_16x16x32_f16 v[144:147], v[202:205], v[198:201], v[144:147]
	s_waitcnt vmcnt(12)
	ds_write_b128 v127, v[44:47] offset:16384
	s_waitcnt lgkmcnt(5)
	v_mfma_f32_16x16x32_f16 v[158:161], v[194:197], v[206:209], v[158:161]
	s_waitcnt vmcnt(11)
	ds_write_b128 v126, v[48:51] offset:49152
	s_waitcnt lgkmcnt(5)
	v_mfma_f32_16x16x32_f16 v[68:71], v[194:197], v[220:223], v[68:71]
	ds_read_b128 v[194:197], v130 offset:32768
	v_mfma_f32_16x16x32_f16 v[162:165], v[202:205], v[206:209], v[162:165]
	s_waitcnt vmcnt(10)
	ds_write_b128 v124, v[52:55] offset:49152
	v_mfma_f32_16x16x32_f16 v[76:79], v[202:205], v[220:223], v[76:79]
	ds_read_b128 v[202:205], v130 offset:34816
	v_mfma_f32_16x16x32_f16 v[140:143], v[210:213], v[190:193], v[140:143]
	s_waitcnt vmcnt(9)
	ds_write_b128 v125, v[56:59] offset:49152
	v_mfma_f32_16x16x32_f16 v[154:157], v[210:213], v[198:201], v[154:157]
	s_waitcnt vmcnt(8)
	ds_write_b128 v127, v[60:63] offset:49152
	s_waitcnt lgkmcnt(9)
	v_mfma_f32_16x16x32_f16 v[64:67], v[224:227], v[190:193], v[64:67]
	ds_read_b128 v[190:193], v129
	v_mfma_f32_16x16x32_f16 v[72:75], v[224:227], v[198:201], v[72:75]
	ds_read_b128 v[198:201], v129 offset:2048
	v_mfma_f32_16x16x32_f16 v[166:169], v[210:213], v[206:209], v[166:169]
	v_mfma_f32_16x16x32_f16 v[84:87], v[210:213], v[220:223], v[84:87]
	ds_read_b128 v[210:213], v130 offset:36864
	v_mfma_f32_16x16x32_f16 v[80:83], v[224:227], v[206:209], v[80:83]
	ds_read_b128 v[206:209], v129 offset:4096
	v_mfma_f32_16x16x32_f16 v[88:91], v[224:227], v[220:223], v[88:91]
	ds_read_b128 v[220:223], v129 offset:6144
	ds_read_b128 v[224:227], v130 offset:38912
	s_waitcnt lgkmcnt(0)
	s_barrier
; #define GL_LOAD(s_, kt_) if (VAR != 1) { a##s_##0 = GL_A(0, kt_); a##s_##1 = GL_A(1, kt_); a##s_##2 = GL_A(2, kt_); a##s_##3 = GL_A(3, kt_); b##s_##0 = GL_B(0, kt_); b##s_##1 = GL_B(1, kt_); b##s_##2 = GL_B(2, kt_); b##s_##3 = GL_B(3, kt_); }
; #define LDS_STORE(s_, buf_) if (VAR != 2) { LDS_ST1(sA, 0, buf_, a##s_##0) LDS_ST1(sA, 1, buf_, a##s_##1) LDS_ST1(sA, 2, buf_, a##s_##2) LDS_ST1(sA, 3, buf_, a##s_##3) LDS_ST1(sB, 0, buf_, b##s_##0) LDS_ST1(sB, 1, buf_, b##s_##1) LDS_ST1(sB, 2, buf_, b##s_##2) LDS_ST1(sB, 3, buf_, b##s_##3) }
;     ...
;   for (int kt = 0; kt < nk; kt += 2) {
;     if (kt + 2 < nk) { GL_LOAD(0, kt + 2) }
;     MMA_TILE(0)
;     LDS_STORE(1, 1)
;     if (VAR != 4) __syncthreads();
;     if (kt + 3 < nk) { GL_LOAD(1, kt + 3) }
;     MMA_TILE(1)
;     if (kt + 2 < nk) { LDS_STORE(0, 0) }
;     if (VAR != 4) __syncthreads();
	v_mfma_f32_16x16x32_f16 v[132:135], v[194:197], v[190:193], v[132:135]
	global_load_dwordx4 v[32:35], v[104:105], off offset:896
	v_mfma_f32_16x16x32_f16 v[92:95], v[194:197], v[198:201], v[92:95]
	global_load_dwordx4 v[36:39], v[106:107], off offset:896
	v_mfma_f32_16x16x32_f16 v[136:139], v[202:205], v[190:193], v[136:139]
	global_load_dwordx4 v[40:43], v[108:109], off offset:896
	v_mfma_f32_16x16x32_f16 v[144:147], v[202:205], v[198:201], v[144:147]
	global_load_dwordx4 v[44:47], v[110:111], off offset:896
	v_mfma_f32_16x16x32_f16 v[158:161], v[194:197], v[206:209], v[158:161]
	global_load_dwordx4 v[48:51], v[112:113], off offset:896
	v_mfma_f32_16x16x32_f16 v[68:71], v[194:197], v[220:223], v[68:71]
	ds_read_b128 v[194:197], v131 offset:49152
	v_mfma_f32_16x16x32_f16 v[162:165], v[202:205], v[206:209], v[162:165]
	global_load_dwordx4 v[52:55], v[114:115], off offset:896
	v_mfma_f32_16x16x32_f16 v[76:79], v[202:205], v[220:223], v[76:79]
	ds_read_b128 v[202:205], v131 offset:51200
	v_mfma_f32_16x16x32_f16 v[140:143], v[210:213], v[190:193], v[140:143]
	global_load_dwordx4 v[56:59], v[116:117], off offset:896
	v_mfma_f32_16x16x32_f16 v[154:157], v[210:213], v[198:201], v[154:157]
	global_load_dwordx4 v[60:63], v[118:119], off offset:896
	v_mfma_f32_16x16x32_f16 v[64:67], v[224:227], v[190:193], v[64:67]
	ds_read_b128 v[190:193], v128 offset:16384
	v_mfma_f32_16x16x32_f16 v[72:75], v[224:227], v[198:201], v[72:75]
	ds_read_b128 v[198:201], v128 offset:18432
	v_mfma_f32_16x16x32_f16 v[166:169], v[210:213], v[206:209], v[166:169]
	s_waitcnt vmcnt(15)
	ds_write_b128 v126, v[0:3]
	v_mfma_f32_16x16x32_f16 v[84:87], v[210:213], v[220:223], v[84:87]
	ds_read_b128 v[210:213], v131 offset:53248
	v_mfma_f32_16x16x32_f16 v[80:83], v[224:227], v[206:209], v[80:83]
	ds_read_b128 v[206:209], v128 offset:20480
	v_mfma_f32_16x16x32_f16 v[88:91], v[224:227], v[220:223], v[88:91]
	ds_read_b128 v[220:223], v128 offset:22528
	s_waitcnt lgkmcnt(5)
	v_mfma_f32_16x16x32_f16 v[132:135], v[194:197], v[190:193], v[132:135]
	ds_read_b128 v[224:227], v131 offset:55296
	s_waitcnt lgkmcnt(5)
	v_mfma_f32_16x16x32_f16 v[92:95], v[194:197], v[198:201], v[92:95]
	s_waitcnt vmcnt(14)
	ds_write_b128 v124, v[4:7]
	v_mfma_f32_16x16x32_f16 v[136:139], v[202:205], v[190:193], v[136:139]
	s_waitcnt vmcnt(13)
	ds_write_b128 v125, v[8:11]
	v_mfma_f32_16x16x32_f16 v[144:147], v[202:205], v[198:201], v[144:147]
	s_waitcnt vmcnt(12)
	ds_write_b128 v127, v[12:15]
	s_waitcnt lgkmcnt(5)
	v_mfma_f32_16x16x32_f16 v[158:161], v[194:197], v[206:209], v[158:161]
	s_waitcnt vmcnt(11)
	ds_write_b128 v126, v[16:19] offset:32768
	s_waitcnt lgkmcnt(5)
	v_mfma_f32_16x16x32_f16 v[68:71], v[194:197], v[220:223], v[68:71]
	ds_read_b128 v[194:197], v130 offset:49152
	v_mfma_f32_16x16x32_f16 v[162:165], v[202:205], v[206:209], v[162:165]
	s_waitcnt vmcnt(10)
	ds_write_b128 v124, v[20:23] offset:32768
	v_mfma_f32_16x16x32_f16 v[76:79], v[202:205], v[220:223], v[76:79]
	ds_read_b128 v[202:205], v130 offset:51200
	v_mfma_f32_16x16x32_f16 v[140:143], v[210:213], v[190:193], v[140:143]
	s_waitcnt vmcnt(9)
	ds_write_b128 v125, v[24:27] offset:32768
	v_mfma_f32_16x16x32_f16 v[154:157], v[210:213], v[198:201], v[154:157]
	s_waitcnt vmcnt(8)
	ds_write_b128 v127, v[28:31] offset:32768
	s_waitcnt lgkmcnt(9)
	v_mfma_f32_16x16x32_f16 v[64:67], v[224:227], v[190:193], v[64:67]
	ds_read_b128 v[190:193], v129 offset:16384
	v_mfma_f32_16x16x32_f16 v[72:75], v[224:227], v[198:201], v[72:75]
	ds_read_b128 v[198:201], v129 offset:18432
	v_mfma_f32_16x16x32_f16 v[166:169], v[210:213], v[206:209], v[166:169]
	v_mfma_f32_16x16x32_f16 v[84:87], v[210:213], v[220:223], v[84:87]
	ds_read_b128 v[210:213], v130 offset:53248
	v_mfma_f32_16x16x32_f16 v[80:83], v[224:227], v[206:209], v[80:83]
	ds_read_b128 v[206:209], v129 offset:20480
	v_mfma_f32_16x16x32_f16 v[88:91], v[224:227], v[220:223], v[88:91]
	ds_read_b128 v[220:223], v129 offset:22528
	ds_read_b128 v[224:227], v130 offset:55296
	s_waitcnt lgkmcnt(0)
	s_barrier
	v_mfma_f32_16x16x32_f16 v[132:135], v[194:197], v[190:193], v[132:135]
	global_load_dwordx4 v[0:3], v[104:105], off offset:1024
	v_mfma_f32_16x16x32_f16 v[92:95], v[194:197], v[198:201], v[92:95]
	global_load_dwordx4 v[4:7], v[106:107], off offset:1024
	v_mfma_f32_16x16x32_f16 v[136:139], v[202:205], v[190:193], v[136:139]
	global_load_dwordx4 v[8:11], v[108:109], off offset:1024
	v_mfma_f32_16x16x32_f16 v[144:147], v[202:205], v[198:201], v[144:147]
	global_load_dwordx4 v[12:15], v[110:111], off offset:1024
	v_mfma_f32_16x16x32_f16 v[158:161], v[194:197], v[206:209], v[158:161]
	global_load_dwordx4 v[16:19], v[112:113], off offset:1024
	v_mfma_f32_16x16x32_f16 v[68:71], v[194:197], v[220:223], v[68:71]
	ds_read_b128 v[194:197], v131 offset:32768
	v_mfma_f32_16x16x32_f16 v[162:165], v[202:205], v[206:209], v[162:165]
	global_load_dwordx4 v[20:23], v[114:115], off offset:1024
	v_mfma_f32_16x16x32_f16 v[76:79], v[202:205], v[220:223], v[76:79]
	ds_read_b128 v[202:205], v131 offset:34816
	v_mfma_f32_16x16x32_f16 v[140:143], v[210:213], v[190:193], v[140:143]
	global_load_dwordx4 v[24:27], v[116:117], off offset:1024
	v_mfma_f32_16x16x32_f16 v[154:157], v[210:213], v[198:201], v[154:157]
	global_load_dwordx4 v[28:31], v[118:119], off offset:1024
	v_mfma_f32_16x16x32_f16 v[64:67], v[224:227], v[190:193], v[64:67]
	ds_read_b128 v[190:193], v128
	v_mfma_f32_16x16x32_f16 v[72:75], v[224:227], v[198:201], v[72:75]
	ds_read_b128 v[198:201], v128 offset:2048
	v_mfma_f32_16x16x32_f16 v[166:169], v[210:213], v[206:209], v[166:169]
	s_waitcnt vmcnt(15)
; #define GL_LOAD(s_, kt_) if (VAR != 1) { a##s_##0 = GL_A(0, kt_); a##s_##1 = GL_A(1, kt_); a##s_##2 = GL_A(2, kt_); a##s_##3 = GL_A(3, kt_); b##s_##0 = GL_B(0, kt_); b##s_##1 = GL_B(1, kt_); b##s_##2 = GL_B(2, kt_); b##s_##3 = GL_B(3, kt_); }
; #define LDS_STORE(s_, buf_) if (VAR != 2) { LDS_ST1(sA, 0, buf_, a##s_##0) LDS_ST1(sA, 1, buf_, a##s_##1) LDS_ST1(sA, 2, buf_, a##s_##2) LDS_ST1(sA, 3, buf_, a##s_##3) LDS_ST1(sB, 0, buf_, b##s_##0) LDS_ST1(sB, 1, buf_, b##s_##1) LDS_ST1(sB, 2, buf_, b##s_##2) LDS_ST1(sB, 3, buf_, b##s_##3) }
;     ...
;   for (int kt = 0; kt < nk; kt += 2) {
;     if (kt + 2 < nk) { GL_LOAD(0, kt + 2) }
;     MMA_TILE(0)
;     LDS_STORE(1, 1)
;     if (VAR != 4) __syncthreads();
;     if (kt + 3 < nk) { GL_LOAD(1, kt + 3) }
;     MMA_TILE(1)
;     if (kt + 2 < nk) { LDS_STORE(0, 0) }
;     if (VAR != 4) __syncthreads();
	ds_write_b128 v126, v[32:35] offset:16384
	v_mfma_f32_16x16x32_f16 v[84:87], v[210:213], v[220:223], v[84:87]
	ds_read_b128 v[210:213], v131 offset:36864
	v_mfma_f32_16x16x32_f16 v[80:83], v[224:227], v[206:209], v[80:83]
	ds_read_b128 v[206:209], v128 offset:4096
	v_mfma_f32_16x16x32_f16 v[88:91], v[224:227], v[220:223], v[88:91]
	ds_read_b128 v[220:223], v128 offset:6144
	s_waitcnt lgkmcnt(5)
	v_mfma_f32_16x16x32_f16 v[132:135], v[194:197], v[190:193], v[132:135]
	ds_read_b128 v[224:227], v131 offset:38912
	s_waitcnt lgkmcnt(5)
	v_mfma_f32_16x16x32_f16 v[92:95], v[194:197], v[198:201], v[92:95]
	s_waitcnt vmcnt(14)
	ds_write_b128 v124, v[36:39] offset:16384
	v_mfma_f32_16x16x32_f16 v[136:139], v[202:205], v[190:193], v[136:139]
	s_waitcnt vmcnt(13)
	ds_write_b128 v125, v[40:43] offset:16384
	v_mfma_f32_16x16x32_f16 v[144:147], v[202:205], v[198:201], v[144:147]
	s_waitcnt vmcnt(12)
	ds_write_b128 v127, v[44:47] offset:16384
	s_waitcnt lgkmcnt(5)
	v_mfma_f32_16x16x32_f16 v[158:161], v[194:197], v[206:209], v[158:161]
	s_waitcnt vmcnt(11)
	ds_write_b128 v126, v[48:51] offset:49152
	s_waitcnt lgkmcnt(5)
	v_mfma_f32_16x16x32_f16 v[68:71], v[194:197], v[220:223], v[68:71]
	ds_read_b128 v[194:197], v130 offset:32768
	v_mfma_f32_16x16x32_f16 v[162:165], v[202:205], v[206:209], v[162:165]
	s_waitcnt vmcnt(10)
	ds_write_b128 v124, v[52:55] offset:49152
	v_mfma_f32_16x16x32_f16 v[76:79], v[202:205], v[220:223], v[76:79]
	ds_read_b128 v[202:205], v130 offset:34816
	v_mfma_f32_16x16x32_f16 v[140:143], v[210:213], v[190:193], v[140:143]
	s_waitcnt vmcnt(9)
	ds_write_b128 v125, v[56:59] offset:49152
	v_mfma_f32_16x16x32_f16 v[154:157], v[210:213], v[198:201], v[154:157]
	s_waitcnt vmcnt(8)
	ds_write_b128 v127, v[60:63] offset:49152
	s_waitcnt lgkmcnt(9)
	v_mfma_f32_16x16x32_f16 v[64:67], v[224:227], v[190:193], v[64:67]
	ds_read_b128 v[190:193], v129
	v_mfma_f32_16x16x32_f16 v[72:75], v[224:227], v[198:201], v[72:75]
	ds_read_b128 v[198:201], v129 offset:2048
	v_mfma_f32_16x16x32_f16 v[166:169], v[210:213], v[206:209], v[166:169]
	v_mfma_f32_16x16x32_f16 v[84:87], v[210:213], v[220:223], v[84:87]
	ds_read_b128 v[210:213], v130 offset:36864
	v_mfma_f32_16x16x32_f16 v[80:83], v[224:227], v[206:209], v[80:83]
	ds_read_b128 v[206:209], v129 offset:4096
	v_mfma_f32_16x16x32_f16 v[88:91], v[224:227], v[220:223], v[88:91]
	ds_read_b128 v[220:223], v129 offset:6144
	ds_read_b128 v[224:227], v130 offset:38912
	s_waitcnt lgkmcnt(0)
	s_barrier
	v_mfma_f32_16x16x32_f16 v[132:135], v[194:197], v[190:193], v[132:135]
	global_load_dwordx4 v[32:35], v[104:105], off offset:1152
	v_mfma_f32_16x16x32_f16 v[92:95], v[194:197], v[198:201], v[92:95]
	global_load_dwordx4 v[36:39], v[106:107], off offset:1152
	v_mfma_f32_16x16x32_f16 v[136:139], v[202:205], v[190:193], v[136:139]
	global_load_dwordx4 v[40:43], v[108:109], off offset:1152
	v_mfma_f32_16x16x32_f16 v[144:147], v[202:205], v[198:201], v[144:147]
	global_load_dwordx4 v[44:47], v[110:111], off offset:1152
	v_mfma_f32_16x16x32_f16 v[158:161], v[194:197], v[206:209], v[158:161]
	global_load_dwordx4 v[48:51], v[112:113], off offset:1152
	v_mfma_f32_16x16x32_f16 v[68:71], v[194:197], v[220:223], v[68:71]
	ds_read_b128 v[194:197], v131 offset:49152
	v_mfma_f32_16x16x32_f16 v[162:165], v[202:205], v[206:209], v[162:165]
	global_load_dwordx4 v[52:55], v[114:115], off offset:1152
	v_mfma_f32_16x16x32_f16 v[76:79], v[202:205], v[220:223], v[76:79]
	ds_read_b128 v[202:205], v131 offset:51200
	v_mfma_f32_16x16x32_f16 v[140:143], v[210:213], v[190:193], v[140:143]
	global_load_dwordx4 v[56:59], v[116:117], off offset:1152
	v_mfma_f32_16x16x32_f16 v[154:157], v[210:213], v[198:201], v[154:157]
	global_load_dwordx4 v[60:63], v[118:119], off offset:1152
	v_mfma_f32_16x16x32_f16 v[64:67], v[224:227], v[190:193], v[64:67]
	ds_read_b128 v[190:193], v128 offset:16384
	v_mfma_f32_16x16x32_f16 v[72:75], v[224:227], v[198:201], v[72:75]
	ds_read_b128 v[198:201], v128 offset:18432
	v_mfma_f32_16x16x32_f16 v[166:169], v[210:213], v[206:209], v[166:169]
	s_waitcnt vmcnt(15)
	ds_write_b128 v126, v[0:3]
	v_mfma_f32_16x16x32_f16 v[84:87], v[210:213], v[220:223], v[84:87]
	ds_read_b128 v[210:213], v131 offset:53248
	v_mfma_f32_16x16x32_f16 v[80:83], v[224:227], v[206:209], v[80:83]
	ds_read_b128 v[206:209], v128 offset:20480
	v_mfma_f32_16x16x32_f16 v[88:91], v[224:227], v[220:223], v[88:91]
	ds_read_b128 v[220:223], v128 offset:22528
	s_waitcnt lgkmcnt(5)
	v_mfma_f32_16x16x32_f16 v[132:135], v[194:197], v[190:193], v[132:135]
	ds_read_b128 v[224:227], v131 offset:55296
	s_waitcnt lgkmcnt(5)
	v_mfma_f32_16x16x32_f16 v[92:95], v[194:197], v[198:201], v[92:95]
	s_waitcnt vmcnt(14)
	ds_write_b128 v124, v[4:7]
	v_mfma_f32_16x16x32_f16 v[136:139], v[202:205], v[190:193], v[136:139]
	s_waitcnt vmcnt(13)
	ds_write_b128 v125, v[8:11]
	v_mfma_f32_16x16x32_f16 v[144:147], v[202:205], v[198:201], v[144:147]
	s_waitcnt vmcnt(12)
	ds_write_b128 v127, v[12:15]
	s_waitcnt lgkmcnt(5)
	v_mfma_f32_16x16x32_f16 v[158:161], v[194:197], v[206:209], v[158:161]
	s_waitcnt vmcnt(11)
	ds_write_b128 v126, v[16:19] offset:32768
	s_waitcnt lgkmcnt(5)
	v_mfma_f32_16x16x32_f16 v[68:71], v[194:197], v[220:223], v[68:71]
	ds_read_b128 v[194:197], v130 offset:49152
	v_mfma_f32_16x16x32_f16 v[162:165], v[202:205], v[206:209], v[162:165]
	s_waitcnt vmcnt(10)
	ds_write_b128 v124, v[20:23] offset:32768
	v_mfma_f32_16x16x32_f16 v[76:79], v[202:205], v[220:223], v[76:79]
	ds_read_b128 v[202:205], v130 offset:51200
	v_mfma_f32_16x16x32_f16 v[140:143], v[210:213], v[190:193], v[140:143]
	s_waitcnt vmcnt(9)
	ds_write_b128 v125, v[24:27] offset:32768
	v_mfma_f32_16x16x32_f16 v[154:157], v[210:213], v[198:201], v[154:157]
	s_waitcnt vmcnt(8)
	ds_write_b128 v127, v[28:31] offset:32768
	s_waitcnt lgkmcnt(9)
	v_mfma_f32_16x16x32_f16 v[64:67], v[224:227], v[190:193], v[64:67]
	ds_read_b128 v[190:193], v129 offset:16384
	v_mfma_f32_16x16x32_f16 v[72:75], v[224:227], v[198:201], v[72:75]
	ds_read_b128 v[198:201], v129 offset:18432
	v_mfma_f32_16x16x32_f16 v[166:169], v[210:213], v[206:209], v[166:169]
	v_mfma_f32_16x16x32_f16 v[84:87], v[210:213], v[220:223], v[84:87]
	ds_read_b128 v[210:213], v130 offset:53248
	v_mfma_f32_16x16x32_f16 v[80:83], v[224:227], v[206:209], v[80:83]
	ds_read_b128 v[206:209], v129 offset:20480
	v_mfma_f32_16x16x32_f16 v[88:91], v[224:227], v[220:223], v[88:91]
	ds_read_b128 v[220:223], v129 offset:22528
	ds_read_b128 v[224:227], v130 offset:55296
	s_waitcnt lgkmcnt(0)
	s_barrier
; #define GL_LOAD(s_, kt_) if (VAR != 1) { a##s_##0 = GL_A(0, kt_); a##s_##1 = GL_A(1, kt_); a##s_##2 = GL_A(2, kt_); a##s_##3 = GL_A(3, kt_); b##s_##0 = GL_B(0, kt_); b##s_##1 = GL_B(1, kt_); b##s_##2 = GL_B(2, kt_); b##s_##3 = GL_B(3, kt_); }
; #define LDS_STORE(s_, buf_) if (VAR != 2) { LDS_ST1(sA, 0, buf_, a##s_##0) LDS_ST1(sA, 1, buf_, a##s_##1) LDS_ST1(sA, 2, buf_, a##s_##2) LDS_ST1(sA, 3, buf_, a##s_##3) LDS_ST1(sB, 0, buf_, b##s_##0) LDS_ST1(sB, 1, buf_, b##s_##1) LDS_ST1(sB, 2, buf_, b##s_##2) LDS_ST1(sB, 3, buf_, b##s_##3) }
;     ...
;   for (int kt = 0; kt < nk; kt += 2) {
;     if (kt + 2 < nk) { GL_LOAD(0, kt + 2) }
;     MMA_TILE(0)
;     LDS_STORE(1, 1)
;     if (VAR != 4) __syncthreads();
;     if (kt + 3 < nk) { GL_LOAD(1, kt + 3) }
;     MMA_TILE(1)
;     if (kt + 2 < nk) { LDS_STORE(0, 0) }
;     if (VAR != 4) __syncthreads();
	v_mfma_f32_16x16x32_f16 v[132:135], v[194:197], v[190:193], v[132:135]
	global_load_dwordx4 v[0:3], v[104:105], off offset:1280
	v_mfma_f32_16x16x32_f16 v[92:95], v[194:197], v[198:201], v[92:95]
	global_load_dwordx4 v[4:7], v[106:107], off offset:1280
	v_mfma_f32_16x16x32_f16 v[136:139], v[202:205], v[190:193], v[136:139]
	global_load_dwordx4 v[8:11], v[108:109], off offset:1280
	v_mfma_f32_16x16x32_f16 v[144:147], v[202:205], v[198:201], v[144:147]
	global_load_dwordx4 v[12:15], v[110:111], off offset:1280
	v_mfma_f32_16x16x32_f16 v[158:161], v[194:197], v[206:209], v[158:161]
	global_load_dwordx4 v[16:19], v[112:113], off offset:1280
	v_mfma_f32_16x16x32_f16 v[68:71], v[194:197], v[220:223], v[68:71]
	ds_read_b128 v[194:197], v131 offset:32768
	v_mfma_f32_16x16x32_f16 v[162:165], v[202:205], v[206:209], v[162:165]
	global_load_dwordx4 v[20:23], v[114:115], off offset:1280
	v_mfma_f32_16x16x32_f16 v[76:79], v[202:205], v[220:223], v[76:79]
	ds_read_b128 v[202:205], v131 offset:34816
	v_mfma_f32_16x16x32_f16 v[140:143], v[210:213], v[190:193], v[140:143]
	global_load_dwordx4 v[24:27], v[116:117], off offset:1280
	v_mfma_f32_16x16x32_f16 v[154:157], v[210:213], v[198:201], v[154:157]
	global_load_dwordx4 v[28:31], v[118:119], off offset:1280
	v_mfma_f32_16x16x32_f16 v[64:67], v[224:227], v[190:193], v[64:67]
	ds_read_b128 v[190:193], v128
	v_mfma_f32_16x16x32_f16 v[72:75], v[224:227], v[198:201], v[72:75]
	ds_read_b128 v[198:201], v128 offset:2048
	v_mfma_f32_16x16x32_f16 v[166:169], v[210:213], v[206:209], v[166:169]
	s_waitcnt vmcnt(15)
	ds_write_b128 v126, v[32:35] offset:16384
	v_mfma_f32_16x16x32_f16 v[84:87], v[210:213], v[220:223], v[84:87]
	ds_read_b128 v[210:213], v131 offset:36864
	v_mfma_f32_16x16x32_f16 v[80:83], v[224:227], v[206:209], v[80:83]
	ds_read_b128 v[206:209], v128 offset:4096
	v_mfma_f32_16x16x32_f16 v[88:91], v[224:227], v[220:223], v[88:91]
	ds_read_b128 v[220:223], v128 offset:6144
	s_waitcnt lgkmcnt(5)
	v_mfma_f32_16x16x32_f16 v[132:135], v[194:197], v[190:193], v[132:135]
	ds_read_b128 v[224:227], v131 offset:38912
	s_waitcnt lgkmcnt(5)
	v_mfma_f32_16x16x32_f16 v[92:95], v[194:197], v[198:201], v[92:95]
	s_waitcnt vmcnt(14)
	ds_write_b128 v124, v[36:39] offset:16384
	v_mfma_f32_16x16x32_f16 v[136:139], v[202:205], v[190:193], v[136:139]
	s_waitcnt vmcnt(13)
	ds_write_b128 v125, v[40:43] offset:16384
	v_mfma_f32_16x16x32_f16 v[144:147], v[202:205], v[198:201], v[144:147]
	s_waitcnt vmcnt(12)
	ds_write_b128 v127, v[44:47] offset:16384
	s_waitcnt lgkmcnt(5)
	v_mfma_f32_16x16x32_f16 v[158:161], v[194:197], v[206:209], v[158:161]
	s_waitcnt vmcnt(11)
	ds_write_b128 v126, v[48:51] offset:49152
	s_waitcnt lgkmcnt(5)
	v_mfma_f32_16x16x32_f16 v[68:71], v[194:197], v[220:223], v[68:71]
	ds_read_b128 v[194:197], v130 offset:32768
	v_mfma_f32_16x16x32_f16 v[162:165], v[202:205], v[206:209], v[162:165]
	s_waitcnt vmcnt(10)
	ds_write_b128 v124, v[52:55] offset:49152
	v_mfma_f32_16x16x32_f16 v[76:79], v[202:205], v[220:223], v[76:79]
	ds_read_b128 v[202:205], v130 offset:34816
	v_mfma_f32_16x16x32_f16 v[140:143], v[210:213], v[190:193], v[140:143]
	s_waitcnt vmcnt(9)
	ds_write_b128 v125, v[56:59] offset:49152
	v_mfma_f32_16x16x32_f16 v[154:157], v[210:213], v[198:201], v[154:157]
	s_waitcnt vmcnt(8)
	ds_write_b128 v127, v[60:63] offset:49152
	s_waitcnt lgkmcnt(9)
	v_mfma_f32_16x16x32_f16 v[64:67], v[224:227], v[190:193], v[64:67]
	ds_read_b128 v[190:193], v129
	v_mfma_f32_16x16x32_f16 v[72:75], v[224:227], v[198:201], v[72:75]
	ds_read_b128 v[198:201], v129 offset:2048
	v_mfma_f32_16x16x32_f16 v[166:169], v[210:213], v[206:209], v[166:169]
	v_mfma_f32_16x16x32_f16 v[84:87], v[210:213], v[220:223], v[84:87]
	ds_read_b128 v[210:213], v130 offset:36864
	v_mfma_f32_16x16x32_f16 v[80:83], v[224:227], v[206:209], v[80:83]
	ds_read_b128 v[206:209], v129 offset:4096
	v_mfma_f32_16x16x32_f16 v[88:91], v[224:227], v[220:223], v[88:91]
	ds_read_b128 v[220:223], v129 offset:6144
	ds_read_b128 v[224:227], v130 offset:38912
	s_waitcnt lgkmcnt(0)
	s_barrier
	v_mfma_f32_16x16x32_f16 v[132:135], v[194:197], v[190:193], v[132:135]
	global_load_dwordx4 v[32:35], v[104:105], off offset:1408
	v_mfma_f32_16x16x32_f16 v[92:95], v[194:197], v[198:201], v[92:95]
	global_load_dwordx4 v[36:39], v[106:107], off offset:1408
	v_mfma_f32_16x16x32_f16 v[136:139], v[202:205], v[190:193], v[136:139]
	global_load_dwordx4 v[40:43], v[108:109], off offset:1408
	v_mfma_f32_16x16x32_f16 v[144:147], v[202:205], v[198:201], v[144:147]
	global_load_dwordx4 v[44:47], v[110:111], off offset:1408
	v_mfma_f32_16x16x32_f16 v[158:161], v[194:197], v[206:209], v[158:161]
	global_load_dwordx4 v[48:51], v[112:113], off offset:1408
	v_mfma_f32_16x16x32_f16 v[68:71], v[194:197], v[220:223], v[68:71]
	ds_read_b128 v[194:197], v131 offset:49152
	v_mfma_f32_16x16x32_f16 v[162:165], v[202:205], v[206:209], v[162:165]
	global_load_dwordx4 v[52:55], v[114:115], off offset:1408
	v_mfma_f32_16x16x32_f16 v[76:79], v[202:205], v[220:223], v[76:79]
	ds_read_b128 v[202:205], v131 offset:51200
	v_mfma_f32_16x16x32_f16 v[140:143], v[210:213], v[190:193], v[140:143]
	global_load_dwordx4 v[56:59], v[116:117], off offset:1408
	v_mfma_f32_16x16x32_f16 v[154:157], v[210:213], v[198:201], v[154:157]
	global_load_dwordx4 v[60:63], v[118:119], off offset:1408
	v_mfma_f32_16x16x32_f16 v[64:67], v[224:227], v[190:193], v[64:67]
	ds_read_b128 v[190:193], v128 offset:16384
	v_mfma_f32_16x16x32_f16 v[72:75], v[224:227], v[198:201], v[72:75]
	ds_read_b128 v[198:201], v128 offset:18432
	v_mfma_f32_16x16x32_f16 v[166:169], v[210:213], v[206:209], v[166:169]
	s_waitcnt vmcnt(15)
; #define GL_LOAD(s_, kt_) if (VAR != 1) { a##s_##0 = GL_A(0, kt_); a##s_##1 = GL_A(1, kt_); a##s_##2 = GL_A(2, kt_); a##s_##3 = GL_A(3, kt_); b##s_##0 = GL_B(0, kt_); b##s_##1 = GL_B(1, kt_); b##s_##2 = GL_B(2, kt_); b##s_##3 = GL_B(3, kt_); }
; #define LDS_STORE(s_, buf_) if (VAR != 2) { LDS_ST1(sA, 0, buf_, a##s_##0) LDS_ST1(sA, 1, buf_, a##s_##1) LDS_ST1(sA, 2, buf_, a##s_##2) LDS_ST1(sA, 3, buf_, a##s_##3) LDS_ST1(sB, 0, buf_, b##s_##0) LDS_ST1(sB, 1, buf_, b##s_##1) LDS_ST1(sB, 2, buf_, b##s_##2) LDS_ST1(sB, 3, buf_, b##s_##3) }
;     ...
;   for (int kt = 0; kt < nk; kt += 2) {
;     if (kt + 2 < nk) { GL_LOAD(0, kt + 2) }
;     MMA_TILE(0)
;     LDS_STORE(1, 1)
;     if (VAR != 4) __syncthreads();
;     if (kt + 3 < nk) { GL_LOAD(1, kt + 3) }
;     MMA_TILE(1)
;     if (kt + 2 < nk) { LDS_STORE(0, 0) }
;     if (VAR != 4) __syncthreads();
	ds_write_b128 v126, v[0:3]
	v_mfma_f32_16x16x32_f16 v[84:87], v[210:213], v[220:223], v[84:87]
	ds_read_b128 v[210:213], v131 offset:53248
	v_mfma_f32_16x16x32_f16 v[80:83], v[224:227], v[206:209], v[80:83]
	ds_read_b128 v[206:209], v128 offset:20480
	v_mfma_f32_16x16x32_f16 v[88:91], v[224:227], v[220:223], v[88:91]
	ds_read_b128 v[220:223], v128 offset:22528
	s_waitcnt lgkmcnt(5)
	v_mfma_f32_16x16x32_f16 v[132:135], v[194:197], v[190:193], v[132:135]
	ds_read_b128 v[224:227], v131 offset:55296
	s_waitcnt lgkmcnt(5)
	v_mfma_f32_16x16x32_f16 v[92:95], v[194:197], v[198:201], v[92:95]
	s_waitcnt vmcnt(14)
	ds_write_b128 v124, v[4:7]
	v_mfma_f32_16x16x32_f16 v[136:139], v[202:205], v[190:193], v[136:139]
	s_waitcnt vmcnt(13)
	ds_write_b128 v125, v[8:11]
	v_mfma_f32_16x16x32_f16 v[144:147], v[202:205], v[198:201], v[144:147]
	s_waitcnt vmcnt(12)
	ds_write_b128 v127, v[12:15]
	s_waitcnt lgkmcnt(5)
	v_mfma_f32_16x16x32_f16 v[158:161], v[194:197], v[206:209], v[158:161]
	s_waitcnt vmcnt(11)
	ds_write_b128 v126, v[16:19] offset:32768
	s_waitcnt lgkmcnt(5)
	v_mfma_f32_16x16x32_f16 v[68:71], v[194:197], v[220:223], v[68:71]
	ds_read_b128 v[194:197], v130 offset:49152
	v_mfma_f32_16x16x32_f16 v[162:165], v[202:205], v[206:209], v[162:165]
	s_waitcnt vmcnt(10)
	ds_write_b128 v124, v[20:23] offset:32768
	v_mfma_f32_16x16x32_f16 v[76:79], v[202:205], v[220:223], v[76:79]
	ds_read_b128 v[202:205], v130 offset:51200
	v_mfma_f32_16x16x32_f16 v[140:143], v[210:213], v[190:193], v[140:143]
	s_waitcnt vmcnt(9)
	ds_write_b128 v125, v[24:27] offset:32768
	v_mfma_f32_16x16x32_f16 v[154:157], v[210:213], v[198:201], v[154:157]
	s_waitcnt vmcnt(8)
	ds_write_b128 v127, v[28:31] offset:32768
	s_waitcnt lgkmcnt(9)
	v_mfma_f32_16x16x32_f16 v[64:67], v[224:227], v[190:193], v[64:67]
	ds_read_b128 v[190:193], v129 offset:16384
	v_mfma_f32_16x16x32_f16 v[72:75], v[224:227], v[198:201], v[72:75]
	ds_read_b128 v[198:201], v129 offset:18432
	v_mfma_f32_16x16x32_f16 v[166:169], v[210:213], v[206:209], v[166:169]
	v_mfma_f32_16x16x32_f16 v[84:87], v[210:213], v[220:223], v[84:87]
	ds_read_b128 v[210:213], v130 offset:53248
	v_mfma_f32_16x16x32_f16 v[80:83], v[224:227], v[206:209], v[80:83]
	ds_read_b128 v[206:209], v129 offset:20480
	v_mfma_f32_16x16x32_f16 v[88:91], v[224:227], v[220:223], v[88:91]
	ds_read_b128 v[220:223], v129 offset:22528
	s_waitcnt lgkmcnt(4)
	v_mfma_f32_16x16x32_f16 v[132:135], v[194:197], v[190:193], v[132:135]
	ds_read_b128 v[224:227], v130 offset:55296
	s_waitcnt lgkmcnt(0)
	s_barrier
	v_mfma_f32_16x16x32_f16 v[136:139], v[202:205], v[190:193], v[136:139]
	ds_read_b128 v[0:3], v128
	v_mfma_f32_16x16x32_f16 v[144:147], v[202:205], v[198:201], v[144:147]
	ds_read_b128 v[4:7], v131 offset:32768
	v_mfma_f32_16x16x32_f16 v[140:143], v[210:213], v[190:193], v[140:143]
	ds_read_b128 v[8:11], v128 offset:2048
	v_mfma_f32_16x16x32_f16 v[154:157], v[210:213], v[198:201], v[154:157]
	ds_read_b128 v[12:15], v131 offset:34816
	v_mfma_f32_16x16x32_f16 v[162:165], v[202:205], v[206:209], v[162:165]
	ds_read_b128 v[16:19], v128 offset:4096
	v_mfma_f32_16x16x32_f16 v[202:205], v[202:205], v[220:223], v[76:79]
	ds_read_b128 v[20:23], v131 offset:36864
	v_mfma_f32_16x16x32_f16 v[166:169], v[210:213], v[206:209], v[166:169]
	ds_read_b128 v[24:27], v128 offset:6144
	v_mfma_f32_16x16x32_f16 v[210:213], v[210:213], v[220:223], v[84:87]
	ds_read_b128 v[28:31], v131 offset:38912
	v_mfma_f32_16x16x32_f16 v[190:193], v[224:227], v[190:193], v[64:67]
	s_nop 2
	global_load_dwordx4 v[64:67], v[104:105], off offset:1536
	v_mfma_f32_16x16x32_f16 v[228:231], v[194:197], v[198:201], v[92:95]
	v_mfma_f32_16x16x32_f16 v[198:201], v[224:227], v[198:201], v[72:75]
	s_waitcnt vmcnt(8)
	ds_write_b128 v126, v[32:35] offset:16384
	s_waitcnt vmcnt(7)
	ds_write_b128 v124, v[36:39] offset:16384
	v_mfma_f32_16x16x32_f16 v[158:161], v[194:197], v[206:209], v[158:161]
	v_mfma_f32_16x16x32_f16 v[206:209], v[224:227], v[206:209], v[80:83]
	s_waitcnt vmcnt(6)
	ds_write_b128 v125, v[40:43] offset:16384
	v_mfma_f32_16x16x32_f16 v[194:197], v[194:197], v[220:223], v[68:71]
	v_mfma_f32_16x16x32_f16 v[220:223], v[224:227], v[220:223], v[88:91]
	ds_read_b128 v[224:227], v130 offset:38912
	s_nop 0
	global_load_dwordx4 v[68:71], v[106:107], off offset:1536
	global_load_dwordx4 v[72:75], v[108:109], off offset:1536
	global_load_dwordx4 v[76:79], v[110:111], off offset:1536
	s_waitcnt lgkmcnt(10)
	v_mfma_f32_16x16x32_f16 v[132:135], v[4:7], v[0:3], v[132:135]
	global_load_dwordx4 v[80:83], v[112:113], off offset:1536
	s_waitcnt lgkmcnt(8)
	v_mfma_f32_16x16x32_f16 v[136:139], v[12:15], v[0:3], v[136:139]
	s_waitcnt lgkmcnt(6)
	v_mfma_f32_16x16x32_f16 v[140:143], v[20:23], v[0:3], v[140:143]
	s_waitcnt lgkmcnt(4)
	v_mfma_f32_16x16x32_f16 v[0:3], v[28:31], v[0:3], v[190:193]
	v_mfma_f32_16x16x32_f16 v[190:193], v[4:7], v[8:11], v[228:231]
	global_load_dwordx4 v[84:87], v[114:115], off offset:1536
	global_load_dwordx4 v[88:91], v[116:117], off offset:1536
	global_load_dwordx4 v[92:95], v[118:119], off offset:1536
	v_mfma_f32_16x16x32_f16 v[144:147], v[12:15], v[8:11], v[144:147]
	s_waitcnt vmcnt(12)
	ds_write_b128 v127, v[44:47] offset:16384
	v_mfma_f32_16x16x32_f16 v[158:161], v[4:7], v[16:19], v[158:161]
	s_waitcnt vmcnt(11)
	ds_write_b128 v126, v[48:51] offset:49152
	v_mfma_f32_16x16x32_f16 v[4:7], v[4:7], v[24:27], v[194:197]
	s_nop 2
	ds_read_b128 v[194:197], v130 offset:32768
	v_mfma_f32_16x16x32_f16 v[162:165], v[12:15], v[16:19], v[162:165]
	s_waitcnt vmcnt(10)
	ds_write_b128 v124, v[52:55] offset:49152
	v_mfma_f32_16x16x32_f16 v[12:15], v[12:15], v[24:27], v[202:205]
	s_nop 2
	ds_read_b128 v[202:205], v130 offset:34816
	s_waitcnt vmcnt(9)
	ds_write_b128 v125, v[56:59] offset:49152
	v_mfma_f32_16x16x32_f16 v[154:157], v[20:23], v[8:11], v[154:157]
	s_waitcnt vmcnt(8)
	ds_write_b128 v127, v[60:63] offset:49152
	v_mfma_f32_16x16x32_f16 v[8:11], v[28:31], v[8:11], v[198:201]
	s_nop 2
	ds_read_b128 v[198:201], v129 offset:2048
	v_mfma_f32_16x16x32_f16 v[166:169], v[20:23], v[16:19], v[166:169]
	v_mfma_f32_16x16x32_f16 v[20:23], v[20:23], v[24:27], v[210:213]
	s_nop 2
	ds_read_b128 v[210:213], v130 offset:36864
	v_mfma_f32_16x16x32_f16 v[16:19], v[28:31], v[16:19], v[206:209]
	s_nop 2
	ds_read_b128 v[206:209], v129 offset:4096
	v_mfma_f32_16x16x32_f16 v[24:27], v[28:31], v[24:27], v[220:223]
	ds_read_b128 v[28:31], v129
	s_waitcnt lgkmcnt(0)
	v_mfma_f32_16x16x32_f16 v[132:135], v[194:197], v[28:31], v[132:135]
	ds_read_b128 v[220:223], v129 offset:6144
	s_waitcnt lgkmcnt(0)
	s_barrier
; #define GL_LOAD(s_, kt_) if (VAR != 1) { a##s_##0 = GL_A(0, kt_); a##s_##1 = GL_A(1, kt_); a##s_##2 = GL_A(2, kt_); a##s_##3 = GL_A(3, kt_); b##s_##0 = GL_B(0, kt_); b##s_##1 = GL_B(1, kt_); b##s_##2 = GL_B(2, kt_); b##s_##3 = GL_B(3, kt_); }
; #define LDS_STORE(s_, buf_) if (VAR != 2) { LDS_ST1(sA, 0, buf_, a##s_##0) LDS_ST1(sA, 1, buf_, a##s_##1) LDS_ST1(sA, 2, buf_, a##s_##2) LDS_ST1(sA, 3, buf_, a##s_##3) LDS_ST1(sB, 0, buf_, b##s_##0) LDS_ST1(sB, 1, buf_, b##s_##1) LDS_ST1(sB, 2, buf_, b##s_##2) LDS_ST1(sB, 3, buf_, b##s_##3) }
;     ...
;   for (int kt = 0; kt < nk; kt += 2) {
;     if (kt + 2 < nk) { GL_LOAD(0, kt + 2) }
;     MMA_TILE(0)
;     LDS_STORE(1, 1)
;     if (VAR != 4) __syncthreads();
;     if (kt + 3 < nk) { GL_LOAD(1, kt + 3) }
;     MMA_TILE(1)
;     if (kt + 2 < nk) { LDS_STORE(0, 0) }
;     if (VAR != 4) __syncthreads();
	v_mfma_f32_16x16x32_f16 v[136:139], v[202:205], v[28:31], v[136:139]
	ds_read_b128 v[32:35], v128 offset:16384
	v_mfma_f32_16x16x32_f16 v[144:147], v[202:205], v[198:201], v[144:147]
	ds_read_b128 v[36:39], v131 offset:49152
	v_mfma_f32_16x16x32_f16 v[140:143], v[210:213], v[28:31], v[140:143]
	ds_read_b128 v[40:43], v128 offset:18432
	v_mfma_f32_16x16x32_f16 v[154:157], v[210:213], v[198:201], v[154:157]
	ds_read_b128 v[44:47], v131 offset:51200
	v_mfma_f32_16x16x32_f16 v[162:165], v[202:205], v[206:209], v[162:165]
	ds_read_b128 v[48:51], v128 offset:20480
	v_mfma_f32_16x16x32_f16 v[202:205], v[202:205], v[220:223], v[12:15]
	ds_read_b128 v[52:55], v131 offset:53248
	v_mfma_f32_16x16x32_f16 v[166:169], v[210:213], v[206:209], v[166:169]
	ds_read_b128 v[56:59], v128 offset:22528
	v_mfma_f32_16x16x32_f16 v[210:213], v[210:213], v[220:223], v[20:23]
	ds_read_b128 v[60:63], v131 offset:55296
	v_mfma_f32_16x16x32_f16 v[228:231], v[224:227], v[28:31], v[0:3]
	global_load_dwordx4 v[28:31], v[104:105], off offset:1664
	v_mfma_f32_16x16x32_f16 v[190:193], v[194:197], v[198:201], v[190:193]
	v_mfma_f32_16x16x32_f16 v[198:201], v[224:227], v[198:201], v[8:11]
	s_waitcnt vmcnt(8)
	ds_write_b128 v126, v[64:67]
	s_waitcnt vmcnt(7)
	ds_write_b128 v124, v[68:71]
	v_mfma_f32_16x16x32_f16 v[158:161], v[194:197], v[206:209], v[158:161]
	v_mfma_f32_16x16x32_f16 v[206:209], v[224:227], v[206:209], v[16:19]
	s_waitcnt vmcnt(6)
	ds_write_b128 v125, v[72:75]
	v_mfma_f32_16x16x32_f16 v[194:197], v[194:197], v[220:223], v[4:7]
	v_mfma_f32_16x16x32_f16 v[220:223], v[224:227], v[220:223], v[24:27]
	ds_read_b128 v[224:227], v130 offset:55296
	s_nop 1
	global_load_dwordx4 v[24:27], v[106:107], off offset:1664
	global_load_dwordx4 v[12:15], v[108:109], off offset:1664
	global_load_dwordx4 v[16:19], v[110:111], off offset:1664
	s_waitcnt lgkmcnt(10)
	v_mfma_f32_16x16x32_f16 v[132:135], v[36:39], v[32:35], v[132:135]
	global_load_dwordx4 v[20:23], v[112:113], off offset:1664
	s_waitcnt lgkmcnt(9)
	v_mfma_f32_16x16x32_f16 v[190:193], v[36:39], v[40:43], v[190:193]
	global_load_dwordx4 v[0:3], v[114:115], off offset:1664
	s_waitcnt lgkmcnt(8)
	v_mfma_f32_16x16x32_f16 v[136:139], v[44:47], v[32:35], v[136:139]
	global_load_dwordx4 v[4:7], v[116:117], off offset:1664
	v_mfma_f32_16x16x32_f16 v[144:147], v[44:47], v[40:43], v[144:147]
	global_load_dwordx4 v[8:11], v[118:119], off offset:1664
	s_waitcnt lgkmcnt(7)
	v_mfma_f32_16x16x32_f16 v[158:161], v[36:39], v[48:51], v[158:161]
	s_waitcnt vmcnt(12)
	ds_write_b128 v127, v[76:79]
	s_waitcnt lgkmcnt(6)
	v_mfma_f32_16x16x32_f16 v[36:39], v[36:39], v[56:59], v[194:197]
	s_nop 2
	ds_read_b128 v[194:197], v130 offset:49152
	v_mfma_f32_16x16x32_f16 v[162:165], v[44:47], v[48:51], v[162:165]
	s_waitcnt vmcnt(11)
	ds_write_b128 v126, v[80:83] offset:32768
	v_mfma_f32_16x16x32_f16 v[44:47], v[44:47], v[56:59], v[202:205]
	s_nop 2
	ds_read_b128 v[202:205], v130 offset:51200
	v_mfma_f32_16x16x32_f16 v[140:143], v[52:55], v[32:35], v[140:143]
	s_waitcnt vmcnt(10)
	ds_write_b128 v124, v[84:87] offset:32768
	v_mfma_f32_16x16x32_f16 v[154:157], v[52:55], v[40:43], v[154:157]
	s_waitcnt vmcnt(9)
	ds_write_b128 v125, v[88:91] offset:32768
	s_waitcnt lgkmcnt(10)
	v_mfma_f32_16x16x32_f16 v[32:35], v[60:63], v[32:35], v[228:231]
	s_waitcnt vmcnt(8)
	ds_write_b128 v127, v[92:95] offset:32768
	v_mfma_f32_16x16x32_f16 v[40:43], v[60:63], v[40:43], v[198:201]
	s_nop 2
	ds_read_b128 v[198:201], v129 offset:18432
	v_mfma_f32_16x16x32_f16 v[166:169], v[52:55], v[48:51], v[166:169]
	v_mfma_f32_16x16x32_f16 v[52:55], v[52:55], v[56:59], v[210:213]
	s_nop 2
	ds_read_b128 v[210:213], v130 offset:53248
	v_mfma_f32_16x16x32_f16 v[48:51], v[60:63], v[48:51], v[206:209]
	s_nop 2
	ds_read_b128 v[206:209], v129 offset:20480
	v_mfma_f32_16x16x32_f16 v[56:59], v[60:63], v[56:59], v[220:223]
	ds_read_b128 v[60:63], v129 offset:16384
	s_waitcnt lgkmcnt(0)
	v_mfma_f32_16x16x32_f16 v[132:135], v[194:197], v[60:63], v[132:135]
	ds_read_b128 v[220:223], v129 offset:22528
	s_waitcnt lgkmcnt(0)
	s_barrier
	v_mfma_f32_16x16x32_f16 v[136:139], v[202:205], v[60:63], v[136:139]
	ds_read_b128 v[64:67], v128
	v_mfma_f32_16x16x32_f16 v[144:147], v[202:205], v[198:201], v[144:147]
	ds_read_b128 v[68:71], v131 offset:32768
	v_mfma_f32_16x16x32_f16 v[140:143], v[210:213], v[60:63], v[140:143]
	ds_read_b128 v[72:75], v128 offset:2048
	v_mfma_f32_16x16x32_f16 v[154:157], v[210:213], v[198:201], v[154:157]
	ds_read_b128 v[76:79], v131 offset:34816
	v_mfma_f32_16x16x32_f16 v[162:165], v[202:205], v[206:209], v[162:165]
	ds_read_b128 v[80:83], v128 offset:4096
	v_mfma_f32_16x16x32_f16 v[202:205], v[202:205], v[220:223], v[44:47]
	ds_read_b128 v[84:87], v131 offset:36864
	v_mfma_f32_16x16x32_f16 v[166:169], v[210:213], v[206:209], v[166:169]
	ds_read_b128 v[88:91], v128 offset:6144
	v_mfma_f32_16x16x32_f16 v[210:213], v[210:213], v[220:223], v[52:55]
	ds_read_b128 v[92:95], v131 offset:38912
	v_mfma_f32_16x16x32_f16 v[228:231], v[224:227], v[60:63], v[32:35]
	s_nop 0
	global_load_dwordx4 v[52:55], v[104:105], off offset:1792
	v_mfma_f32_16x16x32_f16 v[190:193], v[194:197], v[198:201], v[190:193]
	v_mfma_f32_16x16x32_f16 v[198:201], v[224:227], v[198:201], v[40:43]
	s_waitcnt vmcnt(8)
	ds_write_b128 v126, v[28:31] offset:16384
	s_waitcnt vmcnt(7)
	ds_write_b128 v124, v[24:27] offset:16384
	s_waitcnt vmcnt(6)
	ds_write_b128 v125, v[12:15] offset:16384
	v_mfma_f32_16x16x32_f16 v[158:161], v[194:197], v[206:209], v[158:161]
	v_mfma_f32_16x16x32_f16 v[206:209], v[224:227], v[206:209], v[48:51]
	s_waitcnt vmcnt(5)
; #define GL_LOAD(s_, kt_) if (VAR != 1) { a##s_##0 = GL_A(0, kt_); a##s_##1 = GL_A(1, kt_); a##s_##2 = GL_A(2, kt_); a##s_##3 = GL_A(3, kt_); b##s_##0 = GL_B(0, kt_); b##s_##1 = GL_B(1, kt_); b##s_##2 = GL_B(2, kt_); b##s_##3 = GL_B(3, kt_); }
; #define LDS_STORE(s_, buf_) if (VAR != 2) { LDS_ST1(sA, 0, buf_, a##s_##0) LDS_ST1(sA, 1, buf_, a##s_##1) LDS_ST1(sA, 2, buf_, a##s_##2) LDS_ST1(sA, 3, buf_, a##s_##3) LDS_ST1(sB, 0, buf_, b##s_##0) LDS_ST1(sB, 1, buf_, b##s_##1) LDS_ST1(sB, 2, buf_, b##s_##2) LDS_ST1(sB, 3, buf_, b##s_##3) }
;     ...
;   for (int kt = 0; kt < nk; kt += 2) {
;     if (kt + 2 < nk) { GL_LOAD(0, kt + 2) }
;     MMA_TILE(0)
;     LDS_STORE(1, 1)
;     if (VAR != 4) __syncthreads();
;     if (kt + 3 < nk) { GL_LOAD(1, kt + 3) }
;     MMA_TILE(1)
;     if (kt + 2 < nk) { LDS_STORE(0, 0) }
;     if (VAR != 4) __syncthreads();
	ds_write_b128 v127, v[16:19] offset:16384
	v_mfma_f32_16x16x32_f16 v[194:197], v[194:197], v[220:223], v[36:39]
	v_mfma_f32_16x16x32_f16 v[220:223], v[224:227], v[220:223], v[56:59]
	ds_read_b128 v[224:227], v130 offset:38912
	s_nop 1
	global_load_dwordx4 v[56:59], v[106:107], off offset:1792
	global_load_dwordx4 v[60:63], v[108:109], off offset:1792
	global_load_dwordx4 v[40:43], v[110:111], off offset:1792
	s_waitcnt lgkmcnt(11)
	v_mfma_f32_16x16x32_f16 v[132:135], v[68:71], v[64:67], v[132:135]
	global_load_dwordx4 v[44:47], v[112:113], off offset:1792
	s_waitcnt lgkmcnt(10)
	v_mfma_f32_16x16x32_f16 v[190:193], v[68:71], v[72:75], v[190:193]
	global_load_dwordx4 v[48:51], v[114:115], off offset:1792
	s_waitcnt lgkmcnt(9)
	v_mfma_f32_16x16x32_f16 v[136:139], v[76:79], v[64:67], v[136:139]
	global_load_dwordx4 v[32:35], v[116:117], off offset:1792
	v_mfma_f32_16x16x32_f16 v[144:147], v[76:79], v[72:75], v[144:147]
	global_load_dwordx4 v[36:39], v[118:119], off offset:1792
	s_waitcnt lgkmcnt(8)
	v_mfma_f32_16x16x32_f16 v[158:161], v[68:71], v[80:83], v[158:161]
	s_waitcnt vmcnt(11)
	ds_write_b128 v126, v[20:23] offset:49152
	s_waitcnt lgkmcnt(7)
	v_mfma_f32_16x16x32_f16 v[68:71], v[68:71], v[88:91], v[194:197]
	s_nop 2
	ds_read_b128 v[194:197], v130 offset:32768
	v_mfma_f32_16x16x32_f16 v[162:165], v[76:79], v[80:83], v[162:165]
	s_waitcnt vmcnt(10)
	ds_write_b128 v124, v[0:3] offset:49152
	v_mfma_f32_16x16x32_f16 v[76:79], v[76:79], v[88:91], v[202:205]
	s_nop 2
	ds_read_b128 v[202:205], v130 offset:34816
	v_mfma_f32_16x16x32_f16 v[140:143], v[84:87], v[64:67], v[140:143]
	s_waitcnt vmcnt(9)
	ds_write_b128 v125, v[4:7] offset:49152
	v_mfma_f32_16x16x32_f16 v[154:157], v[84:87], v[72:75], v[154:157]
	s_waitcnt vmcnt(8)
	ds_write_b128 v127, v[8:11] offset:49152
	s_waitcnt lgkmcnt(11)
	v_mfma_f32_16x16x32_f16 v[64:67], v[92:95], v[64:67], v[228:231]
	v_mfma_f32_16x16x32_f16 v[72:75], v[92:95], v[72:75], v[198:201]
	s_nop 2
	ds_read_b128 v[198:201], v129 offset:2048
	v_mfma_f32_16x16x32_f16 v[166:169], v[84:87], v[80:83], v[166:169]
	v_mfma_f32_16x16x32_f16 v[84:87], v[84:87], v[88:91], v[210:213]
	s_nop 2
	ds_read_b128 v[210:213], v130 offset:36864
	v_mfma_f32_16x16x32_f16 v[80:83], v[92:95], v[80:83], v[206:209]
	s_nop 2
	ds_read_b128 v[206:209], v129 offset:4096
	v_mfma_f32_16x16x32_f16 v[88:91], v[92:95], v[88:91], v[220:223]
	ds_read_b128 v[92:95], v129
	s_nop 1
	ds_read_b128 v[220:223], v129 offset:6144
	s_waitcnt lgkmcnt(0)
	s_barrier
	v_mfma_f32_16x16x32_f16 v[132:135], v[194:197], v[92:95], v[132:135]
	global_load_dwordx4 v[24:27], v[104:105], off offset:1920
	v_mfma_f32_16x16x32_f16 v[136:139], v[202:205], v[92:95], v[136:139]
	v_mfma_f32_16x16x32_f16 v[140:143], v[210:213], v[92:95], v[140:143]
	v_mfma_f32_16x16x32_f16 v[64:67], v[224:227], v[92:95], v[64:67]
	v_mfma_f32_16x16x32_f16 v[92:95], v[194:197], v[198:201], v[190:193]
	s_nop 2
	ds_read_b128 v[190:193], v128 offset:20480
	global_load_dwordx4 v[28:31], v[106:107], off offset:1920
	ds_read_b128 v[104:107], v128 offset:16384
	v_mfma_f32_16x16x32_f16 v[144:147], v[202:205], v[198:201], v[144:147]
	global_load_dwordx4 v[12:15], v[108:109], off offset:1920
	v_mfma_f32_16x16x32_f16 v[158:161], v[194:197], v[206:209], v[158:161]
	global_load_dwordx4 v[16:19], v[110:111], off offset:1920
	v_mfma_f32_16x16x32_f16 v[68:71], v[194:197], v[220:223], v[68:71]
	ds_read_b128 v[108:111], v131 offset:49152
	v_mfma_f32_16x16x32_f16 v[162:165], v[202:205], v[206:209], v[162:165]
	ds_read_b128 v[194:197], v131 offset:53248
	v_mfma_f32_16x16x32_f16 v[76:79], v[202:205], v[220:223], v[76:79]
	ds_read_b128 v[202:205], v131 offset:55296
	global_load_dwordx4 v[20:23], v[112:113], off offset:1920
	v_mfma_f32_16x16x32_f16 v[154:157], v[210:213], v[198:201], v[154:157]
	global_load_dwordx4 v[0:3], v[114:115], off offset:1920
	ds_read_b128 v[112:115], v128 offset:18432
	v_mfma_f32_16x16x32_f16 v[72:75], v[224:227], v[198:201], v[72:75]
	ds_read_b128 v[198:201], v128 offset:22528
	v_mfma_f32_16x16x32_f16 v[166:169], v[210:213], v[206:209], v[166:169]
	global_load_dwordx4 v[4:7], v[116:117], off offset:1920
	v_mfma_f32_16x16x32_f16 v[84:87], v[210:213], v[220:223], v[84:87]
	global_load_dwordx4 v[8:11], v[118:119], off offset:1920
	v_mfma_f32_16x16x32_f16 v[80:83], v[224:227], v[206:209], v[80:83]
	ds_read_b128 v[116:119], v131 offset:51200
	v_mfma_f32_16x16x32_f16 v[88:91], v[224:227], v[220:223], v[88:91]
	s_waitcnt vmcnt(15)
	ds_write_b128 v126, v[52:55]
	s_waitcnt lgkmcnt(6)
	v_mfma_f32_16x16x32_f16 v[132:135], v[108:111], v[104:107], v[132:135]
	s_waitcnt vmcnt(14)
	ds_write_b128 v124, v[56:59]
	s_waitcnt lgkmcnt(4)
	v_mfma_f32_16x16x32_f16 v[92:95], v[108:111], v[112:115], v[92:95]
	s_waitcnt vmcnt(13)
	ds_write_b128 v125, v[60:63]
	s_waitcnt lgkmcnt(3)
	v_mfma_f32_16x16x32_f16 v[136:139], v[116:119], v[104:107], v[136:139]
	s_waitcnt vmcnt(12)
	ds_write_b128 v127, v[40:43]
	v_mfma_f32_16x16x32_f16 v[140:143], v[194:197], v[104:107], v[140:143]
	v_mfma_f32_16x16x32_f16 v[64:67], v[202:205], v[104:107], v[64:67]
	v_mfma_f32_16x16x32_f16 v[104:107], v[116:119], v[112:115], v[144:147]
	s_waitcnt vmcnt(11)
	ds_write_b128 v126, v[44:47] offset:32768
	v_mfma_f32_16x16x32_f16 v[144:147], v[194:197], v[112:115], v[154:157]
	v_mfma_f32_16x16x32_f16 v[72:75], v[202:205], v[112:115], v[72:75]
	v_mfma_f32_16x16x32_f16 v[112:115], v[108:111], v[190:193], v[158:161]
	s_waitcnt vmcnt(10)
	ds_write_b128 v124, v[48:51] offset:32768
	s_waitcnt vmcnt(9)
	ds_write_b128 v125, v[32:35] offset:32768
	v_mfma_f32_16x16x32_f16 v[68:71], v[108:111], v[198:201], v[68:71]
	ds_read_b128 v[108:111], v129 offset:16384
	v_mfma_f32_16x16x32_f16 v[154:157], v[116:119], v[190:193], v[162:165]
	s_nop 2
	ds_read_b128 v[162:165], v129 offset:18432
	v_mfma_f32_16x16x32_f16 v[76:79], v[116:119], v[198:201], v[76:79]
	ds_read_b128 v[116:119], v130 offset:49152
	s_waitcnt vmcnt(8)
	ds_write_b128 v127, v[36:39] offset:32768
	v_mfma_f32_16x16x32_f16 v[158:161], v[194:197], v[190:193], v[166:169]
	s_nop 2
	ds_read_b128 v[166:169], v130 offset:51200
	v_mfma_f32_16x16x32_f16 v[84:87], v[194:197], v[198:201], v[84:87]
	ds_read_b128 v[194:197], v130 offset:53248
	v_mfma_f32_16x16x32_f16 v[80:83], v[202:205], v[190:193], v[80:83]
	ds_read_b128 v[190:193], v129 offset:20480
	v_mfma_f32_16x16x32_f16 v[88:91], v[202:205], v[198:201], v[88:91]
	ds_read_b128 v[198:201], v129 offset:22528
	s_waitcnt lgkmcnt(5)
	v_mfma_f32_16x16x32_f16 v[132:135], v[116:119], v[108:111], v[132:135]
	ds_read_b128 v[202:205], v130 offset:55296
	s_waitcnt lgkmcnt(0)
	s_barrier
; #define GL_LOAD(s_, kt_) if (VAR != 1) { a##s_##0 = GL_A(0, kt_); a##s_##1 = GL_A(1, kt_); a##s_##2 = GL_A(2, kt_); a##s_##3 = GL_A(3, kt_); b##s_##0 = GL_B(0, kt_); b##s_##1 = GL_B(1, kt_); b##s_##2 = GL_B(2, kt_); b##s_##3 = GL_B(3, kt_); }
; #define LDS_STORE(s_, buf_) if (VAR != 2) { LDS_ST1(sA, 0, buf_, a##s_##0) LDS_ST1(sA, 1, buf_, a##s_##1) LDS_ST1(sA, 2, buf_, a##s_##2) LDS_ST1(sA, 3, buf_, a##s_##3) LDS_ST1(sB, 0, buf_, b##s_##0) LDS_ST1(sB, 1, buf_, b##s_##1) LDS_ST1(sB, 2, buf_, b##s_##2) LDS_ST1(sB, 3, buf_, b##s_##3) }
;     ...
;   for (int kt = 0; kt < nk; kt += 2) {
;     if (kt + 2 < nk) { GL_LOAD(0, kt + 2) }
;     MMA_TILE(0)
;     LDS_STORE(1, 1)
;     if (VAR != 4) __syncthreads();
;     if (kt + 3 < nk) { GL_LOAD(1, kt + 3) }
;     MMA_TILE(1)
;     if (kt + 2 < nk) { LDS_STORE(0, 0) }
;     if (VAR != 4) __syncthreads();
	ds_read_b128 v[32:35], v128
	ds_read_b128 v[36:39], v131 offset:32768
	ds_read_b128 v[40:43], v128 offset:2048
	ds_read_b128 v[44:47], v131 offset:34816
	ds_read_b128 v[48:51], v128 offset:4096
	ds_read_b128 v[52:55], v131 offset:36864
	ds_read_b128 v[56:59], v128 offset:6144
	ds_read_b128 v[60:63], v131 offset:38912
	v_mfma_f32_16x16x32_f16 v[136:139], v[166:169], v[108:111], v[136:139]
	v_mfma_f32_16x16x32_f16 v[140:143], v[194:197], v[108:111], v[140:143]
	v_mfma_f32_16x16x32_f16 v[64:67], v[202:205], v[108:111], v[64:67]
	v_mfma_f32_16x16x32_f16 v[92:95], v[116:119], v[162:165], v[92:95]
	v_mfma_f32_16x16x32_f16 v[104:107], v[166:169], v[162:165], v[104:107]
	v_mfma_f32_16x16x32_f16 v[108:111], v[194:197], v[162:165], v[144:147]
	v_mfma_f32_16x16x32_f16 v[72:75], v[202:205], v[162:165], v[72:75]
	v_mfma_f32_16x16x32_f16 v[112:115], v[116:119], v[190:193], v[112:115]
	v_mfma_f32_16x16x32_f16 v[144:147], v[166:169], v[190:193], v[154:157]
	v_mfma_f32_16x16x32_f16 v[154:157], v[194:197], v[190:193], v[158:161]
	v_mfma_f32_16x16x32_f16 v[80:83], v[202:205], v[190:193], v[80:83]
	v_mfma_f32_16x16x32_f16 v[68:71], v[116:119], v[198:201], v[68:71]
	v_mfma_f32_16x16x32_f16 v[76:79], v[166:169], v[198:201], v[76:79]
	v_mfma_f32_16x16x32_f16 v[84:87], v[194:197], v[198:201], v[84:87]
	v_mfma_f32_16x16x32_f16 v[88:91], v[202:205], v[198:201], v[88:91]
	s_waitcnt lgkmcnt(6)
	v_mfma_f32_16x16x32_f16 v[116:119], v[36:39], v[32:35], v[132:135]
	s_waitcnt lgkmcnt(4)
	v_mfma_f32_16x16x32_f16 v[132:135], v[44:47], v[32:35], v[136:139]
	s_waitcnt lgkmcnt(2)
	v_mfma_f32_16x16x32_f16 v[136:139], v[52:55], v[32:35], v[140:143]
	s_waitcnt lgkmcnt(0)
	v_mfma_f32_16x16x32_f16 v[32:35], v[60:63], v[32:35], v[64:67]
	v_mfma_f32_16x16x32_f16 v[64:67], v[36:39], v[40:43], v[92:95]
	v_mfma_f32_16x16x32_f16 v[92:95], v[44:47], v[40:43], v[104:107]
	v_mfma_f32_16x16x32_f16 v[104:107], v[52:55], v[40:43], v[108:111]
	v_mfma_f32_16x16x32_f16 v[40:43], v[60:63], v[40:43], v[72:75]
	v_mfma_f32_16x16x32_f16 v[72:75], v[36:39], v[48:51], v[112:115]
	v_mfma_f32_16x16x32_f16 v[108:111], v[44:47], v[48:51], v[144:147]
	v_mfma_f32_16x16x32_f16 v[112:115], v[52:55], v[48:51], v[154:157]
	v_mfma_f32_16x16x32_f16 v[48:51], v[60:63], v[48:51], v[80:83]
	v_mfma_f32_16x16x32_f16 v[36:39], v[36:39], v[56:59], v[68:71]
	v_mfma_f32_16x16x32_f16 v[44:47], v[44:47], v[56:59], v[76:79]
	v_mfma_f32_16x16x32_f16 v[52:55], v[52:55], v[56:59], v[84:87]
	v_mfma_f32_16x16x32_f16 v[56:59], v[60:63], v[56:59], v[88:91]
	ds_read_b128 v[60:63], v129
	ds_read_b128 v[68:71], v130 offset:32768
	ds_read_b128 v[76:79], v129 offset:2048
	ds_read_b128 v[80:83], v130 offset:34816
	ds_read_b128 v[84:87], v129 offset:4096
	ds_read_b128 v[88:91], v130 offset:36864
	ds_read_b128 v[140:143], v129 offset:6144
	ds_read_b128 v[144:147], v130 offset:38912
	s_waitcnt vmcnt(7)
	ds_write_b128 v126, v[24:27] offset:16384
	s_waitcnt vmcnt(6)
	ds_write_b128 v124, v[28:31] offset:16384
	s_waitcnt vmcnt(5)
	ds_write_b128 v125, v[12:15] offset:16384
	s_waitcnt vmcnt(4)
	ds_write_b128 v127, v[16:19] offset:16384
	s_waitcnt vmcnt(3)
	ds_write_b128 v126, v[20:23] offset:49152
	s_waitcnt vmcnt(2)
	ds_write_b128 v124, v[0:3] offset:49152
	s_waitcnt vmcnt(1)
	ds_write_b128 v125, v[4:7] offset:49152
	s_waitcnt vmcnt(0)
	ds_write_b128 v127, v[8:11] offset:49152
	s_waitcnt lgkmcnt(0)
	v_mfma_f32_16x16x32_f16 v[116:119], v[68:71], v[60:63], v[116:119]
	s_barrier
	ds_read_b128 v[0:3], v128 offset:16384
	ds_read_b128 v[4:7], v131 offset:49152
	ds_read_b128 v[8:11], v128 offset:18432
	ds_read_b128 v[12:15], v131 offset:51200
	ds_read_b128 v[16:19], v128 offset:20480
	ds_read_b128 v[20:23], v131 offset:53248
	ds_read_b128 v[24:27], v128 offset:22528
	ds_read_b128 v[28:31], v131 offset:55296
	v_mfma_f32_16x16x32_f16 v[132:135], v[80:83], v[60:63], v[132:135]
	v_mfma_f32_16x16x32_f16 v[136:139], v[88:91], v[60:63], v[136:139]
	v_mfma_f32_16x16x32_f16 v[32:35], v[144:147], v[60:63], v[32:35]
	v_mfma_f32_16x16x32_f16 v[60:63], v[68:71], v[76:79], v[64:67]
	v_mfma_f32_16x16x32_f16 v[64:67], v[80:83], v[76:79], v[92:95]
	v_mfma_f32_16x16x32_f16 v[92:95], v[88:91], v[76:79], v[104:107]
	v_mfma_f32_16x16x32_f16 v[40:43], v[144:147], v[76:79], v[40:43]
	v_mfma_f32_16x16x32_f16 v[72:75], v[68:71], v[84:87], v[72:75]
	v_mfma_f32_16x16x32_f16 v[76:79], v[80:83], v[84:87], v[108:111]
	v_mfma_f32_16x16x32_f16 v[104:107], v[88:91], v[84:87], v[112:115]
	v_mfma_f32_16x16x32_f16 v[48:51], v[144:147], v[84:87], v[48:51]
	v_mfma_f32_16x16x32_f16 v[36:39], v[68:71], v[140:143], v[36:39]
	v_mfma_f32_16x16x32_f16 v[44:47], v[80:83], v[140:143], v[44:47]
	v_mfma_f32_16x16x32_f16 v[52:55], v[88:91], v[140:143], v[52:55]
	v_mfma_f32_16x16x32_f16 v[56:59], v[144:147], v[140:143], v[56:59]
	s_waitcnt lgkmcnt(6)
	v_mfma_f32_16x16x32_f16 v[68:71], v[4:7], v[0:3], v[116:119]
	s_waitcnt lgkmcnt(4)
	v_mfma_f32_16x16x32_f16 v[80:83], v[12:15], v[0:3], v[132:135]
	s_waitcnt lgkmcnt(2)
	v_mfma_f32_16x16x32_f16 v[84:87], v[20:23], v[0:3], v[136:139]
	s_waitcnt lgkmcnt(0)
	v_mfma_f32_16x16x32_f16 v[0:3], v[28:31], v[0:3], v[32:35]
	v_mfma_f32_16x16x32_f16 v[32:35], v[4:7], v[8:11], v[60:63]
	v_mfma_f32_16x16x32_f16 v[60:63], v[12:15], v[8:11], v[64:67]
	v_mfma_f32_16x16x32_f16 v[64:67], v[20:23], v[8:11], v[92:95]
	v_mfma_f32_16x16x32_f16 v[8:11], v[28:31], v[8:11], v[40:43]
	v_mfma_f32_16x16x32_f16 v[40:43], v[4:7], v[16:19], v[72:75]
	v_mfma_f32_16x16x32_f16 v[72:75], v[12:15], v[16:19], v[76:79]
	v_mfma_f32_16x16x32_f16 v[92:95], v[20:23], v[16:19], v[104:107]
	v_mfma_f32_16x16x32_f16 v[16:19], v[28:31], v[16:19], v[48:51]
	v_mfma_f32_16x16x32_f16 v[4:7], v[4:7], v[24:27], v[36:39]
	v_mfma_f32_16x16x32_f16 v[12:15], v[12:15], v[24:27], v[44:47]
	v_mfma_f32_16x16x32_f16 v[52:55], v[20:23], v[24:27], v[52:55]
	v_mfma_f32_16x16x32_f16 v[28:31], v[28:31], v[24:27], v[56:59]
	ds_read_b128 v[20:23], v129 offset:16384
	ds_read_b128 v[104:107], v130 offset:49152
	ds_read_b128 v[24:27], v129 offset:18432
	ds_read_b128 v[108:111], v130 offset:51200
	ds_read_b128 v[112:115], v129 offset:20480
	ds_read_b128 v[116:119], v130 offset:53248
	ds_read_b128 v[124:127], v129 offset:22528
	ds_read_b128 v[128:131], v130 offset:55296
	s_waitcnt lgkmcnt(0)
	s_barrier
; DI int TIDX() { int t = threadIdx.x; asm volatile("" : "+v"(t)); return t; }
; DI unsigned pack2(float lo, float hi) { f2_t v = {lo, hi}; h2_t b = __builtin_convertvector(v, h2_t); return __builtin_bit_cast(unsigned, b); }
; DI float lo_f(unsigned u) { return (float)(__builtin_bit_cast(h2_t, u)[0]); }
; DI float hi_f(unsigned u) { return (float)(__builtin_bit_cast(h2_t, u)[1]); }
; DI float sigmoidf_(float x) { return 1.0f / (1.0f + __expf(-x)); }
; DI void epi_residual(const f32x4 (&v)[4][4], int row0, int col0, const float* xsrc, float* x, bf16_t* xb, float* ssq_out, bool write_xb, bool write_ssq) {
;   const int lane = TIDX() & 63, lr = lane & 15, g = lane >> 4;
; #pragma unroll
;   for (int mt = 0; mt < 4; ++mt) {
;     const int row = row0 + mt * 16 + lr;
;     float ss = 0.f;
; #pragma unroll
;     for (int nt = 0; nt < 4; ++nt) {
;       const int col = col0 + nt * 16 + 4 * g;
;       float4* px = (float4*)(x + (size_t)row * DM + col);
;       float4 o = *(const float4*)(xsrc + (size_t)row * DM + col);
;       o.x += v[mt][nt][0]; o.y += v[mt][nt][1]; o.z += v[mt][nt][2]; o.w += v[mt][nt][3];
;       *px = o;
;       ss += (o.x * o.x + o.y * o.y) + (o.z * o.z + o.w * o.w);
;       if (write_xb) *(uint2*)(xb + (size_t)row * DM + col) = make_uint2(pack2(o.x, o.y), pack2(o.z, o.w));
; DI void phase_ple(const Params& P, int l, char* smem) {
;     ...
; #pragma unroll
;     for (int mt = 0; mt < 4; ++mt)
; #pragma unroll
;       for (int h = 0; h < 2; ++h) {
;         const uint4 q = park[mt * 2 + h];
;         acc[mt][2 * h][0] = sigmoidf_(acc[mt][2 * h][0] * rs[mt]) * lo_f(q.x);
;         acc[mt][2 * h][1] = sigmoidf_(acc[mt][2 * h][1] * rs[mt]) * hi_f(q.x);
;         acc[mt][2 * h][2] = sigmoidf_(acc[mt][2 * h][2] * rs[mt]) * lo_f(q.y);
;         acc[mt][2 * h][3] = sigmoidf_(acc[mt][2 * h][3] * rs[mt]) * hi_f(q.y);
;         acc[mt][2 * h + 1][0] = sigmoidf_(acc[mt][2 * h + 1][0] * rs[mt]) * lo_f(q.z);
;         acc[mt][2 * h + 1][1] = sigmoidf_(acc[mt][2 * h + 1][1] * rs[mt]) * hi_f(q.z);
;         acc[mt][2 * h + 1][2] = sigmoidf_(acc[mt][2 * h + 1][2] * rs[mt]) * lo_f(q.w);
;         acc[mt][2 * h + 1][3] = sigmoidf_(acc[mt][2 * h + 1][3] * rs[mt]) * hi_f(q.w);
;       }
;     epi_residual(acc, row0, col0, P.out, P.out, xb2, ssq_out, l + 1 < DEPTH, l + 1 < DEPTH);
	s_setprio 0
	v_mfma_f32_16x16x32_f16 v[132:135], v[104:107], v[20:23], v[68:71]
	v_mfma_f32_16x16x32_f16 v[88:91], v[108:111], v[20:23], v[80:83]
	v_mfma_f32_16x16x32_f16 v[84:87], v[116:119], v[20:23], v[84:87]
	v_mfma_f32_16x16x32_f16 v[76:79], v[128:131], v[20:23], v[0:3]
	v_mfma_f32_16x16x32_f16 v[20:23], v[104:107], v[124:127], v[4:7]
	s_nop 3
	v_mul_f32_e32 v4, v101, v132
	v_mul_f32_e32 v4, 0xbfb8aa3b, v4
	v_mfma_f32_16x16x32_f16 v[36:39], v[108:111], v[112:115], v[72:75]
	s_nop 2
	v_exp_f32_e32 v72, v4
	v_mul_f32_e32 v4, v101, v133
	v_mul_f32_e32 v4, 0xbfb8aa3b, v4
	v_exp_f32_e32 v73, v4
	v_mul_f32_e32 v4, v101, v134
	v_mul_f32_e32 v4, 0xbfb8aa3b, v4
	v_mfma_f32_16x16x32_f16 v[60:63], v[108:111], v[24:27], v[60:63]
	v_mov_b32_e32 v74, v148
	v_pk_add_f32 v[72:73], v[72:73], 1.0 op_sel_hi:[1,0]
	v_mfma_f32_16x16x32_f16 v[12:15], v[108:111], v[124:127], v[12:15]
	v_exp_f32_e32 v110, v4
	v_mul_f32_e32 v4, v101, v135
	v_mul_f32_e32 v4, 0xbfb8aa3b, v4
	v_mfma_f32_16x16x32_f16 v[68:71], v[104:107], v[24:27], v[32:35]
	v_exp_f32_e32 v111, v4
	s_nop 0
	v_pk_add_f32 v[110:111], v[110:111], 1.0 op_sel_hi:[1,0]
	v_mfma_f32_16x16x32_f16 v[56:59], v[116:119], v[24:27], v[64:67]
	v_mfma_f32_16x16x32_f16 v[48:51], v[128:131], v[24:27], v[8:11]
	v_mfma_f32_16x16x32_f16 v[44:47], v[104:107], v[112:115], v[40:43]
	v_mfma_f32_16x16x32_f16 v[32:35], v[116:119], v[112:115], v[92:95]
	v_mfma_f32_16x16x32_f16 v[24:27], v[128:131], v[112:115], v[16:19]
	v_or_b32_e32 v114, s2, v120
	v_mfma_f32_16x16x32_f16 v[8:11], v[116:119], v[124:127], v[52:55]
	s_nop 2
	global_load_dwordx4 v[52:55], v[102:103], off offset:48
	global_load_dwordx4 v[64:67], v[102:103], off offset:32
	global_load_dwordx4 v[80:83], v[102:103], off offset:16
	global_load_dwordx4 v[92:95], v[102:103], off
	s_waitcnt vmcnt(0)
	v_cvt_f32_f16_e32 v116, v92
	v_mfma_f32_16x16x32_f16 v[0:3], v[128:131], v[124:127], v[28:31]
	global_load_dwordx4 v[4:7], v[102:103], off offset:112
	global_load_dwordx4 v[16:19], v[102:103], off offset:96
	s_nop 0
	global_load_dwordx4 v[28:31], v[102:103], off offset:80
	global_load_dwordx4 v[40:43], v[102:103], off offset:64
	v_cvt_f32_f16_sdwa v117, v92 dst_sel:DWORD dst_unused:UNUSED_PAD src0_sel:WORD_1
	v_and_or_b32 v104, v74, 15, v123
	v_bfe_u32 v115, v74, 4, 2
	v_ashrrev_i32_e32 v105, 31, v104
	v_lshl_or_b32 v118, v115, 2, v114
	v_lshlrev_b64 v[74:75], 12, v[104:105]
	v_lshlrev_b64 v[102:103], 11, v[104:105]
	v_lshl_add_u64 v[74:75], s[16:17], 0, v[74:75]
	v_lshl_add_u64 v[106:107], s[6:7], 0, v[102:103]
	v_lshlrev_b32_e32 v102, 2, v118
	v_mov_b32_e32 v103, v151
	v_lshl_add_u64 v[108:109], v[74:75], 0, v[102:103]
	v_div_scale_f32 v74, s[6:7], v73, v73, 1.0
	v_rcp_f32_e32 v75, v74
	v_div_scale_f32 v92, s[6:7], v111, v111, 1.0
	v_fma_f32 v103, -v74, v75, 1.0
	v_fmac_f32_e32 v75, v103, v75
	v_div_scale_f32 v103, vcc, 1.0, v73, 1.0
	v_mul_f32_e32 v112, v103, v75
	v_fma_f32 v113, -v74, v112, v103
	v_fmac_f32_e32 v112, v113, v75
	v_fma_f32 v74, -v74, v112, v103
	v_div_fmas_f32 v74, v74, v75, v112
	v_div_fixup_f32 v113, v74, v73, 1.0
	v_div_scale_f32 v73, s[6:7], v72, v72, 1.0
	v_rcp_f32_e32 v74, v73
	s_nop 0
	v_fma_f32 v75, -v73, v74, 1.0
	v_fmac_f32_e32 v74, v75, v74
	v_div_scale_f32 v75, vcc, 1.0, v72, 1.0
	v_mul_f32_e32 v103, v75, v74
	v_fma_f32 v112, -v73, v103, v75
	v_fmac_f32_e32 v103, v112, v74
	v_fma_f32 v73, -v73, v103, v75
	v_div_fmas_f32 v73, v73, v74, v103
	v_div_fixup_f32 v112, v73, v72, 1.0
	global_load_dwordx4 v[72:75], v[108:109], off
	v_rcp_f32_e32 v103, v92
	s_waitcnt vmcnt(0)
	v_pk_fma_f32 v[72:73], v[112:113], v[116:117], v[72:73]
	v_fma_f32 v112, -v92, v103, 1.0
	v_fmac_f32_e32 v103, v112, v103
	v_div_scale_f32 v112, vcc, 1.0, v111, 1.0
	v_mul_f32_e32 v113, v112, v103
	v_fma_f32 v116, -v92, v113, v112
	v_fmac_f32_e32 v113, v116, v103
	v_fma_f32 v92, -v92, v113, v112
	v_div_fmas_f32 v92, v92, v103, v113
	v_div_fixup_f32 v111, v92, v111, 1.0
	v_div_scale_f32 v92, s[6:7], v110, v110, 1.0
	v_rcp_f32_e32 v103, v92
	s_nop 0
	v_fma_f32 v112, -v92, v103, 1.0
	v_fmac_f32_e32 v103, v112, v103
	v_div_scale_f32 v112, vcc, 1.0, v110, 1.0
	v_mul_f32_e32 v113, v112, v103
	v_fma_f32 v116, -v92, v113, v112
	v_fmac_f32_e32 v113, v116, v103
	v_fma_f32 v92, -v92, v113, v112
	v_div_fmas_f32 v92, v92, v103, v113
	v_div_fixup_f32 v110, v92, v110, 1.0
	v_cvt_f32_f16_e32 v92, v93
	v_cvt_f32_f16_sdwa v93, v93 dst_sel:DWORD dst_unused:UNUSED_PAD src0_sel:WORD_1
	s_andn2_b64 vcc, exec, s[4:5]
	v_pk_fma_f32 v[74:75], v[110:111], v[92:93], v[74:75]
	v_cndmask_b32_e64 v92, 0, 1, s[4:5]
	v_cmp_ne_u32_e64 s[42:43], 1, v92
	v_lshlrev_b32_e32 v92, 1, v118
	global_store_dwordx4 v[108:109], v[72:75], off
	s_cbranch_vccnz .LBB0_1438
	v_mov_b32_e32 v93, v151
	v_cvt_pk_f16_f32 v110, v72, v73
	v_cvt_pk_f16_f32 v111, v74, v75
	v_lshl_add_u64 v[112:113], v[106:107], 0, v[92:93]
	global_store_dwordx2 v[112:113], v[110:111], off
